# k-loop LDS-DMAs in SGPR-base + 32-bit lane offset form (364 of 416 sites), address VALU dropped
# speedup vs baseline: 1.0073x; 1.0048x over previous
; #define PG8_STAGE(bufoff, gbase, voff) do { _Pragma("unroll") for (int _i = 0; _i < 2; ++_i) \
;         __builtin_amdgcn_global_load_lds((const unsigned*)((const char*)(gbase) + (voff)[_i]), (LAS unsigned*)(lds + (bufoff) + ldsw + _i * 8192), 16, 0, 0); } while (0)
; #define PG8_LDA(dst, b, h) do { _Pragma("unroll") for (int m = 0; m < 4; ++m) _Pragma("unroll") for (int k = 0; k < 2; ++k) dst[m][k] = *(const LAS bf16x8*)(lds + PG8_SA(b, h) + aoff + m * 2048 + k * 1024); } while (0)
; #define PG8_LDB(dst, b, h) do { _Pragma("unroll") for (int n = 0; n < 2; ++n) _Pragma("unroll") for (int k = 0; k < 2; ++k) dst[n][k] = *(const LAS bf16x8*)(lds + PG8_SB(b, h) + boff + n * 2048 + k * 1024); } while (0)
; #define PG8_WAIT_V(n) asm volatile("s_waitcnt vmcnt(" #n ")" ::: "memory")
; #define PG8_WAIT_L(n) asm volatile("s_waitcnt lgkmcnt(" #n ")" ::: "memory")
; #define PG8_BAR __builtin_amdgcn_s_barrier()
; #define PG8_SCHED __builtin_amdgcn_sched_barrier(0)
; template <class Epi>
; __device__ __forceinline__ void gemm_phase(LAS unsigned char* lds, const Gemm g, const StaticOrder& S, const Epi& E) {
;     ...
;     for (;;) {
;         const bool has_next = S.next(ui + 1, nxt);
;         const char* nA = has_next ? (const char*)g.A + (size_t)nxt.pm * tstepA + (size_t)(nxt.pn >> g.a_shift) * g.a_step : cA; const char* nB = has_next ? (const char*)g.Bt + (size_t)nxt.pn * tstepB : cB;
;         for (int t = 0; t < nt; t += 2) {
;             const bool last = (t == nt - 2);
;             const char* a1 = cA + (size_t)(t + 1) * kstep;
;             const char* a2 = last ? nA : cA + (size_t)(t + 2) * kstep; const char* b2 = last ? nB : cB + (size_t)(t + 2) * kstep;
;             const char* a3 = a2 + kstep; const char* b3 = b2 + kstep;
;             PG8_LDB(B0, 0, 0); PG8_SCHED; PG8_LDA(At, 0, 0); PG8_STAGE(PG8_SA(1, 1), a1 + hstepA, voffA);
;             PG8_WAIT_L(8); PG8_BAR; PG8_WAIT_L(0); PG8_MMA(0, 0, At, B0); PG8_BAR; PG8_SCHED;
;             PG8_LDB(B1, 0, 1); PG8_STAGE(PG8_SB(0, 0), b2, voffB);
;             PG8_BAR; PG8_WAIT_L(0); PG8_MMA(0, 1, At, B1); PG8_BAR;
;             PG8_LDA(At, 0, 1); PG8_STAGE(PG8_SA(0, 0), a2, voffA);
;             PG8_BAR; PG8_WAIT_L(0); PG8_MMA(1, 0, At, B0); PG8_BAR; PG8_SCHED;
;             PG8_STAGE(PG8_SB(0, 1), b2 + hstepB, voffB);
;             PG8_WAIT_V(6); PG8_BAR; PG8_MMA(1, 1, At, B1); PG8_BAR;
.LBB0_308:
	s_ashr_i32 s27, s26, 31
	v_cmp_lt_i64_e32 vcc, s[28:29], v[228:229]
	s_lshl_b64 s[28:29], s[26:27], 19
	s_add_u32 s28, s66, s28
	s_addc_u32 s29, s67, s29
	s_and_b64 s[30:31], vcc, exec
	s_cselect_b32 s27, s29, s37
	s_cselect_b32 s75, s28, s36
	s_ashr_i32 s25, s24, 31
	s_lshl_b64 s[30:31], s[24:25], 19
	s_add_u32 s30, s4, s30
	s_addc_u32 s31, s5, s31
	s_and_b64 s[40:41], vcc, exec
	s_cselect_b32 s25, s31, s39
	s_cselect_b32 s76, s30, s38
	s_add_u32 s77, s38, 0x100
	s_addc_u32 s78, s39, 0
	s_mov_b32 s79, -2
	ds_read_b128 v[96:99], v243
	ds_read_b128 v[100:103], v243 offset:1024
	ds_read_b128 v[104:107], v243 offset:2048
	ds_read_b128 v[108:111], v243 offset:3072
	s_add_u32 s38, s36, 0x100
	s_addc_u32 s39, s37, 0
	s_cmp_eq_u32 s79, 12
	s_cselect_b32 s43, s27, s39
	s_cselect_b32 s42, s75, s38
	s_cselect_b32 s41, s25, s78
	s_cselect_b32 s40, s76, s77
	s_add_i32 m0, s45, 0xc000
	ds_read_b128 v[112:115], v244
	ds_read_b128 v[116:119], v244 offset:1024
	ds_read_b128 v[120:123], v244 offset:2048
	ds_read_b128 v[124:127], v244 offset:3072
	ds_read_b128 v[160:163], v244 offset:4096
	ds_read_b128 v[164:167], v244 offset:5120
	ds_read_b128 v[168:171], v244 offset:6144
	ds_read_b128 v[172:175], v244 offset:7168
	global_load_lds_dwordx4 v224, s[36:37]
	s_add_i32 m0, s45, 0xe000
	s_nop 0
	global_load_lds_dwordx4 v226, s[36:37]
	ds_read_b128 v[176:179], v245
	ds_read_b128 v[180:183], v245 offset:1024
	ds_read_b128 v[184:187], v245 offset:2048
	ds_read_b128 v[188:191], v245 offset:3072
	s_waitcnt lgkmcnt(0)
	s_barrier
	s_setprio 1
	v_mfma_f32_16x16x32_bf16 v[156:159], v[96:99], v[112:115], 0
	v_mfma_f32_16x16x32_bf16 v[60:63], v[104:107], v[112:115], 0
	v_mfma_f32_16x16x32_bf16 v[144:147], v[96:99], v[120:123], 0
	v_mfma_f32_16x16x32_bf16 v[48:51], v[104:107], v[120:123], 0
	v_mfma_f32_16x16x32_bf16 v[136:139], v[96:99], v[160:163], 0
	v_mfma_f32_16x16x32_bf16 v[40:43], v[104:107], v[160:163], 0
	v_mfma_f32_16x16x32_bf16 v[148:151], v[96:99], v[168:171], 0
	v_mfma_f32_16x16x32_bf16 v[52:55], v[104:107], v[168:171], 0
	v_mfma_f32_16x16x32_bf16 v[156:159], v[100:103], v[116:119], v[156:159]
	v_mfma_f32_16x16x32_bf16 v[60:63], v[108:111], v[116:119], v[60:63]
	v_mfma_f32_16x16x32_bf16 v[144:147], v[100:103], v[124:127], v[144:147]
	v_mfma_f32_16x16x32_bf16 v[48:51], v[108:111], v[124:127], v[48:51]
	v_mfma_f32_16x16x32_bf16 v[136:139], v[100:103], v[164:167], v[136:139]
	v_mfma_f32_16x16x32_bf16 v[40:43], v[108:111], v[164:167], v[40:43]
	v_mfma_f32_16x16x32_bf16 v[148:151], v[100:103], v[172:175], v[148:151]
	v_mfma_f32_16x16x32_bf16 v[52:55], v[108:111], v[172:175], v[52:55]
	v_mfma_f32_16x16x32_bf16 v[152:155], v[176:179], v[112:115], 0
	v_mfma_f32_16x16x32_bf16 v[56:59], v[184:187], v[112:115], 0
	v_mfma_f32_16x16x32_bf16 v[36:39], v[184:187], v[120:123], 0
	v_mfma_f32_16x16x32_bf16 v[32:35], v[184:187], v[160:163], 0
	v_mfma_f32_16x16x32_bf16 v[44:47], v[184:187], v[168:171], 0
	v_mfma_f32_16x16x32_bf16 v[152:155], v[180:183], v[116:119], v[152:155]
	v_mfma_f32_16x16x32_bf16 v[56:59], v[188:191], v[116:119], v[56:59]
	v_mfma_f32_16x16x32_bf16 v[112:115], v[176:179], v[120:123], 0
	v_mfma_f32_16x16x32_bf16 v[36:39], v[188:191], v[124:127], v[36:39]
	v_mfma_f32_16x16x32_bf16 v[116:119], v[176:179], v[160:163], 0
	v_mfma_f32_16x16x32_bf16 v[32:35], v[188:191], v[164:167], v[32:35]
	v_mfma_f32_16x16x32_bf16 v[120:123], v[176:179], v[168:171], 0
	v_mfma_f32_16x16x32_bf16 v[44:47], v[188:191], v[172:175], v[44:47]
	v_mfma_f32_16x16x32_bf16 v[112:115], v[180:183], v[124:127], v[112:115]
	v_mfma_f32_16x16x32_bf16 v[116:119], v[180:183], v[164:167], v[116:119]
	v_mfma_f32_16x16x32_bf16 v[120:123], v[180:183], v[172:175], v[120:123]
	s_setprio 0
	s_barrier
	s_nop 1
	ds_read_b128 v[124:127], v244 offset:16384
	ds_read_b128 v[128:131], v244 offset:17408
	ds_read_b128 v[132:135], v244 offset:18432
	ds_read_b128 v[140:143], v244 offset:19456
	ds_read_b128 v[160:163], v244 offset:20480
	ds_read_b128 v[164:167], v244 offset:21504
	ds_read_b128 v[168:171], v244 offset:22528
	ds_read_b128 v[172:175], v244 offset:23552
	s_add_i32 s36, s72, s6
	v_lshl_add_u64 v[196:197], s[40:41], 0, v[214:215]
	s_mov_b32 m0, s36
	s_nop 0
	global_load_lds_dwordx4 v214, s[40:41]
	v_lshl_add_u64 v[198:199], s[40:41], 0, v[210:211]
	s_add_i32 m0, s36, 0x2000
	s_nop 0
	global_load_lds_dwordx4 v210, s[40:41]
	s_mov_b32 m0, s45
	v_lshl_add_u64 v[200:201], s[42:43], 0, v[216:217]
	global_load_lds_dwordx4 v216, s[42:43]
	v_lshl_add_u64 v[202:203], s[42:43], 0, v[212:213]
	s_mov_b32 m0, s46
	s_nop 0
	global_load_lds_dwordx4 v212, s[42:43]
	s_add_u32 s36, s40, 0x40000
	s_addc_u32 s37, s41, 0
	s_add_i32 s80, s73, s6
	s_mov_b32 m0, s80
	s_nop 0
	global_load_lds_dwordx4 v214, s[36:37]
	s_add_i32 m0, s80, 0x2000
	s_nop 0
	global_load_lds_dwordx4 v210, s[36:37]
	s_waitcnt vmcnt(6)
	s_waitcnt lgkmcnt(0)
	s_barrier
; #define PG8_STAGE(bufoff, gbase, voff) do { _Pragma("unroll") for (int _i = 0; _i < 2; ++_i) \
;         __builtin_amdgcn_global_load_lds((const unsigned*)((const char*)(gbase) + (voff)[_i]), (LAS unsigned*)(lds + (bufoff) + ldsw + _i * 8192), 16, 0, 0); } while (0)
; #define PG8_LDA(dst, b, h) do { _Pragma("unroll") for (int m = 0; m < 4; ++m) _Pragma("unroll") for (int k = 0; k < 2; ++k) dst[m][k] = *(const LAS bf16x8*)(lds + PG8_SA(b, h) + aoff + m * 2048 + k * 1024); } while (0)
; #define PG8_LDB(dst, b, h) do { _Pragma("unroll") for (int n = 0; n < 2; ++n) _Pragma("unroll") for (int k = 0; k < 2; ++k) dst[n][k] = *(const LAS bf16x8*)(lds + PG8_SB(b, h) + boff + n * 2048 + k * 1024); } while (0)
; #define PG8_MMA(ai, bj, At, Bt) do { __builtin_amdgcn_s_setprio(1); _Pragma("unroll") for (int m = 0; m < 4; ++m) _Pragma("unroll") for (int n = 0; n < 2; ++n) _Pragma("unroll") for (int k = 0; k < 2; ++k) \
;         acc[ai][bj][m][n] = __builtin_amdgcn_mfma_f32_16x16x32_bf16(Bt[n][k], At[m][k], acc[ai][bj][m][n], 0, 0, 0); __builtin_amdgcn_s_setprio(0); } while (0)
; #define PG8_WAIT_V(n) asm volatile("s_waitcnt vmcnt(" #n ")" ::: "memory")
; #define PG8_WAIT_L(n) asm volatile("s_waitcnt lgkmcnt(" #n ")" ::: "memory")
; #define PG8_BAR __builtin_amdgcn_s_barrier()
; #define PG8_SCHED __builtin_amdgcn_sched_barrier(0)
; template <class Epi>
; __device__ __forceinline__ void gemm_phase(LAS unsigned char* lds, const Gemm g, const StaticOrder& S, const Epi& E) {
;     ...
;             PG8_BAR; PG8_WAIT_L(0); PG8_MMA(1, 0, At, B0); PG8_BAR; PG8_SCHED;
;             PG8_STAGE(PG8_SB(0, 1), b2 + hstepB, voffB);
;             PG8_WAIT_V(6); PG8_BAR; PG8_MMA(1, 1, At, B1); PG8_BAR;
;             PG8_LDB(B0, 1, 0); PG8_SCHED; PG8_LDA(At, 1, 0); PG8_STAGE(PG8_SA(0, 1), a2 + hstepA, voffA);
;             PG8_WAIT_L(8); PG8_BAR; PG8_WAIT_L(0); PG8_MMA(0, 0, At, B0); PG8_BAR; PG8_SCHED;
;             PG8_LDB(B1, 1, 1); PG8_STAGE(PG8_SB(1, 0), b3, voffB);
	s_setprio 1
	v_mfma_f32_16x16x32_bf16 v[92:95], v[96:99], v[124:127], 0
	v_mfma_f32_16x16x32_bf16 v[28:31], v[104:107], v[124:127], 0
	v_mfma_f32_16x16x32_bf16 v[80:83], v[96:99], v[132:135], 0
	v_mfma_f32_16x16x32_bf16 v[16:19], v[104:107], v[132:135], 0
	v_mfma_f32_16x16x32_bf16 v[76:79], v[96:99], v[160:163], 0
	v_mfma_f32_16x16x32_bf16 v[12:15], v[104:107], v[160:163], 0
	v_mfma_f32_16x16x32_bf16 v[84:87], v[96:99], v[168:171], 0
	v_mfma_f32_16x16x32_bf16 v[20:23], v[104:107], v[168:171], 0
	v_mfma_f32_16x16x32_bf16 v[92:95], v[100:103], v[128:131], v[92:95]
	v_mfma_f32_16x16x32_bf16 v[28:31], v[108:111], v[128:131], v[28:31]
	v_mfma_f32_16x16x32_bf16 v[80:83], v[100:103], v[140:143], v[80:83]
	v_mfma_f32_16x16x32_bf16 v[16:19], v[108:111], v[140:143], v[16:19]
	v_mfma_f32_16x16x32_bf16 v[76:79], v[100:103], v[164:167], v[76:79]
	v_mfma_f32_16x16x32_bf16 v[12:15], v[108:111], v[164:167], v[12:15]
	v_mfma_f32_16x16x32_bf16 v[84:87], v[100:103], v[172:175], v[84:87]
	v_mfma_f32_16x16x32_bf16 v[20:23], v[108:111], v[172:175], v[20:23]
	v_mfma_f32_16x16x32_bf16 v[88:91], v[176:179], v[124:127], 0
	v_mfma_f32_16x16x32_bf16 v[24:27], v[184:187], v[124:127], 0
	v_mfma_f32_16x16x32_bf16 v[68:71], v[176:179], v[132:135], 0
	v_mfma_f32_16x16x32_bf16 v[4:7], v[184:187], v[132:135], 0
	v_mfma_f32_16x16x32_bf16 v[64:67], v[176:179], v[160:163], 0
	v_mfma_f32_16x16x32_bf16 v[0:3], v[184:187], v[160:163], 0
	v_mfma_f32_16x16x32_bf16 v[72:75], v[176:179], v[168:171], 0
	v_mfma_f32_16x16x32_bf16 v[8:11], v[184:187], v[168:171], 0
	v_mfma_f32_16x16x32_bf16 v[88:91], v[180:183], v[128:131], v[88:91]
	v_mfma_f32_16x16x32_bf16 v[24:27], v[188:191], v[128:131], v[24:27]
	v_mfma_f32_16x16x32_bf16 v[68:71], v[180:183], v[140:143], v[68:71]
	v_mfma_f32_16x16x32_bf16 v[4:7], v[188:191], v[140:143], v[4:7]
	v_mfma_f32_16x16x32_bf16 v[64:67], v[180:183], v[164:167], v[64:67]
	v_mfma_f32_16x16x32_bf16 v[0:3], v[188:191], v[164:167], v[0:3]
	v_mfma_f32_16x16x32_bf16 v[72:75], v[180:183], v[172:175], v[72:75]
	v_mfma_f32_16x16x32_bf16 v[8:11], v[188:191], v[172:175], v[8:11]
	s_setprio 0
	s_add_i32 s80, 0, 0x18000
	v_add_u32_e32 v108, s80, v235
	s_barrier
	ds_read_b128 v[96:99], v108
	ds_read_b128 v[100:103], v108 offset:1024
	ds_read_b128 v[104:107], v108 offset:2048
	ds_read_b128 v[108:111], v108 offset:3072
	s_add_u32 s36, s42, 0x40000
	s_addc_u32 s37, s43, 0
	s_mov_b32 m0, s47
	ds_read_b128 v[124:127], v244 offset:32768
	ds_read_b128 v[128:131], v244 offset:33792
	ds_read_b128 v[140:143], v244 offset:34816
	ds_read_b128 v[160:163], v244 offset:35840
	ds_read_b128 v[164:167], v244 offset:36864
	ds_read_b128 v[168:171], v244 offset:37888
	ds_read_b128 v[172:175], v244 offset:38912
	ds_read_b128 v[176:179], v244 offset:39936
	global_load_lds_dwordx4 v216, s[36:37]
	v_lshl_add_u64 v[132:133], s[36:37], 0, v[212:213]
	s_mov_b32 m0, s48
	s_nop 0
	global_load_lds_dwordx4 v212, s[36:37]
	s_add_i32 s42, 0, 0x1c000
	v_add_u32_e32 v132, s42, v235
	ds_read_b128 v[180:183], v132
	ds_read_b128 v[184:187], v132 offset:1024
	ds_read_b128 v[188:191], v132 offset:2048
	ds_read_b128 v[192:195], v132 offset:3072
	s_waitcnt lgkmcnt(0)
	s_barrier
	s_setprio 1
	v_mfma_f32_16x16x32_bf16 v[132:135], v[96:99], v[124:127], v[156:159]
	v_mfma_f32_16x16x32_bf16 v[156:159], v[100:103], v[128:131], v[132:135]
	v_mfma_f32_16x16x32_bf16 v[132:135], v[96:99], v[140:143], v[144:147]
	v_mfma_f32_16x16x32_bf16 v[144:147], v[100:103], v[160:163], v[132:135]
	v_mfma_f32_16x16x32_bf16 v[132:135], v[96:99], v[164:167], v[136:139]
	v_mfma_f32_16x16x32_bf16 v[60:63], v[104:107], v[124:127], v[60:63]
	v_mfma_f32_16x16x32_bf16 v[48:51], v[104:107], v[140:143], v[48:51]
	v_mfma_f32_16x16x32_bf16 v[136:139], v[100:103], v[168:171], v[132:135]
	v_mfma_f32_16x16x32_bf16 v[40:43], v[104:107], v[164:167], v[40:43]
	v_mfma_f32_16x16x32_bf16 v[132:135], v[96:99], v[172:175], v[148:151]
	v_mfma_f32_16x16x32_bf16 v[52:55], v[104:107], v[172:175], v[52:55]
	v_mfma_f32_16x16x32_bf16 v[60:63], v[108:111], v[128:131], v[60:63]
	v_mfma_f32_16x16x32_bf16 v[48:51], v[108:111], v[160:163], v[48:51]
	v_mfma_f32_16x16x32_bf16 v[40:43], v[108:111], v[168:171], v[40:43]
	v_mfma_f32_16x16x32_bf16 v[148:151], v[100:103], v[176:179], v[132:135]
	v_mfma_f32_16x16x32_bf16 v[52:55], v[108:111], v[176:179], v[52:55]
	v_mfma_f32_16x16x32_bf16 v[132:135], v[180:183], v[124:127], v[152:155]
	v_mfma_f32_16x16x32_bf16 v[112:115], v[180:183], v[140:143], v[112:115]
	v_mfma_f32_16x16x32_bf16 v[152:155], v[184:187], v[128:131], v[132:135]
	v_mfma_f32_16x16x32_bf16 v[56:59], v[188:191], v[124:127], v[56:59]
	v_mfma_f32_16x16x32_bf16 v[132:135], v[184:187], v[160:163], v[112:115]
	v_mfma_f32_16x16x32_bf16 v[112:115], v[180:183], v[164:167], v[116:119]
	v_mfma_f32_16x16x32_bf16 v[56:59], v[192:195], v[128:131], v[56:59]
	v_mfma_f32_16x16x32_bf16 v[36:39], v[188:191], v[140:143], v[36:39]
	v_mfma_f32_16x16x32_bf16 v[128:131], v[184:187], v[168:171], v[112:115]
	v_mfma_f32_16x16x32_bf16 v[32:35], v[188:191], v[164:167], v[32:35]
	v_mfma_f32_16x16x32_bf16 v[112:115], v[180:183], v[172:175], v[120:123]
	v_mfma_f32_16x16x32_bf16 v[44:47], v[188:191], v[172:175], v[44:47]
	v_mfma_f32_16x16x32_bf16 v[36:39], v[192:195], v[160:163], v[36:39]
	v_mfma_f32_16x16x32_bf16 v[32:35], v[192:195], v[168:171], v[32:35]
	v_mfma_f32_16x16x32_bf16 v[140:143], v[184:187], v[176:179], v[112:115]
	v_mfma_f32_16x16x32_bf16 v[44:47], v[192:195], v[176:179], v[44:47]
	s_setprio 0
	s_barrier
; #define PG8_STAGE(bufoff, gbase, voff) do { _Pragma("unroll") for (int _i = 0; _i < 2; ++_i) \
;         __builtin_amdgcn_global_load_lds((const unsigned*)((const char*)(gbase) + (voff)[_i]), (LAS unsigned*)(lds + (bufoff) + ldsw + _i * 8192), 16, 0, 0); } while (0)
; #define PG8_LDA(dst, b, h) do { _Pragma("unroll") for (int m = 0; m < 4; ++m) _Pragma("unroll") for (int k = 0; k < 2; ++k) dst[m][k] = *(const LAS bf16x8*)(lds + PG8_SA(b, h) + aoff + m * 2048 + k * 1024); } while (0)
; #define PG8_LDB(dst, b, h) do { _Pragma("unroll") for (int n = 0; n < 2; ++n) _Pragma("unroll") for (int k = 0; k < 2; ++k) dst[n][k] = *(const LAS bf16x8*)(lds + PG8_SB(b, h) + boff + n * 2048 + k * 1024); } while (0)
; #define PG8_MMA(ai, bj, At, Bt) do { __builtin_amdgcn_s_setprio(1); _Pragma("unroll") for (int m = 0; m < 4; ++m) _Pragma("unroll") for (int n = 0; n < 2; ++n) _Pragma("unroll") for (int k = 0; k < 2; ++k) \
;         acc[ai][bj][m][n] = __builtin_amdgcn_mfma_f32_16x16x32_bf16(Bt[n][k], At[m][k], acc[ai][bj][m][n], 0, 0, 0); __builtin_amdgcn_s_setprio(0); } while (0)
; #define PG8_WAIT_V(n) asm volatile("s_waitcnt vmcnt(" #n ")" ::: "memory")
; #define PG8_WAIT_L(n) asm volatile("s_waitcnt lgkmcnt(" #n ")" ::: "memory")
; #define PG8_BAR __builtin_amdgcn_s_barrier()
; #define PG8_SCHED __builtin_amdgcn_sched_barrier(0)
; template <class Epi>
; __device__ __forceinline__ void gemm_phase(LAS unsigned char* lds, const Gemm g, const StaticOrder& S, const Epi& E) {
;     ...
;             PG8_LDB(B0, 0, 0); PG8_SCHED; PG8_LDA(At, 0, 0); PG8_STAGE(PG8_SA(1, 1), a1 + hstepA, voffA);
;             PG8_WAIT_L(8); PG8_BAR; PG8_WAIT_L(0); PG8_MMA(0, 0, At, B0); PG8_BAR; PG8_SCHED;
;     ...
;             PG8_LDB(B0, 1, 0); PG8_SCHED; PG8_LDA(At, 1, 0); PG8_STAGE(PG8_SA(0, 1), a2 + hstepA, voffA);
;             PG8_WAIT_L(8); PG8_BAR; PG8_WAIT_L(0); PG8_MMA(0, 0, At, B0); PG8_BAR; PG8_SCHED;
;             PG8_LDB(B1, 1, 1); PG8_STAGE(PG8_SB(1, 0), b3, voffB);
;             PG8_BAR; PG8_WAIT_L(0); PG8_MMA(0, 1, At, B1); PG8_BAR;
;             PG8_LDA(At, 1, 1); PG8_STAGE(PG8_SA(1, 0), a3, voffA);
;             PG8_BAR; PG8_WAIT_L(0); PG8_MMA(1, 0, At, B0); PG8_BAR; PG8_SCHED;
;             PG8_STAGE(PG8_SB(1, 1), b3 + hstepB, voffB);
;             PG8_WAIT_V(6); PG8_BAR; PG8_MMA(1, 1, At, B1); PG8_BAR;
	s_nop 1
	ds_read_b128 v[112:115], v244 offset:49152
	ds_read_b128 v[116:119], v244 offset:50176
	ds_read_b128 v[120:123], v244 offset:51200
	ds_read_b128 v[124:127], v244 offset:52224
	ds_read_b128 v[160:163], v244 offset:53248
	ds_read_b128 v[164:167], v244 offset:54272
	ds_read_b128 v[168:171], v244 offset:55296
	ds_read_b128 v[172:175], v244 offset:56320
	s_add_i32 s36, s80, s6
	s_mov_b32 m0, s36
	s_nop 0
	s_add_u32 s100, s40, s14
	s_addc_u32 s101, s41, s15
	global_load_lds_dwordx4 v214, s[100:101]
	s_add_i32 m0, s36, 0x2000
	s_nop 0
	s_add_u32 s100, s40, s14
	s_addc_u32 s101, s41, s15
	global_load_lds_dwordx4 v210, s[100:101]
	s_mov_b32 m0, s68
	v_lshl_add_u64 v[254:255], v[200:201], 0, s[14:15]
	global_load_lds_dwordx4 v[254:255], off
	v_lshl_add_u64 v[254:255], v[202:203], 0, s[14:15]
	s_mov_b32 m0, s69
	s_nop 0
	global_load_lds_dwordx4 v[254:255], off
	s_add_u32 s36, s40, 0x40080
	s_addc_u32 s37, s41, 0
	s_add_i32 s40, s42, s6
	s_mov_b32 m0, s40
	s_nop 0
	global_load_lds_dwordx4 v214, s[36:37]
	s_add_i32 m0, s40, 0x2000
	s_nop 0
	global_load_lds_dwordx4 v210, s[36:37]
	s_waitcnt vmcnt(6)
	s_waitcnt lgkmcnt(0)
	s_barrier
	s_setprio 1
	v_mfma_f32_16x16x32_bf16 v[92:95], v[96:99], v[112:115], v[92:95]
	v_mfma_f32_16x16x32_bf16 v[28:31], v[104:107], v[112:115], v[28:31]
	v_mfma_f32_16x16x32_bf16 v[80:83], v[96:99], v[120:123], v[80:83]
	v_mfma_f32_16x16x32_bf16 v[16:19], v[104:107], v[120:123], v[16:19]
	v_mfma_f32_16x16x32_bf16 v[76:79], v[96:99], v[160:163], v[76:79]
	v_mfma_f32_16x16x32_bf16 v[12:15], v[104:107], v[160:163], v[12:15]
	v_mfma_f32_16x16x32_bf16 v[84:87], v[96:99], v[168:171], v[84:87]
	v_mfma_f32_16x16x32_bf16 v[20:23], v[104:107], v[168:171], v[20:23]
	v_mfma_f32_16x16x32_bf16 v[92:95], v[100:103], v[116:119], v[92:95]
	v_mfma_f32_16x16x32_bf16 v[28:31], v[108:111], v[116:119], v[28:31]
	v_mfma_f32_16x16x32_bf16 v[80:83], v[100:103], v[124:127], v[80:83]
	v_mfma_f32_16x16x32_bf16 v[16:19], v[108:111], v[124:127], v[16:19]
	v_mfma_f32_16x16x32_bf16 v[76:79], v[100:103], v[164:167], v[76:79]
	v_mfma_f32_16x16x32_bf16 v[12:15], v[108:111], v[164:167], v[12:15]
	v_mfma_f32_16x16x32_bf16 v[84:87], v[100:103], v[172:175], v[84:87]
	v_mfma_f32_16x16x32_bf16 v[20:23], v[108:111], v[172:175], v[20:23]
	v_mfma_f32_16x16x32_bf16 v[88:91], v[180:183], v[112:115], v[88:91]
	v_mfma_f32_16x16x32_bf16 v[24:27], v[188:191], v[112:115], v[24:27]
	v_mfma_f32_16x16x32_bf16 v[68:71], v[180:183], v[120:123], v[68:71]
	v_mfma_f32_16x16x32_bf16 v[4:7], v[188:191], v[120:123], v[4:7]
	v_mfma_f32_16x16x32_bf16 v[64:67], v[180:183], v[160:163], v[64:67]
	v_mfma_f32_16x16x32_bf16 v[0:3], v[188:191], v[160:163], v[0:3]
	v_mfma_f32_16x16x32_bf16 v[72:75], v[180:183], v[168:171], v[72:75]
	v_mfma_f32_16x16x32_bf16 v[8:11], v[188:191], v[168:171], v[8:11]
	v_mfma_f32_16x16x32_bf16 v[88:91], v[184:187], v[116:119], v[88:91]
	v_mfma_f32_16x16x32_bf16 v[24:27], v[192:195], v[116:119], v[24:27]
	v_mfma_f32_16x16x32_bf16 v[68:71], v[184:187], v[124:127], v[68:71]
	v_mfma_f32_16x16x32_bf16 v[4:7], v[192:195], v[124:127], v[4:7]
	v_mfma_f32_16x16x32_bf16 v[64:67], v[184:187], v[164:167], v[64:67]
	v_mfma_f32_16x16x32_bf16 v[0:3], v[192:195], v[164:167], v[0:3]
	v_mfma_f32_16x16x32_bf16 v[72:75], v[184:187], v[172:175], v[72:75]
	v_mfma_f32_16x16x32_bf16 v[8:11], v[192:195], v[172:175], v[8:11]
	s_setprio 0
	s_add_i32 s79, s79, 2
	s_add_u32 s77, s77, 0x100
	s_addc_u32 s78, s78, 0
	s_cmp_gt_u32 s79, 13
	s_mov_b64 s[36:37], s[38:39]
	s_barrier
.LBB0_309:
	ds_read_b128 v[96:99], v243
	ds_read_b128 v[100:103], v243 offset:1024
	ds_read_b128 v[104:107], v243 offset:2048
	ds_read_b128 v[108:111], v243 offset:3072
	s_add_u32 s38, s36, 0x100
	s_addc_u32 s39, s37, 0
	s_cmp_eq_u32 s79, 12
	s_cselect_b32 s43, s27, s39
	s_cselect_b32 s42, s75, s38
	s_cselect_b32 s41, s25, s78
	s_cselect_b32 s40, s76, s77
	s_add_i32 m0, s45, 0xc000
	ds_read_b128 v[112:115], v244
	ds_read_b128 v[116:119], v244 offset:1024
	ds_read_b128 v[120:123], v244 offset:2048
	ds_read_b128 v[124:127], v244 offset:3072
	ds_read_b128 v[160:163], v244 offset:4096
	ds_read_b128 v[164:167], v244 offset:5120
	ds_read_b128 v[168:171], v244 offset:6144
	ds_read_b128 v[172:175], v244 offset:7168
	global_load_lds_dwordx4 v224, s[36:37]
	s_add_i32 m0, s45, 0xe000
	s_nop 0
	global_load_lds_dwordx4 v226, s[36:37]
	ds_read_b128 v[176:179], v245
	ds_read_b128 v[180:183], v245 offset:1024
	ds_read_b128 v[184:187], v245 offset:2048
	ds_read_b128 v[188:191], v245 offset:3072
	s_waitcnt lgkmcnt(0)
	s_barrier
; #define PG8_STAGE(bufoff, gbase, voff) do { _Pragma("unroll") for (int _i = 0; _i < 2; ++_i) \
;         __builtin_amdgcn_global_load_lds((const unsigned*)((const char*)(gbase) + (voff)[_i]), (LAS unsigned*)(lds + (bufoff) + ldsw + _i * 8192), 16, 0, 0); } while (0)
; #define PG8_LDA(dst, b, h) do { _Pragma("unroll") for (int m = 0; m < 4; ++m) _Pragma("unroll") for (int k = 0; k < 2; ++k) dst[m][k] = *(const LAS bf16x8*)(lds + PG8_SA(b, h) + aoff + m * 2048 + k * 1024); } while (0)
; #define PG8_LDB(dst, b, h) do { _Pragma("unroll") for (int n = 0; n < 2; ++n) _Pragma("unroll") for (int k = 0; k < 2; ++k) dst[n][k] = *(const LAS bf16x8*)(lds + PG8_SB(b, h) + boff + n * 2048 + k * 1024); } while (0)
; #define PG8_MMA(ai, bj, At, Bt) do { __builtin_amdgcn_s_setprio(1); _Pragma("unroll") for (int m = 0; m < 4; ++m) _Pragma("unroll") for (int n = 0; n < 2; ++n) _Pragma("unroll") for (int k = 0; k < 2; ++k) \
;         acc[ai][bj][m][n] = __builtin_amdgcn_mfma_f32_16x16x32_bf16(Bt[n][k], At[m][k], acc[ai][bj][m][n], 0, 0, 0); __builtin_amdgcn_s_setprio(0); } while (0)
; #define PG8_WAIT_V(n) asm volatile("s_waitcnt vmcnt(" #n ")" ::: "memory")
; #define PG8_WAIT_L(n) asm volatile("s_waitcnt lgkmcnt(" #n ")" ::: "memory")
; #define PG8_BAR __builtin_amdgcn_s_barrier()
; #define PG8_SCHED __builtin_amdgcn_sched_barrier(0)
; template <class Epi>
; __device__ __forceinline__ void gemm_phase(LAS unsigned char* lds, const Gemm g, const StaticOrder& S, const Epi& E) {
;     ...
;             PG8_WAIT_L(8); PG8_BAR; PG8_WAIT_L(0); PG8_MMA(0, 0, At, B0); PG8_BAR; PG8_SCHED;
;             PG8_LDB(B1, 0, 1); PG8_STAGE(PG8_SB(0, 0), b2, voffB);
;             PG8_BAR; PG8_WAIT_L(0); PG8_MMA(0, 1, At, B1); PG8_BAR;
;             PG8_LDA(At, 0, 1); PG8_STAGE(PG8_SA(0, 0), a2, voffA);
;             PG8_BAR; PG8_WAIT_L(0); PG8_MMA(1, 0, At, B0); PG8_BAR; PG8_SCHED;
;             PG8_STAGE(PG8_SB(0, 1), b2 + hstepB, voffB);
;             PG8_WAIT_V(6); PG8_BAR; PG8_MMA(1, 1, At, B1); PG8_BAR;
	s_setprio 1
	v_mfma_f32_16x16x32_bf16 v[156:159], v[96:99], v[112:115], v[156:159]
	v_mfma_f32_16x16x32_bf16 v[60:63], v[104:107], v[112:115], v[60:63]
	v_mfma_f32_16x16x32_bf16 v[144:147], v[96:99], v[120:123], v[144:147]
	v_mfma_f32_16x16x32_bf16 v[48:51], v[104:107], v[120:123], v[48:51]
	v_mfma_f32_16x16x32_bf16 v[136:139], v[96:99], v[160:163], v[136:139]
	v_mfma_f32_16x16x32_bf16 v[40:43], v[104:107], v[160:163], v[40:43]
	v_mfma_f32_16x16x32_bf16 v[148:151], v[96:99], v[168:171], v[148:151]
	v_mfma_f32_16x16x32_bf16 v[52:55], v[104:107], v[168:171], v[52:55]
	v_mfma_f32_16x16x32_bf16 v[156:159], v[100:103], v[116:119], v[156:159]
	v_mfma_f32_16x16x32_bf16 v[60:63], v[108:111], v[116:119], v[60:63]
	v_mfma_f32_16x16x32_bf16 v[144:147], v[100:103], v[124:127], v[144:147]
	v_mfma_f32_16x16x32_bf16 v[48:51], v[108:111], v[124:127], v[48:51]
	v_mfma_f32_16x16x32_bf16 v[136:139], v[100:103], v[164:167], v[136:139]
	v_mfma_f32_16x16x32_bf16 v[40:43], v[108:111], v[164:167], v[40:43]
	v_mfma_f32_16x16x32_bf16 v[148:151], v[100:103], v[172:175], v[148:151]
	v_mfma_f32_16x16x32_bf16 v[52:55], v[108:111], v[172:175], v[52:55]
	v_mfma_f32_16x16x32_bf16 v[152:155], v[176:179], v[112:115], v[152:155]
	v_mfma_f32_16x16x32_bf16 v[56:59], v[184:187], v[112:115], v[56:59]
	v_mfma_f32_16x16x32_bf16 v[36:39], v[184:187], v[120:123], v[36:39]
	v_mfma_f32_16x16x32_bf16 v[32:35], v[184:187], v[160:163], v[32:35]
	v_mfma_f32_16x16x32_bf16 v[44:47], v[184:187], v[168:171], v[44:47]
	v_mfma_f32_16x16x32_bf16 v[152:155], v[180:183], v[116:119], v[152:155]
	v_mfma_f32_16x16x32_bf16 v[56:59], v[188:191], v[116:119], v[56:59]
	v_mfma_f32_16x16x32_bf16 v[112:115], v[176:179], v[120:123], v[132:135]
	v_mfma_f32_16x16x32_bf16 v[36:39], v[188:191], v[124:127], v[36:39]
	v_mfma_f32_16x16x32_bf16 v[116:119], v[176:179], v[160:163], v[128:131]
	v_mfma_f32_16x16x32_bf16 v[32:35], v[188:191], v[164:167], v[32:35]
	v_mfma_f32_16x16x32_bf16 v[120:123], v[176:179], v[168:171], v[140:143]
	v_mfma_f32_16x16x32_bf16 v[44:47], v[188:191], v[172:175], v[44:47]
	v_mfma_f32_16x16x32_bf16 v[112:115], v[180:183], v[124:127], v[112:115]
	v_mfma_f32_16x16x32_bf16 v[116:119], v[180:183], v[164:167], v[116:119]
	v_mfma_f32_16x16x32_bf16 v[120:123], v[180:183], v[172:175], v[120:123]
	s_setprio 0
	s_barrier
	s_nop 1
	ds_read_b128 v[124:127], v244 offset:16384
	ds_read_b128 v[128:131], v244 offset:17408
	ds_read_b128 v[132:135], v244 offset:18432
	ds_read_b128 v[140:143], v244 offset:19456
	ds_read_b128 v[160:163], v244 offset:20480
	ds_read_b128 v[164:167], v244 offset:21504
	ds_read_b128 v[168:171], v244 offset:22528
	ds_read_b128 v[172:175], v244 offset:23552
	s_add_i32 s36, s72, s6
	v_lshl_add_u64 v[196:197], s[40:41], 0, v[214:215]
	s_mov_b32 m0, s36
	s_nop 0
	global_load_lds_dwordx4 v214, s[40:41]
	v_lshl_add_u64 v[198:199], s[40:41], 0, v[210:211]
	s_add_i32 m0, s36, 0x2000
	s_nop 0
	global_load_lds_dwordx4 v210, s[40:41]
	s_mov_b32 m0, s45
	v_lshl_add_u64 v[200:201], s[42:43], 0, v[216:217]
	global_load_lds_dwordx4 v216, s[42:43]
	v_lshl_add_u64 v[202:203], s[42:43], 0, v[212:213]
	s_mov_b32 m0, s46
	s_nop 0
	global_load_lds_dwordx4 v212, s[42:43]
	s_add_u32 s36, s40, 0x40000
	s_addc_u32 s37, s41, 0
	s_add_i32 s80, s73, s6
	s_mov_b32 m0, s80
	s_nop 0
	global_load_lds_dwordx4 v214, s[36:37]
	s_add_i32 m0, s80, 0x2000
	s_nop 0
	global_load_lds_dwordx4 v210, s[36:37]
	s_waitcnt vmcnt(6)
	s_waitcnt lgkmcnt(0)
	s_barrier
	s_setprio 1
	v_mfma_f32_16x16x32_bf16 v[92:95], v[96:99], v[124:127], v[92:95]
	v_mfma_f32_16x16x32_bf16 v[28:31], v[104:107], v[124:127], v[28:31]
	v_mfma_f32_16x16x32_bf16 v[80:83], v[96:99], v[132:135], v[80:83]
	v_mfma_f32_16x16x32_bf16 v[16:19], v[104:107], v[132:135], v[16:19]
	v_mfma_f32_16x16x32_bf16 v[76:79], v[96:99], v[160:163], v[76:79]
	v_mfma_f32_16x16x32_bf16 v[12:15], v[104:107], v[160:163], v[12:15]
	v_mfma_f32_16x16x32_bf16 v[84:87], v[96:99], v[168:171], v[84:87]
	v_mfma_f32_16x16x32_bf16 v[20:23], v[104:107], v[168:171], v[20:23]
	v_mfma_f32_16x16x32_bf16 v[92:95], v[100:103], v[128:131], v[92:95]
	v_mfma_f32_16x16x32_bf16 v[28:31], v[108:111], v[128:131], v[28:31]
	v_mfma_f32_16x16x32_bf16 v[80:83], v[100:103], v[140:143], v[80:83]
	v_mfma_f32_16x16x32_bf16 v[16:19], v[108:111], v[140:143], v[16:19]
	v_mfma_f32_16x16x32_bf16 v[76:79], v[100:103], v[164:167], v[76:79]
	v_mfma_f32_16x16x32_bf16 v[12:15], v[108:111], v[164:167], v[12:15]
	v_mfma_f32_16x16x32_bf16 v[84:87], v[100:103], v[172:175], v[84:87]
	v_mfma_f32_16x16x32_bf16 v[20:23], v[108:111], v[172:175], v[20:23]
	v_mfma_f32_16x16x32_bf16 v[88:91], v[176:179], v[124:127], v[88:91]
	v_mfma_f32_16x16x32_bf16 v[24:27], v[184:187], v[124:127], v[24:27]
	v_mfma_f32_16x16x32_bf16 v[68:71], v[176:179], v[132:135], v[68:71]
	v_mfma_f32_16x16x32_bf16 v[4:7], v[184:187], v[132:135], v[4:7]
	v_mfma_f32_16x16x32_bf16 v[64:67], v[176:179], v[160:163], v[64:67]
	v_mfma_f32_16x16x32_bf16 v[0:3], v[184:187], v[160:163], v[0:3]
	v_mfma_f32_16x16x32_bf16 v[72:75], v[176:179], v[168:171], v[72:75]
	v_mfma_f32_16x16x32_bf16 v[8:11], v[184:187], v[168:171], v[8:11]
	v_mfma_f32_16x16x32_bf16 v[88:91], v[180:183], v[128:131], v[88:91]
	v_mfma_f32_16x16x32_bf16 v[24:27], v[188:191], v[128:131], v[24:27]
	v_mfma_f32_16x16x32_bf16 v[68:71], v[180:183], v[140:143], v[68:71]
	v_mfma_f32_16x16x32_bf16 v[4:7], v[188:191], v[140:143], v[4:7]
	v_mfma_f32_16x16x32_bf16 v[64:67], v[180:183], v[164:167], v[64:67]
	v_mfma_f32_16x16x32_bf16 v[0:3], v[188:191], v[164:167], v[0:3]
	v_mfma_f32_16x16x32_bf16 v[72:75], v[180:183], v[172:175], v[72:75]
	v_mfma_f32_16x16x32_bf16 v[8:11], v[188:191], v[172:175], v[8:11]
	s_setprio 0
	s_add_i32 s80, 0, 0x18000
	v_add_u32_e32 v108, s80, v235
	s_barrier
; #define PG8_STAGE(bufoff, gbase, voff) do { _Pragma("unroll") for (int _i = 0; _i < 2; ++_i) \
;         __builtin_amdgcn_global_load_lds((const unsigned*)((const char*)(gbase) + (voff)[_i]), (LAS unsigned*)(lds + (bufoff) + ldsw + _i * 8192), 16, 0, 0); } while (0)
; #define PG8_LDA(dst, b, h) do { _Pragma("unroll") for (int m = 0; m < 4; ++m) _Pragma("unroll") for (int k = 0; k < 2; ++k) dst[m][k] = *(const LAS bf16x8*)(lds + PG8_SA(b, h) + aoff + m * 2048 + k * 1024); } while (0)
; #define PG8_LDB(dst, b, h) do { _Pragma("unroll") for (int n = 0; n < 2; ++n) _Pragma("unroll") for (int k = 0; k < 2; ++k) dst[n][k] = *(const LAS bf16x8*)(lds + PG8_SB(b, h) + boff + n * 2048 + k * 1024); } while (0)
; #define PG8_MMA(ai, bj, At, Bt) do { __builtin_amdgcn_s_setprio(1); _Pragma("unroll") for (int m = 0; m < 4; ++m) _Pragma("unroll") for (int n = 0; n < 2; ++n) _Pragma("unroll") for (int k = 0; k < 2; ++k) \
;         acc[ai][bj][m][n] = __builtin_amdgcn_mfma_f32_16x16x32_bf16(Bt[n][k], At[m][k], acc[ai][bj][m][n], 0, 0, 0); __builtin_amdgcn_s_setprio(0); } while (0)
; #define PG8_WAIT_V(n) asm volatile("s_waitcnt vmcnt(" #n ")" ::: "memory")
; #define PG8_WAIT_L(n) asm volatile("s_waitcnt lgkmcnt(" #n ")" ::: "memory")
; #define PG8_BAR __builtin_amdgcn_s_barrier()
; #define PG8_SCHED __builtin_amdgcn_sched_barrier(0)
; template <class Epi>
; __device__ __forceinline__ void gemm_phase(LAS unsigned char* lds, const Gemm g, const StaticOrder& S, const Epi& E) {
;     ...
;             PG8_WAIT_V(6); PG8_BAR; PG8_MMA(1, 1, At, B1); PG8_BAR;
;             PG8_LDB(B0, 1, 0); PG8_SCHED; PG8_LDA(At, 1, 0); PG8_STAGE(PG8_SA(0, 1), a2 + hstepA, voffA);
;             PG8_WAIT_L(8); PG8_BAR; PG8_WAIT_L(0); PG8_MMA(0, 0, At, B0); PG8_BAR; PG8_SCHED;
;             PG8_LDB(B1, 1, 1); PG8_STAGE(PG8_SB(1, 0), b3, voffB);
;             PG8_BAR; PG8_WAIT_L(0); PG8_MMA(0, 1, At, B1); PG8_BAR;
;             PG8_LDA(At, 1, 1); PG8_STAGE(PG8_SA(1, 0), a3, voffA);
;             PG8_BAR; PG8_WAIT_L(0); PG8_MMA(1, 0, At, B0); PG8_BAR; PG8_SCHED;
;             PG8_STAGE(PG8_SB(1, 1), b3 + hstepB, voffB);
;             PG8_WAIT_V(6); PG8_BAR; PG8_MMA(1, 1, At, B1); PG8_BAR;
	ds_read_b128 v[96:99], v108
	ds_read_b128 v[100:103], v108 offset:1024
	ds_read_b128 v[104:107], v108 offset:2048
	ds_read_b128 v[108:111], v108 offset:3072
	s_add_u32 s36, s42, 0x40000
	s_addc_u32 s37, s43, 0
	s_mov_b32 m0, s47
	ds_read_b128 v[124:127], v244 offset:32768
	ds_read_b128 v[128:131], v244 offset:33792
	ds_read_b128 v[140:143], v244 offset:34816
	ds_read_b128 v[160:163], v244 offset:35840
	ds_read_b128 v[164:167], v244 offset:36864
	ds_read_b128 v[168:171], v244 offset:37888
	ds_read_b128 v[172:175], v244 offset:38912
	ds_read_b128 v[176:179], v244 offset:39936
	global_load_lds_dwordx4 v216, s[36:37]
	v_lshl_add_u64 v[132:133], s[36:37], 0, v[212:213]
	s_mov_b32 m0, s48
	s_nop 0
	global_load_lds_dwordx4 v212, s[36:37]
	s_add_i32 s42, 0, 0x1c000
	v_add_u32_e32 v132, s42, v235
	ds_read_b128 v[180:183], v132
	ds_read_b128 v[184:187], v132 offset:1024
	ds_read_b128 v[188:191], v132 offset:2048
	ds_read_b128 v[192:195], v132 offset:3072
	s_waitcnt lgkmcnt(0)
	s_barrier
	s_setprio 1
	v_mfma_f32_16x16x32_bf16 v[132:135], v[96:99], v[124:127], v[156:159]
	v_mfma_f32_16x16x32_bf16 v[156:159], v[100:103], v[128:131], v[132:135]
	v_mfma_f32_16x16x32_bf16 v[132:135], v[96:99], v[140:143], v[144:147]
	v_mfma_f32_16x16x32_bf16 v[144:147], v[100:103], v[160:163], v[132:135]
	v_mfma_f32_16x16x32_bf16 v[132:135], v[96:99], v[164:167], v[136:139]
	v_mfma_f32_16x16x32_bf16 v[60:63], v[104:107], v[124:127], v[60:63]
	v_mfma_f32_16x16x32_bf16 v[48:51], v[104:107], v[140:143], v[48:51]
	v_mfma_f32_16x16x32_bf16 v[136:139], v[100:103], v[168:171], v[132:135]
	v_mfma_f32_16x16x32_bf16 v[40:43], v[104:107], v[164:167], v[40:43]
	v_mfma_f32_16x16x32_bf16 v[132:135], v[96:99], v[172:175], v[148:151]
	v_mfma_f32_16x16x32_bf16 v[52:55], v[104:107], v[172:175], v[52:55]
	v_mfma_f32_16x16x32_bf16 v[60:63], v[108:111], v[128:131], v[60:63]
	v_mfma_f32_16x16x32_bf16 v[48:51], v[108:111], v[160:163], v[48:51]
	v_mfma_f32_16x16x32_bf16 v[40:43], v[108:111], v[168:171], v[40:43]
	v_mfma_f32_16x16x32_bf16 v[148:151], v[100:103], v[176:179], v[132:135]
	v_mfma_f32_16x16x32_bf16 v[52:55], v[108:111], v[176:179], v[52:55]
	v_mfma_f32_16x16x32_bf16 v[132:135], v[180:183], v[124:127], v[152:155]
	v_mfma_f32_16x16x32_bf16 v[112:115], v[180:183], v[140:143], v[112:115]
	v_mfma_f32_16x16x32_bf16 v[152:155], v[184:187], v[128:131], v[132:135]
	v_mfma_f32_16x16x32_bf16 v[56:59], v[188:191], v[124:127], v[56:59]
	v_mfma_f32_16x16x32_bf16 v[132:135], v[184:187], v[160:163], v[112:115]
	v_mfma_f32_16x16x32_bf16 v[112:115], v[180:183], v[164:167], v[116:119]
	v_mfma_f32_16x16x32_bf16 v[56:59], v[192:195], v[128:131], v[56:59]
	v_mfma_f32_16x16x32_bf16 v[36:39], v[188:191], v[140:143], v[36:39]
	v_mfma_f32_16x16x32_bf16 v[128:131], v[184:187], v[168:171], v[112:115]
	v_mfma_f32_16x16x32_bf16 v[32:35], v[188:191], v[164:167], v[32:35]
	v_mfma_f32_16x16x32_bf16 v[112:115], v[180:183], v[172:175], v[120:123]
	v_mfma_f32_16x16x32_bf16 v[44:47], v[188:191], v[172:175], v[44:47]
	v_mfma_f32_16x16x32_bf16 v[36:39], v[192:195], v[160:163], v[36:39]
	v_mfma_f32_16x16x32_bf16 v[32:35], v[192:195], v[168:171], v[32:35]
	v_mfma_f32_16x16x32_bf16 v[140:143], v[184:187], v[176:179], v[112:115]
	v_mfma_f32_16x16x32_bf16 v[44:47], v[192:195], v[176:179], v[44:47]
	s_setprio 0
	s_barrier
	s_nop 1
	ds_read_b128 v[112:115], v244 offset:49152
	ds_read_b128 v[116:119], v244 offset:50176
	ds_read_b128 v[120:123], v244 offset:51200
	ds_read_b128 v[124:127], v244 offset:52224
	ds_read_b128 v[160:163], v244 offset:53248
	ds_read_b128 v[164:167], v244 offset:54272
	ds_read_b128 v[168:171], v244 offset:55296
	ds_read_b128 v[172:175], v244 offset:56320
	s_add_i32 s36, s80, s6
	s_mov_b32 m0, s36
	s_nop 0
	s_add_u32 s100, s40, s14
	s_addc_u32 s101, s41, s15
	global_load_lds_dwordx4 v214, s[100:101]
	s_add_i32 m0, s36, 0x2000
	s_nop 0
	s_add_u32 s100, s40, s14
	s_addc_u32 s101, s41, s15
	global_load_lds_dwordx4 v210, s[100:101]
	s_mov_b32 m0, s68
	v_lshl_add_u64 v[254:255], v[200:201], 0, s[14:15]
	global_load_lds_dwordx4 v[254:255], off
	v_lshl_add_u64 v[254:255], v[202:203], 0, s[14:15]
	s_mov_b32 m0, s69
	s_nop 0
	global_load_lds_dwordx4 v[254:255], off
	s_add_u32 s36, s40, 0x40080
	s_addc_u32 s37, s41, 0
	s_add_i32 s40, s42, s6
	s_mov_b32 m0, s40
	s_nop 0
	global_load_lds_dwordx4 v214, s[36:37]
	s_add_i32 m0, s40, 0x2000
	s_nop 0
	global_load_lds_dwordx4 v210, s[36:37]
	s_waitcnt vmcnt(6)
	s_waitcnt lgkmcnt(0)
	s_barrier
; #define LAS __attribute__((address_space(3)))
; #define PG8_STAGE(bufoff, gbase, voff) do { _Pragma("unroll") for (int _i = 0; _i < 2; ++_i) \
;         __builtin_amdgcn_global_load_lds((const unsigned*)((const char*)(gbase) + (voff)[_i]), (LAS unsigned*)(lds + (bufoff) + ldsw + _i * 8192), 16, 0, 0); } while (0)
; #define PG8_LDA(dst, b, h) do { _Pragma("unroll") for (int m = 0; m < 4; ++m) _Pragma("unroll") for (int k = 0; k < 2; ++k) dst[m][k] = *(const LAS bf16x8*)(lds + PG8_SA(b, h) + aoff + m * 2048 + k * 1024); } while (0)
; #define PG8_WAIT_V(n) asm volatile("s_waitcnt vmcnt(" #n ")" ::: "memory")
; #define PG8_WAIT_L(n) asm volatile("s_waitcnt lgkmcnt(" #n ")" ::: "memory")
; #define PG8_BAR __builtin_amdgcn_s_barrier()
; #define PG8_SCHED __builtin_amdgcn_sched_barrier(0)
; template <class Epi>
; __device__ __forceinline__ void gemm_phase(LAS unsigned char* lds, const Gemm g, const StaticOrder& S, const Epi& E) {
;     ...
;             PG8_BAR; PG8_WAIT_L(0); PG8_MMA(0, 1, At, B1); PG8_BAR;
;             PG8_LDA(At, 1, 1); PG8_STAGE(PG8_SA(1, 0), a3, voffA);
;             PG8_BAR; PG8_WAIT_L(0); PG8_MMA(1, 0, At, B0); PG8_BAR; PG8_SCHED;
;             PG8_STAGE(PG8_SB(1, 1), b3 + hstepB, voffB);
;             PG8_WAIT_V(6); PG8_BAR; PG8_MMA(1, 1, At, B1); PG8_BAR;
;     __device__ __forceinline__ void operator()(AccRef acc, const Unit& u, int wr, int wc, int fr, int fq) const {
;         const int clb = 32 * wc + 8 * fq;
;         f32x4 cwv[2][8];
;         { const float* cv = cw + 128 * u.pn + clb; const float* cg = cv + FH; const float* bp = cb + 128 * u.pn + clb;
;           cwv[0][0] = *(const f32x4*)(cv); cwv[0][1] = *(const f32x4*)(cv + F2); cwv[0][2] = *(const f32x4*)(cv + 2 * F2); cwv[0][3] = *(const f32x4*)(bp);
;           cwv[0][4] = *(const f32x4*)(cg); cwv[0][5] = *(const f32x4*)(cg + F2); cwv[0][6] = *(const f32x4*)(cg + 2 * F2); cwv[0][7] = *(const f32x4*)(bp + FH); }
;         if (fr == 15) {
; #pragma unroll
;             for (int ai = 0; ai < 2; ++ai)
; #pragma unroll
;                 for (int bj = 0; bj < 2; ++bj)
; #pragma unroll
;                     for (int n = 0; n < 2; ++n) { *(LAS f32x4*)(xch + ((ai * 2 + wr) * 2 + 0) * 256 + bj * 128 + clb + 4 * n) = acc[ai][bj][2][n]; *(LAS f32x4*)(xch + ((ai * 2 + wr) * 2 + 1) * 256 + bj * 128 + clb + 4 * n) = acc[ai][bj][3][n]; }
	s_setprio 1
	v_mfma_f32_16x16x32_bf16 v[92:95], v[96:99], v[112:115], v[92:95]
	v_mfma_f32_16x16x32_bf16 v[28:31], v[104:107], v[112:115], v[28:31]
	v_mfma_f32_16x16x32_bf16 v[80:83], v[96:99], v[120:123], v[80:83]
	v_mfma_f32_16x16x32_bf16 v[16:19], v[104:107], v[120:123], v[16:19]
	v_mfma_f32_16x16x32_bf16 v[76:79], v[96:99], v[160:163], v[76:79]
	v_mfma_f32_16x16x32_bf16 v[12:15], v[104:107], v[160:163], v[12:15]
	v_mfma_f32_16x16x32_bf16 v[84:87], v[96:99], v[168:171], v[84:87]
	v_mfma_f32_16x16x32_bf16 v[20:23], v[104:107], v[168:171], v[20:23]
	v_mfma_f32_16x16x32_bf16 v[92:95], v[100:103], v[116:119], v[92:95]
	v_mfma_f32_16x16x32_bf16 v[28:31], v[108:111], v[116:119], v[28:31]
	v_mfma_f32_16x16x32_bf16 v[80:83], v[100:103], v[124:127], v[80:83]
	v_mfma_f32_16x16x32_bf16 v[16:19], v[108:111], v[124:127], v[16:19]
	v_mfma_f32_16x16x32_bf16 v[76:79], v[100:103], v[164:167], v[76:79]
	v_mfma_f32_16x16x32_bf16 v[12:15], v[108:111], v[164:167], v[12:15]
	v_mfma_f32_16x16x32_bf16 v[84:87], v[100:103], v[172:175], v[84:87]
	v_mfma_f32_16x16x32_bf16 v[20:23], v[108:111], v[172:175], v[20:23]
	v_mfma_f32_16x16x32_bf16 v[88:91], v[180:183], v[112:115], v[88:91]
	v_mfma_f32_16x16x32_bf16 v[24:27], v[188:191], v[112:115], v[24:27]
	v_mfma_f32_16x16x32_bf16 v[68:71], v[180:183], v[120:123], v[68:71]
	v_mfma_f32_16x16x32_bf16 v[4:7], v[188:191], v[120:123], v[4:7]
	v_mfma_f32_16x16x32_bf16 v[64:67], v[180:183], v[160:163], v[64:67]
	v_mfma_f32_16x16x32_bf16 v[0:3], v[188:191], v[160:163], v[0:3]
	v_mfma_f32_16x16x32_bf16 v[72:75], v[180:183], v[168:171], v[72:75]
	v_mfma_f32_16x16x32_bf16 v[8:11], v[188:191], v[168:171], v[8:11]
	v_mfma_f32_16x16x32_bf16 v[88:91], v[184:187], v[116:119], v[88:91]
	v_mfma_f32_16x16x32_bf16 v[24:27], v[192:195], v[116:119], v[24:27]
	v_mfma_f32_16x16x32_bf16 v[68:71], v[184:187], v[124:127], v[68:71]
	v_mfma_f32_16x16x32_bf16 v[4:7], v[192:195], v[124:127], v[4:7]
	v_mfma_f32_16x16x32_bf16 v[64:67], v[184:187], v[164:167], v[64:67]
	v_mfma_f32_16x16x32_bf16 v[0:3], v[192:195], v[164:167], v[0:3]
	v_mfma_f32_16x16x32_bf16 v[72:75], v[184:187], v[172:175], v[72:75]
	v_mfma_f32_16x16x32_bf16 v[8:11], v[192:195], v[172:175], v[8:11]
	s_setprio 0
	s_add_i32 s79, s79, 2
	s_add_u32 s77, s77, 0x100
	s_addc_u32 s78, s78, 0
	s_cmp_gt_u32 s79, 13
	s_mov_b64 s[36:37], s[38:39]
	s_barrier
	s_cbranch_scc0 .LBB0_309
	s_lshl_b32 s36, s35, 7
	s_ashr_i32 s37, s36, 31
	s_lshl_b64 s[38:39], s[36:37], 2
	v_lshl_add_u64 v[96:97], v[220:221], 0, s[38:39]
	v_add_co_u32_e32 v100, vcc, 0x5000, v96
	v_lshl_add_u64 v[98:99], v[222:223], 0, s[38:39]
	s_nop 0
	v_addc_co_u32_e32 v101, vcc, 0, v97, vcc
	v_add_co_u32_e32 v102, vcc, 0xb000, v96
	global_load_dwordx4 v[160:163], v[96:97], off
	s_nop 0
	v_addc_co_u32_e32 v103, vcc, 0, v97, vcc
	global_load_dwordx4 v[164:167], v[100:101], off offset:2048
	global_load_dwordx4 v[168:171], v[102:103], off
	global_load_dwordx4 v[172:175], v[98:99], off
	v_add_co_u32_e32 v100, vcc, s49, v96
	s_nop 1
	v_addc_co_u32_e32 v101, vcc, 0, v97, vcc
	v_add_co_u32_e32 v102, vcc, 0x8000, v96
	s_nop 1
	v_addc_co_u32_e32 v103, vcc, 0, v97, vcc
	v_add_co_u32_e32 v96, vcc, 0xd000, v96
	global_load_dwordx4 v[176:179], v[100:101], off offset:3072
	global_load_dwordx4 v[180:183], v[102:103], off offset:1024
	v_addc_co_u32_e32 v97, vcc, 0, v97, vcc
	global_load_dwordx4 v[184:187], v[96:97], off offset:3072
	v_add_co_u32_e32 v96, vcc, 0x2000, v98
	s_nop 1
	v_addc_co_u32_e32 v97, vcc, 0, v99, vcc
	global_load_dwordx4 v[188:191], v[96:97], off offset:3072
	s_and_saveexec_b64 s[38:39], s[8:9]
	s_cbranch_execz .LBB0_312
	ds_write_b128 v237, v[136:139]
	ds_write_b128 v237, v[148:151] offset:1024
	ds_write_b128 v237, v[40:43] offset:16
	ds_write_b128 v237, v[52:55] offset:1040
	ds_write_b128 v237, v[128:131] offset:512
	ds_write_b128 v237, v[140:143] offset:1536
	ds_write_b128 v237, v[32:35] offset:528
	ds_write_b128 v237, v[44:47] offset:1552
	ds_write_b128 v237, v[76:79] offset:4096
	ds_write_b128 v237, v[84:87] offset:5120
	ds_write_b128 v237, v[12:15] offset:4112
	ds_write_b128 v237, v[20:23] offset:5136
	ds_write_b128 v237, v[64:67] offset:4608
	ds_write_b128 v237, v[72:75] offset:5632
	ds_write_b128 v237, v[0:3] offset:4624
	ds_write_b128 v237, v[8:11] offset:5648

; #define PG8_STAGE(bufoff, gbase, voff) do { _Pragma("unroll") for (int _i = 0; _i < 2; ++_i) \
;         __builtin_amdgcn_global_load_lds((const unsigned*)((const char*)(gbase) + (voff)[_i]), (LAS unsigned*)(lds + (bufoff) + ldsw + _i * 8192), 16, 0, 0); } while (0)
; #define PG8_LDA(dst, b, h) do { _Pragma("unroll") for (int m = 0; m < 4; ++m) _Pragma("unroll") for (int k = 0; k < 2; ++k) dst[m][k] = *(const LAS bf16x8*)(lds + PG8_SA(b, h) + aoff + m * 2048 + k * 1024); } while (0)
; #define PG8_LDB(dst, b, h) do { _Pragma("unroll") for (int n = 0; n < 2; ++n) _Pragma("unroll") for (int k = 0; k < 2; ++k) dst[n][k] = *(const LAS bf16x8*)(lds + PG8_SB(b, h) + boff + n * 2048 + k * 1024); } while (0)
; #define PG8_MMA(ai, bj, At, Bt) do { __builtin_amdgcn_s_setprio(1); _Pragma("unroll") for (int m = 0; m < 4; ++m) _Pragma("unroll") for (int n = 0; n < 2; ++n) _Pragma("unroll") for (int k = 0; k < 2; ++k) \
;         acc[ai][bj][m][n] = __builtin_amdgcn_mfma_f32_16x16x32_bf16(Bt[n][k], At[m][k], acc[ai][bj][m][n], 0, 0, 0); __builtin_amdgcn_s_setprio(0); } while (0)
; #define PG8_WAIT_V(n) asm volatile("s_waitcnt vmcnt(" #n ")" ::: "memory")
; #define PG8_WAIT_L(n) asm volatile("s_waitcnt lgkmcnt(" #n ")" ::: "memory")
; #define PG8_BAR __builtin_amdgcn_s_barrier()
; #define PG8_SCHED __builtin_amdgcn_sched_barrier(0)
; template <class Epi>
; __device__ __forceinline__ void gemm_phase(LAS unsigned char* lds, const Gemm g, const StaticOrder& S, const Epi& E) {
;     ...
;             PG8_LDB(B0, 0, 0); PG8_SCHED; PG8_LDA(At, 0, 0); PG8_STAGE(PG8_SA(1, 1), a1 + hstepA, voffA);
;             PG8_WAIT_L(8); PG8_BAR; PG8_WAIT_L(0); PG8_MMA(0, 0, At, B0); PG8_BAR; PG8_SCHED;
;             PG8_LDB(B1, 0, 1); PG8_STAGE(PG8_SB(0, 0), b2, voffB);
;             PG8_BAR; PG8_WAIT_L(0); PG8_MMA(0, 1, At, B1); PG8_BAR;
;             PG8_LDA(At, 0, 1); PG8_STAGE(PG8_SA(0, 0), a2, voffA);
;             PG8_BAR; PG8_WAIT_L(0); PG8_MMA(1, 0, At, B0); PG8_BAR; PG8_SCHED;
;             PG8_STAGE(PG8_SB(0, 1), b2 + hstepB, voffB);
;             PG8_WAIT_V(6); PG8_BAR; PG8_MMA(1, 1, At, B1); PG8_BAR;
.LBB0_410:
	s_add_u32 s49, s28, 0x100
	s_addc_u32 s63, s29, 0
	s_mov_b32 s68, -2
	ds_read_b128 v[140:143], v149
	ds_read_b128 v[152:155], v149 offset:1024
	ds_read_b128 v[156:159], v149 offset:2048
	ds_read_b128 v[160:163], v149 offset:3072
	s_add_u32 s28, s26, 0x100
	s_addc_u32 s29, s27, 0
	s_cmp_eq_u32 s68, 40
	s_cselect_b32 s35, s11, s29
	s_cselect_b32 s34, s10, s28
	s_cselect_b32 s31, s13, s63
	s_cselect_b32 s30, s12, s49
	s_add_i32 m0, s36, 0xc000
	ds_read_b128 v[164:167], v150
	ds_read_b128 v[168:171], v150 offset:1024
	ds_read_b128 v[172:175], v150 offset:2048
	ds_read_b128 v[176:179], v150 offset:3072
	ds_read_b128 v[180:183], v150 offset:4096
	ds_read_b128 v[184:187], v150 offset:5120
	ds_read_b128 v[188:191], v150 offset:6144
	ds_read_b128 v[192:195], v150 offset:7168
	global_load_lds_dwordx4 v132, s[26:27]
	s_add_i32 m0, s36, 0xe000
	s_nop 0
	global_load_lds_dwordx4 v134, s[26:27]
	ds_read_b128 v[196:199], v151
	ds_read_b128 v[200:203], v151 offset:1024
	ds_read_b128 v[204:207], v151 offset:2048
	ds_read_b128 v[208:211], v151 offset:3072
	s_waitcnt lgkmcnt(0)
	s_barrier
	s_setprio 1
	v_mfma_f32_16x16x32_bf16 v[124:127], v[140:143], v[164:167], 0
	v_mfma_f32_16x16x32_bf16 v[120:123], v[156:159], v[164:167], 0
	v_mfma_f32_16x16x32_bf16 v[112:115], v[140:143], v[172:175], 0
	v_mfma_f32_16x16x32_bf16 v[104:107], v[156:159], v[172:175], 0
	v_mfma_f32_16x16x32_bf16 v[92:95], v[140:143], v[180:183], 0
	v_mfma_f32_16x16x32_bf16 v[88:91], v[156:159], v[180:183], 0
	v_mfma_f32_16x16x32_bf16 v[80:83], v[140:143], v[188:191], 0
	v_mfma_f32_16x16x32_bf16 v[72:75], v[156:159], v[188:191], 0
	v_mfma_f32_16x16x32_bf16 v[124:127], v[152:155], v[168:171], v[124:127]
	v_mfma_f32_16x16x32_bf16 v[120:123], v[160:163], v[168:171], v[120:123]
	v_mfma_f32_16x16x32_bf16 v[112:115], v[152:155], v[176:179], v[112:115]
	v_mfma_f32_16x16x32_bf16 v[104:107], v[160:163], v[176:179], v[104:107]
	v_mfma_f32_16x16x32_bf16 v[92:95], v[152:155], v[184:187], v[92:95]
	v_mfma_f32_16x16x32_bf16 v[88:91], v[160:163], v[184:187], v[88:91]
	v_mfma_f32_16x16x32_bf16 v[80:83], v[152:155], v[192:195], v[80:83]
	v_mfma_f32_16x16x32_bf16 v[72:75], v[160:163], v[192:195], v[72:75]
	v_mfma_f32_16x16x32_bf16 v[116:119], v[196:199], v[164:167], 0
	v_mfma_f32_16x16x32_bf16 v[108:111], v[204:207], v[164:167], 0
	v_mfma_f32_16x16x32_bf16 v[100:103], v[196:199], v[172:175], 0
	v_mfma_f32_16x16x32_bf16 v[96:99], v[204:207], v[172:175], 0
	v_mfma_f32_16x16x32_bf16 v[84:87], v[196:199], v[180:183], 0
	v_mfma_f32_16x16x32_bf16 v[76:79], v[204:207], v[180:183], 0
	v_mfma_f32_16x16x32_bf16 v[68:71], v[196:199], v[188:191], 0
	v_mfma_f32_16x16x32_bf16 v[64:67], v[204:207], v[188:191], 0
	v_mfma_f32_16x16x32_bf16 v[116:119], v[200:203], v[168:171], v[116:119]
	v_mfma_f32_16x16x32_bf16 v[108:111], v[208:211], v[168:171], v[108:111]
	v_mfma_f32_16x16x32_bf16 v[100:103], v[200:203], v[176:179], v[100:103]
	v_mfma_f32_16x16x32_bf16 v[96:99], v[208:211], v[176:179], v[96:99]
	v_mfma_f32_16x16x32_bf16 v[84:87], v[200:203], v[184:187], v[84:87]
	v_mfma_f32_16x16x32_bf16 v[76:79], v[208:211], v[184:187], v[76:79]
	v_mfma_f32_16x16x32_bf16 v[68:71], v[200:203], v[192:195], v[68:71]
	v_mfma_f32_16x16x32_bf16 v[64:67], v[208:211], v[192:195], v[64:67]
	s_setprio 0
	s_barrier
	s_nop 1
	ds_read_b128 v[164:167], v150 offset:16384
	ds_read_b128 v[168:171], v150 offset:17408
	ds_read_b128 v[172:175], v150 offset:18432
	ds_read_b128 v[176:179], v150 offset:19456
	ds_read_b128 v[180:183], v150 offset:20480
	ds_read_b128 v[184:187], v150 offset:21504
	ds_read_b128 v[188:191], v150 offset:22528
	ds_read_b128 v[192:195], v150 offset:23552
	s_add_i32 s26, s43, s7
	v_lshl_add_u64 v[144:145], s[30:31], 0, v[128:129]
	s_mov_b32 m0, s26
	s_nop 0
	global_load_lds_dwordx4 v128, s[30:31]
	v_lshl_add_u64 v[212:213], s[30:31], 0, v[130:131]
	s_add_i32 m0, s26, 0x2000
	s_nop 0
	global_load_lds_dwordx4 v130, s[30:31]
	s_mov_b32 m0, s36
	v_lshl_add_u64 v[214:215], s[34:35], 0, v[128:129]
	global_load_lds_dwordx4 v128, s[34:35]
	v_lshl_add_u64 v[216:217], s[34:35], 0, v[130:131]
	s_mov_b32 m0, s37
	s_nop 0
	global_load_lds_dwordx4 v130, s[34:35]
	s_add_u32 s26, s30, 0xb0000
	s_addc_u32 s27, s31, 0
	s_add_i32 s69, s44, s7
	s_mov_b32 m0, s69
	s_nop 0
	global_load_lds_dwordx4 v128, s[26:27]
	s_add_i32 m0, s69, 0x2000
	s_nop 0
	global_load_lds_dwordx4 v130, s[26:27]
	s_waitcnt vmcnt(6)
	s_waitcnt lgkmcnt(0)
	s_barrier
	s_setprio 1
	v_mfma_f32_16x16x32_bf16 v[60:63], v[140:143], v[164:167], 0
	v_mfma_f32_16x16x32_bf16 v[56:59], v[156:159], v[164:167], 0
	v_mfma_f32_16x16x32_bf16 v[48:51], v[140:143], v[172:175], 0
	v_mfma_f32_16x16x32_bf16 v[40:43], v[156:159], v[172:175], 0
	v_mfma_f32_16x16x32_bf16 v[28:31], v[140:143], v[180:183], 0
	v_mfma_f32_16x16x32_bf16 v[24:27], v[156:159], v[180:183], 0
	v_mfma_f32_16x16x32_bf16 v[16:19], v[140:143], v[188:191], 0
	v_mfma_f32_16x16x32_bf16 v[8:11], v[156:159], v[188:191], 0
	v_mfma_f32_16x16x32_bf16 v[60:63], v[152:155], v[168:171], v[60:63]
	v_mfma_f32_16x16x32_bf16 v[56:59], v[160:163], v[168:171], v[56:59]
	v_mfma_f32_16x16x32_bf16 v[48:51], v[152:155], v[176:179], v[48:51]
	v_mfma_f32_16x16x32_bf16 v[40:43], v[160:163], v[176:179], v[40:43]
	v_mfma_f32_16x16x32_bf16 v[28:31], v[152:155], v[184:187], v[28:31]
	v_mfma_f32_16x16x32_bf16 v[24:27], v[160:163], v[184:187], v[24:27]
	v_mfma_f32_16x16x32_bf16 v[16:19], v[152:155], v[192:195], v[16:19]
	v_mfma_f32_16x16x32_bf16 v[8:11], v[160:163], v[192:195], v[8:11]
	v_mfma_f32_16x16x32_bf16 v[52:55], v[196:199], v[164:167], 0
	v_mfma_f32_16x16x32_bf16 v[44:47], v[204:207], v[164:167], 0
	v_mfma_f32_16x16x32_bf16 v[36:39], v[196:199], v[172:175], 0
	v_mfma_f32_16x16x32_bf16 v[32:35], v[204:207], v[172:175], 0
	v_mfma_f32_16x16x32_bf16 v[20:23], v[196:199], v[180:183], 0
	v_mfma_f32_16x16x32_bf16 v[12:15], v[204:207], v[180:183], 0
	v_mfma_f32_16x16x32_bf16 v[4:7], v[196:199], v[188:191], 0
	v_mfma_f32_16x16x32_bf16 v[0:3], v[204:207], v[188:191], 0
	v_mfma_f32_16x16x32_bf16 v[52:55], v[200:203], v[168:171], v[52:55]
	v_mfma_f32_16x16x32_bf16 v[44:47], v[208:211], v[168:171], v[44:47]
	v_mfma_f32_16x16x32_bf16 v[36:39], v[200:203], v[176:179], v[36:39]
	v_mfma_f32_16x16x32_bf16 v[32:35], v[208:211], v[176:179], v[32:35]
	v_mfma_f32_16x16x32_bf16 v[20:23], v[200:203], v[184:187], v[20:23]
	v_mfma_f32_16x16x32_bf16 v[12:15], v[208:211], v[184:187], v[12:15]
	v_mfma_f32_16x16x32_bf16 v[4:7], v[200:203], v[192:195], v[4:7]
	v_mfma_f32_16x16x32_bf16 v[0:3], v[208:211], v[192:195], v[0:3]
	s_setprio 0
	s_add_i32 s69, 0, 0x18000
	v_add_u32_e32 v160, s69, v147
	s_barrier
; #define PG8_STAGE(bufoff, gbase, voff) do { _Pragma("unroll") for (int _i = 0; _i < 2; ++_i) \
;         __builtin_amdgcn_global_load_lds((const unsigned*)((const char*)(gbase) + (voff)[_i]), (LAS unsigned*)(lds + (bufoff) + ldsw + _i * 8192), 16, 0, 0); } while (0)
; #define PG8_LDA(dst, b, h) do { _Pragma("unroll") for (int m = 0; m < 4; ++m) _Pragma("unroll") for (int k = 0; k < 2; ++k) dst[m][k] = *(const LAS bf16x8*)(lds + PG8_SA(b, h) + aoff + m * 2048 + k * 1024); } while (0)
; #define PG8_LDB(dst, b, h) do { _Pragma("unroll") for (int n = 0; n < 2; ++n) _Pragma("unroll") for (int k = 0; k < 2; ++k) dst[n][k] = *(const LAS bf16x8*)(lds + PG8_SB(b, h) + boff + n * 2048 + k * 1024); } while (0)
; #define PG8_MMA(ai, bj, At, Bt) do { __builtin_amdgcn_s_setprio(1); _Pragma("unroll") for (int m = 0; m < 4; ++m) _Pragma("unroll") for (int n = 0; n < 2; ++n) _Pragma("unroll") for (int k = 0; k < 2; ++k) \
;         acc[ai][bj][m][n] = __builtin_amdgcn_mfma_f32_16x16x32_bf16(Bt[n][k], At[m][k], acc[ai][bj][m][n], 0, 0, 0); __builtin_amdgcn_s_setprio(0); } while (0)
; #define PG8_WAIT_V(n) asm volatile("s_waitcnt vmcnt(" #n ")" ::: "memory")
; #define PG8_WAIT_L(n) asm volatile("s_waitcnt lgkmcnt(" #n ")" ::: "memory")
; #define PG8_BAR __builtin_amdgcn_s_barrier()
; #define PG8_SCHED __builtin_amdgcn_sched_barrier(0)
; template <class Epi>
; __device__ __forceinline__ void gemm_phase(LAS unsigned char* lds, const Gemm g, const StaticOrder& S, const Epi& E) {
;     ...
;             PG8_WAIT_V(6); PG8_BAR; PG8_MMA(1, 1, At, B1); PG8_BAR;
;             PG8_LDB(B0, 1, 0); PG8_SCHED; PG8_LDA(At, 1, 0); PG8_STAGE(PG8_SA(0, 1), a2 + hstepA, voffA);
;             PG8_WAIT_L(8); PG8_BAR; PG8_WAIT_L(0); PG8_MMA(0, 0, At, B0); PG8_BAR; PG8_SCHED;
;             PG8_LDB(B1, 1, 1); PG8_STAGE(PG8_SB(1, 0), b3, voffB);
;             PG8_BAR; PG8_WAIT_L(0); PG8_MMA(0, 1, At, B1); PG8_BAR;
;             PG8_LDA(At, 1, 1); PG8_STAGE(PG8_SA(1, 0), a3, voffA);
;             PG8_BAR; PG8_WAIT_L(0); PG8_MMA(1, 0, At, B0); PG8_BAR; PG8_SCHED;
;             PG8_STAGE(PG8_SB(1, 1), b3 + hstepB, voffB);
;             PG8_WAIT_V(6); PG8_BAR; PG8_MMA(1, 1, At, B1); PG8_BAR;
	ds_read_b128 v[140:143], v160
	ds_read_b128 v[152:155], v160 offset:1024
	ds_read_b128 v[156:159], v160 offset:2048
	ds_read_b128 v[160:163], v160 offset:3072
	s_add_u32 s26, s34, 0xb0000
	s_addc_u32 s27, s35, 0
	s_mov_b32 m0, s38
	ds_read_b128 v[164:167], v150 offset:32768
	ds_read_b128 v[168:171], v150 offset:33792
	ds_read_b128 v[172:175], v150 offset:34816
	ds_read_b128 v[176:179], v150 offset:35840
	ds_read_b128 v[180:183], v150 offset:36864
	ds_read_b128 v[184:187], v150 offset:37888
	ds_read_b128 v[188:191], v150 offset:38912
	ds_read_b128 v[192:195], v150 offset:39936
	global_load_lds_dwordx4 v128, s[26:27]
	s_mov_b32 m0, s39
	s_nop 0
	global_load_lds_dwordx4 v130, s[26:27]
	s_add_i32 s34, 0, 0x1c000
	v_add_u32_e32 v208, s34, v147
	ds_read_b128 v[196:199], v208
	ds_read_b128 v[200:203], v208 offset:1024
	ds_read_b128 v[204:207], v208 offset:2048
	ds_read_b128 v[208:211], v208 offset:3072
	s_waitcnt lgkmcnt(0)
	s_barrier
	s_setprio 1
	v_mfma_f32_16x16x32_bf16 v[124:127], v[140:143], v[164:167], v[124:127]
	v_mfma_f32_16x16x32_bf16 v[120:123], v[156:159], v[164:167], v[120:123]
	v_mfma_f32_16x16x32_bf16 v[112:115], v[140:143], v[172:175], v[112:115]
	v_mfma_f32_16x16x32_bf16 v[104:107], v[156:159], v[172:175], v[104:107]
	v_mfma_f32_16x16x32_bf16 v[92:95], v[140:143], v[180:183], v[92:95]
	v_mfma_f32_16x16x32_bf16 v[88:91], v[156:159], v[180:183], v[88:91]
	v_mfma_f32_16x16x32_bf16 v[80:83], v[140:143], v[188:191], v[80:83]
	v_mfma_f32_16x16x32_bf16 v[72:75], v[156:159], v[188:191], v[72:75]
	v_mfma_f32_16x16x32_bf16 v[124:127], v[152:155], v[168:171], v[124:127]
	v_mfma_f32_16x16x32_bf16 v[120:123], v[160:163], v[168:171], v[120:123]
	v_mfma_f32_16x16x32_bf16 v[112:115], v[152:155], v[176:179], v[112:115]
	v_mfma_f32_16x16x32_bf16 v[104:107], v[160:163], v[176:179], v[104:107]
	v_mfma_f32_16x16x32_bf16 v[92:95], v[152:155], v[184:187], v[92:95]
	v_mfma_f32_16x16x32_bf16 v[88:91], v[160:163], v[184:187], v[88:91]
	v_mfma_f32_16x16x32_bf16 v[80:83], v[152:155], v[192:195], v[80:83]
	v_mfma_f32_16x16x32_bf16 v[72:75], v[160:163], v[192:195], v[72:75]
	v_mfma_f32_16x16x32_bf16 v[116:119], v[196:199], v[164:167], v[116:119]
	v_mfma_f32_16x16x32_bf16 v[108:111], v[204:207], v[164:167], v[108:111]
	v_mfma_f32_16x16x32_bf16 v[100:103], v[196:199], v[172:175], v[100:103]
	v_mfma_f32_16x16x32_bf16 v[96:99], v[204:207], v[172:175], v[96:99]
	v_mfma_f32_16x16x32_bf16 v[84:87], v[196:199], v[180:183], v[84:87]
	v_mfma_f32_16x16x32_bf16 v[76:79], v[204:207], v[180:183], v[76:79]
	v_mfma_f32_16x16x32_bf16 v[68:71], v[196:199], v[188:191], v[68:71]
	v_mfma_f32_16x16x32_bf16 v[64:67], v[204:207], v[188:191], v[64:67]
	v_mfma_f32_16x16x32_bf16 v[116:119], v[200:203], v[168:171], v[116:119]
	v_mfma_f32_16x16x32_bf16 v[108:111], v[208:211], v[168:171], v[108:111]
	v_mfma_f32_16x16x32_bf16 v[100:103], v[200:203], v[176:179], v[100:103]
	v_mfma_f32_16x16x32_bf16 v[96:99], v[208:211], v[176:179], v[96:99]
	v_mfma_f32_16x16x32_bf16 v[84:87], v[200:203], v[184:187], v[84:87]
	v_mfma_f32_16x16x32_bf16 v[76:79], v[208:211], v[184:187], v[76:79]
	v_mfma_f32_16x16x32_bf16 v[68:71], v[200:203], v[192:195], v[68:71]
	v_mfma_f32_16x16x32_bf16 v[64:67], v[208:211], v[192:195], v[64:67]
	s_setprio 0
	s_barrier
	s_nop 1
	ds_read_b128 v[164:167], v150 offset:49152
	ds_read_b128 v[168:171], v150 offset:50176
	ds_read_b128 v[172:175], v150 offset:51200
	ds_read_b128 v[176:179], v150 offset:52224
	ds_read_b128 v[180:183], v150 offset:53248
	ds_read_b128 v[184:187], v150 offset:54272
	ds_read_b128 v[188:191], v150 offset:55296
	ds_read_b128 v[192:195], v150 offset:56320
	s_add_i32 s26, s69, s7
	s_mov_b32 m0, s26
	s_nop 0
	s_add_u32 s100, s30, s16
	s_addc_u32 s101, s31, s17
	global_load_lds_dwordx4 v128, s[100:101]
	s_add_i32 m0, s26, 0x2000
	s_nop 0
	s_add_u32 s100, s30, s16
	s_addc_u32 s101, s31, s17
	global_load_lds_dwordx4 v130, s[100:101]
	s_mov_b32 m0, s41
	v_lshl_add_u64 v[254:255], v[214:215], 0, s[16:17]
	global_load_lds_dwordx4 v[254:255], off
	v_lshl_add_u64 v[144:145], v[216:217], 0, s[16:17]
	s_mov_b32 m0, s42
	s_nop 0
	global_load_lds_dwordx4 v[144:145], off
	s_add_u32 s26, s30, 0xb0080
	s_addc_u32 s27, s31, 0
	s_add_i32 s30, s34, s7
	s_mov_b32 m0, s30
	s_nop 0
	global_load_lds_dwordx4 v128, s[26:27]
	s_add_i32 m0, s30, 0x2000
	s_nop 0
	global_load_lds_dwordx4 v130, s[26:27]
	s_waitcnt vmcnt(6)
	s_waitcnt lgkmcnt(0)
	s_barrier
	s_setprio 1
	v_mfma_f32_16x16x32_bf16 v[60:63], v[140:143], v[164:167], v[60:63]
	v_mfma_f32_16x16x32_bf16 v[56:59], v[156:159], v[164:167], v[56:59]
	v_mfma_f32_16x16x32_bf16 v[48:51], v[140:143], v[172:175], v[48:51]
	v_mfma_f32_16x16x32_bf16 v[40:43], v[156:159], v[172:175], v[40:43]
	v_mfma_f32_16x16x32_bf16 v[28:31], v[140:143], v[180:183], v[28:31]
	v_mfma_f32_16x16x32_bf16 v[24:27], v[156:159], v[180:183], v[24:27]
	v_mfma_f32_16x16x32_bf16 v[16:19], v[140:143], v[188:191], v[16:19]
	v_mfma_f32_16x16x32_bf16 v[8:11], v[156:159], v[188:191], v[8:11]
	v_mfma_f32_16x16x32_bf16 v[60:63], v[152:155], v[168:171], v[60:63]
	v_mfma_f32_16x16x32_bf16 v[56:59], v[160:163], v[168:171], v[56:59]
	v_mfma_f32_16x16x32_bf16 v[48:51], v[152:155], v[176:179], v[48:51]
	v_mfma_f32_16x16x32_bf16 v[40:43], v[160:163], v[176:179], v[40:43]
	v_mfma_f32_16x16x32_bf16 v[28:31], v[152:155], v[184:187], v[28:31]
	v_mfma_f32_16x16x32_bf16 v[24:27], v[160:163], v[184:187], v[24:27]
	v_mfma_f32_16x16x32_bf16 v[16:19], v[152:155], v[192:195], v[16:19]
	v_mfma_f32_16x16x32_bf16 v[8:11], v[160:163], v[192:195], v[8:11]
	v_mfma_f32_16x16x32_bf16 v[52:55], v[196:199], v[164:167], v[52:55]
	v_mfma_f32_16x16x32_bf16 v[44:47], v[204:207], v[164:167], v[44:47]
	v_mfma_f32_16x16x32_bf16 v[36:39], v[196:199], v[172:175], v[36:39]
	v_mfma_f32_16x16x32_bf16 v[32:35], v[204:207], v[172:175], v[32:35]
	v_mfma_f32_16x16x32_bf16 v[20:23], v[196:199], v[180:183], v[20:23]
	v_mfma_f32_16x16x32_bf16 v[12:15], v[204:207], v[180:183], v[12:15]
	v_mfma_f32_16x16x32_bf16 v[4:7], v[196:199], v[188:191], v[4:7]
	v_mfma_f32_16x16x32_bf16 v[0:3], v[204:207], v[188:191], v[0:3]
	v_mfma_f32_16x16x32_bf16 v[52:55], v[200:203], v[168:171], v[52:55]
	v_mfma_f32_16x16x32_bf16 v[44:47], v[208:211], v[168:171], v[44:47]
	v_mfma_f32_16x16x32_bf16 v[36:39], v[200:203], v[176:179], v[36:39]
	v_mfma_f32_16x16x32_bf16 v[32:35], v[208:211], v[176:179], v[32:35]
	v_mfma_f32_16x16x32_bf16 v[20:23], v[200:203], v[184:187], v[20:23]
	v_mfma_f32_16x16x32_bf16 v[12:15], v[208:211], v[184:187], v[12:15]
	v_mfma_f32_16x16x32_bf16 v[4:7], v[200:203], v[192:195], v[4:7]
	v_mfma_f32_16x16x32_bf16 v[0:3], v[208:211], v[192:195], v[0:3]
	s_setprio 0
	s_add_i32 s68, s68, 2
	s_add_u32 s49, s49, 0x100
	s_addc_u32 s63, s63, 0
	s_cmp_gt_u32 s68, 41
	s_mov_b64 s[26:27], s[28:29]
	s_barrier
; #define PG8_STAGE(bufoff, gbase, voff) do { _Pragma("unroll") for (int _i = 0; _i < 2; ++_i) \
;         __builtin_amdgcn_global_load_lds((const unsigned*)((const char*)(gbase) + (voff)[_i]), (LAS unsigned*)(lds + (bufoff) + ldsw + _i * 8192), 16, 0, 0); } while (0)
; #define PG8_LDA(dst, b, h) do { _Pragma("unroll") for (int m = 0; m < 4; ++m) _Pragma("unroll") for (int k = 0; k < 2; ++k) dst[m][k] = *(const LAS bf16x8*)(lds + PG8_SA(b, h) + aoff + m * 2048 + k * 1024); } while (0)
; #define PG8_LDB(dst, b, h) do { _Pragma("unroll") for (int n = 0; n < 2; ++n) _Pragma("unroll") for (int k = 0; k < 2; ++k) dst[n][k] = *(const LAS bf16x8*)(lds + PG8_SB(b, h) + boff + n * 2048 + k * 1024); } while (0)
; #define PG8_MMA(ai, bj, At, Bt) do { __builtin_amdgcn_s_setprio(1); _Pragma("unroll") for (int m = 0; m < 4; ++m) _Pragma("unroll") for (int n = 0; n < 2; ++n) _Pragma("unroll") for (int k = 0; k < 2; ++k) \
;         acc[ai][bj][m][n] = __builtin_amdgcn_mfma_f32_16x16x32_bf16(Bt[n][k], At[m][k], acc[ai][bj][m][n], 0, 0, 0); __builtin_amdgcn_s_setprio(0); } while (0)
; #define PG8_WAIT_V(n) asm volatile("s_waitcnt vmcnt(" #n ")" ::: "memory")
; #define PG8_WAIT_L(n) asm volatile("s_waitcnt lgkmcnt(" #n ")" ::: "memory")
; template <class Epi>
; __device__ __forceinline__ void gemm_phase(LAS unsigned char* lds, const Gemm g, const StaticOrder& S, const Epi& E) {
;     ...
;         for (int t = 0; t < nt; t += 2) {
;             const bool last = (t == nt - 2);
;             const char* a1 = cA + (size_t)(t + 1) * kstep;
;             const char* a2 = last ? nA : cA + (size_t)(t + 2) * kstep; const char* b2 = last ? nB : cB + (size_t)(t + 2) * kstep;
;             const char* a3 = a2 + kstep; const char* b3 = b2 + kstep;
;             PG8_LDB(B0, 0, 0); PG8_SCHED; PG8_LDA(At, 0, 0); PG8_STAGE(PG8_SA(1, 1), a1 + hstepA, voffA);
;             PG8_WAIT_L(8); PG8_BAR; PG8_WAIT_L(0); PG8_MMA(0, 0, At, B0); PG8_BAR; PG8_SCHED;
;             PG8_LDB(B1, 0, 1); PG8_STAGE(PG8_SB(0, 0), b2, voffB);
;             PG8_BAR; PG8_WAIT_L(0); PG8_MMA(0, 1, At, B1); PG8_BAR;
;             PG8_LDA(At, 0, 1); PG8_STAGE(PG8_SA(0, 0), a2, voffA);
;             PG8_BAR; PG8_WAIT_L(0); PG8_MMA(1, 0, At, B0); PG8_BAR; PG8_SCHED;
;             PG8_STAGE(PG8_SB(0, 1), b2 + hstepB, voffB);
;             PG8_WAIT_V(6); PG8_BAR; PG8_MMA(1, 1, At, B1); PG8_BAR;
.LBB0_411:
	ds_read_b128 v[140:143], v149
	ds_read_b128 v[152:155], v149 offset:1024
	ds_read_b128 v[156:159], v149 offset:2048
	ds_read_b128 v[160:163], v149 offset:3072
	s_add_u32 s28, s26, 0x100
	s_addc_u32 s29, s27, 0
	s_cmp_eq_u32 s68, 40
	s_cselect_b32 s35, s11, s29
	s_cselect_b32 s34, s10, s28
	s_cselect_b32 s31, s13, s63
	s_cselect_b32 s30, s12, s49
	s_add_i32 m0, s36, 0xc000
	ds_read_b128 v[164:167], v150
	ds_read_b128 v[168:171], v150 offset:1024
	ds_read_b128 v[172:175], v150 offset:2048
	ds_read_b128 v[176:179], v150 offset:3072
	ds_read_b128 v[180:183], v150 offset:4096
	ds_read_b128 v[184:187], v150 offset:5120
	ds_read_b128 v[188:191], v150 offset:6144
	ds_read_b128 v[192:195], v150 offset:7168
	global_load_lds_dwordx4 v132, s[26:27]
	s_add_i32 m0, s36, 0xe000
	s_nop 0
	global_load_lds_dwordx4 v134, s[26:27]
	ds_read_b128 v[196:199], v151
	ds_read_b128 v[200:203], v151 offset:1024
	ds_read_b128 v[204:207], v151 offset:2048
	ds_read_b128 v[208:211], v151 offset:3072
	s_waitcnt lgkmcnt(0)
	s_barrier
	s_setprio 1
	v_mfma_f32_16x16x32_bf16 v[124:127], v[140:143], v[164:167], v[124:127]
	v_mfma_f32_16x16x32_bf16 v[120:123], v[156:159], v[164:167], v[120:123]
	v_mfma_f32_16x16x32_bf16 v[112:115], v[140:143], v[172:175], v[112:115]
	v_mfma_f32_16x16x32_bf16 v[104:107], v[156:159], v[172:175], v[104:107]
	v_mfma_f32_16x16x32_bf16 v[92:95], v[140:143], v[180:183], v[92:95]
	v_mfma_f32_16x16x32_bf16 v[88:91], v[156:159], v[180:183], v[88:91]
	v_mfma_f32_16x16x32_bf16 v[80:83], v[140:143], v[188:191], v[80:83]
	v_mfma_f32_16x16x32_bf16 v[72:75], v[156:159], v[188:191], v[72:75]
	v_mfma_f32_16x16x32_bf16 v[124:127], v[152:155], v[168:171], v[124:127]
	v_mfma_f32_16x16x32_bf16 v[120:123], v[160:163], v[168:171], v[120:123]
	v_mfma_f32_16x16x32_bf16 v[112:115], v[152:155], v[176:179], v[112:115]
	v_mfma_f32_16x16x32_bf16 v[104:107], v[160:163], v[176:179], v[104:107]
	v_mfma_f32_16x16x32_bf16 v[92:95], v[152:155], v[184:187], v[92:95]
	v_mfma_f32_16x16x32_bf16 v[88:91], v[160:163], v[184:187], v[88:91]
	v_mfma_f32_16x16x32_bf16 v[80:83], v[152:155], v[192:195], v[80:83]
	v_mfma_f32_16x16x32_bf16 v[72:75], v[160:163], v[192:195], v[72:75]
	v_mfma_f32_16x16x32_bf16 v[116:119], v[196:199], v[164:167], v[116:119]
	v_mfma_f32_16x16x32_bf16 v[108:111], v[204:207], v[164:167], v[108:111]
	v_mfma_f32_16x16x32_bf16 v[100:103], v[196:199], v[172:175], v[100:103]
	v_mfma_f32_16x16x32_bf16 v[96:99], v[204:207], v[172:175], v[96:99]
	v_mfma_f32_16x16x32_bf16 v[84:87], v[196:199], v[180:183], v[84:87]
	v_mfma_f32_16x16x32_bf16 v[76:79], v[204:207], v[180:183], v[76:79]
	v_mfma_f32_16x16x32_bf16 v[68:71], v[196:199], v[188:191], v[68:71]
	v_mfma_f32_16x16x32_bf16 v[64:67], v[204:207], v[188:191], v[64:67]
	v_mfma_f32_16x16x32_bf16 v[116:119], v[200:203], v[168:171], v[116:119]
	v_mfma_f32_16x16x32_bf16 v[108:111], v[208:211], v[168:171], v[108:111]
	v_mfma_f32_16x16x32_bf16 v[100:103], v[200:203], v[176:179], v[100:103]
	v_mfma_f32_16x16x32_bf16 v[96:99], v[208:211], v[176:179], v[96:99]
	v_mfma_f32_16x16x32_bf16 v[84:87], v[200:203], v[184:187], v[84:87]
	v_mfma_f32_16x16x32_bf16 v[76:79], v[208:211], v[184:187], v[76:79]
	v_mfma_f32_16x16x32_bf16 v[68:71], v[200:203], v[192:195], v[68:71]
	v_mfma_f32_16x16x32_bf16 v[64:67], v[208:211], v[192:195], v[64:67]
	s_setprio 0
	s_barrier
	s_nop 1
	ds_read_b128 v[164:167], v150 offset:16384
	ds_read_b128 v[168:171], v150 offset:17408
	ds_read_b128 v[172:175], v150 offset:18432
	ds_read_b128 v[176:179], v150 offset:19456
	ds_read_b128 v[180:183], v150 offset:20480
	ds_read_b128 v[184:187], v150 offset:21504
	ds_read_b128 v[188:191], v150 offset:22528
	ds_read_b128 v[192:195], v150 offset:23552
	s_add_i32 s26, s43, s7
	v_lshl_add_u64 v[144:145], s[30:31], 0, v[128:129]
	s_mov_b32 m0, s26
	s_nop 0
	global_load_lds_dwordx4 v128, s[30:31]
	v_lshl_add_u64 v[212:213], s[30:31], 0, v[130:131]
	s_add_i32 m0, s26, 0x2000
	s_nop 0
	global_load_lds_dwordx4 v130, s[30:31]
	s_mov_b32 m0, s36
	v_lshl_add_u64 v[214:215], s[34:35], 0, v[128:129]
	global_load_lds_dwordx4 v128, s[34:35]
	v_lshl_add_u64 v[216:217], s[34:35], 0, v[130:131]
	s_mov_b32 m0, s37
	s_nop 0
	global_load_lds_dwordx4 v130, s[34:35]
	s_add_u32 s26, s30, 0xb0000
	s_addc_u32 s27, s31, 0
	s_add_i32 s69, s44, s7
	s_mov_b32 m0, s69
	s_nop 0
	global_load_lds_dwordx4 v128, s[26:27]
	s_add_i32 m0, s69, 0x2000
	s_nop 0
	global_load_lds_dwordx4 v130, s[26:27]
	s_waitcnt vmcnt(6)
	s_waitcnt lgkmcnt(0)
	s_barrier
	s_setprio 1
	v_mfma_f32_16x16x32_bf16 v[60:63], v[140:143], v[164:167], v[60:63]
	v_mfma_f32_16x16x32_bf16 v[56:59], v[156:159], v[164:167], v[56:59]
	v_mfma_f32_16x16x32_bf16 v[48:51], v[140:143], v[172:175], v[48:51]
	v_mfma_f32_16x16x32_bf16 v[40:43], v[156:159], v[172:175], v[40:43]
	v_mfma_f32_16x16x32_bf16 v[28:31], v[140:143], v[180:183], v[28:31]
	v_mfma_f32_16x16x32_bf16 v[24:27], v[156:159], v[180:183], v[24:27]
	v_mfma_f32_16x16x32_bf16 v[16:19], v[140:143], v[188:191], v[16:19]
	v_mfma_f32_16x16x32_bf16 v[8:11], v[156:159], v[188:191], v[8:11]
	v_mfma_f32_16x16x32_bf16 v[60:63], v[152:155], v[168:171], v[60:63]
	v_mfma_f32_16x16x32_bf16 v[56:59], v[160:163], v[168:171], v[56:59]
	v_mfma_f32_16x16x32_bf16 v[48:51], v[152:155], v[176:179], v[48:51]
	v_mfma_f32_16x16x32_bf16 v[40:43], v[160:163], v[176:179], v[40:43]
	v_mfma_f32_16x16x32_bf16 v[28:31], v[152:155], v[184:187], v[28:31]
	v_mfma_f32_16x16x32_bf16 v[24:27], v[160:163], v[184:187], v[24:27]
	v_mfma_f32_16x16x32_bf16 v[16:19], v[152:155], v[192:195], v[16:19]
	v_mfma_f32_16x16x32_bf16 v[8:11], v[160:163], v[192:195], v[8:11]
	v_mfma_f32_16x16x32_bf16 v[52:55], v[196:199], v[164:167], v[52:55]
	v_mfma_f32_16x16x32_bf16 v[44:47], v[204:207], v[164:167], v[44:47]
	v_mfma_f32_16x16x32_bf16 v[36:39], v[196:199], v[172:175], v[36:39]
	v_mfma_f32_16x16x32_bf16 v[32:35], v[204:207], v[172:175], v[32:35]
	v_mfma_f32_16x16x32_bf16 v[20:23], v[196:199], v[180:183], v[20:23]
	v_mfma_f32_16x16x32_bf16 v[12:15], v[204:207], v[180:183], v[12:15]
	v_mfma_f32_16x16x32_bf16 v[4:7], v[196:199], v[188:191], v[4:7]
	v_mfma_f32_16x16x32_bf16 v[0:3], v[204:207], v[188:191], v[0:3]
	v_mfma_f32_16x16x32_bf16 v[52:55], v[200:203], v[168:171], v[52:55]
	v_mfma_f32_16x16x32_bf16 v[44:47], v[208:211], v[168:171], v[44:47]
	v_mfma_f32_16x16x32_bf16 v[36:39], v[200:203], v[176:179], v[36:39]
	v_mfma_f32_16x16x32_bf16 v[32:35], v[208:211], v[176:179], v[32:35]
	v_mfma_f32_16x16x32_bf16 v[20:23], v[200:203], v[184:187], v[20:23]
	v_mfma_f32_16x16x32_bf16 v[12:15], v[208:211], v[184:187], v[12:15]
	v_mfma_f32_16x16x32_bf16 v[4:7], v[200:203], v[192:195], v[4:7]
	v_mfma_f32_16x16x32_bf16 v[0:3], v[208:211], v[192:195], v[0:3]
	s_setprio 0
	s_add_i32 s69, 0, 0x18000
	v_add_u32_e32 v160, s69, v147
	s_barrier
; #define PG8_STAGE(bufoff, gbase, voff) do { _Pragma("unroll") for (int _i = 0; _i < 2; ++_i) \
;         __builtin_amdgcn_global_load_lds((const unsigned*)((const char*)(gbase) + (voff)[_i]), (LAS unsigned*)(lds + (bufoff) + ldsw + _i * 8192), 16, 0, 0); } while (0)
; #define PG8_LDA(dst, b, h) do { _Pragma("unroll") for (int m = 0; m < 4; ++m) _Pragma("unroll") for (int k = 0; k < 2; ++k) dst[m][k] = *(const LAS bf16x8*)(lds + PG8_SA(b, h) + aoff + m * 2048 + k * 1024); } while (0)
; #define PG8_LDB(dst, b, h) do { _Pragma("unroll") for (int n = 0; n < 2; ++n) _Pragma("unroll") for (int k = 0; k < 2; ++k) dst[n][k] = *(const LAS bf16x8*)(lds + PG8_SB(b, h) + boff + n * 2048 + k * 1024); } while (0)
; #define PG8_MMA(ai, bj, At, Bt) do { __builtin_amdgcn_s_setprio(1); _Pragma("unroll") for (int m = 0; m < 4; ++m) _Pragma("unroll") for (int n = 0; n < 2; ++n) _Pragma("unroll") for (int k = 0; k < 2; ++k) \
;         acc[ai][bj][m][n] = __builtin_amdgcn_mfma_f32_16x16x32_bf16(Bt[n][k], At[m][k], acc[ai][bj][m][n], 0, 0, 0); __builtin_amdgcn_s_setprio(0); } while (0)
; #define PG8_WAIT_V(n) asm volatile("s_waitcnt vmcnt(" #n ")" ::: "memory")
; #define PG8_WAIT_L(n) asm volatile("s_waitcnt lgkmcnt(" #n ")" ::: "memory")
; #define PG8_BAR __builtin_amdgcn_s_barrier()
; #define PG8_SCHED __builtin_amdgcn_sched_barrier(0)
; template <class Epi>
; __device__ __forceinline__ void gemm_phase(LAS unsigned char* lds, const Gemm g, const StaticOrder& S, const Epi& E) {
;     ...
;             PG8_LDB(B0, 1, 0); PG8_SCHED; PG8_LDA(At, 1, 0); PG8_STAGE(PG8_SA(0, 1), a2 + hstepA, voffA);
;             PG8_WAIT_L(8); PG8_BAR; PG8_WAIT_L(0); PG8_MMA(0, 0, At, B0); PG8_BAR; PG8_SCHED;
;             PG8_LDB(B1, 1, 1); PG8_STAGE(PG8_SB(1, 0), b3, voffB);
;             PG8_BAR; PG8_WAIT_L(0); PG8_MMA(0, 1, At, B1); PG8_BAR;
;             PG8_LDA(At, 1, 1); PG8_STAGE(PG8_SA(1, 0), a3, voffA);
;             PG8_BAR; PG8_WAIT_L(0); PG8_MMA(1, 0, At, B0); PG8_BAR; PG8_SCHED;
;             PG8_STAGE(PG8_SB(1, 1), b3 + hstepB, voffB);
;             PG8_WAIT_V(6); PG8_BAR; PG8_MMA(1, 1, At, B1); PG8_BAR;
	ds_read_b128 v[140:143], v160
	ds_read_b128 v[152:155], v160 offset:1024
	ds_read_b128 v[156:159], v160 offset:2048
	ds_read_b128 v[160:163], v160 offset:3072
	s_add_u32 s26, s34, 0xb0000
	s_addc_u32 s27, s35, 0
	s_mov_b32 m0, s38
	ds_read_b128 v[164:167], v150 offset:32768
	ds_read_b128 v[168:171], v150 offset:33792
	ds_read_b128 v[172:175], v150 offset:34816
	ds_read_b128 v[176:179], v150 offset:35840
	ds_read_b128 v[180:183], v150 offset:36864
	ds_read_b128 v[184:187], v150 offset:37888
	ds_read_b128 v[188:191], v150 offset:38912
	ds_read_b128 v[192:195], v150 offset:39936
	global_load_lds_dwordx4 v128, s[26:27]
	s_mov_b32 m0, s39
	s_nop 0
	global_load_lds_dwordx4 v130, s[26:27]
	s_add_i32 s34, 0, 0x1c000
	v_add_u32_e32 v208, s34, v147
	ds_read_b128 v[196:199], v208
	ds_read_b128 v[200:203], v208 offset:1024
	ds_read_b128 v[204:207], v208 offset:2048
	ds_read_b128 v[208:211], v208 offset:3072
	s_waitcnt lgkmcnt(0)
	s_barrier
	s_setprio 1
	v_mfma_f32_16x16x32_bf16 v[124:127], v[140:143], v[164:167], v[124:127]
	v_mfma_f32_16x16x32_bf16 v[120:123], v[156:159], v[164:167], v[120:123]
	v_mfma_f32_16x16x32_bf16 v[112:115], v[140:143], v[172:175], v[112:115]
	v_mfma_f32_16x16x32_bf16 v[104:107], v[156:159], v[172:175], v[104:107]
	v_mfma_f32_16x16x32_bf16 v[92:95], v[140:143], v[180:183], v[92:95]
	v_mfma_f32_16x16x32_bf16 v[88:91], v[156:159], v[180:183], v[88:91]
	v_mfma_f32_16x16x32_bf16 v[80:83], v[140:143], v[188:191], v[80:83]
	v_mfma_f32_16x16x32_bf16 v[72:75], v[156:159], v[188:191], v[72:75]
	v_mfma_f32_16x16x32_bf16 v[124:127], v[152:155], v[168:171], v[124:127]
	v_mfma_f32_16x16x32_bf16 v[120:123], v[160:163], v[168:171], v[120:123]
	v_mfma_f32_16x16x32_bf16 v[112:115], v[152:155], v[176:179], v[112:115]
	v_mfma_f32_16x16x32_bf16 v[104:107], v[160:163], v[176:179], v[104:107]
	v_mfma_f32_16x16x32_bf16 v[92:95], v[152:155], v[184:187], v[92:95]
	v_mfma_f32_16x16x32_bf16 v[88:91], v[160:163], v[184:187], v[88:91]
	v_mfma_f32_16x16x32_bf16 v[80:83], v[152:155], v[192:195], v[80:83]
	v_mfma_f32_16x16x32_bf16 v[72:75], v[160:163], v[192:195], v[72:75]
	v_mfma_f32_16x16x32_bf16 v[116:119], v[196:199], v[164:167], v[116:119]
	v_mfma_f32_16x16x32_bf16 v[108:111], v[204:207], v[164:167], v[108:111]
	v_mfma_f32_16x16x32_bf16 v[100:103], v[196:199], v[172:175], v[100:103]
	v_mfma_f32_16x16x32_bf16 v[96:99], v[204:207], v[172:175], v[96:99]
	v_mfma_f32_16x16x32_bf16 v[84:87], v[196:199], v[180:183], v[84:87]
	v_mfma_f32_16x16x32_bf16 v[76:79], v[204:207], v[180:183], v[76:79]
	v_mfma_f32_16x16x32_bf16 v[68:71], v[196:199], v[188:191], v[68:71]
	v_mfma_f32_16x16x32_bf16 v[64:67], v[204:207], v[188:191], v[64:67]
	v_mfma_f32_16x16x32_bf16 v[116:119], v[200:203], v[168:171], v[116:119]
	v_mfma_f32_16x16x32_bf16 v[108:111], v[208:211], v[168:171], v[108:111]
	v_mfma_f32_16x16x32_bf16 v[100:103], v[200:203], v[176:179], v[100:103]
	v_mfma_f32_16x16x32_bf16 v[96:99], v[208:211], v[176:179], v[96:99]
	v_mfma_f32_16x16x32_bf16 v[84:87], v[200:203], v[184:187], v[84:87]
	v_mfma_f32_16x16x32_bf16 v[76:79], v[208:211], v[184:187], v[76:79]
	v_mfma_f32_16x16x32_bf16 v[68:71], v[200:203], v[192:195], v[68:71]
	v_mfma_f32_16x16x32_bf16 v[64:67], v[208:211], v[192:195], v[64:67]
	s_setprio 0
	s_barrier
	s_nop 1
	ds_read_b128 v[164:167], v150 offset:49152
	ds_read_b128 v[168:171], v150 offset:50176
	ds_read_b128 v[172:175], v150 offset:51200
	ds_read_b128 v[176:179], v150 offset:52224
	ds_read_b128 v[180:183], v150 offset:53248
	ds_read_b128 v[184:187], v150 offset:54272
	ds_read_b128 v[188:191], v150 offset:55296
	ds_read_b128 v[192:195], v150 offset:56320
	s_add_i32 s26, s69, s7
	s_mov_b32 m0, s26
	s_nop 0
	s_add_u32 s100, s30, s16
	s_addc_u32 s101, s31, s17
	global_load_lds_dwordx4 v128, s[100:101]
	s_add_i32 m0, s26, 0x2000
	s_nop 0
	s_add_u32 s100, s30, s16
	s_addc_u32 s101, s31, s17
	global_load_lds_dwordx4 v130, s[100:101]
	s_mov_b32 m0, s41
	v_lshl_add_u64 v[254:255], v[214:215], 0, s[16:17]
	global_load_lds_dwordx4 v[254:255], off
	v_lshl_add_u64 v[144:145], v[216:217], 0, s[16:17]
	s_mov_b32 m0, s42
	s_nop 0
	global_load_lds_dwordx4 v[144:145], off
	s_add_u32 s26, s30, 0xb0080
	s_addc_u32 s27, s31, 0
	s_add_i32 s30, s34, s7
	s_mov_b32 m0, s30
	s_nop 0
	global_load_lds_dwordx4 v128, s[26:27]
	s_add_i32 m0, s30, 0x2000
	s_nop 0
	global_load_lds_dwordx4 v130, s[26:27]
	s_waitcnt vmcnt(6)
	s_waitcnt lgkmcnt(0)
	s_barrier
	s_setprio 1
	v_mfma_f32_16x16x32_bf16 v[60:63], v[140:143], v[164:167], v[60:63]
	v_mfma_f32_16x16x32_bf16 v[56:59], v[156:159], v[164:167], v[56:59]
	v_mfma_f32_16x16x32_bf16 v[48:51], v[140:143], v[172:175], v[48:51]
	v_mfma_f32_16x16x32_bf16 v[40:43], v[156:159], v[172:175], v[40:43]
	v_mfma_f32_16x16x32_bf16 v[28:31], v[140:143], v[180:183], v[28:31]
	v_mfma_f32_16x16x32_bf16 v[24:27], v[156:159], v[180:183], v[24:27]
	v_mfma_f32_16x16x32_bf16 v[16:19], v[140:143], v[188:191], v[16:19]
	v_mfma_f32_16x16x32_bf16 v[8:11], v[156:159], v[188:191], v[8:11]
	v_mfma_f32_16x16x32_bf16 v[60:63], v[152:155], v[168:171], v[60:63]
	v_mfma_f32_16x16x32_bf16 v[56:59], v[160:163], v[168:171], v[56:59]
	v_mfma_f32_16x16x32_bf16 v[48:51], v[152:155], v[176:179], v[48:51]
	v_mfma_f32_16x16x32_bf16 v[40:43], v[160:163], v[176:179], v[40:43]
	v_mfma_f32_16x16x32_bf16 v[28:31], v[152:155], v[184:187], v[28:31]
	v_mfma_f32_16x16x32_bf16 v[24:27], v[160:163], v[184:187], v[24:27]
	v_mfma_f32_16x16x32_bf16 v[16:19], v[152:155], v[192:195], v[16:19]
	v_mfma_f32_16x16x32_bf16 v[8:11], v[160:163], v[192:195], v[8:11]
	v_mfma_f32_16x16x32_bf16 v[52:55], v[196:199], v[164:167], v[52:55]
	v_mfma_f32_16x16x32_bf16 v[44:47], v[204:207], v[164:167], v[44:47]
	v_mfma_f32_16x16x32_bf16 v[36:39], v[196:199], v[172:175], v[36:39]
	v_mfma_f32_16x16x32_bf16 v[32:35], v[204:207], v[172:175], v[32:35]
	v_mfma_f32_16x16x32_bf16 v[20:23], v[196:199], v[180:183], v[20:23]
	v_mfma_f32_16x16x32_bf16 v[12:15], v[204:207], v[180:183], v[12:15]
	v_mfma_f32_16x16x32_bf16 v[4:7], v[196:199], v[188:191], v[4:7]
	v_mfma_f32_16x16x32_bf16 v[0:3], v[204:207], v[188:191], v[0:3]
	v_mfma_f32_16x16x32_bf16 v[52:55], v[200:203], v[168:171], v[52:55]
	v_mfma_f32_16x16x32_bf16 v[44:47], v[208:211], v[168:171], v[44:47]
	v_mfma_f32_16x16x32_bf16 v[36:39], v[200:203], v[176:179], v[36:39]
	v_mfma_f32_16x16x32_bf16 v[32:35], v[208:211], v[176:179], v[32:35]
	v_mfma_f32_16x16x32_bf16 v[20:23], v[200:203], v[184:187], v[20:23]
	v_mfma_f32_16x16x32_bf16 v[12:15], v[208:211], v[184:187], v[12:15]
	v_mfma_f32_16x16x32_bf16 v[4:7], v[200:203], v[192:195], v[4:7]
	v_mfma_f32_16x16x32_bf16 v[0:3], v[208:211], v[192:195], v[0:3]
	s_setprio 0
	s_add_i32 s68, s68, 2
	s_add_u32 s49, s49, 0x100
	s_addc_u32 s63, s63, 0
	s_cmp_gt_u32 s68, 41
	s_mov_b64 s[26:27], s[28:29]
	s_barrier
; template <class Epi>
; __device__ __forceinline__ void gemm_phase(LAS unsigned char* lds, const Gemm g, const StaticOrder& S, const Epi& E) {
;     ...
;         for (int t = 0; t < nt; t += 2) {
;     __device__ __forceinline__ void operator()(AccRef acc, const Unit& u, int wr, int wc, int fr, int fq) const {
;         const int row0 = u.pm * 256 + wr * 64 + fr, col0 = u.pn * 256 + wc * 32 + 4 * fq;
;         f32x4 sv[2][2], bv[2][2];
; #pragma unroll
;         for (int bj = 0; bj < 2; ++bj)
; #pragma unroll
;             for (int n = 0; n < 2; ++n) {
;                 sv[bj][n] = scale ? *(const f32x4*)(scale + col0 + bj * 128 + n * 16) : (f32x4){1.f, 1.f, 1.f, 1.f};
;                 bv[bj][n] = bias ? *(const f32x4*)(bias + col0 + bj * 128 + n * 16) : (f32x4){0.f, 0.f, 0.f, 0.f}; }
; #pragma unroll
;         for (int ai = 0; ai < 2; ++ai)
; #pragma unroll
;             for (int mh = 0; mh < 2; ++mh) {
;                 f32x4 bs[2][2][2];
; #pragma unroll
;                 for (int m = 0; m < 2; ++m)
; #pragma unroll
;                     for (int bj = 0; bj < 2; ++bj)
; #pragma unroll
;                         for (int n = 0; n < 2; ++n) bs[m][bj][n] = *(const f32x4*)(base + (size_t)(row0 + ai * 128 + (2 * mh + m) * 16) * D + col0 + bj * 128 + n * 16);
; #pragma unroll
;                 for (int m = 0; m < 2; ++m)
; #pragma unroll
;                     for (int bj = 0; bj < 2; ++bj)
; #pragma unroll
;                         for (int n = 0; n < 2; ++n) *(f32x4*)(out + (size_t)(row0 + ai * 128 + (2 * mh + m) * 16) * D + col0 + bj * 128 + n * 16) = bs[m][bj][n] + sv[bj][n] * (acc[ai][bj][2 * mh + m][n] + bv[bj][n]);
	s_cbranch_scc0 .LBB0_411
	v_lshl_or_b32 v144, s47, 8, v148
	v_lshl_add_u32 v145, s48, 8, v146
	v_lshlrev_b32_e32 v144, 2, v144
	v_lshl_add_u32 v145, v145, 12, v144
	v_add_u32_e32 v216, 0x10000, v145
	v_add_u32_e32 v217, 0x20000, v145
	v_add_u32_e32 v218, 0x30000, v145
	v_add_u32_e32 v232, 0x80000, v145
	v_add_u32_e32 v233, 0x90000, v145
	v_add_u32_e32 v235, 0xa0000, v145
	v_add_u32_e32 v253, 0xb0000, v145
	s_and_b64 vcc, exec, s[8:9]
	s_mov_b32 s47, s45
	s_mov_b32 s48, s46
	s_mov_b64 s[28:29], s[12:13]
	s_mov_b64 s[26:27], s[10:11]
	global_load_dwordx4 v[140:143], v145, s[52:53]
	global_load_dwordx4 v[152:155], v145, s[52:53] offset:64
	global_load_dwordx4 v[156:159], v145, s[52:53] offset:512
	global_load_dwordx4 v[160:163], v145, s[52:53] offset:576
	global_load_dwordx4 v[164:167], v216, s[52:53]
	global_load_dwordx4 v[168:171], v216, s[52:53] offset:64
	global_load_dwordx4 v[172:175], v216, s[52:53] offset:512
	global_load_dwordx4 v[176:179], v216, s[52:53] offset:576
	global_load_dwordx4 v[180:183], v217, s[52:53]
	global_load_dwordx4 v[184:187], v217, s[52:53] offset:64
	global_load_dwordx4 v[188:191], v217, s[52:53] offset:512
	global_load_dwordx4 v[192:195], v217, s[52:53] offset:576
	global_load_dwordx4 v[196:199], v218, s[52:53]
	global_load_dwordx4 v[200:203], v218, s[52:53] offset:64
	global_load_dwordx4 v[204:207], v218, s[52:53] offset:512
	global_load_dwordx4 v[208:211], v218, s[52:53] offset:576
	global_load_dwordx4 v[212:215], v232, s[52:53]
	global_load_dwordx4 v[220:223], v232, s[52:53] offset:64
	global_load_dwordx4 v[224:227], v232, s[52:53] offset:512
	global_load_dwordx4 v[228:231], v232, s[52:53] offset:576
	global_load_dwordx4 v[236:239], v233, s[52:53]
	global_load_dwordx4 v[240:243], v233, s[52:53] offset:64
	global_load_dwordx4 v[244:247], v233, s[52:53] offset:512
	global_load_dwordx4 v[248:251], v233, s[52:53] offset:576
	v_pk_add_f32 v[124:125], v[124:125], 0 op_sel_hi:[1,0]
	v_pk_add_f32 v[126:127], v[126:127], 0 op_sel_hi:[1,0]
	v_pk_add_f32 v[120:121], v[120:121], 0 op_sel_hi:[1,0]
	v_pk_add_f32 v[122:123], v[122:123], 0 op_sel_hi:[1,0]
	v_pk_add_f32 v[116:117], v[116:117], 0 op_sel_hi:[1,0]
	v_pk_add_f32 v[118:119], v[118:119], 0 op_sel_hi:[1,0]
	v_pk_add_f32 v[108:109], v[108:109], 0 op_sel_hi:[1,0]
	v_pk_add_f32 v[110:111], v[110:111], 0 op_sel_hi:[1,0]
	v_pk_add_f32 v[112:113], v[112:113], 0 op_sel_hi:[1,0]
	v_pk_add_f32 v[114:115], v[114:115], 0 op_sel_hi:[1,0]
	v_pk_add_f32 v[104:105], v[104:105], 0 op_sel_hi:[1,0]
	v_pk_add_f32 v[106:107], v[106:107], 0 op_sel_hi:[1,0]
	v_pk_add_f32 v[100:101], v[100:101], 0 op_sel_hi:[1,0]
	v_pk_add_f32 v[102:103], v[102:103], 0 op_sel_hi:[1,0]
	v_pk_add_f32 v[96:97], v[96:97], 0 op_sel_hi:[1,0]
	v_pk_add_f32 v[98:99], v[98:99], 0 op_sel_hi:[1,0]
	v_pk_add_f32 v[92:93], v[92:93], 0 op_sel_hi:[1,0]
	v_pk_add_f32 v[94:95], v[94:95], 0 op_sel_hi:[1,0]
	v_pk_add_f32 v[88:89], v[88:89], 0 op_sel_hi:[1,0]
	v_pk_add_f32 v[90:91], v[90:91], 0 op_sel_hi:[1,0]
	v_pk_add_f32 v[84:85], v[84:85], 0 op_sel_hi:[1,0]
	v_pk_add_f32 v[86:87], v[86:87], 0 op_sel_hi:[1,0]
	v_pk_add_f32 v[76:77], v[76:77], 0 op_sel_hi:[1,0]
	v_pk_add_f32 v[78:79], v[78:79], 0 op_sel_hi:[1,0]
	v_pk_add_f32 v[80:81], v[80:81], 0 op_sel_hi:[1,0]
	v_pk_add_f32 v[82:83], v[82:83], 0 op_sel_hi:[1,0]
	v_pk_add_f32 v[72:73], v[72:73], 0 op_sel_hi:[1,0]
	v_pk_add_f32 v[74:75], v[74:75], 0 op_sel_hi:[1,0]
	v_pk_add_f32 v[68:69], v[68:69], 0 op_sel_hi:[1,0]
	v_pk_add_f32 v[70:71], v[70:71], 0 op_sel_hi:[1,0]
	v_pk_add_f32 v[64:65], v[64:65], 0 op_sel_hi:[1,0]
	v_pk_add_f32 v[66:67], v[66:67], 0 op_sel_hi:[1,0]
	v_pk_add_f32 v[60:61], v[60:61], 0 op_sel_hi:[1,0]
	v_pk_add_f32 v[62:63], v[62:63], 0 op_sel_hi:[1,0]
	v_pk_add_f32 v[56:57], v[56:57], 0 op_sel_hi:[1,0]
	v_pk_add_f32 v[58:59], v[58:59], 0 op_sel_hi:[1,0]
	v_pk_add_f32 v[52:53], v[52:53], 0 op_sel_hi:[1,0]
	v_pk_add_f32 v[54:55], v[54:55], 0 op_sel_hi:[1,0]
	v_pk_add_f32 v[44:45], v[44:45], 0 op_sel_hi:[1,0]
	v_pk_add_f32 v[46:47], v[46:47], 0 op_sel_hi:[1,0]
	v_pk_add_f32 v[48:49], v[48:49], 0 op_sel_hi:[1,0]
	v_pk_add_f32 v[50:51], v[50:51], 0 op_sel_hi:[1,0]
	v_pk_add_f32 v[40:41], v[40:41], 0 op_sel_hi:[1,0]
	v_pk_add_f32 v[42:43], v[42:43], 0 op_sel_hi:[1,0]
	v_pk_add_f32 v[36:37], v[36:37], 0 op_sel_hi:[1,0]
	v_pk_add_f32 v[38:39], v[38:39], 0 op_sel_hi:[1,0]
	v_pk_add_f32 v[32:33], v[32:33], 0 op_sel_hi:[1,0]
	v_pk_add_f32 v[34:35], v[34:35], 0 op_sel_hi:[1,0]
	v_pk_add_f32 v[28:29], v[28:29], 0 op_sel_hi:[1,0]
	v_pk_add_f32 v[30:31], v[30:31], 0 op_sel_hi:[1,0]
	v_pk_add_f32 v[24:25], v[24:25], 0 op_sel_hi:[1,0]
	v_pk_add_f32 v[26:27], v[26:27], 0 op_sel_hi:[1,0]
	v_pk_add_f32 v[20:21], v[20:21], 0 op_sel_hi:[1,0]
	v_pk_add_f32 v[22:23], v[22:23], 0 op_sel_hi:[1,0]
	v_pk_add_f32 v[12:13], v[12:13], 0 op_sel_hi:[1,0]
	v_pk_add_f32 v[14:15], v[14:15], 0 op_sel_hi:[1,0]
	v_pk_add_f32 v[16:17], v[16:17], 0 op_sel_hi:[1,0]
	v_pk_add_f32 v[18:19], v[18:19], 0 op_sel_hi:[1,0]
	v_pk_add_f32 v[8:9], v[8:9], 0 op_sel_hi:[1,0]
	v_pk_add_f32 v[10:11], v[10:11], 0 op_sel_hi:[1,0]
	v_pk_add_f32 v[4:5], v[4:5], 0 op_sel_hi:[1,0]
	v_pk_add_f32 v[6:7], v[6:7], 0 op_sel_hi:[1,0]
	v_pk_add_f32 v[0:1], v[0:1], 0 op_sel_hi:[1,0]
	v_pk_add_f32 v[2:3], v[2:3], 0 op_sel_hi:[1,0]
	s_waitcnt vmcnt(16)
; #define PG8_WAIT_V(n) asm volatile("s_waitcnt vmcnt(" #n ")" ::: "memory")
; #define PG8_BAR __builtin_amdgcn_s_barrier()
; template <class Epi>
; __device__ __forceinline__ void gemm_phase(LAS unsigned char* lds, const Gemm g, const StaticOrder& S, const Epi& E) {
;     ...
;         if (!has_next) break;
;         {
; #pragma unroll
;         for (int a = 0; a < 2; ++a)
; #pragma unroll
;             for (int b = 0; b < 2; ++b)
; #pragma unroll
;                 for (int m = 0; m < 4; ++m)
; #pragma unroll
;                     for (int n = 0; n < 2; ++n) acc[a][b][m][n] = (f32x4){0.f, 0.f, 0.f, 0.f};
;         }
;         cur = nxt; cA = nA; cB = nB; ++ui;
;     }
;     PG8_WAIT_V(0);
;     if (wr == 0) PG8_BAR;
;     PG8_BAR;
;     __device__ __forceinline__ void operator()(AccRef acc, const Unit& u, int wr, int wc, int fr, int fq) const {
;     ...
;                         for (int n = 0; n < 2; ++n) bs[m][bj][n] = *(const f32x4*)(base + (size_t)(row0 + ai * 128 + (2 * mh + m) * 16) * D + col0 + bj * 128 + n * 16);
; #pragma unroll
;                 for (int m = 0; m < 2; ++m)
; #pragma unroll
;                     for (int bj = 0; bj < 2; ++bj)
; #pragma unroll
;                         for (int n = 0; n < 2; ++n) *(f32x4*)(out + (size_t)(row0 + ai * 128 + (2 * mh + m) * 16) * D + col0 + bj * 128 + n * 16) = bs[m][bj][n] + sv[bj][n] * (acc[ai][bj][2 * mh + m][n] + bv[bj][n]);
;                 asm volatile("" ::: "memory"); }
	v_pk_add_f32 v[124:125], v[124:125], v[140:141]
	v_pk_add_f32 v[126:127], v[126:127], v[142:143]
	v_pk_add_f32 v[120:121], v[120:121], v[152:153]
	v_pk_add_f32 v[122:123], v[122:123], v[154:155]
	v_pk_add_f32 v[116:117], v[116:117], v[156:157]
	v_pk_add_f32 v[118:119], v[118:119], v[158:159]
	v_pk_add_f32 v[108:109], v[108:109], v[160:161]
	v_pk_add_f32 v[110:111], v[110:111], v[162:163]
	v_pk_add_f32 v[112:113], v[112:113], v[164:165]
	v_pk_add_f32 v[114:115], v[114:115], v[166:167]
	v_pk_add_f32 v[104:105], v[104:105], v[168:169]
	v_pk_add_f32 v[106:107], v[106:107], v[170:171]
	v_pk_add_f32 v[100:101], v[100:101], v[172:173]
	v_pk_add_f32 v[102:103], v[102:103], v[174:175]
	v_pk_add_f32 v[96:97], v[96:97], v[176:177]
	v_pk_add_f32 v[98:99], v[98:99], v[178:179]
	global_store_dwordx4 v145, v[124:127], s[52:53]
	global_store_dwordx4 v145, v[120:123], s[52:53] offset:64
	global_store_dwordx4 v145, v[116:119], s[52:53] offset:512
	global_store_dwordx4 v145, v[108:111], s[52:53] offset:576
	global_store_dwordx4 v216, v[112:115], s[52:53]
	global_store_dwordx4 v216, v[104:107], s[52:53] offset:64
	global_store_dwordx4 v216, v[100:103], s[52:53] offset:512
	global_store_dwordx4 v216, v[96:99], s[52:53] offset:576
	global_load_dwordx4 v[140:143], v235, s[52:53]
	global_load_dwordx4 v[152:155], v235, s[52:53] offset:64
	global_load_dwordx4 v[156:159], v235, s[52:53] offset:512
	global_load_dwordx4 v[160:163], v235, s[52:53] offset:576
	global_load_dwordx4 v[164:167], v253, s[52:53]
	global_load_dwordx4 v[168:171], v253, s[52:53] offset:64
	global_load_dwordx4 v[172:175], v253, s[52:53] offset:512
	global_load_dwordx4 v[176:179], v253, s[52:53] offset:576
	s_waitcnt vmcnt(24)
	v_pk_add_f32 v[92:93], v[92:93], v[180:181]
	v_pk_add_f32 v[94:95], v[94:95], v[182:183]
	v_pk_add_f32 v[88:89], v[88:89], v[184:185]
	v_pk_add_f32 v[90:91], v[90:91], v[186:187]
	v_pk_add_f32 v[84:85], v[84:85], v[188:189]
	v_pk_add_f32 v[86:87], v[86:87], v[190:191]
	v_pk_add_f32 v[76:77], v[76:77], v[192:193]
	v_pk_add_f32 v[78:79], v[78:79], v[194:195]
	v_pk_add_f32 v[80:81], v[80:81], v[196:197]
	v_pk_add_f32 v[82:83], v[82:83], v[198:199]
	v_pk_add_f32 v[72:73], v[72:73], v[200:201]
	v_pk_add_f32 v[74:75], v[74:75], v[202:203]
	v_pk_add_f32 v[68:69], v[68:69], v[204:205]
	v_pk_add_f32 v[70:71], v[70:71], v[206:207]
	v_pk_add_f32 v[64:65], v[64:65], v[208:209]
	v_pk_add_f32 v[66:67], v[66:67], v[210:211]
	global_store_dwordx4 v217, v[92:95], s[52:53]
	global_store_dwordx4 v217, v[88:91], s[52:53] offset:64
	global_store_dwordx4 v217, v[84:87], s[52:53] offset:512
	global_store_dwordx4 v217, v[76:79], s[52:53] offset:576
	global_store_dwordx4 v218, v[80:83], s[52:53]
	global_store_dwordx4 v218, v[72:75], s[52:53] offset:64
	global_store_dwordx4 v218, v[68:71], s[52:53] offset:512
	global_store_dwordx4 v218, v[64:67], s[52:53] offset:576
	s_waitcnt vmcnt(24)
	v_pk_add_f32 v[60:61], v[60:61], v[212:213]
	v_pk_add_f32 v[62:63], v[62:63], v[214:215]
	v_pk_add_f32 v[56:57], v[56:57], v[220:221]
	v_pk_add_f32 v[58:59], v[58:59], v[222:223]
	v_pk_add_f32 v[52:53], v[52:53], v[224:225]
	v_pk_add_f32 v[54:55], v[54:55], v[226:227]
	v_pk_add_f32 v[44:45], v[44:45], v[228:229]
	v_pk_add_f32 v[46:47], v[46:47], v[230:231]
	v_pk_add_f32 v[48:49], v[48:49], v[236:237]
	v_pk_add_f32 v[50:51], v[50:51], v[238:239]
	v_pk_add_f32 v[40:41], v[40:41], v[240:241]
	v_pk_add_f32 v[42:43], v[42:43], v[242:243]
	v_pk_add_f32 v[36:37], v[36:37], v[244:245]
	v_pk_add_f32 v[38:39], v[38:39], v[246:247]
	v_pk_add_f32 v[32:33], v[32:33], v[248:249]
	v_pk_add_f32 v[34:35], v[34:35], v[250:251]
	global_store_dwordx4 v232, v[60:63], s[52:53]
	global_store_dwordx4 v232, v[56:59], s[52:53] offset:64
	global_store_dwordx4 v232, v[52:55], s[52:53] offset:512
	global_store_dwordx4 v232, v[44:47], s[52:53] offset:576
	global_store_dwordx4 v233, v[48:51], s[52:53]
	global_store_dwordx4 v233, v[40:43], s[52:53] offset:64
	global_store_dwordx4 v233, v[36:39], s[52:53] offset:512
	global_store_dwordx4 v233, v[32:35], s[52:53] offset:576
	s_waitcnt vmcnt(16)
	v_pk_add_f32 v[28:29], v[28:29], v[140:141]
	v_pk_add_f32 v[30:31], v[30:31], v[142:143]
	v_pk_add_f32 v[24:25], v[24:25], v[152:153]
	v_pk_add_f32 v[26:27], v[26:27], v[154:155]
	v_pk_add_f32 v[20:21], v[20:21], v[156:157]
	v_pk_add_f32 v[22:23], v[22:23], v[158:159]
	v_pk_add_f32 v[12:13], v[12:13], v[160:161]
	v_pk_add_f32 v[14:15], v[14:15], v[162:163]
	v_pk_add_f32 v[16:17], v[16:17], v[164:165]
	v_pk_add_f32 v[18:19], v[18:19], v[166:167]
	v_pk_add_f32 v[8:9], v[8:9], v[168:169]
	v_pk_add_f32 v[10:11], v[10:11], v[170:171]
	v_pk_add_f32 v[4:5], v[4:5], v[172:173]
	v_pk_add_f32 v[6:7], v[6:7], v[174:175]
	v_pk_add_f32 v[0:1], v[0:1], v[176:177]
	v_pk_add_f32 v[2:3], v[2:3], v[178:179]
	global_store_dwordx4 v235, v[28:31], s[52:53]
	global_store_dwordx4 v235, v[24:27], s[52:53] offset:64
	global_store_dwordx4 v235, v[20:23], s[52:53] offset:512
	global_store_dwordx4 v235, v[12:15], s[52:53] offset:576
	global_store_dwordx4 v253, v[16:19], s[52:53]
	global_store_dwordx4 v253, v[8:11], s[52:53] offset:64
	global_store_dwordx4 v253, v[4:7], s[52:53] offset:512
	global_store_dwordx4 v253, v[0:3], s[52:53] offset:576
	s_cbranch_vccz .LBB0_400
	s_waitcnt vmcnt(0)
	s_cmpk_gt_u32 s4, 0xff
	s_cbranch_scc1 .LBB0_415
	s_barrier

; #define PG8_STAGE(bufoff, gbase, voff) do { _Pragma("unroll") for (int _i = 0; _i < 2; ++_i) \
;         __builtin_amdgcn_global_load_lds((const unsigned*)((const char*)(gbase) + (voff)[_i]), (LAS unsigned*)(lds + (bufoff) + ldsw + _i * 8192), 16, 0, 0); } while (0)
; #define PG8_LDA(dst, b, h) do { _Pragma("unroll") for (int m = 0; m < 4; ++m) _Pragma("unroll") for (int k = 0; k < 2; ++k) dst[m][k] = *(const LAS bf16x8*)(lds + PG8_SA(b, h) + aoff + m * 2048 + k * 1024); } while (0)
; #define PG8_LDB(dst, b, h) do { _Pragma("unroll") for (int n = 0; n < 2; ++n) _Pragma("unroll") for (int k = 0; k < 2; ++k) dst[n][k] = *(const LAS bf16x8*)(lds + PG8_SB(b, h) + boff + n * 2048 + k * 1024); } while (0)
; #define PG8_WAIT_V(n) asm volatile("s_waitcnt vmcnt(" #n ")" ::: "memory")
; #define PG8_WAIT_L(n) asm volatile("s_waitcnt lgkmcnt(" #n ")" ::: "memory")
; #define PG8_BAR __builtin_amdgcn_s_barrier()
; #define PG8_SCHED __builtin_amdgcn_sched_barrier(0)
; template <class Epi>
; __device__ __forceinline__ void gemm_phase(LAS unsigned char* lds, const Gemm g, const StaticOrder& S, const Epi& E) {
;     ...
;         const bool has_next = S.next(ui + 1, nxt);
;         const char* nA = has_next ? (const char*)g.A + (size_t)nxt.pm * tstepA + (size_t)(nxt.pn >> g.a_shift) * g.a_step : cA; const char* nB = has_next ? (const char*)g.Bt + (size_t)nxt.pn * tstepB : cB;
;         for (int t = 0; t < nt; t += 2) {
;             const bool last = (t == nt - 2);
;             const char* a1 = cA + (size_t)(t + 1) * kstep;
;             const char* a2 = last ? nA : cA + (size_t)(t + 2) * kstep; const char* b2 = last ? nB : cB + (size_t)(t + 2) * kstep;
;             const char* a3 = a2 + kstep; const char* b3 = b2 + kstep;
;             PG8_LDB(B0, 0, 0); PG8_SCHED; PG8_LDA(At, 0, 0); PG8_STAGE(PG8_SA(1, 1), a1 + hstepA, voffA);
;             PG8_WAIT_L(8); PG8_BAR; PG8_WAIT_L(0); PG8_MMA(0, 0, At, B0); PG8_BAR; PG8_SCHED;
;             PG8_LDB(B1, 0, 1); PG8_STAGE(PG8_SB(0, 0), b2, voffB);
;             PG8_BAR; PG8_WAIT_L(0); PG8_MMA(0, 1, At, B1); PG8_BAR;
;             PG8_LDA(At, 0, 1); PG8_STAGE(PG8_SA(0, 0), a2, voffA);
;             PG8_BAR; PG8_WAIT_L(0); PG8_MMA(1, 0, At, B0); PG8_BAR; PG8_SCHED;
;             PG8_STAGE(PG8_SB(0, 1), b2 + hstepB, voffB);
;             PG8_WAIT_V(6); PG8_BAR; PG8_MMA(1, 1, At, B1); PG8_BAR;
.LBB0_637:
	s_ashr_i32 s31, s30, 31
	v_cmp_lt_i64_e32 vcc, s[34:35], v[168:169]
	s_lshl_b64 s[34:35], s[30:31], 19
	s_add_u32 s34, s60, s34
	s_addc_u32 s35, s61, s35
	s_and_b64 s[36:37], vcc, exec
	s_cselect_b32 s31, s35, s41
	s_cselect_b32 s72, s34, s40
	s_ashr_i32 s29, s28, 31
	s_lshl_b64 s[36:37], s[28:29], 19
	s_add_u32 s36, s5, s36
	s_addc_u32 s37, s6, s37
	s_and_b64 s[44:45], vcc, exec
	s_cselect_b32 s29, s37, s43
	s_cselect_b32 s73, s36, s42
	s_add_u32 s40, s40, 0x40080
	s_addc_u32 s41, s41, 0
	s_add_u32 s74, s42, 0x100
	s_addc_u32 s75, s43, 0
	s_mov_b32 s76, -2
	ds_read_b128 v[128:131], v185
	ds_read_b128 v[132:135], v185 offset:1024
	ds_read_b128 v[136:139], v185 offset:2048
	ds_read_b128 v[140:143], v185 offset:3072
	s_add_u32 s42, s40, 0xfffc0080
	s_addc_u32 s43, s41, -1
	s_cmp_eq_u32 s76, 12
	s_cselect_b32 s45, s31, s43
	s_cselect_b32 s44, s72, s42
	s_cselect_b32 s43, s29, s75
	s_cselect_b32 s42, s73, s74
	s_add_i32 m0, s39, 0xc000
	ds_read_b128 v[144:147], v186
	ds_read_b128 v[148:151], v186 offset:1024
	ds_read_b128 v[152:155], v186 offset:2048
	ds_read_b128 v[172:175], v186 offset:3072
	ds_read_b128 v[176:179], v186 offset:4096
	ds_read_b128 v[188:191], v186 offset:5120
	ds_read_b128 v[192:195], v186 offset:6144
	ds_read_b128 v[196:199], v186 offset:7168
	global_load_lds_dwordx4 v164, s[40:41]
	s_add_i32 m0, s39, 0xe000
	s_nop 0
	global_load_lds_dwordx4 v166, s[40:41]
	ds_read_b128 v[200:203], v187
	ds_read_b128 v[204:207], v187 offset:1024
	ds_read_b128 v[208:211], v187 offset:2048
	ds_read_b128 v[212:215], v187 offset:3072
	s_waitcnt lgkmcnt(0)
	s_barrier
	s_setprio 1
	v_mfma_f32_16x16x32_bf16 v[124:127], v[128:131], v[144:147], 0
	v_mfma_f32_16x16x32_bf16 v[116:119], v[136:139], v[144:147], 0
	v_mfma_f32_16x16x32_bf16 v[108:111], v[128:131], v[152:155], 0
	v_mfma_f32_16x16x32_bf16 v[100:103], v[136:139], v[152:155], 0
	v_mfma_f32_16x16x32_bf16 v[92:95], v[128:131], v[176:179], 0
	v_mfma_f32_16x16x32_bf16 v[84:87], v[136:139], v[176:179], 0
	v_mfma_f32_16x16x32_bf16 v[76:79], v[128:131], v[192:195], 0
	v_mfma_f32_16x16x32_bf16 v[68:71], v[136:139], v[192:195], 0
	v_mfma_f32_16x16x32_bf16 v[124:127], v[132:135], v[148:151], v[124:127]
	v_mfma_f32_16x16x32_bf16 v[116:119], v[140:143], v[148:151], v[116:119]
	v_mfma_f32_16x16x32_bf16 v[108:111], v[132:135], v[172:175], v[108:111]
	v_mfma_f32_16x16x32_bf16 v[100:103], v[140:143], v[172:175], v[100:103]
	v_mfma_f32_16x16x32_bf16 v[92:95], v[132:135], v[188:191], v[92:95]
	v_mfma_f32_16x16x32_bf16 v[84:87], v[140:143], v[188:191], v[84:87]
	v_mfma_f32_16x16x32_bf16 v[76:79], v[132:135], v[196:199], v[76:79]
	v_mfma_f32_16x16x32_bf16 v[68:71], v[140:143], v[196:199], v[68:71]
	v_mfma_f32_16x16x32_bf16 v[120:123], v[200:203], v[144:147], 0
	v_mfma_f32_16x16x32_bf16 v[112:115], v[208:211], v[144:147], 0
	v_mfma_f32_16x16x32_bf16 v[104:107], v[200:203], v[152:155], 0
	v_mfma_f32_16x16x32_bf16 v[96:99], v[208:211], v[152:155], 0
	v_mfma_f32_16x16x32_bf16 v[88:91], v[200:203], v[176:179], 0
	v_mfma_f32_16x16x32_bf16 v[80:83], v[208:211], v[176:179], 0
	v_mfma_f32_16x16x32_bf16 v[72:75], v[200:203], v[192:195], 0
	v_mfma_f32_16x16x32_bf16 v[64:67], v[208:211], v[192:195], 0
	v_mfma_f32_16x16x32_bf16 v[120:123], v[204:207], v[148:151], v[120:123]
	v_mfma_f32_16x16x32_bf16 v[112:115], v[212:215], v[148:151], v[112:115]
	v_mfma_f32_16x16x32_bf16 v[104:107], v[204:207], v[172:175], v[104:107]
	v_mfma_f32_16x16x32_bf16 v[96:99], v[212:215], v[172:175], v[96:99]
	v_mfma_f32_16x16x32_bf16 v[88:91], v[204:207], v[188:191], v[88:91]
	v_mfma_f32_16x16x32_bf16 v[80:83], v[212:215], v[188:191], v[80:83]
	v_mfma_f32_16x16x32_bf16 v[72:75], v[204:207], v[196:199], v[72:75]
	v_mfma_f32_16x16x32_bf16 v[64:67], v[212:215], v[196:199], v[64:67]
	s_setprio 0
	s_barrier
	s_nop 1
	ds_read_b128 v[144:147], v186 offset:16384
	ds_read_b128 v[148:151], v186 offset:17408
	ds_read_b128 v[152:155], v186 offset:18432
	ds_read_b128 v[172:175], v186 offset:19456
	ds_read_b128 v[176:179], v186 offset:20480
	ds_read_b128 v[188:191], v186 offset:21504
	ds_read_b128 v[192:195], v186 offset:22528
	ds_read_b128 v[196:199], v186 offset:23552
	s_add_i32 s77, s69, s7
	v_lshl_add_u64 v[180:181], s[42:43], 0, v[158:159]
	s_mov_b32 m0, s77
	s_nop 0
	global_load_lds_dwordx4 v158, s[42:43]
	v_lshl_add_u64 v[216:217], s[42:43], 0, v[162:163]
	s_add_i32 m0, s77, 0x2000
	s_nop 0
	global_load_lds_dwordx4 v162, s[42:43]
	s_mov_b32 m0, s39
	v_lshl_add_u64 v[220:221], s[44:45], 0, v[156:157]
	global_load_lds_dwordx4 v156, s[44:45]
	v_lshl_add_u64 v[222:223], s[44:45], 0, v[160:161]
	s_mov_b32 m0, s46
	s_nop 0
	global_load_lds_dwordx4 v160, s[44:45]
	s_add_u32 s78, s42, 0x40000
	s_addc_u32 s79, s43, 0
	s_add_i32 s77, s70, s7
	s_mov_b32 m0, s77
	s_nop 0
	global_load_lds_dwordx4 v158, s[78:79]
	s_add_i32 m0, s77, 0x2000
	s_nop 0
	global_load_lds_dwordx4 v162, s[78:79]
	s_waitcnt vmcnt(6)
	s_waitcnt lgkmcnt(0)
	s_barrier
; #define PG8_STAGE(bufoff, gbase, voff) do { _Pragma("unroll") for (int _i = 0; _i < 2; ++_i) \
;         __builtin_amdgcn_global_load_lds((const unsigned*)((const char*)(gbase) + (voff)[_i]), (LAS unsigned*)(lds + (bufoff) + ldsw + _i * 8192), 16, 0, 0); } while (0)
; #define PG8_LDA(dst, b, h) do { _Pragma("unroll") for (int m = 0; m < 4; ++m) _Pragma("unroll") for (int k = 0; k < 2; ++k) dst[m][k] = *(const LAS bf16x8*)(lds + PG8_SA(b, h) + aoff + m * 2048 + k * 1024); } while (0)
; #define PG8_LDB(dst, b, h) do { _Pragma("unroll") for (int n = 0; n < 2; ++n) _Pragma("unroll") for (int k = 0; k < 2; ++k) dst[n][k] = *(const LAS bf16x8*)(lds + PG8_SB(b, h) + boff + n * 2048 + k * 1024); } while (0)
; #define PG8_MMA(ai, bj, At, Bt) do { __builtin_amdgcn_s_setprio(1); _Pragma("unroll") for (int m = 0; m < 4; ++m) _Pragma("unroll") for (int n = 0; n < 2; ++n) _Pragma("unroll") for (int k = 0; k < 2; ++k) \
;         acc[ai][bj][m][n] = __builtin_amdgcn_mfma_f32_16x16x32_bf16(Bt[n][k], At[m][k], acc[ai][bj][m][n], 0, 0, 0); __builtin_amdgcn_s_setprio(0); } while (0)
; #define PG8_WAIT_V(n) asm volatile("s_waitcnt vmcnt(" #n ")" ::: "memory")
; #define PG8_WAIT_L(n) asm volatile("s_waitcnt lgkmcnt(" #n ")" ::: "memory")
; #define PG8_BAR __builtin_amdgcn_s_barrier()
; #define PG8_SCHED __builtin_amdgcn_sched_barrier(0)
; template <class Epi>
; __device__ __forceinline__ void gemm_phase(LAS unsigned char* lds, const Gemm g, const StaticOrder& S, const Epi& E) {
;     ...
;             PG8_BAR; PG8_WAIT_L(0); PG8_MMA(1, 0, At, B0); PG8_BAR; PG8_SCHED;
;             PG8_STAGE(PG8_SB(0, 1), b2 + hstepB, voffB);
;             PG8_WAIT_V(6); PG8_BAR; PG8_MMA(1, 1, At, B1); PG8_BAR;
;             PG8_LDB(B0, 1, 0); PG8_SCHED; PG8_LDA(At, 1, 0); PG8_STAGE(PG8_SA(0, 1), a2 + hstepA, voffA);
;             PG8_WAIT_L(8); PG8_BAR; PG8_WAIT_L(0); PG8_MMA(0, 0, At, B0); PG8_BAR; PG8_SCHED;
;             PG8_LDB(B1, 1, 1); PG8_STAGE(PG8_SB(1, 0), b3, voffB);
;             PG8_BAR; PG8_WAIT_L(0); PG8_MMA(0, 1, At, B1); PG8_BAR;
;             PG8_LDA(At, 1, 1); PG8_STAGE(PG8_SA(1, 0), a3, voffA);
	s_setprio 1
	v_mfma_f32_16x16x32_bf16 v[60:63], v[128:131], v[144:147], 0
	v_mfma_f32_16x16x32_bf16 v[52:55], v[136:139], v[144:147], 0
	v_mfma_f32_16x16x32_bf16 v[44:47], v[128:131], v[152:155], 0
	v_mfma_f32_16x16x32_bf16 v[36:39], v[136:139], v[152:155], 0
	v_mfma_f32_16x16x32_bf16 v[28:31], v[128:131], v[176:179], 0
	v_mfma_f32_16x16x32_bf16 v[20:23], v[136:139], v[176:179], 0
	v_mfma_f32_16x16x32_bf16 v[12:15], v[128:131], v[192:195], 0
	v_mfma_f32_16x16x32_bf16 v[4:7], v[136:139], v[192:195], 0
	v_mfma_f32_16x16x32_bf16 v[60:63], v[132:135], v[148:151], v[60:63]
	v_mfma_f32_16x16x32_bf16 v[52:55], v[140:143], v[148:151], v[52:55]
	v_mfma_f32_16x16x32_bf16 v[44:47], v[132:135], v[172:175], v[44:47]
	v_mfma_f32_16x16x32_bf16 v[36:39], v[140:143], v[172:175], v[36:39]
	v_mfma_f32_16x16x32_bf16 v[28:31], v[132:135], v[188:191], v[28:31]
	v_mfma_f32_16x16x32_bf16 v[20:23], v[140:143], v[188:191], v[20:23]
	v_mfma_f32_16x16x32_bf16 v[12:15], v[132:135], v[196:199], v[12:15]
	v_mfma_f32_16x16x32_bf16 v[4:7], v[140:143], v[196:199], v[4:7]
	v_mfma_f32_16x16x32_bf16 v[56:59], v[200:203], v[144:147], 0
	v_mfma_f32_16x16x32_bf16 v[48:51], v[208:211], v[144:147], 0
	v_mfma_f32_16x16x32_bf16 v[40:43], v[200:203], v[152:155], 0
	v_mfma_f32_16x16x32_bf16 v[32:35], v[208:211], v[152:155], 0
	v_mfma_f32_16x16x32_bf16 v[24:27], v[200:203], v[176:179], 0
	v_mfma_f32_16x16x32_bf16 v[16:19], v[208:211], v[176:179], 0
	v_mfma_f32_16x16x32_bf16 v[8:11], v[200:203], v[192:195], 0
	v_mfma_f32_16x16x32_bf16 v[0:3], v[208:211], v[192:195], 0
	v_mfma_f32_16x16x32_bf16 v[56:59], v[204:207], v[148:151], v[56:59]
	v_mfma_f32_16x16x32_bf16 v[48:51], v[212:215], v[148:151], v[48:51]
	v_mfma_f32_16x16x32_bf16 v[40:43], v[204:207], v[172:175], v[40:43]
	v_mfma_f32_16x16x32_bf16 v[32:35], v[212:215], v[172:175], v[32:35]
	v_mfma_f32_16x16x32_bf16 v[24:27], v[204:207], v[188:191], v[24:27]
	v_mfma_f32_16x16x32_bf16 v[16:19], v[212:215], v[188:191], v[16:19]
	v_mfma_f32_16x16x32_bf16 v[8:11], v[204:207], v[196:199], v[8:11]
	v_mfma_f32_16x16x32_bf16 v[0:3], v[212:215], v[196:199], v[0:3]
	s_setprio 0
	s_add_i32 s77, 0, 0x18000
	v_add_u32_e32 v140, s77, v183
	s_barrier
	ds_read_b128 v[128:131], v140
	ds_read_b128 v[132:135], v140 offset:1024
	ds_read_b128 v[136:139], v140 offset:2048
	ds_read_b128 v[140:143], v140 offset:3072
	s_add_u32 s44, s44, 0x40000
	s_addc_u32 s45, s45, 0
	s_mov_b32 m0, s47
	ds_read_b128 v[144:147], v186 offset:32768
	ds_read_b128 v[148:151], v186 offset:33792
	ds_read_b128 v[152:155], v186 offset:34816
	ds_read_b128 v[172:175], v186 offset:35840
	ds_read_b128 v[176:179], v186 offset:36864
	ds_read_b128 v[188:191], v186 offset:37888
	ds_read_b128 v[192:195], v186 offset:38912
	ds_read_b128 v[196:199], v186 offset:39936
	global_load_lds_dwordx4 v156, s[44:45]
	s_mov_b32 m0, s48
	s_nop 0
	global_load_lds_dwordx4 v160, s[44:45]
	s_add_i32 s44, 0, 0x1c000
	v_add_u32_e32 v212, s44, v183
	ds_read_b128 v[200:203], v212
	ds_read_b128 v[204:207], v212 offset:1024
	ds_read_b128 v[208:211], v212 offset:2048
	ds_read_b128 v[212:215], v212 offset:3072
	s_waitcnt lgkmcnt(0)
	s_barrier
	s_setprio 1
	v_mfma_f32_16x16x32_bf16 v[124:127], v[128:131], v[144:147], v[124:127]
	v_mfma_f32_16x16x32_bf16 v[116:119], v[136:139], v[144:147], v[116:119]
	v_mfma_f32_16x16x32_bf16 v[108:111], v[128:131], v[152:155], v[108:111]
	v_mfma_f32_16x16x32_bf16 v[100:103], v[136:139], v[152:155], v[100:103]
	v_mfma_f32_16x16x32_bf16 v[92:95], v[128:131], v[176:179], v[92:95]
	v_mfma_f32_16x16x32_bf16 v[84:87], v[136:139], v[176:179], v[84:87]
	v_mfma_f32_16x16x32_bf16 v[76:79], v[128:131], v[192:195], v[76:79]
	v_mfma_f32_16x16x32_bf16 v[68:71], v[136:139], v[192:195], v[68:71]
	v_mfma_f32_16x16x32_bf16 v[124:127], v[132:135], v[148:151], v[124:127]
	v_mfma_f32_16x16x32_bf16 v[116:119], v[140:143], v[148:151], v[116:119]
	v_mfma_f32_16x16x32_bf16 v[108:111], v[132:135], v[172:175], v[108:111]
	v_mfma_f32_16x16x32_bf16 v[100:103], v[140:143], v[172:175], v[100:103]
	v_mfma_f32_16x16x32_bf16 v[92:95], v[132:135], v[188:191], v[92:95]
	v_mfma_f32_16x16x32_bf16 v[84:87], v[140:143], v[188:191], v[84:87]
	v_mfma_f32_16x16x32_bf16 v[76:79], v[132:135], v[196:199], v[76:79]
	v_mfma_f32_16x16x32_bf16 v[68:71], v[140:143], v[196:199], v[68:71]
	v_mfma_f32_16x16x32_bf16 v[120:123], v[200:203], v[144:147], v[120:123]
	v_mfma_f32_16x16x32_bf16 v[112:115], v[208:211], v[144:147], v[112:115]
	v_mfma_f32_16x16x32_bf16 v[104:107], v[200:203], v[152:155], v[104:107]
	v_mfma_f32_16x16x32_bf16 v[96:99], v[208:211], v[152:155], v[96:99]
	v_mfma_f32_16x16x32_bf16 v[88:91], v[200:203], v[176:179], v[88:91]
	v_mfma_f32_16x16x32_bf16 v[80:83], v[208:211], v[176:179], v[80:83]
	v_mfma_f32_16x16x32_bf16 v[72:75], v[200:203], v[192:195], v[72:75]
	v_mfma_f32_16x16x32_bf16 v[64:67], v[208:211], v[192:195], v[64:67]
	v_mfma_f32_16x16x32_bf16 v[120:123], v[204:207], v[148:151], v[120:123]
	v_mfma_f32_16x16x32_bf16 v[112:115], v[212:215], v[148:151], v[112:115]
	v_mfma_f32_16x16x32_bf16 v[104:107], v[204:207], v[172:175], v[104:107]
	v_mfma_f32_16x16x32_bf16 v[96:99], v[212:215], v[172:175], v[96:99]
	v_mfma_f32_16x16x32_bf16 v[88:91], v[204:207], v[188:191], v[88:91]
	v_mfma_f32_16x16x32_bf16 v[80:83], v[212:215], v[188:191], v[80:83]
	v_mfma_f32_16x16x32_bf16 v[72:75], v[204:207], v[196:199], v[72:75]
	v_mfma_f32_16x16x32_bf16 v[64:67], v[212:215], v[196:199], v[64:67]
	s_setprio 0
	s_barrier
; #define PG8_STAGE(bufoff, gbase, voff) do { _Pragma("unroll") for (int _i = 0; _i < 2; ++_i) \
;         __builtin_amdgcn_global_load_lds((const unsigned*)((const char*)(gbase) + (voff)[_i]), (LAS unsigned*)(lds + (bufoff) + ldsw + _i * 8192), 16, 0, 0); } while (0)
; #define PG8_LDA(dst, b, h) do { _Pragma("unroll") for (int m = 0; m < 4; ++m) _Pragma("unroll") for (int k = 0; k < 2; ++k) dst[m][k] = *(const LAS bf16x8*)(lds + PG8_SA(b, h) + aoff + m * 2048 + k * 1024); } while (0)
; #define PG8_LDB(dst, b, h) do { _Pragma("unroll") for (int n = 0; n < 2; ++n) _Pragma("unroll") for (int k = 0; k < 2; ++k) dst[n][k] = *(const LAS bf16x8*)(lds + PG8_SB(b, h) + boff + n * 2048 + k * 1024); } while (0)
; #define PG8_MMA(ai, bj, At, Bt) do { __builtin_amdgcn_s_setprio(1); _Pragma("unroll") for (int m = 0; m < 4; ++m) _Pragma("unroll") for (int n = 0; n < 2; ++n) _Pragma("unroll") for (int k = 0; k < 2; ++k) \
;         acc[ai][bj][m][n] = __builtin_amdgcn_mfma_f32_16x16x32_bf16(Bt[n][k], At[m][k], acc[ai][bj][m][n], 0, 0, 0); __builtin_amdgcn_s_setprio(0); } while (0)
; #define PG8_WAIT_V(n) asm volatile("s_waitcnt vmcnt(" #n ")" ::: "memory")
; #define PG8_WAIT_L(n) asm volatile("s_waitcnt lgkmcnt(" #n ")" ::: "memory")
; #define PG8_BAR __builtin_amdgcn_s_barrier()
; #define PG8_SCHED __builtin_amdgcn_sched_barrier(0)
; template <class Epi>
; __device__ __forceinline__ void gemm_phase(LAS unsigned char* lds, const Gemm g, const StaticOrder& S, const Epi& E) {
;     ...
;             PG8_LDB(B0, 0, 0); PG8_SCHED; PG8_LDA(At, 0, 0); PG8_STAGE(PG8_SA(1, 1), a1 + hstepA, voffA);
;             PG8_WAIT_L(8); PG8_BAR; PG8_WAIT_L(0); PG8_MMA(0, 0, At, B0); PG8_BAR; PG8_SCHED;
;             PG8_LDB(B1, 0, 1); PG8_STAGE(PG8_SB(0, 0), b2, voffB);
;             PG8_BAR; PG8_WAIT_L(0); PG8_MMA(0, 1, At, B1); PG8_BAR;
;             PG8_LDA(At, 0, 1); PG8_STAGE(PG8_SA(0, 0), a2, voffA);
;     ...
;             PG8_LDA(At, 1, 1); PG8_STAGE(PG8_SA(1, 0), a3, voffA);
;             PG8_BAR; PG8_WAIT_L(0); PG8_MMA(1, 0, At, B0); PG8_BAR; PG8_SCHED;
;             PG8_STAGE(PG8_SB(1, 1), b3 + hstepB, voffB);
;             PG8_WAIT_V(6); PG8_BAR; PG8_MMA(1, 1, At, B1); PG8_BAR;
	s_nop 1
	ds_read_b128 v[144:147], v186 offset:49152
	ds_read_b128 v[148:151], v186 offset:50176
	ds_read_b128 v[152:155], v186 offset:51200
	ds_read_b128 v[172:175], v186 offset:52224
	ds_read_b128 v[176:179], v186 offset:53248
	ds_read_b128 v[188:191], v186 offset:54272
	ds_read_b128 v[192:195], v186 offset:55296
	ds_read_b128 v[196:199], v186 offset:56320
	s_add_i32 s45, s77, s7
	s_mov_b32 m0, s45
	s_nop 0
	s_add_u32 s100, s42, s12
	s_addc_u32 s101, s43, s13
	global_load_lds_dwordx4 v158, s[100:101]
	s_add_i32 m0, s45, 0x2000
	s_nop 0
	s_add_u32 s100, s42, s12
	s_addc_u32 s101, s43, s13
	global_load_lds_dwordx4 v162, s[100:101]
	s_mov_b32 m0, s63
	v_lshl_add_u64 v[254:255], v[220:221], 0, s[12:13]
	global_load_lds_dwordx4 v[254:255], off
	v_lshl_add_u64 v[180:181], v[222:223], 0, s[12:13]
	s_mov_b32 m0, s68
	s_nop 0
	global_load_lds_dwordx4 v[180:181], off
	s_add_u32 s42, s42, 0x40080
	s_addc_u32 s43, s43, 0
	s_add_i32 s44, s44, s7
	s_mov_b32 m0, s44
	s_nop 0
	global_load_lds_dwordx4 v158, s[42:43]
	s_add_i32 m0, s44, 0x2000
	s_nop 0
	global_load_lds_dwordx4 v162, s[42:43]
	s_waitcnt vmcnt(6)
	s_waitcnt lgkmcnt(0)
	s_barrier
	s_setprio 1
	v_mfma_f32_16x16x32_bf16 v[60:63], v[128:131], v[144:147], v[60:63]
	v_mfma_f32_16x16x32_bf16 v[52:55], v[136:139], v[144:147], v[52:55]
	v_mfma_f32_16x16x32_bf16 v[44:47], v[128:131], v[152:155], v[44:47]
	v_mfma_f32_16x16x32_bf16 v[36:39], v[136:139], v[152:155], v[36:39]
	v_mfma_f32_16x16x32_bf16 v[28:31], v[128:131], v[176:179], v[28:31]
	v_mfma_f32_16x16x32_bf16 v[20:23], v[136:139], v[176:179], v[20:23]
	v_mfma_f32_16x16x32_bf16 v[12:15], v[128:131], v[192:195], v[12:15]
	v_mfma_f32_16x16x32_bf16 v[4:7], v[136:139], v[192:195], v[4:7]
	v_mfma_f32_16x16x32_bf16 v[60:63], v[132:135], v[148:151], v[60:63]
	v_mfma_f32_16x16x32_bf16 v[52:55], v[140:143], v[148:151], v[52:55]
	v_mfma_f32_16x16x32_bf16 v[44:47], v[132:135], v[172:175], v[44:47]
	v_mfma_f32_16x16x32_bf16 v[36:39], v[140:143], v[172:175], v[36:39]
	v_mfma_f32_16x16x32_bf16 v[28:31], v[132:135], v[188:191], v[28:31]
	v_mfma_f32_16x16x32_bf16 v[20:23], v[140:143], v[188:191], v[20:23]
	v_mfma_f32_16x16x32_bf16 v[12:15], v[132:135], v[196:199], v[12:15]
	v_mfma_f32_16x16x32_bf16 v[4:7], v[140:143], v[196:199], v[4:7]
	v_mfma_f32_16x16x32_bf16 v[56:59], v[200:203], v[144:147], v[56:59]
	v_mfma_f32_16x16x32_bf16 v[48:51], v[208:211], v[144:147], v[48:51]
	v_mfma_f32_16x16x32_bf16 v[40:43], v[200:203], v[152:155], v[40:43]
	v_mfma_f32_16x16x32_bf16 v[32:35], v[208:211], v[152:155], v[32:35]
	v_mfma_f32_16x16x32_bf16 v[24:27], v[200:203], v[176:179], v[24:27]
	v_mfma_f32_16x16x32_bf16 v[16:19], v[208:211], v[176:179], v[16:19]
	v_mfma_f32_16x16x32_bf16 v[8:11], v[200:203], v[192:195], v[8:11]
	v_mfma_f32_16x16x32_bf16 v[0:3], v[208:211], v[192:195], v[0:3]
	v_mfma_f32_16x16x32_bf16 v[56:59], v[204:207], v[148:151], v[56:59]
	v_mfma_f32_16x16x32_bf16 v[48:51], v[212:215], v[148:151], v[48:51]
	v_mfma_f32_16x16x32_bf16 v[40:43], v[204:207], v[172:175], v[40:43]
	v_mfma_f32_16x16x32_bf16 v[32:35], v[212:215], v[172:175], v[32:35]
	v_mfma_f32_16x16x32_bf16 v[24:27], v[204:207], v[188:191], v[24:27]
	v_mfma_f32_16x16x32_bf16 v[16:19], v[212:215], v[188:191], v[16:19]
	v_mfma_f32_16x16x32_bf16 v[8:11], v[204:207], v[196:199], v[8:11]
	v_mfma_f32_16x16x32_bf16 v[0:3], v[212:215], v[196:199], v[0:3]
	s_setprio 0
	s_add_i32 s76, s76, 2
	s_add_u32 s40, s40, 0x100
	s_addc_u32 s41, s41, 0
	s_add_u32 s74, s74, 0x100
	s_addc_u32 s75, s75, 0
	s_cmp_gt_u32 s76, 13
	s_barrier
.LBB0_638:
	ds_read_b128 v[128:131], v185
	ds_read_b128 v[132:135], v185 offset:1024
	ds_read_b128 v[136:139], v185 offset:2048
	ds_read_b128 v[140:143], v185 offset:3072
	s_add_u32 s42, s40, 0xfffc0080
	s_addc_u32 s43, s41, -1
	s_cmp_eq_u32 s76, 12
	s_cselect_b32 s45, s31, s43
	s_cselect_b32 s44, s72, s42
	s_cselect_b32 s43, s29, s75
	s_cselect_b32 s42, s73, s74
	s_add_i32 m0, s39, 0xc000
	ds_read_b128 v[144:147], v186
	ds_read_b128 v[148:151], v186 offset:1024
	ds_read_b128 v[152:155], v186 offset:2048
	ds_read_b128 v[172:175], v186 offset:3072
	ds_read_b128 v[176:179], v186 offset:4096
	ds_read_b128 v[188:191], v186 offset:5120
	ds_read_b128 v[192:195], v186 offset:6144
	ds_read_b128 v[196:199], v186 offset:7168
	global_load_lds_dwordx4 v164, s[40:41]
	s_add_i32 m0, s39, 0xe000
	s_nop 0
	global_load_lds_dwordx4 v166, s[40:41]
	ds_read_b128 v[200:203], v187
	ds_read_b128 v[204:207], v187 offset:1024
	ds_read_b128 v[208:211], v187 offset:2048
	ds_read_b128 v[212:215], v187 offset:3072
	s_waitcnt lgkmcnt(0)
	s_barrier
; #define PG8_STAGE(bufoff, gbase, voff) do { _Pragma("unroll") for (int _i = 0; _i < 2; ++_i) \
;         __builtin_amdgcn_global_load_lds((const unsigned*)((const char*)(gbase) + (voff)[_i]), (LAS unsigned*)(lds + (bufoff) + ldsw + _i * 8192), 16, 0, 0); } while (0)
; #define PG8_MMA(ai, bj, At, Bt) do { __builtin_amdgcn_s_setprio(1); _Pragma("unroll") for (int m = 0; m < 4; ++m) _Pragma("unroll") for (int n = 0; n < 2; ++n) _Pragma("unroll") for (int k = 0; k < 2; ++k) \
;         acc[ai][bj][m][n] = __builtin_amdgcn_mfma_f32_16x16x32_bf16(Bt[n][k], At[m][k], acc[ai][bj][m][n], 0, 0, 0); __builtin_amdgcn_s_setprio(0); } while (0)
; #define PG8_WAIT_V(n) asm volatile("s_waitcnt vmcnt(" #n ")" ::: "memory")
; #define PG8_WAIT_L(n) asm volatile("s_waitcnt lgkmcnt(" #n ")" ::: "memory")
; #define PG8_BAR __builtin_amdgcn_s_barrier()
; #define PG8_SCHED __builtin_amdgcn_sched_barrier(0)
; template <class Epi>
; __device__ __forceinline__ void gemm_phase(LAS unsigned char* lds, const Gemm g, const StaticOrder& S, const Epi& E) {
;     ...
;             PG8_BAR; PG8_WAIT_L(0); PG8_MMA(1, 0, At, B0); PG8_BAR; PG8_SCHED;
;             PG8_STAGE(PG8_SB(0, 1), b2 + hstepB, voffB);
;             PG8_WAIT_V(6); PG8_BAR; PG8_MMA(1, 1, At, B1); PG8_BAR;
	s_setprio 1
	v_mfma_f32_16x16x32_bf16 v[124:127], v[128:131], v[144:147], v[124:127]
	v_mfma_f32_16x16x32_bf16 v[116:119], v[136:139], v[144:147], v[116:119]
	v_mfma_f32_16x16x32_bf16 v[108:111], v[128:131], v[152:155], v[108:111]
	v_mfma_f32_16x16x32_bf16 v[100:103], v[136:139], v[152:155], v[100:103]
	v_mfma_f32_16x16x32_bf16 v[92:95], v[128:131], v[176:179], v[92:95]
	v_mfma_f32_16x16x32_bf16 v[84:87], v[136:139], v[176:179], v[84:87]
	v_mfma_f32_16x16x32_bf16 v[76:79], v[128:131], v[192:195], v[76:79]
	v_mfma_f32_16x16x32_bf16 v[68:71], v[136:139], v[192:195], v[68:71]
	v_mfma_f32_16x16x32_bf16 v[124:127], v[132:135], v[148:151], v[124:127]
	v_mfma_f32_16x16x32_bf16 v[116:119], v[140:143], v[148:151], v[116:119]
	v_mfma_f32_16x16x32_bf16 v[108:111], v[132:135], v[172:175], v[108:111]
	v_mfma_f32_16x16x32_bf16 v[100:103], v[140:143], v[172:175], v[100:103]
	v_mfma_f32_16x16x32_bf16 v[92:95], v[132:135], v[188:191], v[92:95]
	v_mfma_f32_16x16x32_bf16 v[84:87], v[140:143], v[188:191], v[84:87]
	v_mfma_f32_16x16x32_bf16 v[76:79], v[132:135], v[196:199], v[76:79]
	v_mfma_f32_16x16x32_bf16 v[68:71], v[140:143], v[196:199], v[68:71]
	v_mfma_f32_16x16x32_bf16 v[120:123], v[200:203], v[144:147], v[120:123]
	v_mfma_f32_16x16x32_bf16 v[112:115], v[208:211], v[144:147], v[112:115]
	v_mfma_f32_16x16x32_bf16 v[104:107], v[200:203], v[152:155], v[104:107]
	v_mfma_f32_16x16x32_bf16 v[96:99], v[208:211], v[152:155], v[96:99]
	v_mfma_f32_16x16x32_bf16 v[88:91], v[200:203], v[176:179], v[88:91]
	v_mfma_f32_16x16x32_bf16 v[80:83], v[208:211], v[176:179], v[80:83]
	v_mfma_f32_16x16x32_bf16 v[72:75], v[200:203], v[192:195], v[72:75]
	v_mfma_f32_16x16x32_bf16 v[64:67], v[208:211], v[192:195], v[64:67]
	v_mfma_f32_16x16x32_bf16 v[120:123], v[204:207], v[148:151], v[120:123]
	v_mfma_f32_16x16x32_bf16 v[112:115], v[212:215], v[148:151], v[112:115]
	v_mfma_f32_16x16x32_bf16 v[104:107], v[204:207], v[172:175], v[104:107]
	v_mfma_f32_16x16x32_bf16 v[96:99], v[212:215], v[172:175], v[96:99]
	v_mfma_f32_16x16x32_bf16 v[88:91], v[204:207], v[188:191], v[88:91]
	v_mfma_f32_16x16x32_bf16 v[80:83], v[212:215], v[188:191], v[80:83]
	v_mfma_f32_16x16x32_bf16 v[72:75], v[204:207], v[196:199], v[72:75]
	v_mfma_f32_16x16x32_bf16 v[64:67], v[212:215], v[196:199], v[64:67]
	s_setprio 0
	s_barrier
	s_nop 1
	ds_read_b128 v[144:147], v186 offset:16384
	ds_read_b128 v[148:151], v186 offset:17408
	ds_read_b128 v[152:155], v186 offset:18432
	ds_read_b128 v[172:175], v186 offset:19456
	ds_read_b128 v[176:179], v186 offset:20480
	ds_read_b128 v[188:191], v186 offset:21504
	ds_read_b128 v[192:195], v186 offset:22528
	ds_read_b128 v[196:199], v186 offset:23552
	s_add_i32 s77, s69, s7
	v_lshl_add_u64 v[180:181], s[42:43], 0, v[158:159]
	s_mov_b32 m0, s77
	s_nop 0
	global_load_lds_dwordx4 v158, s[42:43]
	v_lshl_add_u64 v[216:217], s[42:43], 0, v[162:163]
	s_add_i32 m0, s77, 0x2000
	s_nop 0
	global_load_lds_dwordx4 v162, s[42:43]
	s_mov_b32 m0, s39
	v_lshl_add_u64 v[220:221], s[44:45], 0, v[156:157]
	global_load_lds_dwordx4 v156, s[44:45]
	v_lshl_add_u64 v[222:223], s[44:45], 0, v[160:161]
	s_mov_b32 m0, s46
	s_nop 0
	global_load_lds_dwordx4 v160, s[44:45]
	s_add_u32 s78, s42, 0x40000
	s_addc_u32 s79, s43, 0
	s_add_i32 s77, s70, s7
	s_mov_b32 m0, s77
	s_nop 0
	global_load_lds_dwordx4 v158, s[78:79]
	s_add_i32 m0, s77, 0x2000
	s_nop 0
	global_load_lds_dwordx4 v162, s[78:79]
	s_waitcnt vmcnt(6)
	s_waitcnt lgkmcnt(0)
	s_barrier
	s_setprio 1
	v_mfma_f32_16x16x32_bf16 v[60:63], v[128:131], v[144:147], v[60:63]
	v_mfma_f32_16x16x32_bf16 v[52:55], v[136:139], v[144:147], v[52:55]
	v_mfma_f32_16x16x32_bf16 v[44:47], v[128:131], v[152:155], v[44:47]
	v_mfma_f32_16x16x32_bf16 v[36:39], v[136:139], v[152:155], v[36:39]
	v_mfma_f32_16x16x32_bf16 v[28:31], v[128:131], v[176:179], v[28:31]
	v_mfma_f32_16x16x32_bf16 v[20:23], v[136:139], v[176:179], v[20:23]
	v_mfma_f32_16x16x32_bf16 v[12:15], v[128:131], v[192:195], v[12:15]
	v_mfma_f32_16x16x32_bf16 v[4:7], v[136:139], v[192:195], v[4:7]
	v_mfma_f32_16x16x32_bf16 v[60:63], v[132:135], v[148:151], v[60:63]
	v_mfma_f32_16x16x32_bf16 v[52:55], v[140:143], v[148:151], v[52:55]
	v_mfma_f32_16x16x32_bf16 v[44:47], v[132:135], v[172:175], v[44:47]
	v_mfma_f32_16x16x32_bf16 v[36:39], v[140:143], v[172:175], v[36:39]
	v_mfma_f32_16x16x32_bf16 v[28:31], v[132:135], v[188:191], v[28:31]
	v_mfma_f32_16x16x32_bf16 v[20:23], v[140:143], v[188:191], v[20:23]
	v_mfma_f32_16x16x32_bf16 v[12:15], v[132:135], v[196:199], v[12:15]
	v_mfma_f32_16x16x32_bf16 v[4:7], v[140:143], v[196:199], v[4:7]
	v_mfma_f32_16x16x32_bf16 v[56:59], v[200:203], v[144:147], v[56:59]
	v_mfma_f32_16x16x32_bf16 v[48:51], v[208:211], v[144:147], v[48:51]
	v_mfma_f32_16x16x32_bf16 v[40:43], v[200:203], v[152:155], v[40:43]
	v_mfma_f32_16x16x32_bf16 v[32:35], v[208:211], v[152:155], v[32:35]
	v_mfma_f32_16x16x32_bf16 v[24:27], v[200:203], v[176:179], v[24:27]
	v_mfma_f32_16x16x32_bf16 v[16:19], v[208:211], v[176:179], v[16:19]
	v_mfma_f32_16x16x32_bf16 v[8:11], v[200:203], v[192:195], v[8:11]
	v_mfma_f32_16x16x32_bf16 v[0:3], v[208:211], v[192:195], v[0:3]
	v_mfma_f32_16x16x32_bf16 v[56:59], v[204:207], v[148:151], v[56:59]
	v_mfma_f32_16x16x32_bf16 v[48:51], v[212:215], v[148:151], v[48:51]
	v_mfma_f32_16x16x32_bf16 v[40:43], v[204:207], v[172:175], v[40:43]
	v_mfma_f32_16x16x32_bf16 v[32:35], v[212:215], v[172:175], v[32:35]
	v_mfma_f32_16x16x32_bf16 v[24:27], v[204:207], v[188:191], v[24:27]
	v_mfma_f32_16x16x32_bf16 v[16:19], v[212:215], v[188:191], v[16:19]
	v_mfma_f32_16x16x32_bf16 v[8:11], v[204:207], v[196:199], v[8:11]
	v_mfma_f32_16x16x32_bf16 v[0:3], v[212:215], v[196:199], v[0:3]
	s_setprio 0
	s_add_i32 s77, 0, 0x18000
	v_add_u32_e32 v140, s77, v183
	s_barrier
; #define PG8_STAGE(bufoff, gbase, voff) do { _Pragma("unroll") for (int _i = 0; _i < 2; ++_i) \
;         __builtin_amdgcn_global_load_lds((const unsigned*)((const char*)(gbase) + (voff)[_i]), (LAS unsigned*)(lds + (bufoff) + ldsw + _i * 8192), 16, 0, 0); } while (0)
; #define PG8_LDA(dst, b, h) do { _Pragma("unroll") for (int m = 0; m < 4; ++m) _Pragma("unroll") for (int k = 0; k < 2; ++k) dst[m][k] = *(const LAS bf16x8*)(lds + PG8_SA(b, h) + aoff + m * 2048 + k * 1024); } while (0)
; #define PG8_LDB(dst, b, h) do { _Pragma("unroll") for (int n = 0; n < 2; ++n) _Pragma("unroll") for (int k = 0; k < 2; ++k) dst[n][k] = *(const LAS bf16x8*)(lds + PG8_SB(b, h) + boff + n * 2048 + k * 1024); } while (0)
; #define PG8_MMA(ai, bj, At, Bt) do { __builtin_amdgcn_s_setprio(1); _Pragma("unroll") for (int m = 0; m < 4; ++m) _Pragma("unroll") for (int n = 0; n < 2; ++n) _Pragma("unroll") for (int k = 0; k < 2; ++k) \
;         acc[ai][bj][m][n] = __builtin_amdgcn_mfma_f32_16x16x32_bf16(Bt[n][k], At[m][k], acc[ai][bj][m][n], 0, 0, 0); __builtin_amdgcn_s_setprio(0); } while (0)
; #define PG8_WAIT_V(n) asm volatile("s_waitcnt vmcnt(" #n ")" ::: "memory")
; #define PG8_WAIT_L(n) asm volatile("s_waitcnt lgkmcnt(" #n ")" ::: "memory")
; #define PG8_BAR __builtin_amdgcn_s_barrier()
; #define PG8_SCHED __builtin_amdgcn_sched_barrier(0)
; template <class Epi>
; __device__ __forceinline__ void gemm_phase(LAS unsigned char* lds, const Gemm g, const StaticOrder& S, const Epi& E) {
;     ...
;             PG8_LDB(B0, 1, 0); PG8_SCHED; PG8_LDA(At, 1, 0); PG8_STAGE(PG8_SA(0, 1), a2 + hstepA, voffA);
;             PG8_WAIT_L(8); PG8_BAR; PG8_WAIT_L(0); PG8_MMA(0, 0, At, B0); PG8_BAR; PG8_SCHED;
;             PG8_LDB(B1, 1, 1); PG8_STAGE(PG8_SB(1, 0), b3, voffB);
;             PG8_BAR; PG8_WAIT_L(0); PG8_MMA(0, 1, At, B1); PG8_BAR;
;             PG8_LDA(At, 1, 1); PG8_STAGE(PG8_SA(1, 0), a3, voffA);
;             PG8_BAR; PG8_WAIT_L(0); PG8_MMA(1, 0, At, B0); PG8_BAR; PG8_SCHED;
;             PG8_STAGE(PG8_SB(1, 1), b3 + hstepB, voffB);
;             PG8_WAIT_V(6); PG8_BAR; PG8_MMA(1, 1, At, B1); PG8_BAR;
	ds_read_b128 v[128:131], v140
	ds_read_b128 v[132:135], v140 offset:1024
	ds_read_b128 v[136:139], v140 offset:2048
	ds_read_b128 v[140:143], v140 offset:3072
	s_add_u32 s44, s44, 0x40000
	s_addc_u32 s45, s45, 0
	s_mov_b32 m0, s47
	ds_read_b128 v[144:147], v186 offset:32768
	ds_read_b128 v[148:151], v186 offset:33792
	ds_read_b128 v[152:155], v186 offset:34816
	ds_read_b128 v[172:175], v186 offset:35840
	ds_read_b128 v[176:179], v186 offset:36864
	ds_read_b128 v[188:191], v186 offset:37888
	ds_read_b128 v[192:195], v186 offset:38912
	ds_read_b128 v[196:199], v186 offset:39936
	global_load_lds_dwordx4 v156, s[44:45]
	s_mov_b32 m0, s48
	s_nop 0
	global_load_lds_dwordx4 v160, s[44:45]
	s_add_i32 s44, 0, 0x1c000
	v_add_u32_e32 v212, s44, v183
	ds_read_b128 v[200:203], v212
	ds_read_b128 v[204:207], v212 offset:1024
	ds_read_b128 v[208:211], v212 offset:2048
	ds_read_b128 v[212:215], v212 offset:3072
	s_waitcnt lgkmcnt(0)
	s_barrier
	s_setprio 1
	v_mfma_f32_16x16x32_bf16 v[124:127], v[128:131], v[144:147], v[124:127]
	v_mfma_f32_16x16x32_bf16 v[116:119], v[136:139], v[144:147], v[116:119]
	v_mfma_f32_16x16x32_bf16 v[108:111], v[128:131], v[152:155], v[108:111]
	v_mfma_f32_16x16x32_bf16 v[100:103], v[136:139], v[152:155], v[100:103]
	v_mfma_f32_16x16x32_bf16 v[92:95], v[128:131], v[176:179], v[92:95]
	v_mfma_f32_16x16x32_bf16 v[84:87], v[136:139], v[176:179], v[84:87]
	v_mfma_f32_16x16x32_bf16 v[76:79], v[128:131], v[192:195], v[76:79]
	v_mfma_f32_16x16x32_bf16 v[68:71], v[136:139], v[192:195], v[68:71]
	v_mfma_f32_16x16x32_bf16 v[124:127], v[132:135], v[148:151], v[124:127]
	v_mfma_f32_16x16x32_bf16 v[116:119], v[140:143], v[148:151], v[116:119]
	v_mfma_f32_16x16x32_bf16 v[108:111], v[132:135], v[172:175], v[108:111]
	v_mfma_f32_16x16x32_bf16 v[100:103], v[140:143], v[172:175], v[100:103]
	v_mfma_f32_16x16x32_bf16 v[92:95], v[132:135], v[188:191], v[92:95]
	v_mfma_f32_16x16x32_bf16 v[84:87], v[140:143], v[188:191], v[84:87]
	v_mfma_f32_16x16x32_bf16 v[76:79], v[132:135], v[196:199], v[76:79]
	v_mfma_f32_16x16x32_bf16 v[68:71], v[140:143], v[196:199], v[68:71]
	v_mfma_f32_16x16x32_bf16 v[120:123], v[200:203], v[144:147], v[120:123]
	v_mfma_f32_16x16x32_bf16 v[112:115], v[208:211], v[144:147], v[112:115]
	v_mfma_f32_16x16x32_bf16 v[104:107], v[200:203], v[152:155], v[104:107]
	v_mfma_f32_16x16x32_bf16 v[96:99], v[208:211], v[152:155], v[96:99]
	v_mfma_f32_16x16x32_bf16 v[88:91], v[200:203], v[176:179], v[88:91]
	v_mfma_f32_16x16x32_bf16 v[80:83], v[208:211], v[176:179], v[80:83]
	v_mfma_f32_16x16x32_bf16 v[72:75], v[200:203], v[192:195], v[72:75]
	v_mfma_f32_16x16x32_bf16 v[64:67], v[208:211], v[192:195], v[64:67]
	v_mfma_f32_16x16x32_bf16 v[120:123], v[204:207], v[148:151], v[120:123]
	v_mfma_f32_16x16x32_bf16 v[112:115], v[212:215], v[148:151], v[112:115]
	v_mfma_f32_16x16x32_bf16 v[104:107], v[204:207], v[172:175], v[104:107]
	v_mfma_f32_16x16x32_bf16 v[96:99], v[212:215], v[172:175], v[96:99]
	v_mfma_f32_16x16x32_bf16 v[88:91], v[204:207], v[188:191], v[88:91]
	v_mfma_f32_16x16x32_bf16 v[80:83], v[212:215], v[188:191], v[80:83]
	v_mfma_f32_16x16x32_bf16 v[72:75], v[204:207], v[196:199], v[72:75]
	v_mfma_f32_16x16x32_bf16 v[64:67], v[212:215], v[196:199], v[64:67]
	s_setprio 0
	s_barrier
	s_nop 1
	ds_read_b128 v[144:147], v186 offset:49152
	ds_read_b128 v[148:151], v186 offset:50176
	ds_read_b128 v[152:155], v186 offset:51200
	ds_read_b128 v[172:175], v186 offset:52224
	ds_read_b128 v[176:179], v186 offset:53248
	ds_read_b128 v[188:191], v186 offset:54272
	ds_read_b128 v[192:195], v186 offset:55296
	ds_read_b128 v[196:199], v186 offset:56320
	s_add_i32 s45, s77, s7
	s_mov_b32 m0, s45
	s_nop 0
	s_add_u32 s100, s42, s12
	s_addc_u32 s101, s43, s13
	global_load_lds_dwordx4 v158, s[100:101]
	s_add_i32 m0, s45, 0x2000
	s_nop 0
	s_add_u32 s100, s42, s12
	s_addc_u32 s101, s43, s13
	global_load_lds_dwordx4 v162, s[100:101]
	s_mov_b32 m0, s63
	v_lshl_add_u64 v[254:255], v[220:221], 0, s[12:13]
	global_load_lds_dwordx4 v[254:255], off
	v_lshl_add_u64 v[180:181], v[222:223], 0, s[12:13]
	s_mov_b32 m0, s68
	s_nop 0
	global_load_lds_dwordx4 v[180:181], off
	s_add_u32 s42, s42, 0x40080
	s_addc_u32 s43, s43, 0
	s_add_i32 s44, s44, s7
	s_mov_b32 m0, s44
	s_nop 0
	global_load_lds_dwordx4 v158, s[42:43]
	s_add_i32 m0, s44, 0x2000
	s_nop 0
	global_load_lds_dwordx4 v162, s[42:43]
	s_waitcnt vmcnt(6)
	s_waitcnt lgkmcnt(0)
	s_barrier
	s_setprio 1
	v_mfma_f32_16x16x32_bf16 v[60:63], v[128:131], v[144:147], v[60:63]
	v_mfma_f32_16x16x32_bf16 v[52:55], v[136:139], v[144:147], v[52:55]
	v_mfma_f32_16x16x32_bf16 v[44:47], v[128:131], v[152:155], v[44:47]
	v_mfma_f32_16x16x32_bf16 v[36:39], v[136:139], v[152:155], v[36:39]
	v_mfma_f32_16x16x32_bf16 v[28:31], v[128:131], v[176:179], v[28:31]
	v_mfma_f32_16x16x32_bf16 v[20:23], v[136:139], v[176:179], v[20:23]
	v_mfma_f32_16x16x32_bf16 v[12:15], v[128:131], v[192:195], v[12:15]
	v_mfma_f32_16x16x32_bf16 v[4:7], v[136:139], v[192:195], v[4:7]
	v_mfma_f32_16x16x32_bf16 v[60:63], v[132:135], v[148:151], v[60:63]
	v_mfma_f32_16x16x32_bf16 v[52:55], v[140:143], v[148:151], v[52:55]
	v_mfma_f32_16x16x32_bf16 v[44:47], v[132:135], v[172:175], v[44:47]
	v_mfma_f32_16x16x32_bf16 v[36:39], v[140:143], v[172:175], v[36:39]
	v_mfma_f32_16x16x32_bf16 v[28:31], v[132:135], v[188:191], v[28:31]
	v_mfma_f32_16x16x32_bf16 v[20:23], v[140:143], v[188:191], v[20:23]
	v_mfma_f32_16x16x32_bf16 v[12:15], v[132:135], v[196:199], v[12:15]
	v_mfma_f32_16x16x32_bf16 v[4:7], v[140:143], v[196:199], v[4:7]
	v_mfma_f32_16x16x32_bf16 v[56:59], v[200:203], v[144:147], v[56:59]
	v_mfma_f32_16x16x32_bf16 v[48:51], v[208:211], v[144:147], v[48:51]
	v_mfma_f32_16x16x32_bf16 v[40:43], v[200:203], v[152:155], v[40:43]
	v_mfma_f32_16x16x32_bf16 v[32:35], v[208:211], v[152:155], v[32:35]
	v_mfma_f32_16x16x32_bf16 v[24:27], v[200:203], v[176:179], v[24:27]
	v_mfma_f32_16x16x32_bf16 v[16:19], v[208:211], v[176:179], v[16:19]
	v_mfma_f32_16x16x32_bf16 v[8:11], v[200:203], v[192:195], v[8:11]
	v_mfma_f32_16x16x32_bf16 v[0:3], v[208:211], v[192:195], v[0:3]
	v_mfma_f32_16x16x32_bf16 v[56:59], v[204:207], v[148:151], v[56:59]
	v_mfma_f32_16x16x32_bf16 v[48:51], v[212:215], v[148:151], v[48:51]
	v_mfma_f32_16x16x32_bf16 v[40:43], v[204:207], v[172:175], v[40:43]
	v_mfma_f32_16x16x32_bf16 v[32:35], v[212:215], v[172:175], v[32:35]
	v_mfma_f32_16x16x32_bf16 v[24:27], v[204:207], v[188:191], v[24:27]
	v_mfma_f32_16x16x32_bf16 v[16:19], v[212:215], v[188:191], v[16:19]
	v_mfma_f32_16x16x32_bf16 v[8:11], v[204:207], v[196:199], v[8:11]
	v_mfma_f32_16x16x32_bf16 v[0:3], v[212:215], v[196:199], v[0:3]
	s_setprio 0
	s_add_i32 s76, s76, 2
	s_add_u32 s40, s40, 0x100
	s_addc_u32 s41, s41, 0
	s_add_u32 s74, s74, 0x100
	s_addc_u32 s75, s75, 0
	s_cmp_gt_u32 s76, 13
	s_barrier
; __device__ __forceinline__ float sigmoidf_(float x) { return __builtin_amdgcn_rcpf(1.0f + __expf(-x)); }
;     __device__ __forceinline__ void operator()(AccRef acc, const Unit& u, int wr, int wc, int fr, int fq) const {
;         const int row0 = u.pm * 256 + wr * 64 + fr, col0 = u.pn * 128 + wc * 32 + 8 * fq;
;         f32x4 bv[2], bg[2];
; #pragma unroll
;         for (int n = 0; n < 2; ++n) { bv[n] = *(const f32x4*)(bias + col0 + 4 * n); bg[n] = *(const f32x4*)(bias + D + col0 + 4 * n); }
; #pragma unroll
;         for (int ai = 0; ai < 2; ++ai) {
;             f32x4 xs[4][2];
; #pragma unroll
;             for (int m = 0; m < 4; ++m)
; #pragma unroll
;                 for (int n = 0; n < 2; ++n) xs[m][n] = *(const f32x4*)(x + (size_t)(row0 + ai * 128 + m * 16) * D + col0 + 4 * n);
; #pragma unroll
;             for (int m = 0; m < 4; ++m)
; #pragma unroll
;                 for (int n = 0; n < 2; ++n) { f32x4 xv = xs[m][n]; const f32x4 v = acc[ai][0][m][n] + bv[n], gt = acc[ai][1][m][n] + bg[n];
; #pragma unroll
;                     for (int j = 0; j < 4; ++j) xv[j] += v[j] * sigmoidf_(gt[j]);
;                     *(f32x4*)(x + (size_t)(row0 + ai * 128 + m * 16) * D + col0 + 4 * n) = xv; }
	s_cbranch_scc0 .LBB0_638
	v_lshl_or_b32 v128, s71, 7, v184
	v_ashrrev_i32_e32 v129, 31, v128
	v_lshlrev_b64 v[172:173], 2, v[128:129]
	v_lshl_add_u64 v[128:129], s[14:15], 0, v[172:173]
	global_load_dwordx4 v[140:143], v[128:129], off
	v_lshl_add_u64 v[130:131], s[10:11], 0, v[172:173]
	global_load_dwordx4 v[136:139], v[130:131], off
	global_load_dwordx4 v[132:135], v[128:129], off offset:16
	s_nop 0
	global_load_dwordx4 v[128:131], v[130:131], off offset:16
	v_lshl_add_u32 v144, s38, 8, v182
	v_ashrrev_i32_e32 v145, 31, v144
	v_lshlrev_b64 v[176:177], 12, v[144:145]
	v_lshl_add_u64 v[174:175], s[52:53], 0, v[172:173]
	v_lshl_add_u64 v[146:147], v[174:175], 0, v[176:177]
	global_load_dwordx4 v[188:191], v[146:147], off
	global_load_dwordx4 v[192:195], v[146:147], off offset:16
	v_or_b32_e32 v146, 16, v144
	v_or_b32_e32 v148, 32, v144
	v_or_b32_e32 v144, 48, v144
	v_ashrrev_i32_e32 v147, 31, v146
	v_ashrrev_i32_e32 v149, 31, v148
	v_ashrrev_i32_e32 v145, 31, v144
	v_lshlrev_b64 v[208:209], 12, v[146:147]
	v_lshlrev_b64 v[180:181], 12, v[148:149]
	v_lshlrev_b64 v[178:179], 12, v[144:145]
	v_lshl_add_u64 v[146:147], v[174:175], 0, v[208:209]
	v_lshl_add_u64 v[144:145], s[52:53], 0, v[176:177]
	global_load_dwordx4 v[196:199], v[146:147], off offset:16
	global_load_dwordx4 v[200:203], v[146:147], off
	v_lshl_add_u64 v[146:147], v[174:175], 0, v[180:181]
	v_lshl_add_u64 v[148:149], v[174:175], 0, v[178:179]
	v_lshl_add_u64 v[210:211], v[144:145], 0, v[172:173]
	global_load_dwordx4 v[152:155], v[146:147], off offset:16
	global_load_dwordx4 v[204:207], v[146:147], off
	s_nop 0
	global_load_dwordx4 v[144:147], v[148:149], off offset:16
	s_nop 0
	global_load_dwordx4 v[148:151], v[148:149], off
	s_and_b64 vcc, exec, s[8:9]
	s_mov_b32 s71, s28
	s_mov_b32 s38, s30
	s_mov_b64 s[42:43], s[36:37]
	s_mov_b64 s[40:41], s[34:35]
	s_waitcnt vmcnt(0)
	v_pk_add_f32 v[108:109], v[108:109], v[136:137]
	v_add_f32_e32 v212, v120, v140
	v_add_f32_e32 v213, v121, v141
	v_add_f32_e32 v214, v122, v142
	v_add_f32_e32 v215, v123, v143
	v_pk_add_f32 v[120:121], v[126:127], v[138:139]
	v_pk_add_f32 v[122:123], v[124:125], v[136:137]
	v_add_f32_e32 v112, v112, v132
	v_add_f32_e32 v113, v113, v133
	v_add_f32_e32 v104, v104, v140
	v_mul_f32_e32 v124, 0xbfb8aa3b, v212
	v_mul_f32_e32 v125, 0xbfb8aa3b, v213
	v_mul_f32_e32 v126, 0xbfb8aa3b, v214
	v_mul_f32_e32 v127, 0xbfb8aa3b, v215
	v_mul_f32_e32 v112, 0xbfb8aa3b, v112
	v_mul_f32_e32 v113, 0xbfb8aa3b, v113
	v_mul_f32_e32 v104, 0xbfb8aa3b, v104
	v_exp_f32_e32 v124, v124
	v_exp_f32_e32 v125, v125
	v_exp_f32_e32 v126, v126
	v_exp_f32_e32 v127, v127
	v_exp_f32_e32 v112, v112
	v_exp_f32_e32 v113, v113
	v_exp_f32_e32 v104, v104
	v_add_f32_e32 v114, v114, v134
	v_add_f32_e32 v115, v115, v135
	v_add_f32_e32 v105, v105, v141
	v_mul_f32_e32 v114, 0xbfb8aa3b, v114
	v_mul_f32_e32 v115, 0xbfb8aa3b, v115
	v_mul_f32_e32 v105, 0xbfb8aa3b, v105
	v_exp_f32_e32 v114, v114
	v_exp_f32_e32 v115, v115
	v_exp_f32_e32 v213, v105
	v_add_f32_e32 v105, 1.0, v124
	v_add_f32_e32 v124, 1.0, v125
	v_add_f32_e32 v125, 1.0, v126
	v_add_f32_e32 v126, 1.0, v127
	v_add_f32_e32 v127, 1.0, v112
	v_add_f32_e32 v212, 1.0, v113
	v_add_f32_e32 v214, 1.0, v104
	v_rcp_f32_e32 v104, v105
	v_rcp_f32_e32 v105, v124
	v_rcp_f32_e32 v112, v125
	v_rcp_f32_e32 v113, v126
	v_add_f32_e32 v114, 1.0, v114
	v_add_f32_e32 v115, 1.0, v115
	v_add_f32_e32 v106, v106, v142
	v_rcp_f32_e32 v124, v127
	v_rcp_f32_e32 v126, v114
	v_rcp_f32_e32 v127, v115
	v_pk_fma_f32 v[114:115], v[120:121], v[112:113], v[190:191]
	v_pk_fma_f32 v[112:113], v[122:123], v[104:105], v[188:189]
	v_add_f32_e32 v104, v107, v143
	v_add_f32_e32 v88, v88, v140
	v_add_f32_e32 v89, v89, v141
	v_add_f32_e32 v72, v72, v140
	v_add_f32_e32 v73, v73, v141
	v_mul_f32_e32 v106, 0xbfb8aa3b, v106
	v_mul_f32_e32 v104, 0xbfb8aa3b, v104
	v_add_f32_e32 v96, v96, v132
	v_add_f32_e32 v97, v97, v133
	v_add_f32_e32 v98, v98, v134
	v_add_f32_e32 v99, v99, v135
	v_mul_f32_e32 v88, 0xbfb8aa3b, v88
	v_mul_f32_e32 v89, 0xbfb8aa3b, v89
	v_add_f32_e32 v90, v90, v142
	v_add_f32_e32 v91, v91, v143
	v_add_f32_e32 v80, v80, v132
	v_add_f32_e32 v81, v81, v133
	v_add_f32_e32 v82, v82, v134
	v_add_f32_e32 v83, v83, v135
	v_mul_f32_e32 v72, 0xbfb8aa3b, v72
	v_mul_f32_e32 v73, 0xbfb8aa3b, v73
	v_add_f32_e32 v74, v74, v142
	v_add_f32_e32 v75, v75, v143
	v_add_f32_e32 v64, v64, v132
	v_add_f32_e32 v65, v65, v133
	v_add_f32_e32 v66, v66, v134
	v_add_f32_e32 v67, v67, v135
	v_exp_f32_e32 v106, v106
	v_exp_f32_e32 v105, v104
	v_mul_f32_e32 v96, 0xbfb8aa3b, v96
	v_mul_f32_e32 v97, 0xbfb8aa3b, v97
	v_mul_f32_e32 v98, 0xbfb8aa3b, v98
	v_mul_f32_e32 v99, 0xbfb8aa3b, v99
	v_exp_f32_e32 v88, v88
	v_exp_f32_e32 v89, v89
	v_mul_f32_e32 v90, 0xbfb8aa3b, v90
	v_mul_f32_e32 v91, 0xbfb8aa3b, v91
	v_mul_f32_e32 v80, 0xbfb8aa3b, v80
	v_mul_f32_e32 v81, 0xbfb8aa3b, v81
	v_mul_f32_e32 v82, 0xbfb8aa3b, v82
	v_mul_f32_e32 v83, 0xbfb8aa3b, v83
	v_exp_f32_e32 v72, v72
	v_exp_f32_e32 v73, v73
	v_mul_f32_e32 v74, 0xbfb8aa3b, v74
	v_mul_f32_e32 v75, 0xbfb8aa3b, v75
	v_mul_f32_e32 v64, 0xbfb8aa3b, v64
	v_mul_f32_e32 v65, 0xbfb8aa3b, v65
	v_mul_f32_e32 v66, 0xbfb8aa3b, v66
	v_mul_f32_e32 v67, 0xbfb8aa3b, v67
	v_exp_f32_e32 v96, v96
	v_exp_f32_e32 v97, v97
	v_exp_f32_e32 v98, v98
	v_exp_f32_e32 v99, v99
	v_exp_f32_e32 v90, v90
	v_exp_f32_e32 v91, v91
	v_exp_f32_e32 v80, v80
	v_exp_f32_e32 v81, v81
	v_exp_f32_e32 v82, v82
	v_exp_f32_e32 v83, v83
	v_exp_f32_e32 v74, v74
	v_exp_f32_e32 v75, v75
	v_exp_f32_e32 v64, v64
	v_exp_f32_e32 v65, v65
	v_exp_f32_e32 v66, v66
	v_exp_f32_e32 v67, v67
	v_add_f32_e32 v107, 1.0, v213
	v_add_f32_e32 v104, 1.0, v106
	v_add_f32_e32 v105, 1.0, v105
; __device__ __forceinline__ float sigmoidf_(float x) { return __builtin_amdgcn_rcpf(1.0f + __expf(-x)); }
;     __device__ __forceinline__ void operator()(AccRef acc, const Unit& u, int wr, int wc, int fr, int fq) const {
;     ...
;             for (int m = 0; m < 4; ++m)
; #pragma unroll
;                 for (int n = 0; n < 2; ++n) { f32x4 xv = xs[m][n]; const f32x4 v = acc[ai][0][m][n] + bv[n], gt = acc[ai][1][m][n] + bg[n];
; #pragma unroll
;                     for (int j = 0; j < 4; ++j) xv[j] += v[j] * sigmoidf_(gt[j]);
;                     *(f32x4*)(x + (size_t)(row0 + ai * 128 + m * 16) * D + col0 + 4 * n) = xv; }
	v_add_f32_e32 v88, 1.0, v88
	v_add_f32_e32 v89, 1.0, v89
	v_add_f32_e32 v72, 1.0, v72
	v_add_f32_e32 v73, 1.0, v73
	v_rcp_f32_e32 v125, v212
	v_rcp_f32_e32 v212, v214
	v_rcp_f32_e32 v104, v104
	v_rcp_f32_e32 v105, v105
	v_rcp_f32_e32 v213, v107
	v_add_f32_e32 v96, 1.0, v96
	v_add_f32_e32 v97, 1.0, v97
	v_add_f32_e32 v98, 1.0, v98
	v_add_f32_e32 v99, 1.0, v99
	v_rcp_f32_e32 v88, v88
	v_add_f32_e32 v90, 1.0, v90
	v_add_f32_e32 v91, 1.0, v91
	v_rcp_f32_e32 v89, v89
	v_add_f32_e32 v80, 1.0, v80
	v_add_f32_e32 v81, 1.0, v81
	v_add_f32_e32 v82, 1.0, v82
	v_add_f32_e32 v83, 1.0, v83
	v_rcp_f32_e32 v72, v72
	v_add_f32_e32 v74, 1.0, v74
	v_add_f32_e32 v75, 1.0, v75
	v_rcp_f32_e32 v73, v73
	v_add_f32_e32 v64, 1.0, v64
	v_add_f32_e32 v65, 1.0, v65
	v_add_f32_e32 v66, 1.0, v66
	v_add_f32_e32 v67, 1.0, v67
	v_rcp_f32_e32 v96, v96
	v_rcp_f32_e32 v97, v97
	v_rcp_f32_e32 v98, v98
	v_rcp_f32_e32 v99, v99
	v_rcp_f32_e32 v90, v90
	v_rcp_f32_e32 v91, v91
	v_rcp_f32_e32 v80, v80
	v_rcp_f32_e32 v81, v81
	v_rcp_f32_e32 v82, v82
	v_rcp_f32_e32 v83, v83
	v_rcp_f32_e32 v74, v74
	v_rcp_f32_e32 v75, v75
	v_rcp_f32_e32 v64, v64
	v_rcp_f32_e32 v66, v66
	v_rcp_f32_e32 v67, v67
	v_rcp_f32_e32 v65, v65
	v_pk_add_f32 v[106:107], v[110:111], v[138:139]
	v_pk_add_f32 v[92:93], v[92:93], v[136:137]
	v_pk_add_f32 v[76:77], v[76:77], v[136:137]
	v_pk_fma_f32 v[106:107], v[106:107], v[104:105], v[202:203]
	v_pk_fma_f32 v[104:105], v[108:109], v[212:213], v[200:201]
	v_lshl_add_u64 v[108:109], s[52:53], 0, v[208:209]
	v_pk_add_f32 v[102:103], v[102:103], v[130:131]
	v_pk_add_f32 v[100:101], v[100:101], v[128:129]
	v_pk_add_f32 v[94:95], v[94:95], v[138:139]
	v_pk_fma_f32 v[88:89], v[92:93], v[88:89], v[204:205]
	v_lshl_add_u64 v[92:93], s[52:53], 0, v[180:181]
	v_pk_add_f32 v[86:87], v[86:87], v[130:131]
	v_pk_add_f32 v[84:85], v[84:85], v[128:129]
	v_pk_add_f32 v[78:79], v[78:79], v[138:139]
	v_pk_fma_f32 v[72:73], v[76:77], v[72:73], v[148:149]
	v_lshl_add_u64 v[76:77], s[52:53], 0, v[178:179]
	v_pk_add_f32 v[70:71], v[70:71], v[130:131]
	v_pk_add_f32 v[68:69], v[68:69], v[128:129]
	v_pk_add_f32 v[118:119], v[118:119], v[130:131]
	v_pk_add_f32 v[116:117], v[116:117], v[128:129]
	v_lshl_add_u64 v[108:109], v[108:109], 0, v[172:173]
	v_pk_fma_f32 v[98:99], v[102:103], v[98:99], v[198:199]
	v_pk_fma_f32 v[96:97], v[100:101], v[96:97], v[196:197]
	v_pk_fma_f32 v[90:91], v[94:95], v[90:91], v[206:207]
	v_lshl_add_u64 v[92:93], v[92:93], 0, v[172:173]
	v_pk_fma_f32 v[82:83], v[86:87], v[82:83], v[154:155]
	v_pk_fma_f32 v[80:81], v[84:85], v[80:81], v[152:153]
	v_pk_fma_f32 v[74:75], v[78:79], v[74:75], v[150:151]
	v_lshl_add_u64 v[76:77], v[76:77], 0, v[172:173]
	v_pk_fma_f32 v[66:67], v[70:71], v[66:67], v[146:147]
	v_pk_fma_f32 v[64:65], v[68:69], v[64:65], v[144:145]
	v_pk_fma_f32 v[118:119], v[118:119], v[126:127], v[194:195]
	v_pk_fma_f32 v[116:117], v[116:117], v[124:125], v[192:193]
	global_store_dwordx4 v[210:211], v[112:115], off
	global_store_dwordx4 v[210:211], v[116:119], off offset:16
	global_store_dwordx4 v[108:109], v[104:107], off
	global_store_dwordx4 v[108:109], v[96:99], off offset:16
	global_store_dwordx4 v[92:93], v[88:91], off
	global_store_dwordx4 v[92:93], v[80:83], off offset:16
	global_store_dwordx4 v[76:77], v[72:75], off
	global_store_dwordx4 v[76:77], v[64:67], off offset:16
	v_lshl_add_u64 v[98:99], v[176:177], 0, s[18:19]
	v_lshl_add_u64 v[100:101], v[176:177], 0, s[22:23]
	v_lshl_add_u64 v[64:65], v[174:175], 0, v[98:99]
	global_load_dwordx4 v[78:81], v[64:65], off
	global_load_dwordx4 v[82:85], v[64:65], off offset:16
	v_lshl_add_u64 v[64:65], v[174:175], 0, v[100:101]
	v_lshl_add_u64 v[102:103], v[176:177], 0, s[24:25]
	v_lshl_add_u64 v[76:77], v[176:177], 0, s[26:27]
	global_load_dwordx4 v[86:89], v[64:65], off offset:16
	global_load_dwordx4 v[90:93], v[64:65], off
	v_lshl_add_u64 v[64:65], v[174:175], 0, v[102:103]
	v_lshl_add_u64 v[68:69], v[174:175], 0, v[76:77]
	global_load_dwordx4 v[72:75], v[64:65], off offset:16
	global_load_dwordx4 v[94:97], v[64:65], off
	s_nop 0
	global_load_dwordx4 v[64:67], v[68:69], off offset:16
	s_nop 0
	global_load_dwordx4 v[68:71], v[68:69], off
	v_add_f32_e32 v56, v56, v140
	v_add_f32_e32 v57, v57, v141
	v_add_f32_e32 v40, v40, v140
	v_add_f32_e32 v41, v41, v141
	v_add_f32_e32 v24, v24, v140
	v_add_f32_e32 v25, v25, v141
	v_add_f32_e32 v8, v8, v140
	v_add_f32_e32 v9, v9, v141
	v_mul_f32_e32 v56, 0xbfb8aa3b, v56
	v_mul_f32_e32 v57, 0xbfb8aa3b, v57
	v_add_f32_e32 v58, v58, v142
	v_add_f32_e32 v59, v59, v143
	v_add_f32_e32 v48, v48, v132
	v_add_f32_e32 v49, v49, v133
	v_add_f32_e32 v50, v50, v134
	v_add_f32_e32 v51, v51, v135
	v_mul_f32_e32 v40, 0xbfb8aa3b, v40
	v_mul_f32_e32 v41, 0xbfb8aa3b, v41
	v_add_f32_e32 v42, v42, v142
	v_add_f32_e32 v43, v43, v143
	v_add_f32_e32 v32, v32, v132
	v_add_f32_e32 v33, v33, v133
	v_add_f32_e32 v34, v34, v134
	v_add_f32_e32 v35, v35, v135
	v_mul_f32_e32 v24, 0xbfb8aa3b, v24
	v_mul_f32_e32 v25, 0xbfb8aa3b, v25
	v_add_f32_e32 v26, v26, v142
	v_add_f32_e32 v27, v27, v143
	v_add_f32_e32 v16, v16, v132
	v_add_f32_e32 v17, v17, v133
	v_add_f32_e32 v18, v18, v134
	v_add_f32_e32 v19, v19, v135
	v_mul_f32_e32 v8, 0xbfb8aa3b, v8
	v_mul_f32_e32 v9, 0xbfb8aa3b, v9
	v_add_f32_e32 v10, v10, v142
	v_add_f32_e32 v11, v11, v143
	v_add_f32_e32 v0, v0, v132
	v_add_f32_e32 v1, v1, v133
	v_add_f32_e32 v2, v2, v134
	v_add_f32_e32 v3, v3, v135
	v_exp_f32_e32 v56, v56
	v_exp_f32_e32 v57, v57
	v_mul_f32_e32 v58, 0xbfb8aa3b, v58
	v_mul_f32_e32 v59, 0xbfb8aa3b, v59
	v_mul_f32_e32 v48, 0xbfb8aa3b, v48
	v_mul_f32_e32 v49, 0xbfb8aa3b, v49
; __device__ __forceinline__ float sigmoidf_(float x) { return __builtin_amdgcn_rcpf(1.0f + __expf(-x)); }
;     __device__ __forceinline__ void operator()(AccRef acc, const Unit& u, int wr, int wc, int fr, int fq) const {
;     ...
;             for (int m = 0; m < 4; ++m)
; #pragma unroll
;                 for (int n = 0; n < 2; ++n) { f32x4 xv = xs[m][n]; const f32x4 v = acc[ai][0][m][n] + bv[n], gt = acc[ai][1][m][n] + bg[n];
; #pragma unroll
;                     for (int j = 0; j < 4; ++j) xv[j] += v[j] * sigmoidf_(gt[j]);
;                     *(f32x4*)(x + (size_t)(row0 + ai * 128 + m * 16) * D + col0 + 4 * n) = xv; }
;             asm volatile("" ::: "memory"); }
	v_mul_f32_e32 v50, 0xbfb8aa3b, v50
	v_mul_f32_e32 v51, 0xbfb8aa3b, v51
	v_exp_f32_e32 v40, v40
	v_exp_f32_e32 v41, v41
	v_mul_f32_e32 v42, 0xbfb8aa3b, v42
	v_mul_f32_e32 v43, 0xbfb8aa3b, v43
	v_mul_f32_e32 v32, 0xbfb8aa3b, v32
	v_mul_f32_e32 v33, 0xbfb8aa3b, v33
	v_mul_f32_e32 v34, 0xbfb8aa3b, v34
	v_mul_f32_e32 v35, 0xbfb8aa3b, v35
	v_exp_f32_e32 v24, v24
	v_exp_f32_e32 v25, v25
	v_mul_f32_e32 v26, 0xbfb8aa3b, v26
	v_mul_f32_e32 v27, 0xbfb8aa3b, v27
	v_mul_f32_e32 v16, 0xbfb8aa3b, v16
	v_mul_f32_e32 v17, 0xbfb8aa3b, v17
	v_mul_f32_e32 v18, 0xbfb8aa3b, v18
	v_mul_f32_e32 v19, 0xbfb8aa3b, v19
	v_exp_f32_e32 v8, v8
	v_exp_f32_e32 v9, v9
	v_mul_f32_e32 v10, 0xbfb8aa3b, v10
	v_mul_f32_e32 v11, 0xbfb8aa3b, v11
	v_mul_f32_e32 v0, 0xbfb8aa3b, v0
	v_mul_f32_e32 v1, 0xbfb8aa3b, v1
	v_mul_f32_e32 v2, 0xbfb8aa3b, v2
	v_mul_f32_e32 v3, 0xbfb8aa3b, v3
	v_exp_f32_e32 v58, v58
	v_exp_f32_e32 v59, v59
	v_exp_f32_e32 v48, v48
	v_exp_f32_e32 v49, v49
	v_exp_f32_e32 v50, v50
	v_exp_f32_e32 v51, v51
	v_exp_f32_e32 v42, v42
	v_exp_f32_e32 v43, v43
	v_exp_f32_e32 v32, v32
	v_exp_f32_e32 v33, v33
	v_exp_f32_e32 v34, v34
	v_exp_f32_e32 v35, v35
	v_exp_f32_e32 v26, v26
	v_exp_f32_e32 v27, v27
	v_exp_f32_e32 v16, v16
	v_exp_f32_e32 v17, v17
	v_exp_f32_e32 v18, v18
	v_exp_f32_e32 v19, v19
	v_exp_f32_e32 v10, v10
	v_exp_f32_e32 v11, v11
	v_exp_f32_e32 v0, v0
	v_exp_f32_e32 v1, v1
	v_exp_f32_e32 v2, v2
	v_exp_f32_e32 v3, v3
	v_add_f32_e32 v56, 1.0, v56
	v_add_f32_e32 v57, 1.0, v57
	v_add_f32_e32 v40, 1.0, v40
	v_add_f32_e32 v41, 1.0, v41
	v_add_f32_e32 v24, 1.0, v24
	v_add_f32_e32 v25, 1.0, v25
	v_add_f32_e32 v8, 1.0, v8
	v_add_f32_e32 v9, 1.0, v9
	v_rcp_f32_e32 v56, v56
	v_rcp_f32_e32 v57, v57
	v_add_f32_e32 v58, 1.0, v58
	v_add_f32_e32 v59, 1.0, v59
	v_add_f32_e32 v48, 1.0, v48
	v_add_f32_e32 v49, 1.0, v49
	v_add_f32_e32 v50, 1.0, v50
	v_add_f32_e32 v51, 1.0, v51
	v_rcp_f32_e32 v40, v40
	v_rcp_f32_e32 v41, v41
	v_add_f32_e32 v42, 1.0, v42
	v_add_f32_e32 v43, 1.0, v43
	v_add_f32_e32 v32, 1.0, v32
	v_add_f32_e32 v33, 1.0, v33
	v_add_f32_e32 v34, 1.0, v34
	v_add_f32_e32 v35, 1.0, v35
	v_rcp_f32_e32 v24, v24
	v_rcp_f32_e32 v25, v25
	v_add_f32_e32 v26, 1.0, v26
	v_add_f32_e32 v27, 1.0, v27
	v_add_f32_e32 v16, 1.0, v16
	v_add_f32_e32 v17, 1.0, v17
	v_add_f32_e32 v18, 1.0, v18
	v_add_f32_e32 v19, 1.0, v19
	v_rcp_f32_e32 v8, v8
	v_rcp_f32_e32 v9, v9
	v_add_f32_e32 v10, 1.0, v10
	v_add_f32_e32 v11, 1.0, v11
	v_add_f32_e32 v0, 1.0, v0
	v_add_f32_e32 v1, 1.0, v1
	v_add_f32_e32 v2, 1.0, v2
	v_add_f32_e32 v3, 1.0, v3
	v_rcp_f32_e32 v58, v58
	v_rcp_f32_e32 v59, v59
	v_rcp_f32_e32 v48, v48
	v_rcp_f32_e32 v49, v49
	v_rcp_f32_e32 v50, v50
	v_rcp_f32_e32 v51, v51
	v_rcp_f32_e32 v42, v42
	v_rcp_f32_e32 v43, v43
	v_rcp_f32_e32 v32, v32
	v_rcp_f32_e32 v33, v33
	v_rcp_f32_e32 v34, v34
	v_rcp_f32_e32 v35, v35
	v_rcp_f32_e32 v26, v26
	v_rcp_f32_e32 v27, v27
	v_rcp_f32_e32 v16, v16
	v_rcp_f32_e32 v17, v17
	v_rcp_f32_e32 v18, v18
	v_rcp_f32_e32 v19, v19
	v_rcp_f32_e32 v10, v10
	v_rcp_f32_e32 v11, v11
	v_rcp_f32_e32 v0, v0
	v_rcp_f32_e32 v1, v1
	v_rcp_f32_e32 v2, v2
	v_rcp_f32_e32 v3, v3
	v_pk_add_f32 v[60:61], v[60:61], v[136:137]
	v_pk_add_f32 v[44:45], v[44:45], v[136:137]
	v_pk_add_f32 v[28:29], v[28:29], v[136:137]
	v_pk_add_f32 v[12:13], v[12:13], v[136:137]
	v_pk_add_f32 v[62:63], v[62:63], v[138:139]
	s_waitcnt vmcnt(0)
	v_pk_fma_f32 v[56:57], v[60:61], v[56:57], v[78:79]
	v_lshl_add_u64 v[60:61], s[52:53], 0, v[98:99]
	v_pk_add_f32 v[54:55], v[54:55], v[130:131]
	v_pk_add_f32 v[52:53], v[52:53], v[128:129]
	v_pk_add_f32 v[46:47], v[46:47], v[138:139]
	v_pk_fma_f32 v[40:41], v[44:45], v[40:41], v[90:91]
	v_lshl_add_u64 v[44:45], s[52:53], 0, v[100:101]
	v_pk_add_f32 v[38:39], v[38:39], v[130:131]
	v_pk_add_f32 v[36:37], v[36:37], v[128:129]
	v_pk_add_f32 v[30:31], v[30:31], v[138:139]
	v_pk_fma_f32 v[24:25], v[28:29], v[24:25], v[94:95]
	v_lshl_add_u64 v[28:29], s[52:53], 0, v[102:103]
	v_pk_add_f32 v[22:23], v[22:23], v[130:131]
	v_pk_add_f32 v[20:21], v[20:21], v[128:129]
	v_pk_add_f32 v[14:15], v[14:15], v[138:139]
	v_pk_fma_f32 v[8:9], v[12:13], v[8:9], v[68:69]
	v_lshl_add_u64 v[12:13], s[52:53], 0, v[76:77]
	v_pk_add_f32 v[6:7], v[6:7], v[130:131]
	v_pk_add_f32 v[4:5], v[4:5], v[128:129]
	v_pk_fma_f32 v[58:59], v[62:63], v[58:59], v[80:81]
	v_lshl_add_u64 v[60:61], v[60:61], 0, v[172:173]
	v_pk_fma_f32 v[48:49], v[52:53], v[48:49], v[82:83]
	v_pk_fma_f32 v[50:51], v[54:55], v[50:51], v[84:85]
	v_pk_fma_f32 v[42:43], v[46:47], v[42:43], v[92:93]
	v_lshl_add_u64 v[44:45], v[44:45], 0, v[172:173]
	v_pk_fma_f32 v[32:33], v[36:37], v[32:33], v[86:87]
	v_pk_fma_f32 v[34:35], v[38:39], v[34:35], v[88:89]
	v_pk_fma_f32 v[26:27], v[30:31], v[26:27], v[96:97]
	v_lshl_add_u64 v[28:29], v[28:29], 0, v[172:173]
	v_pk_fma_f32 v[16:17], v[20:21], v[16:17], v[72:73]
	v_pk_fma_f32 v[18:19], v[22:23], v[18:19], v[74:75]
	v_pk_fma_f32 v[10:11], v[14:15], v[10:11], v[70:71]
	v_lshl_add_u64 v[12:13], v[12:13], 0, v[172:173]
	v_pk_fma_f32 v[0:1], v[4:5], v[0:1], v[64:65]
	v_pk_fma_f32 v[2:3], v[6:7], v[2:3], v[66:67]
	global_store_dwordx4 v[60:61], v[56:59], off
	global_store_dwordx4 v[60:61], v[48:51], off offset:16
	global_store_dwordx4 v[44:45], v[40:43], off
	global_store_dwordx4 v[44:45], v[32:35], off offset:16
	global_store_dwordx4 v[28:29], v[24:27], off
	global_store_dwordx4 v[28:29], v[16:19], off offset:16
	global_store_dwordx4 v[12:13], v[8:11], off
	global_store_dwordx4 v[12:13], v[0:3], off offset:16
	s_cbranch_vccz .LBB0_631
	s_waitcnt vmcnt(0)
	s_cmpk_gt_u32 s4, 0xff
	s_cbranch_scc1 .LBB0_642
	s_barrier

; #define PG8_STAGE(bufoff, gbase, voff) do { _Pragma("unroll") for (int _i = 0; _i < 2; ++_i) \
;         __builtin_amdgcn_global_load_lds((const unsigned*)((const char*)(gbase) + (voff)[_i]), (LAS unsigned*)(lds + (bufoff) + ldsw + _i * 8192), 16, 0, 0); } while (0)
; #define PG8_LDA(dst, b, h) do { _Pragma("unroll") for (int m = 0; m < 4; ++m) _Pragma("unroll") for (int k = 0; k < 2; ++k) dst[m][k] = *(const LAS bf16x8*)(lds + PG8_SA(b, h) + aoff + m * 2048 + k * 1024); } while (0)
; #define PG8_LDB(dst, b, h) do { _Pragma("unroll") for (int n = 0; n < 2; ++n) _Pragma("unroll") for (int k = 0; k < 2; ++k) dst[n][k] = *(const LAS bf16x8*)(lds + PG8_SB(b, h) + boff + n * 2048 + k * 1024); } while (0)
; #define PG8_WAIT_V(n) asm volatile("s_waitcnt vmcnt(" #n ")" ::: "memory")
; #define PG8_WAIT_L(n) asm volatile("s_waitcnt lgkmcnt(" #n ")" ::: "memory")
; #define PG8_BAR __builtin_amdgcn_s_barrier()
; #define PG8_SCHED __builtin_amdgcn_sched_barrier(0)
; template <class Epi>
; __device__ __forceinline__ void gemm_phase(LAS unsigned char* lds, const Gemm g, const StaticOrder& S, const Epi& E) {
;     ...
;         const bool has_next = S.next(ui + 1, nxt);
;         const char* nA = has_next ? (const char*)g.A + (size_t)nxt.pm * tstepA + (size_t)(nxt.pn >> g.a_shift) * g.a_step : cA; const char* nB = has_next ? (const char*)g.Bt + (size_t)nxt.pn * tstepB : cB;
;         for (int t = 0; t < nt; t += 2) {
;             const bool last = (t == nt - 2);
;             const char* a1 = cA + (size_t)(t + 1) * kstep;
;             const char* a2 = last ? nA : cA + (size_t)(t + 2) * kstep; const char* b2 = last ? nB : cB + (size_t)(t + 2) * kstep;
;             const char* a3 = a2 + kstep; const char* b3 = b2 + kstep;
;             PG8_LDB(B0, 0, 0); PG8_SCHED; PG8_LDA(At, 0, 0); PG8_STAGE(PG8_SA(1, 1), a1 + hstepA, voffA);
;             PG8_WAIT_L(8); PG8_BAR; PG8_WAIT_L(0); PG8_MMA(0, 0, At, B0); PG8_BAR; PG8_SCHED;
;             PG8_LDB(B1, 0, 1); PG8_STAGE(PG8_SB(0, 0), b2, voffB);
;             PG8_BAR; PG8_WAIT_L(0); PG8_MMA(0, 1, At, B1); PG8_BAR;
;             PG8_LDA(At, 0, 1); PG8_STAGE(PG8_SA(0, 0), a2, voffA);
;             PG8_BAR; PG8_WAIT_L(0); PG8_MMA(1, 0, At, B0); PG8_BAR; PG8_SCHED;
;             PG8_STAGE(PG8_SB(0, 1), b2 + hstepB, voffB);
;             PG8_WAIT_V(6); PG8_BAR; PG8_MMA(1, 1, At, B1); PG8_BAR;
.LBB0_757:
	s_ashr_i32 s35, s34, 31
	v_cmp_lt_i64_e32 vcc, s[36:37], v[228:229]
	s_lshl_b64 s[36:37], s[34:35], 19
	s_add_u32 s36, s66, s36
	s_addc_u32 s37, s67, s37
	s_and_b64 s[38:39], vcc, exec
	s_cselect_b32 s35, s37, s43
	s_cselect_b32 s77, s36, s42
	s_ashr_i32 s31, s30, 31
	s_lshl_b64 s[38:39], s[30:31], 19
	s_add_u32 s38, s5, s38
	s_addc_u32 s39, s6, s39
	s_and_b64 s[46:47], vcc, exec
	s_cselect_b32 s31, s39, s45
	s_cselect_b32 s78, s38, s44
	s_add_u32 s79, s44, 0x100
	s_addc_u32 s80, s45, 0
	s_mov_b32 s81, -2
	ds_read_b128 v[96:99], v243
	ds_read_b128 v[100:103], v243 offset:1024
	ds_read_b128 v[104:107], v243 offset:2048
	ds_read_b128 v[108:111], v243 offset:3072
	s_add_u32 s44, s42, 0x100
	s_addc_u32 s45, s43, 0
	s_cmp_eq_u32 s81, 12
	s_cselect_b32 s49, s35, s45
	s_cselect_b32 s48, s77, s44
	s_cselect_b32 s47, s31, s80
	s_cselect_b32 s46, s78, s79
	s_add_i32 m0, s9, 0xc000
	ds_read_b128 v[112:115], v244
	ds_read_b128 v[116:119], v244 offset:1024
	ds_read_b128 v[120:123], v244 offset:2048
	ds_read_b128 v[124:127], v244 offset:3072
	ds_read_b128 v[160:163], v244 offset:4096
	ds_read_b128 v[164:167], v244 offset:5120
	ds_read_b128 v[168:171], v244 offset:6144
	ds_read_b128 v[172:175], v244 offset:7168
	global_load_lds_dwordx4 v224, s[42:43]
	s_add_i32 m0, s9, 0xe000
	s_nop 0
	global_load_lds_dwordx4 v226, s[42:43]
	ds_read_b128 v[176:179], v245
	ds_read_b128 v[180:183], v245 offset:1024
	ds_read_b128 v[184:187], v245 offset:2048
	ds_read_b128 v[188:191], v245 offset:3072
	s_waitcnt lgkmcnt(0)
	s_barrier
	s_setprio 1
	v_mfma_f32_16x16x32_bf16 v[156:159], v[96:99], v[112:115], 0
	v_mfma_f32_16x16x32_bf16 v[60:63], v[104:107], v[112:115], 0
	v_mfma_f32_16x16x32_bf16 v[144:147], v[96:99], v[120:123], 0
	v_mfma_f32_16x16x32_bf16 v[48:51], v[104:107], v[120:123], 0
	v_mfma_f32_16x16x32_bf16 v[136:139], v[96:99], v[160:163], 0
	v_mfma_f32_16x16x32_bf16 v[40:43], v[104:107], v[160:163], 0
	v_mfma_f32_16x16x32_bf16 v[148:151], v[96:99], v[168:171], 0
	v_mfma_f32_16x16x32_bf16 v[52:55], v[104:107], v[168:171], 0
	v_mfma_f32_16x16x32_bf16 v[156:159], v[100:103], v[116:119], v[156:159]
	v_mfma_f32_16x16x32_bf16 v[60:63], v[108:111], v[116:119], v[60:63]
	v_mfma_f32_16x16x32_bf16 v[144:147], v[100:103], v[124:127], v[144:147]
	v_mfma_f32_16x16x32_bf16 v[48:51], v[108:111], v[124:127], v[48:51]
	v_mfma_f32_16x16x32_bf16 v[136:139], v[100:103], v[164:167], v[136:139]
	v_mfma_f32_16x16x32_bf16 v[40:43], v[108:111], v[164:167], v[40:43]
	v_mfma_f32_16x16x32_bf16 v[148:151], v[100:103], v[172:175], v[148:151]
	v_mfma_f32_16x16x32_bf16 v[52:55], v[108:111], v[172:175], v[52:55]
	v_mfma_f32_16x16x32_bf16 v[152:155], v[176:179], v[112:115], 0
	v_mfma_f32_16x16x32_bf16 v[56:59], v[184:187], v[112:115], 0
	v_mfma_f32_16x16x32_bf16 v[36:39], v[184:187], v[120:123], 0
	v_mfma_f32_16x16x32_bf16 v[32:35], v[184:187], v[160:163], 0
	v_mfma_f32_16x16x32_bf16 v[44:47], v[184:187], v[168:171], 0
	v_mfma_f32_16x16x32_bf16 v[152:155], v[180:183], v[116:119], v[152:155]
	v_mfma_f32_16x16x32_bf16 v[56:59], v[188:191], v[116:119], v[56:59]
	v_mfma_f32_16x16x32_bf16 v[112:115], v[176:179], v[120:123], 0
	v_mfma_f32_16x16x32_bf16 v[36:39], v[188:191], v[124:127], v[36:39]
	v_mfma_f32_16x16x32_bf16 v[116:119], v[176:179], v[160:163], 0
	v_mfma_f32_16x16x32_bf16 v[32:35], v[188:191], v[164:167], v[32:35]
	v_mfma_f32_16x16x32_bf16 v[120:123], v[176:179], v[168:171], 0
	v_mfma_f32_16x16x32_bf16 v[44:47], v[188:191], v[172:175], v[44:47]
	v_mfma_f32_16x16x32_bf16 v[112:115], v[180:183], v[124:127], v[112:115]
	v_mfma_f32_16x16x32_bf16 v[116:119], v[180:183], v[164:167], v[116:119]
	v_mfma_f32_16x16x32_bf16 v[120:123], v[180:183], v[172:175], v[120:123]
	s_setprio 0
	s_barrier
	s_nop 1
	ds_read_b128 v[124:127], v244 offset:16384
	ds_read_b128 v[128:131], v244 offset:17408
	ds_read_b128 v[132:135], v244 offset:18432
	ds_read_b128 v[140:143], v244 offset:19456
	ds_read_b128 v[160:163], v244 offset:20480
	ds_read_b128 v[164:167], v244 offset:21504
	ds_read_b128 v[168:171], v244 offset:22528
	ds_read_b128 v[172:175], v244 offset:23552
	s_add_i32 s42, s74, s7
	v_lshl_add_u64 v[196:197], s[46:47], 0, v[214:215]
	s_mov_b32 m0, s42
	s_nop 0
	global_load_lds_dwordx4 v214, s[46:47]
	v_lshl_add_u64 v[198:199], s[46:47], 0, v[210:211]
	s_add_i32 m0, s42, 0x2000
	s_nop 0
	global_load_lds_dwordx4 v210, s[46:47]
	s_mov_b32 m0, s9
	v_lshl_add_u64 v[200:201], s[48:49], 0, v[216:217]
	global_load_lds_dwordx4 v216, s[48:49]
	v_lshl_add_u64 v[202:203], s[48:49], 0, v[212:213]
	s_mov_b32 m0, s63
	s_nop 0
	global_load_lds_dwordx4 v212, s[48:49]
	s_add_u32 s42, s46, 0x40000
	s_addc_u32 s43, s47, 0
	s_add_i32 s82, s75, s7
	s_mov_b32 m0, s82
	s_nop 0
	global_load_lds_dwordx4 v214, s[42:43]
	s_add_i32 m0, s82, 0x2000
	s_nop 0
	global_load_lds_dwordx4 v210, s[42:43]
	s_waitcnt vmcnt(6)
	s_waitcnt lgkmcnt(0)
	s_barrier
; #define PG8_STAGE(bufoff, gbase, voff) do { _Pragma("unroll") for (int _i = 0; _i < 2; ++_i) \
;         __builtin_amdgcn_global_load_lds((const unsigned*)((const char*)(gbase) + (voff)[_i]), (LAS unsigned*)(lds + (bufoff) + ldsw + _i * 8192), 16, 0, 0); } while (0)
; #define PG8_LDA(dst, b, h) do { _Pragma("unroll") for (int m = 0; m < 4; ++m) _Pragma("unroll") for (int k = 0; k < 2; ++k) dst[m][k] = *(const LAS bf16x8*)(lds + PG8_SA(b, h) + aoff + m * 2048 + k * 1024); } while (0)
; #define PG8_LDB(dst, b, h) do { _Pragma("unroll") for (int n = 0; n < 2; ++n) _Pragma("unroll") for (int k = 0; k < 2; ++k) dst[n][k] = *(const LAS bf16x8*)(lds + PG8_SB(b, h) + boff + n * 2048 + k * 1024); } while (0)
; #define PG8_MMA(ai, bj, At, Bt) do { __builtin_amdgcn_s_setprio(1); _Pragma("unroll") for (int m = 0; m < 4; ++m) _Pragma("unroll") for (int n = 0; n < 2; ++n) _Pragma("unroll") for (int k = 0; k < 2; ++k) \
;         acc[ai][bj][m][n] = __builtin_amdgcn_mfma_f32_16x16x32_bf16(Bt[n][k], At[m][k], acc[ai][bj][m][n], 0, 0, 0); __builtin_amdgcn_s_setprio(0); } while (0)
; #define PG8_WAIT_V(n) asm volatile("s_waitcnt vmcnt(" #n ")" ::: "memory")
; #define PG8_WAIT_L(n) asm volatile("s_waitcnt lgkmcnt(" #n ")" ::: "memory")
; #define PG8_BAR __builtin_amdgcn_s_barrier()
; #define PG8_SCHED __builtin_amdgcn_sched_barrier(0)
; template <class Epi>
; __device__ __forceinline__ void gemm_phase(LAS unsigned char* lds, const Gemm g, const StaticOrder& S, const Epi& E) {
;     ...
;             PG8_BAR; PG8_WAIT_L(0); PG8_MMA(1, 0, At, B0); PG8_BAR; PG8_SCHED;
;             PG8_STAGE(PG8_SB(0, 1), b2 + hstepB, voffB);
;             PG8_WAIT_V(6); PG8_BAR; PG8_MMA(1, 1, At, B1); PG8_BAR;
;             PG8_LDB(B0, 1, 0); PG8_SCHED; PG8_LDA(At, 1, 0); PG8_STAGE(PG8_SA(0, 1), a2 + hstepA, voffA);
;             PG8_WAIT_L(8); PG8_BAR; PG8_WAIT_L(0); PG8_MMA(0, 0, At, B0); PG8_BAR; PG8_SCHED;
;             PG8_LDB(B1, 1, 1); PG8_STAGE(PG8_SB(1, 0), b3, voffB);
;             PG8_BAR; PG8_WAIT_L(0); PG8_MMA(0, 1, At, B1); PG8_BAR;
;             PG8_LDA(At, 1, 1); PG8_STAGE(PG8_SA(1, 0), a3, voffA);
	s_setprio 1
	v_mfma_f32_16x16x32_bf16 v[92:95], v[96:99], v[124:127], 0
	v_mfma_f32_16x16x32_bf16 v[28:31], v[104:107], v[124:127], 0
	v_mfma_f32_16x16x32_bf16 v[80:83], v[96:99], v[132:135], 0
	v_mfma_f32_16x16x32_bf16 v[16:19], v[104:107], v[132:135], 0
	v_mfma_f32_16x16x32_bf16 v[76:79], v[96:99], v[160:163], 0
	v_mfma_f32_16x16x32_bf16 v[12:15], v[104:107], v[160:163], 0
	v_mfma_f32_16x16x32_bf16 v[84:87], v[96:99], v[168:171], 0
	v_mfma_f32_16x16x32_bf16 v[20:23], v[104:107], v[168:171], 0
	v_mfma_f32_16x16x32_bf16 v[92:95], v[100:103], v[128:131], v[92:95]
	v_mfma_f32_16x16x32_bf16 v[28:31], v[108:111], v[128:131], v[28:31]
	v_mfma_f32_16x16x32_bf16 v[80:83], v[100:103], v[140:143], v[80:83]
	v_mfma_f32_16x16x32_bf16 v[16:19], v[108:111], v[140:143], v[16:19]
	v_mfma_f32_16x16x32_bf16 v[76:79], v[100:103], v[164:167], v[76:79]
	v_mfma_f32_16x16x32_bf16 v[12:15], v[108:111], v[164:167], v[12:15]
	v_mfma_f32_16x16x32_bf16 v[84:87], v[100:103], v[172:175], v[84:87]
	v_mfma_f32_16x16x32_bf16 v[20:23], v[108:111], v[172:175], v[20:23]
	v_mfma_f32_16x16x32_bf16 v[88:91], v[176:179], v[124:127], 0
	v_mfma_f32_16x16x32_bf16 v[24:27], v[184:187], v[124:127], 0
	v_mfma_f32_16x16x32_bf16 v[68:71], v[176:179], v[132:135], 0
	v_mfma_f32_16x16x32_bf16 v[4:7], v[184:187], v[132:135], 0
	v_mfma_f32_16x16x32_bf16 v[64:67], v[176:179], v[160:163], 0
	v_mfma_f32_16x16x32_bf16 v[0:3], v[184:187], v[160:163], 0
	v_mfma_f32_16x16x32_bf16 v[72:75], v[176:179], v[168:171], 0
	v_mfma_f32_16x16x32_bf16 v[8:11], v[184:187], v[168:171], 0
	v_mfma_f32_16x16x32_bf16 v[88:91], v[180:183], v[128:131], v[88:91]
	v_mfma_f32_16x16x32_bf16 v[24:27], v[188:191], v[128:131], v[24:27]
	v_mfma_f32_16x16x32_bf16 v[68:71], v[180:183], v[140:143], v[68:71]
	v_mfma_f32_16x16x32_bf16 v[4:7], v[188:191], v[140:143], v[4:7]
	v_mfma_f32_16x16x32_bf16 v[64:67], v[180:183], v[164:167], v[64:67]
	v_mfma_f32_16x16x32_bf16 v[0:3], v[188:191], v[164:167], v[0:3]
	v_mfma_f32_16x16x32_bf16 v[72:75], v[180:183], v[172:175], v[72:75]
	v_mfma_f32_16x16x32_bf16 v[8:11], v[188:191], v[172:175], v[8:11]
	s_setprio 0
	s_add_i32 s82, 0, 0x18000
	v_add_u32_e32 v108, s82, v235
	s_barrier
	ds_read_b128 v[96:99], v108
	ds_read_b128 v[100:103], v108 offset:1024
	ds_read_b128 v[104:107], v108 offset:2048
	ds_read_b128 v[108:111], v108 offset:3072
	s_add_u32 s42, s48, 0x40000
	s_addc_u32 s43, s49, 0
	s_mov_b32 m0, s68
	ds_read_b128 v[124:127], v244 offset:32768
	ds_read_b128 v[128:131], v244 offset:33792
	ds_read_b128 v[140:143], v244 offset:34816
	ds_read_b128 v[160:163], v244 offset:35840
	ds_read_b128 v[164:167], v244 offset:36864
	ds_read_b128 v[168:171], v244 offset:37888
	ds_read_b128 v[172:175], v244 offset:38912
	ds_read_b128 v[176:179], v244 offset:39936
	global_load_lds_dwordx4 v216, s[42:43]
	v_lshl_add_u64 v[132:133], s[42:43], 0, v[212:213]
	s_mov_b32 m0, s69
	s_nop 0
	global_load_lds_dwordx4 v212, s[42:43]
	s_add_i32 s48, 0, 0x1c000
	v_add_u32_e32 v132, s48, v235
	ds_read_b128 v[180:183], v132
	ds_read_b128 v[184:187], v132 offset:1024
	ds_read_b128 v[188:191], v132 offset:2048
	ds_read_b128 v[192:195], v132 offset:3072
	s_waitcnt lgkmcnt(0)
	s_barrier
	s_setprio 1
	v_mfma_f32_16x16x32_bf16 v[132:135], v[96:99], v[124:127], v[156:159]
	v_mfma_f32_16x16x32_bf16 v[156:159], v[100:103], v[128:131], v[132:135]
	v_mfma_f32_16x16x32_bf16 v[132:135], v[96:99], v[140:143], v[144:147]
	v_mfma_f32_16x16x32_bf16 v[144:147], v[100:103], v[160:163], v[132:135]
	v_mfma_f32_16x16x32_bf16 v[132:135], v[96:99], v[164:167], v[136:139]
	v_mfma_f32_16x16x32_bf16 v[60:63], v[104:107], v[124:127], v[60:63]
	v_mfma_f32_16x16x32_bf16 v[48:51], v[104:107], v[140:143], v[48:51]
	v_mfma_f32_16x16x32_bf16 v[136:139], v[100:103], v[168:171], v[132:135]
	v_mfma_f32_16x16x32_bf16 v[40:43], v[104:107], v[164:167], v[40:43]
	v_mfma_f32_16x16x32_bf16 v[132:135], v[96:99], v[172:175], v[148:151]
	v_mfma_f32_16x16x32_bf16 v[52:55], v[104:107], v[172:175], v[52:55]
	v_mfma_f32_16x16x32_bf16 v[60:63], v[108:111], v[128:131], v[60:63]
	v_mfma_f32_16x16x32_bf16 v[48:51], v[108:111], v[160:163], v[48:51]
	v_mfma_f32_16x16x32_bf16 v[40:43], v[108:111], v[168:171], v[40:43]
	v_mfma_f32_16x16x32_bf16 v[148:151], v[100:103], v[176:179], v[132:135]
	v_mfma_f32_16x16x32_bf16 v[52:55], v[108:111], v[176:179], v[52:55]
	v_mfma_f32_16x16x32_bf16 v[132:135], v[180:183], v[124:127], v[152:155]
	v_mfma_f32_16x16x32_bf16 v[112:115], v[180:183], v[140:143], v[112:115]
	v_mfma_f32_16x16x32_bf16 v[152:155], v[184:187], v[128:131], v[132:135]
	v_mfma_f32_16x16x32_bf16 v[56:59], v[188:191], v[124:127], v[56:59]
	v_mfma_f32_16x16x32_bf16 v[132:135], v[184:187], v[160:163], v[112:115]
	v_mfma_f32_16x16x32_bf16 v[112:115], v[180:183], v[164:167], v[116:119]
	v_mfma_f32_16x16x32_bf16 v[56:59], v[192:195], v[128:131], v[56:59]
	v_mfma_f32_16x16x32_bf16 v[36:39], v[188:191], v[140:143], v[36:39]
	v_mfma_f32_16x16x32_bf16 v[128:131], v[184:187], v[168:171], v[112:115]
	v_mfma_f32_16x16x32_bf16 v[32:35], v[188:191], v[164:167], v[32:35]
	v_mfma_f32_16x16x32_bf16 v[112:115], v[180:183], v[172:175], v[120:123]
	v_mfma_f32_16x16x32_bf16 v[44:47], v[188:191], v[172:175], v[44:47]
	v_mfma_f32_16x16x32_bf16 v[36:39], v[192:195], v[160:163], v[36:39]
	v_mfma_f32_16x16x32_bf16 v[32:35], v[192:195], v[168:171], v[32:35]
	v_mfma_f32_16x16x32_bf16 v[140:143], v[184:187], v[176:179], v[112:115]
	v_mfma_f32_16x16x32_bf16 v[44:47], v[192:195], v[176:179], v[44:47]
	s_setprio 0
	s_barrier
; #define PG8_STAGE(bufoff, gbase, voff) do { _Pragma("unroll") for (int _i = 0; _i < 2; ++_i) \
;         __builtin_amdgcn_global_load_lds((const unsigned*)((const char*)(gbase) + (voff)[_i]), (LAS unsigned*)(lds + (bufoff) + ldsw + _i * 8192), 16, 0, 0); } while (0)
; #define PG8_LDA(dst, b, h) do { _Pragma("unroll") for (int m = 0; m < 4; ++m) _Pragma("unroll") for (int k = 0; k < 2; ++k) dst[m][k] = *(const LAS bf16x8*)(lds + PG8_SA(b, h) + aoff + m * 2048 + k * 1024); } while (0)
; #define PG8_LDB(dst, b, h) do { _Pragma("unroll") for (int n = 0; n < 2; ++n) _Pragma("unroll") for (int k = 0; k < 2; ++k) dst[n][k] = *(const LAS bf16x8*)(lds + PG8_SB(b, h) + boff + n * 2048 + k * 1024); } while (0)
; #define PG8_MMA(ai, bj, At, Bt) do { __builtin_amdgcn_s_setprio(1); _Pragma("unroll") for (int m = 0; m < 4; ++m) _Pragma("unroll") for (int n = 0; n < 2; ++n) _Pragma("unroll") for (int k = 0; k < 2; ++k) \
;         acc[ai][bj][m][n] = __builtin_amdgcn_mfma_f32_16x16x32_bf16(Bt[n][k], At[m][k], acc[ai][bj][m][n], 0, 0, 0); __builtin_amdgcn_s_setprio(0); } while (0)
; #define PG8_WAIT_V(n) asm volatile("s_waitcnt vmcnt(" #n ")" ::: "memory")
; #define PG8_WAIT_L(n) asm volatile("s_waitcnt lgkmcnt(" #n ")" ::: "memory")
; #define PG8_BAR __builtin_amdgcn_s_barrier()
; #define PG8_SCHED __builtin_amdgcn_sched_barrier(0)
; template <class Epi>
; __device__ __forceinline__ void gemm_phase(LAS unsigned char* lds, const Gemm g, const StaticOrder& S, const Epi& E) {
;     ...
;             PG8_LDB(B0, 0, 0); PG8_SCHED; PG8_LDA(At, 0, 0); PG8_STAGE(PG8_SA(1, 1), a1 + hstepA, voffA);
;             PG8_WAIT_L(8); PG8_BAR; PG8_WAIT_L(0); PG8_MMA(0, 0, At, B0); PG8_BAR; PG8_SCHED;
;             PG8_LDB(B1, 0, 1); PG8_STAGE(PG8_SB(0, 0), b2, voffB);
;             PG8_BAR; PG8_WAIT_L(0); PG8_MMA(0, 1, At, B1); PG8_BAR;
;             PG8_LDA(At, 0, 1); PG8_STAGE(PG8_SA(0, 0), a2, voffA);
;     ...
;             PG8_LDA(At, 1, 1); PG8_STAGE(PG8_SA(1, 0), a3, voffA);
;             PG8_BAR; PG8_WAIT_L(0); PG8_MMA(1, 0, At, B0); PG8_BAR; PG8_SCHED;
;             PG8_STAGE(PG8_SB(1, 1), b3 + hstepB, voffB);
;             PG8_WAIT_V(6); PG8_BAR; PG8_MMA(1, 1, At, B1); PG8_BAR;
	s_nop 1
	ds_read_b128 v[112:115], v244 offset:49152
	ds_read_b128 v[116:119], v244 offset:50176
	ds_read_b128 v[120:123], v244 offset:51200
	ds_read_b128 v[124:127], v244 offset:52224
	ds_read_b128 v[160:163], v244 offset:53248
	ds_read_b128 v[164:167], v244 offset:54272
	ds_read_b128 v[168:171], v244 offset:55296
	ds_read_b128 v[172:175], v244 offset:56320
	s_add_i32 s42, s82, s7
	s_mov_b32 m0, s42
	s_nop 0
	s_add_u32 s100, s46, s20
	s_addc_u32 s101, s47, s21
	global_load_lds_dwordx4 v214, s[100:101]
	s_add_i32 m0, s42, 0x2000
	s_nop 0
	s_add_u32 s100, s46, s20
	s_addc_u32 s101, s47, s21
	global_load_lds_dwordx4 v210, s[100:101]
	s_mov_b32 m0, s72
	v_lshl_add_u64 v[254:255], v[200:201], 0, s[20:21]
	global_load_lds_dwordx4 v[254:255], off
	v_lshl_add_u64 v[254:255], v[202:203], 0, s[20:21]
	s_mov_b32 m0, s73
	s_nop 0
	global_load_lds_dwordx4 v[254:255], off
	s_add_u32 s42, s46, 0x40080
	s_addc_u32 s43, s47, 0
	s_add_i32 s46, s48, s7
	s_mov_b32 m0, s46
	s_nop 0
	global_load_lds_dwordx4 v214, s[42:43]
	s_add_i32 m0, s46, 0x2000
	s_nop 0
	global_load_lds_dwordx4 v210, s[42:43]
	s_waitcnt vmcnt(6)
	s_waitcnt lgkmcnt(0)
	s_barrier
	s_setprio 1
	v_mfma_f32_16x16x32_bf16 v[92:95], v[96:99], v[112:115], v[92:95]
	v_mfma_f32_16x16x32_bf16 v[28:31], v[104:107], v[112:115], v[28:31]
	v_mfma_f32_16x16x32_bf16 v[80:83], v[96:99], v[120:123], v[80:83]
	v_mfma_f32_16x16x32_bf16 v[16:19], v[104:107], v[120:123], v[16:19]
	v_mfma_f32_16x16x32_bf16 v[76:79], v[96:99], v[160:163], v[76:79]
	v_mfma_f32_16x16x32_bf16 v[12:15], v[104:107], v[160:163], v[12:15]
	v_mfma_f32_16x16x32_bf16 v[84:87], v[96:99], v[168:171], v[84:87]
	v_mfma_f32_16x16x32_bf16 v[20:23], v[104:107], v[168:171], v[20:23]
	v_mfma_f32_16x16x32_bf16 v[92:95], v[100:103], v[116:119], v[92:95]
	v_mfma_f32_16x16x32_bf16 v[28:31], v[108:111], v[116:119], v[28:31]
	v_mfma_f32_16x16x32_bf16 v[80:83], v[100:103], v[124:127], v[80:83]
	v_mfma_f32_16x16x32_bf16 v[16:19], v[108:111], v[124:127], v[16:19]
	v_mfma_f32_16x16x32_bf16 v[76:79], v[100:103], v[164:167], v[76:79]
	v_mfma_f32_16x16x32_bf16 v[12:15], v[108:111], v[164:167], v[12:15]
	v_mfma_f32_16x16x32_bf16 v[84:87], v[100:103], v[172:175], v[84:87]
	v_mfma_f32_16x16x32_bf16 v[20:23], v[108:111], v[172:175], v[20:23]
	v_mfma_f32_16x16x32_bf16 v[88:91], v[180:183], v[112:115], v[88:91]
	v_mfma_f32_16x16x32_bf16 v[24:27], v[188:191], v[112:115], v[24:27]
	v_mfma_f32_16x16x32_bf16 v[68:71], v[180:183], v[120:123], v[68:71]
	v_mfma_f32_16x16x32_bf16 v[4:7], v[188:191], v[120:123], v[4:7]
	v_mfma_f32_16x16x32_bf16 v[64:67], v[180:183], v[160:163], v[64:67]
	v_mfma_f32_16x16x32_bf16 v[0:3], v[188:191], v[160:163], v[0:3]
	v_mfma_f32_16x16x32_bf16 v[72:75], v[180:183], v[168:171], v[72:75]
	v_mfma_f32_16x16x32_bf16 v[8:11], v[188:191], v[168:171], v[8:11]
	v_mfma_f32_16x16x32_bf16 v[88:91], v[184:187], v[116:119], v[88:91]
	v_mfma_f32_16x16x32_bf16 v[24:27], v[192:195], v[116:119], v[24:27]
	v_mfma_f32_16x16x32_bf16 v[68:71], v[184:187], v[124:127], v[68:71]
	v_mfma_f32_16x16x32_bf16 v[4:7], v[192:195], v[124:127], v[4:7]
	v_mfma_f32_16x16x32_bf16 v[64:67], v[184:187], v[164:167], v[64:67]
	v_mfma_f32_16x16x32_bf16 v[0:3], v[192:195], v[164:167], v[0:3]
	v_mfma_f32_16x16x32_bf16 v[72:75], v[184:187], v[172:175], v[72:75]
	v_mfma_f32_16x16x32_bf16 v[8:11], v[192:195], v[172:175], v[8:11]
	s_setprio 0
	s_add_i32 s81, s81, 2
	s_add_u32 s79, s79, 0x100
	s_addc_u32 s80, s80, 0
	s_cmp_gt_u32 s81, 13
	s_mov_b64 s[42:43], s[44:45]
	s_barrier
.LBB0_758:
	ds_read_b128 v[96:99], v243
	ds_read_b128 v[100:103], v243 offset:1024
	ds_read_b128 v[104:107], v243 offset:2048
	ds_read_b128 v[108:111], v243 offset:3072
	s_add_u32 s44, s42, 0x100
	s_addc_u32 s45, s43, 0
	s_cmp_eq_u32 s81, 12
	s_cselect_b32 s49, s35, s45
	s_cselect_b32 s48, s77, s44
	s_cselect_b32 s47, s31, s80
	s_cselect_b32 s46, s78, s79
	s_add_i32 m0, s9, 0xc000
	ds_read_b128 v[112:115], v244
	ds_read_b128 v[116:119], v244 offset:1024
	ds_read_b128 v[120:123], v244 offset:2048
	ds_read_b128 v[124:127], v244 offset:3072
	ds_read_b128 v[160:163], v244 offset:4096
	ds_read_b128 v[164:167], v244 offset:5120
	ds_read_b128 v[168:171], v244 offset:6144
	ds_read_b128 v[172:175], v244 offset:7168
	global_load_lds_dwordx4 v224, s[42:43]
	s_add_i32 m0, s9, 0xe000
	s_nop 0
	global_load_lds_dwordx4 v226, s[42:43]
	ds_read_b128 v[176:179], v245
	ds_read_b128 v[180:183], v245 offset:1024
	ds_read_b128 v[184:187], v245 offset:2048
	ds_read_b128 v[188:191], v245 offset:3072
	s_waitcnt lgkmcnt(0)
	s_barrier
; #define PG8_STAGE(bufoff, gbase, voff) do { _Pragma("unroll") for (int _i = 0; _i < 2; ++_i) \
;         __builtin_amdgcn_global_load_lds((const unsigned*)((const char*)(gbase) + (voff)[_i]), (LAS unsigned*)(lds + (bufoff) + ldsw + _i * 8192), 16, 0, 0); } while (0)
; #define PG8_MMA(ai, bj, At, Bt) do { __builtin_amdgcn_s_setprio(1); _Pragma("unroll") for (int m = 0; m < 4; ++m) _Pragma("unroll") for (int n = 0; n < 2; ++n) _Pragma("unroll") for (int k = 0; k < 2; ++k) \
;         acc[ai][bj][m][n] = __builtin_amdgcn_mfma_f32_16x16x32_bf16(Bt[n][k], At[m][k], acc[ai][bj][m][n], 0, 0, 0); __builtin_amdgcn_s_setprio(0); } while (0)
; #define PG8_WAIT_V(n) asm volatile("s_waitcnt vmcnt(" #n ")" ::: "memory")
; #define PG8_WAIT_L(n) asm volatile("s_waitcnt lgkmcnt(" #n ")" ::: "memory")
; #define PG8_BAR __builtin_amdgcn_s_barrier()
; #define PG8_SCHED __builtin_amdgcn_sched_barrier(0)
; template <class Epi>
; __device__ __forceinline__ void gemm_phase(LAS unsigned char* lds, const Gemm g, const StaticOrder& S, const Epi& E) {
;     ...
;             PG8_BAR; PG8_WAIT_L(0); PG8_MMA(1, 0, At, B0); PG8_BAR; PG8_SCHED;
;             PG8_STAGE(PG8_SB(0, 1), b2 + hstepB, voffB);
;             PG8_WAIT_V(6); PG8_BAR; PG8_MMA(1, 1, At, B1); PG8_BAR;
	s_setprio 1
	v_mfma_f32_16x16x32_bf16 v[156:159], v[96:99], v[112:115], v[156:159]
	v_mfma_f32_16x16x32_bf16 v[60:63], v[104:107], v[112:115], v[60:63]
	v_mfma_f32_16x16x32_bf16 v[144:147], v[96:99], v[120:123], v[144:147]
	v_mfma_f32_16x16x32_bf16 v[48:51], v[104:107], v[120:123], v[48:51]
	v_mfma_f32_16x16x32_bf16 v[136:139], v[96:99], v[160:163], v[136:139]
	v_mfma_f32_16x16x32_bf16 v[40:43], v[104:107], v[160:163], v[40:43]
	v_mfma_f32_16x16x32_bf16 v[148:151], v[96:99], v[168:171], v[148:151]
	v_mfma_f32_16x16x32_bf16 v[52:55], v[104:107], v[168:171], v[52:55]
	v_mfma_f32_16x16x32_bf16 v[156:159], v[100:103], v[116:119], v[156:159]
	v_mfma_f32_16x16x32_bf16 v[60:63], v[108:111], v[116:119], v[60:63]
	v_mfma_f32_16x16x32_bf16 v[144:147], v[100:103], v[124:127], v[144:147]
	v_mfma_f32_16x16x32_bf16 v[48:51], v[108:111], v[124:127], v[48:51]
	v_mfma_f32_16x16x32_bf16 v[136:139], v[100:103], v[164:167], v[136:139]
	v_mfma_f32_16x16x32_bf16 v[40:43], v[108:111], v[164:167], v[40:43]
	v_mfma_f32_16x16x32_bf16 v[148:151], v[100:103], v[172:175], v[148:151]
	v_mfma_f32_16x16x32_bf16 v[52:55], v[108:111], v[172:175], v[52:55]
	v_mfma_f32_16x16x32_bf16 v[152:155], v[176:179], v[112:115], v[152:155]
	v_mfma_f32_16x16x32_bf16 v[56:59], v[184:187], v[112:115], v[56:59]
	v_mfma_f32_16x16x32_bf16 v[36:39], v[184:187], v[120:123], v[36:39]
	v_mfma_f32_16x16x32_bf16 v[32:35], v[184:187], v[160:163], v[32:35]
	v_mfma_f32_16x16x32_bf16 v[44:47], v[184:187], v[168:171], v[44:47]
	v_mfma_f32_16x16x32_bf16 v[152:155], v[180:183], v[116:119], v[152:155]
	v_mfma_f32_16x16x32_bf16 v[56:59], v[188:191], v[116:119], v[56:59]
	v_mfma_f32_16x16x32_bf16 v[112:115], v[176:179], v[120:123], v[132:135]
	v_mfma_f32_16x16x32_bf16 v[36:39], v[188:191], v[124:127], v[36:39]
	v_mfma_f32_16x16x32_bf16 v[116:119], v[176:179], v[160:163], v[128:131]
	v_mfma_f32_16x16x32_bf16 v[32:35], v[188:191], v[164:167], v[32:35]
	v_mfma_f32_16x16x32_bf16 v[120:123], v[176:179], v[168:171], v[140:143]
	v_mfma_f32_16x16x32_bf16 v[44:47], v[188:191], v[172:175], v[44:47]
	v_mfma_f32_16x16x32_bf16 v[112:115], v[180:183], v[124:127], v[112:115]
	v_mfma_f32_16x16x32_bf16 v[116:119], v[180:183], v[164:167], v[116:119]
	v_mfma_f32_16x16x32_bf16 v[120:123], v[180:183], v[172:175], v[120:123]
	s_setprio 0
	s_barrier
	s_nop 1
	ds_read_b128 v[124:127], v244 offset:16384
	ds_read_b128 v[128:131], v244 offset:17408
	ds_read_b128 v[132:135], v244 offset:18432
	ds_read_b128 v[140:143], v244 offset:19456
	ds_read_b128 v[160:163], v244 offset:20480
	ds_read_b128 v[164:167], v244 offset:21504
	ds_read_b128 v[168:171], v244 offset:22528
	ds_read_b128 v[172:175], v244 offset:23552
	s_add_i32 s42, s74, s7
	v_lshl_add_u64 v[196:197], s[46:47], 0, v[214:215]
	s_mov_b32 m0, s42
	s_nop 0
	global_load_lds_dwordx4 v214, s[46:47]
	v_lshl_add_u64 v[198:199], s[46:47], 0, v[210:211]
	s_add_i32 m0, s42, 0x2000
	s_nop 0
	global_load_lds_dwordx4 v210, s[46:47]
	s_mov_b32 m0, s9
	v_lshl_add_u64 v[200:201], s[48:49], 0, v[216:217]
	global_load_lds_dwordx4 v216, s[48:49]
	v_lshl_add_u64 v[202:203], s[48:49], 0, v[212:213]
	s_mov_b32 m0, s63
	s_nop 0
	global_load_lds_dwordx4 v212, s[48:49]
	s_add_u32 s42, s46, 0x40000
	s_addc_u32 s43, s47, 0
	s_add_i32 s82, s75, s7
	s_mov_b32 m0, s82
	s_nop 0
	global_load_lds_dwordx4 v214, s[42:43]
	s_add_i32 m0, s82, 0x2000
	s_nop 0
	global_load_lds_dwordx4 v210, s[42:43]
	s_waitcnt vmcnt(6)
	s_waitcnt lgkmcnt(0)
	s_barrier
	s_setprio 1
	v_mfma_f32_16x16x32_bf16 v[92:95], v[96:99], v[124:127], v[92:95]
	v_mfma_f32_16x16x32_bf16 v[28:31], v[104:107], v[124:127], v[28:31]
	v_mfma_f32_16x16x32_bf16 v[80:83], v[96:99], v[132:135], v[80:83]
	v_mfma_f32_16x16x32_bf16 v[16:19], v[104:107], v[132:135], v[16:19]
	v_mfma_f32_16x16x32_bf16 v[76:79], v[96:99], v[160:163], v[76:79]
	v_mfma_f32_16x16x32_bf16 v[12:15], v[104:107], v[160:163], v[12:15]
	v_mfma_f32_16x16x32_bf16 v[84:87], v[96:99], v[168:171], v[84:87]
	v_mfma_f32_16x16x32_bf16 v[20:23], v[104:107], v[168:171], v[20:23]
	v_mfma_f32_16x16x32_bf16 v[92:95], v[100:103], v[128:131], v[92:95]
	v_mfma_f32_16x16x32_bf16 v[28:31], v[108:111], v[128:131], v[28:31]
	v_mfma_f32_16x16x32_bf16 v[80:83], v[100:103], v[140:143], v[80:83]
	v_mfma_f32_16x16x32_bf16 v[16:19], v[108:111], v[140:143], v[16:19]
	v_mfma_f32_16x16x32_bf16 v[76:79], v[100:103], v[164:167], v[76:79]
	v_mfma_f32_16x16x32_bf16 v[12:15], v[108:111], v[164:167], v[12:15]
	v_mfma_f32_16x16x32_bf16 v[84:87], v[100:103], v[172:175], v[84:87]
	v_mfma_f32_16x16x32_bf16 v[20:23], v[108:111], v[172:175], v[20:23]
	v_mfma_f32_16x16x32_bf16 v[88:91], v[176:179], v[124:127], v[88:91]
	v_mfma_f32_16x16x32_bf16 v[24:27], v[184:187], v[124:127], v[24:27]
	v_mfma_f32_16x16x32_bf16 v[68:71], v[176:179], v[132:135], v[68:71]
	v_mfma_f32_16x16x32_bf16 v[4:7], v[184:187], v[132:135], v[4:7]
	v_mfma_f32_16x16x32_bf16 v[64:67], v[176:179], v[160:163], v[64:67]
	v_mfma_f32_16x16x32_bf16 v[0:3], v[184:187], v[160:163], v[0:3]
	v_mfma_f32_16x16x32_bf16 v[72:75], v[176:179], v[168:171], v[72:75]
	v_mfma_f32_16x16x32_bf16 v[8:11], v[184:187], v[168:171], v[8:11]
	v_mfma_f32_16x16x32_bf16 v[88:91], v[180:183], v[128:131], v[88:91]
	v_mfma_f32_16x16x32_bf16 v[24:27], v[188:191], v[128:131], v[24:27]
	v_mfma_f32_16x16x32_bf16 v[68:71], v[180:183], v[140:143], v[68:71]
	v_mfma_f32_16x16x32_bf16 v[4:7], v[188:191], v[140:143], v[4:7]
	v_mfma_f32_16x16x32_bf16 v[64:67], v[180:183], v[164:167], v[64:67]
	v_mfma_f32_16x16x32_bf16 v[0:3], v[188:191], v[164:167], v[0:3]
	v_mfma_f32_16x16x32_bf16 v[72:75], v[180:183], v[172:175], v[72:75]
	v_mfma_f32_16x16x32_bf16 v[8:11], v[188:191], v[172:175], v[8:11]
	s_setprio 0
	s_add_i32 s82, 0, 0x18000
	v_add_u32_e32 v108, s82, v235
	s_barrier
; #define PG8_STAGE(bufoff, gbase, voff) do { _Pragma("unroll") for (int _i = 0; _i < 2; ++_i) \
;         __builtin_amdgcn_global_load_lds((const unsigned*)((const char*)(gbase) + (voff)[_i]), (LAS unsigned*)(lds + (bufoff) + ldsw + _i * 8192), 16, 0, 0); } while (0)
; #define PG8_LDA(dst, b, h) do { _Pragma("unroll") for (int m = 0; m < 4; ++m) _Pragma("unroll") for (int k = 0; k < 2; ++k) dst[m][k] = *(const LAS bf16x8*)(lds + PG8_SA(b, h) + aoff + m * 2048 + k * 1024); } while (0)
; #define PG8_LDB(dst, b, h) do { _Pragma("unroll") for (int n = 0; n < 2; ++n) _Pragma("unroll") for (int k = 0; k < 2; ++k) dst[n][k] = *(const LAS bf16x8*)(lds + PG8_SB(b, h) + boff + n * 2048 + k * 1024); } while (0)
; #define PG8_MMA(ai, bj, At, Bt) do { __builtin_amdgcn_s_setprio(1); _Pragma("unroll") for (int m = 0; m < 4; ++m) _Pragma("unroll") for (int n = 0; n < 2; ++n) _Pragma("unroll") for (int k = 0; k < 2; ++k) \
;         acc[ai][bj][m][n] = __builtin_amdgcn_mfma_f32_16x16x32_bf16(Bt[n][k], At[m][k], acc[ai][bj][m][n], 0, 0, 0); __builtin_amdgcn_s_setprio(0); } while (0)
; #define PG8_WAIT_V(n) asm volatile("s_waitcnt vmcnt(" #n ")" ::: "memory")
; #define PG8_WAIT_L(n) asm volatile("s_waitcnt lgkmcnt(" #n ")" ::: "memory")
; #define PG8_BAR __builtin_amdgcn_s_barrier()
; #define PG8_SCHED __builtin_amdgcn_sched_barrier(0)
; template <class Epi>
; __device__ __forceinline__ void gemm_phase(LAS unsigned char* lds, const Gemm g, const StaticOrder& S, const Epi& E) {
;     ...
;             PG8_LDB(B0, 1, 0); PG8_SCHED; PG8_LDA(At, 1, 0); PG8_STAGE(PG8_SA(0, 1), a2 + hstepA, voffA);
;             PG8_WAIT_L(8); PG8_BAR; PG8_WAIT_L(0); PG8_MMA(0, 0, At, B0); PG8_BAR; PG8_SCHED;
;             PG8_LDB(B1, 1, 1); PG8_STAGE(PG8_SB(1, 0), b3, voffB);
;             PG8_BAR; PG8_WAIT_L(0); PG8_MMA(0, 1, At, B1); PG8_BAR;
;             PG8_LDA(At, 1, 1); PG8_STAGE(PG8_SA(1, 0), a3, voffA);
;             PG8_BAR; PG8_WAIT_L(0); PG8_MMA(1, 0, At, B0); PG8_BAR; PG8_SCHED;
;             PG8_STAGE(PG8_SB(1, 1), b3 + hstepB, voffB);
;             PG8_WAIT_V(6); PG8_BAR; PG8_MMA(1, 1, At, B1); PG8_BAR;
	ds_read_b128 v[96:99], v108
	ds_read_b128 v[100:103], v108 offset:1024
	ds_read_b128 v[104:107], v108 offset:2048
	ds_read_b128 v[108:111], v108 offset:3072
	s_add_u32 s42, s48, 0x40000
	s_addc_u32 s43, s49, 0
	s_mov_b32 m0, s68
	ds_read_b128 v[124:127], v244 offset:32768
	ds_read_b128 v[128:131], v244 offset:33792
	ds_read_b128 v[140:143], v244 offset:34816
	ds_read_b128 v[160:163], v244 offset:35840
	ds_read_b128 v[164:167], v244 offset:36864
	ds_read_b128 v[168:171], v244 offset:37888
	ds_read_b128 v[172:175], v244 offset:38912
	ds_read_b128 v[176:179], v244 offset:39936
	global_load_lds_dwordx4 v216, s[42:43]
	v_lshl_add_u64 v[132:133], s[42:43], 0, v[212:213]
	s_mov_b32 m0, s69
	s_nop 0
	global_load_lds_dwordx4 v212, s[42:43]
	s_add_i32 s48, 0, 0x1c000
	v_add_u32_e32 v132, s48, v235
	ds_read_b128 v[180:183], v132
	ds_read_b128 v[184:187], v132 offset:1024
	ds_read_b128 v[188:191], v132 offset:2048
	ds_read_b128 v[192:195], v132 offset:3072
	s_waitcnt lgkmcnt(0)
	s_barrier
	s_setprio 1
	v_mfma_f32_16x16x32_bf16 v[132:135], v[96:99], v[124:127], v[156:159]
	v_mfma_f32_16x16x32_bf16 v[156:159], v[100:103], v[128:131], v[132:135]
	v_mfma_f32_16x16x32_bf16 v[132:135], v[96:99], v[140:143], v[144:147]
	v_mfma_f32_16x16x32_bf16 v[144:147], v[100:103], v[160:163], v[132:135]
	v_mfma_f32_16x16x32_bf16 v[132:135], v[96:99], v[164:167], v[136:139]
	v_mfma_f32_16x16x32_bf16 v[60:63], v[104:107], v[124:127], v[60:63]
	v_mfma_f32_16x16x32_bf16 v[48:51], v[104:107], v[140:143], v[48:51]
	v_mfma_f32_16x16x32_bf16 v[136:139], v[100:103], v[168:171], v[132:135]
	v_mfma_f32_16x16x32_bf16 v[40:43], v[104:107], v[164:167], v[40:43]
	v_mfma_f32_16x16x32_bf16 v[132:135], v[96:99], v[172:175], v[148:151]
	v_mfma_f32_16x16x32_bf16 v[52:55], v[104:107], v[172:175], v[52:55]
	v_mfma_f32_16x16x32_bf16 v[60:63], v[108:111], v[128:131], v[60:63]
	v_mfma_f32_16x16x32_bf16 v[48:51], v[108:111], v[160:163], v[48:51]
	v_mfma_f32_16x16x32_bf16 v[40:43], v[108:111], v[168:171], v[40:43]
	v_mfma_f32_16x16x32_bf16 v[148:151], v[100:103], v[176:179], v[132:135]
	v_mfma_f32_16x16x32_bf16 v[52:55], v[108:111], v[176:179], v[52:55]
	v_mfma_f32_16x16x32_bf16 v[132:135], v[180:183], v[124:127], v[152:155]
	v_mfma_f32_16x16x32_bf16 v[112:115], v[180:183], v[140:143], v[112:115]
	v_mfma_f32_16x16x32_bf16 v[152:155], v[184:187], v[128:131], v[132:135]
	v_mfma_f32_16x16x32_bf16 v[56:59], v[188:191], v[124:127], v[56:59]
	v_mfma_f32_16x16x32_bf16 v[132:135], v[184:187], v[160:163], v[112:115]
	v_mfma_f32_16x16x32_bf16 v[112:115], v[180:183], v[164:167], v[116:119]
	v_mfma_f32_16x16x32_bf16 v[56:59], v[192:195], v[128:131], v[56:59]
	v_mfma_f32_16x16x32_bf16 v[36:39], v[188:191], v[140:143], v[36:39]
	v_mfma_f32_16x16x32_bf16 v[128:131], v[184:187], v[168:171], v[112:115]
	v_mfma_f32_16x16x32_bf16 v[32:35], v[188:191], v[164:167], v[32:35]
	v_mfma_f32_16x16x32_bf16 v[112:115], v[180:183], v[172:175], v[120:123]
	v_mfma_f32_16x16x32_bf16 v[44:47], v[188:191], v[172:175], v[44:47]
	v_mfma_f32_16x16x32_bf16 v[36:39], v[192:195], v[160:163], v[36:39]
	v_mfma_f32_16x16x32_bf16 v[32:35], v[192:195], v[168:171], v[32:35]
	v_mfma_f32_16x16x32_bf16 v[140:143], v[184:187], v[176:179], v[112:115]
	v_mfma_f32_16x16x32_bf16 v[44:47], v[192:195], v[176:179], v[44:47]
	s_setprio 0
	s_barrier
	s_nop 1
	ds_read_b128 v[112:115], v244 offset:49152
	ds_read_b128 v[116:119], v244 offset:50176
	ds_read_b128 v[120:123], v244 offset:51200
	ds_read_b128 v[124:127], v244 offset:52224
	ds_read_b128 v[160:163], v244 offset:53248
	ds_read_b128 v[164:167], v244 offset:54272
	ds_read_b128 v[168:171], v244 offset:55296
	ds_read_b128 v[172:175], v244 offset:56320
	s_add_i32 s42, s82, s7
	s_mov_b32 m0, s42
	s_nop 0
	s_add_u32 s100, s46, s20
	s_addc_u32 s101, s47, s21
	global_load_lds_dwordx4 v214, s[100:101]
	s_add_i32 m0, s42, 0x2000
	s_nop 0
	s_add_u32 s100, s46, s20
	s_addc_u32 s101, s47, s21
	global_load_lds_dwordx4 v210, s[100:101]
	s_mov_b32 m0, s72
	v_lshl_add_u64 v[254:255], v[200:201], 0, s[20:21]
	global_load_lds_dwordx4 v[254:255], off
	v_lshl_add_u64 v[254:255], v[202:203], 0, s[20:21]
	s_mov_b32 m0, s73
	s_nop 0
	global_load_lds_dwordx4 v[254:255], off
	s_add_u32 s42, s46, 0x40080
	s_addc_u32 s43, s47, 0
	s_add_i32 s46, s48, s7
	s_mov_b32 m0, s46
	s_nop 0
	global_load_lds_dwordx4 v214, s[42:43]
	s_add_i32 m0, s46, 0x2000
	s_nop 0
	global_load_lds_dwordx4 v210, s[42:43]
	s_waitcnt vmcnt(6)
	s_waitcnt lgkmcnt(0)
	s_barrier
; #define LAS __attribute__((address_space(3)))
; #define PG8_STAGE(bufoff, gbase, voff) do { _Pragma("unroll") for (int _i = 0; _i < 2; ++_i) \
;         __builtin_amdgcn_global_load_lds((const unsigned*)((const char*)(gbase) + (voff)[_i]), (LAS unsigned*)(lds + (bufoff) + ldsw + _i * 8192), 16, 0, 0); } while (0)
; #define PG8_MMA(ai, bj, At, Bt) do { __builtin_amdgcn_s_setprio(1); _Pragma("unroll") for (int m = 0; m < 4; ++m) _Pragma("unroll") for (int n = 0; n < 2; ++n) _Pragma("unroll") for (int k = 0; k < 2; ++k) \
;         acc[ai][bj][m][n] = __builtin_amdgcn_mfma_f32_16x16x32_bf16(Bt[n][k], At[m][k], acc[ai][bj][m][n], 0, 0, 0); __builtin_amdgcn_s_setprio(0); } while (0)
; #define PG8_WAIT_V(n) asm volatile("s_waitcnt vmcnt(" #n ")" ::: "memory")
; #define PG8_WAIT_L(n) asm volatile("s_waitcnt lgkmcnt(" #n ")" ::: "memory")
; #define PG8_BAR __builtin_amdgcn_s_barrier()
; #define PG8_SCHED __builtin_amdgcn_sched_barrier(0)
; template <class Epi>
; __device__ __forceinline__ void gemm_phase(LAS unsigned char* lds, const Gemm g, const StaticOrder& S, const Epi& E) {
;     ...
;             PG8_BAR; PG8_WAIT_L(0); PG8_MMA(1, 0, At, B0); PG8_BAR; PG8_SCHED;
;             PG8_STAGE(PG8_SB(1, 1), b3 + hstepB, voffB);
;             PG8_WAIT_V(6); PG8_BAR; PG8_MMA(1, 1, At, B1); PG8_BAR;
;     __device__ __forceinline__ void operator()(AccRef acc, const Unit& u, int wr, int wc, int fr, int fq) const {
;         const int clb = 32 * wc + 8 * fq;
;         f32x4 cwv[2][8];
;         { const float* cv = cw + 128 * u.pn + clb; const float* cg = cv + FH; const float* bp = cb + 128 * u.pn + clb;
;           cwv[0][0] = *(const f32x4*)(cv); cwv[0][1] = *(const f32x4*)(cv + F2); cwv[0][2] = *(const f32x4*)(cv + 2 * F2); cwv[0][3] = *(const f32x4*)(bp);
;           cwv[0][4] = *(const f32x4*)(cg); cwv[0][5] = *(const f32x4*)(cg + F2); cwv[0][6] = *(const f32x4*)(cg + 2 * F2); cwv[0][7] = *(const f32x4*)(bp + FH); }
;         if (fr == 15) {
; #pragma unroll
;             for (int ai = 0; ai < 2; ++ai)
; #pragma unroll
;                 for (int bj = 0; bj < 2; ++bj)
; #pragma unroll
;                     for (int n = 0; n < 2; ++n) { *(LAS f32x4*)(xch + ((ai * 2 + wr) * 2 + 0) * 256 + bj * 128 + clb + 4 * n) = acc[ai][bj][2][n]; *(LAS f32x4*)(xch + ((ai * 2 + wr) * 2 + 1) * 256 + bj * 128 + clb + 4 * n) = acc[ai][bj][3][n]; }
	s_setprio 1
	v_mfma_f32_16x16x32_bf16 v[92:95], v[96:99], v[112:115], v[92:95]
	v_mfma_f32_16x16x32_bf16 v[28:31], v[104:107], v[112:115], v[28:31]
	v_mfma_f32_16x16x32_bf16 v[80:83], v[96:99], v[120:123], v[80:83]
	v_mfma_f32_16x16x32_bf16 v[16:19], v[104:107], v[120:123], v[16:19]
	v_mfma_f32_16x16x32_bf16 v[76:79], v[96:99], v[160:163], v[76:79]
	v_mfma_f32_16x16x32_bf16 v[12:15], v[104:107], v[160:163], v[12:15]
	v_mfma_f32_16x16x32_bf16 v[84:87], v[96:99], v[168:171], v[84:87]
	v_mfma_f32_16x16x32_bf16 v[20:23], v[104:107], v[168:171], v[20:23]
	v_mfma_f32_16x16x32_bf16 v[92:95], v[100:103], v[116:119], v[92:95]
	v_mfma_f32_16x16x32_bf16 v[28:31], v[108:111], v[116:119], v[28:31]
	v_mfma_f32_16x16x32_bf16 v[80:83], v[100:103], v[124:127], v[80:83]
	v_mfma_f32_16x16x32_bf16 v[16:19], v[108:111], v[124:127], v[16:19]
	v_mfma_f32_16x16x32_bf16 v[76:79], v[100:103], v[164:167], v[76:79]
	v_mfma_f32_16x16x32_bf16 v[12:15], v[108:111], v[164:167], v[12:15]
	v_mfma_f32_16x16x32_bf16 v[84:87], v[100:103], v[172:175], v[84:87]
	v_mfma_f32_16x16x32_bf16 v[20:23], v[108:111], v[172:175], v[20:23]
	v_mfma_f32_16x16x32_bf16 v[88:91], v[180:183], v[112:115], v[88:91]
	v_mfma_f32_16x16x32_bf16 v[24:27], v[188:191], v[112:115], v[24:27]
	v_mfma_f32_16x16x32_bf16 v[68:71], v[180:183], v[120:123], v[68:71]
	v_mfma_f32_16x16x32_bf16 v[4:7], v[188:191], v[120:123], v[4:7]
	v_mfma_f32_16x16x32_bf16 v[64:67], v[180:183], v[160:163], v[64:67]
	v_mfma_f32_16x16x32_bf16 v[0:3], v[188:191], v[160:163], v[0:3]
	v_mfma_f32_16x16x32_bf16 v[72:75], v[180:183], v[168:171], v[72:75]
	v_mfma_f32_16x16x32_bf16 v[8:11], v[188:191], v[168:171], v[8:11]
	v_mfma_f32_16x16x32_bf16 v[88:91], v[184:187], v[116:119], v[88:91]
	v_mfma_f32_16x16x32_bf16 v[24:27], v[192:195], v[116:119], v[24:27]
	v_mfma_f32_16x16x32_bf16 v[68:71], v[184:187], v[124:127], v[68:71]
	v_mfma_f32_16x16x32_bf16 v[4:7], v[192:195], v[124:127], v[4:7]
	v_mfma_f32_16x16x32_bf16 v[64:67], v[184:187], v[164:167], v[64:67]
	v_mfma_f32_16x16x32_bf16 v[0:3], v[192:195], v[164:167], v[0:3]
	v_mfma_f32_16x16x32_bf16 v[72:75], v[184:187], v[172:175], v[72:75]
	v_mfma_f32_16x16x32_bf16 v[8:11], v[192:195], v[172:175], v[8:11]
	s_setprio 0
	s_add_i32 s81, s81, 2
	s_add_u32 s79, s79, 0x100
	s_addc_u32 s80, s80, 0
	s_cmp_gt_u32 s81, 13
	s_mov_b64 s[42:43], s[44:45]
	s_barrier
	s_cbranch_scc0 .LBB0_758
	s_lshl_b32 s42, s41, 7
	s_ashr_i32 s43, s42, 31
	s_lshl_b64 s[44:45], s[42:43], 2
	v_lshl_add_u64 v[96:97], v[220:221], 0, s[44:45]
	v_add_co_u32_e32 v100, vcc, 0x5000, v96
	v_lshl_add_u64 v[98:99], v[222:223], 0, s[44:45]
	s_nop 0
	v_addc_co_u32_e32 v101, vcc, 0, v97, vcc
	v_add_co_u32_e32 v102, vcc, 0xb000, v96
	global_load_dwordx4 v[160:163], v[96:97], off
	s_nop 0
	v_addc_co_u32_e32 v103, vcc, 0, v97, vcc
	global_load_dwordx4 v[164:167], v[100:101], off offset:2048
	global_load_dwordx4 v[168:171], v[102:103], off
	global_load_dwordx4 v[172:175], v[98:99], off
	v_add_co_u32_e32 v100, vcc, s70, v96
	s_nop 1
	v_addc_co_u32_e32 v101, vcc, 0, v97, vcc
	v_add_co_u32_e32 v102, vcc, 0x8000, v96
	s_nop 1
	v_addc_co_u32_e32 v103, vcc, 0, v97, vcc
	v_add_co_u32_e32 v96, vcc, 0xd000, v96
	global_load_dwordx4 v[176:179], v[100:101], off offset:3072
	global_load_dwordx4 v[180:183], v[102:103], off offset:1024
	v_addc_co_u32_e32 v97, vcc, 0, v97, vcc
	global_load_dwordx4 v[184:187], v[96:97], off offset:3072
	v_add_co_u32_e32 v96, vcc, 0x2000, v98
	s_nop 1
	v_addc_co_u32_e32 v97, vcc, 0, v99, vcc
	global_load_dwordx4 v[188:191], v[96:97], off offset:3072
	s_and_saveexec_b64 s[44:45], s[10:11]
	s_cbranch_execz .LBB0_761
	ds_write_b128 v237, v[136:139]
	ds_write_b128 v237, v[148:151] offset:1024
	ds_write_b128 v237, v[40:43] offset:16
	ds_write_b128 v237, v[52:55] offset:1040
	ds_write_b128 v237, v[128:131] offset:512
	ds_write_b128 v237, v[140:143] offset:1536
	ds_write_b128 v237, v[32:35] offset:528
	ds_write_b128 v237, v[44:47] offset:1552
	ds_write_b128 v237, v[76:79] offset:4096
	ds_write_b128 v237, v[84:87] offset:5120
	ds_write_b128 v237, v[12:15] offset:4112
	ds_write_b128 v237, v[20:23] offset:5136
	ds_write_b128 v237, v[64:67] offset:4608
	ds_write_b128 v237, v[72:75] offset:5632
	ds_write_b128 v237, v[0:3] offset:4624
	ds_write_b128 v237, v[8:11] offset:5648

; #define PG8_STAGE(bufoff, gbase, voff) do { _Pragma("unroll") for (int _i = 0; _i < 2; ++_i) \
;         __builtin_amdgcn_global_load_lds((const unsigned*)((const char*)(gbase) + (voff)[_i]), (LAS unsigned*)(lds + (bufoff) + ldsw + _i * 8192), 16, 0, 0); } while (0)
; #define PG8_LDA(dst, b, h) do { _Pragma("unroll") for (int m = 0; m < 4; ++m) _Pragma("unroll") for (int k = 0; k < 2; ++k) dst[m][k] = *(const LAS bf16x8*)(lds + PG8_SA(b, h) + aoff + m * 2048 + k * 1024); } while (0)
; #define PG8_LDB(dst, b, h) do { _Pragma("unroll") for (int n = 0; n < 2; ++n) _Pragma("unroll") for (int k = 0; k < 2; ++k) dst[n][k] = *(const LAS bf16x8*)(lds + PG8_SB(b, h) + boff + n * 2048 + k * 1024); } while (0)
; #define PG8_WAIT_V(n) asm volatile("s_waitcnt vmcnt(" #n ")" ::: "memory")
; #define PG8_WAIT_L(n) asm volatile("s_waitcnt lgkmcnt(" #n ")" ::: "memory")
; #define PG8_BAR __builtin_amdgcn_s_barrier()
; #define PG8_SCHED __builtin_amdgcn_sched_barrier(0)
; template <class Epi>
; __device__ __forceinline__ void gemm_phase(LAS unsigned char* lds, const Gemm g, const StaticOrder& S, const Epi& E) {
;     ...
;         const bool has_next = S.next(ui + 1, nxt);
;         const char* nA = has_next ? (const char*)g.A + (size_t)nxt.pm * tstepA + (size_t)(nxt.pn >> g.a_shift) * g.a_step : cA; const char* nB = has_next ? (const char*)g.Bt + (size_t)nxt.pn * tstepB : cB;
;         for (int t = 0; t < nt; t += 2) {
;             const bool last = (t == nt - 2);
;             const char* a1 = cA + (size_t)(t + 1) * kstep;
;             const char* a2 = last ? nA : cA + (size_t)(t + 2) * kstep; const char* b2 = last ? nB : cB + (size_t)(t + 2) * kstep;
;             const char* a3 = a2 + kstep; const char* b3 = b2 + kstep;
;             PG8_LDB(B0, 0, 0); PG8_SCHED; PG8_LDA(At, 0, 0); PG8_STAGE(PG8_SA(1, 1), a1 + hstepA, voffA);
;             PG8_WAIT_L(8); PG8_BAR; PG8_WAIT_L(0); PG8_MMA(0, 0, At, B0); PG8_BAR; PG8_SCHED;
;             PG8_LDB(B1, 0, 1); PG8_STAGE(PG8_SB(0, 0), b2, voffB);
;             PG8_BAR; PG8_WAIT_L(0); PG8_MMA(0, 1, At, B1); PG8_BAR;
;             PG8_LDA(At, 0, 1); PG8_STAGE(PG8_SA(0, 0), a2, voffA);
;             PG8_BAR; PG8_WAIT_L(0); PG8_MMA(1, 0, At, B0); PG8_BAR; PG8_SCHED;
;             PG8_STAGE(PG8_SB(0, 1), b2 + hstepB, voffB);
;             PG8_WAIT_V(6); PG8_BAR; PG8_MMA(1, 1, At, B1); PG8_BAR;
.LBB0_859:
	s_add_u32 s49, s30, 0x100
	s_addc_u32 s63, s31, 0
	s_mov_b32 s68, -2
	ds_read_b128 v[140:143], v149
	ds_read_b128 v[152:155], v149 offset:1024
	ds_read_b128 v[156:159], v149 offset:2048
	ds_read_b128 v[160:163], v149 offset:3072
	s_add_u32 s30, s28, 0x100
	s_addc_u32 s31, s29, 0
	s_cmp_eq_u32 s68, 40
	s_cselect_b32 s37, s13, s31
	s_cselect_b32 s36, s12, s30
	s_cselect_b32 s35, s15, s63
	s_cselect_b32 s34, s14, s49
	s_add_i32 m0, s8, 0xc000
	ds_read_b128 v[164:167], v150
	ds_read_b128 v[168:171], v150 offset:1024
	ds_read_b128 v[172:175], v150 offset:2048
	ds_read_b128 v[176:179], v150 offset:3072
	ds_read_b128 v[180:183], v150 offset:4096
	ds_read_b128 v[184:187], v150 offset:5120
	ds_read_b128 v[188:191], v150 offset:6144
	ds_read_b128 v[192:195], v150 offset:7168
	global_load_lds_dwordx4 v132, s[28:29]
	s_add_i32 m0, s8, 0xe000
	s_nop 0
	global_load_lds_dwordx4 v134, s[28:29]
	ds_read_b128 v[196:199], v151
	ds_read_b128 v[200:203], v151 offset:1024
	ds_read_b128 v[204:207], v151 offset:2048
	ds_read_b128 v[208:211], v151 offset:3072
	s_waitcnt lgkmcnt(0)
	s_barrier
	s_setprio 1
	v_mfma_f32_16x16x32_bf16 v[124:127], v[140:143], v[164:167], 0
	v_mfma_f32_16x16x32_bf16 v[120:123], v[156:159], v[164:167], 0
	v_mfma_f32_16x16x32_bf16 v[112:115], v[140:143], v[172:175], 0
	v_mfma_f32_16x16x32_bf16 v[104:107], v[156:159], v[172:175], 0
	v_mfma_f32_16x16x32_bf16 v[92:95], v[140:143], v[180:183], 0
	v_mfma_f32_16x16x32_bf16 v[88:91], v[156:159], v[180:183], 0
	v_mfma_f32_16x16x32_bf16 v[80:83], v[140:143], v[188:191], 0
	v_mfma_f32_16x16x32_bf16 v[72:75], v[156:159], v[188:191], 0
	v_mfma_f32_16x16x32_bf16 v[124:127], v[152:155], v[168:171], v[124:127]
	v_mfma_f32_16x16x32_bf16 v[120:123], v[160:163], v[168:171], v[120:123]
	v_mfma_f32_16x16x32_bf16 v[112:115], v[152:155], v[176:179], v[112:115]
	v_mfma_f32_16x16x32_bf16 v[104:107], v[160:163], v[176:179], v[104:107]
	v_mfma_f32_16x16x32_bf16 v[92:95], v[152:155], v[184:187], v[92:95]
	v_mfma_f32_16x16x32_bf16 v[88:91], v[160:163], v[184:187], v[88:91]
	v_mfma_f32_16x16x32_bf16 v[80:83], v[152:155], v[192:195], v[80:83]
	v_mfma_f32_16x16x32_bf16 v[72:75], v[160:163], v[192:195], v[72:75]
	v_mfma_f32_16x16x32_bf16 v[116:119], v[196:199], v[164:167], 0
	v_mfma_f32_16x16x32_bf16 v[108:111], v[204:207], v[164:167], 0
	v_mfma_f32_16x16x32_bf16 v[100:103], v[196:199], v[172:175], 0
	v_mfma_f32_16x16x32_bf16 v[96:99], v[204:207], v[172:175], 0
	v_mfma_f32_16x16x32_bf16 v[84:87], v[196:199], v[180:183], 0
	v_mfma_f32_16x16x32_bf16 v[76:79], v[204:207], v[180:183], 0
	v_mfma_f32_16x16x32_bf16 v[68:71], v[196:199], v[188:191], 0
	v_mfma_f32_16x16x32_bf16 v[64:67], v[204:207], v[188:191], 0
	v_mfma_f32_16x16x32_bf16 v[116:119], v[200:203], v[168:171], v[116:119]
	v_mfma_f32_16x16x32_bf16 v[108:111], v[208:211], v[168:171], v[108:111]
	v_mfma_f32_16x16x32_bf16 v[100:103], v[200:203], v[176:179], v[100:103]
	v_mfma_f32_16x16x32_bf16 v[96:99], v[208:211], v[176:179], v[96:99]
	v_mfma_f32_16x16x32_bf16 v[84:87], v[200:203], v[184:187], v[84:87]
	v_mfma_f32_16x16x32_bf16 v[76:79], v[208:211], v[184:187], v[76:79]
	v_mfma_f32_16x16x32_bf16 v[68:71], v[200:203], v[192:195], v[68:71]
	v_mfma_f32_16x16x32_bf16 v[64:67], v[208:211], v[192:195], v[64:67]
	s_setprio 0
	s_barrier
	s_nop 1
	ds_read_b128 v[164:167], v150 offset:16384
	ds_read_b128 v[168:171], v150 offset:17408
	ds_read_b128 v[172:175], v150 offset:18432
	ds_read_b128 v[176:179], v150 offset:19456
	ds_read_b128 v[180:183], v150 offset:20480
	ds_read_b128 v[184:187], v150 offset:21504
	ds_read_b128 v[188:191], v150 offset:22528
	ds_read_b128 v[192:195], v150 offset:23552
	s_add_i32 s28, s43, s7
	v_lshl_add_u64 v[144:145], s[34:35], 0, v[128:129]
	s_mov_b32 m0, s28
	s_nop 0
	global_load_lds_dwordx4 v128, s[34:35]
	v_lshl_add_u64 v[212:213], s[34:35], 0, v[130:131]
	s_add_i32 m0, s28, 0x2000
	s_nop 0
	global_load_lds_dwordx4 v130, s[34:35]
	s_mov_b32 m0, s8
	v_lshl_add_u64 v[214:215], s[36:37], 0, v[128:129]
	global_load_lds_dwordx4 v128, s[36:37]
	v_lshl_add_u64 v[216:217], s[36:37], 0, v[130:131]
	s_mov_b32 m0, s9
	s_nop 0
	global_load_lds_dwordx4 v130, s[36:37]
	s_add_u32 s28, s34, 0xb0000
	s_addc_u32 s29, s35, 0
	s_add_i32 s69, s44, s7
	s_mov_b32 m0, s69
	s_nop 0
	global_load_lds_dwordx4 v128, s[28:29]
	s_add_i32 m0, s69, 0x2000
	s_nop 0
	global_load_lds_dwordx4 v130, s[28:29]
	s_waitcnt vmcnt(6)
	s_waitcnt lgkmcnt(0)
	s_barrier
	s_setprio 1
	v_mfma_f32_16x16x32_bf16 v[60:63], v[140:143], v[164:167], 0
	v_mfma_f32_16x16x32_bf16 v[56:59], v[156:159], v[164:167], 0
	v_mfma_f32_16x16x32_bf16 v[48:51], v[140:143], v[172:175], 0
	v_mfma_f32_16x16x32_bf16 v[40:43], v[156:159], v[172:175], 0
	v_mfma_f32_16x16x32_bf16 v[28:31], v[140:143], v[180:183], 0
	v_mfma_f32_16x16x32_bf16 v[24:27], v[156:159], v[180:183], 0
	v_mfma_f32_16x16x32_bf16 v[16:19], v[140:143], v[188:191], 0
	v_mfma_f32_16x16x32_bf16 v[8:11], v[156:159], v[188:191], 0
	v_mfma_f32_16x16x32_bf16 v[60:63], v[152:155], v[168:171], v[60:63]
	v_mfma_f32_16x16x32_bf16 v[56:59], v[160:163], v[168:171], v[56:59]
	v_mfma_f32_16x16x32_bf16 v[48:51], v[152:155], v[176:179], v[48:51]
	v_mfma_f32_16x16x32_bf16 v[40:43], v[160:163], v[176:179], v[40:43]
	v_mfma_f32_16x16x32_bf16 v[28:31], v[152:155], v[184:187], v[28:31]
	v_mfma_f32_16x16x32_bf16 v[24:27], v[160:163], v[184:187], v[24:27]
	v_mfma_f32_16x16x32_bf16 v[16:19], v[152:155], v[192:195], v[16:19]
	v_mfma_f32_16x16x32_bf16 v[8:11], v[160:163], v[192:195], v[8:11]
	v_mfma_f32_16x16x32_bf16 v[52:55], v[196:199], v[164:167], 0
	v_mfma_f32_16x16x32_bf16 v[44:47], v[204:207], v[164:167], 0
	v_mfma_f32_16x16x32_bf16 v[36:39], v[196:199], v[172:175], 0
	v_mfma_f32_16x16x32_bf16 v[32:35], v[204:207], v[172:175], 0
	v_mfma_f32_16x16x32_bf16 v[20:23], v[196:199], v[180:183], 0
	v_mfma_f32_16x16x32_bf16 v[12:15], v[204:207], v[180:183], 0
	v_mfma_f32_16x16x32_bf16 v[4:7], v[196:199], v[188:191], 0
	v_mfma_f32_16x16x32_bf16 v[0:3], v[204:207], v[188:191], 0
	v_mfma_f32_16x16x32_bf16 v[52:55], v[200:203], v[168:171], v[52:55]
	v_mfma_f32_16x16x32_bf16 v[44:47], v[208:211], v[168:171], v[44:47]
	v_mfma_f32_16x16x32_bf16 v[36:39], v[200:203], v[176:179], v[36:39]
	v_mfma_f32_16x16x32_bf16 v[32:35], v[208:211], v[176:179], v[32:35]
	v_mfma_f32_16x16x32_bf16 v[20:23], v[200:203], v[184:187], v[20:23]
	v_mfma_f32_16x16x32_bf16 v[12:15], v[208:211], v[184:187], v[12:15]
	v_mfma_f32_16x16x32_bf16 v[4:7], v[200:203], v[192:195], v[4:7]
	v_mfma_f32_16x16x32_bf16 v[0:3], v[208:211], v[192:195], v[0:3]
	s_setprio 0
	s_add_i32 s69, 0, 0x18000
	v_add_u32_e32 v160, s69, v147
	s_barrier
; #define PG8_STAGE(bufoff, gbase, voff) do { _Pragma("unroll") for (int _i = 0; _i < 2; ++_i) \
;         __builtin_amdgcn_global_load_lds((const unsigned*)((const char*)(gbase) + (voff)[_i]), (LAS unsigned*)(lds + (bufoff) + ldsw + _i * 8192), 16, 0, 0); } while (0)
; #define PG8_LDA(dst, b, h) do { _Pragma("unroll") for (int m = 0; m < 4; ++m) _Pragma("unroll") for (int k = 0; k < 2; ++k) dst[m][k] = *(const LAS bf16x8*)(lds + PG8_SA(b, h) + aoff + m * 2048 + k * 1024); } while (0)
; #define PG8_LDB(dst, b, h) do { _Pragma("unroll") for (int n = 0; n < 2; ++n) _Pragma("unroll") for (int k = 0; k < 2; ++k) dst[n][k] = *(const LAS bf16x8*)(lds + PG8_SB(b, h) + boff + n * 2048 + k * 1024); } while (0)
; #define PG8_MMA(ai, bj, At, Bt) do { __builtin_amdgcn_s_setprio(1); _Pragma("unroll") for (int m = 0; m < 4; ++m) _Pragma("unroll") for (int n = 0; n < 2; ++n) _Pragma("unroll") for (int k = 0; k < 2; ++k) \
;         acc[ai][bj][m][n] = __builtin_amdgcn_mfma_f32_16x16x32_bf16(Bt[n][k], At[m][k], acc[ai][bj][m][n], 0, 0, 0); __builtin_amdgcn_s_setprio(0); } while (0)
; #define PG8_WAIT_V(n) asm volatile("s_waitcnt vmcnt(" #n ")" ::: "memory")
; #define PG8_WAIT_L(n) asm volatile("s_waitcnt lgkmcnt(" #n ")" ::: "memory")
; #define PG8_BAR __builtin_amdgcn_s_barrier()
; #define PG8_SCHED __builtin_amdgcn_sched_barrier(0)
; template <class Epi>
; __device__ __forceinline__ void gemm_phase(LAS unsigned char* lds, const Gemm g, const StaticOrder& S, const Epi& E) {
;     ...
;             PG8_LDB(B0, 1, 0); PG8_SCHED; PG8_LDA(At, 1, 0); PG8_STAGE(PG8_SA(0, 1), a2 + hstepA, voffA);
;             PG8_WAIT_L(8); PG8_BAR; PG8_WAIT_L(0); PG8_MMA(0, 0, At, B0); PG8_BAR; PG8_SCHED;
;             PG8_LDB(B1, 1, 1); PG8_STAGE(PG8_SB(1, 0), b3, voffB);
;             PG8_BAR; PG8_WAIT_L(0); PG8_MMA(0, 1, At, B1); PG8_BAR;
;             PG8_LDA(At, 1, 1); PG8_STAGE(PG8_SA(1, 0), a3, voffA);
;             PG8_BAR; PG8_WAIT_L(0); PG8_MMA(1, 0, At, B0); PG8_BAR; PG8_SCHED;
;             PG8_STAGE(PG8_SB(1, 1), b3 + hstepB, voffB);
;             PG8_WAIT_V(6); PG8_BAR; PG8_MMA(1, 1, At, B1); PG8_BAR;
	ds_read_b128 v[140:143], v160
	ds_read_b128 v[152:155], v160 offset:1024
	ds_read_b128 v[156:159], v160 offset:2048
	ds_read_b128 v[160:163], v160 offset:3072
	s_add_u32 s28, s36, 0xb0000
	s_addc_u32 s29, s37, 0
	s_mov_b32 m0, s38
	ds_read_b128 v[164:167], v150 offset:32768
	ds_read_b128 v[168:171], v150 offset:33792
	ds_read_b128 v[172:175], v150 offset:34816
	ds_read_b128 v[176:179], v150 offset:35840
	ds_read_b128 v[180:183], v150 offset:36864
	ds_read_b128 v[184:187], v150 offset:37888
	ds_read_b128 v[188:191], v150 offset:38912
	ds_read_b128 v[192:195], v150 offset:39936
	global_load_lds_dwordx4 v128, s[28:29]
	s_mov_b32 m0, s39
	s_nop 0
	global_load_lds_dwordx4 v130, s[28:29]
	s_add_i32 s36, 0, 0x1c000
	v_add_u32_e32 v208, s36, v147
	ds_read_b128 v[196:199], v208
	ds_read_b128 v[200:203], v208 offset:1024
	ds_read_b128 v[204:207], v208 offset:2048
	ds_read_b128 v[208:211], v208 offset:3072
	s_waitcnt lgkmcnt(0)
	s_barrier
	s_setprio 1
	v_mfma_f32_16x16x32_bf16 v[124:127], v[140:143], v[164:167], v[124:127]
	v_mfma_f32_16x16x32_bf16 v[120:123], v[156:159], v[164:167], v[120:123]
	v_mfma_f32_16x16x32_bf16 v[112:115], v[140:143], v[172:175], v[112:115]
	v_mfma_f32_16x16x32_bf16 v[104:107], v[156:159], v[172:175], v[104:107]
	v_mfma_f32_16x16x32_bf16 v[92:95], v[140:143], v[180:183], v[92:95]
	v_mfma_f32_16x16x32_bf16 v[88:91], v[156:159], v[180:183], v[88:91]
	v_mfma_f32_16x16x32_bf16 v[80:83], v[140:143], v[188:191], v[80:83]
	v_mfma_f32_16x16x32_bf16 v[72:75], v[156:159], v[188:191], v[72:75]
	v_mfma_f32_16x16x32_bf16 v[124:127], v[152:155], v[168:171], v[124:127]
	v_mfma_f32_16x16x32_bf16 v[120:123], v[160:163], v[168:171], v[120:123]
	v_mfma_f32_16x16x32_bf16 v[112:115], v[152:155], v[176:179], v[112:115]
	v_mfma_f32_16x16x32_bf16 v[104:107], v[160:163], v[176:179], v[104:107]
	v_mfma_f32_16x16x32_bf16 v[92:95], v[152:155], v[184:187], v[92:95]
	v_mfma_f32_16x16x32_bf16 v[88:91], v[160:163], v[184:187], v[88:91]
	v_mfma_f32_16x16x32_bf16 v[80:83], v[152:155], v[192:195], v[80:83]
	v_mfma_f32_16x16x32_bf16 v[72:75], v[160:163], v[192:195], v[72:75]
	v_mfma_f32_16x16x32_bf16 v[116:119], v[196:199], v[164:167], v[116:119]
	v_mfma_f32_16x16x32_bf16 v[108:111], v[204:207], v[164:167], v[108:111]
	v_mfma_f32_16x16x32_bf16 v[100:103], v[196:199], v[172:175], v[100:103]
	v_mfma_f32_16x16x32_bf16 v[96:99], v[204:207], v[172:175], v[96:99]
	v_mfma_f32_16x16x32_bf16 v[84:87], v[196:199], v[180:183], v[84:87]
	v_mfma_f32_16x16x32_bf16 v[76:79], v[204:207], v[180:183], v[76:79]
	v_mfma_f32_16x16x32_bf16 v[68:71], v[196:199], v[188:191], v[68:71]
	v_mfma_f32_16x16x32_bf16 v[64:67], v[204:207], v[188:191], v[64:67]
	v_mfma_f32_16x16x32_bf16 v[116:119], v[200:203], v[168:171], v[116:119]
	v_mfma_f32_16x16x32_bf16 v[108:111], v[208:211], v[168:171], v[108:111]
	v_mfma_f32_16x16x32_bf16 v[100:103], v[200:203], v[176:179], v[100:103]
	v_mfma_f32_16x16x32_bf16 v[96:99], v[208:211], v[176:179], v[96:99]
	v_mfma_f32_16x16x32_bf16 v[84:87], v[200:203], v[184:187], v[84:87]
	v_mfma_f32_16x16x32_bf16 v[76:79], v[208:211], v[184:187], v[76:79]
	v_mfma_f32_16x16x32_bf16 v[68:71], v[200:203], v[192:195], v[68:71]
	v_mfma_f32_16x16x32_bf16 v[64:67], v[208:211], v[192:195], v[64:67]
	s_setprio 0
	s_barrier
	s_nop 1
	ds_read_b128 v[164:167], v150 offset:49152
	ds_read_b128 v[168:171], v150 offset:50176
	ds_read_b128 v[172:175], v150 offset:51200
	ds_read_b128 v[176:179], v150 offset:52224
	ds_read_b128 v[180:183], v150 offset:53248
	ds_read_b128 v[184:187], v150 offset:54272
	ds_read_b128 v[188:191], v150 offset:55296
	ds_read_b128 v[192:195], v150 offset:56320
	s_add_i32 s28, s69, s7
	s_mov_b32 m0, s28
	s_nop 0
	s_add_u32 s100, s34, s20
	s_addc_u32 s101, s35, s21
	global_load_lds_dwordx4 v128, s[100:101]
	s_add_i32 m0, s28, 0x2000
	s_nop 0
	s_add_u32 s100, s34, s20
	s_addc_u32 s101, s35, s21
	global_load_lds_dwordx4 v130, s[100:101]
	s_mov_b32 m0, s41
	v_lshl_add_u64 v[254:255], v[214:215], 0, s[20:21]
	global_load_lds_dwordx4 v[254:255], off
	v_lshl_add_u64 v[144:145], v[216:217], 0, s[20:21]
	s_mov_b32 m0, s42
	s_nop 0
	global_load_lds_dwordx4 v[144:145], off
	s_add_u32 s28, s34, 0xb0080
	s_addc_u32 s29, s35, 0
	s_add_i32 s34, s36, s7
	s_mov_b32 m0, s34
	s_nop 0
	global_load_lds_dwordx4 v128, s[28:29]
	s_add_i32 m0, s34, 0x2000
	s_nop 0
	global_load_lds_dwordx4 v130, s[28:29]
	s_waitcnt vmcnt(6)
	s_waitcnt lgkmcnt(0)
	s_barrier
	s_setprio 1
	v_mfma_f32_16x16x32_bf16 v[60:63], v[140:143], v[164:167], v[60:63]
	v_mfma_f32_16x16x32_bf16 v[56:59], v[156:159], v[164:167], v[56:59]
	v_mfma_f32_16x16x32_bf16 v[48:51], v[140:143], v[172:175], v[48:51]
	v_mfma_f32_16x16x32_bf16 v[40:43], v[156:159], v[172:175], v[40:43]
	v_mfma_f32_16x16x32_bf16 v[28:31], v[140:143], v[180:183], v[28:31]
	v_mfma_f32_16x16x32_bf16 v[24:27], v[156:159], v[180:183], v[24:27]
	v_mfma_f32_16x16x32_bf16 v[16:19], v[140:143], v[188:191], v[16:19]
	v_mfma_f32_16x16x32_bf16 v[8:11], v[156:159], v[188:191], v[8:11]
	v_mfma_f32_16x16x32_bf16 v[60:63], v[152:155], v[168:171], v[60:63]
	v_mfma_f32_16x16x32_bf16 v[56:59], v[160:163], v[168:171], v[56:59]
	v_mfma_f32_16x16x32_bf16 v[48:51], v[152:155], v[176:179], v[48:51]
	v_mfma_f32_16x16x32_bf16 v[40:43], v[160:163], v[176:179], v[40:43]
	v_mfma_f32_16x16x32_bf16 v[28:31], v[152:155], v[184:187], v[28:31]
	v_mfma_f32_16x16x32_bf16 v[24:27], v[160:163], v[184:187], v[24:27]
	v_mfma_f32_16x16x32_bf16 v[16:19], v[152:155], v[192:195], v[16:19]
	v_mfma_f32_16x16x32_bf16 v[8:11], v[160:163], v[192:195], v[8:11]
	v_mfma_f32_16x16x32_bf16 v[52:55], v[196:199], v[164:167], v[52:55]
	v_mfma_f32_16x16x32_bf16 v[44:47], v[204:207], v[164:167], v[44:47]
	v_mfma_f32_16x16x32_bf16 v[36:39], v[196:199], v[172:175], v[36:39]
	v_mfma_f32_16x16x32_bf16 v[32:35], v[204:207], v[172:175], v[32:35]
	v_mfma_f32_16x16x32_bf16 v[20:23], v[196:199], v[180:183], v[20:23]
	v_mfma_f32_16x16x32_bf16 v[12:15], v[204:207], v[180:183], v[12:15]
	v_mfma_f32_16x16x32_bf16 v[4:7], v[196:199], v[188:191], v[4:7]
	v_mfma_f32_16x16x32_bf16 v[0:3], v[204:207], v[188:191], v[0:3]
	v_mfma_f32_16x16x32_bf16 v[52:55], v[200:203], v[168:171], v[52:55]
	v_mfma_f32_16x16x32_bf16 v[44:47], v[208:211], v[168:171], v[44:47]
	v_mfma_f32_16x16x32_bf16 v[36:39], v[200:203], v[176:179], v[36:39]
	v_mfma_f32_16x16x32_bf16 v[32:35], v[208:211], v[176:179], v[32:35]
	v_mfma_f32_16x16x32_bf16 v[20:23], v[200:203], v[184:187], v[20:23]
	v_mfma_f32_16x16x32_bf16 v[12:15], v[208:211], v[184:187], v[12:15]
	v_mfma_f32_16x16x32_bf16 v[4:7], v[200:203], v[192:195], v[4:7]
	v_mfma_f32_16x16x32_bf16 v[0:3], v[208:211], v[192:195], v[0:3]
	s_setprio 0
	s_add_i32 s68, s68, 2
	s_add_u32 s49, s49, 0x100
	s_addc_u32 s63, s63, 0
	s_cmp_gt_u32 s68, 41
	s_mov_b64 s[28:29], s[30:31]
	s_barrier
; #define PG8_STAGE(bufoff, gbase, voff) do { _Pragma("unroll") for (int _i = 0; _i < 2; ++_i) \
;         __builtin_amdgcn_global_load_lds((const unsigned*)((const char*)(gbase) + (voff)[_i]), (LAS unsigned*)(lds + (bufoff) + ldsw + _i * 8192), 16, 0, 0); } while (0)
; #define PG8_LDA(dst, b, h) do { _Pragma("unroll") for (int m = 0; m < 4; ++m) _Pragma("unroll") for (int k = 0; k < 2; ++k) dst[m][k] = *(const LAS bf16x8*)(lds + PG8_SA(b, h) + aoff + m * 2048 + k * 1024); } while (0)
; #define PG8_LDB(dst, b, h) do { _Pragma("unroll") for (int n = 0; n < 2; ++n) _Pragma("unroll") for (int k = 0; k < 2; ++k) dst[n][k] = *(const LAS bf16x8*)(lds + PG8_SB(b, h) + boff + n * 2048 + k * 1024); } while (0)
; #define PG8_MMA(ai, bj, At, Bt) do { __builtin_amdgcn_s_setprio(1); _Pragma("unroll") for (int m = 0; m < 4; ++m) _Pragma("unroll") for (int n = 0; n < 2; ++n) _Pragma("unroll") for (int k = 0; k < 2; ++k) \
;         acc[ai][bj][m][n] = __builtin_amdgcn_mfma_f32_16x16x32_bf16(Bt[n][k], At[m][k], acc[ai][bj][m][n], 0, 0, 0); __builtin_amdgcn_s_setprio(0); } while (0)
; #define PG8_WAIT_V(n) asm volatile("s_waitcnt vmcnt(" #n ")" ::: "memory")
; #define PG8_WAIT_L(n) asm volatile("s_waitcnt lgkmcnt(" #n ")" ::: "memory")
; template <class Epi>
; __device__ __forceinline__ void gemm_phase(LAS unsigned char* lds, const Gemm g, const StaticOrder& S, const Epi& E) {
;     ...
;         for (int t = 0; t < nt; t += 2) {
;             const bool last = (t == nt - 2);
;             const char* a1 = cA + (size_t)(t + 1) * kstep;
;             const char* a2 = last ? nA : cA + (size_t)(t + 2) * kstep; const char* b2 = last ? nB : cB + (size_t)(t + 2) * kstep;
;             const char* a3 = a2 + kstep; const char* b3 = b2 + kstep;
;             PG8_LDB(B0, 0, 0); PG8_SCHED; PG8_LDA(At, 0, 0); PG8_STAGE(PG8_SA(1, 1), a1 + hstepA, voffA);
;             PG8_WAIT_L(8); PG8_BAR; PG8_WAIT_L(0); PG8_MMA(0, 0, At, B0); PG8_BAR; PG8_SCHED;
;             PG8_LDB(B1, 0, 1); PG8_STAGE(PG8_SB(0, 0), b2, voffB);
;             PG8_BAR; PG8_WAIT_L(0); PG8_MMA(0, 1, At, B1); PG8_BAR;
;             PG8_LDA(At, 0, 1); PG8_STAGE(PG8_SA(0, 0), a2, voffA);
;             PG8_BAR; PG8_WAIT_L(0); PG8_MMA(1, 0, At, B0); PG8_BAR; PG8_SCHED;
;             PG8_STAGE(PG8_SB(0, 1), b2 + hstepB, voffB);
;             PG8_WAIT_V(6); PG8_BAR; PG8_MMA(1, 1, At, B1); PG8_BAR;
.LBB0_860:
	ds_read_b128 v[140:143], v149
	ds_read_b128 v[152:155], v149 offset:1024
	ds_read_b128 v[156:159], v149 offset:2048
	ds_read_b128 v[160:163], v149 offset:3072
	s_add_u32 s30, s28, 0x100
	s_addc_u32 s31, s29, 0
	s_cmp_eq_u32 s68, 40
	s_cselect_b32 s37, s13, s31
	s_cselect_b32 s36, s12, s30
	s_cselect_b32 s35, s15, s63
	s_cselect_b32 s34, s14, s49
	s_add_i32 m0, s8, 0xc000
	ds_read_b128 v[164:167], v150
	ds_read_b128 v[168:171], v150 offset:1024
	ds_read_b128 v[172:175], v150 offset:2048
	ds_read_b128 v[176:179], v150 offset:3072
	ds_read_b128 v[180:183], v150 offset:4096
	ds_read_b128 v[184:187], v150 offset:5120
	ds_read_b128 v[188:191], v150 offset:6144
	ds_read_b128 v[192:195], v150 offset:7168
	global_load_lds_dwordx4 v132, s[28:29]
	s_add_i32 m0, s8, 0xe000
	s_nop 0
	global_load_lds_dwordx4 v134, s[28:29]
	ds_read_b128 v[196:199], v151
	ds_read_b128 v[200:203], v151 offset:1024
	ds_read_b128 v[204:207], v151 offset:2048
	ds_read_b128 v[208:211], v151 offset:3072
	s_waitcnt lgkmcnt(0)
	s_barrier
	s_setprio 1
	v_mfma_f32_16x16x32_bf16 v[124:127], v[140:143], v[164:167], v[124:127]
	v_mfma_f32_16x16x32_bf16 v[120:123], v[156:159], v[164:167], v[120:123]
	v_mfma_f32_16x16x32_bf16 v[112:115], v[140:143], v[172:175], v[112:115]
	v_mfma_f32_16x16x32_bf16 v[104:107], v[156:159], v[172:175], v[104:107]
	v_mfma_f32_16x16x32_bf16 v[92:95], v[140:143], v[180:183], v[92:95]
	v_mfma_f32_16x16x32_bf16 v[88:91], v[156:159], v[180:183], v[88:91]
	v_mfma_f32_16x16x32_bf16 v[80:83], v[140:143], v[188:191], v[80:83]
	v_mfma_f32_16x16x32_bf16 v[72:75], v[156:159], v[188:191], v[72:75]
	v_mfma_f32_16x16x32_bf16 v[124:127], v[152:155], v[168:171], v[124:127]
	v_mfma_f32_16x16x32_bf16 v[120:123], v[160:163], v[168:171], v[120:123]
	v_mfma_f32_16x16x32_bf16 v[112:115], v[152:155], v[176:179], v[112:115]
	v_mfma_f32_16x16x32_bf16 v[104:107], v[160:163], v[176:179], v[104:107]
	v_mfma_f32_16x16x32_bf16 v[92:95], v[152:155], v[184:187], v[92:95]
	v_mfma_f32_16x16x32_bf16 v[88:91], v[160:163], v[184:187], v[88:91]
	v_mfma_f32_16x16x32_bf16 v[80:83], v[152:155], v[192:195], v[80:83]
	v_mfma_f32_16x16x32_bf16 v[72:75], v[160:163], v[192:195], v[72:75]
	v_mfma_f32_16x16x32_bf16 v[116:119], v[196:199], v[164:167], v[116:119]
	v_mfma_f32_16x16x32_bf16 v[108:111], v[204:207], v[164:167], v[108:111]
	v_mfma_f32_16x16x32_bf16 v[100:103], v[196:199], v[172:175], v[100:103]
	v_mfma_f32_16x16x32_bf16 v[96:99], v[204:207], v[172:175], v[96:99]
	v_mfma_f32_16x16x32_bf16 v[84:87], v[196:199], v[180:183], v[84:87]
	v_mfma_f32_16x16x32_bf16 v[76:79], v[204:207], v[180:183], v[76:79]
	v_mfma_f32_16x16x32_bf16 v[68:71], v[196:199], v[188:191], v[68:71]
	v_mfma_f32_16x16x32_bf16 v[64:67], v[204:207], v[188:191], v[64:67]
	v_mfma_f32_16x16x32_bf16 v[116:119], v[200:203], v[168:171], v[116:119]
	v_mfma_f32_16x16x32_bf16 v[108:111], v[208:211], v[168:171], v[108:111]
	v_mfma_f32_16x16x32_bf16 v[100:103], v[200:203], v[176:179], v[100:103]
	v_mfma_f32_16x16x32_bf16 v[96:99], v[208:211], v[176:179], v[96:99]
	v_mfma_f32_16x16x32_bf16 v[84:87], v[200:203], v[184:187], v[84:87]
	v_mfma_f32_16x16x32_bf16 v[76:79], v[208:211], v[184:187], v[76:79]
	v_mfma_f32_16x16x32_bf16 v[68:71], v[200:203], v[192:195], v[68:71]
	v_mfma_f32_16x16x32_bf16 v[64:67], v[208:211], v[192:195], v[64:67]
	s_setprio 0
	s_barrier
	s_nop 1
	ds_read_b128 v[164:167], v150 offset:16384
	ds_read_b128 v[168:171], v150 offset:17408
	ds_read_b128 v[172:175], v150 offset:18432
	ds_read_b128 v[176:179], v150 offset:19456
	ds_read_b128 v[180:183], v150 offset:20480
	ds_read_b128 v[184:187], v150 offset:21504
	ds_read_b128 v[188:191], v150 offset:22528
	ds_read_b128 v[192:195], v150 offset:23552
	s_add_i32 s28, s43, s7
	v_lshl_add_u64 v[144:145], s[34:35], 0, v[128:129]
	s_mov_b32 m0, s28
	s_nop 0
	global_load_lds_dwordx4 v128, s[34:35]
	v_lshl_add_u64 v[212:213], s[34:35], 0, v[130:131]
	s_add_i32 m0, s28, 0x2000
	s_nop 0
	global_load_lds_dwordx4 v130, s[34:35]
	s_mov_b32 m0, s8
	v_lshl_add_u64 v[214:215], s[36:37], 0, v[128:129]
	global_load_lds_dwordx4 v128, s[36:37]
	v_lshl_add_u64 v[216:217], s[36:37], 0, v[130:131]
	s_mov_b32 m0, s9
	s_nop 0
	global_load_lds_dwordx4 v130, s[36:37]
	s_add_u32 s28, s34, 0xb0000
	s_addc_u32 s29, s35, 0
	s_add_i32 s69, s44, s7
	s_mov_b32 m0, s69
	s_nop 0
	global_load_lds_dwordx4 v128, s[28:29]
	s_add_i32 m0, s69, 0x2000
	s_nop 0
	global_load_lds_dwordx4 v130, s[28:29]
	s_waitcnt vmcnt(6)
	s_waitcnt lgkmcnt(0)
	s_barrier
	s_setprio 1
	v_mfma_f32_16x16x32_bf16 v[60:63], v[140:143], v[164:167], v[60:63]
	v_mfma_f32_16x16x32_bf16 v[56:59], v[156:159], v[164:167], v[56:59]
	v_mfma_f32_16x16x32_bf16 v[48:51], v[140:143], v[172:175], v[48:51]
	v_mfma_f32_16x16x32_bf16 v[40:43], v[156:159], v[172:175], v[40:43]
	v_mfma_f32_16x16x32_bf16 v[28:31], v[140:143], v[180:183], v[28:31]
	v_mfma_f32_16x16x32_bf16 v[24:27], v[156:159], v[180:183], v[24:27]
	v_mfma_f32_16x16x32_bf16 v[16:19], v[140:143], v[188:191], v[16:19]
	v_mfma_f32_16x16x32_bf16 v[8:11], v[156:159], v[188:191], v[8:11]
	v_mfma_f32_16x16x32_bf16 v[60:63], v[152:155], v[168:171], v[60:63]
	v_mfma_f32_16x16x32_bf16 v[56:59], v[160:163], v[168:171], v[56:59]
	v_mfma_f32_16x16x32_bf16 v[48:51], v[152:155], v[176:179], v[48:51]
	v_mfma_f32_16x16x32_bf16 v[40:43], v[160:163], v[176:179], v[40:43]
	v_mfma_f32_16x16x32_bf16 v[28:31], v[152:155], v[184:187], v[28:31]
	v_mfma_f32_16x16x32_bf16 v[24:27], v[160:163], v[184:187], v[24:27]
	v_mfma_f32_16x16x32_bf16 v[16:19], v[152:155], v[192:195], v[16:19]
	v_mfma_f32_16x16x32_bf16 v[8:11], v[160:163], v[192:195], v[8:11]
	v_mfma_f32_16x16x32_bf16 v[52:55], v[196:199], v[164:167], v[52:55]
	v_mfma_f32_16x16x32_bf16 v[44:47], v[204:207], v[164:167], v[44:47]
	v_mfma_f32_16x16x32_bf16 v[36:39], v[196:199], v[172:175], v[36:39]
	v_mfma_f32_16x16x32_bf16 v[32:35], v[204:207], v[172:175], v[32:35]
	v_mfma_f32_16x16x32_bf16 v[20:23], v[196:199], v[180:183], v[20:23]
	v_mfma_f32_16x16x32_bf16 v[12:15], v[204:207], v[180:183], v[12:15]
	v_mfma_f32_16x16x32_bf16 v[4:7], v[196:199], v[188:191], v[4:7]
	v_mfma_f32_16x16x32_bf16 v[0:3], v[204:207], v[188:191], v[0:3]
	v_mfma_f32_16x16x32_bf16 v[52:55], v[200:203], v[168:171], v[52:55]
	v_mfma_f32_16x16x32_bf16 v[44:47], v[208:211], v[168:171], v[44:47]
	v_mfma_f32_16x16x32_bf16 v[36:39], v[200:203], v[176:179], v[36:39]
	v_mfma_f32_16x16x32_bf16 v[32:35], v[208:211], v[176:179], v[32:35]
	v_mfma_f32_16x16x32_bf16 v[20:23], v[200:203], v[184:187], v[20:23]
	v_mfma_f32_16x16x32_bf16 v[12:15], v[208:211], v[184:187], v[12:15]
	v_mfma_f32_16x16x32_bf16 v[4:7], v[200:203], v[192:195], v[4:7]
	v_mfma_f32_16x16x32_bf16 v[0:3], v[208:211], v[192:195], v[0:3]
	s_setprio 0
	s_add_i32 s69, 0, 0x18000
	v_add_u32_e32 v160, s69, v147
	s_barrier
; #define PG8_STAGE(bufoff, gbase, voff) do { _Pragma("unroll") for (int _i = 0; _i < 2; ++_i) \
;         __builtin_amdgcn_global_load_lds((const unsigned*)((const char*)(gbase) + (voff)[_i]), (LAS unsigned*)(lds + (bufoff) + ldsw + _i * 8192), 16, 0, 0); } while (0)
; #define PG8_LDA(dst, b, h) do { _Pragma("unroll") for (int m = 0; m < 4; ++m) _Pragma("unroll") for (int k = 0; k < 2; ++k) dst[m][k] = *(const LAS bf16x8*)(lds + PG8_SA(b, h) + aoff + m * 2048 + k * 1024); } while (0)
; #define PG8_LDB(dst, b, h) do { _Pragma("unroll") for (int n = 0; n < 2; ++n) _Pragma("unroll") for (int k = 0; k < 2; ++k) dst[n][k] = *(const LAS bf16x8*)(lds + PG8_SB(b, h) + boff + n * 2048 + k * 1024); } while (0)
; #define PG8_MMA(ai, bj, At, Bt) do { __builtin_amdgcn_s_setprio(1); _Pragma("unroll") for (int m = 0; m < 4; ++m) _Pragma("unroll") for (int n = 0; n < 2; ++n) _Pragma("unroll") for (int k = 0; k < 2; ++k) \
;         acc[ai][bj][m][n] = __builtin_amdgcn_mfma_f32_16x16x32_bf16(Bt[n][k], At[m][k], acc[ai][bj][m][n], 0, 0, 0); __builtin_amdgcn_s_setprio(0); } while (0)
; #define PG8_WAIT_V(n) asm volatile("s_waitcnt vmcnt(" #n ")" ::: "memory")
; #define PG8_WAIT_L(n) asm volatile("s_waitcnt lgkmcnt(" #n ")" ::: "memory")
; #define PG8_BAR __builtin_amdgcn_s_barrier()
; #define PG8_SCHED __builtin_amdgcn_sched_barrier(0)
; template <class Epi>
; __device__ __forceinline__ void gemm_phase(LAS unsigned char* lds, const Gemm g, const StaticOrder& S, const Epi& E) {
;     ...
;             PG8_LDB(B0, 1, 0); PG8_SCHED; PG8_LDA(At, 1, 0); PG8_STAGE(PG8_SA(0, 1), a2 + hstepA, voffA);
;             PG8_WAIT_L(8); PG8_BAR; PG8_WAIT_L(0); PG8_MMA(0, 0, At, B0); PG8_BAR; PG8_SCHED;
;             PG8_LDB(B1, 1, 1); PG8_STAGE(PG8_SB(1, 0), b3, voffB);
;             PG8_BAR; PG8_WAIT_L(0); PG8_MMA(0, 1, At, B1); PG8_BAR;
;             PG8_LDA(At, 1, 1); PG8_STAGE(PG8_SA(1, 0), a3, voffA);
;             PG8_BAR; PG8_WAIT_L(0); PG8_MMA(1, 0, At, B0); PG8_BAR; PG8_SCHED;
;             PG8_STAGE(PG8_SB(1, 1), b3 + hstepB, voffB);
;             PG8_WAIT_V(6); PG8_BAR; PG8_MMA(1, 1, At, B1); PG8_BAR;
	ds_read_b128 v[140:143], v160
	ds_read_b128 v[152:155], v160 offset:1024
	ds_read_b128 v[156:159], v160 offset:2048
	ds_read_b128 v[160:163], v160 offset:3072
	s_add_u32 s28, s36, 0xb0000
	s_addc_u32 s29, s37, 0
	s_mov_b32 m0, s38
	ds_read_b128 v[164:167], v150 offset:32768
	ds_read_b128 v[168:171], v150 offset:33792
	ds_read_b128 v[172:175], v150 offset:34816
	ds_read_b128 v[176:179], v150 offset:35840
	ds_read_b128 v[180:183], v150 offset:36864
	ds_read_b128 v[184:187], v150 offset:37888
	ds_read_b128 v[188:191], v150 offset:38912
	ds_read_b128 v[192:195], v150 offset:39936
	global_load_lds_dwordx4 v128, s[28:29]
	s_mov_b32 m0, s39
	s_nop 0
	global_load_lds_dwordx4 v130, s[28:29]
	s_add_i32 s36, 0, 0x1c000
	v_add_u32_e32 v208, s36, v147
	ds_read_b128 v[196:199], v208
	ds_read_b128 v[200:203], v208 offset:1024
	ds_read_b128 v[204:207], v208 offset:2048
	ds_read_b128 v[208:211], v208 offset:3072
	s_waitcnt lgkmcnt(0)
	s_barrier
	s_setprio 1
	v_mfma_f32_16x16x32_bf16 v[124:127], v[140:143], v[164:167], v[124:127]
	v_mfma_f32_16x16x32_bf16 v[120:123], v[156:159], v[164:167], v[120:123]
	v_mfma_f32_16x16x32_bf16 v[112:115], v[140:143], v[172:175], v[112:115]
	v_mfma_f32_16x16x32_bf16 v[104:107], v[156:159], v[172:175], v[104:107]
	v_mfma_f32_16x16x32_bf16 v[92:95], v[140:143], v[180:183], v[92:95]
	v_mfma_f32_16x16x32_bf16 v[88:91], v[156:159], v[180:183], v[88:91]
	v_mfma_f32_16x16x32_bf16 v[80:83], v[140:143], v[188:191], v[80:83]
	v_mfma_f32_16x16x32_bf16 v[72:75], v[156:159], v[188:191], v[72:75]
	v_mfma_f32_16x16x32_bf16 v[124:127], v[152:155], v[168:171], v[124:127]
	v_mfma_f32_16x16x32_bf16 v[120:123], v[160:163], v[168:171], v[120:123]
	v_mfma_f32_16x16x32_bf16 v[112:115], v[152:155], v[176:179], v[112:115]
	v_mfma_f32_16x16x32_bf16 v[104:107], v[160:163], v[176:179], v[104:107]
	v_mfma_f32_16x16x32_bf16 v[92:95], v[152:155], v[184:187], v[92:95]
	v_mfma_f32_16x16x32_bf16 v[88:91], v[160:163], v[184:187], v[88:91]
	v_mfma_f32_16x16x32_bf16 v[80:83], v[152:155], v[192:195], v[80:83]
	v_mfma_f32_16x16x32_bf16 v[72:75], v[160:163], v[192:195], v[72:75]
	v_mfma_f32_16x16x32_bf16 v[116:119], v[196:199], v[164:167], v[116:119]
	v_mfma_f32_16x16x32_bf16 v[108:111], v[204:207], v[164:167], v[108:111]
	v_mfma_f32_16x16x32_bf16 v[100:103], v[196:199], v[172:175], v[100:103]
	v_mfma_f32_16x16x32_bf16 v[96:99], v[204:207], v[172:175], v[96:99]
	v_mfma_f32_16x16x32_bf16 v[84:87], v[196:199], v[180:183], v[84:87]
	v_mfma_f32_16x16x32_bf16 v[76:79], v[204:207], v[180:183], v[76:79]
	v_mfma_f32_16x16x32_bf16 v[68:71], v[196:199], v[188:191], v[68:71]
	v_mfma_f32_16x16x32_bf16 v[64:67], v[204:207], v[188:191], v[64:67]
	v_mfma_f32_16x16x32_bf16 v[116:119], v[200:203], v[168:171], v[116:119]
	v_mfma_f32_16x16x32_bf16 v[108:111], v[208:211], v[168:171], v[108:111]
	v_mfma_f32_16x16x32_bf16 v[100:103], v[200:203], v[176:179], v[100:103]
	v_mfma_f32_16x16x32_bf16 v[96:99], v[208:211], v[176:179], v[96:99]
	v_mfma_f32_16x16x32_bf16 v[84:87], v[200:203], v[184:187], v[84:87]
	v_mfma_f32_16x16x32_bf16 v[76:79], v[208:211], v[184:187], v[76:79]
	v_mfma_f32_16x16x32_bf16 v[68:71], v[200:203], v[192:195], v[68:71]
	v_mfma_f32_16x16x32_bf16 v[64:67], v[208:211], v[192:195], v[64:67]
	s_setprio 0
	s_barrier
	s_nop 1
	ds_read_b128 v[164:167], v150 offset:49152
	ds_read_b128 v[168:171], v150 offset:50176
	ds_read_b128 v[172:175], v150 offset:51200
	ds_read_b128 v[176:179], v150 offset:52224
	ds_read_b128 v[180:183], v150 offset:53248
	ds_read_b128 v[184:187], v150 offset:54272
	ds_read_b128 v[188:191], v150 offset:55296
	ds_read_b128 v[192:195], v150 offset:56320
	s_add_i32 s28, s69, s7
	s_mov_b32 m0, s28
	s_nop 0
	s_add_u32 s100, s34, s20
	s_addc_u32 s101, s35, s21
	global_load_lds_dwordx4 v128, s[100:101]
	s_add_i32 m0, s28, 0x2000
	s_nop 0
	s_add_u32 s100, s34, s20
	s_addc_u32 s101, s35, s21
	global_load_lds_dwordx4 v130, s[100:101]
	s_mov_b32 m0, s41
	v_lshl_add_u64 v[254:255], v[214:215], 0, s[20:21]
	global_load_lds_dwordx4 v[254:255], off
	v_lshl_add_u64 v[144:145], v[216:217], 0, s[20:21]
	s_mov_b32 m0, s42
	s_nop 0
	global_load_lds_dwordx4 v[144:145], off
	s_add_u32 s28, s34, 0xb0080
	s_addc_u32 s29, s35, 0
	s_add_i32 s34, s36, s7
	s_mov_b32 m0, s34
	s_nop 0
	global_load_lds_dwordx4 v128, s[28:29]
	s_add_i32 m0, s34, 0x2000
	s_nop 0
	global_load_lds_dwordx4 v130, s[28:29]
	s_waitcnt vmcnt(6)
	s_waitcnt lgkmcnt(0)
	s_barrier
	s_setprio 1
	v_mfma_f32_16x16x32_bf16 v[60:63], v[140:143], v[164:167], v[60:63]
	v_mfma_f32_16x16x32_bf16 v[56:59], v[156:159], v[164:167], v[56:59]
	v_mfma_f32_16x16x32_bf16 v[48:51], v[140:143], v[172:175], v[48:51]
	v_mfma_f32_16x16x32_bf16 v[40:43], v[156:159], v[172:175], v[40:43]
	v_mfma_f32_16x16x32_bf16 v[28:31], v[140:143], v[180:183], v[28:31]
	v_mfma_f32_16x16x32_bf16 v[24:27], v[156:159], v[180:183], v[24:27]
	v_mfma_f32_16x16x32_bf16 v[16:19], v[140:143], v[188:191], v[16:19]
	v_mfma_f32_16x16x32_bf16 v[8:11], v[156:159], v[188:191], v[8:11]
	v_mfma_f32_16x16x32_bf16 v[60:63], v[152:155], v[168:171], v[60:63]
	v_mfma_f32_16x16x32_bf16 v[56:59], v[160:163], v[168:171], v[56:59]
	v_mfma_f32_16x16x32_bf16 v[48:51], v[152:155], v[176:179], v[48:51]
	v_mfma_f32_16x16x32_bf16 v[40:43], v[160:163], v[176:179], v[40:43]
	v_mfma_f32_16x16x32_bf16 v[28:31], v[152:155], v[184:187], v[28:31]
	v_mfma_f32_16x16x32_bf16 v[24:27], v[160:163], v[184:187], v[24:27]
	v_mfma_f32_16x16x32_bf16 v[16:19], v[152:155], v[192:195], v[16:19]
	v_mfma_f32_16x16x32_bf16 v[8:11], v[160:163], v[192:195], v[8:11]
	v_mfma_f32_16x16x32_bf16 v[52:55], v[196:199], v[164:167], v[52:55]
	v_mfma_f32_16x16x32_bf16 v[44:47], v[204:207], v[164:167], v[44:47]
	v_mfma_f32_16x16x32_bf16 v[36:39], v[196:199], v[172:175], v[36:39]
	v_mfma_f32_16x16x32_bf16 v[32:35], v[204:207], v[172:175], v[32:35]
	v_mfma_f32_16x16x32_bf16 v[20:23], v[196:199], v[180:183], v[20:23]
	v_mfma_f32_16x16x32_bf16 v[12:15], v[204:207], v[180:183], v[12:15]
	v_mfma_f32_16x16x32_bf16 v[4:7], v[196:199], v[188:191], v[4:7]
	v_mfma_f32_16x16x32_bf16 v[0:3], v[204:207], v[188:191], v[0:3]
	v_mfma_f32_16x16x32_bf16 v[52:55], v[200:203], v[168:171], v[52:55]
	v_mfma_f32_16x16x32_bf16 v[44:47], v[208:211], v[168:171], v[44:47]
	v_mfma_f32_16x16x32_bf16 v[36:39], v[200:203], v[176:179], v[36:39]
	v_mfma_f32_16x16x32_bf16 v[32:35], v[208:211], v[176:179], v[32:35]
	v_mfma_f32_16x16x32_bf16 v[20:23], v[200:203], v[184:187], v[20:23]
	v_mfma_f32_16x16x32_bf16 v[12:15], v[208:211], v[184:187], v[12:15]
	v_mfma_f32_16x16x32_bf16 v[4:7], v[200:203], v[192:195], v[4:7]
	v_mfma_f32_16x16x32_bf16 v[0:3], v[208:211], v[192:195], v[0:3]
	s_setprio 0
	s_add_i32 s68, s68, 2
	s_add_u32 s49, s49, 0x100
	s_addc_u32 s63, s63, 0
	s_cmp_gt_u32 s68, 41
	s_mov_b64 s[28:29], s[30:31]
	s_barrier
;     __device__ __forceinline__ void operator()(AccRef acc, const Unit& u, int wr, int wc, int fr, int fq) const {
;         const int row0 = u.pm * 256 + wr * 64 + fr, col0 = u.pn * 256 + wc * 32 + 4 * fq;
;         f32x4 sv[2][2], bv[2][2];
; #pragma unroll
;         for (int bj = 0; bj < 2; ++bj)
; #pragma unroll
;             for (int n = 0; n < 2; ++n) {
;                 sv[bj][n] = scale ? *(const f32x4*)(scale + col0 + bj * 128 + n * 16) : (f32x4){1.f, 1.f, 1.f, 1.f};
;                 bv[bj][n] = bias ? *(const f32x4*)(bias + col0 + bj * 128 + n * 16) : (f32x4){0.f, 0.f, 0.f, 0.f}; }
; #pragma unroll
;         for (int ai = 0; ai < 2; ++ai)
; #pragma unroll
;             for (int mh = 0; mh < 2; ++mh) {
;                 f32x4 bs[2][2][2];
; #pragma unroll
;                 for (int m = 0; m < 2; ++m)
; #pragma unroll
;                     for (int bj = 0; bj < 2; ++bj)
; #pragma unroll
;                         for (int n = 0; n < 2; ++n) bs[m][bj][n] = *(const f32x4*)(base + (size_t)(row0 + ai * 128 + (2 * mh + m) * 16) * D + col0 + bj * 128 + n * 16);
; #pragma unroll
;                 for (int m = 0; m < 2; ++m)
; #pragma unroll
;                     for (int bj = 0; bj < 2; ++bj)
; #pragma unroll
;                         for (int n = 0; n < 2; ++n) *(f32x4*)(out + (size_t)(row0 + ai * 128 + (2 * mh + m) * 16) * D + col0 + bj * 128 + n * 16) = bs[m][bj][n] + sv[bj][n] * (acc[ai][bj][2 * mh + m][n] + bv[bj][n]);
	s_cbranch_scc0 .LBB0_860
	v_lshl_or_b32 v144, s47, 8, v148
	v_lshl_add_u32 v145, s48, 8, v146
	v_lshlrev_b32_e32 v144, 2, v144
	v_lshl_add_u32 v145, v145, 12, v144
	v_add_u32_e32 v216, 0x10000, v145
	v_add_u32_e32 v217, 0x20000, v145
	v_add_u32_e32 v218, 0x30000, v145
	v_add_u32_e32 v232, 0x80000, v145
	v_add_u32_e32 v233, 0x90000, v145
	v_add_u32_e32 v235, 0xa0000, v145
	v_add_u32_e32 v253, 0xb0000, v145
	s_and_b64 vcc, exec, s[10:11]
	s_mov_b32 s47, s45
	s_mov_b32 s48, s46
	s_mov_b64 s[30:31], s[14:15]
	s_mov_b64 s[28:29], s[12:13]
	global_load_dwordx4 v[140:143], v145, s[52:53]
	global_load_dwordx4 v[152:155], v145, s[52:53] offset:64
	global_load_dwordx4 v[156:159], v145, s[52:53] offset:512
	global_load_dwordx4 v[160:163], v145, s[52:53] offset:576
	global_load_dwordx4 v[164:167], v216, s[52:53]
	global_load_dwordx4 v[168:171], v216, s[52:53] offset:64
	global_load_dwordx4 v[172:175], v216, s[52:53] offset:512
	global_load_dwordx4 v[176:179], v216, s[52:53] offset:576
	global_load_dwordx4 v[180:183], v217, s[52:53]
	global_load_dwordx4 v[184:187], v217, s[52:53] offset:64
	global_load_dwordx4 v[188:191], v217, s[52:53] offset:512
	global_load_dwordx4 v[192:195], v217, s[52:53] offset:576
	global_load_dwordx4 v[196:199], v218, s[52:53]
	global_load_dwordx4 v[200:203], v218, s[52:53] offset:64
	global_load_dwordx4 v[204:207], v218, s[52:53] offset:512
	global_load_dwordx4 v[208:211], v218, s[52:53] offset:576
	global_load_dwordx4 v[212:215], v232, s[52:53]
	global_load_dwordx4 v[220:223], v232, s[52:53] offset:64
	global_load_dwordx4 v[224:227], v232, s[52:53] offset:512
	global_load_dwordx4 v[228:231], v232, s[52:53] offset:576
	global_load_dwordx4 v[236:239], v233, s[52:53]
	global_load_dwordx4 v[240:243], v233, s[52:53] offset:64
	global_load_dwordx4 v[244:247], v233, s[52:53] offset:512
	global_load_dwordx4 v[248:251], v233, s[52:53] offset:576
	v_pk_add_f32 v[124:125], v[124:125], 0 op_sel_hi:[1,0]
	v_pk_add_f32 v[126:127], v[126:127], 0 op_sel_hi:[1,0]
	v_pk_add_f32 v[120:121], v[120:121], 0 op_sel_hi:[1,0]
	v_pk_add_f32 v[122:123], v[122:123], 0 op_sel_hi:[1,0]
	v_pk_add_f32 v[116:117], v[116:117], 0 op_sel_hi:[1,0]
	v_pk_add_f32 v[118:119], v[118:119], 0 op_sel_hi:[1,0]
	v_pk_add_f32 v[108:109], v[108:109], 0 op_sel_hi:[1,0]
	v_pk_add_f32 v[110:111], v[110:111], 0 op_sel_hi:[1,0]
	v_pk_add_f32 v[112:113], v[112:113], 0 op_sel_hi:[1,0]
	v_pk_add_f32 v[114:115], v[114:115], 0 op_sel_hi:[1,0]
	v_pk_add_f32 v[104:105], v[104:105], 0 op_sel_hi:[1,0]
	v_pk_add_f32 v[106:107], v[106:107], 0 op_sel_hi:[1,0]
	v_pk_add_f32 v[100:101], v[100:101], 0 op_sel_hi:[1,0]
	v_pk_add_f32 v[102:103], v[102:103], 0 op_sel_hi:[1,0]
	v_pk_add_f32 v[96:97], v[96:97], 0 op_sel_hi:[1,0]
	v_pk_add_f32 v[98:99], v[98:99], 0 op_sel_hi:[1,0]
	v_pk_add_f32 v[92:93], v[92:93], 0 op_sel_hi:[1,0]
	v_pk_add_f32 v[94:95], v[94:95], 0 op_sel_hi:[1,0]
	v_pk_add_f32 v[88:89], v[88:89], 0 op_sel_hi:[1,0]
	v_pk_add_f32 v[90:91], v[90:91], 0 op_sel_hi:[1,0]
	v_pk_add_f32 v[84:85], v[84:85], 0 op_sel_hi:[1,0]
	v_pk_add_f32 v[86:87], v[86:87], 0 op_sel_hi:[1,0]
	v_pk_add_f32 v[76:77], v[76:77], 0 op_sel_hi:[1,0]
	v_pk_add_f32 v[78:79], v[78:79], 0 op_sel_hi:[1,0]
	v_pk_add_f32 v[80:81], v[80:81], 0 op_sel_hi:[1,0]
	v_pk_add_f32 v[82:83], v[82:83], 0 op_sel_hi:[1,0]
	v_pk_add_f32 v[72:73], v[72:73], 0 op_sel_hi:[1,0]
	v_pk_add_f32 v[74:75], v[74:75], 0 op_sel_hi:[1,0]
	v_pk_add_f32 v[68:69], v[68:69], 0 op_sel_hi:[1,0]
	v_pk_add_f32 v[70:71], v[70:71], 0 op_sel_hi:[1,0]
	v_pk_add_f32 v[64:65], v[64:65], 0 op_sel_hi:[1,0]
	v_pk_add_f32 v[66:67], v[66:67], 0 op_sel_hi:[1,0]
	v_pk_add_f32 v[60:61], v[60:61], 0 op_sel_hi:[1,0]
	v_pk_add_f32 v[62:63], v[62:63], 0 op_sel_hi:[1,0]
	v_pk_add_f32 v[56:57], v[56:57], 0 op_sel_hi:[1,0]
	v_pk_add_f32 v[58:59], v[58:59], 0 op_sel_hi:[1,0]
	v_pk_add_f32 v[52:53], v[52:53], 0 op_sel_hi:[1,0]
	v_pk_add_f32 v[54:55], v[54:55], 0 op_sel_hi:[1,0]
	v_pk_add_f32 v[44:45], v[44:45], 0 op_sel_hi:[1,0]
	v_pk_add_f32 v[46:47], v[46:47], 0 op_sel_hi:[1,0]
	v_pk_add_f32 v[48:49], v[48:49], 0 op_sel_hi:[1,0]
	v_pk_add_f32 v[50:51], v[50:51], 0 op_sel_hi:[1,0]
	v_pk_add_f32 v[40:41], v[40:41], 0 op_sel_hi:[1,0]
	v_pk_add_f32 v[42:43], v[42:43], 0 op_sel_hi:[1,0]
	v_pk_add_f32 v[36:37], v[36:37], 0 op_sel_hi:[1,0]
	v_pk_add_f32 v[38:39], v[38:39], 0 op_sel_hi:[1,0]
	v_pk_add_f32 v[32:33], v[32:33], 0 op_sel_hi:[1,0]
	v_pk_add_f32 v[34:35], v[34:35], 0 op_sel_hi:[1,0]
	v_pk_add_f32 v[28:29], v[28:29], 0 op_sel_hi:[1,0]
	v_pk_add_f32 v[30:31], v[30:31], 0 op_sel_hi:[1,0]
	v_pk_add_f32 v[24:25], v[24:25], 0 op_sel_hi:[1,0]
	v_pk_add_f32 v[26:27], v[26:27], 0 op_sel_hi:[1,0]
	v_pk_add_f32 v[20:21], v[20:21], 0 op_sel_hi:[1,0]
	v_pk_add_f32 v[22:23], v[22:23], 0 op_sel_hi:[1,0]
	v_pk_add_f32 v[12:13], v[12:13], 0 op_sel_hi:[1,0]
	v_pk_add_f32 v[14:15], v[14:15], 0 op_sel_hi:[1,0]
	v_pk_add_f32 v[16:17], v[16:17], 0 op_sel_hi:[1,0]
	v_pk_add_f32 v[18:19], v[18:19], 0 op_sel_hi:[1,0]
	v_pk_add_f32 v[8:9], v[8:9], 0 op_sel_hi:[1,0]
	v_pk_add_f32 v[10:11], v[10:11], 0 op_sel_hi:[1,0]
	v_pk_add_f32 v[4:5], v[4:5], 0 op_sel_hi:[1,0]
	v_pk_add_f32 v[6:7], v[6:7], 0 op_sel_hi:[1,0]
	v_pk_add_f32 v[0:1], v[0:1], 0 op_sel_hi:[1,0]
	v_pk_add_f32 v[2:3], v[2:3], 0 op_sel_hi:[1,0]
	s_waitcnt vmcnt(16)
;     __device__ __forceinline__ void operator()(AccRef acc, const Unit& u, int wr, int wc, int fr, int fq) const {
;     ...
;                         for (int n = 0; n < 2; ++n) bs[m][bj][n] = *(const f32x4*)(base + (size_t)(row0 + ai * 128 + (2 * mh + m) * 16) * D + col0 + bj * 128 + n * 16);
; #pragma unroll
;                 for (int m = 0; m < 2; ++m)
; #pragma unroll
;                     for (int bj = 0; bj < 2; ++bj)
; #pragma unroll
;                         for (int n = 0; n < 2; ++n) *(f32x4*)(out + (size_t)(row0 + ai * 128 + (2 * mh + m) * 16) * D + col0 + bj * 128 + n * 16) = bs[m][bj][n] + sv[bj][n] * (acc[ai][bj][2 * mh + m][n] + bv[bj][n]);
;                 asm volatile("" ::: "memory"); }
	v_pk_add_f32 v[124:125], v[124:125], v[140:141]
	v_pk_add_f32 v[126:127], v[126:127], v[142:143]
	v_pk_add_f32 v[120:121], v[120:121], v[152:153]
	v_pk_add_f32 v[122:123], v[122:123], v[154:155]
	v_pk_add_f32 v[116:117], v[116:117], v[156:157]
	v_pk_add_f32 v[118:119], v[118:119], v[158:159]
	v_pk_add_f32 v[108:109], v[108:109], v[160:161]
	v_pk_add_f32 v[110:111], v[110:111], v[162:163]
	v_pk_add_f32 v[112:113], v[112:113], v[164:165]
	v_pk_add_f32 v[114:115], v[114:115], v[166:167]
	v_pk_add_f32 v[104:105], v[104:105], v[168:169]
	v_pk_add_f32 v[106:107], v[106:107], v[170:171]
	v_pk_add_f32 v[100:101], v[100:101], v[172:173]
	v_pk_add_f32 v[102:103], v[102:103], v[174:175]
	v_pk_add_f32 v[96:97], v[96:97], v[176:177]
	v_pk_add_f32 v[98:99], v[98:99], v[178:179]
	global_store_dwordx4 v145, v[124:127], s[52:53]
	global_store_dwordx4 v145, v[120:123], s[52:53] offset:64
	global_store_dwordx4 v145, v[116:119], s[52:53] offset:512
	global_store_dwordx4 v145, v[108:111], s[52:53] offset:576
	global_store_dwordx4 v216, v[112:115], s[52:53]
	global_store_dwordx4 v216, v[104:107], s[52:53] offset:64
	global_store_dwordx4 v216, v[100:103], s[52:53] offset:512
	global_store_dwordx4 v216, v[96:99], s[52:53] offset:576
	global_load_dwordx4 v[140:143], v235, s[52:53]
	global_load_dwordx4 v[152:155], v235, s[52:53] offset:64
	global_load_dwordx4 v[156:159], v235, s[52:53] offset:512
	global_load_dwordx4 v[160:163], v235, s[52:53] offset:576
	global_load_dwordx4 v[164:167], v253, s[52:53]
	global_load_dwordx4 v[168:171], v253, s[52:53] offset:64
	global_load_dwordx4 v[172:175], v253, s[52:53] offset:512
	global_load_dwordx4 v[176:179], v253, s[52:53] offset:576
	s_waitcnt vmcnt(24)
	v_pk_add_f32 v[92:93], v[92:93], v[180:181]
	v_pk_add_f32 v[94:95], v[94:95], v[182:183]
	v_pk_add_f32 v[88:89], v[88:89], v[184:185]
	v_pk_add_f32 v[90:91], v[90:91], v[186:187]
	v_pk_add_f32 v[84:85], v[84:85], v[188:189]
	v_pk_add_f32 v[86:87], v[86:87], v[190:191]
	v_pk_add_f32 v[76:77], v[76:77], v[192:193]
	v_pk_add_f32 v[78:79], v[78:79], v[194:195]
	v_pk_add_f32 v[80:81], v[80:81], v[196:197]
	v_pk_add_f32 v[82:83], v[82:83], v[198:199]
	v_pk_add_f32 v[72:73], v[72:73], v[200:201]
	v_pk_add_f32 v[74:75], v[74:75], v[202:203]
	v_pk_add_f32 v[68:69], v[68:69], v[204:205]
	v_pk_add_f32 v[70:71], v[70:71], v[206:207]
	v_pk_add_f32 v[64:65], v[64:65], v[208:209]
	v_pk_add_f32 v[66:67], v[66:67], v[210:211]
	global_store_dwordx4 v217, v[92:95], s[52:53]
	global_store_dwordx4 v217, v[88:91], s[52:53] offset:64
	global_store_dwordx4 v217, v[84:87], s[52:53] offset:512
	global_store_dwordx4 v217, v[76:79], s[52:53] offset:576
	global_store_dwordx4 v218, v[80:83], s[52:53]
	global_store_dwordx4 v218, v[72:75], s[52:53] offset:64
	global_store_dwordx4 v218, v[68:71], s[52:53] offset:512
	global_store_dwordx4 v218, v[64:67], s[52:53] offset:576
	s_waitcnt vmcnt(24)
	v_pk_add_f32 v[60:61], v[60:61], v[212:213]
	v_pk_add_f32 v[62:63], v[62:63], v[214:215]
	v_pk_add_f32 v[56:57], v[56:57], v[220:221]
	v_pk_add_f32 v[58:59], v[58:59], v[222:223]
	v_pk_add_f32 v[52:53], v[52:53], v[224:225]
	v_pk_add_f32 v[54:55], v[54:55], v[226:227]
	v_pk_add_f32 v[44:45], v[44:45], v[228:229]
	v_pk_add_f32 v[46:47], v[46:47], v[230:231]
	v_pk_add_f32 v[48:49], v[48:49], v[236:237]
	v_pk_add_f32 v[50:51], v[50:51], v[238:239]
	v_pk_add_f32 v[40:41], v[40:41], v[240:241]
	v_pk_add_f32 v[42:43], v[42:43], v[242:243]
	v_pk_add_f32 v[36:37], v[36:37], v[244:245]
	v_pk_add_f32 v[38:39], v[38:39], v[246:247]
	v_pk_add_f32 v[32:33], v[32:33], v[248:249]
	v_pk_add_f32 v[34:35], v[34:35], v[250:251]
	global_store_dwordx4 v232, v[60:63], s[52:53]
	global_store_dwordx4 v232, v[56:59], s[52:53] offset:64
	global_store_dwordx4 v232, v[52:55], s[52:53] offset:512
	global_store_dwordx4 v232, v[44:47], s[52:53] offset:576
	global_store_dwordx4 v233, v[48:51], s[52:53]
	global_store_dwordx4 v233, v[40:43], s[52:53] offset:64
	global_store_dwordx4 v233, v[36:39], s[52:53] offset:512
	global_store_dwordx4 v233, v[32:35], s[52:53] offset:576
	s_waitcnt vmcnt(16)
	v_pk_add_f32 v[28:29], v[28:29], v[140:141]
	v_pk_add_f32 v[30:31], v[30:31], v[142:143]
	v_pk_add_f32 v[24:25], v[24:25], v[152:153]
	v_pk_add_f32 v[26:27], v[26:27], v[154:155]
	v_pk_add_f32 v[20:21], v[20:21], v[156:157]
	v_pk_add_f32 v[22:23], v[22:23], v[158:159]
	v_pk_add_f32 v[12:13], v[12:13], v[160:161]
	v_pk_add_f32 v[14:15], v[14:15], v[162:163]
	v_pk_add_f32 v[16:17], v[16:17], v[164:165]
	v_pk_add_f32 v[18:19], v[18:19], v[166:167]
	v_pk_add_f32 v[8:9], v[8:9], v[168:169]
	v_pk_add_f32 v[10:11], v[10:11], v[170:171]
	v_pk_add_f32 v[4:5], v[4:5], v[172:173]
	v_pk_add_f32 v[6:7], v[6:7], v[174:175]
	v_pk_add_f32 v[0:1], v[0:1], v[176:177]
	v_pk_add_f32 v[2:3], v[2:3], v[178:179]
	global_store_dwordx4 v235, v[28:31], s[52:53]
	global_store_dwordx4 v235, v[24:27], s[52:53] offset:64
	global_store_dwordx4 v235, v[20:23], s[52:53] offset:512
	global_store_dwordx4 v235, v[12:15], s[52:53] offset:576
	global_store_dwordx4 v253, v[16:19], s[52:53]
	global_store_dwordx4 v253, v[8:11], s[52:53] offset:64
	global_store_dwordx4 v253, v[4:7], s[52:53] offset:512
	global_store_dwordx4 v253, v[0:3], s[52:53] offset:576
	s_cbranch_vccz .LBB0_849
	s_waitcnt vmcnt(0)
	s_cmpk_gt_u32 s4, 0xff
	s_cbranch_scc1 .LBB0_864
	s_barrier

; #define PG8_STAGE(bufoff, gbase, voff) do { _Pragma("unroll") for (int _i = 0; _i < 2; ++_i) \
;         __builtin_amdgcn_global_load_lds((const unsigned*)((const char*)(gbase) + (voff)[_i]), (LAS unsigned*)(lds + (bufoff) + ldsw + _i * 8192), 16, 0, 0); } while (0)
; #define PG8_LDA(dst, b, h) do { _Pragma("unroll") for (int m = 0; m < 4; ++m) _Pragma("unroll") for (int k = 0; k < 2; ++k) dst[m][k] = *(const LAS bf16x8*)(lds + PG8_SA(b, h) + aoff + m * 2048 + k * 1024); } while (0)
; #define PG8_LDB(dst, b, h) do { _Pragma("unroll") for (int n = 0; n < 2; ++n) _Pragma("unroll") for (int k = 0; k < 2; ++k) dst[n][k] = *(const LAS bf16x8*)(lds + PG8_SB(b, h) + boff + n * 2048 + k * 1024); } while (0)
; #define PG8_WAIT_V(n) asm volatile("s_waitcnt vmcnt(" #n ")" ::: "memory")
; #define PG8_WAIT_L(n) asm volatile("s_waitcnt lgkmcnt(" #n ")" ::: "memory")
; #define PG8_BAR __builtin_amdgcn_s_barrier()
; #define PG8_SCHED __builtin_amdgcn_sched_barrier(0)
; template <class Epi>
; __device__ __forceinline__ void gemm_phase(LAS unsigned char* lds, const Gemm g, const StaticOrder& S, const Epi& E) {
;     ...
;         const bool has_next = S.next(ui + 1, nxt);
;         const char* nA = has_next ? (const char*)g.A + (size_t)nxt.pm * tstepA + (size_t)(nxt.pn >> g.a_shift) * g.a_step : cA; const char* nB = has_next ? (const char*)g.Bt + (size_t)nxt.pn * tstepB : cB;
;         for (int t = 0; t < nt; t += 2) {
;             const bool last = (t == nt - 2);
;             const char* a1 = cA + (size_t)(t + 1) * kstep;
;             const char* a2 = last ? nA : cA + (size_t)(t + 2) * kstep; const char* b2 = last ? nB : cB + (size_t)(t + 2) * kstep;
;             const char* a3 = a2 + kstep; const char* b3 = b2 + kstep;
;             PG8_LDB(B0, 0, 0); PG8_SCHED; PG8_LDA(At, 0, 0); PG8_STAGE(PG8_SA(1, 1), a1 + hstepA, voffA);
;             PG8_WAIT_L(8); PG8_BAR; PG8_WAIT_L(0); PG8_MMA(0, 0, At, B0); PG8_BAR; PG8_SCHED;
;             PG8_LDB(B1, 0, 1); PG8_STAGE(PG8_SB(0, 0), b2, voffB);
;             PG8_BAR; PG8_WAIT_L(0); PG8_MMA(0, 1, At, B1); PG8_BAR;
;             PG8_LDA(At, 0, 1); PG8_STAGE(PG8_SA(0, 0), a2, voffA);
;             PG8_BAR; PG8_WAIT_L(0); PG8_MMA(1, 0, At, B0); PG8_BAR; PG8_SCHED;
;             PG8_STAGE(PG8_SB(0, 1), b2 + hstepB, voffB);
;             PG8_WAIT_V(6); PG8_BAR; PG8_MMA(1, 1, At, B1); PG8_BAR;
.LBB0_989:
	s_ashr_i32 s71, s70, 31
	s_lshl_b64 s[10:11], s[70:71], 19
	v_cmp_lt_i64_e32 vcc, s[72:73], v[178:179]
	s_add_u32 s72, s66, s10
	s_addc_u32 s73, s67, s11
	s_and_b64 s[10:11], vcc, exec
	s_cselect_b32 s71, s73, s81
	s_cselect_b32 s77, s72, s80
	s_ashr_i32 s69, s68, 31
	s_lshl_b64 s[10:11], s[68:69], 19
	s_add_u32 s74, s88, s10
	s_addc_u32 s75, s89, s11
	s_and_b64 s[10:11], vcc, exec
	s_cselect_b32 s69, s75, s83
	s_cselect_b32 s79, s74, s82
	s_add_u32 vcc_lo, s82, 0x100
	s_addc_u32 vcc_hi, s83, 0
	s_mov_b32 s10, -2
	ds_read_b128 v[128:131], v214
	ds_read_b128 v[132:135], v214 offset:1024
	ds_read_b128 v[136:139], v214 offset:2048
	ds_read_b128 v[140:143], v214 offset:3072
	s_add_u32 s82, s80, 0x100
	s_addc_u32 s83, s81, 0
	s_cmp_eq_u32 s10, 12
	s_cselect_b32 s87, s71, s83
	s_cselect_b32 s86, s77, s82
	s_cselect_b32 s85, s69, vcc_hi
	s_cselect_b32 s84, s79, vcc_lo
	s_add_i32 m0, s91, 0xc000
	ds_read_b128 v[144:147], v215
	ds_read_b128 v[148:151], v215 offset:1024
	ds_read_b128 v[152:155], v215 offset:2048
	ds_read_b128 v[156:159], v215 offset:3072
	ds_read_b128 v[182:185], v215 offset:4096
	ds_read_b128 v[186:189], v215 offset:5120
	ds_read_b128 v[190:193], v215 offset:6144
	ds_read_b128 v[194:197], v215 offset:7168
	global_load_lds_dwordx4 v174, s[80:81]
	s_add_i32 m0, s91, 0xe000
	s_nop 0
	global_load_lds_dwordx4 v176, s[80:81]
	ds_read_b128 v[198:201], v216
	ds_read_b128 v[220:223], v216 offset:1024
	ds_read_b128 v[224:227], v216 offset:2048
	ds_read_b128 v[228:231], v216 offset:3072
	s_waitcnt lgkmcnt(0)
	s_barrier
	s_setprio 1
	v_mfma_f32_16x16x32_bf16 v[124:127], v[128:131], v[144:147], 0
	v_mfma_f32_16x16x32_bf16 v[120:123], v[136:139], v[144:147], 0
	v_mfma_f32_16x16x32_bf16 v[108:111], v[128:131], v[152:155], 0
	v_mfma_f32_16x16x32_bf16 v[104:107], v[136:139], v[152:155], 0
	v_mfma_f32_16x16x32_bf16 v[92:95], v[128:131], v[182:185], 0
	v_mfma_f32_16x16x32_bf16 v[88:91], v[136:139], v[182:185], 0
	v_mfma_f32_16x16x32_bf16 v[76:79], v[128:131], v[190:193], 0
	v_mfma_f32_16x16x32_bf16 v[72:75], v[136:139], v[190:193], 0
	v_mfma_f32_16x16x32_bf16 v[124:127], v[132:135], v[148:151], v[124:127]
	v_mfma_f32_16x16x32_bf16 v[120:123], v[140:143], v[148:151], v[120:123]
	v_mfma_f32_16x16x32_bf16 v[108:111], v[132:135], v[156:159], v[108:111]
	v_mfma_f32_16x16x32_bf16 v[104:107], v[140:143], v[156:159], v[104:107]
	v_mfma_f32_16x16x32_bf16 v[92:95], v[132:135], v[186:189], v[92:95]
	v_mfma_f32_16x16x32_bf16 v[88:91], v[140:143], v[186:189], v[88:91]
	v_mfma_f32_16x16x32_bf16 v[76:79], v[132:135], v[194:197], v[76:79]
	v_mfma_f32_16x16x32_bf16 v[72:75], v[140:143], v[194:197], v[72:75]
	v_mfma_f32_16x16x32_bf16 v[116:119], v[198:201], v[144:147], 0
	v_mfma_f32_16x16x32_bf16 v[112:115], v[224:227], v[144:147], 0
	v_mfma_f32_16x16x32_bf16 v[100:103], v[198:201], v[152:155], 0
	v_mfma_f32_16x16x32_bf16 v[96:99], v[224:227], v[152:155], 0
	v_mfma_f32_16x16x32_bf16 v[84:87], v[198:201], v[182:185], 0
	v_mfma_f32_16x16x32_bf16 v[80:83], v[224:227], v[182:185], 0
	v_mfma_f32_16x16x32_bf16 v[68:71], v[198:201], v[190:193], 0
	v_mfma_f32_16x16x32_bf16 v[64:67], v[224:227], v[190:193], 0
	v_mfma_f32_16x16x32_bf16 v[116:119], v[220:223], v[148:151], v[116:119]
	v_mfma_f32_16x16x32_bf16 v[112:115], v[228:231], v[148:151], v[112:115]
	v_mfma_f32_16x16x32_bf16 v[100:103], v[220:223], v[156:159], v[100:103]
	v_mfma_f32_16x16x32_bf16 v[96:99], v[228:231], v[156:159], v[96:99]
	v_mfma_f32_16x16x32_bf16 v[84:87], v[220:223], v[186:189], v[84:87]
	v_mfma_f32_16x16x32_bf16 v[80:83], v[228:231], v[186:189], v[80:83]
	v_mfma_f32_16x16x32_bf16 v[68:71], v[220:223], v[194:197], v[68:71]
	v_mfma_f32_16x16x32_bf16 v[64:67], v[228:231], v[194:197], v[64:67]
	s_setprio 0
	s_barrier
	s_nop 1
	ds_read_b128 v[144:147], v215 offset:16384
	ds_read_b128 v[148:151], v215 offset:17408
	ds_read_b128 v[152:155], v215 offset:18432
	ds_read_b128 v[156:159], v215 offset:19456
	ds_read_b128 v[182:185], v215 offset:20480
	ds_read_b128 v[186:189], v215 offset:21504
	ds_read_b128 v[190:193], v215 offset:22528
	ds_read_b128 v[194:197], v215 offset:23552
	s_add_i32 s11, s93, s90
	v_lshl_add_u64 v[160:161], s[84:85], 0, v[164:165]
	s_mov_b32 m0, s11
	s_nop 0
	global_load_lds_dwordx4 v164, s[84:85]
	v_lshl_add_u64 v[202:203], s[84:85], 0, v[168:169]
	s_add_i32 m0, s11, 0x2000
	s_nop 0
	global_load_lds_dwordx4 v168, s[84:85]
	s_mov_b32 m0, s91
	v_lshl_add_u64 v[232:233], s[86:87], 0, v[162:163]
	global_load_lds_dwordx4 v162, s[86:87]
	v_lshl_add_u64 v[236:237], s[86:87], 0, v[166:167]
	s_mov_b32 m0, s97
	s_nop 0
	global_load_lds_dwordx4 v166, s[86:87]
	s_add_u32 s80, s84, 0x40000
	s_addc_u32 s81, s85, 0
	s_add_i32 s11, s96, s90
	s_mov_b32 m0, s11
	s_nop 0
	global_load_lds_dwordx4 v164, s[80:81]
	s_add_i32 m0, s11, 0x2000
	s_nop 0
	global_load_lds_dwordx4 v168, s[80:81]
	s_waitcnt vmcnt(6)
	s_waitcnt lgkmcnt(0)
	s_barrier
; #define PG8_STAGE(bufoff, gbase, voff) do { _Pragma("unroll") for (int _i = 0; _i < 2; ++_i) \
;         __builtin_amdgcn_global_load_lds((const unsigned*)((const char*)(gbase) + (voff)[_i]), (LAS unsigned*)(lds + (bufoff) + ldsw + _i * 8192), 16, 0, 0); } while (0)
; #define PG8_LDA(dst, b, h) do { _Pragma("unroll") for (int m = 0; m < 4; ++m) _Pragma("unroll") for (int k = 0; k < 2; ++k) dst[m][k] = *(const LAS bf16x8*)(lds + PG8_SA(b, h) + aoff + m * 2048 + k * 1024); } while (0)
; #define PG8_LDB(dst, b, h) do { _Pragma("unroll") for (int n = 0; n < 2; ++n) _Pragma("unroll") for (int k = 0; k < 2; ++k) dst[n][k] = *(const LAS bf16x8*)(lds + PG8_SB(b, h) + boff + n * 2048 + k * 1024); } while (0)
; #define PG8_MMA(ai, bj, At, Bt) do { __builtin_amdgcn_s_setprio(1); _Pragma("unroll") for (int m = 0; m < 4; ++m) _Pragma("unroll") for (int n = 0; n < 2; ++n) _Pragma("unroll") for (int k = 0; k < 2; ++k) \
;         acc[ai][bj][m][n] = __builtin_amdgcn_mfma_f32_16x16x32_bf16(Bt[n][k], At[m][k], acc[ai][bj][m][n], 0, 0, 0); __builtin_amdgcn_s_setprio(0); } while (0)
; #define PG8_WAIT_V(n) asm volatile("s_waitcnt vmcnt(" #n ")" ::: "memory")
; #define PG8_WAIT_L(n) asm volatile("s_waitcnt lgkmcnt(" #n ")" ::: "memory")
; #define PG8_BAR __builtin_amdgcn_s_barrier()
; #define PG8_SCHED __builtin_amdgcn_sched_barrier(0)
; template <class Epi>
; __device__ __forceinline__ void gemm_phase(LAS unsigned char* lds, const Gemm g, const StaticOrder& S, const Epi& E) {
;     ...
;             PG8_WAIT_V(6); PG8_BAR; PG8_MMA(1, 1, At, B1); PG8_BAR;
;             PG8_LDB(B0, 1, 0); PG8_SCHED; PG8_LDA(At, 1, 0); PG8_STAGE(PG8_SA(0, 1), a2 + hstepA, voffA);
;             PG8_WAIT_L(8); PG8_BAR; PG8_WAIT_L(0); PG8_MMA(0, 0, At, B0); PG8_BAR; PG8_SCHED;
;             PG8_LDB(B1, 1, 1); PG8_STAGE(PG8_SB(1, 0), b3, voffB);
;             PG8_BAR; PG8_WAIT_L(0); PG8_MMA(0, 1, At, B1); PG8_BAR;
	s_setprio 1
	v_mfma_f32_16x16x32_bf16 v[60:63], v[128:131], v[144:147], 0
	v_mfma_f32_16x16x32_bf16 v[56:59], v[136:139], v[144:147], 0
	v_mfma_f32_16x16x32_bf16 v[44:47], v[128:131], v[152:155], 0
	v_mfma_f32_16x16x32_bf16 v[40:43], v[136:139], v[152:155], 0
	v_mfma_f32_16x16x32_bf16 v[28:31], v[128:131], v[182:185], 0
	v_mfma_f32_16x16x32_bf16 v[24:27], v[136:139], v[182:185], 0
	v_mfma_f32_16x16x32_bf16 v[12:15], v[128:131], v[190:193], 0
	v_mfma_f32_16x16x32_bf16 v[8:11], v[136:139], v[190:193], 0
	v_mfma_f32_16x16x32_bf16 v[60:63], v[132:135], v[148:151], v[60:63]
	v_mfma_f32_16x16x32_bf16 v[56:59], v[140:143], v[148:151], v[56:59]
	v_mfma_f32_16x16x32_bf16 v[44:47], v[132:135], v[156:159], v[44:47]
	v_mfma_f32_16x16x32_bf16 v[40:43], v[140:143], v[156:159], v[40:43]
	v_mfma_f32_16x16x32_bf16 v[28:31], v[132:135], v[186:189], v[28:31]
	v_mfma_f32_16x16x32_bf16 v[24:27], v[140:143], v[186:189], v[24:27]
	v_mfma_f32_16x16x32_bf16 v[12:15], v[132:135], v[194:197], v[12:15]
	v_mfma_f32_16x16x32_bf16 v[8:11], v[140:143], v[194:197], v[8:11]
	v_mfma_f32_16x16x32_bf16 v[52:55], v[198:201], v[144:147], 0
	v_mfma_f32_16x16x32_bf16 v[48:51], v[224:227], v[144:147], 0
	v_mfma_f32_16x16x32_bf16 v[36:39], v[198:201], v[152:155], 0
	v_mfma_f32_16x16x32_bf16 v[32:35], v[224:227], v[152:155], 0
	v_mfma_f32_16x16x32_bf16 v[20:23], v[198:201], v[182:185], 0
	v_mfma_f32_16x16x32_bf16 v[16:19], v[224:227], v[182:185], 0
	v_mfma_f32_16x16x32_bf16 v[4:7], v[198:201], v[190:193], 0
	v_mfma_f32_16x16x32_bf16 v[0:3], v[224:227], v[190:193], 0
	v_mfma_f32_16x16x32_bf16 v[52:55], v[220:223], v[148:151], v[52:55]
	v_mfma_f32_16x16x32_bf16 v[48:51], v[228:231], v[148:151], v[48:51]
	v_mfma_f32_16x16x32_bf16 v[36:39], v[220:223], v[156:159], v[36:39]
	v_mfma_f32_16x16x32_bf16 v[32:35], v[228:231], v[156:159], v[32:35]
	v_mfma_f32_16x16x32_bf16 v[20:23], v[220:223], v[186:189], v[20:23]
	v_mfma_f32_16x16x32_bf16 v[16:19], v[228:231], v[186:189], v[16:19]
	v_mfma_f32_16x16x32_bf16 v[4:7], v[220:223], v[194:197], v[4:7]
	v_mfma_f32_16x16x32_bf16 v[0:3], v[228:231], v[194:197], v[0:3]
	s_setprio 0
	s_add_i32 s11, 0, 0x18000
	v_add_u32_e32 v140, s11, v173
	s_barrier
	ds_read_b128 v[128:131], v140
	ds_read_b128 v[132:135], v140 offset:1024
	ds_read_b128 v[136:139], v140 offset:2048
	ds_read_b128 v[140:143], v140 offset:3072
	s_add_u32 s80, s86, 0x40000
	s_addc_u32 s81, s87, 0
	s_mov_b32 m0, s8
	ds_read_b128 v[144:147], v215 offset:32768
	ds_read_b128 v[148:151], v215 offset:33792
	ds_read_b128 v[152:155], v215 offset:34816
	ds_read_b128 v[156:159], v215 offset:35840
	ds_read_b128 v[182:185], v215 offset:36864
	ds_read_b128 v[186:189], v215 offset:37888
	ds_read_b128 v[190:193], v215 offset:38912
	ds_read_b128 v[194:197], v215 offset:39936
	global_load_lds_dwordx4 v162, s[80:81]
	s_mov_b32 m0, s9
	s_nop 0
	global_load_lds_dwordx4 v166, s[80:81]
	s_add_i32 s86, 0, 0x1c000
	v_add_u32_e32 v170, s86, v173
	ds_read_b128 v[198:201], v170
	ds_read_b128 v[220:223], v170 offset:1024
	ds_read_b128 v[224:227], v170 offset:2048
	ds_read_b128 v[228:231], v170 offset:3072
	s_waitcnt lgkmcnt(0)
	s_barrier
	s_setprio 1
	v_mfma_f32_16x16x32_bf16 v[124:127], v[128:131], v[144:147], v[124:127]
	v_mfma_f32_16x16x32_bf16 v[120:123], v[136:139], v[144:147], v[120:123]
	v_mfma_f32_16x16x32_bf16 v[108:111], v[128:131], v[152:155], v[108:111]
	v_mfma_f32_16x16x32_bf16 v[104:107], v[136:139], v[152:155], v[104:107]
	v_mfma_f32_16x16x32_bf16 v[92:95], v[128:131], v[182:185], v[92:95]
	v_mfma_f32_16x16x32_bf16 v[88:91], v[136:139], v[182:185], v[88:91]
	v_mfma_f32_16x16x32_bf16 v[76:79], v[128:131], v[190:193], v[76:79]
	v_mfma_f32_16x16x32_bf16 v[72:75], v[136:139], v[190:193], v[72:75]
	v_mfma_f32_16x16x32_bf16 v[124:127], v[132:135], v[148:151], v[124:127]
	v_mfma_f32_16x16x32_bf16 v[120:123], v[140:143], v[148:151], v[120:123]
	v_mfma_f32_16x16x32_bf16 v[108:111], v[132:135], v[156:159], v[108:111]
	v_mfma_f32_16x16x32_bf16 v[104:107], v[140:143], v[156:159], v[104:107]
	v_mfma_f32_16x16x32_bf16 v[92:95], v[132:135], v[186:189], v[92:95]
	v_mfma_f32_16x16x32_bf16 v[88:91], v[140:143], v[186:189], v[88:91]
	v_mfma_f32_16x16x32_bf16 v[76:79], v[132:135], v[194:197], v[76:79]
	v_mfma_f32_16x16x32_bf16 v[72:75], v[140:143], v[194:197], v[72:75]
	v_mfma_f32_16x16x32_bf16 v[116:119], v[198:201], v[144:147], v[116:119]
	v_mfma_f32_16x16x32_bf16 v[112:115], v[224:227], v[144:147], v[112:115]
	v_mfma_f32_16x16x32_bf16 v[100:103], v[198:201], v[152:155], v[100:103]
	v_mfma_f32_16x16x32_bf16 v[96:99], v[224:227], v[152:155], v[96:99]
	v_mfma_f32_16x16x32_bf16 v[84:87], v[198:201], v[182:185], v[84:87]
	v_mfma_f32_16x16x32_bf16 v[80:83], v[224:227], v[182:185], v[80:83]
	v_mfma_f32_16x16x32_bf16 v[68:71], v[198:201], v[190:193], v[68:71]
	v_mfma_f32_16x16x32_bf16 v[64:67], v[224:227], v[190:193], v[64:67]
	v_mfma_f32_16x16x32_bf16 v[116:119], v[220:223], v[148:151], v[116:119]
	v_mfma_f32_16x16x32_bf16 v[112:115], v[228:231], v[148:151], v[112:115]
	v_mfma_f32_16x16x32_bf16 v[100:103], v[220:223], v[156:159], v[100:103]
	v_mfma_f32_16x16x32_bf16 v[96:99], v[228:231], v[156:159], v[96:99]
	v_mfma_f32_16x16x32_bf16 v[84:87], v[220:223], v[186:189], v[84:87]
	v_mfma_f32_16x16x32_bf16 v[80:83], v[228:231], v[186:189], v[80:83]
	v_mfma_f32_16x16x32_bf16 v[68:71], v[220:223], v[194:197], v[68:71]
	v_mfma_f32_16x16x32_bf16 v[64:67], v[228:231], v[194:197], v[64:67]
	s_setprio 0
	s_barrier
; #define PG8_STAGE(bufoff, gbase, voff) do { _Pragma("unroll") for (int _i = 0; _i < 2; ++_i) \
;         __builtin_amdgcn_global_load_lds((const unsigned*)((const char*)(gbase) + (voff)[_i]), (LAS unsigned*)(lds + (bufoff) + ldsw + _i * 8192), 16, 0, 0); } while (0)
; #define PG8_LDA(dst, b, h) do { _Pragma("unroll") for (int m = 0; m < 4; ++m) _Pragma("unroll") for (int k = 0; k < 2; ++k) dst[m][k] = *(const LAS bf16x8*)(lds + PG8_SA(b, h) + aoff + m * 2048 + k * 1024); } while (0)
; #define PG8_LDB(dst, b, h) do { _Pragma("unroll") for (int n = 0; n < 2; ++n) _Pragma("unroll") for (int k = 0; k < 2; ++k) dst[n][k] = *(const LAS bf16x8*)(lds + PG8_SB(b, h) + boff + n * 2048 + k * 1024); } while (0)
; #define PG8_MMA(ai, bj, At, Bt) do { __builtin_amdgcn_s_setprio(1); _Pragma("unroll") for (int m = 0; m < 4; ++m) _Pragma("unroll") for (int n = 0; n < 2; ++n) _Pragma("unroll") for (int k = 0; k < 2; ++k) \
;         acc[ai][bj][m][n] = __builtin_amdgcn_mfma_f32_16x16x32_bf16(Bt[n][k], At[m][k], acc[ai][bj][m][n], 0, 0, 0); __builtin_amdgcn_s_setprio(0); } while (0)
; #define PG8_WAIT_V(n) asm volatile("s_waitcnt vmcnt(" #n ")" ::: "memory")
; #define PG8_WAIT_L(n) asm volatile("s_waitcnt lgkmcnt(" #n ")" ::: "memory")
; #define PG8_BAR __builtin_amdgcn_s_barrier()
; #define PG8_SCHED __builtin_amdgcn_sched_barrier(0)
; template <class Epi>
; __device__ __forceinline__ void gemm_phase(LAS unsigned char* lds, const Gemm g, const StaticOrder& S, const Epi& E) {
;     ...
;             PG8_LDB(B0, 0, 0); PG8_SCHED; PG8_LDA(At, 0, 0); PG8_STAGE(PG8_SA(1, 1), a1 + hstepA, voffA);
;             PG8_WAIT_L(8); PG8_BAR; PG8_WAIT_L(0); PG8_MMA(0, 0, At, B0); PG8_BAR; PG8_SCHED;
;             PG8_LDB(B1, 0, 1); PG8_STAGE(PG8_SB(0, 0), b2, voffB);
;             PG8_BAR; PG8_WAIT_L(0); PG8_MMA(0, 1, At, B1); PG8_BAR;
;             PG8_LDA(At, 0, 1); PG8_STAGE(PG8_SA(0, 0), a2, voffA);
;     ...
;             PG8_LDA(At, 1, 1); PG8_STAGE(PG8_SA(1, 0), a3, voffA);
;             PG8_BAR; PG8_WAIT_L(0); PG8_MMA(1, 0, At, B0); PG8_BAR; PG8_SCHED;
;             PG8_STAGE(PG8_SB(1, 1), b3 + hstepB, voffB);
;             PG8_WAIT_V(6); PG8_BAR; PG8_MMA(1, 1, At, B1); PG8_BAR;
	s_nop 1
	ds_read_b128 v[144:147], v215 offset:49152
	ds_read_b128 v[148:151], v215 offset:50176
	ds_read_b128 v[152:155], v215 offset:51200
	ds_read_b128 v[156:159], v215 offset:52224
	ds_read_b128 v[182:185], v215 offset:53248
	ds_read_b128 v[186:189], v215 offset:54272
	ds_read_b128 v[190:193], v215 offset:55296
	ds_read_b128 v[194:197], v215 offset:56320
	s_add_i32 s11, s11, s90
	s_mov_b32 m0, s11
	s_nop 0
	s_add_u32 s100, s84, s28
	s_addc_u32 s101, s85, s29
	global_load_lds_dwordx4 v164, s[100:101]
	s_add_i32 m0, s11, 0x2000
	s_nop 0
	s_add_u32 s100, s84, s28
	s_addc_u32 s101, s85, s29
	global_load_lds_dwordx4 v168, s[100:101]
	s_mov_b32 m0, s4
	v_lshl_add_u64 v[254:255], v[232:233], 0, s[28:29]
	global_load_lds_dwordx4 v[254:255], off
	v_lshl_add_u64 v[160:161], v[236:237], 0, s[28:29]
	s_mov_b32 m0, s5
	s_nop 0
	global_load_lds_dwordx4 v[160:161], off
	s_add_u32 s80, s84, 0x40080
	s_addc_u32 s81, s85, 0
	s_add_i32 s11, s86, s90
	s_mov_b32 m0, s11
	s_nop 0
	global_load_lds_dwordx4 v164, s[80:81]
	s_add_i32 m0, s11, 0x2000
	s_nop 0
	global_load_lds_dwordx4 v168, s[80:81]
	s_waitcnt vmcnt(6)
	s_waitcnt lgkmcnt(0)
	s_barrier
	s_setprio 1
	v_mfma_f32_16x16x32_bf16 v[60:63], v[128:131], v[144:147], v[60:63]
	v_mfma_f32_16x16x32_bf16 v[56:59], v[136:139], v[144:147], v[56:59]
	v_mfma_f32_16x16x32_bf16 v[44:47], v[128:131], v[152:155], v[44:47]
	v_mfma_f32_16x16x32_bf16 v[40:43], v[136:139], v[152:155], v[40:43]
	v_mfma_f32_16x16x32_bf16 v[28:31], v[128:131], v[182:185], v[28:31]
	v_mfma_f32_16x16x32_bf16 v[24:27], v[136:139], v[182:185], v[24:27]
	v_mfma_f32_16x16x32_bf16 v[12:15], v[128:131], v[190:193], v[12:15]
	v_mfma_f32_16x16x32_bf16 v[8:11], v[136:139], v[190:193], v[8:11]
	v_mfma_f32_16x16x32_bf16 v[60:63], v[132:135], v[148:151], v[60:63]
	v_mfma_f32_16x16x32_bf16 v[56:59], v[140:143], v[148:151], v[56:59]
	v_mfma_f32_16x16x32_bf16 v[44:47], v[132:135], v[156:159], v[44:47]
	v_mfma_f32_16x16x32_bf16 v[40:43], v[140:143], v[156:159], v[40:43]
	v_mfma_f32_16x16x32_bf16 v[28:31], v[132:135], v[186:189], v[28:31]
	v_mfma_f32_16x16x32_bf16 v[24:27], v[140:143], v[186:189], v[24:27]
	v_mfma_f32_16x16x32_bf16 v[12:15], v[132:135], v[194:197], v[12:15]
	v_mfma_f32_16x16x32_bf16 v[8:11], v[140:143], v[194:197], v[8:11]
	v_mfma_f32_16x16x32_bf16 v[52:55], v[198:201], v[144:147], v[52:55]
	v_mfma_f32_16x16x32_bf16 v[48:51], v[224:227], v[144:147], v[48:51]
	v_mfma_f32_16x16x32_bf16 v[36:39], v[198:201], v[152:155], v[36:39]
	v_mfma_f32_16x16x32_bf16 v[32:35], v[224:227], v[152:155], v[32:35]
	v_mfma_f32_16x16x32_bf16 v[20:23], v[198:201], v[182:185], v[20:23]
	v_mfma_f32_16x16x32_bf16 v[16:19], v[224:227], v[182:185], v[16:19]
	v_mfma_f32_16x16x32_bf16 v[4:7], v[198:201], v[190:193], v[4:7]
	v_mfma_f32_16x16x32_bf16 v[0:3], v[224:227], v[190:193], v[0:3]
	v_mfma_f32_16x16x32_bf16 v[52:55], v[220:223], v[148:151], v[52:55]
	v_mfma_f32_16x16x32_bf16 v[48:51], v[228:231], v[148:151], v[48:51]
	v_mfma_f32_16x16x32_bf16 v[36:39], v[220:223], v[156:159], v[36:39]
	v_mfma_f32_16x16x32_bf16 v[32:35], v[228:231], v[156:159], v[32:35]
	v_mfma_f32_16x16x32_bf16 v[20:23], v[220:223], v[186:189], v[20:23]
	v_mfma_f32_16x16x32_bf16 v[16:19], v[228:231], v[186:189], v[16:19]
	v_mfma_f32_16x16x32_bf16 v[4:7], v[220:223], v[194:197], v[4:7]
	v_mfma_f32_16x16x32_bf16 v[0:3], v[228:231], v[194:197], v[0:3]
	s_setprio 0
	s_add_i32 s10, s10, 2
	s_add_u32 vcc_lo, vcc_lo, 0x100
	s_addc_u32 vcc_hi, vcc_hi, 0
	s_cmp_gt_u32 s10, 13
	s_mov_b64 s[80:81], s[82:83]
	s_barrier
.LBB0_990:
	ds_read_b128 v[128:131], v214
	ds_read_b128 v[132:135], v214 offset:1024
	ds_read_b128 v[136:139], v214 offset:2048
	ds_read_b128 v[140:143], v214 offset:3072
	s_add_u32 s82, s80, 0x100
	s_addc_u32 s83, s81, 0
	s_cmp_eq_u32 s10, 12
	s_cselect_b32 s87, s71, s83
	s_cselect_b32 s86, s77, s82
	s_cselect_b32 s85, s69, vcc_hi
	s_cselect_b32 s84, s79, vcc_lo
	s_add_i32 m0, s91, 0xc000
	ds_read_b128 v[144:147], v215
	ds_read_b128 v[148:151], v215 offset:1024
	ds_read_b128 v[152:155], v215 offset:2048
	ds_read_b128 v[156:159], v215 offset:3072
	ds_read_b128 v[182:185], v215 offset:4096
	ds_read_b128 v[186:189], v215 offset:5120
	ds_read_b128 v[190:193], v215 offset:6144
	ds_read_b128 v[194:197], v215 offset:7168
	global_load_lds_dwordx4 v174, s[80:81]
	s_add_i32 m0, s91, 0xe000
	s_nop 0
	global_load_lds_dwordx4 v176, s[80:81]
	ds_read_b128 v[198:201], v216
	ds_read_b128 v[220:223], v216 offset:1024
	ds_read_b128 v[224:227], v216 offset:2048
	ds_read_b128 v[228:231], v216 offset:3072
	s_waitcnt lgkmcnt(0)
	s_barrier
; #define PG8_STAGE(bufoff, gbase, voff) do { _Pragma("unroll") for (int _i = 0; _i < 2; ++_i) \
;         __builtin_amdgcn_global_load_lds((const unsigned*)((const char*)(gbase) + (voff)[_i]), (LAS unsigned*)(lds + (bufoff) + ldsw + _i * 8192), 16, 0, 0); } while (0)
; #define PG8_LDA(dst, b, h) do { _Pragma("unroll") for (int m = 0; m < 4; ++m) _Pragma("unroll") for (int k = 0; k < 2; ++k) dst[m][k] = *(const LAS bf16x8*)(lds + PG8_SA(b, h) + aoff + m * 2048 + k * 1024); } while (0)
; #define PG8_LDB(dst, b, h) do { _Pragma("unroll") for (int n = 0; n < 2; ++n) _Pragma("unroll") for (int k = 0; k < 2; ++k) dst[n][k] = *(const LAS bf16x8*)(lds + PG8_SB(b, h) + boff + n * 2048 + k * 1024); } while (0)
; #define PG8_MMA(ai, bj, At, Bt) do { __builtin_amdgcn_s_setprio(1); _Pragma("unroll") for (int m = 0; m < 4; ++m) _Pragma("unroll") for (int n = 0; n < 2; ++n) _Pragma("unroll") for (int k = 0; k < 2; ++k) \
;         acc[ai][bj][m][n] = __builtin_amdgcn_mfma_f32_16x16x32_bf16(Bt[n][k], At[m][k], acc[ai][bj][m][n], 0, 0, 0); __builtin_amdgcn_s_setprio(0); } while (0)
; #define PG8_WAIT_V(n) asm volatile("s_waitcnt vmcnt(" #n ")" ::: "memory")
; #define PG8_WAIT_L(n) asm volatile("s_waitcnt lgkmcnt(" #n ")" ::: "memory")
; #define PG8_BAR __builtin_amdgcn_s_barrier()
; #define PG8_SCHED __builtin_amdgcn_sched_barrier(0)
; template <class Epi>
; __device__ __forceinline__ void gemm_phase(LAS unsigned char* lds, const Gemm g, const StaticOrder& S, const Epi& E) {
;     ...
;             PG8_LDB(B0, 0, 0); PG8_SCHED; PG8_LDA(At, 0, 0); PG8_STAGE(PG8_SA(1, 1), a1 + hstepA, voffA);
;             PG8_WAIT_L(8); PG8_BAR; PG8_WAIT_L(0); PG8_MMA(0, 0, At, B0); PG8_BAR; PG8_SCHED;
;             PG8_LDB(B1, 0, 1); PG8_STAGE(PG8_SB(0, 0), b2, voffB);
;             PG8_BAR; PG8_WAIT_L(0); PG8_MMA(0, 1, At, B1); PG8_BAR;
;             PG8_LDA(At, 0, 1); PG8_STAGE(PG8_SA(0, 0), a2, voffA);
;             PG8_BAR; PG8_WAIT_L(0); PG8_MMA(1, 0, At, B0); PG8_BAR; PG8_SCHED;
;             PG8_STAGE(PG8_SB(0, 1), b2 + hstepB, voffB);
;             PG8_WAIT_V(6); PG8_BAR; PG8_MMA(1, 1, At, B1); PG8_BAR;
	s_setprio 1
	v_mfma_f32_16x16x32_bf16 v[124:127], v[128:131], v[144:147], v[124:127]
	v_mfma_f32_16x16x32_bf16 v[120:123], v[136:139], v[144:147], v[120:123]
	v_mfma_f32_16x16x32_bf16 v[108:111], v[128:131], v[152:155], v[108:111]
	v_mfma_f32_16x16x32_bf16 v[104:107], v[136:139], v[152:155], v[104:107]
	v_mfma_f32_16x16x32_bf16 v[92:95], v[128:131], v[182:185], v[92:95]
	v_mfma_f32_16x16x32_bf16 v[88:91], v[136:139], v[182:185], v[88:91]
	v_mfma_f32_16x16x32_bf16 v[76:79], v[128:131], v[190:193], v[76:79]
	v_mfma_f32_16x16x32_bf16 v[72:75], v[136:139], v[190:193], v[72:75]
	v_mfma_f32_16x16x32_bf16 v[124:127], v[132:135], v[148:151], v[124:127]
	v_mfma_f32_16x16x32_bf16 v[120:123], v[140:143], v[148:151], v[120:123]
	v_mfma_f32_16x16x32_bf16 v[108:111], v[132:135], v[156:159], v[108:111]
	v_mfma_f32_16x16x32_bf16 v[104:107], v[140:143], v[156:159], v[104:107]
	v_mfma_f32_16x16x32_bf16 v[92:95], v[132:135], v[186:189], v[92:95]
	v_mfma_f32_16x16x32_bf16 v[88:91], v[140:143], v[186:189], v[88:91]
	v_mfma_f32_16x16x32_bf16 v[76:79], v[132:135], v[194:197], v[76:79]
	v_mfma_f32_16x16x32_bf16 v[72:75], v[140:143], v[194:197], v[72:75]
	v_mfma_f32_16x16x32_bf16 v[116:119], v[198:201], v[144:147], v[116:119]
	v_mfma_f32_16x16x32_bf16 v[112:115], v[224:227], v[144:147], v[112:115]
	v_mfma_f32_16x16x32_bf16 v[100:103], v[198:201], v[152:155], v[100:103]
	v_mfma_f32_16x16x32_bf16 v[96:99], v[224:227], v[152:155], v[96:99]
	v_mfma_f32_16x16x32_bf16 v[84:87], v[198:201], v[182:185], v[84:87]
	v_mfma_f32_16x16x32_bf16 v[80:83], v[224:227], v[182:185], v[80:83]
	v_mfma_f32_16x16x32_bf16 v[68:71], v[198:201], v[190:193], v[68:71]
	v_mfma_f32_16x16x32_bf16 v[64:67], v[224:227], v[190:193], v[64:67]
	v_mfma_f32_16x16x32_bf16 v[116:119], v[220:223], v[148:151], v[116:119]
	v_mfma_f32_16x16x32_bf16 v[112:115], v[228:231], v[148:151], v[112:115]
	v_mfma_f32_16x16x32_bf16 v[100:103], v[220:223], v[156:159], v[100:103]
	v_mfma_f32_16x16x32_bf16 v[96:99], v[228:231], v[156:159], v[96:99]
	v_mfma_f32_16x16x32_bf16 v[84:87], v[220:223], v[186:189], v[84:87]
	v_mfma_f32_16x16x32_bf16 v[80:83], v[228:231], v[186:189], v[80:83]
	v_mfma_f32_16x16x32_bf16 v[68:71], v[220:223], v[194:197], v[68:71]
	v_mfma_f32_16x16x32_bf16 v[64:67], v[228:231], v[194:197], v[64:67]
	s_setprio 0
	s_barrier
	s_nop 1
	ds_read_b128 v[144:147], v215 offset:16384
	ds_read_b128 v[148:151], v215 offset:17408
	ds_read_b128 v[152:155], v215 offset:18432
	ds_read_b128 v[156:159], v215 offset:19456
	ds_read_b128 v[182:185], v215 offset:20480
	ds_read_b128 v[186:189], v215 offset:21504
	ds_read_b128 v[190:193], v215 offset:22528
	ds_read_b128 v[194:197], v215 offset:23552
	s_add_i32 s11, s93, s90
	v_lshl_add_u64 v[160:161], s[84:85], 0, v[164:165]
	s_mov_b32 m0, s11
	s_nop 0
	global_load_lds_dwordx4 v164, s[84:85]
	v_lshl_add_u64 v[202:203], s[84:85], 0, v[168:169]
	s_add_i32 m0, s11, 0x2000
	s_nop 0
	global_load_lds_dwordx4 v168, s[84:85]
	s_mov_b32 m0, s91
	v_lshl_add_u64 v[232:233], s[86:87], 0, v[162:163]
	global_load_lds_dwordx4 v162, s[86:87]
	v_lshl_add_u64 v[236:237], s[86:87], 0, v[166:167]
	s_mov_b32 m0, s97
	s_nop 0
	global_load_lds_dwordx4 v166, s[86:87]
	s_add_u32 s80, s84, 0x40000
	s_addc_u32 s81, s85, 0
	s_add_i32 s11, s96, s90
	s_mov_b32 m0, s11
	s_nop 0
	global_load_lds_dwordx4 v164, s[80:81]
	s_add_i32 m0, s11, 0x2000
	s_nop 0
	global_load_lds_dwordx4 v168, s[80:81]
	s_waitcnt vmcnt(6)
	s_waitcnt lgkmcnt(0)
	s_barrier
	s_setprio 1
	v_mfma_f32_16x16x32_bf16 v[60:63], v[128:131], v[144:147], v[60:63]
	v_mfma_f32_16x16x32_bf16 v[56:59], v[136:139], v[144:147], v[56:59]
	v_mfma_f32_16x16x32_bf16 v[44:47], v[128:131], v[152:155], v[44:47]
	v_mfma_f32_16x16x32_bf16 v[40:43], v[136:139], v[152:155], v[40:43]
	v_mfma_f32_16x16x32_bf16 v[28:31], v[128:131], v[182:185], v[28:31]
	v_mfma_f32_16x16x32_bf16 v[24:27], v[136:139], v[182:185], v[24:27]
	v_mfma_f32_16x16x32_bf16 v[12:15], v[128:131], v[190:193], v[12:15]
	v_mfma_f32_16x16x32_bf16 v[8:11], v[136:139], v[190:193], v[8:11]
	v_mfma_f32_16x16x32_bf16 v[60:63], v[132:135], v[148:151], v[60:63]
	v_mfma_f32_16x16x32_bf16 v[56:59], v[140:143], v[148:151], v[56:59]
	v_mfma_f32_16x16x32_bf16 v[44:47], v[132:135], v[156:159], v[44:47]
	v_mfma_f32_16x16x32_bf16 v[40:43], v[140:143], v[156:159], v[40:43]
	v_mfma_f32_16x16x32_bf16 v[28:31], v[132:135], v[186:189], v[28:31]
	v_mfma_f32_16x16x32_bf16 v[24:27], v[140:143], v[186:189], v[24:27]
	v_mfma_f32_16x16x32_bf16 v[12:15], v[132:135], v[194:197], v[12:15]
	v_mfma_f32_16x16x32_bf16 v[8:11], v[140:143], v[194:197], v[8:11]
	v_mfma_f32_16x16x32_bf16 v[52:55], v[198:201], v[144:147], v[52:55]
	v_mfma_f32_16x16x32_bf16 v[48:51], v[224:227], v[144:147], v[48:51]
	v_mfma_f32_16x16x32_bf16 v[36:39], v[198:201], v[152:155], v[36:39]
	v_mfma_f32_16x16x32_bf16 v[32:35], v[224:227], v[152:155], v[32:35]
	v_mfma_f32_16x16x32_bf16 v[20:23], v[198:201], v[182:185], v[20:23]
	v_mfma_f32_16x16x32_bf16 v[16:19], v[224:227], v[182:185], v[16:19]
	v_mfma_f32_16x16x32_bf16 v[4:7], v[198:201], v[190:193], v[4:7]
	v_mfma_f32_16x16x32_bf16 v[0:3], v[224:227], v[190:193], v[0:3]
	v_mfma_f32_16x16x32_bf16 v[52:55], v[220:223], v[148:151], v[52:55]
	v_mfma_f32_16x16x32_bf16 v[48:51], v[228:231], v[148:151], v[48:51]
	v_mfma_f32_16x16x32_bf16 v[36:39], v[220:223], v[156:159], v[36:39]
	v_mfma_f32_16x16x32_bf16 v[32:35], v[228:231], v[156:159], v[32:35]
	v_mfma_f32_16x16x32_bf16 v[20:23], v[220:223], v[186:189], v[20:23]
	v_mfma_f32_16x16x32_bf16 v[16:19], v[228:231], v[186:189], v[16:19]
	v_mfma_f32_16x16x32_bf16 v[4:7], v[220:223], v[194:197], v[4:7]
	v_mfma_f32_16x16x32_bf16 v[0:3], v[228:231], v[194:197], v[0:3]
	s_setprio 0
	s_add_i32 s11, 0, 0x18000
	v_add_u32_e32 v140, s11, v173
	s_barrier
; #define PG8_STAGE(bufoff, gbase, voff) do { _Pragma("unroll") for (int _i = 0; _i < 2; ++_i) \
;         __builtin_amdgcn_global_load_lds((const unsigned*)((const char*)(gbase) + (voff)[_i]), (LAS unsigned*)(lds + (bufoff) + ldsw + _i * 8192), 16, 0, 0); } while (0)
; #define PG8_LDA(dst, b, h) do { _Pragma("unroll") for (int m = 0; m < 4; ++m) _Pragma("unroll") for (int k = 0; k < 2; ++k) dst[m][k] = *(const LAS bf16x8*)(lds + PG8_SA(b, h) + aoff + m * 2048 + k * 1024); } while (0)
; #define PG8_LDB(dst, b, h) do { _Pragma("unroll") for (int n = 0; n < 2; ++n) _Pragma("unroll") for (int k = 0; k < 2; ++k) dst[n][k] = *(const LAS bf16x8*)(lds + PG8_SB(b, h) + boff + n * 2048 + k * 1024); } while (0)
; #define PG8_MMA(ai, bj, At, Bt) do { __builtin_amdgcn_s_setprio(1); _Pragma("unroll") for (int m = 0; m < 4; ++m) _Pragma("unroll") for (int n = 0; n < 2; ++n) _Pragma("unroll") for (int k = 0; k < 2; ++k) \
;         acc[ai][bj][m][n] = __builtin_amdgcn_mfma_f32_16x16x32_bf16(Bt[n][k], At[m][k], acc[ai][bj][m][n], 0, 0, 0); __builtin_amdgcn_s_setprio(0); } while (0)
; #define PG8_WAIT_V(n) asm volatile("s_waitcnt vmcnt(" #n ")" ::: "memory")
; #define PG8_WAIT_L(n) asm volatile("s_waitcnt lgkmcnt(" #n ")" ::: "memory")
; #define PG8_BAR __builtin_amdgcn_s_barrier()
; #define PG8_SCHED __builtin_amdgcn_sched_barrier(0)
; template <class Epi>
; __device__ __forceinline__ void gemm_phase(LAS unsigned char* lds, const Gemm g, const StaticOrder& S, const Epi& E) {
;     ...
;             PG8_LDB(B0, 1, 0); PG8_SCHED; PG8_LDA(At, 1, 0); PG8_STAGE(PG8_SA(0, 1), a2 + hstepA, voffA);
;             PG8_WAIT_L(8); PG8_BAR; PG8_WAIT_L(0); PG8_MMA(0, 0, At, B0); PG8_BAR; PG8_SCHED;
;             PG8_LDB(B1, 1, 1); PG8_STAGE(PG8_SB(1, 0), b3, voffB);
;             PG8_BAR; PG8_WAIT_L(0); PG8_MMA(0, 1, At, B1); PG8_BAR;
;             PG8_LDA(At, 1, 1); PG8_STAGE(PG8_SA(1, 0), a3, voffA);
;             PG8_BAR; PG8_WAIT_L(0); PG8_MMA(1, 0, At, B0); PG8_BAR; PG8_SCHED;
;             PG8_STAGE(PG8_SB(1, 1), b3 + hstepB, voffB);
;             PG8_WAIT_V(6); PG8_BAR; PG8_MMA(1, 1, At, B1); PG8_BAR;
	ds_read_b128 v[128:131], v140
	ds_read_b128 v[132:135], v140 offset:1024
	ds_read_b128 v[136:139], v140 offset:2048
	ds_read_b128 v[140:143], v140 offset:3072
	s_add_u32 s80, s86, 0x40000
	s_addc_u32 s81, s87, 0
	s_mov_b32 m0, s8
	ds_read_b128 v[144:147], v215 offset:32768
	ds_read_b128 v[148:151], v215 offset:33792
	ds_read_b128 v[152:155], v215 offset:34816
	ds_read_b128 v[156:159], v215 offset:35840
	ds_read_b128 v[182:185], v215 offset:36864
	ds_read_b128 v[186:189], v215 offset:37888
	ds_read_b128 v[190:193], v215 offset:38912
	ds_read_b128 v[194:197], v215 offset:39936
	global_load_lds_dwordx4 v162, s[80:81]
	s_mov_b32 m0, s9
	s_nop 0
	global_load_lds_dwordx4 v166, s[80:81]
	s_add_i32 s86, 0, 0x1c000
	v_add_u32_e32 v170, s86, v173
	ds_read_b128 v[198:201], v170
	ds_read_b128 v[220:223], v170 offset:1024
	ds_read_b128 v[224:227], v170 offset:2048
	ds_read_b128 v[228:231], v170 offset:3072
	s_waitcnt lgkmcnt(0)
	s_barrier
	s_setprio 1
	v_mfma_f32_16x16x32_bf16 v[124:127], v[128:131], v[144:147], v[124:127]
	v_mfma_f32_16x16x32_bf16 v[120:123], v[136:139], v[144:147], v[120:123]
	v_mfma_f32_16x16x32_bf16 v[108:111], v[128:131], v[152:155], v[108:111]
	v_mfma_f32_16x16x32_bf16 v[104:107], v[136:139], v[152:155], v[104:107]
	v_mfma_f32_16x16x32_bf16 v[92:95], v[128:131], v[182:185], v[92:95]
	v_mfma_f32_16x16x32_bf16 v[88:91], v[136:139], v[182:185], v[88:91]
	v_mfma_f32_16x16x32_bf16 v[76:79], v[128:131], v[190:193], v[76:79]
	v_mfma_f32_16x16x32_bf16 v[72:75], v[136:139], v[190:193], v[72:75]
	v_mfma_f32_16x16x32_bf16 v[124:127], v[132:135], v[148:151], v[124:127]
	v_mfma_f32_16x16x32_bf16 v[120:123], v[140:143], v[148:151], v[120:123]
	v_mfma_f32_16x16x32_bf16 v[108:111], v[132:135], v[156:159], v[108:111]
	v_mfma_f32_16x16x32_bf16 v[104:107], v[140:143], v[156:159], v[104:107]
	v_mfma_f32_16x16x32_bf16 v[92:95], v[132:135], v[186:189], v[92:95]
	v_mfma_f32_16x16x32_bf16 v[88:91], v[140:143], v[186:189], v[88:91]
	v_mfma_f32_16x16x32_bf16 v[76:79], v[132:135], v[194:197], v[76:79]
	v_mfma_f32_16x16x32_bf16 v[72:75], v[140:143], v[194:197], v[72:75]
	v_mfma_f32_16x16x32_bf16 v[116:119], v[198:201], v[144:147], v[116:119]
	v_mfma_f32_16x16x32_bf16 v[112:115], v[224:227], v[144:147], v[112:115]
	v_mfma_f32_16x16x32_bf16 v[100:103], v[198:201], v[152:155], v[100:103]
	v_mfma_f32_16x16x32_bf16 v[96:99], v[224:227], v[152:155], v[96:99]
	v_mfma_f32_16x16x32_bf16 v[84:87], v[198:201], v[182:185], v[84:87]
	v_mfma_f32_16x16x32_bf16 v[80:83], v[224:227], v[182:185], v[80:83]
	v_mfma_f32_16x16x32_bf16 v[68:71], v[198:201], v[190:193], v[68:71]
	v_mfma_f32_16x16x32_bf16 v[64:67], v[224:227], v[190:193], v[64:67]
	v_mfma_f32_16x16x32_bf16 v[116:119], v[220:223], v[148:151], v[116:119]
	v_mfma_f32_16x16x32_bf16 v[112:115], v[228:231], v[148:151], v[112:115]
	v_mfma_f32_16x16x32_bf16 v[100:103], v[220:223], v[156:159], v[100:103]
	v_mfma_f32_16x16x32_bf16 v[96:99], v[228:231], v[156:159], v[96:99]
	v_mfma_f32_16x16x32_bf16 v[84:87], v[220:223], v[186:189], v[84:87]
	v_mfma_f32_16x16x32_bf16 v[80:83], v[228:231], v[186:189], v[80:83]
	v_mfma_f32_16x16x32_bf16 v[68:71], v[220:223], v[194:197], v[68:71]
	v_mfma_f32_16x16x32_bf16 v[64:67], v[228:231], v[194:197], v[64:67]
	s_setprio 0
	s_barrier
	s_nop 1
	ds_read_b128 v[144:147], v215 offset:49152
	ds_read_b128 v[148:151], v215 offset:50176
	ds_read_b128 v[152:155], v215 offset:51200
	ds_read_b128 v[156:159], v215 offset:52224
	ds_read_b128 v[182:185], v215 offset:53248
	ds_read_b128 v[186:189], v215 offset:54272
	ds_read_b128 v[190:193], v215 offset:55296
	ds_read_b128 v[194:197], v215 offset:56320
	s_add_i32 s11, s11, s90
	s_mov_b32 m0, s11
	s_nop 0
	s_add_u32 s100, s84, s28
	s_addc_u32 s101, s85, s29
	global_load_lds_dwordx4 v164, s[100:101]
	s_add_i32 m0, s11, 0x2000
	s_nop 0
	s_add_u32 s100, s84, s28
	s_addc_u32 s101, s85, s29
	global_load_lds_dwordx4 v168, s[100:101]
	s_mov_b32 m0, s4
	v_lshl_add_u64 v[254:255], v[232:233], 0, s[28:29]
	global_load_lds_dwordx4 v[254:255], off
	v_lshl_add_u64 v[160:161], v[236:237], 0, s[28:29]
	s_mov_b32 m0, s5
	s_nop 0
	global_load_lds_dwordx4 v[160:161], off
	s_add_u32 s80, s84, 0x40080
	s_addc_u32 s81, s85, 0
	s_add_i32 s11, s86, s90
	s_mov_b32 m0, s11
	s_nop 0
	global_load_lds_dwordx4 v164, s[80:81]
	s_add_i32 m0, s11, 0x2000
	s_nop 0
	global_load_lds_dwordx4 v168, s[80:81]
	s_waitcnt vmcnt(6)
	s_waitcnt lgkmcnt(0)
	s_barrier
; #define LAS __attribute__((address_space(3)))
; __device__ __forceinline__ float gelu_tanh(float x) { const float k = 1.5957691216f * (x + 0.044715f * x * x * x); return x * __builtin_amdgcn_rcpf(1.0f + __expf(-k)); }
; #define PG8_MMA(ai, bj, At, Bt) do { __builtin_amdgcn_s_setprio(1); _Pragma("unroll") for (int m = 0; m < 4; ++m) _Pragma("unroll") for (int n = 0; n < 2; ++n) _Pragma("unroll") for (int k = 0; k < 2; ++k) \
;         acc[ai][bj][m][n] = __builtin_amdgcn_mfma_f32_16x16x32_bf16(Bt[n][k], At[m][k], acc[ai][bj][m][n], 0, 0, 0); __builtin_amdgcn_s_setprio(0); } while (0)
; #define PG8_WAIT_V(n) asm volatile("s_waitcnt vmcnt(" #n ")" ::: "memory")
; #define PG8_BAR __builtin_amdgcn_s_barrier()
; template <class Epi>
; __device__ __forceinline__ void gemm_phase(LAS unsigned char* lds, const Gemm g, const StaticOrder& S, const Epi& E) {
;     ...
;             PG8_WAIT_V(6); PG8_BAR; PG8_MMA(1, 1, At, B1); PG8_BAR;
;         }
;     __device__ __forceinline__ void operator()(AccRef acc, const Unit& u, int wr, int wc, int fr, int fq) const {
;         const int row0 = u.pm * 256 + wr * 64 + 4 * fr, clb = wc * 32 + 8 * fq, col0 = (u.pn & 3) * 256 + clb;
;         if (u.pn < 4) {
; #pragma unroll
;             for (int ai = 0; ai < 2; ++ai)
; #pragma unroll
;                 for (int m = 0; m < 4; ++m) { bf16_t* rp = GG + (size_t)(row0 + ai * 128 + m) * D + col0;
; #pragma unroll
;                     for (int bj = 0; bj < 2; ++bj) { f32x4 v0 = acc[ai][bj][m][0], v1 = acc[ai][bj][m][1];
; #pragma unroll
;                         for (int j = 0; j < 4; ++j) { v0[j] = gelu_tanh(v0[j]); v1[j] = gelu_tanh(v1[j]); }
;                         u32x4 w; w.x = cvt_pk_bf16(v0[0], v0[1]); w.y = cvt_pk_bf16(v0[2], v0[3]); w.z = cvt_pk_bf16(v1[0], v1[1]); w.w = cvt_pk_bf16(v1[2], v1[3]);
;                         *(u32x4*)(rp + bj * 128) = w; } }
;             return;
;         }
;         if (fr == 15) {
; #pragma unroll
;             for (int ai = 0; ai < 2; ++ai)
; #pragma unroll
;                 for (int bj = 0; bj < 2; ++bj)
; #pragma unroll
;                     for (int n = 0; n < 2; ++n)
; #pragma unroll
;                         for (int q = 0; q < 3; ++q) *(LAS f32x4*)(xch + ((ai * 2 + wr) * 3 + q) * 256 + bj * 128 + clb + 4 * n) = acc[ai][bj][1 + q][n];
;         }
	s_setprio 1
	v_mfma_f32_16x16x32_bf16 v[60:63], v[128:131], v[144:147], v[60:63]
	v_mfma_f32_16x16x32_bf16 v[56:59], v[136:139], v[144:147], v[56:59]
	v_mfma_f32_16x16x32_bf16 v[44:47], v[128:131], v[152:155], v[44:47]
	v_mfma_f32_16x16x32_bf16 v[40:43], v[136:139], v[152:155], v[40:43]
	v_mfma_f32_16x16x32_bf16 v[28:31], v[128:131], v[182:185], v[28:31]
	v_mfma_f32_16x16x32_bf16 v[24:27], v[136:139], v[182:185], v[24:27]
	v_mfma_f32_16x16x32_bf16 v[12:15], v[128:131], v[190:193], v[12:15]
	v_mfma_f32_16x16x32_bf16 v[8:11], v[136:139], v[190:193], v[8:11]
	v_mfma_f32_16x16x32_bf16 v[60:63], v[132:135], v[148:151], v[60:63]
	v_mfma_f32_16x16x32_bf16 v[56:59], v[140:143], v[148:151], v[56:59]
	v_mfma_f32_16x16x32_bf16 v[44:47], v[132:135], v[156:159], v[44:47]
	v_mfma_f32_16x16x32_bf16 v[40:43], v[140:143], v[156:159], v[40:43]
	v_mfma_f32_16x16x32_bf16 v[28:31], v[132:135], v[186:189], v[28:31]
	v_mfma_f32_16x16x32_bf16 v[24:27], v[140:143], v[186:189], v[24:27]
	v_mfma_f32_16x16x32_bf16 v[12:15], v[132:135], v[194:197], v[12:15]
	v_mfma_f32_16x16x32_bf16 v[8:11], v[140:143], v[194:197], v[8:11]
	v_mfma_f32_16x16x32_bf16 v[52:55], v[198:201], v[144:147], v[52:55]
	v_mfma_f32_16x16x32_bf16 v[48:51], v[224:227], v[144:147], v[48:51]
	v_mfma_f32_16x16x32_bf16 v[36:39], v[198:201], v[152:155], v[36:39]
	v_mfma_f32_16x16x32_bf16 v[32:35], v[224:227], v[152:155], v[32:35]
	v_mfma_f32_16x16x32_bf16 v[20:23], v[198:201], v[182:185], v[20:23]
	v_mfma_f32_16x16x32_bf16 v[16:19], v[224:227], v[182:185], v[16:19]
	v_mfma_f32_16x16x32_bf16 v[4:7], v[198:201], v[190:193], v[4:7]
	v_mfma_f32_16x16x32_bf16 v[0:3], v[224:227], v[190:193], v[0:3]
	v_mfma_f32_16x16x32_bf16 v[52:55], v[220:223], v[148:151], v[52:55]
	v_mfma_f32_16x16x32_bf16 v[48:51], v[228:231], v[148:151], v[48:51]
	v_mfma_f32_16x16x32_bf16 v[36:39], v[220:223], v[156:159], v[36:39]
	v_mfma_f32_16x16x32_bf16 v[32:35], v[228:231], v[156:159], v[32:35]
	v_mfma_f32_16x16x32_bf16 v[20:23], v[220:223], v[186:189], v[20:23]
	v_mfma_f32_16x16x32_bf16 v[16:19], v[228:231], v[186:189], v[16:19]
	v_mfma_f32_16x16x32_bf16 v[4:7], v[220:223], v[194:197], v[4:7]
	v_mfma_f32_16x16x32_bf16 v[0:3], v[228:231], v[194:197], v[0:3]
	s_setprio 0
	s_add_i32 s10, s10, 2
	s_add_u32 vcc_lo, vcc_lo, 0x100
	s_addc_u32 vcc_hi, vcc_hi, 0
	s_cmp_gt_u32 s10, 13
	s_mov_b64 s[80:81], s[82:83]
	s_barrier
	s_cbranch_scc0 .LBB0_990
	s_lshl_b32 s10, s78, 8
	s_and_b32 s10, s10, 0x300
	v_lshl_add_u32 v182, s76, 8, v204
	v_or_b32_e32 v220, s10, v172
	s_cmp_gt_i32 s78, 3
	s_mov_b64 s[80:81], -1
	s_cbranch_scc0 .LBB0_1015
	s_and_saveexec_b64 s[80:81], s[12:13]
	s_cbranch_execz .LBB0_994
	ds_write_b128 v205, v[108:111]
	ds_write_b128 v205, v[92:95] offset:1024
	ds_write_b128 v205, v[76:79] offset:2048
	ds_write_b128 v205, v[104:107] offset:16
	ds_write_b128 v205, v[88:91] offset:1040
	ds_write_b128 v205, v[72:75] offset:2064
	ds_write_b128 v205, v[100:103] offset:512
	ds_write_b128 v205, v[84:87] offset:1536
	ds_write_b128 v205, v[68:71] offset:2560
	ds_write_b128 v205, v[96:99] offset:528
	ds_write_b128 v205, v[80:83] offset:1552
	ds_write_b128 v205, v[64:67] offset:2576
	ds_write_b128 v205, v[44:47] offset:6144
	ds_write_b128 v205, v[28:31] offset:7168
	ds_write_b128 v205, v[12:15] offset:8192
	ds_write_b128 v205, v[40:43] offset:6160
	ds_write_b128 v205, v[24:27] offset:7184
	ds_write_b128 v205, v[8:11] offset:8208
	ds_write_b128 v205, v[36:39] offset:6656
	ds_write_b128 v205, v[20:23] offset:7680
	ds_write_b128 v205, v[4:7] offset:8704
	ds_write_b128 v205, v[32:35] offset:6672
	ds_write_b128 v205, v[16:19] offset:7696
	ds_write_b128 v205, v[0:3] offset:8720

; #define PG8_STAGE(bufoff, gbase, voff) do { _Pragma("unroll") for (int _i = 0; _i < 2; ++_i) \
;         __builtin_amdgcn_global_load_lds((const unsigned*)((const char*)(gbase) + (voff)[_i]), (LAS unsigned*)(lds + (bufoff) + ldsw + _i * 8192), 16, 0, 0); } while (0)
; #define PG8_LDA(dst, b, h) do { _Pragma("unroll") for (int m = 0; m < 4; ++m) _Pragma("unroll") for (int k = 0; k < 2; ++k) dst[m][k] = *(const LAS bf16x8*)(lds + PG8_SA(b, h) + aoff + m * 2048 + k * 1024); } while (0)
; #define PG8_LDB(dst, b, h) do { _Pragma("unroll") for (int n = 0; n < 2; ++n) _Pragma("unroll") for (int k = 0; k < 2; ++k) dst[n][k] = *(const LAS bf16x8*)(lds + PG8_SB(b, h) + boff + n * 2048 + k * 1024); } while (0)
; #define PG8_WAIT_V(n) asm volatile("s_waitcnt vmcnt(" #n ")" ::: "memory")
; #define PG8_WAIT_L(n) asm volatile("s_waitcnt lgkmcnt(" #n ")" ::: "memory")
; #define PG8_BAR __builtin_amdgcn_s_barrier()
; #define PG8_SCHED __builtin_amdgcn_sched_barrier(0)
; template <class Epi>
; __device__ __forceinline__ void gemm_phase(LAS unsigned char* lds, const Gemm g, const StaticOrder& S, const Epi& E) {
;     ...
;         const bool has_next = S.next(ui + 1, nxt);
;         const char* nA = has_next ? (const char*)g.A + (size_t)nxt.pm * tstepA + (size_t)(nxt.pn >> g.a_shift) * g.a_step : cA; const char* nB = has_next ? (const char*)g.Bt + (size_t)nxt.pn * tstepB : cB;
;         for (int t = 0; t < nt; t += 2) {
;             const bool last = (t == nt - 2);
;             const char* a1 = cA + (size_t)(t + 1) * kstep;
;             const char* a2 = last ? nA : cA + (size_t)(t + 2) * kstep; const char* b2 = last ? nB : cB + (size_t)(t + 2) * kstep;
;             const char* a3 = a2 + kstep; const char* b3 = b2 + kstep;
;             PG8_LDB(B0, 0, 0); PG8_SCHED; PG8_LDA(At, 0, 0); PG8_STAGE(PG8_SA(1, 1), a1 + hstepA, voffA);
;             PG8_WAIT_L(8); PG8_BAR; PG8_WAIT_L(0); PG8_MMA(0, 0, At, B0); PG8_BAR; PG8_SCHED;
;             PG8_LDB(B1, 0, 1); PG8_STAGE(PG8_SB(0, 0), b2, voffB);
;             PG8_BAR; PG8_WAIT_L(0); PG8_MMA(0, 1, At, B1); PG8_BAR;
;             PG8_LDA(At, 0, 1); PG8_STAGE(PG8_SA(0, 0), a2, voffA);
;             PG8_BAR; PG8_WAIT_L(0); PG8_MMA(1, 0, At, B0); PG8_BAR; PG8_SCHED;
;             PG8_STAGE(PG8_SB(0, 1), b2 + hstepB, voffB);
;             PG8_WAIT_V(6); PG8_BAR; PG8_MMA(1, 1, At, B1); PG8_BAR;
.LBB0_1238:
	s_ashr_i32 s29, s28, 31
	v_cmp_lt_i64_e32 vcc, s[30:31], v[136:137]
	s_lshl_b64 s[30:31], s[28:29], 19
	s_add_u32 s30, s60, s30
	s_addc_u32 s31, s61, s31
	s_and_b64 s[34:35], vcc, exec
	s_cselect_b32 s29, s31, s39
	s_cselect_b32 s72, s30, s38
	s_ashr_i32 s27, s26, 31
	s_lshl_b64 s[34:35], s[26:27], 19
	s_add_u32 s34, s5, s34
	s_addc_u32 s35, s6, s35
	s_and_b64 s[42:43], vcc, exec
	s_cselect_b32 s27, s35, s41
	s_cselect_b32 s73, s34, s40
	s_add_u32 s38, s38, 0x40080
	s_addc_u32 s39, s39, 0
	s_add_u32 s74, s40, 0x100
	s_addc_u32 s75, s41, 0
	s_mov_b32 s76, -2
	ds_read_b128 v[140:143], v149
	ds_read_b128 v[152:155], v149 offset:1024
	ds_read_b128 v[156:159], v149 offset:2048
	ds_read_b128 v[160:163], v149 offset:3072
	s_add_u32 s40, s38, 0xfffc0080
	s_addc_u32 s41, s39, -1
	s_cmp_eq_u32 s76, 12
	s_cselect_b32 s43, s29, s41
	s_cselect_b32 s42, s72, s40
	s_cselect_b32 s41, s27, s75
	s_cselect_b32 s40, s73, s74
	s_add_i32 m0, s8, 0xc000
	ds_read_b128 v[164:167], v150
	ds_read_b128 v[168:171], v150 offset:1024
	ds_read_b128 v[172:175], v150 offset:2048
	ds_read_b128 v[176:179], v150 offset:3072
	ds_read_b128 v[180:183], v150 offset:4096
	ds_read_b128 v[184:187], v150 offset:5120
	ds_read_b128 v[188:191], v150 offset:6144
	ds_read_b128 v[192:195], v150 offset:7168
	global_load_lds_dwordx4 v132, s[38:39]
	s_add_i32 m0, s8, 0xe000
	s_nop 0
	global_load_lds_dwordx4 v134, s[38:39]
	ds_read_b128 v[196:199], v151
	ds_read_b128 v[200:203], v151 offset:1024
	ds_read_b128 v[204:207], v151 offset:2048
	ds_read_b128 v[208:211], v151 offset:3072
	s_waitcnt lgkmcnt(0)
	s_barrier
	s_setprio 1
	v_mfma_f32_16x16x32_bf16 v[124:127], v[140:143], v[164:167], 0
	v_mfma_f32_16x16x32_bf16 v[120:123], v[156:159], v[164:167], 0
	v_mfma_f32_16x16x32_bf16 v[112:115], v[140:143], v[172:175], 0
	v_mfma_f32_16x16x32_bf16 v[104:107], v[156:159], v[172:175], 0
	v_mfma_f32_16x16x32_bf16 v[92:95], v[140:143], v[180:183], 0
	v_mfma_f32_16x16x32_bf16 v[88:91], v[156:159], v[180:183], 0
	v_mfma_f32_16x16x32_bf16 v[80:83], v[140:143], v[188:191], 0
	v_mfma_f32_16x16x32_bf16 v[72:75], v[156:159], v[188:191], 0
	v_mfma_f32_16x16x32_bf16 v[124:127], v[152:155], v[168:171], v[124:127]
	v_mfma_f32_16x16x32_bf16 v[120:123], v[160:163], v[168:171], v[120:123]
	v_mfma_f32_16x16x32_bf16 v[112:115], v[152:155], v[176:179], v[112:115]
	v_mfma_f32_16x16x32_bf16 v[104:107], v[160:163], v[176:179], v[104:107]
	v_mfma_f32_16x16x32_bf16 v[92:95], v[152:155], v[184:187], v[92:95]
	v_mfma_f32_16x16x32_bf16 v[88:91], v[160:163], v[184:187], v[88:91]
	v_mfma_f32_16x16x32_bf16 v[80:83], v[152:155], v[192:195], v[80:83]
	v_mfma_f32_16x16x32_bf16 v[72:75], v[160:163], v[192:195], v[72:75]
	v_mfma_f32_16x16x32_bf16 v[116:119], v[196:199], v[164:167], 0
	v_mfma_f32_16x16x32_bf16 v[108:111], v[204:207], v[164:167], 0
	v_mfma_f32_16x16x32_bf16 v[100:103], v[196:199], v[172:175], 0
	v_mfma_f32_16x16x32_bf16 v[96:99], v[204:207], v[172:175], 0
	v_mfma_f32_16x16x32_bf16 v[84:87], v[196:199], v[180:183], 0
	v_mfma_f32_16x16x32_bf16 v[76:79], v[204:207], v[180:183], 0
	v_mfma_f32_16x16x32_bf16 v[68:71], v[196:199], v[188:191], 0
	v_mfma_f32_16x16x32_bf16 v[64:67], v[204:207], v[188:191], 0
	v_mfma_f32_16x16x32_bf16 v[116:119], v[200:203], v[168:171], v[116:119]
	v_mfma_f32_16x16x32_bf16 v[108:111], v[208:211], v[168:171], v[108:111]
	v_mfma_f32_16x16x32_bf16 v[100:103], v[200:203], v[176:179], v[100:103]
	v_mfma_f32_16x16x32_bf16 v[96:99], v[208:211], v[176:179], v[96:99]
	v_mfma_f32_16x16x32_bf16 v[84:87], v[200:203], v[184:187], v[84:87]
	v_mfma_f32_16x16x32_bf16 v[76:79], v[208:211], v[184:187], v[76:79]
	v_mfma_f32_16x16x32_bf16 v[68:71], v[200:203], v[192:195], v[68:71]
	v_mfma_f32_16x16x32_bf16 v[64:67], v[208:211], v[192:195], v[64:67]
	s_setprio 0
	s_barrier
	s_nop 1
	ds_read_b128 v[164:167], v150 offset:16384
	ds_read_b128 v[168:171], v150 offset:17408
	ds_read_b128 v[172:175], v150 offset:18432
	ds_read_b128 v[176:179], v150 offset:19456
	ds_read_b128 v[180:183], v150 offset:20480
	ds_read_b128 v[184:187], v150 offset:21504
	ds_read_b128 v[188:191], v150 offset:22528
	ds_read_b128 v[192:195], v150 offset:23552
	s_add_i32 s77, s48, s7
	v_lshl_add_u64 v[144:145], s[40:41], 0, v[128:129]
	s_mov_b32 m0, s77
	s_nop 0
	global_load_lds_dwordx4 v128, s[40:41]
	v_lshl_add_u64 v[212:213], s[40:41], 0, v[130:131]
	s_add_i32 m0, s77, 0x2000
	s_nop 0
	global_load_lds_dwordx4 v130, s[40:41]
	s_mov_b32 m0, s8
	v_lshl_add_u64 v[214:215], s[42:43], 0, v[128:129]
	global_load_lds_dwordx4 v128, s[42:43]
	v_lshl_add_u64 v[216:217], s[42:43], 0, v[130:131]
	s_mov_b32 m0, s9
	s_nop 0
	global_load_lds_dwordx4 v130, s[42:43]
	s_add_u32 s78, s40, 0x40000
	s_addc_u32 s79, s41, 0
	s_add_i32 s77, s49, s7
	s_mov_b32 m0, s77
	s_nop 0
	global_load_lds_dwordx4 v128, s[78:79]
	s_add_i32 m0, s77, 0x2000
	s_nop 0
	global_load_lds_dwordx4 v130, s[78:79]
	s_waitcnt vmcnt(6)
	s_waitcnt lgkmcnt(0)
	s_barrier
; #define PG8_STAGE(bufoff, gbase, voff) do { _Pragma("unroll") for (int _i = 0; _i < 2; ++_i) \
;         __builtin_amdgcn_global_load_lds((const unsigned*)((const char*)(gbase) + (voff)[_i]), (LAS unsigned*)(lds + (bufoff) + ldsw + _i * 8192), 16, 0, 0); } while (0)
; #define PG8_LDA(dst, b, h) do { _Pragma("unroll") for (int m = 0; m < 4; ++m) _Pragma("unroll") for (int k = 0; k < 2; ++k) dst[m][k] = *(const LAS bf16x8*)(lds + PG8_SA(b, h) + aoff + m * 2048 + k * 1024); } while (0)
; #define PG8_LDB(dst, b, h) do { _Pragma("unroll") for (int n = 0; n < 2; ++n) _Pragma("unroll") for (int k = 0; k < 2; ++k) dst[n][k] = *(const LAS bf16x8*)(lds + PG8_SB(b, h) + boff + n * 2048 + k * 1024); } while (0)
; #define PG8_MMA(ai, bj, At, Bt) do { __builtin_amdgcn_s_setprio(1); _Pragma("unroll") for (int m = 0; m < 4; ++m) _Pragma("unroll") for (int n = 0; n < 2; ++n) _Pragma("unroll") for (int k = 0; k < 2; ++k) \
;         acc[ai][bj][m][n] = __builtin_amdgcn_mfma_f32_16x16x32_bf16(Bt[n][k], At[m][k], acc[ai][bj][m][n], 0, 0, 0); __builtin_amdgcn_s_setprio(0); } while (0)
; #define PG8_WAIT_V(n) asm volatile("s_waitcnt vmcnt(" #n ")" ::: "memory")
; #define PG8_WAIT_L(n) asm volatile("s_waitcnt lgkmcnt(" #n ")" ::: "memory")
; #define PG8_BAR __builtin_amdgcn_s_barrier()
; #define PG8_SCHED __builtin_amdgcn_sched_barrier(0)
; template <class Epi>
; __device__ __forceinline__ void gemm_phase(LAS unsigned char* lds, const Gemm g, const StaticOrder& S, const Epi& E) {
;     ...
;             PG8_WAIT_V(6); PG8_BAR; PG8_MMA(1, 1, At, B1); PG8_BAR;
;             PG8_LDB(B0, 1, 0); PG8_SCHED; PG8_LDA(At, 1, 0); PG8_STAGE(PG8_SA(0, 1), a2 + hstepA, voffA);
;             PG8_WAIT_L(8); PG8_BAR; PG8_WAIT_L(0); PG8_MMA(0, 0, At, B0); PG8_BAR; PG8_SCHED;
;             PG8_LDB(B1, 1, 1); PG8_STAGE(PG8_SB(1, 0), b3, voffB);
;             PG8_BAR; PG8_WAIT_L(0); PG8_MMA(0, 1, At, B1); PG8_BAR;
	s_setprio 1
	v_mfma_f32_16x16x32_bf16 v[60:63], v[140:143], v[164:167], 0
	v_mfma_f32_16x16x32_bf16 v[56:59], v[156:159], v[164:167], 0
	v_mfma_f32_16x16x32_bf16 v[48:51], v[140:143], v[172:175], 0
	v_mfma_f32_16x16x32_bf16 v[40:43], v[156:159], v[172:175], 0
	v_mfma_f32_16x16x32_bf16 v[28:31], v[140:143], v[180:183], 0
	v_mfma_f32_16x16x32_bf16 v[24:27], v[156:159], v[180:183], 0
	v_mfma_f32_16x16x32_bf16 v[16:19], v[140:143], v[188:191], 0
	v_mfma_f32_16x16x32_bf16 v[8:11], v[156:159], v[188:191], 0
	v_mfma_f32_16x16x32_bf16 v[60:63], v[152:155], v[168:171], v[60:63]
	v_mfma_f32_16x16x32_bf16 v[56:59], v[160:163], v[168:171], v[56:59]
	v_mfma_f32_16x16x32_bf16 v[48:51], v[152:155], v[176:179], v[48:51]
	v_mfma_f32_16x16x32_bf16 v[40:43], v[160:163], v[176:179], v[40:43]
	v_mfma_f32_16x16x32_bf16 v[28:31], v[152:155], v[184:187], v[28:31]
	v_mfma_f32_16x16x32_bf16 v[24:27], v[160:163], v[184:187], v[24:27]
	v_mfma_f32_16x16x32_bf16 v[16:19], v[152:155], v[192:195], v[16:19]
	v_mfma_f32_16x16x32_bf16 v[8:11], v[160:163], v[192:195], v[8:11]
	v_mfma_f32_16x16x32_bf16 v[52:55], v[196:199], v[164:167], 0
	v_mfma_f32_16x16x32_bf16 v[44:47], v[204:207], v[164:167], 0
	v_mfma_f32_16x16x32_bf16 v[36:39], v[196:199], v[172:175], 0
	v_mfma_f32_16x16x32_bf16 v[32:35], v[204:207], v[172:175], 0
	v_mfma_f32_16x16x32_bf16 v[20:23], v[196:199], v[180:183], 0
	v_mfma_f32_16x16x32_bf16 v[12:15], v[204:207], v[180:183], 0
	v_mfma_f32_16x16x32_bf16 v[4:7], v[196:199], v[188:191], 0
	v_mfma_f32_16x16x32_bf16 v[0:3], v[204:207], v[188:191], 0
	v_mfma_f32_16x16x32_bf16 v[52:55], v[200:203], v[168:171], v[52:55]
	v_mfma_f32_16x16x32_bf16 v[44:47], v[208:211], v[168:171], v[44:47]
	v_mfma_f32_16x16x32_bf16 v[36:39], v[200:203], v[176:179], v[36:39]
	v_mfma_f32_16x16x32_bf16 v[32:35], v[208:211], v[176:179], v[32:35]
	v_mfma_f32_16x16x32_bf16 v[20:23], v[200:203], v[184:187], v[20:23]
	v_mfma_f32_16x16x32_bf16 v[12:15], v[208:211], v[184:187], v[12:15]
	v_mfma_f32_16x16x32_bf16 v[4:7], v[200:203], v[192:195], v[4:7]
	v_mfma_f32_16x16x32_bf16 v[0:3], v[208:211], v[192:195], v[0:3]
	s_setprio 0
	s_add_i32 s77, 0, 0x18000
	v_add_u32_e32 v160, s77, v147
	s_barrier
	ds_read_b128 v[140:143], v160
	ds_read_b128 v[152:155], v160 offset:1024
	ds_read_b128 v[156:159], v160 offset:2048
	ds_read_b128 v[160:163], v160 offset:3072
	s_add_u32 s42, s42, 0x40000
	s_addc_u32 s43, s43, 0
	s_mov_b32 m0, s37
	ds_read_b128 v[164:167], v150 offset:32768
	ds_read_b128 v[168:171], v150 offset:33792
	ds_read_b128 v[172:175], v150 offset:34816
	ds_read_b128 v[176:179], v150 offset:35840
	ds_read_b128 v[180:183], v150 offset:36864
	ds_read_b128 v[184:187], v150 offset:37888
	ds_read_b128 v[188:191], v150 offset:38912
	ds_read_b128 v[192:195], v150 offset:39936
	global_load_lds_dwordx4 v128, s[42:43]
	s_mov_b32 m0, s44
	s_nop 0
	global_load_lds_dwordx4 v130, s[42:43]
	s_add_i32 s42, 0, 0x1c000
	v_add_u32_e32 v208, s42, v147
	ds_read_b128 v[196:199], v208
	ds_read_b128 v[200:203], v208 offset:1024
	ds_read_b128 v[204:207], v208 offset:2048
	ds_read_b128 v[208:211], v208 offset:3072
	s_waitcnt lgkmcnt(0)
	s_barrier
	s_setprio 1
	v_mfma_f32_16x16x32_bf16 v[124:127], v[140:143], v[164:167], v[124:127]
	v_mfma_f32_16x16x32_bf16 v[120:123], v[156:159], v[164:167], v[120:123]
	v_mfma_f32_16x16x32_bf16 v[112:115], v[140:143], v[172:175], v[112:115]
	v_mfma_f32_16x16x32_bf16 v[104:107], v[156:159], v[172:175], v[104:107]
	v_mfma_f32_16x16x32_bf16 v[92:95], v[140:143], v[180:183], v[92:95]
	v_mfma_f32_16x16x32_bf16 v[88:91], v[156:159], v[180:183], v[88:91]
	v_mfma_f32_16x16x32_bf16 v[80:83], v[140:143], v[188:191], v[80:83]
	v_mfma_f32_16x16x32_bf16 v[72:75], v[156:159], v[188:191], v[72:75]
	v_mfma_f32_16x16x32_bf16 v[124:127], v[152:155], v[168:171], v[124:127]
	v_mfma_f32_16x16x32_bf16 v[120:123], v[160:163], v[168:171], v[120:123]
	v_mfma_f32_16x16x32_bf16 v[112:115], v[152:155], v[176:179], v[112:115]
	v_mfma_f32_16x16x32_bf16 v[104:107], v[160:163], v[176:179], v[104:107]
	v_mfma_f32_16x16x32_bf16 v[92:95], v[152:155], v[184:187], v[92:95]
	v_mfma_f32_16x16x32_bf16 v[88:91], v[160:163], v[184:187], v[88:91]
	v_mfma_f32_16x16x32_bf16 v[80:83], v[152:155], v[192:195], v[80:83]
	v_mfma_f32_16x16x32_bf16 v[72:75], v[160:163], v[192:195], v[72:75]
	v_mfma_f32_16x16x32_bf16 v[116:119], v[196:199], v[164:167], v[116:119]
	v_mfma_f32_16x16x32_bf16 v[108:111], v[204:207], v[164:167], v[108:111]
	v_mfma_f32_16x16x32_bf16 v[100:103], v[196:199], v[172:175], v[100:103]
	v_mfma_f32_16x16x32_bf16 v[96:99], v[204:207], v[172:175], v[96:99]
	v_mfma_f32_16x16x32_bf16 v[84:87], v[196:199], v[180:183], v[84:87]
	v_mfma_f32_16x16x32_bf16 v[76:79], v[204:207], v[180:183], v[76:79]
	v_mfma_f32_16x16x32_bf16 v[68:71], v[196:199], v[188:191], v[68:71]
	v_mfma_f32_16x16x32_bf16 v[64:67], v[204:207], v[188:191], v[64:67]
	v_mfma_f32_16x16x32_bf16 v[116:119], v[200:203], v[168:171], v[116:119]
	v_mfma_f32_16x16x32_bf16 v[108:111], v[208:211], v[168:171], v[108:111]
	v_mfma_f32_16x16x32_bf16 v[100:103], v[200:203], v[176:179], v[100:103]
	v_mfma_f32_16x16x32_bf16 v[96:99], v[208:211], v[176:179], v[96:99]
	v_mfma_f32_16x16x32_bf16 v[84:87], v[200:203], v[184:187], v[84:87]
	v_mfma_f32_16x16x32_bf16 v[76:79], v[208:211], v[184:187], v[76:79]
	v_mfma_f32_16x16x32_bf16 v[68:71], v[200:203], v[192:195], v[68:71]
	v_mfma_f32_16x16x32_bf16 v[64:67], v[208:211], v[192:195], v[64:67]
	s_setprio 0
	s_barrier
; #define PG8_STAGE(bufoff, gbase, voff) do { _Pragma("unroll") for (int _i = 0; _i < 2; ++_i) \
;         __builtin_amdgcn_global_load_lds((const unsigned*)((const char*)(gbase) + (voff)[_i]), (LAS unsigned*)(lds + (bufoff) + ldsw + _i * 8192), 16, 0, 0); } while (0)
; #define PG8_LDA(dst, b, h) do { _Pragma("unroll") for (int m = 0; m < 4; ++m) _Pragma("unroll") for (int k = 0; k < 2; ++k) dst[m][k] = *(const LAS bf16x8*)(lds + PG8_SA(b, h) + aoff + m * 2048 + k * 1024); } while (0)
; #define PG8_LDB(dst, b, h) do { _Pragma("unroll") for (int n = 0; n < 2; ++n) _Pragma("unroll") for (int k = 0; k < 2; ++k) dst[n][k] = *(const LAS bf16x8*)(lds + PG8_SB(b, h) + boff + n * 2048 + k * 1024); } while (0)
; #define PG8_MMA(ai, bj, At, Bt) do { __builtin_amdgcn_s_setprio(1); _Pragma("unroll") for (int m = 0; m < 4; ++m) _Pragma("unroll") for (int n = 0; n < 2; ++n) _Pragma("unroll") for (int k = 0; k < 2; ++k) \
;         acc[ai][bj][m][n] = __builtin_amdgcn_mfma_f32_16x16x32_bf16(Bt[n][k], At[m][k], acc[ai][bj][m][n], 0, 0, 0); __builtin_amdgcn_s_setprio(0); } while (0)
; #define PG8_WAIT_V(n) asm volatile("s_waitcnt vmcnt(" #n ")" ::: "memory")
; #define PG8_WAIT_L(n) asm volatile("s_waitcnt lgkmcnt(" #n ")" ::: "memory")
; #define PG8_BAR __builtin_amdgcn_s_barrier()
; #define PG8_SCHED __builtin_amdgcn_sched_barrier(0)
; template <class Epi>
; __device__ __forceinline__ void gemm_phase(LAS unsigned char* lds, const Gemm g, const StaticOrder& S, const Epi& E) {
;     ...
;             PG8_LDB(B0, 0, 0); PG8_SCHED; PG8_LDA(At, 0, 0); PG8_STAGE(PG8_SA(1, 1), a1 + hstepA, voffA);
;             PG8_WAIT_L(8); PG8_BAR; PG8_WAIT_L(0); PG8_MMA(0, 0, At, B0); PG8_BAR; PG8_SCHED;
;             PG8_LDB(B1, 0, 1); PG8_STAGE(PG8_SB(0, 0), b2, voffB);
;             PG8_BAR; PG8_WAIT_L(0); PG8_MMA(0, 1, At, B1); PG8_BAR;
;             PG8_LDA(At, 0, 1); PG8_STAGE(PG8_SA(0, 0), a2, voffA);
;     ...
;             PG8_LDA(At, 1, 1); PG8_STAGE(PG8_SA(1, 0), a3, voffA);
;             PG8_BAR; PG8_WAIT_L(0); PG8_MMA(1, 0, At, B0); PG8_BAR; PG8_SCHED;
;             PG8_STAGE(PG8_SB(1, 1), b3 + hstepB, voffB);
;             PG8_WAIT_V(6); PG8_BAR; PG8_MMA(1, 1, At, B1); PG8_BAR;
	s_nop 1
	ds_read_b128 v[164:167], v150 offset:49152
	ds_read_b128 v[168:171], v150 offset:50176
	ds_read_b128 v[172:175], v150 offset:51200
	ds_read_b128 v[176:179], v150 offset:52224
	ds_read_b128 v[180:183], v150 offset:53248
	ds_read_b128 v[184:187], v150 offset:54272
	ds_read_b128 v[188:191], v150 offset:55296
	ds_read_b128 v[192:195], v150 offset:56320
	s_add_i32 s43, s77, s7
	s_mov_b32 m0, s43
	s_nop 0
	s_add_u32 s100, s40, s12
	s_addc_u32 s101, s41, s13
	global_load_lds_dwordx4 v128, s[100:101]
	s_add_i32 m0, s43, 0x2000
	s_nop 0
	s_add_u32 s100, s40, s12
	s_addc_u32 s101, s41, s13
	global_load_lds_dwordx4 v130, s[100:101]
	s_mov_b32 m0, s46
	v_lshl_add_u64 v[254:255], v[214:215], 0, s[12:13]
	global_load_lds_dwordx4 v[254:255], off
	v_lshl_add_u64 v[144:145], v[216:217], 0, s[12:13]
	s_mov_b32 m0, s47
	s_nop 0
	global_load_lds_dwordx4 v[144:145], off
	s_add_u32 s40, s40, 0x40080
	s_addc_u32 s41, s41, 0
	s_add_i32 s42, s42, s7
	s_mov_b32 m0, s42
	s_nop 0
	global_load_lds_dwordx4 v128, s[40:41]
	s_add_i32 m0, s42, 0x2000
	s_nop 0
	global_load_lds_dwordx4 v130, s[40:41]
	s_waitcnt vmcnt(6)
	s_waitcnt lgkmcnt(0)
	s_barrier
	s_setprio 1
	v_mfma_f32_16x16x32_bf16 v[60:63], v[140:143], v[164:167], v[60:63]
	v_mfma_f32_16x16x32_bf16 v[56:59], v[156:159], v[164:167], v[56:59]
	v_mfma_f32_16x16x32_bf16 v[48:51], v[140:143], v[172:175], v[48:51]
	v_mfma_f32_16x16x32_bf16 v[40:43], v[156:159], v[172:175], v[40:43]
	v_mfma_f32_16x16x32_bf16 v[28:31], v[140:143], v[180:183], v[28:31]
	v_mfma_f32_16x16x32_bf16 v[24:27], v[156:159], v[180:183], v[24:27]
	v_mfma_f32_16x16x32_bf16 v[16:19], v[140:143], v[188:191], v[16:19]
	v_mfma_f32_16x16x32_bf16 v[8:11], v[156:159], v[188:191], v[8:11]
	v_mfma_f32_16x16x32_bf16 v[60:63], v[152:155], v[168:171], v[60:63]
	v_mfma_f32_16x16x32_bf16 v[56:59], v[160:163], v[168:171], v[56:59]
	v_mfma_f32_16x16x32_bf16 v[48:51], v[152:155], v[176:179], v[48:51]
	v_mfma_f32_16x16x32_bf16 v[40:43], v[160:163], v[176:179], v[40:43]
	v_mfma_f32_16x16x32_bf16 v[28:31], v[152:155], v[184:187], v[28:31]
	v_mfma_f32_16x16x32_bf16 v[24:27], v[160:163], v[184:187], v[24:27]
	v_mfma_f32_16x16x32_bf16 v[16:19], v[152:155], v[192:195], v[16:19]
	v_mfma_f32_16x16x32_bf16 v[8:11], v[160:163], v[192:195], v[8:11]
	v_mfma_f32_16x16x32_bf16 v[52:55], v[196:199], v[164:167], v[52:55]
	v_mfma_f32_16x16x32_bf16 v[44:47], v[204:207], v[164:167], v[44:47]
	v_mfma_f32_16x16x32_bf16 v[36:39], v[196:199], v[172:175], v[36:39]
	v_mfma_f32_16x16x32_bf16 v[32:35], v[204:207], v[172:175], v[32:35]
	v_mfma_f32_16x16x32_bf16 v[20:23], v[196:199], v[180:183], v[20:23]
	v_mfma_f32_16x16x32_bf16 v[12:15], v[204:207], v[180:183], v[12:15]
	v_mfma_f32_16x16x32_bf16 v[4:7], v[196:199], v[188:191], v[4:7]
	v_mfma_f32_16x16x32_bf16 v[0:3], v[204:207], v[188:191], v[0:3]
	v_mfma_f32_16x16x32_bf16 v[52:55], v[200:203], v[168:171], v[52:55]
	v_mfma_f32_16x16x32_bf16 v[44:47], v[208:211], v[168:171], v[44:47]
	v_mfma_f32_16x16x32_bf16 v[36:39], v[200:203], v[176:179], v[36:39]
	v_mfma_f32_16x16x32_bf16 v[32:35], v[208:211], v[176:179], v[32:35]
	v_mfma_f32_16x16x32_bf16 v[20:23], v[200:203], v[184:187], v[20:23]
	v_mfma_f32_16x16x32_bf16 v[12:15], v[208:211], v[184:187], v[12:15]
	v_mfma_f32_16x16x32_bf16 v[4:7], v[200:203], v[192:195], v[4:7]
	v_mfma_f32_16x16x32_bf16 v[0:3], v[208:211], v[192:195], v[0:3]
	s_setprio 0
	s_add_i32 s76, s76, 2
	s_add_u32 s38, s38, 0x100
	s_addc_u32 s39, s39, 0
	s_add_u32 s74, s74, 0x100
	s_addc_u32 s75, s75, 0
	s_cmp_gt_u32 s76, 13
	s_barrier
.LBB0_1239:
	ds_read_b128 v[140:143], v149
	ds_read_b128 v[152:155], v149 offset:1024
	ds_read_b128 v[156:159], v149 offset:2048
	ds_read_b128 v[160:163], v149 offset:3072
	s_add_u32 s40, s38, 0xfffc0080
	s_addc_u32 s41, s39, -1
	s_cmp_eq_u32 s76, 12
	s_cselect_b32 s43, s29, s41
	s_cselect_b32 s42, s72, s40
	s_cselect_b32 s41, s27, s75
	s_cselect_b32 s40, s73, s74
	s_add_i32 m0, s8, 0xc000
	ds_read_b128 v[164:167], v150
	ds_read_b128 v[168:171], v150 offset:1024
	ds_read_b128 v[172:175], v150 offset:2048
	ds_read_b128 v[176:179], v150 offset:3072
	ds_read_b128 v[180:183], v150 offset:4096
	ds_read_b128 v[184:187], v150 offset:5120
	ds_read_b128 v[188:191], v150 offset:6144
	ds_read_b128 v[192:195], v150 offset:7168
	global_load_lds_dwordx4 v132, s[38:39]
	s_add_i32 m0, s8, 0xe000
	s_nop 0
	global_load_lds_dwordx4 v134, s[38:39]
	ds_read_b128 v[196:199], v151
	ds_read_b128 v[200:203], v151 offset:1024
	ds_read_b128 v[204:207], v151 offset:2048
	ds_read_b128 v[208:211], v151 offset:3072
	s_waitcnt lgkmcnt(0)
	s_barrier
; #define PG8_STAGE(bufoff, gbase, voff) do { _Pragma("unroll") for (int _i = 0; _i < 2; ++_i) \
;         __builtin_amdgcn_global_load_lds((const unsigned*)((const char*)(gbase) + (voff)[_i]), (LAS unsigned*)(lds + (bufoff) + ldsw + _i * 8192), 16, 0, 0); } while (0)
; #define PG8_LDA(dst, b, h) do { _Pragma("unroll") for (int m = 0; m < 4; ++m) _Pragma("unroll") for (int k = 0; k < 2; ++k) dst[m][k] = *(const LAS bf16x8*)(lds + PG8_SA(b, h) + aoff + m * 2048 + k * 1024); } while (0)
; #define PG8_LDB(dst, b, h) do { _Pragma("unroll") for (int n = 0; n < 2; ++n) _Pragma("unroll") for (int k = 0; k < 2; ++k) dst[n][k] = *(const LAS bf16x8*)(lds + PG8_SB(b, h) + boff + n * 2048 + k * 1024); } while (0)
; #define PG8_MMA(ai, bj, At, Bt) do { __builtin_amdgcn_s_setprio(1); _Pragma("unroll") for (int m = 0; m < 4; ++m) _Pragma("unroll") for (int n = 0; n < 2; ++n) _Pragma("unroll") for (int k = 0; k < 2; ++k) \
;         acc[ai][bj][m][n] = __builtin_amdgcn_mfma_f32_16x16x32_bf16(Bt[n][k], At[m][k], acc[ai][bj][m][n], 0, 0, 0); __builtin_amdgcn_s_setprio(0); } while (0)
; #define PG8_WAIT_V(n) asm volatile("s_waitcnt vmcnt(" #n ")" ::: "memory")
; #define PG8_WAIT_L(n) asm volatile("s_waitcnt lgkmcnt(" #n ")" ::: "memory")
; #define PG8_BAR __builtin_amdgcn_s_barrier()
; #define PG8_SCHED __builtin_amdgcn_sched_barrier(0)
; template <class Epi>
; __device__ __forceinline__ void gemm_phase(LAS unsigned char* lds, const Gemm g, const StaticOrder& S, const Epi& E) {
;     ...
;             PG8_LDB(B0, 0, 0); PG8_SCHED; PG8_LDA(At, 0, 0); PG8_STAGE(PG8_SA(1, 1), a1 + hstepA, voffA);
;             PG8_WAIT_L(8); PG8_BAR; PG8_WAIT_L(0); PG8_MMA(0, 0, At, B0); PG8_BAR; PG8_SCHED;
;             PG8_LDB(B1, 0, 1); PG8_STAGE(PG8_SB(0, 0), b2, voffB);
;             PG8_BAR; PG8_WAIT_L(0); PG8_MMA(0, 1, At, B1); PG8_BAR;
;             PG8_LDA(At, 0, 1); PG8_STAGE(PG8_SA(0, 0), a2, voffA);
;             PG8_BAR; PG8_WAIT_L(0); PG8_MMA(1, 0, At, B0); PG8_BAR; PG8_SCHED;
;             PG8_STAGE(PG8_SB(0, 1), b2 + hstepB, voffB);
;             PG8_WAIT_V(6); PG8_BAR; PG8_MMA(1, 1, At, B1); PG8_BAR;
	s_setprio 1
	v_mfma_f32_16x16x32_bf16 v[124:127], v[140:143], v[164:167], v[124:127]
	v_mfma_f32_16x16x32_bf16 v[120:123], v[156:159], v[164:167], v[120:123]
	v_mfma_f32_16x16x32_bf16 v[112:115], v[140:143], v[172:175], v[112:115]
	v_mfma_f32_16x16x32_bf16 v[104:107], v[156:159], v[172:175], v[104:107]
	v_mfma_f32_16x16x32_bf16 v[92:95], v[140:143], v[180:183], v[92:95]
	v_mfma_f32_16x16x32_bf16 v[88:91], v[156:159], v[180:183], v[88:91]
	v_mfma_f32_16x16x32_bf16 v[80:83], v[140:143], v[188:191], v[80:83]
	v_mfma_f32_16x16x32_bf16 v[72:75], v[156:159], v[188:191], v[72:75]
	v_mfma_f32_16x16x32_bf16 v[124:127], v[152:155], v[168:171], v[124:127]
	v_mfma_f32_16x16x32_bf16 v[120:123], v[160:163], v[168:171], v[120:123]
	v_mfma_f32_16x16x32_bf16 v[112:115], v[152:155], v[176:179], v[112:115]
	v_mfma_f32_16x16x32_bf16 v[104:107], v[160:163], v[176:179], v[104:107]
	v_mfma_f32_16x16x32_bf16 v[92:95], v[152:155], v[184:187], v[92:95]
	v_mfma_f32_16x16x32_bf16 v[88:91], v[160:163], v[184:187], v[88:91]
	v_mfma_f32_16x16x32_bf16 v[80:83], v[152:155], v[192:195], v[80:83]
	v_mfma_f32_16x16x32_bf16 v[72:75], v[160:163], v[192:195], v[72:75]
	v_mfma_f32_16x16x32_bf16 v[116:119], v[196:199], v[164:167], v[116:119]
	v_mfma_f32_16x16x32_bf16 v[108:111], v[204:207], v[164:167], v[108:111]
	v_mfma_f32_16x16x32_bf16 v[100:103], v[196:199], v[172:175], v[100:103]
	v_mfma_f32_16x16x32_bf16 v[96:99], v[204:207], v[172:175], v[96:99]
	v_mfma_f32_16x16x32_bf16 v[84:87], v[196:199], v[180:183], v[84:87]
	v_mfma_f32_16x16x32_bf16 v[76:79], v[204:207], v[180:183], v[76:79]
	v_mfma_f32_16x16x32_bf16 v[68:71], v[196:199], v[188:191], v[68:71]
	v_mfma_f32_16x16x32_bf16 v[64:67], v[204:207], v[188:191], v[64:67]
	v_mfma_f32_16x16x32_bf16 v[116:119], v[200:203], v[168:171], v[116:119]
	v_mfma_f32_16x16x32_bf16 v[108:111], v[208:211], v[168:171], v[108:111]
	v_mfma_f32_16x16x32_bf16 v[100:103], v[200:203], v[176:179], v[100:103]
	v_mfma_f32_16x16x32_bf16 v[96:99], v[208:211], v[176:179], v[96:99]
	v_mfma_f32_16x16x32_bf16 v[84:87], v[200:203], v[184:187], v[84:87]
	v_mfma_f32_16x16x32_bf16 v[76:79], v[208:211], v[184:187], v[76:79]
	v_mfma_f32_16x16x32_bf16 v[68:71], v[200:203], v[192:195], v[68:71]
	v_mfma_f32_16x16x32_bf16 v[64:67], v[208:211], v[192:195], v[64:67]
	s_setprio 0
	s_barrier
	s_nop 1
	ds_read_b128 v[164:167], v150 offset:16384
	ds_read_b128 v[168:171], v150 offset:17408
	ds_read_b128 v[172:175], v150 offset:18432
	ds_read_b128 v[176:179], v150 offset:19456
	ds_read_b128 v[180:183], v150 offset:20480
	ds_read_b128 v[184:187], v150 offset:21504
	ds_read_b128 v[188:191], v150 offset:22528
	ds_read_b128 v[192:195], v150 offset:23552
	s_add_i32 s77, s48, s7
	v_lshl_add_u64 v[144:145], s[40:41], 0, v[128:129]
	s_mov_b32 m0, s77
	s_nop 0
	global_load_lds_dwordx4 v128, s[40:41]
	v_lshl_add_u64 v[212:213], s[40:41], 0, v[130:131]
	s_add_i32 m0, s77, 0x2000
	s_nop 0
	global_load_lds_dwordx4 v130, s[40:41]
	s_mov_b32 m0, s8
	v_lshl_add_u64 v[214:215], s[42:43], 0, v[128:129]
	global_load_lds_dwordx4 v128, s[42:43]
	v_lshl_add_u64 v[216:217], s[42:43], 0, v[130:131]
	s_mov_b32 m0, s9
	s_nop 0
	global_load_lds_dwordx4 v130, s[42:43]
	s_add_u32 s78, s40, 0x40000
	s_addc_u32 s79, s41, 0
	s_add_i32 s77, s49, s7
	s_mov_b32 m0, s77
	s_nop 0
	global_load_lds_dwordx4 v128, s[78:79]
	s_add_i32 m0, s77, 0x2000
	s_nop 0
	global_load_lds_dwordx4 v130, s[78:79]
	s_waitcnt vmcnt(6)
	s_waitcnt lgkmcnt(0)
	s_barrier
	s_setprio 1
	v_mfma_f32_16x16x32_bf16 v[60:63], v[140:143], v[164:167], v[60:63]
	v_mfma_f32_16x16x32_bf16 v[56:59], v[156:159], v[164:167], v[56:59]
	v_mfma_f32_16x16x32_bf16 v[48:51], v[140:143], v[172:175], v[48:51]
	v_mfma_f32_16x16x32_bf16 v[40:43], v[156:159], v[172:175], v[40:43]
	v_mfma_f32_16x16x32_bf16 v[28:31], v[140:143], v[180:183], v[28:31]
	v_mfma_f32_16x16x32_bf16 v[24:27], v[156:159], v[180:183], v[24:27]
	v_mfma_f32_16x16x32_bf16 v[16:19], v[140:143], v[188:191], v[16:19]
	v_mfma_f32_16x16x32_bf16 v[8:11], v[156:159], v[188:191], v[8:11]
	v_mfma_f32_16x16x32_bf16 v[60:63], v[152:155], v[168:171], v[60:63]
	v_mfma_f32_16x16x32_bf16 v[56:59], v[160:163], v[168:171], v[56:59]
	v_mfma_f32_16x16x32_bf16 v[48:51], v[152:155], v[176:179], v[48:51]
	v_mfma_f32_16x16x32_bf16 v[40:43], v[160:163], v[176:179], v[40:43]
	v_mfma_f32_16x16x32_bf16 v[28:31], v[152:155], v[184:187], v[28:31]
	v_mfma_f32_16x16x32_bf16 v[24:27], v[160:163], v[184:187], v[24:27]
	v_mfma_f32_16x16x32_bf16 v[16:19], v[152:155], v[192:195], v[16:19]
	v_mfma_f32_16x16x32_bf16 v[8:11], v[160:163], v[192:195], v[8:11]
	v_mfma_f32_16x16x32_bf16 v[52:55], v[196:199], v[164:167], v[52:55]
	v_mfma_f32_16x16x32_bf16 v[44:47], v[204:207], v[164:167], v[44:47]
	v_mfma_f32_16x16x32_bf16 v[36:39], v[196:199], v[172:175], v[36:39]
	v_mfma_f32_16x16x32_bf16 v[32:35], v[204:207], v[172:175], v[32:35]
	v_mfma_f32_16x16x32_bf16 v[20:23], v[196:199], v[180:183], v[20:23]
	v_mfma_f32_16x16x32_bf16 v[12:15], v[204:207], v[180:183], v[12:15]
	v_mfma_f32_16x16x32_bf16 v[4:7], v[196:199], v[188:191], v[4:7]
	v_mfma_f32_16x16x32_bf16 v[0:3], v[204:207], v[188:191], v[0:3]
	v_mfma_f32_16x16x32_bf16 v[52:55], v[200:203], v[168:171], v[52:55]
	v_mfma_f32_16x16x32_bf16 v[44:47], v[208:211], v[168:171], v[44:47]
	v_mfma_f32_16x16x32_bf16 v[36:39], v[200:203], v[176:179], v[36:39]
	v_mfma_f32_16x16x32_bf16 v[32:35], v[208:211], v[176:179], v[32:35]
	v_mfma_f32_16x16x32_bf16 v[20:23], v[200:203], v[184:187], v[20:23]
	v_mfma_f32_16x16x32_bf16 v[12:15], v[208:211], v[184:187], v[12:15]
	v_mfma_f32_16x16x32_bf16 v[4:7], v[200:203], v[192:195], v[4:7]
	v_mfma_f32_16x16x32_bf16 v[0:3], v[208:211], v[192:195], v[0:3]
	s_setprio 0
	s_add_i32 s77, 0, 0x18000
	v_add_u32_e32 v160, s77, v147
	s_barrier
; #define PG8_STAGE(bufoff, gbase, voff) do { _Pragma("unroll") for (int _i = 0; _i < 2; ++_i) \
;         __builtin_amdgcn_global_load_lds((const unsigned*)((const char*)(gbase) + (voff)[_i]), (LAS unsigned*)(lds + (bufoff) + ldsw + _i * 8192), 16, 0, 0); } while (0)
; #define PG8_LDA(dst, b, h) do { _Pragma("unroll") for (int m = 0; m < 4; ++m) _Pragma("unroll") for (int k = 0; k < 2; ++k) dst[m][k] = *(const LAS bf16x8*)(lds + PG8_SA(b, h) + aoff + m * 2048 + k * 1024); } while (0)
; #define PG8_LDB(dst, b, h) do { _Pragma("unroll") for (int n = 0; n < 2; ++n) _Pragma("unroll") for (int k = 0; k < 2; ++k) dst[n][k] = *(const LAS bf16x8*)(lds + PG8_SB(b, h) + boff + n * 2048 + k * 1024); } while (0)
; #define PG8_MMA(ai, bj, At, Bt) do { __builtin_amdgcn_s_setprio(1); _Pragma("unroll") for (int m = 0; m < 4; ++m) _Pragma("unroll") for (int n = 0; n < 2; ++n) _Pragma("unroll") for (int k = 0; k < 2; ++k) \
;         acc[ai][bj][m][n] = __builtin_amdgcn_mfma_f32_16x16x32_bf16(Bt[n][k], At[m][k], acc[ai][bj][m][n], 0, 0, 0); __builtin_amdgcn_s_setprio(0); } while (0)
; #define PG8_WAIT_V(n) asm volatile("s_waitcnt vmcnt(" #n ")" ::: "memory")
; #define PG8_WAIT_L(n) asm volatile("s_waitcnt lgkmcnt(" #n ")" ::: "memory")
; #define PG8_BAR __builtin_amdgcn_s_barrier()
; #define PG8_SCHED __builtin_amdgcn_sched_barrier(0)
; template <class Epi>
; __device__ __forceinline__ void gemm_phase(LAS unsigned char* lds, const Gemm g, const StaticOrder& S, const Epi& E) {
;     ...
;             PG8_LDB(B0, 1, 0); PG8_SCHED; PG8_LDA(At, 1, 0); PG8_STAGE(PG8_SA(0, 1), a2 + hstepA, voffA);
;             PG8_WAIT_L(8); PG8_BAR; PG8_WAIT_L(0); PG8_MMA(0, 0, At, B0); PG8_BAR; PG8_SCHED;
;             PG8_LDB(B1, 1, 1); PG8_STAGE(PG8_SB(1, 0), b3, voffB);
;             PG8_BAR; PG8_WAIT_L(0); PG8_MMA(0, 1, At, B1); PG8_BAR;
;             PG8_LDA(At, 1, 1); PG8_STAGE(PG8_SA(1, 0), a3, voffA);
;             PG8_BAR; PG8_WAIT_L(0); PG8_MMA(1, 0, At, B0); PG8_BAR; PG8_SCHED;
;             PG8_STAGE(PG8_SB(1, 1), b3 + hstepB, voffB);
;             PG8_WAIT_V(6); PG8_BAR; PG8_MMA(1, 1, At, B1); PG8_BAR;
	ds_read_b128 v[140:143], v160
	ds_read_b128 v[152:155], v160 offset:1024
	ds_read_b128 v[156:159], v160 offset:2048
	ds_read_b128 v[160:163], v160 offset:3072
	s_add_u32 s42, s42, 0x40000
	s_addc_u32 s43, s43, 0
	s_mov_b32 m0, s37
	ds_read_b128 v[164:167], v150 offset:32768
	ds_read_b128 v[168:171], v150 offset:33792
	ds_read_b128 v[172:175], v150 offset:34816
	ds_read_b128 v[176:179], v150 offset:35840
	ds_read_b128 v[180:183], v150 offset:36864
	ds_read_b128 v[184:187], v150 offset:37888
	ds_read_b128 v[188:191], v150 offset:38912
	ds_read_b128 v[192:195], v150 offset:39936
	global_load_lds_dwordx4 v128, s[42:43]
	s_mov_b32 m0, s44
	s_nop 0
	global_load_lds_dwordx4 v130, s[42:43]
	s_add_i32 s42, 0, 0x1c000
	v_add_u32_e32 v208, s42, v147
	ds_read_b128 v[196:199], v208
	ds_read_b128 v[200:203], v208 offset:1024
	ds_read_b128 v[204:207], v208 offset:2048
	ds_read_b128 v[208:211], v208 offset:3072
	s_waitcnt lgkmcnt(0)
	s_barrier
	s_setprio 1
	v_mfma_f32_16x16x32_bf16 v[124:127], v[140:143], v[164:167], v[124:127]
	v_mfma_f32_16x16x32_bf16 v[120:123], v[156:159], v[164:167], v[120:123]
	v_mfma_f32_16x16x32_bf16 v[112:115], v[140:143], v[172:175], v[112:115]
	v_mfma_f32_16x16x32_bf16 v[104:107], v[156:159], v[172:175], v[104:107]
	v_mfma_f32_16x16x32_bf16 v[92:95], v[140:143], v[180:183], v[92:95]
	v_mfma_f32_16x16x32_bf16 v[88:91], v[156:159], v[180:183], v[88:91]
	v_mfma_f32_16x16x32_bf16 v[80:83], v[140:143], v[188:191], v[80:83]
	v_mfma_f32_16x16x32_bf16 v[72:75], v[156:159], v[188:191], v[72:75]
	v_mfma_f32_16x16x32_bf16 v[124:127], v[152:155], v[168:171], v[124:127]
	v_mfma_f32_16x16x32_bf16 v[120:123], v[160:163], v[168:171], v[120:123]
	v_mfma_f32_16x16x32_bf16 v[112:115], v[152:155], v[176:179], v[112:115]
	v_mfma_f32_16x16x32_bf16 v[104:107], v[160:163], v[176:179], v[104:107]
	v_mfma_f32_16x16x32_bf16 v[92:95], v[152:155], v[184:187], v[92:95]
	v_mfma_f32_16x16x32_bf16 v[88:91], v[160:163], v[184:187], v[88:91]
	v_mfma_f32_16x16x32_bf16 v[80:83], v[152:155], v[192:195], v[80:83]
	v_mfma_f32_16x16x32_bf16 v[72:75], v[160:163], v[192:195], v[72:75]
	v_mfma_f32_16x16x32_bf16 v[116:119], v[196:199], v[164:167], v[116:119]
	v_mfma_f32_16x16x32_bf16 v[108:111], v[204:207], v[164:167], v[108:111]
	v_mfma_f32_16x16x32_bf16 v[100:103], v[196:199], v[172:175], v[100:103]
	v_mfma_f32_16x16x32_bf16 v[96:99], v[204:207], v[172:175], v[96:99]
	v_mfma_f32_16x16x32_bf16 v[84:87], v[196:199], v[180:183], v[84:87]
	v_mfma_f32_16x16x32_bf16 v[76:79], v[204:207], v[180:183], v[76:79]
	v_mfma_f32_16x16x32_bf16 v[68:71], v[196:199], v[188:191], v[68:71]
	v_mfma_f32_16x16x32_bf16 v[64:67], v[204:207], v[188:191], v[64:67]
	v_mfma_f32_16x16x32_bf16 v[116:119], v[200:203], v[168:171], v[116:119]
	v_mfma_f32_16x16x32_bf16 v[108:111], v[208:211], v[168:171], v[108:111]
	v_mfma_f32_16x16x32_bf16 v[100:103], v[200:203], v[176:179], v[100:103]
	v_mfma_f32_16x16x32_bf16 v[96:99], v[208:211], v[176:179], v[96:99]
	v_mfma_f32_16x16x32_bf16 v[84:87], v[200:203], v[184:187], v[84:87]
	v_mfma_f32_16x16x32_bf16 v[76:79], v[208:211], v[184:187], v[76:79]
	v_mfma_f32_16x16x32_bf16 v[68:71], v[200:203], v[192:195], v[68:71]
	v_mfma_f32_16x16x32_bf16 v[64:67], v[208:211], v[192:195], v[64:67]
	s_setprio 0
	s_barrier
	s_nop 1
	ds_read_b128 v[164:167], v150 offset:49152
	ds_read_b128 v[168:171], v150 offset:50176
	ds_read_b128 v[172:175], v150 offset:51200
	ds_read_b128 v[176:179], v150 offset:52224
	ds_read_b128 v[180:183], v150 offset:53248
	ds_read_b128 v[184:187], v150 offset:54272
	ds_read_b128 v[188:191], v150 offset:55296
	ds_read_b128 v[192:195], v150 offset:56320
	s_add_i32 s43, s77, s7
	s_mov_b32 m0, s43
	s_nop 0
	s_add_u32 s100, s40, s12
	s_addc_u32 s101, s41, s13
	global_load_lds_dwordx4 v128, s[100:101]
	s_add_i32 m0, s43, 0x2000
	s_nop 0
	s_add_u32 s100, s40, s12
	s_addc_u32 s101, s41, s13
	global_load_lds_dwordx4 v130, s[100:101]
	s_mov_b32 m0, s46
	v_lshl_add_u64 v[254:255], v[214:215], 0, s[12:13]
	global_load_lds_dwordx4 v[254:255], off
	v_lshl_add_u64 v[144:145], v[216:217], 0, s[12:13]
	s_mov_b32 m0, s47
	s_nop 0
	global_load_lds_dwordx4 v[144:145], off
	s_add_u32 s40, s40, 0x40080
	s_addc_u32 s41, s41, 0
	s_add_i32 s42, s42, s7
	s_mov_b32 m0, s42
	s_nop 0
	global_load_lds_dwordx4 v128, s[40:41]
	s_add_i32 m0, s42, 0x2000
	s_nop 0
	global_load_lds_dwordx4 v130, s[40:41]
	s_waitcnt vmcnt(6)
	s_waitcnt lgkmcnt(0)
	s_barrier
	s_setprio 1
	v_mfma_f32_16x16x32_bf16 v[60:63], v[140:143], v[164:167], v[60:63]
	v_mfma_f32_16x16x32_bf16 v[56:59], v[156:159], v[164:167], v[56:59]
	v_mfma_f32_16x16x32_bf16 v[48:51], v[140:143], v[172:175], v[48:51]
	v_mfma_f32_16x16x32_bf16 v[40:43], v[156:159], v[172:175], v[40:43]
	v_mfma_f32_16x16x32_bf16 v[28:31], v[140:143], v[180:183], v[28:31]
	v_mfma_f32_16x16x32_bf16 v[24:27], v[156:159], v[180:183], v[24:27]
	v_mfma_f32_16x16x32_bf16 v[16:19], v[140:143], v[188:191], v[16:19]
	v_mfma_f32_16x16x32_bf16 v[8:11], v[156:159], v[188:191], v[8:11]
	v_mfma_f32_16x16x32_bf16 v[60:63], v[152:155], v[168:171], v[60:63]
	v_mfma_f32_16x16x32_bf16 v[56:59], v[160:163], v[168:171], v[56:59]
	v_mfma_f32_16x16x32_bf16 v[48:51], v[152:155], v[176:179], v[48:51]
	v_mfma_f32_16x16x32_bf16 v[40:43], v[160:163], v[176:179], v[40:43]
	v_mfma_f32_16x16x32_bf16 v[28:31], v[152:155], v[184:187], v[28:31]
	v_mfma_f32_16x16x32_bf16 v[24:27], v[160:163], v[184:187], v[24:27]
	v_mfma_f32_16x16x32_bf16 v[16:19], v[152:155], v[192:195], v[16:19]
	v_mfma_f32_16x16x32_bf16 v[8:11], v[160:163], v[192:195], v[8:11]
	v_mfma_f32_16x16x32_bf16 v[52:55], v[196:199], v[164:167], v[52:55]
	v_mfma_f32_16x16x32_bf16 v[44:47], v[204:207], v[164:167], v[44:47]
	v_mfma_f32_16x16x32_bf16 v[36:39], v[196:199], v[172:175], v[36:39]
	v_mfma_f32_16x16x32_bf16 v[32:35], v[204:207], v[172:175], v[32:35]
	v_mfma_f32_16x16x32_bf16 v[20:23], v[196:199], v[180:183], v[20:23]
	v_mfma_f32_16x16x32_bf16 v[12:15], v[204:207], v[180:183], v[12:15]
	v_mfma_f32_16x16x32_bf16 v[4:7], v[196:199], v[188:191], v[4:7]
	v_mfma_f32_16x16x32_bf16 v[0:3], v[204:207], v[188:191], v[0:3]
	v_mfma_f32_16x16x32_bf16 v[52:55], v[200:203], v[168:171], v[52:55]
	v_mfma_f32_16x16x32_bf16 v[44:47], v[208:211], v[168:171], v[44:47]
	v_mfma_f32_16x16x32_bf16 v[36:39], v[200:203], v[176:179], v[36:39]
	v_mfma_f32_16x16x32_bf16 v[32:35], v[208:211], v[176:179], v[32:35]
	v_mfma_f32_16x16x32_bf16 v[20:23], v[200:203], v[184:187], v[20:23]
	v_mfma_f32_16x16x32_bf16 v[12:15], v[208:211], v[184:187], v[12:15]
	v_mfma_f32_16x16x32_bf16 v[4:7], v[200:203], v[192:195], v[4:7]
	v_mfma_f32_16x16x32_bf16 v[0:3], v[208:211], v[192:195], v[0:3]
	s_setprio 0
	s_add_i32 s76, s76, 2
	s_add_u32 s38, s38, 0x100
	s_addc_u32 s39, s39, 0
	s_add_u32 s74, s74, 0x100
	s_addc_u32 s75, s75, 0
	s_cmp_gt_u32 s76, 13
	s_barrier
;     __device__ __forceinline__ void operator()(AccRef acc, const Unit& u, int wr, int wc, int fr, int fq) const {
;         const int row0 = u.pm * 256 + wr * 64 + fr, col0 = u.pn * 256 + wc * 32 + 4 * fq;
;         f32x4 sv[2][2], bv[2][2];
; #pragma unroll
;         for (int bj = 0; bj < 2; ++bj)
; #pragma unroll
;             for (int n = 0; n < 2; ++n) {
;                 sv[bj][n] = scale ? *(const f32x4*)(scale + col0 + bj * 128 + n * 16) : (f32x4){1.f, 1.f, 1.f, 1.f};
;                 bv[bj][n] = bias ? *(const f32x4*)(bias + col0 + bj * 128 + n * 16) : (f32x4){0.f, 0.f, 0.f, 0.f}; }
; #pragma unroll
;         for (int ai = 0; ai < 2; ++ai)
; #pragma unroll
;             for (int mh = 0; mh < 2; ++mh) {
;                 f32x4 bs[2][2][2];
; #pragma unroll
;                 for (int m = 0; m < 2; ++m)
; #pragma unroll
;                     for (int bj = 0; bj < 2; ++bj)
; #pragma unroll
;                         for (int n = 0; n < 2; ++n) bs[m][bj][n] = *(const f32x4*)(base + (size_t)(row0 + ai * 128 + (2 * mh + m) * 16) * D + col0 + bj * 128 + n * 16);
; #pragma unroll
;                 for (int m = 0; m < 2; ++m)
; #pragma unroll
;                     for (int bj = 0; bj < 2; ++bj)
; #pragma unroll
;                         for (int n = 0; n < 2; ++n) *(f32x4*)(out + (size_t)(row0 + ai * 128 + (2 * mh + m) * 16) * D + col0 + bj * 128 + n * 16) = bs[m][bj][n] + sv[bj][n] * (acc[ai][bj][2 * mh + m][n] + bv[bj][n]);
	s_cbranch_scc0 .LBB0_1239
	v_lshl_or_b32 v144, s63, 8, v148
	v_lshl_add_u32 v145, s36, 8, v146
	v_lshlrev_b32_e32 v144, 2, v144
	v_lshl_add_u32 v145, v145, 12, v144
	v_add_u32_e32 v216, 0x10000, v145
	v_add_u32_e32 v217, 0x20000, v145
	v_add_u32_e32 v218, 0x30000, v145
	v_add_u32_e32 v232, 0x80000, v145
	v_add_u32_e32 v233, 0x90000, v145
	v_add_u32_e32 v235, 0xa0000, v145
	v_add_u32_e32 v253, 0xb0000, v145
	s_and_b64 vcc, exec, s[10:11]
	s_mov_b32 s63, s26
	s_mov_b32 s36, s28
	s_mov_b64 s[40:41], s[34:35]
	s_mov_b64 s[38:39], s[30:31]
	global_load_dwordx4 v[140:143], v145, s[52:53]
	global_load_dwordx4 v[152:155], v145, s[52:53] offset:64
	global_load_dwordx4 v[156:159], v145, s[52:53] offset:512
	global_load_dwordx4 v[160:163], v145, s[52:53] offset:576
	global_load_dwordx4 v[164:167], v216, s[52:53]
	global_load_dwordx4 v[168:171], v216, s[52:53] offset:64
	global_load_dwordx4 v[172:175], v216, s[52:53] offset:512
	global_load_dwordx4 v[176:179], v216, s[52:53] offset:576
	global_load_dwordx4 v[180:183], v217, s[52:53]
	global_load_dwordx4 v[184:187], v217, s[52:53] offset:64
	global_load_dwordx4 v[188:191], v217, s[52:53] offset:512
	global_load_dwordx4 v[192:195], v217, s[52:53] offset:576
	global_load_dwordx4 v[196:199], v218, s[52:53]
	global_load_dwordx4 v[200:203], v218, s[52:53] offset:64
	global_load_dwordx4 v[204:207], v218, s[52:53] offset:512
	global_load_dwordx4 v[208:211], v218, s[52:53] offset:576
	global_load_dwordx4 v[212:215], v232, s[52:53]
	global_load_dwordx4 v[220:223], v232, s[52:53] offset:64
	global_load_dwordx4 v[224:227], v232, s[52:53] offset:512
	global_load_dwordx4 v[228:231], v232, s[52:53] offset:576
	global_load_dwordx4 v[236:239], v233, s[52:53]
	global_load_dwordx4 v[240:243], v233, s[52:53] offset:64
	global_load_dwordx4 v[244:247], v233, s[52:53] offset:512
	global_load_dwordx4 v[248:251], v233, s[52:53] offset:576
	v_pk_add_f32 v[124:125], v[124:125], 0 op_sel_hi:[1,0]
	v_pk_add_f32 v[126:127], v[126:127], 0 op_sel_hi:[1,0]
	v_pk_add_f32 v[120:121], v[120:121], 0 op_sel_hi:[1,0]
	v_pk_add_f32 v[122:123], v[122:123], 0 op_sel_hi:[1,0]
	v_pk_add_f32 v[116:117], v[116:117], 0 op_sel_hi:[1,0]
	v_pk_add_f32 v[118:119], v[118:119], 0 op_sel_hi:[1,0]
	v_pk_add_f32 v[108:109], v[108:109], 0 op_sel_hi:[1,0]
	v_pk_add_f32 v[110:111], v[110:111], 0 op_sel_hi:[1,0]
	v_pk_add_f32 v[112:113], v[112:113], 0 op_sel_hi:[1,0]
	v_pk_add_f32 v[114:115], v[114:115], 0 op_sel_hi:[1,0]
	v_pk_add_f32 v[104:105], v[104:105], 0 op_sel_hi:[1,0]
	v_pk_add_f32 v[106:107], v[106:107], 0 op_sel_hi:[1,0]
	v_pk_add_f32 v[100:101], v[100:101], 0 op_sel_hi:[1,0]
	v_pk_add_f32 v[102:103], v[102:103], 0 op_sel_hi:[1,0]
	v_pk_add_f32 v[96:97], v[96:97], 0 op_sel_hi:[1,0]
	v_pk_add_f32 v[98:99], v[98:99], 0 op_sel_hi:[1,0]
	v_pk_add_f32 v[92:93], v[92:93], 0 op_sel_hi:[1,0]
	v_pk_add_f32 v[94:95], v[94:95], 0 op_sel_hi:[1,0]
	v_pk_add_f32 v[88:89], v[88:89], 0 op_sel_hi:[1,0]
	v_pk_add_f32 v[90:91], v[90:91], 0 op_sel_hi:[1,0]
	v_pk_add_f32 v[84:85], v[84:85], 0 op_sel_hi:[1,0]
	v_pk_add_f32 v[86:87], v[86:87], 0 op_sel_hi:[1,0]
	v_pk_add_f32 v[76:77], v[76:77], 0 op_sel_hi:[1,0]
	v_pk_add_f32 v[78:79], v[78:79], 0 op_sel_hi:[1,0]
	v_pk_add_f32 v[80:81], v[80:81], 0 op_sel_hi:[1,0]
	v_pk_add_f32 v[82:83], v[82:83], 0 op_sel_hi:[1,0]
	v_pk_add_f32 v[72:73], v[72:73], 0 op_sel_hi:[1,0]
	v_pk_add_f32 v[74:75], v[74:75], 0 op_sel_hi:[1,0]
	v_pk_add_f32 v[68:69], v[68:69], 0 op_sel_hi:[1,0]
	v_pk_add_f32 v[70:71], v[70:71], 0 op_sel_hi:[1,0]
	v_pk_add_f32 v[64:65], v[64:65], 0 op_sel_hi:[1,0]
	v_pk_add_f32 v[66:67], v[66:67], 0 op_sel_hi:[1,0]
	v_pk_add_f32 v[60:61], v[60:61], 0 op_sel_hi:[1,0]
	v_pk_add_f32 v[62:63], v[62:63], 0 op_sel_hi:[1,0]
	v_pk_add_f32 v[56:57], v[56:57], 0 op_sel_hi:[1,0]
	v_pk_add_f32 v[58:59], v[58:59], 0 op_sel_hi:[1,0]
	v_pk_add_f32 v[52:53], v[52:53], 0 op_sel_hi:[1,0]
	v_pk_add_f32 v[54:55], v[54:55], 0 op_sel_hi:[1,0]
	v_pk_add_f32 v[44:45], v[44:45], 0 op_sel_hi:[1,0]
	v_pk_add_f32 v[46:47], v[46:47], 0 op_sel_hi:[1,0]
	v_pk_add_f32 v[48:49], v[48:49], 0 op_sel_hi:[1,0]
	v_pk_add_f32 v[50:51], v[50:51], 0 op_sel_hi:[1,0]
	v_pk_add_f32 v[40:41], v[40:41], 0 op_sel_hi:[1,0]
	v_pk_add_f32 v[42:43], v[42:43], 0 op_sel_hi:[1,0]
	v_pk_add_f32 v[36:37], v[36:37], 0 op_sel_hi:[1,0]
	v_pk_add_f32 v[38:39], v[38:39], 0 op_sel_hi:[1,0]
	v_pk_add_f32 v[32:33], v[32:33], 0 op_sel_hi:[1,0]
	v_pk_add_f32 v[34:35], v[34:35], 0 op_sel_hi:[1,0]
	v_pk_add_f32 v[28:29], v[28:29], 0 op_sel_hi:[1,0]
	v_pk_add_f32 v[30:31], v[30:31], 0 op_sel_hi:[1,0]
	v_pk_add_f32 v[24:25], v[24:25], 0 op_sel_hi:[1,0]
	v_pk_add_f32 v[26:27], v[26:27], 0 op_sel_hi:[1,0]
	v_pk_add_f32 v[20:21], v[20:21], 0 op_sel_hi:[1,0]
	v_pk_add_f32 v[22:23], v[22:23], 0 op_sel_hi:[1,0]
	v_pk_add_f32 v[12:13], v[12:13], 0 op_sel_hi:[1,0]
	v_pk_add_f32 v[14:15], v[14:15], 0 op_sel_hi:[1,0]
	v_pk_add_f32 v[16:17], v[16:17], 0 op_sel_hi:[1,0]
	v_pk_add_f32 v[18:19], v[18:19], 0 op_sel_hi:[1,0]
	v_pk_add_f32 v[8:9], v[8:9], 0 op_sel_hi:[1,0]
	v_pk_add_f32 v[10:11], v[10:11], 0 op_sel_hi:[1,0]
	v_pk_add_f32 v[4:5], v[4:5], 0 op_sel_hi:[1,0]
	v_pk_add_f32 v[6:7], v[6:7], 0 op_sel_hi:[1,0]
	v_pk_add_f32 v[0:1], v[0:1], 0 op_sel_hi:[1,0]
	v_pk_add_f32 v[2:3], v[2:3], 0 op_sel_hi:[1,0]
	s_waitcnt vmcnt(16)
;     __device__ __forceinline__ void operator()(AccRef acc, const Unit& u, int wr, int wc, int fr, int fq) const {
;     ...
;                         for (int n = 0; n < 2; ++n) bs[m][bj][n] = *(const f32x4*)(base + (size_t)(row0 + ai * 128 + (2 * mh + m) * 16) * D + col0 + bj * 128 + n * 16);
; #pragma unroll
;                 for (int m = 0; m < 2; ++m)
; #pragma unroll
;                     for (int bj = 0; bj < 2; ++bj)
; #pragma unroll
;                         for (int n = 0; n < 2; ++n) *(f32x4*)(out + (size_t)(row0 + ai * 128 + (2 * mh + m) * 16) * D + col0 + bj * 128 + n * 16) = bs[m][bj][n] + sv[bj][n] * (acc[ai][bj][2 * mh + m][n] + bv[bj][n]);
;                 asm volatile("" ::: "memory"); }
	v_pk_add_f32 v[124:125], v[124:125], v[140:141]
	v_pk_add_f32 v[126:127], v[126:127], v[142:143]
	v_pk_add_f32 v[120:121], v[120:121], v[152:153]
	v_pk_add_f32 v[122:123], v[122:123], v[154:155]
	v_pk_add_f32 v[116:117], v[116:117], v[156:157]
	v_pk_add_f32 v[118:119], v[118:119], v[158:159]
	v_pk_add_f32 v[108:109], v[108:109], v[160:161]
	v_pk_add_f32 v[110:111], v[110:111], v[162:163]
	v_pk_add_f32 v[112:113], v[112:113], v[164:165]
	v_pk_add_f32 v[114:115], v[114:115], v[166:167]
	v_pk_add_f32 v[104:105], v[104:105], v[168:169]
	v_pk_add_f32 v[106:107], v[106:107], v[170:171]
	v_pk_add_f32 v[100:101], v[100:101], v[172:173]
	v_pk_add_f32 v[102:103], v[102:103], v[174:175]
	v_pk_add_f32 v[96:97], v[96:97], v[176:177]
	v_pk_add_f32 v[98:99], v[98:99], v[178:179]
	global_store_dwordx4 v145, v[124:127], s[52:53]
	global_store_dwordx4 v145, v[120:123], s[52:53] offset:64
	global_store_dwordx4 v145, v[116:119], s[52:53] offset:512
	global_store_dwordx4 v145, v[108:111], s[52:53] offset:576
	global_store_dwordx4 v216, v[112:115], s[52:53]
	global_store_dwordx4 v216, v[104:107], s[52:53] offset:64
	global_store_dwordx4 v216, v[100:103], s[52:53] offset:512
	global_store_dwordx4 v216, v[96:99], s[52:53] offset:576
	global_load_dwordx4 v[140:143], v235, s[52:53]
	global_load_dwordx4 v[152:155], v235, s[52:53] offset:64
	global_load_dwordx4 v[156:159], v235, s[52:53] offset:512
	global_load_dwordx4 v[160:163], v235, s[52:53] offset:576
	global_load_dwordx4 v[164:167], v253, s[52:53]
	global_load_dwordx4 v[168:171], v253, s[52:53] offset:64
	global_load_dwordx4 v[172:175], v253, s[52:53] offset:512
	global_load_dwordx4 v[176:179], v253, s[52:53] offset:576
	s_waitcnt vmcnt(24)
	v_pk_add_f32 v[92:93], v[92:93], v[180:181]
	v_pk_add_f32 v[94:95], v[94:95], v[182:183]
	v_pk_add_f32 v[88:89], v[88:89], v[184:185]
	v_pk_add_f32 v[90:91], v[90:91], v[186:187]
	v_pk_add_f32 v[84:85], v[84:85], v[188:189]
	v_pk_add_f32 v[86:87], v[86:87], v[190:191]
	v_pk_add_f32 v[76:77], v[76:77], v[192:193]
	v_pk_add_f32 v[78:79], v[78:79], v[194:195]
	v_pk_add_f32 v[80:81], v[80:81], v[196:197]
	v_pk_add_f32 v[82:83], v[82:83], v[198:199]
	v_pk_add_f32 v[72:73], v[72:73], v[200:201]
	v_pk_add_f32 v[74:75], v[74:75], v[202:203]
	v_pk_add_f32 v[68:69], v[68:69], v[204:205]
	v_pk_add_f32 v[70:71], v[70:71], v[206:207]
	v_pk_add_f32 v[64:65], v[64:65], v[208:209]
	v_pk_add_f32 v[66:67], v[66:67], v[210:211]
	global_store_dwordx4 v217, v[92:95], s[52:53]
	global_store_dwordx4 v217, v[88:91], s[52:53] offset:64
	global_store_dwordx4 v217, v[84:87], s[52:53] offset:512
	global_store_dwordx4 v217, v[76:79], s[52:53] offset:576
	global_store_dwordx4 v218, v[80:83], s[52:53]
	global_store_dwordx4 v218, v[72:75], s[52:53] offset:64
	global_store_dwordx4 v218, v[68:71], s[52:53] offset:512
	global_store_dwordx4 v218, v[64:67], s[52:53] offset:576
	s_waitcnt vmcnt(24)
	v_pk_add_f32 v[60:61], v[60:61], v[212:213]
	v_pk_add_f32 v[62:63], v[62:63], v[214:215]
	v_pk_add_f32 v[56:57], v[56:57], v[220:221]
	v_pk_add_f32 v[58:59], v[58:59], v[222:223]
	v_pk_add_f32 v[52:53], v[52:53], v[224:225]
	v_pk_add_f32 v[54:55], v[54:55], v[226:227]
	v_pk_add_f32 v[44:45], v[44:45], v[228:229]
	v_pk_add_f32 v[46:47], v[46:47], v[230:231]
	v_pk_add_f32 v[48:49], v[48:49], v[236:237]
	v_pk_add_f32 v[50:51], v[50:51], v[238:239]
	v_pk_add_f32 v[40:41], v[40:41], v[240:241]
	v_pk_add_f32 v[42:43], v[42:43], v[242:243]
	v_pk_add_f32 v[36:37], v[36:37], v[244:245]
	v_pk_add_f32 v[38:39], v[38:39], v[246:247]
	v_pk_add_f32 v[32:33], v[32:33], v[248:249]
	v_pk_add_f32 v[34:35], v[34:35], v[250:251]
	global_store_dwordx4 v232, v[60:63], s[52:53]
	global_store_dwordx4 v232, v[56:59], s[52:53] offset:64
	global_store_dwordx4 v232, v[52:55], s[52:53] offset:512
	global_store_dwordx4 v232, v[44:47], s[52:53] offset:576
	global_store_dwordx4 v233, v[48:51], s[52:53]
	global_store_dwordx4 v233, v[40:43], s[52:53] offset:64
	global_store_dwordx4 v233, v[36:39], s[52:53] offset:512
	global_store_dwordx4 v233, v[32:35], s[52:53] offset:576
	s_waitcnt vmcnt(16)
	v_pk_add_f32 v[28:29], v[28:29], v[140:141]
	v_pk_add_f32 v[30:31], v[30:31], v[142:143]
	v_pk_add_f32 v[24:25], v[24:25], v[152:153]
	v_pk_add_f32 v[26:27], v[26:27], v[154:155]
	v_pk_add_f32 v[20:21], v[20:21], v[156:157]
	v_pk_add_f32 v[22:23], v[22:23], v[158:159]
	v_pk_add_f32 v[12:13], v[12:13], v[160:161]
	v_pk_add_f32 v[14:15], v[14:15], v[162:163]
	v_pk_add_f32 v[16:17], v[16:17], v[164:165]
	v_pk_add_f32 v[18:19], v[18:19], v[166:167]
	v_pk_add_f32 v[8:9], v[8:9], v[168:169]
	v_pk_add_f32 v[10:11], v[10:11], v[170:171]
	v_pk_add_f32 v[4:5], v[4:5], v[172:173]
	v_pk_add_f32 v[6:7], v[6:7], v[174:175]
	v_pk_add_f32 v[0:1], v[0:1], v[176:177]
	v_pk_add_f32 v[2:3], v[2:3], v[178:179]
	global_store_dwordx4 v235, v[28:31], s[52:53]
	global_store_dwordx4 v235, v[24:27], s[52:53] offset:64
	global_store_dwordx4 v235, v[20:23], s[52:53] offset:512
	global_store_dwordx4 v235, v[12:15], s[52:53] offset:576
	global_store_dwordx4 v253, v[16:19], s[52:53]
	global_store_dwordx4 v253, v[8:11], s[52:53] offset:64
	global_store_dwordx4 v253, v[4:7], s[52:53] offset:512
	global_store_dwordx4 v253, v[0:3], s[52:53] offset:576
	s_cbranch_vccz .LBB0_1232
	s_waitcnt vmcnt(0)
	s_cmpk_gt_u32 s4, 0xff
	s_cbranch_scc1 .LBB0_1243
	s_barrier

; #define PG8_STAGE(bufoff, gbase, voff) do { _Pragma("unroll") for (int _i = 0; _i < 2; ++_i) \
;         __builtin_amdgcn_global_load_lds((const unsigned*)((const char*)(gbase) + (voff)[_i]), (LAS unsigned*)(lds + (bufoff) + ldsw + _i * 8192), 16, 0, 0); } while (0)
; #define PG8_LDA(dst, b, h) do { _Pragma("unroll") for (int m = 0; m < 4; ++m) _Pragma("unroll") for (int k = 0; k < 2; ++k) dst[m][k] = *(const LAS bf16x8*)(lds + PG8_SA(b, h) + aoff + m * 2048 + k * 1024); } while (0)
; #define PG8_LDB(dst, b, h) do { _Pragma("unroll") for (int n = 0; n < 2; ++n) _Pragma("unroll") for (int k = 0; k < 2; ++k) dst[n][k] = *(const LAS bf16x8*)(lds + PG8_SB(b, h) + boff + n * 2048 + k * 1024); } while (0)
; #define PG8_WAIT_V(n) asm volatile("s_waitcnt vmcnt(" #n ")" ::: "memory")
; #define PG8_WAIT_L(n) asm volatile("s_waitcnt lgkmcnt(" #n ")" ::: "memory")
; #define PG8_BAR __builtin_amdgcn_s_barrier()
; #define PG8_SCHED __builtin_amdgcn_sched_barrier(0)
; template <class Epi>
; __device__ __forceinline__ void gemm_phase(LAS unsigned char* lds, const Gemm g, const StaticOrder& S, const Epi& E) {
;     ...
;         const bool has_next = S.next(ui + 1, nxt);
;         const char* nA = has_next ? (const char*)g.A + (size_t)nxt.pm * tstepA + (size_t)(nxt.pn >> g.a_shift) * g.a_step : cA; const char* nB = has_next ? (const char*)g.Bt + (size_t)nxt.pn * tstepB : cB;
;         for (int t = 0; t < nt; t += 2) {
;             const bool last = (t == nt - 2);
;             const char* a1 = cA + (size_t)(t + 1) * kstep;
;             const char* a2 = last ? nA : cA + (size_t)(t + 2) * kstep; const char* b2 = last ? nB : cB + (size_t)(t + 2) * kstep;
;             const char* a3 = a2 + kstep; const char* b3 = b2 + kstep;
;             PG8_LDB(B0, 0, 0); PG8_SCHED; PG8_LDA(At, 0, 0); PG8_STAGE(PG8_SA(1, 1), a1 + hstepA, voffA);
;             PG8_WAIT_L(8); PG8_BAR; PG8_WAIT_L(0); PG8_MMA(0, 0, At, B0); PG8_BAR; PG8_SCHED;
;             PG8_LDB(B1, 0, 1); PG8_STAGE(PG8_SB(0, 0), b2, voffB);
;             PG8_BAR; PG8_WAIT_L(0); PG8_MMA(0, 1, At, B1); PG8_BAR;
;             PG8_LDA(At, 0, 1); PG8_STAGE(PG8_SA(0, 0), a2, voffA);
;             PG8_BAR; PG8_WAIT_L(0); PG8_MMA(1, 0, At, B0); PG8_BAR; PG8_SCHED;
;             PG8_STAGE(PG8_SB(0, 1), b2 + hstepB, voffB);
;             PG8_WAIT_V(6); PG8_BAR; PG8_MMA(1, 1, At, B1); PG8_BAR;
.LBB0_1358:
	s_ashr_i32 s37, s36, 31
	v_cmp_lt_i64_e32 vcc, s[38:39], v[228:229]
	s_lshl_b64 s[38:39], s[36:37], 19
	s_add_u32 s38, s66, s38
	s_addc_u32 s39, s67, s39
	s_and_b64 s[40:41], vcc, exec
	s_cselect_b32 s37, s39, s45
	s_cselect_b32 s83, s38, s44
	s_ashr_i32 s35, s34, 31
	s_lshl_b64 s[40:41], s[34:35], 19
	s_add_u32 s40, s5, s40
	s_addc_u32 s41, s6, s41
	s_and_b64 s[48:49], vcc, exec
	s_cselect_b32 s35, s41, s47
	s_cselect_b32 s84, s40, s46
	s_add_u32 s85, s46, 0x100
	s_addc_u32 s86, s47, 0
	s_mov_b32 s87, -2
	ds_read_b128 v[96:99], v243
	ds_read_b128 v[100:103], v243 offset:1024
	ds_read_b128 v[104:107], v243 offset:2048
	ds_read_b128 v[108:111], v243 offset:3072
	s_add_u32 s46, s44, 0x100
	s_addc_u32 s47, s45, 0
	s_cmp_eq_u32 s87, 12
	s_cselect_b32 s73, s37, s47
	s_cselect_b32 s72, s83, s46
	s_cselect_b32 s49, s35, s86
	s_cselect_b32 s48, s84, s85
	s_add_i32 m0, s9, 0xc000
	ds_read_b128 v[112:115], v244
	ds_read_b128 v[116:119], v244 offset:1024
	ds_read_b128 v[120:123], v244 offset:2048
	ds_read_b128 v[124:127], v244 offset:3072
	ds_read_b128 v[160:163], v244 offset:4096
	ds_read_b128 v[164:167], v244 offset:5120
	ds_read_b128 v[168:171], v244 offset:6144
	ds_read_b128 v[172:175], v244 offset:7168
	global_load_lds_dwordx4 v224, s[44:45]
	s_add_i32 m0, s9, 0xe000
	s_nop 0
	global_load_lds_dwordx4 v226, s[44:45]
	ds_read_b128 v[176:179], v245
	ds_read_b128 v[180:183], v245 offset:1024
	ds_read_b128 v[184:187], v245 offset:2048
	ds_read_b128 v[188:191], v245 offset:3072
	s_waitcnt lgkmcnt(0)
	s_barrier
	s_setprio 1
	v_mfma_f32_16x16x32_bf16 v[156:159], v[96:99], v[112:115], 0
	v_mfma_f32_16x16x32_bf16 v[60:63], v[104:107], v[112:115], 0
	v_mfma_f32_16x16x32_bf16 v[144:147], v[96:99], v[120:123], 0
	v_mfma_f32_16x16x32_bf16 v[48:51], v[104:107], v[120:123], 0
	v_mfma_f32_16x16x32_bf16 v[136:139], v[96:99], v[160:163], 0
	v_mfma_f32_16x16x32_bf16 v[40:43], v[104:107], v[160:163], 0
	v_mfma_f32_16x16x32_bf16 v[148:151], v[96:99], v[168:171], 0
	v_mfma_f32_16x16x32_bf16 v[52:55], v[104:107], v[168:171], 0
	v_mfma_f32_16x16x32_bf16 v[156:159], v[100:103], v[116:119], v[156:159]
	v_mfma_f32_16x16x32_bf16 v[60:63], v[108:111], v[116:119], v[60:63]
	v_mfma_f32_16x16x32_bf16 v[144:147], v[100:103], v[124:127], v[144:147]
	v_mfma_f32_16x16x32_bf16 v[48:51], v[108:111], v[124:127], v[48:51]
	v_mfma_f32_16x16x32_bf16 v[136:139], v[100:103], v[164:167], v[136:139]
	v_mfma_f32_16x16x32_bf16 v[40:43], v[108:111], v[164:167], v[40:43]
	v_mfma_f32_16x16x32_bf16 v[148:151], v[100:103], v[172:175], v[148:151]
	v_mfma_f32_16x16x32_bf16 v[52:55], v[108:111], v[172:175], v[52:55]
	v_mfma_f32_16x16x32_bf16 v[152:155], v[176:179], v[112:115], 0
	v_mfma_f32_16x16x32_bf16 v[56:59], v[184:187], v[112:115], 0
	v_mfma_f32_16x16x32_bf16 v[36:39], v[184:187], v[120:123], 0
	v_mfma_f32_16x16x32_bf16 v[32:35], v[184:187], v[160:163], 0
	v_mfma_f32_16x16x32_bf16 v[44:47], v[184:187], v[168:171], 0
	v_mfma_f32_16x16x32_bf16 v[152:155], v[180:183], v[116:119], v[152:155]
	v_mfma_f32_16x16x32_bf16 v[56:59], v[188:191], v[116:119], v[56:59]
	v_mfma_f32_16x16x32_bf16 v[112:115], v[176:179], v[120:123], 0
	v_mfma_f32_16x16x32_bf16 v[36:39], v[188:191], v[124:127], v[36:39]
	v_mfma_f32_16x16x32_bf16 v[116:119], v[176:179], v[160:163], 0
	v_mfma_f32_16x16x32_bf16 v[32:35], v[188:191], v[164:167], v[32:35]
	v_mfma_f32_16x16x32_bf16 v[120:123], v[176:179], v[168:171], 0
	v_mfma_f32_16x16x32_bf16 v[44:47], v[188:191], v[172:175], v[44:47]
	v_mfma_f32_16x16x32_bf16 v[112:115], v[180:183], v[124:127], v[112:115]
	v_mfma_f32_16x16x32_bf16 v[116:119], v[180:183], v[164:167], v[116:119]
	v_mfma_f32_16x16x32_bf16 v[120:123], v[180:183], v[172:175], v[120:123]
	s_setprio 0
	s_barrier
	s_nop 1
	ds_read_b128 v[124:127], v244 offset:16384
	ds_read_b128 v[128:131], v244 offset:17408
	ds_read_b128 v[132:135], v244 offset:18432
	ds_read_b128 v[140:143], v244 offset:19456
	ds_read_b128 v[160:163], v244 offset:20480
	ds_read_b128 v[164:167], v244 offset:21504
	ds_read_b128 v[168:171], v244 offset:22528
	ds_read_b128 v[172:175], v244 offset:23552
	s_add_i32 s44, s80, s7
	v_lshl_add_u64 v[196:197], s[48:49], 0, v[214:215]
	s_mov_b32 m0, s44
	s_nop 0
	global_load_lds_dwordx4 v214, s[48:49]
	v_lshl_add_u64 v[198:199], s[48:49], 0, v[210:211]
	s_add_i32 m0, s44, 0x2000
	s_nop 0
	global_load_lds_dwordx4 v210, s[48:49]
	s_mov_b32 m0, s9
	v_lshl_add_u64 v[200:201], s[72:73], 0, v[216:217]
	global_load_lds_dwordx4 v216, s[72:73]
	v_lshl_add_u64 v[202:203], s[72:73], 0, v[212:213]
	s_mov_b32 m0, s63
	s_nop 0
	global_load_lds_dwordx4 v212, s[72:73]
	s_add_u32 s44, s48, 0x40000
	s_addc_u32 s45, s49, 0
	s_add_i32 s88, s81, s7
	s_mov_b32 m0, s88
	s_nop 0
	global_load_lds_dwordx4 v214, s[44:45]
	s_add_i32 m0, s88, 0x2000
	s_nop 0
	global_load_lds_dwordx4 v210, s[44:45]
	s_waitcnt vmcnt(6)
	s_waitcnt lgkmcnt(0)
	s_barrier
; #define PG8_STAGE(bufoff, gbase, voff) do { _Pragma("unroll") for (int _i = 0; _i < 2; ++_i) \
;         __builtin_amdgcn_global_load_lds((const unsigned*)((const char*)(gbase) + (voff)[_i]), (LAS unsigned*)(lds + (bufoff) + ldsw + _i * 8192), 16, 0, 0); } while (0)
; #define PG8_LDA(dst, b, h) do { _Pragma("unroll") for (int m = 0; m < 4; ++m) _Pragma("unroll") for (int k = 0; k < 2; ++k) dst[m][k] = *(const LAS bf16x8*)(lds + PG8_SA(b, h) + aoff + m * 2048 + k * 1024); } while (0)
; #define PG8_LDB(dst, b, h) do { _Pragma("unroll") for (int n = 0; n < 2; ++n) _Pragma("unroll") for (int k = 0; k < 2; ++k) dst[n][k] = *(const LAS bf16x8*)(lds + PG8_SB(b, h) + boff + n * 2048 + k * 1024); } while (0)
; #define PG8_MMA(ai, bj, At, Bt) do { __builtin_amdgcn_s_setprio(1); _Pragma("unroll") for (int m = 0; m < 4; ++m) _Pragma("unroll") for (int n = 0; n < 2; ++n) _Pragma("unroll") for (int k = 0; k < 2; ++k) \
;         acc[ai][bj][m][n] = __builtin_amdgcn_mfma_f32_16x16x32_bf16(Bt[n][k], At[m][k], acc[ai][bj][m][n], 0, 0, 0); __builtin_amdgcn_s_setprio(0); } while (0)
; #define PG8_WAIT_V(n) asm volatile("s_waitcnt vmcnt(" #n ")" ::: "memory")
; #define PG8_WAIT_L(n) asm volatile("s_waitcnt lgkmcnt(" #n ")" ::: "memory")
; #define PG8_BAR __builtin_amdgcn_s_barrier()
; #define PG8_SCHED __builtin_amdgcn_sched_barrier(0)
; template <class Epi>
; __device__ __forceinline__ void gemm_phase(LAS unsigned char* lds, const Gemm g, const StaticOrder& S, const Epi& E) {
;     ...
;             PG8_WAIT_V(6); PG8_BAR; PG8_MMA(1, 1, At, B1); PG8_BAR;
;             PG8_LDB(B0, 1, 0); PG8_SCHED; PG8_LDA(At, 1, 0); PG8_STAGE(PG8_SA(0, 1), a2 + hstepA, voffA);
;             PG8_WAIT_L(8); PG8_BAR; PG8_WAIT_L(0); PG8_MMA(0, 0, At, B0); PG8_BAR; PG8_SCHED;
;             PG8_LDB(B1, 1, 1); PG8_STAGE(PG8_SB(1, 0), b3, voffB);
;             PG8_BAR; PG8_WAIT_L(0); PG8_MMA(0, 1, At, B1); PG8_BAR;
	s_setprio 1
	v_mfma_f32_16x16x32_bf16 v[92:95], v[96:99], v[124:127], 0
	v_mfma_f32_16x16x32_bf16 v[28:31], v[104:107], v[124:127], 0
	v_mfma_f32_16x16x32_bf16 v[80:83], v[96:99], v[132:135], 0
	v_mfma_f32_16x16x32_bf16 v[16:19], v[104:107], v[132:135], 0
	v_mfma_f32_16x16x32_bf16 v[76:79], v[96:99], v[160:163], 0
	v_mfma_f32_16x16x32_bf16 v[12:15], v[104:107], v[160:163], 0
	v_mfma_f32_16x16x32_bf16 v[84:87], v[96:99], v[168:171], 0
	v_mfma_f32_16x16x32_bf16 v[20:23], v[104:107], v[168:171], 0
	v_mfma_f32_16x16x32_bf16 v[92:95], v[100:103], v[128:131], v[92:95]
	v_mfma_f32_16x16x32_bf16 v[28:31], v[108:111], v[128:131], v[28:31]
	v_mfma_f32_16x16x32_bf16 v[80:83], v[100:103], v[140:143], v[80:83]
	v_mfma_f32_16x16x32_bf16 v[16:19], v[108:111], v[140:143], v[16:19]
	v_mfma_f32_16x16x32_bf16 v[76:79], v[100:103], v[164:167], v[76:79]
	v_mfma_f32_16x16x32_bf16 v[12:15], v[108:111], v[164:167], v[12:15]
	v_mfma_f32_16x16x32_bf16 v[84:87], v[100:103], v[172:175], v[84:87]
	v_mfma_f32_16x16x32_bf16 v[20:23], v[108:111], v[172:175], v[20:23]
	v_mfma_f32_16x16x32_bf16 v[88:91], v[176:179], v[124:127], 0
	v_mfma_f32_16x16x32_bf16 v[24:27], v[184:187], v[124:127], 0
	v_mfma_f32_16x16x32_bf16 v[68:71], v[176:179], v[132:135], 0
	v_mfma_f32_16x16x32_bf16 v[4:7], v[184:187], v[132:135], 0
	v_mfma_f32_16x16x32_bf16 v[64:67], v[176:179], v[160:163], 0
	v_mfma_f32_16x16x32_bf16 v[0:3], v[184:187], v[160:163], 0
	v_mfma_f32_16x16x32_bf16 v[72:75], v[176:179], v[168:171], 0
	v_mfma_f32_16x16x32_bf16 v[8:11], v[184:187], v[168:171], 0
	v_mfma_f32_16x16x32_bf16 v[88:91], v[180:183], v[128:131], v[88:91]
	v_mfma_f32_16x16x32_bf16 v[24:27], v[188:191], v[128:131], v[24:27]
	v_mfma_f32_16x16x32_bf16 v[68:71], v[180:183], v[140:143], v[68:71]
	v_mfma_f32_16x16x32_bf16 v[4:7], v[188:191], v[140:143], v[4:7]
	v_mfma_f32_16x16x32_bf16 v[64:67], v[180:183], v[164:167], v[64:67]
	v_mfma_f32_16x16x32_bf16 v[0:3], v[188:191], v[164:167], v[0:3]
	v_mfma_f32_16x16x32_bf16 v[72:75], v[180:183], v[172:175], v[72:75]
	v_mfma_f32_16x16x32_bf16 v[8:11], v[188:191], v[172:175], v[8:11]
	s_setprio 0
	s_add_i32 s88, 0, 0x18000
	v_add_u32_e32 v108, s88, v235
	s_barrier
	ds_read_b128 v[96:99], v108
	ds_read_b128 v[100:103], v108 offset:1024
	ds_read_b128 v[104:107], v108 offset:2048
	ds_read_b128 v[108:111], v108 offset:3072
	s_add_u32 s44, s72, 0x40000
	s_addc_u32 s45, s73, 0
	s_mov_b32 m0, s74
	ds_read_b128 v[124:127], v244 offset:32768
	ds_read_b128 v[128:131], v244 offset:33792
	ds_read_b128 v[140:143], v244 offset:34816
	ds_read_b128 v[160:163], v244 offset:35840
	ds_read_b128 v[164:167], v244 offset:36864
	ds_read_b128 v[168:171], v244 offset:37888
	ds_read_b128 v[172:175], v244 offset:38912
	ds_read_b128 v[176:179], v244 offset:39936
	global_load_lds_dwordx4 v216, s[44:45]
	v_lshl_add_u64 v[132:133], s[44:45], 0, v[212:213]
	s_mov_b32 m0, s75
	s_nop 0
	global_load_lds_dwordx4 v212, s[44:45]
	s_add_i32 s72, 0, 0x1c000
	v_add_u32_e32 v132, s72, v235
	ds_read_b128 v[180:183], v132
	ds_read_b128 v[184:187], v132 offset:1024
	ds_read_b128 v[188:191], v132 offset:2048
	ds_read_b128 v[192:195], v132 offset:3072
	s_waitcnt lgkmcnt(0)
	s_barrier
	s_setprio 1
	v_mfma_f32_16x16x32_bf16 v[132:135], v[96:99], v[124:127], v[156:159]
	v_mfma_f32_16x16x32_bf16 v[156:159], v[100:103], v[128:131], v[132:135]
	v_mfma_f32_16x16x32_bf16 v[132:135], v[96:99], v[140:143], v[144:147]
	v_mfma_f32_16x16x32_bf16 v[144:147], v[100:103], v[160:163], v[132:135]
	v_mfma_f32_16x16x32_bf16 v[132:135], v[96:99], v[164:167], v[136:139]
	v_mfma_f32_16x16x32_bf16 v[60:63], v[104:107], v[124:127], v[60:63]
	v_mfma_f32_16x16x32_bf16 v[48:51], v[104:107], v[140:143], v[48:51]
	v_mfma_f32_16x16x32_bf16 v[136:139], v[100:103], v[168:171], v[132:135]
	v_mfma_f32_16x16x32_bf16 v[40:43], v[104:107], v[164:167], v[40:43]
	v_mfma_f32_16x16x32_bf16 v[132:135], v[96:99], v[172:175], v[148:151]
	v_mfma_f32_16x16x32_bf16 v[52:55], v[104:107], v[172:175], v[52:55]
	v_mfma_f32_16x16x32_bf16 v[60:63], v[108:111], v[128:131], v[60:63]
	v_mfma_f32_16x16x32_bf16 v[48:51], v[108:111], v[160:163], v[48:51]
	v_mfma_f32_16x16x32_bf16 v[40:43], v[108:111], v[168:171], v[40:43]
	v_mfma_f32_16x16x32_bf16 v[148:151], v[100:103], v[176:179], v[132:135]
	v_mfma_f32_16x16x32_bf16 v[52:55], v[108:111], v[176:179], v[52:55]
	v_mfma_f32_16x16x32_bf16 v[132:135], v[180:183], v[124:127], v[152:155]
	v_mfma_f32_16x16x32_bf16 v[112:115], v[180:183], v[140:143], v[112:115]
	v_mfma_f32_16x16x32_bf16 v[152:155], v[184:187], v[128:131], v[132:135]
	v_mfma_f32_16x16x32_bf16 v[56:59], v[188:191], v[124:127], v[56:59]
	v_mfma_f32_16x16x32_bf16 v[132:135], v[184:187], v[160:163], v[112:115]
	v_mfma_f32_16x16x32_bf16 v[112:115], v[180:183], v[164:167], v[116:119]
	v_mfma_f32_16x16x32_bf16 v[56:59], v[192:195], v[128:131], v[56:59]
	v_mfma_f32_16x16x32_bf16 v[36:39], v[188:191], v[140:143], v[36:39]
	v_mfma_f32_16x16x32_bf16 v[128:131], v[184:187], v[168:171], v[112:115]
	v_mfma_f32_16x16x32_bf16 v[32:35], v[188:191], v[164:167], v[32:35]
	v_mfma_f32_16x16x32_bf16 v[112:115], v[180:183], v[172:175], v[120:123]
	v_mfma_f32_16x16x32_bf16 v[44:47], v[188:191], v[172:175], v[44:47]
	v_mfma_f32_16x16x32_bf16 v[36:39], v[192:195], v[160:163], v[36:39]
	v_mfma_f32_16x16x32_bf16 v[32:35], v[192:195], v[168:171], v[32:35]
	v_mfma_f32_16x16x32_bf16 v[140:143], v[184:187], v[176:179], v[112:115]
	v_mfma_f32_16x16x32_bf16 v[44:47], v[192:195], v[176:179], v[44:47]
	s_setprio 0
	s_barrier
; #define PG8_STAGE(bufoff, gbase, voff) do { _Pragma("unroll") for (int _i = 0; _i < 2; ++_i) \
;         __builtin_amdgcn_global_load_lds((const unsigned*)((const char*)(gbase) + (voff)[_i]), (LAS unsigned*)(lds + (bufoff) + ldsw + _i * 8192), 16, 0, 0); } while (0)
; #define PG8_LDA(dst, b, h) do { _Pragma("unroll") for (int m = 0; m < 4; ++m) _Pragma("unroll") for (int k = 0; k < 2; ++k) dst[m][k] = *(const LAS bf16x8*)(lds + PG8_SA(b, h) + aoff + m * 2048 + k * 1024); } while (0)
; #define PG8_WAIT_V(n) asm volatile("s_waitcnt vmcnt(" #n ")" ::: "memory")
; #define PG8_WAIT_L(n) asm volatile("s_waitcnt lgkmcnt(" #n ")" ::: "memory")
; template <class Epi>
; __device__ __forceinline__ void gemm_phase(LAS unsigned char* lds, const Gemm g, const StaticOrder& S, const Epi& E) {
;     ...
;         for (int t = 0; t < nt; t += 2) {
;             const bool last = (t == nt - 2);
;             const char* a1 = cA + (size_t)(t + 1) * kstep;
;             const char* a2 = last ? nA : cA + (size_t)(t + 2) * kstep; const char* b2 = last ? nB : cB + (size_t)(t + 2) * kstep;
;             const char* a3 = a2 + kstep; const char* b3 = b2 + kstep;
;             PG8_LDB(B0, 0, 0); PG8_SCHED; PG8_LDA(At, 0, 0); PG8_STAGE(PG8_SA(1, 1), a1 + hstepA, voffA);
;             PG8_WAIT_L(8); PG8_BAR; PG8_WAIT_L(0); PG8_MMA(0, 0, At, B0); PG8_BAR; PG8_SCHED;
;             PG8_LDB(B1, 0, 1); PG8_STAGE(PG8_SB(0, 0), b2, voffB);
;             PG8_BAR; PG8_WAIT_L(0); PG8_MMA(0, 1, At, B1); PG8_BAR;
;             PG8_LDA(At, 0, 1); PG8_STAGE(PG8_SA(0, 0), a2, voffA);
;             PG8_BAR; PG8_WAIT_L(0); PG8_MMA(1, 0, At, B0); PG8_BAR; PG8_SCHED;
;             PG8_STAGE(PG8_SB(0, 1), b2 + hstepB, voffB);
;             PG8_WAIT_V(6); PG8_BAR; PG8_MMA(1, 1, At, B1); PG8_BAR;
;             PG8_LDB(B0, 1, 0); PG8_SCHED; PG8_LDA(At, 1, 0); PG8_STAGE(PG8_SA(0, 1), a2 + hstepA, voffA);
;             PG8_WAIT_L(8); PG8_BAR; PG8_WAIT_L(0); PG8_MMA(0, 0, At, B0); PG8_BAR; PG8_SCHED;
;             PG8_LDB(B1, 1, 1); PG8_STAGE(PG8_SB(1, 0), b3, voffB);
;             PG8_BAR; PG8_WAIT_L(0); PG8_MMA(0, 1, At, B1); PG8_BAR;
;             PG8_LDA(At, 1, 1); PG8_STAGE(PG8_SA(1, 0), a3, voffA);
;             PG8_BAR; PG8_WAIT_L(0); PG8_MMA(1, 0, At, B0); PG8_BAR; PG8_SCHED;
;             PG8_STAGE(PG8_SB(1, 1), b3 + hstepB, voffB);
;             PG8_WAIT_V(6); PG8_BAR; PG8_MMA(1, 1, At, B1); PG8_BAR;
	s_nop 1
	ds_read_b128 v[112:115], v244 offset:49152
	ds_read_b128 v[116:119], v244 offset:50176
	ds_read_b128 v[120:123], v244 offset:51200
	ds_read_b128 v[124:127], v244 offset:52224
	ds_read_b128 v[160:163], v244 offset:53248
	ds_read_b128 v[164:167], v244 offset:54272
	ds_read_b128 v[168:171], v244 offset:55296
	ds_read_b128 v[172:175], v244 offset:56320
	s_add_i32 s44, s88, s7
	s_mov_b32 m0, s44
	s_nop 0
	s_add_u32 s100, s48, s24
	s_addc_u32 s101, s49, s25
	global_load_lds_dwordx4 v214, s[100:101]
	s_add_i32 m0, s44, 0x2000
	s_nop 0
	s_add_u32 s100, s48, s24
	s_addc_u32 s101, s49, s25
	global_load_lds_dwordx4 v210, s[100:101]
	s_mov_b32 m0, s78
	v_lshl_add_u64 v[254:255], v[200:201], 0, s[24:25]
	global_load_lds_dwordx4 v[254:255], off
	v_lshl_add_u64 v[254:255], v[202:203], 0, s[24:25]
	s_mov_b32 m0, s79
	s_nop 0
	global_load_lds_dwordx4 v[254:255], off
	s_add_u32 s44, s48, 0x40080
	s_addc_u32 s45, s49, 0
	s_add_i32 s48, s72, s7
	s_mov_b32 m0, s48
	s_nop 0
	global_load_lds_dwordx4 v214, s[44:45]
	s_add_i32 m0, s48, 0x2000
	s_nop 0
	global_load_lds_dwordx4 v210, s[44:45]
	s_waitcnt vmcnt(6)
	s_waitcnt lgkmcnt(0)
	s_barrier
	s_setprio 1
	v_mfma_f32_16x16x32_bf16 v[92:95], v[96:99], v[112:115], v[92:95]
	v_mfma_f32_16x16x32_bf16 v[28:31], v[104:107], v[112:115], v[28:31]
	v_mfma_f32_16x16x32_bf16 v[80:83], v[96:99], v[120:123], v[80:83]
	v_mfma_f32_16x16x32_bf16 v[16:19], v[104:107], v[120:123], v[16:19]
	v_mfma_f32_16x16x32_bf16 v[76:79], v[96:99], v[160:163], v[76:79]
	v_mfma_f32_16x16x32_bf16 v[12:15], v[104:107], v[160:163], v[12:15]
	v_mfma_f32_16x16x32_bf16 v[84:87], v[96:99], v[168:171], v[84:87]
	v_mfma_f32_16x16x32_bf16 v[20:23], v[104:107], v[168:171], v[20:23]
	v_mfma_f32_16x16x32_bf16 v[92:95], v[100:103], v[116:119], v[92:95]
	v_mfma_f32_16x16x32_bf16 v[28:31], v[108:111], v[116:119], v[28:31]
	v_mfma_f32_16x16x32_bf16 v[80:83], v[100:103], v[124:127], v[80:83]
	v_mfma_f32_16x16x32_bf16 v[16:19], v[108:111], v[124:127], v[16:19]
	v_mfma_f32_16x16x32_bf16 v[76:79], v[100:103], v[164:167], v[76:79]
	v_mfma_f32_16x16x32_bf16 v[12:15], v[108:111], v[164:167], v[12:15]
	v_mfma_f32_16x16x32_bf16 v[84:87], v[100:103], v[172:175], v[84:87]
	v_mfma_f32_16x16x32_bf16 v[20:23], v[108:111], v[172:175], v[20:23]
	v_mfma_f32_16x16x32_bf16 v[88:91], v[180:183], v[112:115], v[88:91]
	v_mfma_f32_16x16x32_bf16 v[24:27], v[188:191], v[112:115], v[24:27]
	v_mfma_f32_16x16x32_bf16 v[68:71], v[180:183], v[120:123], v[68:71]
	v_mfma_f32_16x16x32_bf16 v[4:7], v[188:191], v[120:123], v[4:7]
	v_mfma_f32_16x16x32_bf16 v[64:67], v[180:183], v[160:163], v[64:67]
	v_mfma_f32_16x16x32_bf16 v[0:3], v[188:191], v[160:163], v[0:3]
	v_mfma_f32_16x16x32_bf16 v[72:75], v[180:183], v[168:171], v[72:75]
	v_mfma_f32_16x16x32_bf16 v[8:11], v[188:191], v[168:171], v[8:11]
	v_mfma_f32_16x16x32_bf16 v[88:91], v[184:187], v[116:119], v[88:91]
	v_mfma_f32_16x16x32_bf16 v[24:27], v[192:195], v[116:119], v[24:27]
	v_mfma_f32_16x16x32_bf16 v[68:71], v[184:187], v[124:127], v[68:71]
	v_mfma_f32_16x16x32_bf16 v[4:7], v[192:195], v[124:127], v[4:7]
	v_mfma_f32_16x16x32_bf16 v[64:67], v[184:187], v[164:167], v[64:67]
	v_mfma_f32_16x16x32_bf16 v[0:3], v[192:195], v[164:167], v[0:3]
	v_mfma_f32_16x16x32_bf16 v[72:75], v[184:187], v[172:175], v[72:75]
	v_mfma_f32_16x16x32_bf16 v[8:11], v[192:195], v[172:175], v[8:11]
	s_setprio 0
	s_add_i32 s87, s87, 2
	s_add_u32 s85, s85, 0x100
	s_addc_u32 s86, s86, 0
	s_cmp_gt_u32 s87, 13
	s_mov_b64 s[44:45], s[46:47]
	s_barrier
.LBB0_1359:
	ds_read_b128 v[96:99], v243
	ds_read_b128 v[100:103], v243 offset:1024
	ds_read_b128 v[104:107], v243 offset:2048
	ds_read_b128 v[108:111], v243 offset:3072
	s_add_u32 s46, s44, 0x100
	s_addc_u32 s47, s45, 0
	s_cmp_eq_u32 s87, 12
	s_cselect_b32 s73, s37, s47
	s_cselect_b32 s72, s83, s46
	s_cselect_b32 s49, s35, s86
	s_cselect_b32 s48, s84, s85
	s_add_i32 m0, s9, 0xc000
	ds_read_b128 v[112:115], v244
	ds_read_b128 v[116:119], v244 offset:1024
	ds_read_b128 v[120:123], v244 offset:2048
	ds_read_b128 v[124:127], v244 offset:3072
	ds_read_b128 v[160:163], v244 offset:4096
	ds_read_b128 v[164:167], v244 offset:5120
	ds_read_b128 v[168:171], v244 offset:6144
	ds_read_b128 v[172:175], v244 offset:7168
	global_load_lds_dwordx4 v224, s[44:45]
	s_add_i32 m0, s9, 0xe000
	s_nop 0
	global_load_lds_dwordx4 v226, s[44:45]
	ds_read_b128 v[176:179], v245
	ds_read_b128 v[180:183], v245 offset:1024
	ds_read_b128 v[184:187], v245 offset:2048
	ds_read_b128 v[188:191], v245 offset:3072
	s_waitcnt lgkmcnt(0)
	s_barrier
; #define PG8_STAGE(bufoff, gbase, voff) do { _Pragma("unroll") for (int _i = 0; _i < 2; ++_i) \
;         __builtin_amdgcn_global_load_lds((const unsigned*)((const char*)(gbase) + (voff)[_i]), (LAS unsigned*)(lds + (bufoff) + ldsw + _i * 8192), 16, 0, 0); } while (0)
; #define PG8_LDA(dst, b, h) do { _Pragma("unroll") for (int m = 0; m < 4; ++m) _Pragma("unroll") for (int k = 0; k < 2; ++k) dst[m][k] = *(const LAS bf16x8*)(lds + PG8_SA(b, h) + aoff + m * 2048 + k * 1024); } while (0)
; #define PG8_WAIT_V(n) asm volatile("s_waitcnt vmcnt(" #n ")" ::: "memory")
; #define PG8_WAIT_L(n) asm volatile("s_waitcnt lgkmcnt(" #n ")" ::: "memory")
; template <class Epi>
; __device__ __forceinline__ void gemm_phase(LAS unsigned char* lds, const Gemm g, const StaticOrder& S, const Epi& E) {
;     ...
;         for (int t = 0; t < nt; t += 2) {
;             const bool last = (t == nt - 2);
;             const char* a1 = cA + (size_t)(t + 1) * kstep;
;             const char* a2 = last ? nA : cA + (size_t)(t + 2) * kstep; const char* b2 = last ? nB : cB + (size_t)(t + 2) * kstep;
;             const char* a3 = a2 + kstep; const char* b3 = b2 + kstep;
;             PG8_LDB(B0, 0, 0); PG8_SCHED; PG8_LDA(At, 0, 0); PG8_STAGE(PG8_SA(1, 1), a1 + hstepA, voffA);
;             PG8_WAIT_L(8); PG8_BAR; PG8_WAIT_L(0); PG8_MMA(0, 0, At, B0); PG8_BAR; PG8_SCHED;
;             PG8_LDB(B1, 0, 1); PG8_STAGE(PG8_SB(0, 0), b2, voffB);
;             PG8_BAR; PG8_WAIT_L(0); PG8_MMA(0, 1, At, B1); PG8_BAR;
;             PG8_LDA(At, 0, 1); PG8_STAGE(PG8_SA(0, 0), a2, voffA);
;             PG8_BAR; PG8_WAIT_L(0); PG8_MMA(1, 0, At, B0); PG8_BAR; PG8_SCHED;
;             PG8_STAGE(PG8_SB(0, 1), b2 + hstepB, voffB);
;             PG8_WAIT_V(6); PG8_BAR; PG8_MMA(1, 1, At, B1); PG8_BAR;
;             PG8_LDB(B0, 1, 0); PG8_SCHED; PG8_LDA(At, 1, 0); PG8_STAGE(PG8_SA(0, 1), a2 + hstepA, voffA);
;             PG8_WAIT_L(8); PG8_BAR; PG8_WAIT_L(0); PG8_MMA(0, 0, At, B0); PG8_BAR; PG8_SCHED;
;             PG8_LDB(B1, 1, 1); PG8_STAGE(PG8_SB(1, 0), b3, voffB);
;             PG8_BAR; PG8_WAIT_L(0); PG8_MMA(0, 1, At, B1); PG8_BAR;
;             PG8_LDA(At, 1, 1); PG8_STAGE(PG8_SA(1, 0), a3, voffA);
;             PG8_BAR; PG8_WAIT_L(0); PG8_MMA(1, 0, At, B0); PG8_BAR; PG8_SCHED;
;             PG8_STAGE(PG8_SB(1, 1), b3 + hstepB, voffB);
;             PG8_WAIT_V(6); PG8_BAR; PG8_MMA(1, 1, At, B1); PG8_BAR;
	s_setprio 1
	v_mfma_f32_16x16x32_bf16 v[156:159], v[96:99], v[112:115], v[156:159]
	v_mfma_f32_16x16x32_bf16 v[60:63], v[104:107], v[112:115], v[60:63]
	v_mfma_f32_16x16x32_bf16 v[144:147], v[96:99], v[120:123], v[144:147]
	v_mfma_f32_16x16x32_bf16 v[48:51], v[104:107], v[120:123], v[48:51]
	v_mfma_f32_16x16x32_bf16 v[136:139], v[96:99], v[160:163], v[136:139]
	v_mfma_f32_16x16x32_bf16 v[40:43], v[104:107], v[160:163], v[40:43]
	v_mfma_f32_16x16x32_bf16 v[148:151], v[96:99], v[168:171], v[148:151]
	v_mfma_f32_16x16x32_bf16 v[52:55], v[104:107], v[168:171], v[52:55]
	v_mfma_f32_16x16x32_bf16 v[156:159], v[100:103], v[116:119], v[156:159]
	v_mfma_f32_16x16x32_bf16 v[60:63], v[108:111], v[116:119], v[60:63]
	v_mfma_f32_16x16x32_bf16 v[144:147], v[100:103], v[124:127], v[144:147]
	v_mfma_f32_16x16x32_bf16 v[48:51], v[108:111], v[124:127], v[48:51]
	v_mfma_f32_16x16x32_bf16 v[136:139], v[100:103], v[164:167], v[136:139]
	v_mfma_f32_16x16x32_bf16 v[40:43], v[108:111], v[164:167], v[40:43]
	v_mfma_f32_16x16x32_bf16 v[148:151], v[100:103], v[172:175], v[148:151]
	v_mfma_f32_16x16x32_bf16 v[52:55], v[108:111], v[172:175], v[52:55]
	v_mfma_f32_16x16x32_bf16 v[152:155], v[176:179], v[112:115], v[152:155]
	v_mfma_f32_16x16x32_bf16 v[56:59], v[184:187], v[112:115], v[56:59]
	v_mfma_f32_16x16x32_bf16 v[36:39], v[184:187], v[120:123], v[36:39]
	v_mfma_f32_16x16x32_bf16 v[32:35], v[184:187], v[160:163], v[32:35]
	v_mfma_f32_16x16x32_bf16 v[44:47], v[184:187], v[168:171], v[44:47]
	v_mfma_f32_16x16x32_bf16 v[152:155], v[180:183], v[116:119], v[152:155]
	v_mfma_f32_16x16x32_bf16 v[56:59], v[188:191], v[116:119], v[56:59]
	v_mfma_f32_16x16x32_bf16 v[112:115], v[176:179], v[120:123], v[132:135]
	v_mfma_f32_16x16x32_bf16 v[36:39], v[188:191], v[124:127], v[36:39]
	v_mfma_f32_16x16x32_bf16 v[116:119], v[176:179], v[160:163], v[128:131]
	v_mfma_f32_16x16x32_bf16 v[32:35], v[188:191], v[164:167], v[32:35]
	v_mfma_f32_16x16x32_bf16 v[120:123], v[176:179], v[168:171], v[140:143]
	v_mfma_f32_16x16x32_bf16 v[44:47], v[188:191], v[172:175], v[44:47]
	v_mfma_f32_16x16x32_bf16 v[112:115], v[180:183], v[124:127], v[112:115]
	v_mfma_f32_16x16x32_bf16 v[116:119], v[180:183], v[164:167], v[116:119]
	v_mfma_f32_16x16x32_bf16 v[120:123], v[180:183], v[172:175], v[120:123]
	s_setprio 0
	s_barrier
	s_nop 1
	ds_read_b128 v[124:127], v244 offset:16384
	ds_read_b128 v[128:131], v244 offset:17408
	ds_read_b128 v[132:135], v244 offset:18432
	ds_read_b128 v[140:143], v244 offset:19456
	ds_read_b128 v[160:163], v244 offset:20480
	ds_read_b128 v[164:167], v244 offset:21504
	ds_read_b128 v[168:171], v244 offset:22528
	ds_read_b128 v[172:175], v244 offset:23552
	s_add_i32 s44, s80, s7
	v_lshl_add_u64 v[196:197], s[48:49], 0, v[214:215]
	s_mov_b32 m0, s44
	s_nop 0
	global_load_lds_dwordx4 v214, s[48:49]
	v_lshl_add_u64 v[198:199], s[48:49], 0, v[210:211]
	s_add_i32 m0, s44, 0x2000
	s_nop 0
	global_load_lds_dwordx4 v210, s[48:49]
	s_mov_b32 m0, s9
	v_lshl_add_u64 v[200:201], s[72:73], 0, v[216:217]
	global_load_lds_dwordx4 v216, s[72:73]
	v_lshl_add_u64 v[202:203], s[72:73], 0, v[212:213]
	s_mov_b32 m0, s63
	s_nop 0
	global_load_lds_dwordx4 v212, s[72:73]
	s_add_u32 s44, s48, 0x40000
	s_addc_u32 s45, s49, 0
	s_add_i32 s88, s81, s7
	s_mov_b32 m0, s88
	s_nop 0
	global_load_lds_dwordx4 v214, s[44:45]
	s_add_i32 m0, s88, 0x2000
	s_nop 0
	global_load_lds_dwordx4 v210, s[44:45]
	s_waitcnt vmcnt(6)
	s_waitcnt lgkmcnt(0)
	s_barrier
	s_setprio 1
	v_mfma_f32_16x16x32_bf16 v[92:95], v[96:99], v[124:127], v[92:95]
	v_mfma_f32_16x16x32_bf16 v[28:31], v[104:107], v[124:127], v[28:31]
	v_mfma_f32_16x16x32_bf16 v[80:83], v[96:99], v[132:135], v[80:83]
	v_mfma_f32_16x16x32_bf16 v[16:19], v[104:107], v[132:135], v[16:19]
	v_mfma_f32_16x16x32_bf16 v[76:79], v[96:99], v[160:163], v[76:79]
	v_mfma_f32_16x16x32_bf16 v[12:15], v[104:107], v[160:163], v[12:15]
	v_mfma_f32_16x16x32_bf16 v[84:87], v[96:99], v[168:171], v[84:87]
	v_mfma_f32_16x16x32_bf16 v[20:23], v[104:107], v[168:171], v[20:23]
	v_mfma_f32_16x16x32_bf16 v[92:95], v[100:103], v[128:131], v[92:95]
	v_mfma_f32_16x16x32_bf16 v[28:31], v[108:111], v[128:131], v[28:31]
	v_mfma_f32_16x16x32_bf16 v[80:83], v[100:103], v[140:143], v[80:83]
	v_mfma_f32_16x16x32_bf16 v[16:19], v[108:111], v[140:143], v[16:19]
	v_mfma_f32_16x16x32_bf16 v[76:79], v[100:103], v[164:167], v[76:79]
	v_mfma_f32_16x16x32_bf16 v[12:15], v[108:111], v[164:167], v[12:15]
	v_mfma_f32_16x16x32_bf16 v[84:87], v[100:103], v[172:175], v[84:87]
	v_mfma_f32_16x16x32_bf16 v[20:23], v[108:111], v[172:175], v[20:23]
	v_mfma_f32_16x16x32_bf16 v[88:91], v[176:179], v[124:127], v[88:91]
	v_mfma_f32_16x16x32_bf16 v[24:27], v[184:187], v[124:127], v[24:27]
	v_mfma_f32_16x16x32_bf16 v[68:71], v[176:179], v[132:135], v[68:71]
	v_mfma_f32_16x16x32_bf16 v[4:7], v[184:187], v[132:135], v[4:7]
	v_mfma_f32_16x16x32_bf16 v[64:67], v[176:179], v[160:163], v[64:67]
	v_mfma_f32_16x16x32_bf16 v[0:3], v[184:187], v[160:163], v[0:3]
	v_mfma_f32_16x16x32_bf16 v[72:75], v[176:179], v[168:171], v[72:75]
	v_mfma_f32_16x16x32_bf16 v[8:11], v[184:187], v[168:171], v[8:11]
	v_mfma_f32_16x16x32_bf16 v[88:91], v[180:183], v[128:131], v[88:91]
	v_mfma_f32_16x16x32_bf16 v[24:27], v[188:191], v[128:131], v[24:27]
	v_mfma_f32_16x16x32_bf16 v[68:71], v[180:183], v[140:143], v[68:71]
	v_mfma_f32_16x16x32_bf16 v[4:7], v[188:191], v[140:143], v[4:7]
	v_mfma_f32_16x16x32_bf16 v[64:67], v[180:183], v[164:167], v[64:67]
	v_mfma_f32_16x16x32_bf16 v[0:3], v[188:191], v[164:167], v[0:3]
	v_mfma_f32_16x16x32_bf16 v[72:75], v[180:183], v[172:175], v[72:75]
	v_mfma_f32_16x16x32_bf16 v[8:11], v[188:191], v[172:175], v[8:11]
	s_setprio 0
	s_add_i32 s88, 0, 0x18000
	v_add_u32_e32 v108, s88, v235
	s_barrier
; #define PG8_STAGE(bufoff, gbase, voff) do { _Pragma("unroll") for (int _i = 0; _i < 2; ++_i) \
;         __builtin_amdgcn_global_load_lds((const unsigned*)((const char*)(gbase) + (voff)[_i]), (LAS unsigned*)(lds + (bufoff) + ldsw + _i * 8192), 16, 0, 0); } while (0)
; #define PG8_LDA(dst, b, h) do { _Pragma("unroll") for (int m = 0; m < 4; ++m) _Pragma("unroll") for (int k = 0; k < 2; ++k) dst[m][k] = *(const LAS bf16x8*)(lds + PG8_SA(b, h) + aoff + m * 2048 + k * 1024); } while (0)
; #define PG8_WAIT_V(n) asm volatile("s_waitcnt vmcnt(" #n ")" ::: "memory")
; #define PG8_WAIT_L(n) asm volatile("s_waitcnt lgkmcnt(" #n ")" ::: "memory")
; template <class Epi>
; __device__ __forceinline__ void gemm_phase(LAS unsigned char* lds, const Gemm g, const StaticOrder& S, const Epi& E) {
;     ...
;         for (int t = 0; t < nt; t += 2) {
;             const bool last = (t == nt - 2);
;             const char* a1 = cA + (size_t)(t + 1) * kstep;
;             const char* a2 = last ? nA : cA + (size_t)(t + 2) * kstep; const char* b2 = last ? nB : cB + (size_t)(t + 2) * kstep;
;             const char* a3 = a2 + kstep; const char* b3 = b2 + kstep;
;             PG8_LDB(B0, 0, 0); PG8_SCHED; PG8_LDA(At, 0, 0); PG8_STAGE(PG8_SA(1, 1), a1 + hstepA, voffA);
;             PG8_WAIT_L(8); PG8_BAR; PG8_WAIT_L(0); PG8_MMA(0, 0, At, B0); PG8_BAR; PG8_SCHED;
;             PG8_LDB(B1, 0, 1); PG8_STAGE(PG8_SB(0, 0), b2, voffB);
;             PG8_BAR; PG8_WAIT_L(0); PG8_MMA(0, 1, At, B1); PG8_BAR;
;             PG8_LDA(At, 0, 1); PG8_STAGE(PG8_SA(0, 0), a2, voffA);
;             PG8_BAR; PG8_WAIT_L(0); PG8_MMA(1, 0, At, B0); PG8_BAR; PG8_SCHED;
;             PG8_STAGE(PG8_SB(0, 1), b2 + hstepB, voffB);
;             PG8_WAIT_V(6); PG8_BAR; PG8_MMA(1, 1, At, B1); PG8_BAR;
;             PG8_LDB(B0, 1, 0); PG8_SCHED; PG8_LDA(At, 1, 0); PG8_STAGE(PG8_SA(0, 1), a2 + hstepA, voffA);
;             PG8_WAIT_L(8); PG8_BAR; PG8_WAIT_L(0); PG8_MMA(0, 0, At, B0); PG8_BAR; PG8_SCHED;
;             PG8_LDB(B1, 1, 1); PG8_STAGE(PG8_SB(1, 0), b3, voffB);
;             PG8_BAR; PG8_WAIT_L(0); PG8_MMA(0, 1, At, B1); PG8_BAR;
;             PG8_LDA(At, 1, 1); PG8_STAGE(PG8_SA(1, 0), a3, voffA);
;             PG8_BAR; PG8_WAIT_L(0); PG8_MMA(1, 0, At, B0); PG8_BAR; PG8_SCHED;
;             PG8_STAGE(PG8_SB(1, 1), b3 + hstepB, voffB);
;             PG8_WAIT_V(6); PG8_BAR; PG8_MMA(1, 1, At, B1); PG8_BAR;
	ds_read_b128 v[96:99], v108
	ds_read_b128 v[100:103], v108 offset:1024
	ds_read_b128 v[104:107], v108 offset:2048
	ds_read_b128 v[108:111], v108 offset:3072
	s_add_u32 s44, s72, 0x40000
	s_addc_u32 s45, s73, 0
	s_mov_b32 m0, s74
	ds_read_b128 v[124:127], v244 offset:32768
	ds_read_b128 v[128:131], v244 offset:33792
	ds_read_b128 v[140:143], v244 offset:34816
	ds_read_b128 v[160:163], v244 offset:35840
	ds_read_b128 v[164:167], v244 offset:36864
	ds_read_b128 v[168:171], v244 offset:37888
	ds_read_b128 v[172:175], v244 offset:38912
	ds_read_b128 v[176:179], v244 offset:39936
	global_load_lds_dwordx4 v216, s[44:45]
	v_lshl_add_u64 v[132:133], s[44:45], 0, v[212:213]
	s_mov_b32 m0, s75
	s_nop 0
	global_load_lds_dwordx4 v212, s[44:45]
	s_add_i32 s72, 0, 0x1c000
	v_add_u32_e32 v132, s72, v235
	ds_read_b128 v[180:183], v132
	ds_read_b128 v[184:187], v132 offset:1024
	ds_read_b128 v[188:191], v132 offset:2048
	ds_read_b128 v[192:195], v132 offset:3072
	s_waitcnt lgkmcnt(0)
	s_barrier
	s_setprio 1
	v_mfma_f32_16x16x32_bf16 v[132:135], v[96:99], v[124:127], v[156:159]
	v_mfma_f32_16x16x32_bf16 v[156:159], v[100:103], v[128:131], v[132:135]
	v_mfma_f32_16x16x32_bf16 v[132:135], v[96:99], v[140:143], v[144:147]
	v_mfma_f32_16x16x32_bf16 v[144:147], v[100:103], v[160:163], v[132:135]
	v_mfma_f32_16x16x32_bf16 v[132:135], v[96:99], v[164:167], v[136:139]
	v_mfma_f32_16x16x32_bf16 v[60:63], v[104:107], v[124:127], v[60:63]
	v_mfma_f32_16x16x32_bf16 v[48:51], v[104:107], v[140:143], v[48:51]
	v_mfma_f32_16x16x32_bf16 v[136:139], v[100:103], v[168:171], v[132:135]
	v_mfma_f32_16x16x32_bf16 v[40:43], v[104:107], v[164:167], v[40:43]
	v_mfma_f32_16x16x32_bf16 v[132:135], v[96:99], v[172:175], v[148:151]
	v_mfma_f32_16x16x32_bf16 v[52:55], v[104:107], v[172:175], v[52:55]
	v_mfma_f32_16x16x32_bf16 v[60:63], v[108:111], v[128:131], v[60:63]
	v_mfma_f32_16x16x32_bf16 v[48:51], v[108:111], v[160:163], v[48:51]
	v_mfma_f32_16x16x32_bf16 v[40:43], v[108:111], v[168:171], v[40:43]
	v_mfma_f32_16x16x32_bf16 v[148:151], v[100:103], v[176:179], v[132:135]
	v_mfma_f32_16x16x32_bf16 v[52:55], v[108:111], v[176:179], v[52:55]
	v_mfma_f32_16x16x32_bf16 v[132:135], v[180:183], v[124:127], v[152:155]
	v_mfma_f32_16x16x32_bf16 v[112:115], v[180:183], v[140:143], v[112:115]
	v_mfma_f32_16x16x32_bf16 v[152:155], v[184:187], v[128:131], v[132:135]
	v_mfma_f32_16x16x32_bf16 v[56:59], v[188:191], v[124:127], v[56:59]
	v_mfma_f32_16x16x32_bf16 v[132:135], v[184:187], v[160:163], v[112:115]
	v_mfma_f32_16x16x32_bf16 v[112:115], v[180:183], v[164:167], v[116:119]
	v_mfma_f32_16x16x32_bf16 v[56:59], v[192:195], v[128:131], v[56:59]
	v_mfma_f32_16x16x32_bf16 v[36:39], v[188:191], v[140:143], v[36:39]
	v_mfma_f32_16x16x32_bf16 v[128:131], v[184:187], v[168:171], v[112:115]
	v_mfma_f32_16x16x32_bf16 v[32:35], v[188:191], v[164:167], v[32:35]
	v_mfma_f32_16x16x32_bf16 v[112:115], v[180:183], v[172:175], v[120:123]
	v_mfma_f32_16x16x32_bf16 v[44:47], v[188:191], v[172:175], v[44:47]
	v_mfma_f32_16x16x32_bf16 v[36:39], v[192:195], v[160:163], v[36:39]
	v_mfma_f32_16x16x32_bf16 v[32:35], v[192:195], v[168:171], v[32:35]
	v_mfma_f32_16x16x32_bf16 v[140:143], v[184:187], v[176:179], v[112:115]
	v_mfma_f32_16x16x32_bf16 v[44:47], v[192:195], v[176:179], v[44:47]
	s_setprio 0
	s_barrier
	s_nop 1
	ds_read_b128 v[112:115], v244 offset:49152
	ds_read_b128 v[116:119], v244 offset:50176
	ds_read_b128 v[120:123], v244 offset:51200
	ds_read_b128 v[124:127], v244 offset:52224
	ds_read_b128 v[160:163], v244 offset:53248
	ds_read_b128 v[164:167], v244 offset:54272
	ds_read_b128 v[168:171], v244 offset:55296
	ds_read_b128 v[172:175], v244 offset:56320
	s_add_i32 s44, s88, s7
	s_mov_b32 m0, s44
	s_nop 0
	s_add_u32 s100, s48, s24
	s_addc_u32 s101, s49, s25
	global_load_lds_dwordx4 v214, s[100:101]
	s_add_i32 m0, s44, 0x2000
	s_nop 0
	s_add_u32 s100, s48, s24
	s_addc_u32 s101, s49, s25
	global_load_lds_dwordx4 v210, s[100:101]
	s_mov_b32 m0, s78
	v_lshl_add_u64 v[254:255], v[200:201], 0, s[24:25]
	global_load_lds_dwordx4 v[254:255], off
	v_lshl_add_u64 v[254:255], v[202:203], 0, s[24:25]
	s_mov_b32 m0, s79
	s_nop 0
	global_load_lds_dwordx4 v[254:255], off
	s_add_u32 s44, s48, 0x40080
	s_addc_u32 s45, s49, 0
	s_add_i32 s48, s72, s7
	s_mov_b32 m0, s48
	s_nop 0
	global_load_lds_dwordx4 v214, s[44:45]
	s_add_i32 m0, s48, 0x2000
	s_nop 0
	global_load_lds_dwordx4 v210, s[44:45]
	s_waitcnt vmcnt(6)
	s_waitcnt lgkmcnt(0)
	s_barrier
; #define LAS __attribute__((address_space(3)))
; #define PG8_STAGE(bufoff, gbase, voff) do { _Pragma("unroll") for (int _i = 0; _i < 2; ++_i) \
;         __builtin_amdgcn_global_load_lds((const unsigned*)((const char*)(gbase) + (voff)[_i]), (LAS unsigned*)(lds + (bufoff) + ldsw + _i * 8192), 16, 0, 0); } while (0)
; #define PG8_WAIT_V(n) asm volatile("s_waitcnt vmcnt(" #n ")" ::: "memory")
; #define PG8_WAIT_L(n) asm volatile("s_waitcnt lgkmcnt(" #n ")" ::: "memory")
; #define PG8_BAR __builtin_amdgcn_s_barrier()
; template <class Epi>
; __device__ __forceinline__ void gemm_phase(LAS unsigned char* lds, const Gemm g, const StaticOrder& S, const Epi& E) {
;     ...
;             PG8_WAIT_V(6); PG8_BAR; PG8_MMA(1, 1, At, B1); PG8_BAR;
;             PG8_LDB(B0, 1, 0); PG8_SCHED; PG8_LDA(At, 1, 0); PG8_STAGE(PG8_SA(0, 1), a2 + hstepA, voffA);
;             PG8_WAIT_L(8); PG8_BAR; PG8_WAIT_L(0); PG8_MMA(0, 0, At, B0); PG8_BAR; PG8_SCHED;
;             PG8_LDB(B1, 1, 1); PG8_STAGE(PG8_SB(1, 0), b3, voffB);
;             PG8_BAR; PG8_WAIT_L(0); PG8_MMA(0, 1, At, B1); PG8_BAR;
;             PG8_LDA(At, 1, 1); PG8_STAGE(PG8_SA(1, 0), a3, voffA);
;             PG8_BAR; PG8_WAIT_L(0); PG8_MMA(1, 0, At, B0); PG8_BAR; PG8_SCHED;
;             PG8_STAGE(PG8_SB(1, 1), b3 + hstepB, voffB);
;             PG8_WAIT_V(6); PG8_BAR; PG8_MMA(1, 1, At, B1); PG8_BAR;
;         }
;         E(acc, cur, wr, wc, fr, fq);
;     __device__ __forceinline__ void operator()(AccRef acc, const Unit& u, int wr, int wc, int fr, int fq) const {
;     ...
;         { const float* cv = cw + 128 * u.pn + clb; const float* cg = cv + FH; const float* bp = cb + 128 * u.pn + clb;
;           cwv[0][0] = *(const f32x4*)(cv); cwv[0][1] = *(const f32x4*)(cv + F2); cwv[0][2] = *(const f32x4*)(cv + 2 * F2); cwv[0][3] = *(const f32x4*)(bp);
;           cwv[0][4] = *(const f32x4*)(cg); cwv[0][5] = *(const f32x4*)(cg + F2); cwv[0][6] = *(const f32x4*)(cg + 2 * F2); cwv[0][7] = *(const f32x4*)(bp + FH); }
;         if (fr == 15) {
; #pragma unroll
;             for (int ai = 0; ai < 2; ++ai)
; #pragma unroll
;                 for (int bj = 0; bj < 2; ++bj)
; #pragma unroll
;                     for (int n = 0; n < 2; ++n) { *(LAS f32x4*)(xch + ((ai * 2 + wr) * 2 + 0) * 256 + bj * 128 + clb + 4 * n) = acc[ai][bj][2][n]; *(LAS f32x4*)(xch + ((ai * 2 + wr) * 2 + 1) * 256 + bj * 128 + clb + 4 * n) = acc[ai][bj][3][n]; }
	s_setprio 1
	v_mfma_f32_16x16x32_bf16 v[92:95], v[96:99], v[112:115], v[92:95]
	v_mfma_f32_16x16x32_bf16 v[28:31], v[104:107], v[112:115], v[28:31]
	v_mfma_f32_16x16x32_bf16 v[80:83], v[96:99], v[120:123], v[80:83]
	v_mfma_f32_16x16x32_bf16 v[16:19], v[104:107], v[120:123], v[16:19]
	v_mfma_f32_16x16x32_bf16 v[76:79], v[96:99], v[160:163], v[76:79]
	v_mfma_f32_16x16x32_bf16 v[12:15], v[104:107], v[160:163], v[12:15]
	v_mfma_f32_16x16x32_bf16 v[84:87], v[96:99], v[168:171], v[84:87]
	v_mfma_f32_16x16x32_bf16 v[20:23], v[104:107], v[168:171], v[20:23]
	v_mfma_f32_16x16x32_bf16 v[92:95], v[100:103], v[116:119], v[92:95]
	v_mfma_f32_16x16x32_bf16 v[28:31], v[108:111], v[116:119], v[28:31]
	v_mfma_f32_16x16x32_bf16 v[80:83], v[100:103], v[124:127], v[80:83]
	v_mfma_f32_16x16x32_bf16 v[16:19], v[108:111], v[124:127], v[16:19]
	v_mfma_f32_16x16x32_bf16 v[76:79], v[100:103], v[164:167], v[76:79]
	v_mfma_f32_16x16x32_bf16 v[12:15], v[108:111], v[164:167], v[12:15]
	v_mfma_f32_16x16x32_bf16 v[84:87], v[100:103], v[172:175], v[84:87]
	v_mfma_f32_16x16x32_bf16 v[20:23], v[108:111], v[172:175], v[20:23]
	v_mfma_f32_16x16x32_bf16 v[88:91], v[180:183], v[112:115], v[88:91]
	v_mfma_f32_16x16x32_bf16 v[24:27], v[188:191], v[112:115], v[24:27]
	v_mfma_f32_16x16x32_bf16 v[68:71], v[180:183], v[120:123], v[68:71]
	v_mfma_f32_16x16x32_bf16 v[4:7], v[188:191], v[120:123], v[4:7]
	v_mfma_f32_16x16x32_bf16 v[64:67], v[180:183], v[160:163], v[64:67]
	v_mfma_f32_16x16x32_bf16 v[0:3], v[188:191], v[160:163], v[0:3]
	v_mfma_f32_16x16x32_bf16 v[72:75], v[180:183], v[168:171], v[72:75]
	v_mfma_f32_16x16x32_bf16 v[8:11], v[188:191], v[168:171], v[8:11]
	v_mfma_f32_16x16x32_bf16 v[88:91], v[184:187], v[116:119], v[88:91]
	v_mfma_f32_16x16x32_bf16 v[24:27], v[192:195], v[116:119], v[24:27]
	v_mfma_f32_16x16x32_bf16 v[68:71], v[184:187], v[124:127], v[68:71]
	v_mfma_f32_16x16x32_bf16 v[4:7], v[192:195], v[124:127], v[4:7]
	v_mfma_f32_16x16x32_bf16 v[64:67], v[184:187], v[164:167], v[64:67]
	v_mfma_f32_16x16x32_bf16 v[0:3], v[192:195], v[164:167], v[0:3]
	v_mfma_f32_16x16x32_bf16 v[72:75], v[184:187], v[172:175], v[72:75]
	v_mfma_f32_16x16x32_bf16 v[8:11], v[192:195], v[172:175], v[8:11]
	s_setprio 0
	s_add_i32 s87, s87, 2
	s_add_u32 s85, s85, 0x100
	s_addc_u32 s86, s86, 0
	s_cmp_gt_u32 s87, 13
	s_mov_b64 s[44:45], s[46:47]
	s_barrier
	s_cbranch_scc0 .LBB0_1359
	s_lshl_b32 s44, s43, 7
	s_ashr_i32 s45, s44, 31
	s_lshl_b64 s[46:47], s[44:45], 2
	v_lshl_add_u64 v[96:97], v[220:221], 0, s[46:47]
	v_add_co_u32_e32 v100, vcc, 0x5000, v96
	v_lshl_add_u64 v[98:99], v[222:223], 0, s[46:47]
	s_nop 0
	v_addc_co_u32_e32 v101, vcc, 0, v97, vcc
	v_add_co_u32_e32 v102, vcc, 0xb000, v96
	global_load_dwordx4 v[160:163], v[96:97], off
	s_nop 0
	v_addc_co_u32_e32 v103, vcc, 0, v97, vcc
	global_load_dwordx4 v[164:167], v[100:101], off offset:2048
	global_load_dwordx4 v[168:171], v[102:103], off
	global_load_dwordx4 v[172:175], v[98:99], off
	v_add_co_u32_e32 v100, vcc, s76, v96
	s_nop 1
	v_addc_co_u32_e32 v101, vcc, 0, v97, vcc
	v_add_co_u32_e32 v102, vcc, 0x8000, v96
	s_nop 1
	v_addc_co_u32_e32 v103, vcc, 0, v97, vcc
	v_add_co_u32_e32 v96, vcc, 0xd000, v96
	global_load_dwordx4 v[176:179], v[100:101], off offset:3072
	global_load_dwordx4 v[180:183], v[102:103], off offset:1024
	v_addc_co_u32_e32 v97, vcc, 0, v97, vcc
	global_load_dwordx4 v[184:187], v[96:97], off offset:3072
	v_add_co_u32_e32 v96, vcc, 0x2000, v98
	s_nop 1
	v_addc_co_u32_e32 v97, vcc, 0, v99, vcc
	global_load_dwordx4 v[188:191], v[96:97], off offset:3072
	s_and_saveexec_b64 s[46:47], s[10:11]
	s_cbranch_execz .LBB0_1362
	ds_write_b128 v237, v[136:139]
	ds_write_b128 v237, v[148:151] offset:1024
	ds_write_b128 v237, v[40:43] offset:16
	ds_write_b128 v237, v[52:55] offset:1040
	ds_write_b128 v237, v[128:131] offset:512
	ds_write_b128 v237, v[140:143] offset:1536
	ds_write_b128 v237, v[32:35] offset:528
	ds_write_b128 v237, v[44:47] offset:1552
	ds_write_b128 v237, v[76:79] offset:4096
	ds_write_b128 v237, v[84:87] offset:5120
	ds_write_b128 v237, v[12:15] offset:4112
	ds_write_b128 v237, v[20:23] offset:5136
	ds_write_b128 v237, v[64:67] offset:4608
	ds_write_b128 v237, v[72:75] offset:5632
	ds_write_b128 v237, v[0:3] offset:4624
	ds_write_b128 v237, v[8:11] offset:5648

; #define PG8_STAGE(bufoff, gbase, voff) do { _Pragma("unroll") for (int _i = 0; _i < 2; ++_i) \
;         __builtin_amdgcn_global_load_lds((const unsigned*)((const char*)(gbase) + (voff)[_i]), (LAS unsigned*)(lds + (bufoff) + ldsw + _i * 8192), 16, 0, 0); } while (0)
; #define PG8_WAIT_V(n) asm volatile("s_waitcnt vmcnt(" #n ")" ::: "memory")
; template <class Epi>
; __device__ __forceinline__ void gemm_phase(LAS unsigned char* lds, const Gemm g, const StaticOrder& S, const Epi& E) {
;     ...
;     for (;;) {
;         const bool has_next = S.next(ui + 1, nxt);
;         const char* nA = has_next ? (const char*)g.A + (size_t)nxt.pm * tstepA + (size_t)(nxt.pn >> g.a_shift) * g.a_step : cA; const char* nB = has_next ? (const char*)g.Bt + (size_t)nxt.pn * tstepB : cB;
;         for (int t = 0; t < nt; t += 2) {
;             const bool last = (t == nt - 2);
;             const char* a1 = cA + (size_t)(t + 1) * kstep;
;             const char* a2 = last ? nA : cA + (size_t)(t + 2) * kstep; const char* b2 = last ? nB : cB + (size_t)(t + 2) * kstep;
;             const char* a3 = a2 + kstep; const char* b3 = b2 + kstep;
;             PG8_LDB(B0, 0, 0); PG8_SCHED; PG8_LDA(At, 0, 0); PG8_STAGE(PG8_SA(1, 1), a1 + hstepA, voffA);
;             PG8_WAIT_L(8); PG8_BAR; PG8_WAIT_L(0); PG8_MMA(0, 0, At, B0); PG8_BAR; PG8_SCHED;
;             PG8_LDB(B1, 0, 1); PG8_STAGE(PG8_SB(0, 0), b2, voffB);
;             PG8_BAR; PG8_WAIT_L(0); PG8_MMA(0, 1, At, B1); PG8_BAR;
;             PG8_LDA(At, 0, 1); PG8_STAGE(PG8_SA(0, 0), a2, voffA);
;             PG8_BAR; PG8_WAIT_L(0); PG8_MMA(1, 0, At, B0); PG8_BAR; PG8_SCHED;
;             PG8_STAGE(PG8_SB(0, 1), b2 + hstepB, voffB);
;             PG8_WAIT_V(6); PG8_BAR; PG8_MMA(1, 1, At, B1); PG8_BAR;
;             PG8_LDB(B0, 1, 0); PG8_SCHED; PG8_LDA(At, 1, 0); PG8_STAGE(PG8_SA(0, 1), a2 + hstepA, voffA);
;             PG8_WAIT_L(8); PG8_BAR; PG8_WAIT_L(0); PG8_MMA(0, 0, At, B0); PG8_BAR; PG8_SCHED;
;             PG8_LDB(B1, 1, 1); PG8_STAGE(PG8_SB(1, 0), b3, voffB);
;             PG8_BAR; PG8_WAIT_L(0); PG8_MMA(0, 1, At, B1); PG8_BAR;
;             PG8_LDA(At, 1, 1); PG8_STAGE(PG8_SA(1, 0), a3, voffA);
;             PG8_BAR; PG8_WAIT_L(0); PG8_MMA(1, 0, At, B0); PG8_BAR; PG8_SCHED;
;             PG8_STAGE(PG8_SB(1, 1), b3 + hstepB, voffB);
;             PG8_WAIT_V(6); PG8_BAR; PG8_MMA(1, 1, At, B1); PG8_BAR;
.LBB0_1460:
	s_add_u32 s72, s34, 0x100
	s_addc_u32 s73, s35, 0
	s_mov_b32 s74, -2
	ds_read_b128 v[140:143], v149
	ds_read_b128 v[152:155], v149 offset:1024
	ds_read_b128 v[156:159], v149 offset:2048
	ds_read_b128 v[160:163], v149 offset:3072
	s_add_u32 s34, s30, 0x100
	s_addc_u32 s35, s31, 0
	s_cmp_eq_u32 s74, 40
	s_cselect_b32 s39, s13, s35
	s_cselect_b32 s38, s12, s34
	s_cselect_b32 s37, s15, s73
	s_cselect_b32 s36, s14, s72
	s_add_i32 m0, s8, 0xc000
	ds_read_b128 v[164:167], v150
	ds_read_b128 v[168:171], v150 offset:1024
	ds_read_b128 v[172:175], v150 offset:2048
	ds_read_b128 v[176:179], v150 offset:3072
	ds_read_b128 v[180:183], v150 offset:4096
	ds_read_b128 v[184:187], v150 offset:5120
	ds_read_b128 v[188:191], v150 offset:6144
	ds_read_b128 v[192:195], v150 offset:7168
	global_load_lds_dwordx4 v132, s[30:31]
	s_add_i32 m0, s8, 0xe000
	s_nop 0
	global_load_lds_dwordx4 v134, s[30:31]
	ds_read_b128 v[196:199], v151
	ds_read_b128 v[200:203], v151 offset:1024
	ds_read_b128 v[204:207], v151 offset:2048
	ds_read_b128 v[208:211], v151 offset:3072
	s_waitcnt lgkmcnt(0)
	s_barrier
	s_setprio 1
	v_mfma_f32_16x16x32_bf16 v[124:127], v[140:143], v[164:167], 0
	v_mfma_f32_16x16x32_bf16 v[120:123], v[156:159], v[164:167], 0
	v_mfma_f32_16x16x32_bf16 v[112:115], v[140:143], v[172:175], 0
	v_mfma_f32_16x16x32_bf16 v[104:107], v[156:159], v[172:175], 0
	v_mfma_f32_16x16x32_bf16 v[92:95], v[140:143], v[180:183], 0
	v_mfma_f32_16x16x32_bf16 v[88:91], v[156:159], v[180:183], 0
	v_mfma_f32_16x16x32_bf16 v[80:83], v[140:143], v[188:191], 0
	v_mfma_f32_16x16x32_bf16 v[72:75], v[156:159], v[188:191], 0
	v_mfma_f32_16x16x32_bf16 v[124:127], v[152:155], v[168:171], v[124:127]
	v_mfma_f32_16x16x32_bf16 v[120:123], v[160:163], v[168:171], v[120:123]
	v_mfma_f32_16x16x32_bf16 v[112:115], v[152:155], v[176:179], v[112:115]
	v_mfma_f32_16x16x32_bf16 v[104:107], v[160:163], v[176:179], v[104:107]
	v_mfma_f32_16x16x32_bf16 v[92:95], v[152:155], v[184:187], v[92:95]
	v_mfma_f32_16x16x32_bf16 v[88:91], v[160:163], v[184:187], v[88:91]
	v_mfma_f32_16x16x32_bf16 v[80:83], v[152:155], v[192:195], v[80:83]
	v_mfma_f32_16x16x32_bf16 v[72:75], v[160:163], v[192:195], v[72:75]
	v_mfma_f32_16x16x32_bf16 v[116:119], v[196:199], v[164:167], 0
	v_mfma_f32_16x16x32_bf16 v[108:111], v[204:207], v[164:167], 0
	v_mfma_f32_16x16x32_bf16 v[100:103], v[196:199], v[172:175], 0
	v_mfma_f32_16x16x32_bf16 v[96:99], v[204:207], v[172:175], 0
	v_mfma_f32_16x16x32_bf16 v[84:87], v[196:199], v[180:183], 0
	v_mfma_f32_16x16x32_bf16 v[76:79], v[204:207], v[180:183], 0
	v_mfma_f32_16x16x32_bf16 v[68:71], v[196:199], v[188:191], 0
	v_mfma_f32_16x16x32_bf16 v[64:67], v[204:207], v[188:191], 0
	v_mfma_f32_16x16x32_bf16 v[116:119], v[200:203], v[168:171], v[116:119]
	v_mfma_f32_16x16x32_bf16 v[108:111], v[208:211], v[168:171], v[108:111]
	v_mfma_f32_16x16x32_bf16 v[100:103], v[200:203], v[176:179], v[100:103]
	v_mfma_f32_16x16x32_bf16 v[96:99], v[208:211], v[176:179], v[96:99]
	v_mfma_f32_16x16x32_bf16 v[84:87], v[200:203], v[184:187], v[84:87]
	v_mfma_f32_16x16x32_bf16 v[76:79], v[208:211], v[184:187], v[76:79]
	v_mfma_f32_16x16x32_bf16 v[68:71], v[200:203], v[192:195], v[68:71]
	v_mfma_f32_16x16x32_bf16 v[64:67], v[208:211], v[192:195], v[64:67]
	s_setprio 0
	s_barrier
	s_nop 1
	ds_read_b128 v[164:167], v150 offset:16384
	ds_read_b128 v[168:171], v150 offset:17408
	ds_read_b128 v[172:175], v150 offset:18432
	ds_read_b128 v[176:179], v150 offset:19456
	ds_read_b128 v[180:183], v150 offset:20480
	ds_read_b128 v[184:187], v150 offset:21504
	ds_read_b128 v[188:191], v150 offset:22528
	ds_read_b128 v[192:195], v150 offset:23552
	s_add_i32 s30, s45, s7
	v_lshl_add_u64 v[144:145], s[36:37], 0, v[128:129]
	s_mov_b32 m0, s30
	s_nop 0
	global_load_lds_dwordx4 v128, s[36:37]
	v_lshl_add_u64 v[212:213], s[36:37], 0, v[130:131]
	s_add_i32 m0, s30, 0x2000
	s_nop 0
	global_load_lds_dwordx4 v130, s[36:37]
	s_mov_b32 m0, s8
	v_lshl_add_u64 v[214:215], s[38:39], 0, v[128:129]
	global_load_lds_dwordx4 v128, s[38:39]
	v_lshl_add_u64 v[216:217], s[38:39], 0, v[130:131]
	s_mov_b32 m0, s9
	s_nop 0
	global_load_lds_dwordx4 v130, s[38:39]
	s_add_u32 s30, s36, 0xb0000
	s_addc_u32 s31, s37, 0
	s_add_i32 s75, s46, s7
	s_mov_b32 m0, s75
	s_nop 0
	global_load_lds_dwordx4 v128, s[30:31]
	s_add_i32 m0, s75, 0x2000
	s_nop 0
	global_load_lds_dwordx4 v130, s[30:31]
	s_waitcnt vmcnt(6)
	s_waitcnt lgkmcnt(0)
	s_barrier
	s_setprio 1
	v_mfma_f32_16x16x32_bf16 v[60:63], v[140:143], v[164:167], 0
	v_mfma_f32_16x16x32_bf16 v[56:59], v[156:159], v[164:167], 0
	v_mfma_f32_16x16x32_bf16 v[48:51], v[140:143], v[172:175], 0
	v_mfma_f32_16x16x32_bf16 v[40:43], v[156:159], v[172:175], 0
	v_mfma_f32_16x16x32_bf16 v[28:31], v[140:143], v[180:183], 0
	v_mfma_f32_16x16x32_bf16 v[24:27], v[156:159], v[180:183], 0
	v_mfma_f32_16x16x32_bf16 v[16:19], v[140:143], v[188:191], 0
	v_mfma_f32_16x16x32_bf16 v[8:11], v[156:159], v[188:191], 0
	v_mfma_f32_16x16x32_bf16 v[60:63], v[152:155], v[168:171], v[60:63]
	v_mfma_f32_16x16x32_bf16 v[56:59], v[160:163], v[168:171], v[56:59]
	v_mfma_f32_16x16x32_bf16 v[48:51], v[152:155], v[176:179], v[48:51]
	v_mfma_f32_16x16x32_bf16 v[40:43], v[160:163], v[176:179], v[40:43]
	v_mfma_f32_16x16x32_bf16 v[28:31], v[152:155], v[184:187], v[28:31]
	v_mfma_f32_16x16x32_bf16 v[24:27], v[160:163], v[184:187], v[24:27]
	v_mfma_f32_16x16x32_bf16 v[16:19], v[152:155], v[192:195], v[16:19]
	v_mfma_f32_16x16x32_bf16 v[8:11], v[160:163], v[192:195], v[8:11]
	v_mfma_f32_16x16x32_bf16 v[52:55], v[196:199], v[164:167], 0
	v_mfma_f32_16x16x32_bf16 v[44:47], v[204:207], v[164:167], 0
	v_mfma_f32_16x16x32_bf16 v[36:39], v[196:199], v[172:175], 0
	v_mfma_f32_16x16x32_bf16 v[32:35], v[204:207], v[172:175], 0
	v_mfma_f32_16x16x32_bf16 v[20:23], v[196:199], v[180:183], 0
	v_mfma_f32_16x16x32_bf16 v[12:15], v[204:207], v[180:183], 0
	v_mfma_f32_16x16x32_bf16 v[4:7], v[196:199], v[188:191], 0
	v_mfma_f32_16x16x32_bf16 v[0:3], v[204:207], v[188:191], 0
	v_mfma_f32_16x16x32_bf16 v[52:55], v[200:203], v[168:171], v[52:55]
	v_mfma_f32_16x16x32_bf16 v[44:47], v[208:211], v[168:171], v[44:47]
	v_mfma_f32_16x16x32_bf16 v[36:39], v[200:203], v[176:179], v[36:39]
	v_mfma_f32_16x16x32_bf16 v[32:35], v[208:211], v[176:179], v[32:35]
	v_mfma_f32_16x16x32_bf16 v[20:23], v[200:203], v[184:187], v[20:23]
	v_mfma_f32_16x16x32_bf16 v[12:15], v[208:211], v[184:187], v[12:15]
	v_mfma_f32_16x16x32_bf16 v[4:7], v[200:203], v[192:195], v[4:7]
	v_mfma_f32_16x16x32_bf16 v[0:3], v[208:211], v[192:195], v[0:3]
	s_setprio 0
	s_add_i32 s75, 0, 0x18000
	v_add_u32_e32 v160, s75, v147
	s_barrier
; #define PG8_STAGE(bufoff, gbase, voff) do { _Pragma("unroll") for (int _i = 0; _i < 2; ++_i) \
;         __builtin_amdgcn_global_load_lds((const unsigned*)((const char*)(gbase) + (voff)[_i]), (LAS unsigned*)(lds + (bufoff) + ldsw + _i * 8192), 16, 0, 0); } while (0)
; #define PG8_LDA(dst, b, h) do { _Pragma("unroll") for (int m = 0; m < 4; ++m) _Pragma("unroll") for (int k = 0; k < 2; ++k) dst[m][k] = *(const LAS bf16x8*)(lds + PG8_SA(b, h) + aoff + m * 2048 + k * 1024); } while (0)
; #define PG8_WAIT_V(n) asm volatile("s_waitcnt vmcnt(" #n ")" ::: "memory")
; #define PG8_WAIT_L(n) asm volatile("s_waitcnt lgkmcnt(" #n ")" ::: "memory")
; template <class Epi>
; __device__ __forceinline__ void gemm_phase(LAS unsigned char* lds, const Gemm g, const StaticOrder& S, const Epi& E) {
;     ...
;         for (int t = 0; t < nt; t += 2) {
;             const bool last = (t == nt - 2);
;             const char* a1 = cA + (size_t)(t + 1) * kstep;
;             const char* a2 = last ? nA : cA + (size_t)(t + 2) * kstep; const char* b2 = last ? nB : cB + (size_t)(t + 2) * kstep;
;             const char* a3 = a2 + kstep; const char* b3 = b2 + kstep;
;             PG8_LDB(B0, 0, 0); PG8_SCHED; PG8_LDA(At, 0, 0); PG8_STAGE(PG8_SA(1, 1), a1 + hstepA, voffA);
;             PG8_WAIT_L(8); PG8_BAR; PG8_WAIT_L(0); PG8_MMA(0, 0, At, B0); PG8_BAR; PG8_SCHED;
;             PG8_LDB(B1, 0, 1); PG8_STAGE(PG8_SB(0, 0), b2, voffB);
;             PG8_BAR; PG8_WAIT_L(0); PG8_MMA(0, 1, At, B1); PG8_BAR;
;             PG8_LDA(At, 0, 1); PG8_STAGE(PG8_SA(0, 0), a2, voffA);
;             PG8_BAR; PG8_WAIT_L(0); PG8_MMA(1, 0, At, B0); PG8_BAR; PG8_SCHED;
;             PG8_STAGE(PG8_SB(0, 1), b2 + hstepB, voffB);
;             PG8_WAIT_V(6); PG8_BAR; PG8_MMA(1, 1, At, B1); PG8_BAR;
;             PG8_LDB(B0, 1, 0); PG8_SCHED; PG8_LDA(At, 1, 0); PG8_STAGE(PG8_SA(0, 1), a2 + hstepA, voffA);
;             PG8_WAIT_L(8); PG8_BAR; PG8_WAIT_L(0); PG8_MMA(0, 0, At, B0); PG8_BAR; PG8_SCHED;
;             PG8_LDB(B1, 1, 1); PG8_STAGE(PG8_SB(1, 0), b3, voffB);
;             PG8_BAR; PG8_WAIT_L(0); PG8_MMA(0, 1, At, B1); PG8_BAR;
;             PG8_LDA(At, 1, 1); PG8_STAGE(PG8_SA(1, 0), a3, voffA);
;             PG8_BAR; PG8_WAIT_L(0); PG8_MMA(1, 0, At, B0); PG8_BAR; PG8_SCHED;
;             PG8_STAGE(PG8_SB(1, 1), b3 + hstepB, voffB);
;             PG8_WAIT_V(6); PG8_BAR; PG8_MMA(1, 1, At, B1); PG8_BAR;
	ds_read_b128 v[140:143], v160
	ds_read_b128 v[152:155], v160 offset:1024
	ds_read_b128 v[156:159], v160 offset:2048
	ds_read_b128 v[160:163], v160 offset:3072
	s_add_u32 s30, s38, 0xb0000
	s_addc_u32 s31, s39, 0
	s_mov_b32 m0, s40
	ds_read_b128 v[164:167], v150 offset:32768
	ds_read_b128 v[168:171], v150 offset:33792
	ds_read_b128 v[172:175], v150 offset:34816
	ds_read_b128 v[176:179], v150 offset:35840
	ds_read_b128 v[180:183], v150 offset:36864
	ds_read_b128 v[184:187], v150 offset:37888
	ds_read_b128 v[188:191], v150 offset:38912
	ds_read_b128 v[192:195], v150 offset:39936
	global_load_lds_dwordx4 v128, s[30:31]
	s_mov_b32 m0, s41
	s_nop 0
	global_load_lds_dwordx4 v130, s[30:31]
	s_add_i32 s38, 0, 0x1c000
	v_add_u32_e32 v208, s38, v147
	ds_read_b128 v[196:199], v208
	ds_read_b128 v[200:203], v208 offset:1024
	ds_read_b128 v[204:207], v208 offset:2048
	ds_read_b128 v[208:211], v208 offset:3072
	s_waitcnt lgkmcnt(0)
	s_barrier
	s_setprio 1
	v_mfma_f32_16x16x32_bf16 v[124:127], v[140:143], v[164:167], v[124:127]
	v_mfma_f32_16x16x32_bf16 v[120:123], v[156:159], v[164:167], v[120:123]
	v_mfma_f32_16x16x32_bf16 v[112:115], v[140:143], v[172:175], v[112:115]
	v_mfma_f32_16x16x32_bf16 v[104:107], v[156:159], v[172:175], v[104:107]
	v_mfma_f32_16x16x32_bf16 v[92:95], v[140:143], v[180:183], v[92:95]
	v_mfma_f32_16x16x32_bf16 v[88:91], v[156:159], v[180:183], v[88:91]
	v_mfma_f32_16x16x32_bf16 v[80:83], v[140:143], v[188:191], v[80:83]
	v_mfma_f32_16x16x32_bf16 v[72:75], v[156:159], v[188:191], v[72:75]
	v_mfma_f32_16x16x32_bf16 v[124:127], v[152:155], v[168:171], v[124:127]
	v_mfma_f32_16x16x32_bf16 v[120:123], v[160:163], v[168:171], v[120:123]
	v_mfma_f32_16x16x32_bf16 v[112:115], v[152:155], v[176:179], v[112:115]
	v_mfma_f32_16x16x32_bf16 v[104:107], v[160:163], v[176:179], v[104:107]
	v_mfma_f32_16x16x32_bf16 v[92:95], v[152:155], v[184:187], v[92:95]
	v_mfma_f32_16x16x32_bf16 v[88:91], v[160:163], v[184:187], v[88:91]
	v_mfma_f32_16x16x32_bf16 v[80:83], v[152:155], v[192:195], v[80:83]
	v_mfma_f32_16x16x32_bf16 v[72:75], v[160:163], v[192:195], v[72:75]
	v_mfma_f32_16x16x32_bf16 v[116:119], v[196:199], v[164:167], v[116:119]
	v_mfma_f32_16x16x32_bf16 v[108:111], v[204:207], v[164:167], v[108:111]
	v_mfma_f32_16x16x32_bf16 v[100:103], v[196:199], v[172:175], v[100:103]
	v_mfma_f32_16x16x32_bf16 v[96:99], v[204:207], v[172:175], v[96:99]
	v_mfma_f32_16x16x32_bf16 v[84:87], v[196:199], v[180:183], v[84:87]
	v_mfma_f32_16x16x32_bf16 v[76:79], v[204:207], v[180:183], v[76:79]
	v_mfma_f32_16x16x32_bf16 v[68:71], v[196:199], v[188:191], v[68:71]
	v_mfma_f32_16x16x32_bf16 v[64:67], v[204:207], v[188:191], v[64:67]
	v_mfma_f32_16x16x32_bf16 v[116:119], v[200:203], v[168:171], v[116:119]
	v_mfma_f32_16x16x32_bf16 v[108:111], v[208:211], v[168:171], v[108:111]
	v_mfma_f32_16x16x32_bf16 v[100:103], v[200:203], v[176:179], v[100:103]
	v_mfma_f32_16x16x32_bf16 v[96:99], v[208:211], v[176:179], v[96:99]
	v_mfma_f32_16x16x32_bf16 v[84:87], v[200:203], v[184:187], v[84:87]
	v_mfma_f32_16x16x32_bf16 v[76:79], v[208:211], v[184:187], v[76:79]
	v_mfma_f32_16x16x32_bf16 v[68:71], v[200:203], v[192:195], v[68:71]
	v_mfma_f32_16x16x32_bf16 v[64:67], v[208:211], v[192:195], v[64:67]
	s_setprio 0
	s_barrier
	s_nop 1
	ds_read_b128 v[164:167], v150 offset:49152
	ds_read_b128 v[168:171], v150 offset:50176
	ds_read_b128 v[172:175], v150 offset:51200
	ds_read_b128 v[176:179], v150 offset:52224
	ds_read_b128 v[180:183], v150 offset:53248
	ds_read_b128 v[184:187], v150 offset:54272
	ds_read_b128 v[188:191], v150 offset:55296
	ds_read_b128 v[192:195], v150 offset:56320
	s_add_i32 s30, s75, s7
	s_mov_b32 m0, s30
	s_nop 0
	s_add_u32 s100, s36, s22
	s_addc_u32 s101, s37, s23
	global_load_lds_dwordx4 v128, s[100:101]
	s_add_i32 m0, s30, 0x2000
	s_nop 0
	s_add_u32 s100, s36, s22
	s_addc_u32 s101, s37, s23
	global_load_lds_dwordx4 v130, s[100:101]
	s_mov_b32 m0, s43
	v_lshl_add_u64 v[254:255], v[214:215], 0, s[22:23]
	global_load_lds_dwordx4 v[254:255], off
	v_lshl_add_u64 v[144:145], v[216:217], 0, s[22:23]
	s_mov_b32 m0, s44
	s_nop 0
	global_load_lds_dwordx4 v[144:145], off
	s_add_u32 s30, s36, 0xb0080
	s_addc_u32 s31, s37, 0
	s_add_i32 s36, s38, s7
	s_mov_b32 m0, s36
	s_nop 0
	global_load_lds_dwordx4 v128, s[30:31]
	s_add_i32 m0, s36, 0x2000
	s_nop 0
	global_load_lds_dwordx4 v130, s[30:31]
	s_waitcnt vmcnt(6)
	s_waitcnt lgkmcnt(0)
	s_barrier
	s_setprio 1
	v_mfma_f32_16x16x32_bf16 v[60:63], v[140:143], v[164:167], v[60:63]
	v_mfma_f32_16x16x32_bf16 v[56:59], v[156:159], v[164:167], v[56:59]
	v_mfma_f32_16x16x32_bf16 v[48:51], v[140:143], v[172:175], v[48:51]
	v_mfma_f32_16x16x32_bf16 v[40:43], v[156:159], v[172:175], v[40:43]
	v_mfma_f32_16x16x32_bf16 v[28:31], v[140:143], v[180:183], v[28:31]
	v_mfma_f32_16x16x32_bf16 v[24:27], v[156:159], v[180:183], v[24:27]
	v_mfma_f32_16x16x32_bf16 v[16:19], v[140:143], v[188:191], v[16:19]
	v_mfma_f32_16x16x32_bf16 v[8:11], v[156:159], v[188:191], v[8:11]
	v_mfma_f32_16x16x32_bf16 v[60:63], v[152:155], v[168:171], v[60:63]
	v_mfma_f32_16x16x32_bf16 v[56:59], v[160:163], v[168:171], v[56:59]
	v_mfma_f32_16x16x32_bf16 v[48:51], v[152:155], v[176:179], v[48:51]
	v_mfma_f32_16x16x32_bf16 v[40:43], v[160:163], v[176:179], v[40:43]
	v_mfma_f32_16x16x32_bf16 v[28:31], v[152:155], v[184:187], v[28:31]
	v_mfma_f32_16x16x32_bf16 v[24:27], v[160:163], v[184:187], v[24:27]
	v_mfma_f32_16x16x32_bf16 v[16:19], v[152:155], v[192:195], v[16:19]
	v_mfma_f32_16x16x32_bf16 v[8:11], v[160:163], v[192:195], v[8:11]
	v_mfma_f32_16x16x32_bf16 v[52:55], v[196:199], v[164:167], v[52:55]
	v_mfma_f32_16x16x32_bf16 v[44:47], v[204:207], v[164:167], v[44:47]
	v_mfma_f32_16x16x32_bf16 v[36:39], v[196:199], v[172:175], v[36:39]
	v_mfma_f32_16x16x32_bf16 v[32:35], v[204:207], v[172:175], v[32:35]
	v_mfma_f32_16x16x32_bf16 v[20:23], v[196:199], v[180:183], v[20:23]
	v_mfma_f32_16x16x32_bf16 v[12:15], v[204:207], v[180:183], v[12:15]
	v_mfma_f32_16x16x32_bf16 v[4:7], v[196:199], v[188:191], v[4:7]
	v_mfma_f32_16x16x32_bf16 v[0:3], v[204:207], v[188:191], v[0:3]
	v_mfma_f32_16x16x32_bf16 v[52:55], v[200:203], v[168:171], v[52:55]
	v_mfma_f32_16x16x32_bf16 v[44:47], v[208:211], v[168:171], v[44:47]
	v_mfma_f32_16x16x32_bf16 v[36:39], v[200:203], v[176:179], v[36:39]
	v_mfma_f32_16x16x32_bf16 v[32:35], v[208:211], v[176:179], v[32:35]
	v_mfma_f32_16x16x32_bf16 v[20:23], v[200:203], v[184:187], v[20:23]
	v_mfma_f32_16x16x32_bf16 v[12:15], v[208:211], v[184:187], v[12:15]
	v_mfma_f32_16x16x32_bf16 v[4:7], v[200:203], v[192:195], v[4:7]
	v_mfma_f32_16x16x32_bf16 v[0:3], v[208:211], v[192:195], v[0:3]
	s_setprio 0
	s_add_i32 s74, s74, 2
	s_add_u32 s72, s72, 0x100
	s_addc_u32 s73, s73, 0
	s_cmp_gt_u32 s74, 41
	s_mov_b64 s[30:31], s[34:35]
	s_barrier
; #define PG8_STAGE(bufoff, gbase, voff) do { _Pragma("unroll") for (int _i = 0; _i < 2; ++_i) \
;         __builtin_amdgcn_global_load_lds((const unsigned*)((const char*)(gbase) + (voff)[_i]), (LAS unsigned*)(lds + (bufoff) + ldsw + _i * 8192), 16, 0, 0); } while (0)
; #define PG8_LDA(dst, b, h) do { _Pragma("unroll") for (int m = 0; m < 4; ++m) _Pragma("unroll") for (int k = 0; k < 2; ++k) dst[m][k] = *(const LAS bf16x8*)(lds + PG8_SA(b, h) + aoff + m * 2048 + k * 1024); } while (0)
; #define PG8_WAIT_V(n) asm volatile("s_waitcnt vmcnt(" #n ")" ::: "memory")
; #define PG8_WAIT_L(n) asm volatile("s_waitcnt lgkmcnt(" #n ")" ::: "memory")
; template <class Epi>
; __device__ __forceinline__ void gemm_phase(LAS unsigned char* lds, const Gemm g, const StaticOrder& S, const Epi& E) {
;     ...
;         for (int t = 0; t < nt; t += 2) {
;             const bool last = (t == nt - 2);
;             const char* a1 = cA + (size_t)(t + 1) * kstep;
;             const char* a2 = last ? nA : cA + (size_t)(t + 2) * kstep; const char* b2 = last ? nB : cB + (size_t)(t + 2) * kstep;
;             const char* a3 = a2 + kstep; const char* b3 = b2 + kstep;
;             PG8_LDB(B0, 0, 0); PG8_SCHED; PG8_LDA(At, 0, 0); PG8_STAGE(PG8_SA(1, 1), a1 + hstepA, voffA);
;             PG8_WAIT_L(8); PG8_BAR; PG8_WAIT_L(0); PG8_MMA(0, 0, At, B0); PG8_BAR; PG8_SCHED;
;             PG8_LDB(B1, 0, 1); PG8_STAGE(PG8_SB(0, 0), b2, voffB);
;             PG8_BAR; PG8_WAIT_L(0); PG8_MMA(0, 1, At, B1); PG8_BAR;
;             PG8_LDA(At, 0, 1); PG8_STAGE(PG8_SA(0, 0), a2, voffA);
;             PG8_BAR; PG8_WAIT_L(0); PG8_MMA(1, 0, At, B0); PG8_BAR; PG8_SCHED;
;             PG8_STAGE(PG8_SB(0, 1), b2 + hstepB, voffB);
;             PG8_WAIT_V(6); PG8_BAR; PG8_MMA(1, 1, At, B1); PG8_BAR;
;             PG8_LDB(B0, 1, 0); PG8_SCHED; PG8_LDA(At, 1, 0); PG8_STAGE(PG8_SA(0, 1), a2 + hstepA, voffA);
;             PG8_WAIT_L(8); PG8_BAR; PG8_WAIT_L(0); PG8_MMA(0, 0, At, B0); PG8_BAR; PG8_SCHED;
;             PG8_LDB(B1, 1, 1); PG8_STAGE(PG8_SB(1, 0), b3, voffB);
;             PG8_BAR; PG8_WAIT_L(0); PG8_MMA(0, 1, At, B1); PG8_BAR;
;             PG8_LDA(At, 1, 1); PG8_STAGE(PG8_SA(1, 0), a3, voffA);
;             PG8_BAR; PG8_WAIT_L(0); PG8_MMA(1, 0, At, B0); PG8_BAR; PG8_SCHED;
;             PG8_STAGE(PG8_SB(1, 1), b3 + hstepB, voffB);
;             PG8_WAIT_V(6); PG8_BAR; PG8_MMA(1, 1, At, B1); PG8_BAR;
.LBB0_1461:
	ds_read_b128 v[140:143], v149
	ds_read_b128 v[152:155], v149 offset:1024
	ds_read_b128 v[156:159], v149 offset:2048
	ds_read_b128 v[160:163], v149 offset:3072
	s_add_u32 s34, s30, 0x100
	s_addc_u32 s35, s31, 0
	s_cmp_eq_u32 s74, 40
	s_cselect_b32 s39, s13, s35
	s_cselect_b32 s38, s12, s34
	s_cselect_b32 s37, s15, s73
	s_cselect_b32 s36, s14, s72
	s_add_i32 m0, s8, 0xc000
	ds_read_b128 v[164:167], v150
	ds_read_b128 v[168:171], v150 offset:1024
	ds_read_b128 v[172:175], v150 offset:2048
	ds_read_b128 v[176:179], v150 offset:3072
	ds_read_b128 v[180:183], v150 offset:4096
	ds_read_b128 v[184:187], v150 offset:5120
	ds_read_b128 v[188:191], v150 offset:6144
	ds_read_b128 v[192:195], v150 offset:7168
	global_load_lds_dwordx4 v132, s[30:31]
	s_add_i32 m0, s8, 0xe000
	s_nop 0
	global_load_lds_dwordx4 v134, s[30:31]
	ds_read_b128 v[196:199], v151
	ds_read_b128 v[200:203], v151 offset:1024
	ds_read_b128 v[204:207], v151 offset:2048
	ds_read_b128 v[208:211], v151 offset:3072
	s_waitcnt lgkmcnt(0)
	s_barrier
	s_setprio 1
	v_mfma_f32_16x16x32_bf16 v[124:127], v[140:143], v[164:167], v[124:127]
	v_mfma_f32_16x16x32_bf16 v[120:123], v[156:159], v[164:167], v[120:123]
	v_mfma_f32_16x16x32_bf16 v[112:115], v[140:143], v[172:175], v[112:115]
	v_mfma_f32_16x16x32_bf16 v[104:107], v[156:159], v[172:175], v[104:107]
	v_mfma_f32_16x16x32_bf16 v[92:95], v[140:143], v[180:183], v[92:95]
	v_mfma_f32_16x16x32_bf16 v[88:91], v[156:159], v[180:183], v[88:91]
	v_mfma_f32_16x16x32_bf16 v[80:83], v[140:143], v[188:191], v[80:83]
	v_mfma_f32_16x16x32_bf16 v[72:75], v[156:159], v[188:191], v[72:75]
	v_mfma_f32_16x16x32_bf16 v[124:127], v[152:155], v[168:171], v[124:127]
	v_mfma_f32_16x16x32_bf16 v[120:123], v[160:163], v[168:171], v[120:123]
	v_mfma_f32_16x16x32_bf16 v[112:115], v[152:155], v[176:179], v[112:115]
	v_mfma_f32_16x16x32_bf16 v[104:107], v[160:163], v[176:179], v[104:107]
	v_mfma_f32_16x16x32_bf16 v[92:95], v[152:155], v[184:187], v[92:95]
	v_mfma_f32_16x16x32_bf16 v[88:91], v[160:163], v[184:187], v[88:91]
	v_mfma_f32_16x16x32_bf16 v[80:83], v[152:155], v[192:195], v[80:83]
	v_mfma_f32_16x16x32_bf16 v[72:75], v[160:163], v[192:195], v[72:75]
	v_mfma_f32_16x16x32_bf16 v[116:119], v[196:199], v[164:167], v[116:119]
	v_mfma_f32_16x16x32_bf16 v[108:111], v[204:207], v[164:167], v[108:111]
	v_mfma_f32_16x16x32_bf16 v[100:103], v[196:199], v[172:175], v[100:103]
	v_mfma_f32_16x16x32_bf16 v[96:99], v[204:207], v[172:175], v[96:99]
	v_mfma_f32_16x16x32_bf16 v[84:87], v[196:199], v[180:183], v[84:87]
	v_mfma_f32_16x16x32_bf16 v[76:79], v[204:207], v[180:183], v[76:79]
	v_mfma_f32_16x16x32_bf16 v[68:71], v[196:199], v[188:191], v[68:71]
	v_mfma_f32_16x16x32_bf16 v[64:67], v[204:207], v[188:191], v[64:67]
	v_mfma_f32_16x16x32_bf16 v[116:119], v[200:203], v[168:171], v[116:119]
	v_mfma_f32_16x16x32_bf16 v[108:111], v[208:211], v[168:171], v[108:111]
	v_mfma_f32_16x16x32_bf16 v[100:103], v[200:203], v[176:179], v[100:103]
	v_mfma_f32_16x16x32_bf16 v[96:99], v[208:211], v[176:179], v[96:99]
	v_mfma_f32_16x16x32_bf16 v[84:87], v[200:203], v[184:187], v[84:87]
	v_mfma_f32_16x16x32_bf16 v[76:79], v[208:211], v[184:187], v[76:79]
	v_mfma_f32_16x16x32_bf16 v[68:71], v[200:203], v[192:195], v[68:71]
	v_mfma_f32_16x16x32_bf16 v[64:67], v[208:211], v[192:195], v[64:67]
	s_setprio 0
	s_barrier
	s_nop 1
	ds_read_b128 v[164:167], v150 offset:16384
	ds_read_b128 v[168:171], v150 offset:17408
	ds_read_b128 v[172:175], v150 offset:18432
	ds_read_b128 v[176:179], v150 offset:19456
	ds_read_b128 v[180:183], v150 offset:20480
	ds_read_b128 v[184:187], v150 offset:21504
	ds_read_b128 v[188:191], v150 offset:22528
	ds_read_b128 v[192:195], v150 offset:23552
	s_add_i32 s30, s45, s7
	v_lshl_add_u64 v[144:145], s[36:37], 0, v[128:129]
	s_mov_b32 m0, s30
	s_nop 0
	global_load_lds_dwordx4 v128, s[36:37]
	v_lshl_add_u64 v[212:213], s[36:37], 0, v[130:131]
	s_add_i32 m0, s30, 0x2000
	s_nop 0
	global_load_lds_dwordx4 v130, s[36:37]
	s_mov_b32 m0, s8
	v_lshl_add_u64 v[214:215], s[38:39], 0, v[128:129]
	global_load_lds_dwordx4 v128, s[38:39]
	v_lshl_add_u64 v[216:217], s[38:39], 0, v[130:131]
	s_mov_b32 m0, s9
	s_nop 0
	global_load_lds_dwordx4 v130, s[38:39]
	s_add_u32 s30, s36, 0xb0000
	s_addc_u32 s31, s37, 0
	s_add_i32 s75, s46, s7
	s_mov_b32 m0, s75
	s_nop 0
	global_load_lds_dwordx4 v128, s[30:31]
	s_add_i32 m0, s75, 0x2000
	s_nop 0
	global_load_lds_dwordx4 v130, s[30:31]
	s_waitcnt vmcnt(6)
	s_waitcnt lgkmcnt(0)
	s_barrier
	s_setprio 1
	v_mfma_f32_16x16x32_bf16 v[60:63], v[140:143], v[164:167], v[60:63]
	v_mfma_f32_16x16x32_bf16 v[56:59], v[156:159], v[164:167], v[56:59]
	v_mfma_f32_16x16x32_bf16 v[48:51], v[140:143], v[172:175], v[48:51]
	v_mfma_f32_16x16x32_bf16 v[40:43], v[156:159], v[172:175], v[40:43]
	v_mfma_f32_16x16x32_bf16 v[28:31], v[140:143], v[180:183], v[28:31]
	v_mfma_f32_16x16x32_bf16 v[24:27], v[156:159], v[180:183], v[24:27]
	v_mfma_f32_16x16x32_bf16 v[16:19], v[140:143], v[188:191], v[16:19]
	v_mfma_f32_16x16x32_bf16 v[8:11], v[156:159], v[188:191], v[8:11]
	v_mfma_f32_16x16x32_bf16 v[60:63], v[152:155], v[168:171], v[60:63]
	v_mfma_f32_16x16x32_bf16 v[56:59], v[160:163], v[168:171], v[56:59]
	v_mfma_f32_16x16x32_bf16 v[48:51], v[152:155], v[176:179], v[48:51]
	v_mfma_f32_16x16x32_bf16 v[40:43], v[160:163], v[176:179], v[40:43]
	v_mfma_f32_16x16x32_bf16 v[28:31], v[152:155], v[184:187], v[28:31]
	v_mfma_f32_16x16x32_bf16 v[24:27], v[160:163], v[184:187], v[24:27]
	v_mfma_f32_16x16x32_bf16 v[16:19], v[152:155], v[192:195], v[16:19]
	v_mfma_f32_16x16x32_bf16 v[8:11], v[160:163], v[192:195], v[8:11]
	v_mfma_f32_16x16x32_bf16 v[52:55], v[196:199], v[164:167], v[52:55]
	v_mfma_f32_16x16x32_bf16 v[44:47], v[204:207], v[164:167], v[44:47]
	v_mfma_f32_16x16x32_bf16 v[36:39], v[196:199], v[172:175], v[36:39]
	v_mfma_f32_16x16x32_bf16 v[32:35], v[204:207], v[172:175], v[32:35]
	v_mfma_f32_16x16x32_bf16 v[20:23], v[196:199], v[180:183], v[20:23]
	v_mfma_f32_16x16x32_bf16 v[12:15], v[204:207], v[180:183], v[12:15]
	v_mfma_f32_16x16x32_bf16 v[4:7], v[196:199], v[188:191], v[4:7]
	v_mfma_f32_16x16x32_bf16 v[0:3], v[204:207], v[188:191], v[0:3]
	v_mfma_f32_16x16x32_bf16 v[52:55], v[200:203], v[168:171], v[52:55]
	v_mfma_f32_16x16x32_bf16 v[44:47], v[208:211], v[168:171], v[44:47]
	v_mfma_f32_16x16x32_bf16 v[36:39], v[200:203], v[176:179], v[36:39]
	v_mfma_f32_16x16x32_bf16 v[32:35], v[208:211], v[176:179], v[32:35]
	v_mfma_f32_16x16x32_bf16 v[20:23], v[200:203], v[184:187], v[20:23]
	v_mfma_f32_16x16x32_bf16 v[12:15], v[208:211], v[184:187], v[12:15]
	v_mfma_f32_16x16x32_bf16 v[4:7], v[200:203], v[192:195], v[4:7]
	v_mfma_f32_16x16x32_bf16 v[0:3], v[208:211], v[192:195], v[0:3]
	s_setprio 0
	s_add_i32 s75, 0, 0x18000
	v_add_u32_e32 v160, s75, v147
	s_barrier
; #define PG8_STAGE(bufoff, gbase, voff) do { _Pragma("unroll") for (int _i = 0; _i < 2; ++_i) \
;         __builtin_amdgcn_global_load_lds((const unsigned*)((const char*)(gbase) + (voff)[_i]), (LAS unsigned*)(lds + (bufoff) + ldsw + _i * 8192), 16, 0, 0); } while (0)
; #define PG8_LDA(dst, b, h) do { _Pragma("unroll") for (int m = 0; m < 4; ++m) _Pragma("unroll") for (int k = 0; k < 2; ++k) dst[m][k] = *(const LAS bf16x8*)(lds + PG8_SA(b, h) + aoff + m * 2048 + k * 1024); } while (0)
; #define PG8_WAIT_V(n) asm volatile("s_waitcnt vmcnt(" #n ")" ::: "memory")
; #define PG8_WAIT_L(n) asm volatile("s_waitcnt lgkmcnt(" #n ")" ::: "memory")
; template <class Epi>
; __device__ __forceinline__ void gemm_phase(LAS unsigned char* lds, const Gemm g, const StaticOrder& S, const Epi& E) {
;     ...
;         for (int t = 0; t < nt; t += 2) {
;             const bool last = (t == nt - 2);
;             const char* a1 = cA + (size_t)(t + 1) * kstep;
;             const char* a2 = last ? nA : cA + (size_t)(t + 2) * kstep; const char* b2 = last ? nB : cB + (size_t)(t + 2) * kstep;
;             const char* a3 = a2 + kstep; const char* b3 = b2 + kstep;
;             PG8_LDB(B0, 0, 0); PG8_SCHED; PG8_LDA(At, 0, 0); PG8_STAGE(PG8_SA(1, 1), a1 + hstepA, voffA);
;             PG8_WAIT_L(8); PG8_BAR; PG8_WAIT_L(0); PG8_MMA(0, 0, At, B0); PG8_BAR; PG8_SCHED;
;             PG8_LDB(B1, 0, 1); PG8_STAGE(PG8_SB(0, 0), b2, voffB);
;             PG8_BAR; PG8_WAIT_L(0); PG8_MMA(0, 1, At, B1); PG8_BAR;
;             PG8_LDA(At, 0, 1); PG8_STAGE(PG8_SA(0, 0), a2, voffA);
;             PG8_BAR; PG8_WAIT_L(0); PG8_MMA(1, 0, At, B0); PG8_BAR; PG8_SCHED;
;             PG8_STAGE(PG8_SB(0, 1), b2 + hstepB, voffB);
;             PG8_WAIT_V(6); PG8_BAR; PG8_MMA(1, 1, At, B1); PG8_BAR;
;             PG8_LDB(B0, 1, 0); PG8_SCHED; PG8_LDA(At, 1, 0); PG8_STAGE(PG8_SA(0, 1), a2 + hstepA, voffA);
;             PG8_WAIT_L(8); PG8_BAR; PG8_WAIT_L(0); PG8_MMA(0, 0, At, B0); PG8_BAR; PG8_SCHED;
;             PG8_LDB(B1, 1, 1); PG8_STAGE(PG8_SB(1, 0), b3, voffB);
;             PG8_BAR; PG8_WAIT_L(0); PG8_MMA(0, 1, At, B1); PG8_BAR;
;             PG8_LDA(At, 1, 1); PG8_STAGE(PG8_SA(1, 0), a3, voffA);
;             PG8_BAR; PG8_WAIT_L(0); PG8_MMA(1, 0, At, B0); PG8_BAR; PG8_SCHED;
;             PG8_STAGE(PG8_SB(1, 1), b3 + hstepB, voffB);
;             PG8_WAIT_V(6); PG8_BAR; PG8_MMA(1, 1, At, B1); PG8_BAR;
	ds_read_b128 v[140:143], v160
	ds_read_b128 v[152:155], v160 offset:1024
	ds_read_b128 v[156:159], v160 offset:2048
	ds_read_b128 v[160:163], v160 offset:3072
	s_add_u32 s30, s38, 0xb0000
	s_addc_u32 s31, s39, 0
	s_mov_b32 m0, s40
	ds_read_b128 v[164:167], v150 offset:32768
	ds_read_b128 v[168:171], v150 offset:33792
	ds_read_b128 v[172:175], v150 offset:34816
	ds_read_b128 v[176:179], v150 offset:35840
	ds_read_b128 v[180:183], v150 offset:36864
	ds_read_b128 v[184:187], v150 offset:37888
	ds_read_b128 v[188:191], v150 offset:38912
	ds_read_b128 v[192:195], v150 offset:39936
	global_load_lds_dwordx4 v128, s[30:31]
	s_mov_b32 m0, s41
	s_nop 0
	global_load_lds_dwordx4 v130, s[30:31]
	s_add_i32 s38, 0, 0x1c000
	v_add_u32_e32 v208, s38, v147
	ds_read_b128 v[196:199], v208
	ds_read_b128 v[200:203], v208 offset:1024
	ds_read_b128 v[204:207], v208 offset:2048
	ds_read_b128 v[208:211], v208 offset:3072
	s_waitcnt lgkmcnt(0)
	s_barrier
	s_setprio 1
	v_mfma_f32_16x16x32_bf16 v[124:127], v[140:143], v[164:167], v[124:127]
	v_mfma_f32_16x16x32_bf16 v[120:123], v[156:159], v[164:167], v[120:123]
	v_mfma_f32_16x16x32_bf16 v[112:115], v[140:143], v[172:175], v[112:115]
	v_mfma_f32_16x16x32_bf16 v[104:107], v[156:159], v[172:175], v[104:107]
	v_mfma_f32_16x16x32_bf16 v[92:95], v[140:143], v[180:183], v[92:95]
	v_mfma_f32_16x16x32_bf16 v[88:91], v[156:159], v[180:183], v[88:91]
	v_mfma_f32_16x16x32_bf16 v[80:83], v[140:143], v[188:191], v[80:83]
	v_mfma_f32_16x16x32_bf16 v[72:75], v[156:159], v[188:191], v[72:75]
	v_mfma_f32_16x16x32_bf16 v[124:127], v[152:155], v[168:171], v[124:127]
	v_mfma_f32_16x16x32_bf16 v[120:123], v[160:163], v[168:171], v[120:123]
	v_mfma_f32_16x16x32_bf16 v[112:115], v[152:155], v[176:179], v[112:115]
	v_mfma_f32_16x16x32_bf16 v[104:107], v[160:163], v[176:179], v[104:107]
	v_mfma_f32_16x16x32_bf16 v[92:95], v[152:155], v[184:187], v[92:95]
	v_mfma_f32_16x16x32_bf16 v[88:91], v[160:163], v[184:187], v[88:91]
	v_mfma_f32_16x16x32_bf16 v[80:83], v[152:155], v[192:195], v[80:83]
	v_mfma_f32_16x16x32_bf16 v[72:75], v[160:163], v[192:195], v[72:75]
	v_mfma_f32_16x16x32_bf16 v[116:119], v[196:199], v[164:167], v[116:119]
	v_mfma_f32_16x16x32_bf16 v[108:111], v[204:207], v[164:167], v[108:111]
	v_mfma_f32_16x16x32_bf16 v[100:103], v[196:199], v[172:175], v[100:103]
	v_mfma_f32_16x16x32_bf16 v[96:99], v[204:207], v[172:175], v[96:99]
	v_mfma_f32_16x16x32_bf16 v[84:87], v[196:199], v[180:183], v[84:87]
	v_mfma_f32_16x16x32_bf16 v[76:79], v[204:207], v[180:183], v[76:79]
	v_mfma_f32_16x16x32_bf16 v[68:71], v[196:199], v[188:191], v[68:71]
	v_mfma_f32_16x16x32_bf16 v[64:67], v[204:207], v[188:191], v[64:67]
	v_mfma_f32_16x16x32_bf16 v[116:119], v[200:203], v[168:171], v[116:119]
	v_mfma_f32_16x16x32_bf16 v[108:111], v[208:211], v[168:171], v[108:111]
	v_mfma_f32_16x16x32_bf16 v[100:103], v[200:203], v[176:179], v[100:103]
	v_mfma_f32_16x16x32_bf16 v[96:99], v[208:211], v[176:179], v[96:99]
	v_mfma_f32_16x16x32_bf16 v[84:87], v[200:203], v[184:187], v[84:87]
	v_mfma_f32_16x16x32_bf16 v[76:79], v[208:211], v[184:187], v[76:79]
	v_mfma_f32_16x16x32_bf16 v[68:71], v[200:203], v[192:195], v[68:71]
	v_mfma_f32_16x16x32_bf16 v[64:67], v[208:211], v[192:195], v[64:67]
	s_setprio 0
	s_barrier
	s_nop 1
	ds_read_b128 v[164:167], v150 offset:49152
	ds_read_b128 v[168:171], v150 offset:50176
	ds_read_b128 v[172:175], v150 offset:51200
	ds_read_b128 v[176:179], v150 offset:52224
	ds_read_b128 v[180:183], v150 offset:53248
	ds_read_b128 v[184:187], v150 offset:54272
	ds_read_b128 v[188:191], v150 offset:55296
	ds_read_b128 v[192:195], v150 offset:56320
	s_add_i32 s30, s75, s7
	s_mov_b32 m0, s30
	s_nop 0
	s_add_u32 s100, s36, s22
	s_addc_u32 s101, s37, s23
	global_load_lds_dwordx4 v128, s[100:101]
	s_add_i32 m0, s30, 0x2000
	s_nop 0
	s_add_u32 s100, s36, s22
	s_addc_u32 s101, s37, s23
	global_load_lds_dwordx4 v130, s[100:101]
	s_mov_b32 m0, s43
	v_lshl_add_u64 v[254:255], v[214:215], 0, s[22:23]
	global_load_lds_dwordx4 v[254:255], off
	v_lshl_add_u64 v[144:145], v[216:217], 0, s[22:23]
	s_mov_b32 m0, s44
	s_nop 0
	global_load_lds_dwordx4 v[144:145], off
	s_add_u32 s30, s36, 0xb0080
	s_addc_u32 s31, s37, 0
	s_add_i32 s36, s38, s7
	s_mov_b32 m0, s36
	s_nop 0
	global_load_lds_dwordx4 v128, s[30:31]
	s_add_i32 m0, s36, 0x2000
	s_nop 0
	global_load_lds_dwordx4 v130, s[30:31]
	s_waitcnt vmcnt(6)
	s_waitcnt lgkmcnt(0)
	s_barrier
	s_setprio 1
	v_mfma_f32_16x16x32_bf16 v[60:63], v[140:143], v[164:167], v[60:63]
	v_mfma_f32_16x16x32_bf16 v[56:59], v[156:159], v[164:167], v[56:59]
	v_mfma_f32_16x16x32_bf16 v[48:51], v[140:143], v[172:175], v[48:51]
	v_mfma_f32_16x16x32_bf16 v[40:43], v[156:159], v[172:175], v[40:43]
	v_mfma_f32_16x16x32_bf16 v[28:31], v[140:143], v[180:183], v[28:31]
	v_mfma_f32_16x16x32_bf16 v[24:27], v[156:159], v[180:183], v[24:27]
	v_mfma_f32_16x16x32_bf16 v[16:19], v[140:143], v[188:191], v[16:19]
	v_mfma_f32_16x16x32_bf16 v[8:11], v[156:159], v[188:191], v[8:11]
	v_mfma_f32_16x16x32_bf16 v[60:63], v[152:155], v[168:171], v[60:63]
	v_mfma_f32_16x16x32_bf16 v[56:59], v[160:163], v[168:171], v[56:59]
	v_mfma_f32_16x16x32_bf16 v[48:51], v[152:155], v[176:179], v[48:51]
	v_mfma_f32_16x16x32_bf16 v[40:43], v[160:163], v[176:179], v[40:43]
	v_mfma_f32_16x16x32_bf16 v[28:31], v[152:155], v[184:187], v[28:31]
	v_mfma_f32_16x16x32_bf16 v[24:27], v[160:163], v[184:187], v[24:27]
	v_mfma_f32_16x16x32_bf16 v[16:19], v[152:155], v[192:195], v[16:19]
	v_mfma_f32_16x16x32_bf16 v[8:11], v[160:163], v[192:195], v[8:11]
	v_mfma_f32_16x16x32_bf16 v[52:55], v[196:199], v[164:167], v[52:55]
	v_mfma_f32_16x16x32_bf16 v[44:47], v[204:207], v[164:167], v[44:47]
	v_mfma_f32_16x16x32_bf16 v[36:39], v[196:199], v[172:175], v[36:39]
	v_mfma_f32_16x16x32_bf16 v[32:35], v[204:207], v[172:175], v[32:35]
	v_mfma_f32_16x16x32_bf16 v[20:23], v[196:199], v[180:183], v[20:23]
	v_mfma_f32_16x16x32_bf16 v[12:15], v[204:207], v[180:183], v[12:15]
	v_mfma_f32_16x16x32_bf16 v[4:7], v[196:199], v[188:191], v[4:7]
	v_mfma_f32_16x16x32_bf16 v[0:3], v[204:207], v[188:191], v[0:3]
	v_mfma_f32_16x16x32_bf16 v[52:55], v[200:203], v[168:171], v[52:55]
	v_mfma_f32_16x16x32_bf16 v[44:47], v[208:211], v[168:171], v[44:47]
	v_mfma_f32_16x16x32_bf16 v[36:39], v[200:203], v[176:179], v[36:39]
	v_mfma_f32_16x16x32_bf16 v[32:35], v[208:211], v[176:179], v[32:35]
	v_mfma_f32_16x16x32_bf16 v[20:23], v[200:203], v[184:187], v[20:23]
	v_mfma_f32_16x16x32_bf16 v[12:15], v[208:211], v[184:187], v[12:15]
	v_mfma_f32_16x16x32_bf16 v[4:7], v[200:203], v[192:195], v[4:7]
	v_mfma_f32_16x16x32_bf16 v[0:3], v[208:211], v[192:195], v[0:3]
	s_setprio 0
	s_add_i32 s74, s74, 2
	s_add_u32 s72, s72, 0x100
	s_addc_u32 s73, s73, 0
	s_cmp_gt_u32 s74, 41
	s_mov_b64 s[30:31], s[34:35]
	s_barrier
;     __device__ __forceinline__ void operator()(AccRef acc, const Unit& u, int wr, int wc, int fr, int fq) const {
;         const int row0 = u.pm * 256 + wr * 64 + fr, col0 = u.pn * 256 + wc * 32 + 4 * fq;
;         f32x4 sv[2][2], bv[2][2];
; #pragma unroll
;         for (int bj = 0; bj < 2; ++bj)
; #pragma unroll
;             for (int n = 0; n < 2; ++n) {
;                 sv[bj][n] = scale ? *(const f32x4*)(scale + col0 + bj * 128 + n * 16) : (f32x4){1.f, 1.f, 1.f, 1.f};
;                 bv[bj][n] = bias ? *(const f32x4*)(bias + col0 + bj * 128 + n * 16) : (f32x4){0.f, 0.f, 0.f, 0.f}; }
; #pragma unroll
;         for (int ai = 0; ai < 2; ++ai)
; #pragma unroll
;             for (int mh = 0; mh < 2; ++mh) {
;                 f32x4 bs[2][2][2];
; #pragma unroll
;                 for (int m = 0; m < 2; ++m)
; #pragma unroll
;                     for (int bj = 0; bj < 2; ++bj)
; #pragma unroll
;                         for (int n = 0; n < 2; ++n) bs[m][bj][n] = *(const f32x4*)(base + (size_t)(row0 + ai * 128 + (2 * mh + m) * 16) * D + col0 + bj * 128 + n * 16);
; #pragma unroll
;                 for (int m = 0; m < 2; ++m)
; #pragma unroll
;                     for (int bj = 0; bj < 2; ++bj)
; #pragma unroll
;                         for (int n = 0; n < 2; ++n) *(f32x4*)(out + (size_t)(row0 + ai * 128 + (2 * mh + m) * 16) * D + col0 + bj * 128 + n * 16) = bs[m][bj][n] + sv[bj][n] * (acc[ai][bj][2 * mh + m][n] + bv[bj][n]);
	s_cbranch_scc0 .LBB0_1461
	v_lshl_or_b32 v144, s49, 8, v148
	v_lshl_add_u32 v145, s63, 8, v146
	v_lshlrev_b32_e32 v144, 2, v144
	v_lshl_add_u32 v145, v145, 12, v144
	v_add_u32_e32 v216, 0x10000, v145
	v_add_u32_e32 v217, 0x20000, v145
	v_add_u32_e32 v218, 0x30000, v145
	v_add_u32_e32 v232, 0x80000, v145
	v_add_u32_e32 v233, 0x90000, v145
	v_add_u32_e32 v235, 0xa0000, v145
	v_add_u32_e32 v253, 0xb0000, v145
	s_and_b64 vcc, exec, s[10:11]
	s_mov_b32 s49, s47
	s_mov_b32 s63, s48
	s_mov_b64 s[34:35], s[14:15]
	s_mov_b64 s[30:31], s[12:13]
	global_load_dwordx4 v[140:143], v145, s[52:53]
	global_load_dwordx4 v[152:155], v145, s[52:53] offset:64
	global_load_dwordx4 v[156:159], v145, s[52:53] offset:512
	global_load_dwordx4 v[160:163], v145, s[52:53] offset:576
	global_load_dwordx4 v[164:167], v216, s[52:53]
	global_load_dwordx4 v[168:171], v216, s[52:53] offset:64
	global_load_dwordx4 v[172:175], v216, s[52:53] offset:512
	global_load_dwordx4 v[176:179], v216, s[52:53] offset:576
	global_load_dwordx4 v[180:183], v217, s[52:53]
	global_load_dwordx4 v[184:187], v217, s[52:53] offset:64
	global_load_dwordx4 v[188:191], v217, s[52:53] offset:512
	global_load_dwordx4 v[192:195], v217, s[52:53] offset:576
	global_load_dwordx4 v[196:199], v218, s[52:53]
	global_load_dwordx4 v[200:203], v218, s[52:53] offset:64
	global_load_dwordx4 v[204:207], v218, s[52:53] offset:512
	global_load_dwordx4 v[208:211], v218, s[52:53] offset:576
	global_load_dwordx4 v[212:215], v232, s[52:53]
	global_load_dwordx4 v[220:223], v232, s[52:53] offset:64
	global_load_dwordx4 v[224:227], v232, s[52:53] offset:512
	global_load_dwordx4 v[228:231], v232, s[52:53] offset:576
	global_load_dwordx4 v[236:239], v233, s[52:53]
	global_load_dwordx4 v[240:243], v233, s[52:53] offset:64
	global_load_dwordx4 v[244:247], v233, s[52:53] offset:512
	global_load_dwordx4 v[248:251], v233, s[52:53] offset:576
	v_pk_add_f32 v[124:125], v[124:125], 0 op_sel_hi:[1,0]
	v_pk_add_f32 v[126:127], v[126:127], 0 op_sel_hi:[1,0]
	v_pk_add_f32 v[120:121], v[120:121], 0 op_sel_hi:[1,0]
	v_pk_add_f32 v[122:123], v[122:123], 0 op_sel_hi:[1,0]
	v_pk_add_f32 v[116:117], v[116:117], 0 op_sel_hi:[1,0]
	v_pk_add_f32 v[118:119], v[118:119], 0 op_sel_hi:[1,0]
	v_pk_add_f32 v[108:109], v[108:109], 0 op_sel_hi:[1,0]
	v_pk_add_f32 v[110:111], v[110:111], 0 op_sel_hi:[1,0]
	v_pk_add_f32 v[112:113], v[112:113], 0 op_sel_hi:[1,0]
	v_pk_add_f32 v[114:115], v[114:115], 0 op_sel_hi:[1,0]
	v_pk_add_f32 v[104:105], v[104:105], 0 op_sel_hi:[1,0]
	v_pk_add_f32 v[106:107], v[106:107], 0 op_sel_hi:[1,0]
	v_pk_add_f32 v[100:101], v[100:101], 0 op_sel_hi:[1,0]
	v_pk_add_f32 v[102:103], v[102:103], 0 op_sel_hi:[1,0]
	v_pk_add_f32 v[96:97], v[96:97], 0 op_sel_hi:[1,0]
	v_pk_add_f32 v[98:99], v[98:99], 0 op_sel_hi:[1,0]
	v_pk_add_f32 v[92:93], v[92:93], 0 op_sel_hi:[1,0]
	v_pk_add_f32 v[94:95], v[94:95], 0 op_sel_hi:[1,0]
	v_pk_add_f32 v[88:89], v[88:89], 0 op_sel_hi:[1,0]
	v_pk_add_f32 v[90:91], v[90:91], 0 op_sel_hi:[1,0]
	v_pk_add_f32 v[84:85], v[84:85], 0 op_sel_hi:[1,0]
	v_pk_add_f32 v[86:87], v[86:87], 0 op_sel_hi:[1,0]
	v_pk_add_f32 v[76:77], v[76:77], 0 op_sel_hi:[1,0]
	v_pk_add_f32 v[78:79], v[78:79], 0 op_sel_hi:[1,0]
	v_pk_add_f32 v[80:81], v[80:81], 0 op_sel_hi:[1,0]
	v_pk_add_f32 v[82:83], v[82:83], 0 op_sel_hi:[1,0]
	v_pk_add_f32 v[72:73], v[72:73], 0 op_sel_hi:[1,0]
	v_pk_add_f32 v[74:75], v[74:75], 0 op_sel_hi:[1,0]
	v_pk_add_f32 v[68:69], v[68:69], 0 op_sel_hi:[1,0]
	v_pk_add_f32 v[70:71], v[70:71], 0 op_sel_hi:[1,0]
	v_pk_add_f32 v[64:65], v[64:65], 0 op_sel_hi:[1,0]
	v_pk_add_f32 v[66:67], v[66:67], 0 op_sel_hi:[1,0]
	v_pk_add_f32 v[60:61], v[60:61], 0 op_sel_hi:[1,0]
	v_pk_add_f32 v[62:63], v[62:63], 0 op_sel_hi:[1,0]
	v_pk_add_f32 v[56:57], v[56:57], 0 op_sel_hi:[1,0]
	v_pk_add_f32 v[58:59], v[58:59], 0 op_sel_hi:[1,0]
	v_pk_add_f32 v[52:53], v[52:53], 0 op_sel_hi:[1,0]
	v_pk_add_f32 v[54:55], v[54:55], 0 op_sel_hi:[1,0]
	v_pk_add_f32 v[44:45], v[44:45], 0 op_sel_hi:[1,0]
	v_pk_add_f32 v[46:47], v[46:47], 0 op_sel_hi:[1,0]
	v_pk_add_f32 v[48:49], v[48:49], 0 op_sel_hi:[1,0]
	v_pk_add_f32 v[50:51], v[50:51], 0 op_sel_hi:[1,0]
	v_pk_add_f32 v[40:41], v[40:41], 0 op_sel_hi:[1,0]
	v_pk_add_f32 v[42:43], v[42:43], 0 op_sel_hi:[1,0]
	v_pk_add_f32 v[36:37], v[36:37], 0 op_sel_hi:[1,0]
	v_pk_add_f32 v[38:39], v[38:39], 0 op_sel_hi:[1,0]
	v_pk_add_f32 v[32:33], v[32:33], 0 op_sel_hi:[1,0]
	v_pk_add_f32 v[34:35], v[34:35], 0 op_sel_hi:[1,0]
	v_pk_add_f32 v[28:29], v[28:29], 0 op_sel_hi:[1,0]
	v_pk_add_f32 v[30:31], v[30:31], 0 op_sel_hi:[1,0]
	v_pk_add_f32 v[24:25], v[24:25], 0 op_sel_hi:[1,0]
	v_pk_add_f32 v[26:27], v[26:27], 0 op_sel_hi:[1,0]
	v_pk_add_f32 v[20:21], v[20:21], 0 op_sel_hi:[1,0]
	v_pk_add_f32 v[22:23], v[22:23], 0 op_sel_hi:[1,0]
	v_pk_add_f32 v[12:13], v[12:13], 0 op_sel_hi:[1,0]
	v_pk_add_f32 v[14:15], v[14:15], 0 op_sel_hi:[1,0]
	v_pk_add_f32 v[16:17], v[16:17], 0 op_sel_hi:[1,0]
	v_pk_add_f32 v[18:19], v[18:19], 0 op_sel_hi:[1,0]
	v_pk_add_f32 v[8:9], v[8:9], 0 op_sel_hi:[1,0]
	v_pk_add_f32 v[10:11], v[10:11], 0 op_sel_hi:[1,0]
	v_pk_add_f32 v[4:5], v[4:5], 0 op_sel_hi:[1,0]
	v_pk_add_f32 v[6:7], v[6:7], 0 op_sel_hi:[1,0]
	v_pk_add_f32 v[0:1], v[0:1], 0 op_sel_hi:[1,0]
	v_pk_add_f32 v[2:3], v[2:3], 0 op_sel_hi:[1,0]
	s_waitcnt vmcnt(16)
; #define PG8_WAIT_V(n) asm volatile("s_waitcnt vmcnt(" #n ")" ::: "memory")
; #define PG8_BAR __builtin_amdgcn_s_barrier()
; template <class Epi>
; __device__ __forceinline__ void gemm_phase(LAS unsigned char* lds, const Gemm g, const StaticOrder& S, const Epi& E) {
;     ...
;     PG8_WAIT_V(0);
;     if (wr == 0) PG8_BAR;
;     PG8_BAR;
;     __device__ __forceinline__ void operator()(AccRef acc, const Unit& u, int wr, int wc, int fr, int fq) const {
;         const int row0 = u.pm * 256 + wr * 64 + fr, col0 = u.pn * 256 + wc * 32 + 4 * fq;
;         f32x4 sv[2][2], bv[2][2];
; #pragma unroll
;         for (int bj = 0; bj < 2; ++bj)
; #pragma unroll
;             for (int n = 0; n < 2; ++n) {
;                 sv[bj][n] = scale ? *(const f32x4*)(scale + col0 + bj * 128 + n * 16) : (f32x4){1.f, 1.f, 1.f, 1.f};
;                 bv[bj][n] = bias ? *(const f32x4*)(bias + col0 + bj * 128 + n * 16) : (f32x4){0.f, 0.f, 0.f, 0.f}; }
; #pragma unroll
;         for (int ai = 0; ai < 2; ++ai)
; #pragma unroll
;             for (int mh = 0; mh < 2; ++mh) {
;                 f32x4 bs[2][2][2];
; #pragma unroll
;                 for (int m = 0; m < 2; ++m)
; #pragma unroll
;                     for (int bj = 0; bj < 2; ++bj)
; #pragma unroll
;                         for (int n = 0; n < 2; ++n) bs[m][bj][n] = *(const f32x4*)(base + (size_t)(row0 + ai * 128 + (2 * mh + m) * 16) * D + col0 + bj * 128 + n * 16);
; #pragma unroll
;                 for (int m = 0; m < 2; ++m)
; #pragma unroll
;                     for (int bj = 0; bj < 2; ++bj)
; #pragma unroll
;                         for (int n = 0; n < 2; ++n) *(f32x4*)(out + (size_t)(row0 + ai * 128 + (2 * mh + m) * 16) * D + col0 + bj * 128 + n * 16) = bs[m][bj][n] + sv[bj][n] * (acc[ai][bj][2 * mh + m][n] + bv[bj][n]);
;                 asm volatile("" ::: "memory"); }
	v_pk_add_f32 v[124:125], v[124:125], v[140:141]
	v_pk_add_f32 v[126:127], v[126:127], v[142:143]
	v_pk_add_f32 v[120:121], v[120:121], v[152:153]
	v_pk_add_f32 v[122:123], v[122:123], v[154:155]
	v_pk_add_f32 v[116:117], v[116:117], v[156:157]
	v_pk_add_f32 v[118:119], v[118:119], v[158:159]
	v_pk_add_f32 v[108:109], v[108:109], v[160:161]
	v_pk_add_f32 v[110:111], v[110:111], v[162:163]
	v_pk_add_f32 v[112:113], v[112:113], v[164:165]
	v_pk_add_f32 v[114:115], v[114:115], v[166:167]
	v_pk_add_f32 v[104:105], v[104:105], v[168:169]
	v_pk_add_f32 v[106:107], v[106:107], v[170:171]
	v_pk_add_f32 v[100:101], v[100:101], v[172:173]
	v_pk_add_f32 v[102:103], v[102:103], v[174:175]
	v_pk_add_f32 v[96:97], v[96:97], v[176:177]
	v_pk_add_f32 v[98:99], v[98:99], v[178:179]
	global_store_dwordx4 v145, v[124:127], s[52:53]
	global_store_dwordx4 v145, v[120:123], s[52:53] offset:64
	global_store_dwordx4 v145, v[116:119], s[52:53] offset:512
	global_store_dwordx4 v145, v[108:111], s[52:53] offset:576
	global_store_dwordx4 v216, v[112:115], s[52:53]
	global_store_dwordx4 v216, v[104:107], s[52:53] offset:64
	global_store_dwordx4 v216, v[100:103], s[52:53] offset:512
	global_store_dwordx4 v216, v[96:99], s[52:53] offset:576
	global_load_dwordx4 v[140:143], v235, s[52:53]
	global_load_dwordx4 v[152:155], v235, s[52:53] offset:64
	global_load_dwordx4 v[156:159], v235, s[52:53] offset:512
	global_load_dwordx4 v[160:163], v235, s[52:53] offset:576
	global_load_dwordx4 v[164:167], v253, s[52:53]
	global_load_dwordx4 v[168:171], v253, s[52:53] offset:64
	global_load_dwordx4 v[172:175], v253, s[52:53] offset:512
	global_load_dwordx4 v[176:179], v253, s[52:53] offset:576
	s_waitcnt vmcnt(24)
	v_pk_add_f32 v[92:93], v[92:93], v[180:181]
	v_pk_add_f32 v[94:95], v[94:95], v[182:183]
	v_pk_add_f32 v[88:89], v[88:89], v[184:185]
	v_pk_add_f32 v[90:91], v[90:91], v[186:187]
	v_pk_add_f32 v[84:85], v[84:85], v[188:189]
	v_pk_add_f32 v[86:87], v[86:87], v[190:191]
	v_pk_add_f32 v[76:77], v[76:77], v[192:193]
	v_pk_add_f32 v[78:79], v[78:79], v[194:195]
	v_pk_add_f32 v[80:81], v[80:81], v[196:197]
	v_pk_add_f32 v[82:83], v[82:83], v[198:199]
	v_pk_add_f32 v[72:73], v[72:73], v[200:201]
	v_pk_add_f32 v[74:75], v[74:75], v[202:203]
	v_pk_add_f32 v[68:69], v[68:69], v[204:205]
	v_pk_add_f32 v[70:71], v[70:71], v[206:207]
	v_pk_add_f32 v[64:65], v[64:65], v[208:209]
	v_pk_add_f32 v[66:67], v[66:67], v[210:211]
	global_store_dwordx4 v217, v[92:95], s[52:53]
	global_store_dwordx4 v217, v[88:91], s[52:53] offset:64
	global_store_dwordx4 v217, v[84:87], s[52:53] offset:512
	global_store_dwordx4 v217, v[76:79], s[52:53] offset:576
	global_store_dwordx4 v218, v[80:83], s[52:53]
	global_store_dwordx4 v218, v[72:75], s[52:53] offset:64
	global_store_dwordx4 v218, v[68:71], s[52:53] offset:512
	global_store_dwordx4 v218, v[64:67], s[52:53] offset:576
	s_waitcnt vmcnt(24)
	v_pk_add_f32 v[60:61], v[60:61], v[212:213]
	v_pk_add_f32 v[62:63], v[62:63], v[214:215]
	v_pk_add_f32 v[56:57], v[56:57], v[220:221]
	v_pk_add_f32 v[58:59], v[58:59], v[222:223]
	v_pk_add_f32 v[52:53], v[52:53], v[224:225]
	v_pk_add_f32 v[54:55], v[54:55], v[226:227]
	v_pk_add_f32 v[44:45], v[44:45], v[228:229]
	v_pk_add_f32 v[46:47], v[46:47], v[230:231]
	v_pk_add_f32 v[48:49], v[48:49], v[236:237]
	v_pk_add_f32 v[50:51], v[50:51], v[238:239]
	v_pk_add_f32 v[40:41], v[40:41], v[240:241]
	v_pk_add_f32 v[42:43], v[42:43], v[242:243]
	v_pk_add_f32 v[36:37], v[36:37], v[244:245]
	v_pk_add_f32 v[38:39], v[38:39], v[246:247]
	v_pk_add_f32 v[32:33], v[32:33], v[248:249]
	v_pk_add_f32 v[34:35], v[34:35], v[250:251]
	global_store_dwordx4 v232, v[60:63], s[52:53]
	global_store_dwordx4 v232, v[56:59], s[52:53] offset:64
	global_store_dwordx4 v232, v[52:55], s[52:53] offset:512
	global_store_dwordx4 v232, v[44:47], s[52:53] offset:576
	global_store_dwordx4 v233, v[48:51], s[52:53]
	global_store_dwordx4 v233, v[40:43], s[52:53] offset:64
	global_store_dwordx4 v233, v[36:39], s[52:53] offset:512
	global_store_dwordx4 v233, v[32:35], s[52:53] offset:576
	s_waitcnt vmcnt(16)
	v_pk_add_f32 v[28:29], v[28:29], v[140:141]
	v_pk_add_f32 v[30:31], v[30:31], v[142:143]
	v_pk_add_f32 v[24:25], v[24:25], v[152:153]
	v_pk_add_f32 v[26:27], v[26:27], v[154:155]
	v_pk_add_f32 v[20:21], v[20:21], v[156:157]
	v_pk_add_f32 v[22:23], v[22:23], v[158:159]
	v_pk_add_f32 v[12:13], v[12:13], v[160:161]
	v_pk_add_f32 v[14:15], v[14:15], v[162:163]
	v_pk_add_f32 v[16:17], v[16:17], v[164:165]
	v_pk_add_f32 v[18:19], v[18:19], v[166:167]
	v_pk_add_f32 v[8:9], v[8:9], v[168:169]
	v_pk_add_f32 v[10:11], v[10:11], v[170:171]
	v_pk_add_f32 v[4:5], v[4:5], v[172:173]
	v_pk_add_f32 v[6:7], v[6:7], v[174:175]
	v_pk_add_f32 v[0:1], v[0:1], v[176:177]
	v_pk_add_f32 v[2:3], v[2:3], v[178:179]
	global_store_dwordx4 v235, v[28:31], s[52:53]
	global_store_dwordx4 v235, v[24:27], s[52:53] offset:64
	global_store_dwordx4 v235, v[20:23], s[52:53] offset:512
	global_store_dwordx4 v235, v[12:15], s[52:53] offset:576
	global_store_dwordx4 v253, v[16:19], s[52:53]
	global_store_dwordx4 v253, v[8:11], s[52:53] offset:64
	global_store_dwordx4 v253, v[4:7], s[52:53] offset:512
	global_store_dwordx4 v253, v[0:3], s[52:53] offset:576
	s_cbranch_vccz .LBB0_1450
	s_waitcnt vmcnt(0)
	s_cmpk_gt_u32 s4, 0xff
	s_cbranch_scc1 .LBB0_1465
	s_barrier

; #define PG8_STAGE(bufoff, gbase, voff) do { _Pragma("unroll") for (int _i = 0; _i < 2; ++_i) \
;         __builtin_amdgcn_global_load_lds((const unsigned*)((const char*)(gbase) + (voff)[_i]), (LAS unsigned*)(lds + (bufoff) + ldsw + _i * 8192), 16, 0, 0); } while (0)
; #define PG8_WAIT_V(n) asm volatile("s_waitcnt vmcnt(" #n ")" ::: "memory")
; template <class Epi>
; __device__ __forceinline__ void gemm_phase(LAS unsigned char* lds, const Gemm g, const StaticOrder& S, const Epi& E) {
;     ...
;     for (;;) {
;         const bool has_next = S.next(ui + 1, nxt);
;         const char* nA = has_next ? (const char*)g.A + (size_t)nxt.pm * tstepA + (size_t)(nxt.pn >> g.a_shift) * g.a_step : cA; const char* nB = has_next ? (const char*)g.Bt + (size_t)nxt.pn * tstepB : cB;
;         for (int t = 0; t < nt; t += 2) {
;             const bool last = (t == nt - 2);
;             const char* a1 = cA + (size_t)(t + 1) * kstep;
;             const char* a2 = last ? nA : cA + (size_t)(t + 2) * kstep; const char* b2 = last ? nB : cB + (size_t)(t + 2) * kstep;
;             const char* a3 = a2 + kstep; const char* b3 = b2 + kstep;
;             PG8_LDB(B0, 0, 0); PG8_SCHED; PG8_LDA(At, 0, 0); PG8_STAGE(PG8_SA(1, 1), a1 + hstepA, voffA);
;             PG8_WAIT_L(8); PG8_BAR; PG8_WAIT_L(0); PG8_MMA(0, 0, At, B0); PG8_BAR; PG8_SCHED;
;             PG8_LDB(B1, 0, 1); PG8_STAGE(PG8_SB(0, 0), b2, voffB);
;             PG8_BAR; PG8_WAIT_L(0); PG8_MMA(0, 1, At, B1); PG8_BAR;
;             PG8_LDA(At, 0, 1); PG8_STAGE(PG8_SA(0, 0), a2, voffA);
;             PG8_BAR; PG8_WAIT_L(0); PG8_MMA(1, 0, At, B0); PG8_BAR; PG8_SCHED;
;             PG8_STAGE(PG8_SB(0, 1), b2 + hstepB, voffB);
;             PG8_WAIT_V(6); PG8_BAR; PG8_MMA(1, 1, At, B1); PG8_BAR;
;             PG8_LDB(B0, 1, 0); PG8_SCHED; PG8_LDA(At, 1, 0); PG8_STAGE(PG8_SA(0, 1), a2 + hstepA, voffA);
;             PG8_WAIT_L(8); PG8_BAR; PG8_WAIT_L(0); PG8_MMA(0, 0, At, B0); PG8_BAR; PG8_SCHED;
;             PG8_LDB(B1, 1, 1); PG8_STAGE(PG8_SB(1, 0), b3, voffB);
;             PG8_BAR; PG8_WAIT_L(0); PG8_MMA(0, 1, At, B1); PG8_BAR;
;             PG8_LDA(At, 1, 1); PG8_STAGE(PG8_SA(1, 0), a3, voffA);
;             PG8_BAR; PG8_WAIT_L(0); PG8_MMA(1, 0, At, B0); PG8_BAR; PG8_SCHED;
;             PG8_STAGE(PG8_SB(1, 1), b3 + hstepB, voffB);
;             PG8_WAIT_V(6); PG8_BAR; PG8_MMA(1, 1, At, B1); PG8_BAR;
.LBB0_1582:
	s_ashr_i32 s25, s24, 31
	v_cmp_lt_i64_e32 vcc, s[12:13], v[162:163]
	s_lshl_b64 s[12:13], s[24:25], 19
	s_add_u32 s26, s66, s12
	s_addc_u32 s27, s67, s13
	s_and_b64 s[12:13], vcc, exec
	s_cselect_b32 s25, s27, s39
	s_cselect_b32 s31, s26, s38
	s_ashr_i32 s23, s22, 31
	s_lshl_b64 s[12:13], s[22:23], 19
	s_add_u32 s28, s5, s12
	s_addc_u32 s29, s6, s13
	s_and_b64 s[12:13], vcc, exec
	s_cselect_b32 s23, s29, s37
	s_cselect_b32 s35, s28, s36
	s_add_u32 s12, s38, 0x40080
	s_addc_u32 s13, s39, 0
	s_add_u32 s38, s36, 0x100
	s_addc_u32 s39, s37, 0
	s_mov_b32 s74, -2
	ds_read_b128 v[80:83], v180
	ds_read_b128 v[84:87], v180 offset:1024
	ds_read_b128 v[88:91], v180 offset:2048
	ds_read_b128 v[92:95], v180 offset:3072
	s_add_u32 s14, s12, 0xfffc0080
	s_addc_u32 s15, s13, -1
	s_cmp_eq_u32 s74, 12
	s_cselect_b32 s37, s25, s15
	s_cselect_b32 s36, s31, s14
	s_cselect_b32 s15, s23, s39
	s_cselect_b32 s14, s35, s38
	s_add_i32 m0, s8, 0xc000
	ds_read_b128 v[166:169], v181
	ds_read_b128 v[170:173], v181 offset:1024
	ds_read_b128 v[186:189], v181 offset:2048
	ds_read_b128 v[190:193], v181 offset:3072
	ds_read_b128 v[194:197], v181 offset:4096
	ds_read_b128 v[198:201], v181 offset:5120
	ds_read_b128 v[202:205], v181 offset:6144
	ds_read_b128 v[206:209], v181 offset:7168
	global_load_lds_dwordx4 v158, s[12:13]
	s_add_i32 m0, s8, 0xe000
	s_nop 0
	global_load_lds_dwordx4 v160, s[12:13]
	ds_read_b128 v[210:213], v182
	ds_read_b128 v[214:217], v182 offset:1024
	ds_read_b128 v[220:223], v182 offset:2048
	ds_read_b128 v[224:227], v182 offset:3072
	s_waitcnt lgkmcnt(0)
	s_barrier
	s_setprio 1
	v_mfma_f32_16x16x32_bf16 v[140:143], v[80:83], v[166:169], 0
	v_mfma_f32_16x16x32_bf16 v[136:139], v[88:91], v[166:169], 0
	v_mfma_f32_16x16x32_bf16 v[124:127], v[80:83], v[186:189], 0
	v_mfma_f32_16x16x32_bf16 v[120:123], v[88:91], v[186:189], 0
	v_mfma_f32_16x16x32_bf16 v[108:111], v[80:83], v[194:197], 0
	v_mfma_f32_16x16x32_bf16 v[104:107], v[88:91], v[194:197], 0
	v_mfma_f32_16x16x32_bf16 v[76:79], v[80:83], v[202:205], 0
	v_mfma_f32_16x16x32_bf16 v[72:75], v[88:91], v[202:205], 0
	v_mfma_f32_16x16x32_bf16 v[140:143], v[84:87], v[170:173], v[140:143]
	v_mfma_f32_16x16x32_bf16 v[136:139], v[92:95], v[170:173], v[136:139]
	v_mfma_f32_16x16x32_bf16 v[124:127], v[84:87], v[190:193], v[124:127]
	v_mfma_f32_16x16x32_bf16 v[120:123], v[92:95], v[190:193], v[120:123]
	v_mfma_f32_16x16x32_bf16 v[108:111], v[84:87], v[198:201], v[108:111]
	v_mfma_f32_16x16x32_bf16 v[104:107], v[92:95], v[198:201], v[104:107]
	v_mfma_f32_16x16x32_bf16 v[76:79], v[84:87], v[206:209], v[76:79]
	v_mfma_f32_16x16x32_bf16 v[72:75], v[92:95], v[206:209], v[72:75]
	v_mfma_f32_16x16x32_bf16 v[132:135], v[210:213], v[166:169], 0
	v_mfma_f32_16x16x32_bf16 v[128:131], v[220:223], v[166:169], 0
	v_mfma_f32_16x16x32_bf16 v[116:119], v[210:213], v[186:189], 0
	v_mfma_f32_16x16x32_bf16 v[112:115], v[220:223], v[186:189], 0
	v_mfma_f32_16x16x32_bf16 v[100:103], v[210:213], v[194:197], 0
	v_mfma_f32_16x16x32_bf16 v[96:99], v[220:223], v[194:197], 0
	v_mfma_f32_16x16x32_bf16 v[68:71], v[210:213], v[202:205], 0
	v_mfma_f32_16x16x32_bf16 v[64:67], v[220:223], v[202:205], 0
	v_mfma_f32_16x16x32_bf16 v[132:135], v[214:217], v[170:173], v[132:135]
	v_mfma_f32_16x16x32_bf16 v[128:131], v[224:227], v[170:173], v[128:131]
	v_mfma_f32_16x16x32_bf16 v[116:119], v[214:217], v[190:193], v[116:119]
	v_mfma_f32_16x16x32_bf16 v[112:115], v[224:227], v[190:193], v[112:115]
	v_mfma_f32_16x16x32_bf16 v[100:103], v[214:217], v[198:201], v[100:103]
	v_mfma_f32_16x16x32_bf16 v[96:99], v[224:227], v[198:201], v[96:99]
	v_mfma_f32_16x16x32_bf16 v[68:71], v[214:217], v[206:209], v[68:71]
	v_mfma_f32_16x16x32_bf16 v[64:67], v[224:227], v[206:209], v[64:67]
	s_setprio 0
	s_barrier
	s_nop 1
	ds_read_b128 v[166:169], v181 offset:16384
	ds_read_b128 v[170:173], v181 offset:17408
	ds_read_b128 v[186:189], v181 offset:18432
	ds_read_b128 v[190:193], v181 offset:19456
	ds_read_b128 v[194:197], v181 offset:20480
	ds_read_b128 v[198:201], v181 offset:21504
	ds_read_b128 v[202:205], v181 offset:22528
	ds_read_b128 v[206:209], v181 offset:23552
	s_add_i32 s75, s48, s7
	v_lshl_add_u64 v[228:229], s[14:15], 0, v[146:147]
	s_mov_b32 m0, s75
	s_nop 0
	global_load_lds_dwordx4 v146, s[14:15]
	v_lshl_add_u64 v[230:231], s[14:15], 0, v[150:151]
	s_add_i32 m0, s75, 0x2000
	s_nop 0
	global_load_lds_dwordx4 v150, s[14:15]
	s_mov_b32 m0, s8
	v_lshl_add_u64 v[232:233], s[36:37], 0, v[144:145]
	global_load_lds_dwordx4 v144, s[36:37]
	v_lshl_add_u64 v[236:237], s[36:37], 0, v[148:149]
	s_mov_b32 m0, s9
	s_nop 0
	global_load_lds_dwordx4 v148, s[36:37]
	s_add_u32 s76, s14, 0x40000
	s_addc_u32 s77, s15, 0
	s_add_i32 s75, s49, s7
	s_mov_b32 m0, s75
	s_nop 0
	global_load_lds_dwordx4 v146, s[76:77]
	s_add_i32 m0, s75, 0x2000
	s_nop 0
	global_load_lds_dwordx4 v150, s[76:77]
	s_waitcnt vmcnt(6)
	s_waitcnt lgkmcnt(0)
	s_barrier
; #define PG8_STAGE(bufoff, gbase, voff) do { _Pragma("unroll") for (int _i = 0; _i < 2; ++_i) \
;         __builtin_amdgcn_global_load_lds((const unsigned*)((const char*)(gbase) + (voff)[_i]), (LAS unsigned*)(lds + (bufoff) + ldsw + _i * 8192), 16, 0, 0); } while (0)
; #define PG8_LDA(dst, b, h) do { _Pragma("unroll") for (int m = 0; m < 4; ++m) _Pragma("unroll") for (int k = 0; k < 2; ++k) dst[m][k] = *(const LAS bf16x8*)(lds + PG8_SA(b, h) + aoff + m * 2048 + k * 1024); } while (0)
; #define PG8_WAIT_V(n) asm volatile("s_waitcnt vmcnt(" #n ")" ::: "memory")
; #define PG8_WAIT_L(n) asm volatile("s_waitcnt lgkmcnt(" #n ")" ::: "memory")
; template <class Epi>
; __device__ __forceinline__ void gemm_phase(LAS unsigned char* lds, const Gemm g, const StaticOrder& S, const Epi& E) {
;     ...
;         for (int t = 0; t < nt; t += 2) {
;             const bool last = (t == nt - 2);
;             const char* a1 = cA + (size_t)(t + 1) * kstep;
;             const char* a2 = last ? nA : cA + (size_t)(t + 2) * kstep; const char* b2 = last ? nB : cB + (size_t)(t + 2) * kstep;
;             const char* a3 = a2 + kstep; const char* b3 = b2 + kstep;
;             PG8_LDB(B0, 0, 0); PG8_SCHED; PG8_LDA(At, 0, 0); PG8_STAGE(PG8_SA(1, 1), a1 + hstepA, voffA);
;             PG8_WAIT_L(8); PG8_BAR; PG8_WAIT_L(0); PG8_MMA(0, 0, At, B0); PG8_BAR; PG8_SCHED;
;             PG8_LDB(B1, 0, 1); PG8_STAGE(PG8_SB(0, 0), b2, voffB);
;             PG8_BAR; PG8_WAIT_L(0); PG8_MMA(0, 1, At, B1); PG8_BAR;
;             PG8_LDA(At, 0, 1); PG8_STAGE(PG8_SA(0, 0), a2, voffA);
;             PG8_BAR; PG8_WAIT_L(0); PG8_MMA(1, 0, At, B0); PG8_BAR; PG8_SCHED;
;             PG8_STAGE(PG8_SB(0, 1), b2 + hstepB, voffB);
;             PG8_WAIT_V(6); PG8_BAR; PG8_MMA(1, 1, At, B1); PG8_BAR;
;             PG8_LDB(B0, 1, 0); PG8_SCHED; PG8_LDA(At, 1, 0); PG8_STAGE(PG8_SA(0, 1), a2 + hstepA, voffA);
;             PG8_WAIT_L(8); PG8_BAR; PG8_WAIT_L(0); PG8_MMA(0, 0, At, B0); PG8_BAR; PG8_SCHED;
;             PG8_LDB(B1, 1, 1); PG8_STAGE(PG8_SB(1, 0), b3, voffB);
;             PG8_BAR; PG8_WAIT_L(0); PG8_MMA(0, 1, At, B1); PG8_BAR;
;             PG8_LDA(At, 1, 1); PG8_STAGE(PG8_SA(1, 0), a3, voffA);
;             PG8_BAR; PG8_WAIT_L(0); PG8_MMA(1, 0, At, B0); PG8_BAR; PG8_SCHED;
;             PG8_STAGE(PG8_SB(1, 1), b3 + hstepB, voffB);
;             PG8_WAIT_V(6); PG8_BAR; PG8_MMA(1, 1, At, B1); PG8_BAR;
	s_setprio 1
	v_mfma_f32_16x16x32_bf16 v[60:63], v[80:83], v[166:169], 0
	v_mfma_f32_16x16x32_bf16 v[56:59], v[88:91], v[166:169], 0
	v_mfma_f32_16x16x32_bf16 v[44:47], v[80:83], v[186:189], 0
	v_mfma_f32_16x16x32_bf16 v[40:43], v[88:91], v[186:189], 0
	v_mfma_f32_16x16x32_bf16 v[28:31], v[80:83], v[194:197], 0
	v_mfma_f32_16x16x32_bf16 v[24:27], v[88:91], v[194:197], 0
	v_mfma_f32_16x16x32_bf16 v[12:15], v[80:83], v[202:205], 0
	v_mfma_f32_16x16x32_bf16 v[8:11], v[88:91], v[202:205], 0
	v_mfma_f32_16x16x32_bf16 v[60:63], v[84:87], v[170:173], v[60:63]
	v_mfma_f32_16x16x32_bf16 v[56:59], v[92:95], v[170:173], v[56:59]
	v_mfma_f32_16x16x32_bf16 v[44:47], v[84:87], v[190:193], v[44:47]
	v_mfma_f32_16x16x32_bf16 v[40:43], v[92:95], v[190:193], v[40:43]
	v_mfma_f32_16x16x32_bf16 v[28:31], v[84:87], v[198:201], v[28:31]
	v_mfma_f32_16x16x32_bf16 v[24:27], v[92:95], v[198:201], v[24:27]
	v_mfma_f32_16x16x32_bf16 v[12:15], v[84:87], v[206:209], v[12:15]
	v_mfma_f32_16x16x32_bf16 v[8:11], v[92:95], v[206:209], v[8:11]
	v_mfma_f32_16x16x32_bf16 v[52:55], v[210:213], v[166:169], 0
	v_mfma_f32_16x16x32_bf16 v[48:51], v[220:223], v[166:169], 0
	v_mfma_f32_16x16x32_bf16 v[36:39], v[210:213], v[186:189], 0
	v_mfma_f32_16x16x32_bf16 v[32:35], v[220:223], v[186:189], 0
	v_mfma_f32_16x16x32_bf16 v[20:23], v[210:213], v[194:197], 0
	v_mfma_f32_16x16x32_bf16 v[16:19], v[220:223], v[194:197], 0
	v_mfma_f32_16x16x32_bf16 v[4:7], v[210:213], v[202:205], 0
	v_mfma_f32_16x16x32_bf16 v[0:3], v[220:223], v[202:205], 0
	v_mfma_f32_16x16x32_bf16 v[52:55], v[214:217], v[170:173], v[52:55]
	v_mfma_f32_16x16x32_bf16 v[48:51], v[224:227], v[170:173], v[48:51]
	v_mfma_f32_16x16x32_bf16 v[36:39], v[214:217], v[190:193], v[36:39]
	v_mfma_f32_16x16x32_bf16 v[32:35], v[224:227], v[190:193], v[32:35]
	v_mfma_f32_16x16x32_bf16 v[20:23], v[214:217], v[198:201], v[20:23]
	v_mfma_f32_16x16x32_bf16 v[16:19], v[224:227], v[198:201], v[16:19]
	v_mfma_f32_16x16x32_bf16 v[4:7], v[214:217], v[206:209], v[4:7]
	v_mfma_f32_16x16x32_bf16 v[0:3], v[224:227], v[206:209], v[0:3]
	s_setprio 0
	s_add_i32 s75, 0, 0x18000
	v_add_u32_e32 v92, s75, v175
	s_barrier
	ds_read_b128 v[80:83], v92
	ds_read_b128 v[84:87], v92 offset:1024
	ds_read_b128 v[88:91], v92 offset:2048
	ds_read_b128 v[92:95], v92 offset:3072
	s_add_u32 s36, s36, 0x40000
	s_addc_u32 s37, s37, 0
	s_mov_b32 m0, s40
	ds_read_b128 v[166:169], v181 offset:32768
	ds_read_b128 v[170:173], v181 offset:33792
	ds_read_b128 v[186:189], v181 offset:34816
	ds_read_b128 v[190:193], v181 offset:35840
	ds_read_b128 v[194:197], v181 offset:36864
	ds_read_b128 v[198:201], v181 offset:37888
	ds_read_b128 v[202:205], v181 offset:38912
	ds_read_b128 v[206:209], v181 offset:39936
	global_load_lds_dwordx4 v144, s[36:37]
	s_mov_b32 m0, s41
	s_nop 0
	global_load_lds_dwordx4 v148, s[36:37]
	s_add_i32 s36, 0, 0x1c000
	v_add_u32_e32 v152, s36, v175
	ds_read_b128 v[210:213], v152
	ds_read_b128 v[214:217], v152 offset:1024
	ds_read_b128 v[220:223], v152 offset:2048
	ds_read_b128 v[224:227], v152 offset:3072
	s_waitcnt lgkmcnt(0)
	s_barrier
	s_setprio 1
	v_mfma_f32_16x16x32_bf16 v[140:143], v[80:83], v[166:169], v[140:143]
	v_mfma_f32_16x16x32_bf16 v[136:139], v[88:91], v[166:169], v[136:139]
	v_mfma_f32_16x16x32_bf16 v[124:127], v[80:83], v[186:189], v[124:127]
	v_mfma_f32_16x16x32_bf16 v[120:123], v[88:91], v[186:189], v[120:123]
	v_mfma_f32_16x16x32_bf16 v[108:111], v[80:83], v[194:197], v[108:111]
	v_mfma_f32_16x16x32_bf16 v[104:107], v[88:91], v[194:197], v[104:107]
	v_mfma_f32_16x16x32_bf16 v[76:79], v[80:83], v[202:205], v[76:79]
	v_mfma_f32_16x16x32_bf16 v[72:75], v[88:91], v[202:205], v[72:75]
	v_mfma_f32_16x16x32_bf16 v[140:143], v[84:87], v[170:173], v[140:143]
	v_mfma_f32_16x16x32_bf16 v[136:139], v[92:95], v[170:173], v[136:139]
	v_mfma_f32_16x16x32_bf16 v[124:127], v[84:87], v[190:193], v[124:127]
	v_mfma_f32_16x16x32_bf16 v[120:123], v[92:95], v[190:193], v[120:123]
	v_mfma_f32_16x16x32_bf16 v[108:111], v[84:87], v[198:201], v[108:111]
	v_mfma_f32_16x16x32_bf16 v[104:107], v[92:95], v[198:201], v[104:107]
	v_mfma_f32_16x16x32_bf16 v[76:79], v[84:87], v[206:209], v[76:79]
	v_mfma_f32_16x16x32_bf16 v[72:75], v[92:95], v[206:209], v[72:75]
	v_mfma_f32_16x16x32_bf16 v[132:135], v[210:213], v[166:169], v[132:135]
	v_mfma_f32_16x16x32_bf16 v[128:131], v[220:223], v[166:169], v[128:131]
	v_mfma_f32_16x16x32_bf16 v[116:119], v[210:213], v[186:189], v[116:119]
	v_mfma_f32_16x16x32_bf16 v[112:115], v[220:223], v[186:189], v[112:115]
	v_mfma_f32_16x16x32_bf16 v[100:103], v[210:213], v[194:197], v[100:103]
	v_mfma_f32_16x16x32_bf16 v[96:99], v[220:223], v[194:197], v[96:99]
	v_mfma_f32_16x16x32_bf16 v[68:71], v[210:213], v[202:205], v[68:71]
	v_mfma_f32_16x16x32_bf16 v[64:67], v[220:223], v[202:205], v[64:67]
	v_mfma_f32_16x16x32_bf16 v[132:135], v[214:217], v[170:173], v[132:135]
	v_mfma_f32_16x16x32_bf16 v[128:131], v[224:227], v[170:173], v[128:131]
	v_mfma_f32_16x16x32_bf16 v[116:119], v[214:217], v[190:193], v[116:119]
	v_mfma_f32_16x16x32_bf16 v[112:115], v[224:227], v[190:193], v[112:115]
	v_mfma_f32_16x16x32_bf16 v[100:103], v[214:217], v[198:201], v[100:103]
	v_mfma_f32_16x16x32_bf16 v[96:99], v[224:227], v[198:201], v[96:99]
	v_mfma_f32_16x16x32_bf16 v[68:71], v[214:217], v[206:209], v[68:71]
	v_mfma_f32_16x16x32_bf16 v[64:67], v[224:227], v[206:209], v[64:67]
	s_setprio 0
	s_barrier
; #define PG8_STAGE(bufoff, gbase, voff) do { _Pragma("unroll") for (int _i = 0; _i < 2; ++_i) \
;         __builtin_amdgcn_global_load_lds((const unsigned*)((const char*)(gbase) + (voff)[_i]), (LAS unsigned*)(lds + (bufoff) + ldsw + _i * 8192), 16, 0, 0); } while (0)
; #define PG8_LDA(dst, b, h) do { _Pragma("unroll") for (int m = 0; m < 4; ++m) _Pragma("unroll") for (int k = 0; k < 2; ++k) dst[m][k] = *(const LAS bf16x8*)(lds + PG8_SA(b, h) + aoff + m * 2048 + k * 1024); } while (0)
; #define PG8_WAIT_V(n) asm volatile("s_waitcnt vmcnt(" #n ")" ::: "memory")
; #define PG8_WAIT_L(n) asm volatile("s_waitcnt lgkmcnt(" #n ")" ::: "memory")
; template <class Epi>
; __device__ __forceinline__ void gemm_phase(LAS unsigned char* lds, const Gemm g, const StaticOrder& S, const Epi& E) {
;     ...
;         for (int t = 0; t < nt; t += 2) {
;             const bool last = (t == nt - 2);
;             const char* a1 = cA + (size_t)(t + 1) * kstep;
;             const char* a2 = last ? nA : cA + (size_t)(t + 2) * kstep; const char* b2 = last ? nB : cB + (size_t)(t + 2) * kstep;
;             const char* a3 = a2 + kstep; const char* b3 = b2 + kstep;
;             PG8_LDB(B0, 0, 0); PG8_SCHED; PG8_LDA(At, 0, 0); PG8_STAGE(PG8_SA(1, 1), a1 + hstepA, voffA);
;             PG8_WAIT_L(8); PG8_BAR; PG8_WAIT_L(0); PG8_MMA(0, 0, At, B0); PG8_BAR; PG8_SCHED;
;             PG8_LDB(B1, 0, 1); PG8_STAGE(PG8_SB(0, 0), b2, voffB);
;             PG8_BAR; PG8_WAIT_L(0); PG8_MMA(0, 1, At, B1); PG8_BAR;
;             PG8_LDA(At, 0, 1); PG8_STAGE(PG8_SA(0, 0), a2, voffA);
;             PG8_BAR; PG8_WAIT_L(0); PG8_MMA(1, 0, At, B0); PG8_BAR; PG8_SCHED;
;             PG8_STAGE(PG8_SB(0, 1), b2 + hstepB, voffB);
;             PG8_WAIT_V(6); PG8_BAR; PG8_MMA(1, 1, At, B1); PG8_BAR;
;             PG8_LDB(B0, 1, 0); PG8_SCHED; PG8_LDA(At, 1, 0); PG8_STAGE(PG8_SA(0, 1), a2 + hstepA, voffA);
;             PG8_WAIT_L(8); PG8_BAR; PG8_WAIT_L(0); PG8_MMA(0, 0, At, B0); PG8_BAR; PG8_SCHED;
;             PG8_LDB(B1, 1, 1); PG8_STAGE(PG8_SB(1, 0), b3, voffB);
;             PG8_BAR; PG8_WAIT_L(0); PG8_MMA(0, 1, At, B1); PG8_BAR;
;             PG8_LDA(At, 1, 1); PG8_STAGE(PG8_SA(1, 0), a3, voffA);
;             PG8_BAR; PG8_WAIT_L(0); PG8_MMA(1, 0, At, B0); PG8_BAR; PG8_SCHED;
;             PG8_STAGE(PG8_SB(1, 1), b3 + hstepB, voffB);
;             PG8_WAIT_V(6); PG8_BAR; PG8_MMA(1, 1, At, B1); PG8_BAR;
	s_nop 1
	ds_read_b128 v[166:169], v181 offset:49152
	ds_read_b128 v[170:173], v181 offset:50176
	ds_read_b128 v[186:189], v181 offset:51200
	ds_read_b128 v[190:193], v181 offset:52224
	ds_read_b128 v[194:197], v181 offset:53248
	ds_read_b128 v[198:201], v181 offset:54272
	ds_read_b128 v[202:205], v181 offset:55296
	ds_read_b128 v[206:209], v181 offset:56320
	s_add_i32 s37, s75, s7
	s_mov_b32 m0, s37
	s_nop 0
	s_add_u32 s100, s14, s16
	s_addc_u32 s101, s15, s17
	global_load_lds_dwordx4 v146, s[100:101]
	s_add_i32 m0, s37, 0x2000
	s_nop 0
	s_add_u32 s100, s14, s16
	s_addc_u32 s101, s15, s17
	global_load_lds_dwordx4 v150, s[100:101]
	s_mov_b32 m0, s45
	v_lshl_add_u64 v[254:255], v[232:233], 0, s[16:17]
	global_load_lds_dwordx4 v[254:255], off
	v_lshl_add_u64 v[228:229], v[236:237], 0, s[16:17]
	s_mov_b32 m0, s46
	s_nop 0
	global_load_lds_dwordx4 v[228:229], off
	s_add_u32 s14, s14, 0x40080
	s_addc_u32 s15, s15, 0
	s_add_i32 s36, s36, s7
	s_mov_b32 m0, s36
	s_nop 0
	global_load_lds_dwordx4 v146, s[14:15]
	s_add_i32 m0, s36, 0x2000
	s_nop 0
	global_load_lds_dwordx4 v150, s[14:15]
	s_waitcnt vmcnt(6)
	s_waitcnt lgkmcnt(0)
	s_barrier
	s_setprio 1
	v_mfma_f32_16x16x32_bf16 v[60:63], v[80:83], v[166:169], v[60:63]
	v_mfma_f32_16x16x32_bf16 v[56:59], v[88:91], v[166:169], v[56:59]
	v_mfma_f32_16x16x32_bf16 v[44:47], v[80:83], v[186:189], v[44:47]
	v_mfma_f32_16x16x32_bf16 v[40:43], v[88:91], v[186:189], v[40:43]
	v_mfma_f32_16x16x32_bf16 v[28:31], v[80:83], v[194:197], v[28:31]
	v_mfma_f32_16x16x32_bf16 v[24:27], v[88:91], v[194:197], v[24:27]
	v_mfma_f32_16x16x32_bf16 v[12:15], v[80:83], v[202:205], v[12:15]
	v_mfma_f32_16x16x32_bf16 v[8:11], v[88:91], v[202:205], v[8:11]
	v_mfma_f32_16x16x32_bf16 v[60:63], v[84:87], v[170:173], v[60:63]
	v_mfma_f32_16x16x32_bf16 v[56:59], v[92:95], v[170:173], v[56:59]
	v_mfma_f32_16x16x32_bf16 v[44:47], v[84:87], v[190:193], v[44:47]
	v_mfma_f32_16x16x32_bf16 v[40:43], v[92:95], v[190:193], v[40:43]
	v_mfma_f32_16x16x32_bf16 v[28:31], v[84:87], v[198:201], v[28:31]
	v_mfma_f32_16x16x32_bf16 v[24:27], v[92:95], v[198:201], v[24:27]
	v_mfma_f32_16x16x32_bf16 v[12:15], v[84:87], v[206:209], v[12:15]
	v_mfma_f32_16x16x32_bf16 v[8:11], v[92:95], v[206:209], v[8:11]
	v_mfma_f32_16x16x32_bf16 v[52:55], v[210:213], v[166:169], v[52:55]
	v_mfma_f32_16x16x32_bf16 v[48:51], v[220:223], v[166:169], v[48:51]
	v_mfma_f32_16x16x32_bf16 v[36:39], v[210:213], v[186:189], v[36:39]
	v_mfma_f32_16x16x32_bf16 v[32:35], v[220:223], v[186:189], v[32:35]
	v_mfma_f32_16x16x32_bf16 v[20:23], v[210:213], v[194:197], v[20:23]
	v_mfma_f32_16x16x32_bf16 v[16:19], v[220:223], v[194:197], v[16:19]
	v_mfma_f32_16x16x32_bf16 v[4:7], v[210:213], v[202:205], v[4:7]
	v_mfma_f32_16x16x32_bf16 v[0:3], v[220:223], v[202:205], v[0:3]
	v_mfma_f32_16x16x32_bf16 v[52:55], v[214:217], v[170:173], v[52:55]
	v_mfma_f32_16x16x32_bf16 v[48:51], v[224:227], v[170:173], v[48:51]
	v_mfma_f32_16x16x32_bf16 v[36:39], v[214:217], v[190:193], v[36:39]
	v_mfma_f32_16x16x32_bf16 v[32:35], v[224:227], v[190:193], v[32:35]
	v_mfma_f32_16x16x32_bf16 v[20:23], v[214:217], v[198:201], v[20:23]
	v_mfma_f32_16x16x32_bf16 v[16:19], v[224:227], v[198:201], v[16:19]
	v_mfma_f32_16x16x32_bf16 v[4:7], v[214:217], v[206:209], v[4:7]
	v_mfma_f32_16x16x32_bf16 v[0:3], v[224:227], v[206:209], v[0:3]
	s_setprio 0
	s_add_i32 s74, s74, 2
	s_add_u32 s12, s12, 0x100
	s_addc_u32 s13, s13, 0
	s_add_u32 s38, s38, 0x100
	s_addc_u32 s39, s39, 0
	s_cmp_gt_u32 s74, 13
	s_barrier
.LBB0_1583:
	ds_read_b128 v[80:83], v180
	ds_read_b128 v[84:87], v180 offset:1024
	ds_read_b128 v[88:91], v180 offset:2048
	ds_read_b128 v[92:95], v180 offset:3072
	s_add_u32 s14, s12, 0xfffc0080
	s_addc_u32 s15, s13, -1
	s_cmp_eq_u32 s74, 12
	s_cselect_b32 s37, s25, s15
	s_cselect_b32 s36, s31, s14
	s_cselect_b32 s15, s23, s39
	s_cselect_b32 s14, s35, s38
	s_add_i32 m0, s8, 0xc000
	ds_read_b128 v[166:169], v181
	ds_read_b128 v[170:173], v181 offset:1024
	ds_read_b128 v[186:189], v181 offset:2048
	ds_read_b128 v[190:193], v181 offset:3072
	ds_read_b128 v[194:197], v181 offset:4096
	ds_read_b128 v[198:201], v181 offset:5120
	ds_read_b128 v[202:205], v181 offset:6144
	ds_read_b128 v[206:209], v181 offset:7168
	global_load_lds_dwordx4 v158, s[12:13]
	s_add_i32 m0, s8, 0xe000
	s_nop 0
	global_load_lds_dwordx4 v160, s[12:13]
	ds_read_b128 v[210:213], v182
	ds_read_b128 v[214:217], v182 offset:1024
	ds_read_b128 v[220:223], v182 offset:2048
	ds_read_b128 v[224:227], v182 offset:3072
	s_waitcnt lgkmcnt(0)
	s_barrier
; #define PG8_STAGE(bufoff, gbase, voff) do { _Pragma("unroll") for (int _i = 0; _i < 2; ++_i) \
;         __builtin_amdgcn_global_load_lds((const unsigned*)((const char*)(gbase) + (voff)[_i]), (LAS unsigned*)(lds + (bufoff) + ldsw + _i * 8192), 16, 0, 0); } while (0)
; #define PG8_LDA(dst, b, h) do { _Pragma("unroll") for (int m = 0; m < 4; ++m) _Pragma("unroll") for (int k = 0; k < 2; ++k) dst[m][k] = *(const LAS bf16x8*)(lds + PG8_SA(b, h) + aoff + m * 2048 + k * 1024); } while (0)
; #define PG8_WAIT_V(n) asm volatile("s_waitcnt vmcnt(" #n ")" ::: "memory")
; #define PG8_WAIT_L(n) asm volatile("s_waitcnt lgkmcnt(" #n ")" ::: "memory")
; template <class Epi>
; __device__ __forceinline__ void gemm_phase(LAS unsigned char* lds, const Gemm g, const StaticOrder& S, const Epi& E) {
;     ...
;         for (int t = 0; t < nt; t += 2) {
;             const bool last = (t == nt - 2);
;             const char* a1 = cA + (size_t)(t + 1) * kstep;
;             const char* a2 = last ? nA : cA + (size_t)(t + 2) * kstep; const char* b2 = last ? nB : cB + (size_t)(t + 2) * kstep;
;             const char* a3 = a2 + kstep; const char* b3 = b2 + kstep;
;             PG8_LDB(B0, 0, 0); PG8_SCHED; PG8_LDA(At, 0, 0); PG8_STAGE(PG8_SA(1, 1), a1 + hstepA, voffA);
;             PG8_WAIT_L(8); PG8_BAR; PG8_WAIT_L(0); PG8_MMA(0, 0, At, B0); PG8_BAR; PG8_SCHED;
;             PG8_LDB(B1, 0, 1); PG8_STAGE(PG8_SB(0, 0), b2, voffB);
;             PG8_BAR; PG8_WAIT_L(0); PG8_MMA(0, 1, At, B1); PG8_BAR;
;             PG8_LDA(At, 0, 1); PG8_STAGE(PG8_SA(0, 0), a2, voffA);
;             PG8_BAR; PG8_WAIT_L(0); PG8_MMA(1, 0, At, B0); PG8_BAR; PG8_SCHED;
;             PG8_STAGE(PG8_SB(0, 1), b2 + hstepB, voffB);
;             PG8_WAIT_V(6); PG8_BAR; PG8_MMA(1, 1, At, B1); PG8_BAR;
;             PG8_LDB(B0, 1, 0); PG8_SCHED; PG8_LDA(At, 1, 0); PG8_STAGE(PG8_SA(0, 1), a2 + hstepA, voffA);
;             PG8_WAIT_L(8); PG8_BAR; PG8_WAIT_L(0); PG8_MMA(0, 0, At, B0); PG8_BAR; PG8_SCHED;
;             PG8_LDB(B1, 1, 1); PG8_STAGE(PG8_SB(1, 0), b3, voffB);
;             PG8_BAR; PG8_WAIT_L(0); PG8_MMA(0, 1, At, B1); PG8_BAR;
;             PG8_LDA(At, 1, 1); PG8_STAGE(PG8_SA(1, 0), a3, voffA);
;             PG8_BAR; PG8_WAIT_L(0); PG8_MMA(1, 0, At, B0); PG8_BAR; PG8_SCHED;
;             PG8_STAGE(PG8_SB(1, 1), b3 + hstepB, voffB);
;             PG8_WAIT_V(6); PG8_BAR; PG8_MMA(1, 1, At, B1); PG8_BAR;
	s_setprio 1
	v_mfma_f32_16x16x32_bf16 v[140:143], v[80:83], v[166:169], v[140:143]
	v_mfma_f32_16x16x32_bf16 v[136:139], v[88:91], v[166:169], v[136:139]
	v_mfma_f32_16x16x32_bf16 v[124:127], v[80:83], v[186:189], v[124:127]
	v_mfma_f32_16x16x32_bf16 v[120:123], v[88:91], v[186:189], v[120:123]
	v_mfma_f32_16x16x32_bf16 v[108:111], v[80:83], v[194:197], v[108:111]
	v_mfma_f32_16x16x32_bf16 v[104:107], v[88:91], v[194:197], v[104:107]
	v_mfma_f32_16x16x32_bf16 v[76:79], v[80:83], v[202:205], v[76:79]
	v_mfma_f32_16x16x32_bf16 v[72:75], v[88:91], v[202:205], v[72:75]
	v_mfma_f32_16x16x32_bf16 v[140:143], v[84:87], v[170:173], v[140:143]
	v_mfma_f32_16x16x32_bf16 v[136:139], v[92:95], v[170:173], v[136:139]
	v_mfma_f32_16x16x32_bf16 v[124:127], v[84:87], v[190:193], v[124:127]
	v_mfma_f32_16x16x32_bf16 v[120:123], v[92:95], v[190:193], v[120:123]
	v_mfma_f32_16x16x32_bf16 v[108:111], v[84:87], v[198:201], v[108:111]
	v_mfma_f32_16x16x32_bf16 v[104:107], v[92:95], v[198:201], v[104:107]
	v_mfma_f32_16x16x32_bf16 v[76:79], v[84:87], v[206:209], v[76:79]
	v_mfma_f32_16x16x32_bf16 v[72:75], v[92:95], v[206:209], v[72:75]
	v_mfma_f32_16x16x32_bf16 v[132:135], v[210:213], v[166:169], v[132:135]
	v_mfma_f32_16x16x32_bf16 v[128:131], v[220:223], v[166:169], v[128:131]
	v_mfma_f32_16x16x32_bf16 v[116:119], v[210:213], v[186:189], v[116:119]
	v_mfma_f32_16x16x32_bf16 v[112:115], v[220:223], v[186:189], v[112:115]
	v_mfma_f32_16x16x32_bf16 v[100:103], v[210:213], v[194:197], v[100:103]
	v_mfma_f32_16x16x32_bf16 v[96:99], v[220:223], v[194:197], v[96:99]
	v_mfma_f32_16x16x32_bf16 v[68:71], v[210:213], v[202:205], v[68:71]
	v_mfma_f32_16x16x32_bf16 v[64:67], v[220:223], v[202:205], v[64:67]
	v_mfma_f32_16x16x32_bf16 v[132:135], v[214:217], v[170:173], v[132:135]
	v_mfma_f32_16x16x32_bf16 v[128:131], v[224:227], v[170:173], v[128:131]
	v_mfma_f32_16x16x32_bf16 v[116:119], v[214:217], v[190:193], v[116:119]
	v_mfma_f32_16x16x32_bf16 v[112:115], v[224:227], v[190:193], v[112:115]
	v_mfma_f32_16x16x32_bf16 v[100:103], v[214:217], v[198:201], v[100:103]
	v_mfma_f32_16x16x32_bf16 v[96:99], v[224:227], v[198:201], v[96:99]
	v_mfma_f32_16x16x32_bf16 v[68:71], v[214:217], v[206:209], v[68:71]
	v_mfma_f32_16x16x32_bf16 v[64:67], v[224:227], v[206:209], v[64:67]
	s_setprio 0
	s_barrier
	s_nop 1
	ds_read_b128 v[166:169], v181 offset:16384
	ds_read_b128 v[170:173], v181 offset:17408
	ds_read_b128 v[186:189], v181 offset:18432
	ds_read_b128 v[190:193], v181 offset:19456
	ds_read_b128 v[194:197], v181 offset:20480
	ds_read_b128 v[198:201], v181 offset:21504
	ds_read_b128 v[202:205], v181 offset:22528
	ds_read_b128 v[206:209], v181 offset:23552
	s_add_i32 s75, s48, s7
	v_lshl_add_u64 v[228:229], s[14:15], 0, v[146:147]
	s_mov_b32 m0, s75
	s_nop 0
	global_load_lds_dwordx4 v146, s[14:15]
	v_lshl_add_u64 v[230:231], s[14:15], 0, v[150:151]
	s_add_i32 m0, s75, 0x2000
	s_nop 0
	global_load_lds_dwordx4 v150, s[14:15]
	s_mov_b32 m0, s8
	v_lshl_add_u64 v[232:233], s[36:37], 0, v[144:145]
	global_load_lds_dwordx4 v144, s[36:37]
	v_lshl_add_u64 v[236:237], s[36:37], 0, v[148:149]
	s_mov_b32 m0, s9
	s_nop 0
	global_load_lds_dwordx4 v148, s[36:37]
	s_add_u32 s76, s14, 0x40000
	s_addc_u32 s77, s15, 0
	s_add_i32 s75, s49, s7
	s_mov_b32 m0, s75
	s_nop 0
	global_load_lds_dwordx4 v146, s[76:77]
	s_add_i32 m0, s75, 0x2000
	s_nop 0
	global_load_lds_dwordx4 v150, s[76:77]
	s_waitcnt vmcnt(6)
	s_waitcnt lgkmcnt(0)
	s_barrier
	s_setprio 1
	v_mfma_f32_16x16x32_bf16 v[60:63], v[80:83], v[166:169], v[60:63]
	v_mfma_f32_16x16x32_bf16 v[56:59], v[88:91], v[166:169], v[56:59]
	v_mfma_f32_16x16x32_bf16 v[44:47], v[80:83], v[186:189], v[44:47]
	v_mfma_f32_16x16x32_bf16 v[40:43], v[88:91], v[186:189], v[40:43]
	v_mfma_f32_16x16x32_bf16 v[28:31], v[80:83], v[194:197], v[28:31]
	v_mfma_f32_16x16x32_bf16 v[24:27], v[88:91], v[194:197], v[24:27]
	v_mfma_f32_16x16x32_bf16 v[12:15], v[80:83], v[202:205], v[12:15]
	v_mfma_f32_16x16x32_bf16 v[8:11], v[88:91], v[202:205], v[8:11]
	v_mfma_f32_16x16x32_bf16 v[60:63], v[84:87], v[170:173], v[60:63]
	v_mfma_f32_16x16x32_bf16 v[56:59], v[92:95], v[170:173], v[56:59]
	v_mfma_f32_16x16x32_bf16 v[44:47], v[84:87], v[190:193], v[44:47]
	v_mfma_f32_16x16x32_bf16 v[40:43], v[92:95], v[190:193], v[40:43]
	v_mfma_f32_16x16x32_bf16 v[28:31], v[84:87], v[198:201], v[28:31]
	v_mfma_f32_16x16x32_bf16 v[24:27], v[92:95], v[198:201], v[24:27]
	v_mfma_f32_16x16x32_bf16 v[12:15], v[84:87], v[206:209], v[12:15]
	v_mfma_f32_16x16x32_bf16 v[8:11], v[92:95], v[206:209], v[8:11]
	v_mfma_f32_16x16x32_bf16 v[52:55], v[210:213], v[166:169], v[52:55]
	v_mfma_f32_16x16x32_bf16 v[48:51], v[220:223], v[166:169], v[48:51]
	v_mfma_f32_16x16x32_bf16 v[36:39], v[210:213], v[186:189], v[36:39]
	v_mfma_f32_16x16x32_bf16 v[32:35], v[220:223], v[186:189], v[32:35]
	v_mfma_f32_16x16x32_bf16 v[20:23], v[210:213], v[194:197], v[20:23]
	v_mfma_f32_16x16x32_bf16 v[16:19], v[220:223], v[194:197], v[16:19]
	v_mfma_f32_16x16x32_bf16 v[4:7], v[210:213], v[202:205], v[4:7]
	v_mfma_f32_16x16x32_bf16 v[0:3], v[220:223], v[202:205], v[0:3]
	v_mfma_f32_16x16x32_bf16 v[52:55], v[214:217], v[170:173], v[52:55]
	v_mfma_f32_16x16x32_bf16 v[48:51], v[224:227], v[170:173], v[48:51]
	v_mfma_f32_16x16x32_bf16 v[36:39], v[214:217], v[190:193], v[36:39]
	v_mfma_f32_16x16x32_bf16 v[32:35], v[224:227], v[190:193], v[32:35]
	v_mfma_f32_16x16x32_bf16 v[20:23], v[214:217], v[198:201], v[20:23]
	v_mfma_f32_16x16x32_bf16 v[16:19], v[224:227], v[198:201], v[16:19]
	v_mfma_f32_16x16x32_bf16 v[4:7], v[214:217], v[206:209], v[4:7]
	v_mfma_f32_16x16x32_bf16 v[0:3], v[224:227], v[206:209], v[0:3]
	s_setprio 0
	s_add_i32 s75, 0, 0x18000
	v_add_u32_e32 v92, s75, v175
	s_barrier
; template <class Epi>
; __device__ __forceinline__ void gemm_phase(LAS unsigned char* lds, const Gemm g, const StaticOrder& S, const Epi& E) {
;     ...
;         for (int t = 0; t < nt; t += 2) {
;             const bool last = (t == nt - 2);
;             const char* a1 = cA + (size_t)(t + 1) * kstep;
;             const char* a2 = last ? nA : cA + (size_t)(t + 2) * kstep; const char* b2 = last ? nB : cB + (size_t)(t + 2) * kstep;
;             const char* a3 = a2 + kstep; const char* b3 = b2 + kstep;
;             PG8_LDB(B0, 0, 0); PG8_SCHED; PG8_LDA(At, 0, 0); PG8_STAGE(PG8_SA(1, 1), a1 + hstepA, voffA);
;             PG8_WAIT_L(8); PG8_BAR; PG8_WAIT_L(0); PG8_MMA(0, 0, At, B0); PG8_BAR; PG8_SCHED;
;             PG8_LDB(B1, 0, 1); PG8_STAGE(PG8_SB(0, 0), b2, voffB);
;             PG8_BAR; PG8_WAIT_L(0); PG8_MMA(0, 1, At, B1); PG8_BAR;
;             PG8_LDA(At, 0, 1); PG8_STAGE(PG8_SA(0, 0), a2, voffA);
;             PG8_BAR; PG8_WAIT_L(0); PG8_MMA(1, 0, At, B0); PG8_BAR; PG8_SCHED;
;             PG8_STAGE(PG8_SB(0, 1), b2 + hstepB, voffB);
;             PG8_WAIT_V(6); PG8_BAR; PG8_MMA(1, 1, At, B1); PG8_BAR;
;             PG8_LDB(B0, 1, 0); PG8_SCHED; PG8_LDA(At, 1, 0); PG8_STAGE(PG8_SA(0, 1), a2 + hstepA, voffA);
;             PG8_WAIT_L(8); PG8_BAR; PG8_WAIT_L(0); PG8_MMA(0, 0, At, B0); PG8_BAR; PG8_SCHED;
;             PG8_LDB(B1, 1, 1); PG8_STAGE(PG8_SB(1, 0), b3, voffB);
;             PG8_BAR; PG8_WAIT_L(0); PG8_MMA(0, 1, At, B1); PG8_BAR;
;             PG8_LDA(At, 1, 1); PG8_STAGE(PG8_SA(1, 0), a3, voffA);
;             PG8_BAR; PG8_WAIT_L(0); PG8_MMA(1, 0, At, B0); PG8_BAR; PG8_SCHED;
;             PG8_STAGE(PG8_SB(1, 1), b3 + hstepB, voffB);
;             PG8_WAIT_V(6); PG8_BAR; PG8_MMA(1, 1, At, B1); PG8_BAR;
;     __device__ __forceinline__ void operator()(AccRef acc, const Unit& u, int wr, int wc, int fr, int fq) const {
;         const int which = u.pn >> 2, row0 = u.pm * 256 + wr * 64 + fr, col0 = (u.pn & 3) * 256 + wc * 64 + 8 * fq;
;         bf16_t* dst = QKV + (size_t)which * ((size_t)T * D);
;         f32x4 gv[2][2];
; #pragma unroll
;         for (int bj = 0; bj < 2; ++bj)
; #pragma unroll
;             for (int n = 0; n < 2; ++n) { const f32x4 a = *(const f32x4*)(qg + 32 * bj + 8 * fq + 4 * n), b = *(const f32x4*)(kg + 32 * bj + 8 * fq + 4 * n);
;                 gv[bj][n] = which == 0 ? a : (which == 1 ? b : (f32x4){1.f, 1.f, 1.f, 1.f}); }
	ds_read_b128 v[80:83], v92
	ds_read_b128 v[84:87], v92 offset:1024
	ds_read_b128 v[88:91], v92 offset:2048
	ds_read_b128 v[92:95], v92 offset:3072
	s_add_u32 s36, s36, 0x40000
	s_addc_u32 s37, s37, 0
	s_mov_b32 m0, s40
	ds_read_b128 v[166:169], v181 offset:32768
	ds_read_b128 v[170:173], v181 offset:33792
	ds_read_b128 v[186:189], v181 offset:34816
	ds_read_b128 v[190:193], v181 offset:35840
	ds_read_b128 v[194:197], v181 offset:36864
	ds_read_b128 v[198:201], v181 offset:37888
	ds_read_b128 v[202:205], v181 offset:38912
	ds_read_b128 v[206:209], v181 offset:39936
	global_load_lds_dwordx4 v144, s[36:37]
	s_mov_b32 m0, s41
	s_nop 0
	global_load_lds_dwordx4 v148, s[36:37]
	s_add_i32 s36, 0, 0x1c000
	v_add_u32_e32 v152, s36, v175
	ds_read_b128 v[210:213], v152
	ds_read_b128 v[214:217], v152 offset:1024
	ds_read_b128 v[220:223], v152 offset:2048
	ds_read_b128 v[224:227], v152 offset:3072
	s_waitcnt lgkmcnt(0)
	s_barrier
	s_setprio 1
	v_mfma_f32_16x16x32_bf16 v[140:143], v[80:83], v[166:169], v[140:143]
	v_mfma_f32_16x16x32_bf16 v[136:139], v[88:91], v[166:169], v[136:139]
	v_mfma_f32_16x16x32_bf16 v[124:127], v[80:83], v[186:189], v[124:127]
	v_mfma_f32_16x16x32_bf16 v[120:123], v[88:91], v[186:189], v[120:123]
	v_mfma_f32_16x16x32_bf16 v[108:111], v[80:83], v[194:197], v[108:111]
	v_mfma_f32_16x16x32_bf16 v[104:107], v[88:91], v[194:197], v[104:107]
	v_mfma_f32_16x16x32_bf16 v[76:79], v[80:83], v[202:205], v[76:79]
	v_mfma_f32_16x16x32_bf16 v[72:75], v[88:91], v[202:205], v[72:75]
	v_mfma_f32_16x16x32_bf16 v[140:143], v[84:87], v[170:173], v[140:143]
	v_mfma_f32_16x16x32_bf16 v[136:139], v[92:95], v[170:173], v[136:139]
	v_mfma_f32_16x16x32_bf16 v[124:127], v[84:87], v[190:193], v[124:127]
	v_mfma_f32_16x16x32_bf16 v[120:123], v[92:95], v[190:193], v[120:123]
	v_mfma_f32_16x16x32_bf16 v[108:111], v[84:87], v[198:201], v[108:111]
	v_mfma_f32_16x16x32_bf16 v[104:107], v[92:95], v[198:201], v[104:107]
	v_mfma_f32_16x16x32_bf16 v[76:79], v[84:87], v[206:209], v[76:79]
	v_mfma_f32_16x16x32_bf16 v[72:75], v[92:95], v[206:209], v[72:75]
	v_mfma_f32_16x16x32_bf16 v[132:135], v[210:213], v[166:169], v[132:135]
	v_mfma_f32_16x16x32_bf16 v[128:131], v[220:223], v[166:169], v[128:131]
	v_mfma_f32_16x16x32_bf16 v[116:119], v[210:213], v[186:189], v[116:119]
	v_mfma_f32_16x16x32_bf16 v[112:115], v[220:223], v[186:189], v[112:115]
	v_mfma_f32_16x16x32_bf16 v[100:103], v[210:213], v[194:197], v[100:103]
	v_mfma_f32_16x16x32_bf16 v[96:99], v[220:223], v[194:197], v[96:99]
	v_mfma_f32_16x16x32_bf16 v[68:71], v[210:213], v[202:205], v[68:71]
	v_mfma_f32_16x16x32_bf16 v[64:67], v[220:223], v[202:205], v[64:67]
	v_mfma_f32_16x16x32_bf16 v[132:135], v[214:217], v[170:173], v[132:135]
	v_mfma_f32_16x16x32_bf16 v[128:131], v[224:227], v[170:173], v[128:131]
	v_mfma_f32_16x16x32_bf16 v[116:119], v[214:217], v[190:193], v[116:119]
	v_mfma_f32_16x16x32_bf16 v[112:115], v[224:227], v[190:193], v[112:115]
	v_mfma_f32_16x16x32_bf16 v[100:103], v[214:217], v[198:201], v[100:103]
	v_mfma_f32_16x16x32_bf16 v[96:99], v[224:227], v[198:201], v[96:99]
	v_mfma_f32_16x16x32_bf16 v[68:71], v[214:217], v[206:209], v[68:71]
	v_mfma_f32_16x16x32_bf16 v[64:67], v[224:227], v[206:209], v[64:67]
	s_setprio 0
	s_barrier
	s_nop 1
	ds_read_b128 v[166:169], v181 offset:49152
	ds_read_b128 v[170:173], v181 offset:50176
	ds_read_b128 v[186:189], v181 offset:51200
	ds_read_b128 v[190:193], v181 offset:52224
	ds_read_b128 v[194:197], v181 offset:53248
	ds_read_b128 v[198:201], v181 offset:54272
	ds_read_b128 v[202:205], v181 offset:55296
	ds_read_b128 v[206:209], v181 offset:56320
	s_add_i32 s37, s75, s7
	s_mov_b32 m0, s37
	s_nop 0
	s_add_u32 s100, s14, s16
	s_addc_u32 s101, s15, s17
	global_load_lds_dwordx4 v146, s[100:101]
	s_add_i32 m0, s37, 0x2000
	s_nop 0
	s_add_u32 s100, s14, s16
	s_addc_u32 s101, s15, s17
	global_load_lds_dwordx4 v150, s[100:101]
	s_mov_b32 m0, s45
	v_lshl_add_u64 v[254:255], v[232:233], 0, s[16:17]
	global_load_lds_dwordx4 v[254:255], off
	v_lshl_add_u64 v[228:229], v[236:237], 0, s[16:17]
	s_mov_b32 m0, s46
	s_nop 0
	global_load_lds_dwordx4 v[228:229], off
	s_add_u32 s14, s14, 0x40080
	s_addc_u32 s15, s15, 0
	s_add_i32 s36, s36, s7
	s_mov_b32 m0, s36
	s_nop 0
	global_load_lds_dwordx4 v146, s[14:15]
	s_add_i32 m0, s36, 0x2000
	s_nop 0
	global_load_lds_dwordx4 v150, s[14:15]
	s_waitcnt vmcnt(6)
	s_waitcnt lgkmcnt(0)
	s_barrier
	s_setprio 1
	v_mfma_f32_16x16x32_bf16 v[60:63], v[80:83], v[166:169], v[60:63]
	v_mfma_f32_16x16x32_bf16 v[56:59], v[88:91], v[166:169], v[56:59]
	v_mfma_f32_16x16x32_bf16 v[44:47], v[80:83], v[186:189], v[44:47]
	v_mfma_f32_16x16x32_bf16 v[40:43], v[88:91], v[186:189], v[40:43]
	v_mfma_f32_16x16x32_bf16 v[28:31], v[80:83], v[194:197], v[28:31]
	v_mfma_f32_16x16x32_bf16 v[24:27], v[88:91], v[194:197], v[24:27]
	v_mfma_f32_16x16x32_bf16 v[12:15], v[80:83], v[202:205], v[12:15]
	v_mfma_f32_16x16x32_bf16 v[8:11], v[88:91], v[202:205], v[8:11]
	v_mfma_f32_16x16x32_bf16 v[60:63], v[84:87], v[170:173], v[60:63]
	v_mfma_f32_16x16x32_bf16 v[56:59], v[92:95], v[170:173], v[56:59]
	v_mfma_f32_16x16x32_bf16 v[44:47], v[84:87], v[190:193], v[44:47]
	v_mfma_f32_16x16x32_bf16 v[40:43], v[92:95], v[190:193], v[40:43]
	v_mfma_f32_16x16x32_bf16 v[28:31], v[84:87], v[198:201], v[28:31]
	v_mfma_f32_16x16x32_bf16 v[24:27], v[92:95], v[198:201], v[24:27]
	v_mfma_f32_16x16x32_bf16 v[12:15], v[84:87], v[206:209], v[12:15]
	v_mfma_f32_16x16x32_bf16 v[8:11], v[92:95], v[206:209], v[8:11]
	v_mfma_f32_16x16x32_bf16 v[52:55], v[210:213], v[166:169], v[52:55]
	v_mfma_f32_16x16x32_bf16 v[48:51], v[220:223], v[166:169], v[48:51]
	v_mfma_f32_16x16x32_bf16 v[36:39], v[210:213], v[186:189], v[36:39]
	v_mfma_f32_16x16x32_bf16 v[32:35], v[220:223], v[186:189], v[32:35]
	v_mfma_f32_16x16x32_bf16 v[20:23], v[210:213], v[194:197], v[20:23]
	v_mfma_f32_16x16x32_bf16 v[16:19], v[220:223], v[194:197], v[16:19]
	v_mfma_f32_16x16x32_bf16 v[4:7], v[210:213], v[202:205], v[4:7]
	v_mfma_f32_16x16x32_bf16 v[0:3], v[220:223], v[202:205], v[0:3]
	v_mfma_f32_16x16x32_bf16 v[52:55], v[214:217], v[170:173], v[52:55]
	v_mfma_f32_16x16x32_bf16 v[48:51], v[224:227], v[170:173], v[48:51]
	v_mfma_f32_16x16x32_bf16 v[36:39], v[214:217], v[190:193], v[36:39]
	v_mfma_f32_16x16x32_bf16 v[32:35], v[224:227], v[190:193], v[32:35]
	v_mfma_f32_16x16x32_bf16 v[20:23], v[214:217], v[198:201], v[20:23]
	v_mfma_f32_16x16x32_bf16 v[16:19], v[224:227], v[198:201], v[16:19]
	v_mfma_f32_16x16x32_bf16 v[4:7], v[214:217], v[206:209], v[4:7]
	v_mfma_f32_16x16x32_bf16 v[0:3], v[224:227], v[206:209], v[0:3]
	s_setprio 0
	s_add_i32 s74, s74, 2
	s_add_u32 s12, s12, 0x100
	s_addc_u32 s13, s13, 0
	s_add_u32 s38, s38, 0x100
	s_addc_u32 s39, s39, 0
	s_cmp_gt_u32 s74, 13
	s_barrier
	s_cbranch_scc0 .LBB0_1583
	s_ashr_i32 s36, s30, 2
	s_cmp_gt_u32 s30, 3
	s_cselect_b64 s[38:39], -1, 0
	s_cmp_eq_u32 s36, 1
	s_mov_b64 s[14:15], -1
	s_cselect_b64 s[12:13], -1, 0
	s_and_b64 vcc, exec, s[38:39]
	s_cbranch_vccz .LBB0_1586
	global_load_dwordx4 v[80:83], v[154:155], off
	s_mov_b64 s[14:15], 0

; #define PG8_STAGE(bufoff, gbase, voff) do { _Pragma("unroll") for (int _i = 0; _i < 2; ++_i) \
;         __builtin_amdgcn_global_load_lds((const unsigned*)((const char*)(gbase) + (voff)[_i]), (LAS unsigned*)(lds + (bufoff) + ldsw + _i * 8192), 16, 0, 0); } while (0)
; #define PG8_WAIT_V(n) asm volatile("s_waitcnt vmcnt(" #n ")" ::: "memory")
; template <class Epi>
; __device__ __forceinline__ void gemm_phase(LAS unsigned char* lds, const Gemm g, const StaticOrder& S, const Epi& E) {
;     ...
;     for (;;) {
;         const bool has_next = S.next(ui + 1, nxt);
;         const char* nA = has_next ? (const char*)g.A + (size_t)nxt.pm * tstepA + (size_t)(nxt.pn >> g.a_shift) * g.a_step : cA; const char* nB = has_next ? (const char*)g.Bt + (size_t)nxt.pn * tstepB : cB;
;         for (int t = 0; t < nt; t += 2) {
;             const bool last = (t == nt - 2);
;             const char* a1 = cA + (size_t)(t + 1) * kstep;
;             const char* a2 = last ? nA : cA + (size_t)(t + 2) * kstep; const char* b2 = last ? nB : cB + (size_t)(t + 2) * kstep;
;             const char* a3 = a2 + kstep; const char* b3 = b2 + kstep;
;             PG8_LDB(B0, 0, 0); PG8_SCHED; PG8_LDA(At, 0, 0); PG8_STAGE(PG8_SA(1, 1), a1 + hstepA, voffA);
;             PG8_WAIT_L(8); PG8_BAR; PG8_WAIT_L(0); PG8_MMA(0, 0, At, B0); PG8_BAR; PG8_SCHED;
;             PG8_LDB(B1, 0, 1); PG8_STAGE(PG8_SB(0, 0), b2, voffB);
;             PG8_BAR; PG8_WAIT_L(0); PG8_MMA(0, 1, At, B1); PG8_BAR;
;             PG8_LDA(At, 0, 1); PG8_STAGE(PG8_SA(0, 0), a2, voffA);
;             PG8_BAR; PG8_WAIT_L(0); PG8_MMA(1, 0, At, B0); PG8_BAR; PG8_SCHED;
;             PG8_STAGE(PG8_SB(0, 1), b2 + hstepB, voffB);
;             PG8_WAIT_V(6); PG8_BAR; PG8_MMA(1, 1, At, B1); PG8_BAR;
;             PG8_LDB(B0, 1, 0); PG8_SCHED; PG8_LDA(At, 1, 0); PG8_STAGE(PG8_SA(0, 1), a2 + hstepA, voffA);
;             PG8_WAIT_L(8); PG8_BAR; PG8_WAIT_L(0); PG8_MMA(0, 0, At, B0); PG8_BAR; PG8_SCHED;
;             PG8_LDB(B1, 1, 1); PG8_STAGE(PG8_SB(1, 0), b3, voffB);
;             PG8_BAR; PG8_WAIT_L(0); PG8_MMA(0, 1, At, B1); PG8_BAR;
;             PG8_LDA(At, 1, 1); PG8_STAGE(PG8_SA(1, 0), a3, voffA);
;             PG8_BAR; PG8_WAIT_L(0); PG8_MMA(1, 0, At, B0); PG8_BAR; PG8_SCHED;
;             PG8_STAGE(PG8_SB(1, 1), b3 + hstepB, voffB);
;             PG8_WAIT_V(6); PG8_BAR; PG8_MMA(1, 1, At, B1); PG8_BAR;
.LBB0_1819:
	s_ashr_i32 s25, s24, 31
	v_cmp_lt_i64_e32 vcc, s[26:27], v[136:137]
	s_lshl_b64 s[26:27], s[24:25], 19
	s_add_u32 s26, s68, s26
	s_addc_u32 s27, s69, s27
	s_and_b64 s[28:29], vcc, exec
	s_cselect_b32 s25, s27, s35
	s_cselect_b32 s47, s26, s34
	s_ashr_i32 s23, s22, 31
	s_lshl_b64 s[28:29], s[22:23], 19
	s_add_u32 s28, s5, s28
	s_addc_u32 s29, s6, s29
	s_and_b64 s[38:39], vcc, exec
	s_cselect_b32 s23, s29, s37
	s_cselect_b32 s48, s28, s36
	s_add_u32 s34, s34, 0x40080
	s_addc_u32 s35, s35, 0
	s_add_u32 s49, s36, 0x100
	s_addc_u32 s63, s37, 0
	s_mov_b32 s70, -2
	ds_read_b128 v[140:143], v149
	ds_read_b128 v[152:155], v149 offset:1024
	ds_read_b128 v[156:159], v149 offset:2048
	ds_read_b128 v[160:163], v149 offset:3072
	s_add_u32 s36, s34, 0xfffc0080
	s_addc_u32 s37, s35, -1
	s_cmp_eq_u32 s70, 12
	s_cselect_b32 s39, s25, s37
	s_cselect_b32 s38, s47, s36
	s_cselect_b32 s37, s23, s63
	s_cselect_b32 s36, s48, s49
	s_add_i32 m0, s8, 0xc000
	ds_read_b128 v[164:167], v150
	ds_read_b128 v[168:171], v150 offset:1024
	ds_read_b128 v[172:175], v150 offset:2048
	ds_read_b128 v[176:179], v150 offset:3072
	ds_read_b128 v[180:183], v150 offset:4096
	ds_read_b128 v[184:187], v150 offset:5120
	ds_read_b128 v[188:191], v150 offset:6144
	ds_read_b128 v[192:195], v150 offset:7168
	global_load_lds_dwordx4 v132, s[34:35]
	s_add_i32 m0, s8, 0xe000
	s_nop 0
	global_load_lds_dwordx4 v134, s[34:35]
	ds_read_b128 v[196:199], v151
	ds_read_b128 v[200:203], v151 offset:1024
	ds_read_b128 v[204:207], v151 offset:2048
	ds_read_b128 v[208:211], v151 offset:3072
	s_waitcnt lgkmcnt(0)
	s_barrier
	s_setprio 1
	v_mfma_f32_16x16x32_bf16 v[124:127], v[140:143], v[164:167], 0
	v_mfma_f32_16x16x32_bf16 v[120:123], v[156:159], v[164:167], 0
	v_mfma_f32_16x16x32_bf16 v[112:115], v[140:143], v[172:175], 0
	v_mfma_f32_16x16x32_bf16 v[104:107], v[156:159], v[172:175], 0
	v_mfma_f32_16x16x32_bf16 v[92:95], v[140:143], v[180:183], 0
	v_mfma_f32_16x16x32_bf16 v[88:91], v[156:159], v[180:183], 0
	v_mfma_f32_16x16x32_bf16 v[80:83], v[140:143], v[188:191], 0
	v_mfma_f32_16x16x32_bf16 v[72:75], v[156:159], v[188:191], 0
	v_mfma_f32_16x16x32_bf16 v[124:127], v[152:155], v[168:171], v[124:127]
	v_mfma_f32_16x16x32_bf16 v[120:123], v[160:163], v[168:171], v[120:123]
	v_mfma_f32_16x16x32_bf16 v[112:115], v[152:155], v[176:179], v[112:115]
	v_mfma_f32_16x16x32_bf16 v[104:107], v[160:163], v[176:179], v[104:107]
	v_mfma_f32_16x16x32_bf16 v[92:95], v[152:155], v[184:187], v[92:95]
	v_mfma_f32_16x16x32_bf16 v[88:91], v[160:163], v[184:187], v[88:91]
	v_mfma_f32_16x16x32_bf16 v[80:83], v[152:155], v[192:195], v[80:83]
	v_mfma_f32_16x16x32_bf16 v[72:75], v[160:163], v[192:195], v[72:75]
	v_mfma_f32_16x16x32_bf16 v[116:119], v[196:199], v[164:167], 0
	v_mfma_f32_16x16x32_bf16 v[108:111], v[204:207], v[164:167], 0
	v_mfma_f32_16x16x32_bf16 v[100:103], v[196:199], v[172:175], 0
	v_mfma_f32_16x16x32_bf16 v[96:99], v[204:207], v[172:175], 0
	v_mfma_f32_16x16x32_bf16 v[84:87], v[196:199], v[180:183], 0
	v_mfma_f32_16x16x32_bf16 v[76:79], v[204:207], v[180:183], 0
	v_mfma_f32_16x16x32_bf16 v[68:71], v[196:199], v[188:191], 0
	v_mfma_f32_16x16x32_bf16 v[64:67], v[204:207], v[188:191], 0
	v_mfma_f32_16x16x32_bf16 v[116:119], v[200:203], v[168:171], v[116:119]
	v_mfma_f32_16x16x32_bf16 v[108:111], v[208:211], v[168:171], v[108:111]
	v_mfma_f32_16x16x32_bf16 v[100:103], v[200:203], v[176:179], v[100:103]
	v_mfma_f32_16x16x32_bf16 v[96:99], v[208:211], v[176:179], v[96:99]
	v_mfma_f32_16x16x32_bf16 v[84:87], v[200:203], v[184:187], v[84:87]
	v_mfma_f32_16x16x32_bf16 v[76:79], v[208:211], v[184:187], v[76:79]
	v_mfma_f32_16x16x32_bf16 v[68:71], v[200:203], v[192:195], v[68:71]
	v_mfma_f32_16x16x32_bf16 v[64:67], v[208:211], v[192:195], v[64:67]
	s_setprio 0
	s_barrier
	s_nop 1
	ds_read_b128 v[164:167], v150 offset:16384
	ds_read_b128 v[168:171], v150 offset:17408
	ds_read_b128 v[172:175], v150 offset:18432
	ds_read_b128 v[176:179], v150 offset:19456
	ds_read_b128 v[180:183], v150 offset:20480
	ds_read_b128 v[184:187], v150 offset:21504
	ds_read_b128 v[188:191], v150 offset:22528
	ds_read_b128 v[192:195], v150 offset:23552
	s_add_i32 s71, s44, s7
	v_lshl_add_u64 v[144:145], s[36:37], 0, v[128:129]
	s_mov_b32 m0, s71
	s_nop 0
	global_load_lds_dwordx4 v128, s[36:37]
	v_lshl_add_u64 v[212:213], s[36:37], 0, v[130:131]
	s_add_i32 m0, s71, 0x2000
	s_nop 0
	global_load_lds_dwordx4 v130, s[36:37]
	s_mov_b32 m0, s8
	v_lshl_add_u64 v[214:215], s[38:39], 0, v[128:129]
	global_load_lds_dwordx4 v128, s[38:39]
	v_lshl_add_u64 v[216:217], s[38:39], 0, v[130:131]
	s_mov_b32 m0, s9
	s_nop 0
	global_load_lds_dwordx4 v130, s[38:39]
	s_add_u32 s72, s36, 0x40000
	s_addc_u32 s73, s37, 0
	s_add_i32 s71, s45, s7
	s_mov_b32 m0, s71
	s_nop 0
	global_load_lds_dwordx4 v128, s[72:73]
	s_add_i32 m0, s71, 0x2000
	s_nop 0
	global_load_lds_dwordx4 v130, s[72:73]
	s_waitcnt vmcnt(6)
	s_waitcnt lgkmcnt(0)
	s_barrier
; #define PG8_STAGE(bufoff, gbase, voff) do { _Pragma("unroll") for (int _i = 0; _i < 2; ++_i) \
;         __builtin_amdgcn_global_load_lds((const unsigned*)((const char*)(gbase) + (voff)[_i]), (LAS unsigned*)(lds + (bufoff) + ldsw + _i * 8192), 16, 0, 0); } while (0)
; #define PG8_LDA(dst, b, h) do { _Pragma("unroll") for (int m = 0; m < 4; ++m) _Pragma("unroll") for (int k = 0; k < 2; ++k) dst[m][k] = *(const LAS bf16x8*)(lds + PG8_SA(b, h) + aoff + m * 2048 + k * 1024); } while (0)
; #define PG8_WAIT_V(n) asm volatile("s_waitcnt vmcnt(" #n ")" ::: "memory")
; #define PG8_WAIT_L(n) asm volatile("s_waitcnt lgkmcnt(" #n ")" ::: "memory")
; template <class Epi>
; __device__ __forceinline__ void gemm_phase(LAS unsigned char* lds, const Gemm g, const StaticOrder& S, const Epi& E) {
;     ...
;         for (int t = 0; t < nt; t += 2) {
;             const bool last = (t == nt - 2);
;             const char* a1 = cA + (size_t)(t + 1) * kstep;
;             const char* a2 = last ? nA : cA + (size_t)(t + 2) * kstep; const char* b2 = last ? nB : cB + (size_t)(t + 2) * kstep;
;             const char* a3 = a2 + kstep; const char* b3 = b2 + kstep;
;             PG8_LDB(B0, 0, 0); PG8_SCHED; PG8_LDA(At, 0, 0); PG8_STAGE(PG8_SA(1, 1), a1 + hstepA, voffA);
;             PG8_WAIT_L(8); PG8_BAR; PG8_WAIT_L(0); PG8_MMA(0, 0, At, B0); PG8_BAR; PG8_SCHED;
;             PG8_LDB(B1, 0, 1); PG8_STAGE(PG8_SB(0, 0), b2, voffB);
;             PG8_BAR; PG8_WAIT_L(0); PG8_MMA(0, 1, At, B1); PG8_BAR;
;             PG8_LDA(At, 0, 1); PG8_STAGE(PG8_SA(0, 0), a2, voffA);
;             PG8_BAR; PG8_WAIT_L(0); PG8_MMA(1, 0, At, B0); PG8_BAR; PG8_SCHED;
;             PG8_STAGE(PG8_SB(0, 1), b2 + hstepB, voffB);
;             PG8_WAIT_V(6); PG8_BAR; PG8_MMA(1, 1, At, B1); PG8_BAR;
;             PG8_LDB(B0, 1, 0); PG8_SCHED; PG8_LDA(At, 1, 0); PG8_STAGE(PG8_SA(0, 1), a2 + hstepA, voffA);
;             PG8_WAIT_L(8); PG8_BAR; PG8_WAIT_L(0); PG8_MMA(0, 0, At, B0); PG8_BAR; PG8_SCHED;
;             PG8_LDB(B1, 1, 1); PG8_STAGE(PG8_SB(1, 0), b3, voffB);
;             PG8_BAR; PG8_WAIT_L(0); PG8_MMA(0, 1, At, B1); PG8_BAR;
;             PG8_LDA(At, 1, 1); PG8_STAGE(PG8_SA(1, 0), a3, voffA);
;             PG8_BAR; PG8_WAIT_L(0); PG8_MMA(1, 0, At, B0); PG8_BAR; PG8_SCHED;
;             PG8_STAGE(PG8_SB(1, 1), b3 + hstepB, voffB);
;             PG8_WAIT_V(6); PG8_BAR; PG8_MMA(1, 1, At, B1); PG8_BAR;
	s_setprio 1
	v_mfma_f32_16x16x32_bf16 v[60:63], v[140:143], v[164:167], 0
	v_mfma_f32_16x16x32_bf16 v[56:59], v[156:159], v[164:167], 0
	v_mfma_f32_16x16x32_bf16 v[48:51], v[140:143], v[172:175], 0
	v_mfma_f32_16x16x32_bf16 v[40:43], v[156:159], v[172:175], 0
	v_mfma_f32_16x16x32_bf16 v[28:31], v[140:143], v[180:183], 0
	v_mfma_f32_16x16x32_bf16 v[24:27], v[156:159], v[180:183], 0
	v_mfma_f32_16x16x32_bf16 v[16:19], v[140:143], v[188:191], 0
	v_mfma_f32_16x16x32_bf16 v[8:11], v[156:159], v[188:191], 0
	v_mfma_f32_16x16x32_bf16 v[60:63], v[152:155], v[168:171], v[60:63]
	v_mfma_f32_16x16x32_bf16 v[56:59], v[160:163], v[168:171], v[56:59]
	v_mfma_f32_16x16x32_bf16 v[48:51], v[152:155], v[176:179], v[48:51]
	v_mfma_f32_16x16x32_bf16 v[40:43], v[160:163], v[176:179], v[40:43]
	v_mfma_f32_16x16x32_bf16 v[28:31], v[152:155], v[184:187], v[28:31]
	v_mfma_f32_16x16x32_bf16 v[24:27], v[160:163], v[184:187], v[24:27]
	v_mfma_f32_16x16x32_bf16 v[16:19], v[152:155], v[192:195], v[16:19]
	v_mfma_f32_16x16x32_bf16 v[8:11], v[160:163], v[192:195], v[8:11]
	v_mfma_f32_16x16x32_bf16 v[52:55], v[196:199], v[164:167], 0
	v_mfma_f32_16x16x32_bf16 v[44:47], v[204:207], v[164:167], 0
	v_mfma_f32_16x16x32_bf16 v[36:39], v[196:199], v[172:175], 0
	v_mfma_f32_16x16x32_bf16 v[32:35], v[204:207], v[172:175], 0
	v_mfma_f32_16x16x32_bf16 v[20:23], v[196:199], v[180:183], 0
	v_mfma_f32_16x16x32_bf16 v[12:15], v[204:207], v[180:183], 0
	v_mfma_f32_16x16x32_bf16 v[4:7], v[196:199], v[188:191], 0
	v_mfma_f32_16x16x32_bf16 v[0:3], v[204:207], v[188:191], 0
	v_mfma_f32_16x16x32_bf16 v[52:55], v[200:203], v[168:171], v[52:55]
	v_mfma_f32_16x16x32_bf16 v[44:47], v[208:211], v[168:171], v[44:47]
	v_mfma_f32_16x16x32_bf16 v[36:39], v[200:203], v[176:179], v[36:39]
	v_mfma_f32_16x16x32_bf16 v[32:35], v[208:211], v[176:179], v[32:35]
	v_mfma_f32_16x16x32_bf16 v[20:23], v[200:203], v[184:187], v[20:23]
	v_mfma_f32_16x16x32_bf16 v[12:15], v[208:211], v[184:187], v[12:15]
	v_mfma_f32_16x16x32_bf16 v[4:7], v[200:203], v[192:195], v[4:7]
	v_mfma_f32_16x16x32_bf16 v[0:3], v[208:211], v[192:195], v[0:3]
	s_setprio 0
	s_add_i32 s71, 0, 0x18000
	v_add_u32_e32 v160, s71, v147
	s_barrier
	ds_read_b128 v[140:143], v160
	ds_read_b128 v[152:155], v160 offset:1024
	ds_read_b128 v[156:159], v160 offset:2048
	ds_read_b128 v[160:163], v160 offset:3072
	s_add_u32 s38, s38, 0x40000
	s_addc_u32 s39, s39, 0
	s_mov_b32 m0, s31
	ds_read_b128 v[164:167], v150 offset:32768
	ds_read_b128 v[168:171], v150 offset:33792
	ds_read_b128 v[172:175], v150 offset:34816
	ds_read_b128 v[176:179], v150 offset:35840
	ds_read_b128 v[180:183], v150 offset:36864
	ds_read_b128 v[184:187], v150 offset:37888
	ds_read_b128 v[188:191], v150 offset:38912
	ds_read_b128 v[192:195], v150 offset:39936
	global_load_lds_dwordx4 v128, s[38:39]
	s_mov_b32 m0, s40
	s_nop 0
	global_load_lds_dwordx4 v130, s[38:39]
	s_add_i32 s38, 0, 0x1c000
	v_add_u32_e32 v208, s38, v147
	ds_read_b128 v[196:199], v208
	ds_read_b128 v[200:203], v208 offset:1024
	ds_read_b128 v[204:207], v208 offset:2048
	ds_read_b128 v[208:211], v208 offset:3072
	s_waitcnt lgkmcnt(0)
	s_barrier
	s_setprio 1
	v_mfma_f32_16x16x32_bf16 v[124:127], v[140:143], v[164:167], v[124:127]
	v_mfma_f32_16x16x32_bf16 v[120:123], v[156:159], v[164:167], v[120:123]
	v_mfma_f32_16x16x32_bf16 v[112:115], v[140:143], v[172:175], v[112:115]
	v_mfma_f32_16x16x32_bf16 v[104:107], v[156:159], v[172:175], v[104:107]
	v_mfma_f32_16x16x32_bf16 v[92:95], v[140:143], v[180:183], v[92:95]
	v_mfma_f32_16x16x32_bf16 v[88:91], v[156:159], v[180:183], v[88:91]
	v_mfma_f32_16x16x32_bf16 v[80:83], v[140:143], v[188:191], v[80:83]
	v_mfma_f32_16x16x32_bf16 v[72:75], v[156:159], v[188:191], v[72:75]
	v_mfma_f32_16x16x32_bf16 v[124:127], v[152:155], v[168:171], v[124:127]
	v_mfma_f32_16x16x32_bf16 v[120:123], v[160:163], v[168:171], v[120:123]
	v_mfma_f32_16x16x32_bf16 v[112:115], v[152:155], v[176:179], v[112:115]
	v_mfma_f32_16x16x32_bf16 v[104:107], v[160:163], v[176:179], v[104:107]
	v_mfma_f32_16x16x32_bf16 v[92:95], v[152:155], v[184:187], v[92:95]
	v_mfma_f32_16x16x32_bf16 v[88:91], v[160:163], v[184:187], v[88:91]
	v_mfma_f32_16x16x32_bf16 v[80:83], v[152:155], v[192:195], v[80:83]
	v_mfma_f32_16x16x32_bf16 v[72:75], v[160:163], v[192:195], v[72:75]
	v_mfma_f32_16x16x32_bf16 v[116:119], v[196:199], v[164:167], v[116:119]
	v_mfma_f32_16x16x32_bf16 v[108:111], v[204:207], v[164:167], v[108:111]
	v_mfma_f32_16x16x32_bf16 v[100:103], v[196:199], v[172:175], v[100:103]
	v_mfma_f32_16x16x32_bf16 v[96:99], v[204:207], v[172:175], v[96:99]
	v_mfma_f32_16x16x32_bf16 v[84:87], v[196:199], v[180:183], v[84:87]
	v_mfma_f32_16x16x32_bf16 v[76:79], v[204:207], v[180:183], v[76:79]
	v_mfma_f32_16x16x32_bf16 v[68:71], v[196:199], v[188:191], v[68:71]
	v_mfma_f32_16x16x32_bf16 v[64:67], v[204:207], v[188:191], v[64:67]
	v_mfma_f32_16x16x32_bf16 v[116:119], v[200:203], v[168:171], v[116:119]
	v_mfma_f32_16x16x32_bf16 v[108:111], v[208:211], v[168:171], v[108:111]
	v_mfma_f32_16x16x32_bf16 v[100:103], v[200:203], v[176:179], v[100:103]
	v_mfma_f32_16x16x32_bf16 v[96:99], v[208:211], v[176:179], v[96:99]
	v_mfma_f32_16x16x32_bf16 v[84:87], v[200:203], v[184:187], v[84:87]
	v_mfma_f32_16x16x32_bf16 v[76:79], v[208:211], v[184:187], v[76:79]
	v_mfma_f32_16x16x32_bf16 v[68:71], v[200:203], v[192:195], v[68:71]
	v_mfma_f32_16x16x32_bf16 v[64:67], v[208:211], v[192:195], v[64:67]
	s_setprio 0
	s_barrier
; #define PG8_STAGE(bufoff, gbase, voff) do { _Pragma("unroll") for (int _i = 0; _i < 2; ++_i) \
;         __builtin_amdgcn_global_load_lds((const unsigned*)((const char*)(gbase) + (voff)[_i]), (LAS unsigned*)(lds + (bufoff) + ldsw + _i * 8192), 16, 0, 0); } while (0)
; #define PG8_LDA(dst, b, h) do { _Pragma("unroll") for (int m = 0; m < 4; ++m) _Pragma("unroll") for (int k = 0; k < 2; ++k) dst[m][k] = *(const LAS bf16x8*)(lds + PG8_SA(b, h) + aoff + m * 2048 + k * 1024); } while (0)
; #define PG8_WAIT_V(n) asm volatile("s_waitcnt vmcnt(" #n ")" ::: "memory")
; #define PG8_WAIT_L(n) asm volatile("s_waitcnt lgkmcnt(" #n ")" ::: "memory")
; template <class Epi>
; __device__ __forceinline__ void gemm_phase(LAS unsigned char* lds, const Gemm g, const StaticOrder& S, const Epi& E) {
;     ...
;         for (int t = 0; t < nt; t += 2) {
;             const bool last = (t == nt - 2);
;             const char* a1 = cA + (size_t)(t + 1) * kstep;
;             const char* a2 = last ? nA : cA + (size_t)(t + 2) * kstep; const char* b2 = last ? nB : cB + (size_t)(t + 2) * kstep;
;             const char* a3 = a2 + kstep; const char* b3 = b2 + kstep;
;             PG8_LDB(B0, 0, 0); PG8_SCHED; PG8_LDA(At, 0, 0); PG8_STAGE(PG8_SA(1, 1), a1 + hstepA, voffA);
;             PG8_WAIT_L(8); PG8_BAR; PG8_WAIT_L(0); PG8_MMA(0, 0, At, B0); PG8_BAR; PG8_SCHED;
;             PG8_LDB(B1, 0, 1); PG8_STAGE(PG8_SB(0, 0), b2, voffB);
;             PG8_BAR; PG8_WAIT_L(0); PG8_MMA(0, 1, At, B1); PG8_BAR;
;             PG8_LDA(At, 0, 1); PG8_STAGE(PG8_SA(0, 0), a2, voffA);
;             PG8_BAR; PG8_WAIT_L(0); PG8_MMA(1, 0, At, B0); PG8_BAR; PG8_SCHED;
;             PG8_STAGE(PG8_SB(0, 1), b2 + hstepB, voffB);
;             PG8_WAIT_V(6); PG8_BAR; PG8_MMA(1, 1, At, B1); PG8_BAR;
;             PG8_LDB(B0, 1, 0); PG8_SCHED; PG8_LDA(At, 1, 0); PG8_STAGE(PG8_SA(0, 1), a2 + hstepA, voffA);
;             PG8_WAIT_L(8); PG8_BAR; PG8_WAIT_L(0); PG8_MMA(0, 0, At, B0); PG8_BAR; PG8_SCHED;
;             PG8_LDB(B1, 1, 1); PG8_STAGE(PG8_SB(1, 0), b3, voffB);
;             PG8_BAR; PG8_WAIT_L(0); PG8_MMA(0, 1, At, B1); PG8_BAR;
;             PG8_LDA(At, 1, 1); PG8_STAGE(PG8_SA(1, 0), a3, voffA);
;             PG8_BAR; PG8_WAIT_L(0); PG8_MMA(1, 0, At, B0); PG8_BAR; PG8_SCHED;
;             PG8_STAGE(PG8_SB(1, 1), b3 + hstepB, voffB);
;             PG8_WAIT_V(6); PG8_BAR; PG8_MMA(1, 1, At, B1); PG8_BAR;
	s_nop 1
	ds_read_b128 v[164:167], v150 offset:49152
	ds_read_b128 v[168:171], v150 offset:50176
	ds_read_b128 v[172:175], v150 offset:51200
	ds_read_b128 v[176:179], v150 offset:52224
	ds_read_b128 v[180:183], v150 offset:53248
	ds_read_b128 v[184:187], v150 offset:54272
	ds_read_b128 v[188:191], v150 offset:55296
	ds_read_b128 v[192:195], v150 offset:56320
	s_add_i32 s39, s71, s7
	s_mov_b32 m0, s39
	s_nop 0
	s_add_u32 s100, s36, s12
	s_addc_u32 s101, s37, s13
	global_load_lds_dwordx4 v128, s[100:101]
	s_add_i32 m0, s39, 0x2000
	s_nop 0
	s_add_u32 s100, s36, s12
	s_addc_u32 s101, s37, s13
	global_load_lds_dwordx4 v130, s[100:101]
	s_mov_b32 m0, s42
	v_lshl_add_u64 v[254:255], v[214:215], 0, s[12:13]
	global_load_lds_dwordx4 v[254:255], off
	v_lshl_add_u64 v[144:145], v[216:217], 0, s[12:13]
	s_mov_b32 m0, s43
	s_nop 0
	global_load_lds_dwordx4 v[144:145], off
	s_add_u32 s36, s36, 0x40080
	s_addc_u32 s37, s37, 0
	s_add_i32 s38, s38, s7
	s_mov_b32 m0, s38
	s_nop 0
	global_load_lds_dwordx4 v128, s[36:37]
	s_add_i32 m0, s38, 0x2000
	s_nop 0
	global_load_lds_dwordx4 v130, s[36:37]
	s_waitcnt vmcnt(6)
	s_waitcnt lgkmcnt(0)
	s_barrier
	s_setprio 1
	v_mfma_f32_16x16x32_bf16 v[60:63], v[140:143], v[164:167], v[60:63]
	v_mfma_f32_16x16x32_bf16 v[56:59], v[156:159], v[164:167], v[56:59]
	v_mfma_f32_16x16x32_bf16 v[48:51], v[140:143], v[172:175], v[48:51]
	v_mfma_f32_16x16x32_bf16 v[40:43], v[156:159], v[172:175], v[40:43]
	v_mfma_f32_16x16x32_bf16 v[28:31], v[140:143], v[180:183], v[28:31]
	v_mfma_f32_16x16x32_bf16 v[24:27], v[156:159], v[180:183], v[24:27]
	v_mfma_f32_16x16x32_bf16 v[16:19], v[140:143], v[188:191], v[16:19]
	v_mfma_f32_16x16x32_bf16 v[8:11], v[156:159], v[188:191], v[8:11]
	v_mfma_f32_16x16x32_bf16 v[60:63], v[152:155], v[168:171], v[60:63]
	v_mfma_f32_16x16x32_bf16 v[56:59], v[160:163], v[168:171], v[56:59]
	v_mfma_f32_16x16x32_bf16 v[48:51], v[152:155], v[176:179], v[48:51]
	v_mfma_f32_16x16x32_bf16 v[40:43], v[160:163], v[176:179], v[40:43]
	v_mfma_f32_16x16x32_bf16 v[28:31], v[152:155], v[184:187], v[28:31]
	v_mfma_f32_16x16x32_bf16 v[24:27], v[160:163], v[184:187], v[24:27]
	v_mfma_f32_16x16x32_bf16 v[16:19], v[152:155], v[192:195], v[16:19]
	v_mfma_f32_16x16x32_bf16 v[8:11], v[160:163], v[192:195], v[8:11]
	v_mfma_f32_16x16x32_bf16 v[52:55], v[196:199], v[164:167], v[52:55]
	v_mfma_f32_16x16x32_bf16 v[44:47], v[204:207], v[164:167], v[44:47]
	v_mfma_f32_16x16x32_bf16 v[36:39], v[196:199], v[172:175], v[36:39]
	v_mfma_f32_16x16x32_bf16 v[32:35], v[204:207], v[172:175], v[32:35]
	v_mfma_f32_16x16x32_bf16 v[20:23], v[196:199], v[180:183], v[20:23]
	v_mfma_f32_16x16x32_bf16 v[12:15], v[204:207], v[180:183], v[12:15]
	v_mfma_f32_16x16x32_bf16 v[4:7], v[196:199], v[188:191], v[4:7]
	v_mfma_f32_16x16x32_bf16 v[0:3], v[204:207], v[188:191], v[0:3]
	v_mfma_f32_16x16x32_bf16 v[52:55], v[200:203], v[168:171], v[52:55]
	v_mfma_f32_16x16x32_bf16 v[44:47], v[208:211], v[168:171], v[44:47]
	v_mfma_f32_16x16x32_bf16 v[36:39], v[200:203], v[176:179], v[36:39]
	v_mfma_f32_16x16x32_bf16 v[32:35], v[208:211], v[176:179], v[32:35]
	v_mfma_f32_16x16x32_bf16 v[20:23], v[200:203], v[184:187], v[20:23]
	v_mfma_f32_16x16x32_bf16 v[12:15], v[208:211], v[184:187], v[12:15]
	v_mfma_f32_16x16x32_bf16 v[4:7], v[200:203], v[192:195], v[4:7]
	v_mfma_f32_16x16x32_bf16 v[0:3], v[208:211], v[192:195], v[0:3]
	s_setprio 0
	s_add_i32 s70, s70, 2
	s_add_u32 s34, s34, 0x100
	s_addc_u32 s35, s35, 0
	s_add_u32 s49, s49, 0x100
	s_addc_u32 s63, s63, 0
	s_cmp_gt_u32 s70, 13
	s_barrier
.LBB0_1820:
	ds_read_b128 v[140:143], v149
	ds_read_b128 v[152:155], v149 offset:1024
	ds_read_b128 v[156:159], v149 offset:2048
	ds_read_b128 v[160:163], v149 offset:3072
	s_add_u32 s36, s34, 0xfffc0080
	s_addc_u32 s37, s35, -1
	s_cmp_eq_u32 s70, 12
	s_cselect_b32 s39, s25, s37
	s_cselect_b32 s38, s47, s36
	s_cselect_b32 s37, s23, s63
	s_cselect_b32 s36, s48, s49
	s_add_i32 m0, s8, 0xc000
	ds_read_b128 v[164:167], v150
	ds_read_b128 v[168:171], v150 offset:1024
	ds_read_b128 v[172:175], v150 offset:2048
	ds_read_b128 v[176:179], v150 offset:3072
	ds_read_b128 v[180:183], v150 offset:4096
	ds_read_b128 v[184:187], v150 offset:5120
	ds_read_b128 v[188:191], v150 offset:6144
	ds_read_b128 v[192:195], v150 offset:7168
	global_load_lds_dwordx4 v132, s[34:35]
	s_add_i32 m0, s8, 0xe000
	s_nop 0
	global_load_lds_dwordx4 v134, s[34:35]
	ds_read_b128 v[196:199], v151
	ds_read_b128 v[200:203], v151 offset:1024
	ds_read_b128 v[204:207], v151 offset:2048
	ds_read_b128 v[208:211], v151 offset:3072
	s_waitcnt lgkmcnt(0)
	s_barrier
; #define PG8_STAGE(bufoff, gbase, voff) do { _Pragma("unroll") for (int _i = 0; _i < 2; ++_i) \
;         __builtin_amdgcn_global_load_lds((const unsigned*)((const char*)(gbase) + (voff)[_i]), (LAS unsigned*)(lds + (bufoff) + ldsw + _i * 8192), 16, 0, 0); } while (0)
; #define PG8_LDA(dst, b, h) do { _Pragma("unroll") for (int m = 0; m < 4; ++m) _Pragma("unroll") for (int k = 0; k < 2; ++k) dst[m][k] = *(const LAS bf16x8*)(lds + PG8_SA(b, h) + aoff + m * 2048 + k * 1024); } while (0)
; #define PG8_WAIT_V(n) asm volatile("s_waitcnt vmcnt(" #n ")" ::: "memory")
; #define PG8_WAIT_L(n) asm volatile("s_waitcnt lgkmcnt(" #n ")" ::: "memory")
; template <class Epi>
; __device__ __forceinline__ void gemm_phase(LAS unsigned char* lds, const Gemm g, const StaticOrder& S, const Epi& E) {
;     ...
;         for (int t = 0; t < nt; t += 2) {
;             const bool last = (t == nt - 2);
;             const char* a1 = cA + (size_t)(t + 1) * kstep;
;             const char* a2 = last ? nA : cA + (size_t)(t + 2) * kstep; const char* b2 = last ? nB : cB + (size_t)(t + 2) * kstep;
;             const char* a3 = a2 + kstep; const char* b3 = b2 + kstep;
;             PG8_LDB(B0, 0, 0); PG8_SCHED; PG8_LDA(At, 0, 0); PG8_STAGE(PG8_SA(1, 1), a1 + hstepA, voffA);
;             PG8_WAIT_L(8); PG8_BAR; PG8_WAIT_L(0); PG8_MMA(0, 0, At, B0); PG8_BAR; PG8_SCHED;
;             PG8_LDB(B1, 0, 1); PG8_STAGE(PG8_SB(0, 0), b2, voffB);
;             PG8_BAR; PG8_WAIT_L(0); PG8_MMA(0, 1, At, B1); PG8_BAR;
;             PG8_LDA(At, 0, 1); PG8_STAGE(PG8_SA(0, 0), a2, voffA);
;             PG8_BAR; PG8_WAIT_L(0); PG8_MMA(1, 0, At, B0); PG8_BAR; PG8_SCHED;
;             PG8_STAGE(PG8_SB(0, 1), b2 + hstepB, voffB);
;             PG8_WAIT_V(6); PG8_BAR; PG8_MMA(1, 1, At, B1); PG8_BAR;
;             PG8_LDB(B0, 1, 0); PG8_SCHED; PG8_LDA(At, 1, 0); PG8_STAGE(PG8_SA(0, 1), a2 + hstepA, voffA);
;             PG8_WAIT_L(8); PG8_BAR; PG8_WAIT_L(0); PG8_MMA(0, 0, At, B0); PG8_BAR; PG8_SCHED;
;             PG8_LDB(B1, 1, 1); PG8_STAGE(PG8_SB(1, 0), b3, voffB);
;             PG8_BAR; PG8_WAIT_L(0); PG8_MMA(0, 1, At, B1); PG8_BAR;
;             PG8_LDA(At, 1, 1); PG8_STAGE(PG8_SA(1, 0), a3, voffA);
;             PG8_BAR; PG8_WAIT_L(0); PG8_MMA(1, 0, At, B0); PG8_BAR; PG8_SCHED;
;             PG8_STAGE(PG8_SB(1, 1), b3 + hstepB, voffB);
;             PG8_WAIT_V(6); PG8_BAR; PG8_MMA(1, 1, At, B1); PG8_BAR;
	s_setprio 1
	v_mfma_f32_16x16x32_bf16 v[124:127], v[140:143], v[164:167], v[124:127]
	v_mfma_f32_16x16x32_bf16 v[120:123], v[156:159], v[164:167], v[120:123]
	v_mfma_f32_16x16x32_bf16 v[112:115], v[140:143], v[172:175], v[112:115]
	v_mfma_f32_16x16x32_bf16 v[104:107], v[156:159], v[172:175], v[104:107]
	v_mfma_f32_16x16x32_bf16 v[92:95], v[140:143], v[180:183], v[92:95]
	v_mfma_f32_16x16x32_bf16 v[88:91], v[156:159], v[180:183], v[88:91]
	v_mfma_f32_16x16x32_bf16 v[80:83], v[140:143], v[188:191], v[80:83]
	v_mfma_f32_16x16x32_bf16 v[72:75], v[156:159], v[188:191], v[72:75]
	v_mfma_f32_16x16x32_bf16 v[124:127], v[152:155], v[168:171], v[124:127]
	v_mfma_f32_16x16x32_bf16 v[120:123], v[160:163], v[168:171], v[120:123]
	v_mfma_f32_16x16x32_bf16 v[112:115], v[152:155], v[176:179], v[112:115]
	v_mfma_f32_16x16x32_bf16 v[104:107], v[160:163], v[176:179], v[104:107]
	v_mfma_f32_16x16x32_bf16 v[92:95], v[152:155], v[184:187], v[92:95]
	v_mfma_f32_16x16x32_bf16 v[88:91], v[160:163], v[184:187], v[88:91]
	v_mfma_f32_16x16x32_bf16 v[80:83], v[152:155], v[192:195], v[80:83]
	v_mfma_f32_16x16x32_bf16 v[72:75], v[160:163], v[192:195], v[72:75]
	v_mfma_f32_16x16x32_bf16 v[116:119], v[196:199], v[164:167], v[116:119]
	v_mfma_f32_16x16x32_bf16 v[108:111], v[204:207], v[164:167], v[108:111]
	v_mfma_f32_16x16x32_bf16 v[100:103], v[196:199], v[172:175], v[100:103]
	v_mfma_f32_16x16x32_bf16 v[96:99], v[204:207], v[172:175], v[96:99]
	v_mfma_f32_16x16x32_bf16 v[84:87], v[196:199], v[180:183], v[84:87]
	v_mfma_f32_16x16x32_bf16 v[76:79], v[204:207], v[180:183], v[76:79]
	v_mfma_f32_16x16x32_bf16 v[68:71], v[196:199], v[188:191], v[68:71]
	v_mfma_f32_16x16x32_bf16 v[64:67], v[204:207], v[188:191], v[64:67]
	v_mfma_f32_16x16x32_bf16 v[116:119], v[200:203], v[168:171], v[116:119]
	v_mfma_f32_16x16x32_bf16 v[108:111], v[208:211], v[168:171], v[108:111]
	v_mfma_f32_16x16x32_bf16 v[100:103], v[200:203], v[176:179], v[100:103]
	v_mfma_f32_16x16x32_bf16 v[96:99], v[208:211], v[176:179], v[96:99]
	v_mfma_f32_16x16x32_bf16 v[84:87], v[200:203], v[184:187], v[84:87]
	v_mfma_f32_16x16x32_bf16 v[76:79], v[208:211], v[184:187], v[76:79]
	v_mfma_f32_16x16x32_bf16 v[68:71], v[200:203], v[192:195], v[68:71]
	v_mfma_f32_16x16x32_bf16 v[64:67], v[208:211], v[192:195], v[64:67]
	s_setprio 0
	s_barrier
	s_nop 1
	ds_read_b128 v[164:167], v150 offset:16384
	ds_read_b128 v[168:171], v150 offset:17408
	ds_read_b128 v[172:175], v150 offset:18432
	ds_read_b128 v[176:179], v150 offset:19456
	ds_read_b128 v[180:183], v150 offset:20480
	ds_read_b128 v[184:187], v150 offset:21504
	ds_read_b128 v[188:191], v150 offset:22528
	ds_read_b128 v[192:195], v150 offset:23552
	s_add_i32 s71, s44, s7
	v_lshl_add_u64 v[144:145], s[36:37], 0, v[128:129]
	s_mov_b32 m0, s71
	s_nop 0
	global_load_lds_dwordx4 v128, s[36:37]
	v_lshl_add_u64 v[212:213], s[36:37], 0, v[130:131]
	s_add_i32 m0, s71, 0x2000
	s_nop 0
	global_load_lds_dwordx4 v130, s[36:37]
	s_mov_b32 m0, s8
	v_lshl_add_u64 v[214:215], s[38:39], 0, v[128:129]
	global_load_lds_dwordx4 v128, s[38:39]
	v_lshl_add_u64 v[216:217], s[38:39], 0, v[130:131]
	s_mov_b32 m0, s9
	s_nop 0
	global_load_lds_dwordx4 v130, s[38:39]
	s_add_u32 s72, s36, 0x40000
	s_addc_u32 s73, s37, 0
	s_add_i32 s71, s45, s7
	s_mov_b32 m0, s71
	s_nop 0
	global_load_lds_dwordx4 v128, s[72:73]
	s_add_i32 m0, s71, 0x2000
	s_nop 0
	global_load_lds_dwordx4 v130, s[72:73]
	s_waitcnt vmcnt(6)
	s_waitcnt lgkmcnt(0)
	s_barrier
	s_setprio 1
	v_mfma_f32_16x16x32_bf16 v[60:63], v[140:143], v[164:167], v[60:63]
	v_mfma_f32_16x16x32_bf16 v[56:59], v[156:159], v[164:167], v[56:59]
	v_mfma_f32_16x16x32_bf16 v[48:51], v[140:143], v[172:175], v[48:51]
	v_mfma_f32_16x16x32_bf16 v[40:43], v[156:159], v[172:175], v[40:43]
	v_mfma_f32_16x16x32_bf16 v[28:31], v[140:143], v[180:183], v[28:31]
	v_mfma_f32_16x16x32_bf16 v[24:27], v[156:159], v[180:183], v[24:27]
	v_mfma_f32_16x16x32_bf16 v[16:19], v[140:143], v[188:191], v[16:19]
	v_mfma_f32_16x16x32_bf16 v[8:11], v[156:159], v[188:191], v[8:11]
	v_mfma_f32_16x16x32_bf16 v[60:63], v[152:155], v[168:171], v[60:63]
	v_mfma_f32_16x16x32_bf16 v[56:59], v[160:163], v[168:171], v[56:59]
	v_mfma_f32_16x16x32_bf16 v[48:51], v[152:155], v[176:179], v[48:51]
	v_mfma_f32_16x16x32_bf16 v[40:43], v[160:163], v[176:179], v[40:43]
	v_mfma_f32_16x16x32_bf16 v[28:31], v[152:155], v[184:187], v[28:31]
	v_mfma_f32_16x16x32_bf16 v[24:27], v[160:163], v[184:187], v[24:27]
	v_mfma_f32_16x16x32_bf16 v[16:19], v[152:155], v[192:195], v[16:19]
	v_mfma_f32_16x16x32_bf16 v[8:11], v[160:163], v[192:195], v[8:11]
	v_mfma_f32_16x16x32_bf16 v[52:55], v[196:199], v[164:167], v[52:55]
	v_mfma_f32_16x16x32_bf16 v[44:47], v[204:207], v[164:167], v[44:47]
	v_mfma_f32_16x16x32_bf16 v[36:39], v[196:199], v[172:175], v[36:39]
	v_mfma_f32_16x16x32_bf16 v[32:35], v[204:207], v[172:175], v[32:35]
	v_mfma_f32_16x16x32_bf16 v[20:23], v[196:199], v[180:183], v[20:23]
	v_mfma_f32_16x16x32_bf16 v[12:15], v[204:207], v[180:183], v[12:15]
	v_mfma_f32_16x16x32_bf16 v[4:7], v[196:199], v[188:191], v[4:7]
	v_mfma_f32_16x16x32_bf16 v[0:3], v[204:207], v[188:191], v[0:3]
	v_mfma_f32_16x16x32_bf16 v[52:55], v[200:203], v[168:171], v[52:55]
	v_mfma_f32_16x16x32_bf16 v[44:47], v[208:211], v[168:171], v[44:47]
	v_mfma_f32_16x16x32_bf16 v[36:39], v[200:203], v[176:179], v[36:39]
	v_mfma_f32_16x16x32_bf16 v[32:35], v[208:211], v[176:179], v[32:35]
	v_mfma_f32_16x16x32_bf16 v[20:23], v[200:203], v[184:187], v[20:23]
	v_mfma_f32_16x16x32_bf16 v[12:15], v[208:211], v[184:187], v[12:15]
	v_mfma_f32_16x16x32_bf16 v[4:7], v[200:203], v[192:195], v[4:7]
	v_mfma_f32_16x16x32_bf16 v[0:3], v[208:211], v[192:195], v[0:3]
	s_setprio 0
	s_add_i32 s71, 0, 0x18000
	v_add_u32_e32 v160, s71, v147
	s_barrier
; #define PG8_STAGE(bufoff, gbase, voff) do { _Pragma("unroll") for (int _i = 0; _i < 2; ++_i) \
;         __builtin_amdgcn_global_load_lds((const unsigned*)((const char*)(gbase) + (voff)[_i]), (LAS unsigned*)(lds + (bufoff) + ldsw + _i * 8192), 16, 0, 0); } while (0)
; #define PG8_LDA(dst, b, h) do { _Pragma("unroll") for (int m = 0; m < 4; ++m) _Pragma("unroll") for (int k = 0; k < 2; ++k) dst[m][k] = *(const LAS bf16x8*)(lds + PG8_SA(b, h) + aoff + m * 2048 + k * 1024); } while (0)
; #define PG8_WAIT_V(n) asm volatile("s_waitcnt vmcnt(" #n ")" ::: "memory")
; #define PG8_WAIT_L(n) asm volatile("s_waitcnt lgkmcnt(" #n ")" ::: "memory")
; template <class Epi>
; __device__ __forceinline__ void gemm_phase(LAS unsigned char* lds, const Gemm g, const StaticOrder& S, const Epi& E) {
;     ...
;         for (int t = 0; t < nt; t += 2) {
;             const bool last = (t == nt - 2);
;             const char* a1 = cA + (size_t)(t + 1) * kstep;
;             const char* a2 = last ? nA : cA + (size_t)(t + 2) * kstep; const char* b2 = last ? nB : cB + (size_t)(t + 2) * kstep;
;             const char* a3 = a2 + kstep; const char* b3 = b2 + kstep;
;             PG8_LDB(B0, 0, 0); PG8_SCHED; PG8_LDA(At, 0, 0); PG8_STAGE(PG8_SA(1, 1), a1 + hstepA, voffA);
;             PG8_WAIT_L(8); PG8_BAR; PG8_WAIT_L(0); PG8_MMA(0, 0, At, B0); PG8_BAR; PG8_SCHED;
;             PG8_LDB(B1, 0, 1); PG8_STAGE(PG8_SB(0, 0), b2, voffB);
;             PG8_BAR; PG8_WAIT_L(0); PG8_MMA(0, 1, At, B1); PG8_BAR;
;             PG8_LDA(At, 0, 1); PG8_STAGE(PG8_SA(0, 0), a2, voffA);
;             PG8_BAR; PG8_WAIT_L(0); PG8_MMA(1, 0, At, B0); PG8_BAR; PG8_SCHED;
;             PG8_STAGE(PG8_SB(0, 1), b2 + hstepB, voffB);
;             PG8_WAIT_V(6); PG8_BAR; PG8_MMA(1, 1, At, B1); PG8_BAR;
;             PG8_LDB(B0, 1, 0); PG8_SCHED; PG8_LDA(At, 1, 0); PG8_STAGE(PG8_SA(0, 1), a2 + hstepA, voffA);
;             PG8_WAIT_L(8); PG8_BAR; PG8_WAIT_L(0); PG8_MMA(0, 0, At, B0); PG8_BAR; PG8_SCHED;
;             PG8_LDB(B1, 1, 1); PG8_STAGE(PG8_SB(1, 0), b3, voffB);
;             PG8_BAR; PG8_WAIT_L(0); PG8_MMA(0, 1, At, B1); PG8_BAR;
;             PG8_LDA(At, 1, 1); PG8_STAGE(PG8_SA(1, 0), a3, voffA);
;             PG8_BAR; PG8_WAIT_L(0); PG8_MMA(1, 0, At, B0); PG8_BAR; PG8_SCHED;
;             PG8_STAGE(PG8_SB(1, 1), b3 + hstepB, voffB);
;             PG8_WAIT_V(6); PG8_BAR; PG8_MMA(1, 1, At, B1); PG8_BAR;
	ds_read_b128 v[140:143], v160
	ds_read_b128 v[152:155], v160 offset:1024
	ds_read_b128 v[156:159], v160 offset:2048
	ds_read_b128 v[160:163], v160 offset:3072
	s_add_u32 s38, s38, 0x40000
	s_addc_u32 s39, s39, 0
	s_mov_b32 m0, s31
	ds_read_b128 v[164:167], v150 offset:32768
	ds_read_b128 v[168:171], v150 offset:33792
	ds_read_b128 v[172:175], v150 offset:34816
	ds_read_b128 v[176:179], v150 offset:35840
	ds_read_b128 v[180:183], v150 offset:36864
	ds_read_b128 v[184:187], v150 offset:37888
	ds_read_b128 v[188:191], v150 offset:38912
	ds_read_b128 v[192:195], v150 offset:39936
	global_load_lds_dwordx4 v128, s[38:39]
	s_mov_b32 m0, s40
	s_nop 0
	global_load_lds_dwordx4 v130, s[38:39]
	s_add_i32 s38, 0, 0x1c000
	v_add_u32_e32 v208, s38, v147
	ds_read_b128 v[196:199], v208
	ds_read_b128 v[200:203], v208 offset:1024
	ds_read_b128 v[204:207], v208 offset:2048
	ds_read_b128 v[208:211], v208 offset:3072
	s_waitcnt lgkmcnt(0)
	s_barrier
	s_setprio 1
	v_mfma_f32_16x16x32_bf16 v[124:127], v[140:143], v[164:167], v[124:127]
	v_mfma_f32_16x16x32_bf16 v[120:123], v[156:159], v[164:167], v[120:123]
	v_mfma_f32_16x16x32_bf16 v[112:115], v[140:143], v[172:175], v[112:115]
	v_mfma_f32_16x16x32_bf16 v[104:107], v[156:159], v[172:175], v[104:107]
	v_mfma_f32_16x16x32_bf16 v[92:95], v[140:143], v[180:183], v[92:95]
	v_mfma_f32_16x16x32_bf16 v[88:91], v[156:159], v[180:183], v[88:91]
	v_mfma_f32_16x16x32_bf16 v[80:83], v[140:143], v[188:191], v[80:83]
	v_mfma_f32_16x16x32_bf16 v[72:75], v[156:159], v[188:191], v[72:75]
	v_mfma_f32_16x16x32_bf16 v[124:127], v[152:155], v[168:171], v[124:127]
	v_mfma_f32_16x16x32_bf16 v[120:123], v[160:163], v[168:171], v[120:123]
	v_mfma_f32_16x16x32_bf16 v[112:115], v[152:155], v[176:179], v[112:115]
	v_mfma_f32_16x16x32_bf16 v[104:107], v[160:163], v[176:179], v[104:107]
	v_mfma_f32_16x16x32_bf16 v[92:95], v[152:155], v[184:187], v[92:95]
	v_mfma_f32_16x16x32_bf16 v[88:91], v[160:163], v[184:187], v[88:91]
	v_mfma_f32_16x16x32_bf16 v[80:83], v[152:155], v[192:195], v[80:83]
	v_mfma_f32_16x16x32_bf16 v[72:75], v[160:163], v[192:195], v[72:75]
	v_mfma_f32_16x16x32_bf16 v[116:119], v[196:199], v[164:167], v[116:119]
	v_mfma_f32_16x16x32_bf16 v[108:111], v[204:207], v[164:167], v[108:111]
	v_mfma_f32_16x16x32_bf16 v[100:103], v[196:199], v[172:175], v[100:103]
	v_mfma_f32_16x16x32_bf16 v[96:99], v[204:207], v[172:175], v[96:99]
	v_mfma_f32_16x16x32_bf16 v[84:87], v[196:199], v[180:183], v[84:87]
	v_mfma_f32_16x16x32_bf16 v[76:79], v[204:207], v[180:183], v[76:79]
	v_mfma_f32_16x16x32_bf16 v[68:71], v[196:199], v[188:191], v[68:71]
	v_mfma_f32_16x16x32_bf16 v[64:67], v[204:207], v[188:191], v[64:67]
	v_mfma_f32_16x16x32_bf16 v[116:119], v[200:203], v[168:171], v[116:119]
	v_mfma_f32_16x16x32_bf16 v[108:111], v[208:211], v[168:171], v[108:111]
	v_mfma_f32_16x16x32_bf16 v[100:103], v[200:203], v[176:179], v[100:103]
	v_mfma_f32_16x16x32_bf16 v[96:99], v[208:211], v[176:179], v[96:99]
	v_mfma_f32_16x16x32_bf16 v[84:87], v[200:203], v[184:187], v[84:87]
	v_mfma_f32_16x16x32_bf16 v[76:79], v[208:211], v[184:187], v[76:79]
	v_mfma_f32_16x16x32_bf16 v[68:71], v[200:203], v[192:195], v[68:71]
	v_mfma_f32_16x16x32_bf16 v[64:67], v[208:211], v[192:195], v[64:67]
	s_setprio 0
	s_barrier
	s_nop 1
	ds_read_b128 v[164:167], v150 offset:49152
	ds_read_b128 v[168:171], v150 offset:50176
	ds_read_b128 v[172:175], v150 offset:51200
	ds_read_b128 v[176:179], v150 offset:52224
	ds_read_b128 v[180:183], v150 offset:53248
	ds_read_b128 v[184:187], v150 offset:54272
	ds_read_b128 v[188:191], v150 offset:55296
	ds_read_b128 v[192:195], v150 offset:56320
	s_add_i32 s39, s71, s7
	s_mov_b32 m0, s39
	s_nop 0
	s_add_u32 s100, s36, s12
	s_addc_u32 s101, s37, s13
	global_load_lds_dwordx4 v128, s[100:101]
	s_add_i32 m0, s39, 0x2000
	s_nop 0
	s_add_u32 s100, s36, s12
	s_addc_u32 s101, s37, s13
	global_load_lds_dwordx4 v130, s[100:101]
	s_mov_b32 m0, s42
	v_lshl_add_u64 v[254:255], v[214:215], 0, s[12:13]
	global_load_lds_dwordx4 v[254:255], off
	v_lshl_add_u64 v[144:145], v[216:217], 0, s[12:13]
	s_mov_b32 m0, s43
	s_nop 0
	global_load_lds_dwordx4 v[144:145], off
	s_add_u32 s36, s36, 0x40080
	s_addc_u32 s37, s37, 0
	s_add_i32 s38, s38, s7
	s_mov_b32 m0, s38
	s_nop 0
	global_load_lds_dwordx4 v128, s[36:37]
	s_add_i32 m0, s38, 0x2000
	s_nop 0
	global_load_lds_dwordx4 v130, s[36:37]
	s_waitcnt vmcnt(6)
	s_waitcnt lgkmcnt(0)
	s_barrier
	s_setprio 1
	v_mfma_f32_16x16x32_bf16 v[60:63], v[140:143], v[164:167], v[60:63]
	v_mfma_f32_16x16x32_bf16 v[56:59], v[156:159], v[164:167], v[56:59]
	v_mfma_f32_16x16x32_bf16 v[48:51], v[140:143], v[172:175], v[48:51]
	v_mfma_f32_16x16x32_bf16 v[40:43], v[156:159], v[172:175], v[40:43]
	v_mfma_f32_16x16x32_bf16 v[28:31], v[140:143], v[180:183], v[28:31]
	v_mfma_f32_16x16x32_bf16 v[24:27], v[156:159], v[180:183], v[24:27]
	v_mfma_f32_16x16x32_bf16 v[16:19], v[140:143], v[188:191], v[16:19]
	v_mfma_f32_16x16x32_bf16 v[8:11], v[156:159], v[188:191], v[8:11]
	v_mfma_f32_16x16x32_bf16 v[60:63], v[152:155], v[168:171], v[60:63]
	v_mfma_f32_16x16x32_bf16 v[56:59], v[160:163], v[168:171], v[56:59]
	v_mfma_f32_16x16x32_bf16 v[48:51], v[152:155], v[176:179], v[48:51]
	v_mfma_f32_16x16x32_bf16 v[40:43], v[160:163], v[176:179], v[40:43]
	v_mfma_f32_16x16x32_bf16 v[28:31], v[152:155], v[184:187], v[28:31]
	v_mfma_f32_16x16x32_bf16 v[24:27], v[160:163], v[184:187], v[24:27]
	v_mfma_f32_16x16x32_bf16 v[16:19], v[152:155], v[192:195], v[16:19]
	v_mfma_f32_16x16x32_bf16 v[8:11], v[160:163], v[192:195], v[8:11]
	v_mfma_f32_16x16x32_bf16 v[52:55], v[196:199], v[164:167], v[52:55]
	v_mfma_f32_16x16x32_bf16 v[44:47], v[204:207], v[164:167], v[44:47]
	v_mfma_f32_16x16x32_bf16 v[36:39], v[196:199], v[172:175], v[36:39]
	v_mfma_f32_16x16x32_bf16 v[32:35], v[204:207], v[172:175], v[32:35]
	v_mfma_f32_16x16x32_bf16 v[20:23], v[196:199], v[180:183], v[20:23]
	v_mfma_f32_16x16x32_bf16 v[12:15], v[204:207], v[180:183], v[12:15]
	v_mfma_f32_16x16x32_bf16 v[4:7], v[196:199], v[188:191], v[4:7]
	v_mfma_f32_16x16x32_bf16 v[0:3], v[204:207], v[188:191], v[0:3]
	v_mfma_f32_16x16x32_bf16 v[52:55], v[200:203], v[168:171], v[52:55]
	v_mfma_f32_16x16x32_bf16 v[44:47], v[208:211], v[168:171], v[44:47]
	v_mfma_f32_16x16x32_bf16 v[36:39], v[200:203], v[176:179], v[36:39]
	v_mfma_f32_16x16x32_bf16 v[32:35], v[208:211], v[176:179], v[32:35]
	v_mfma_f32_16x16x32_bf16 v[20:23], v[200:203], v[184:187], v[20:23]
	v_mfma_f32_16x16x32_bf16 v[12:15], v[208:211], v[184:187], v[12:15]
	v_mfma_f32_16x16x32_bf16 v[4:7], v[200:203], v[192:195], v[4:7]
	v_mfma_f32_16x16x32_bf16 v[0:3], v[208:211], v[192:195], v[0:3]
	s_setprio 0
	s_add_i32 s70, s70, 2
	s_add_u32 s34, s34, 0x100
	s_addc_u32 s35, s35, 0
	s_add_u32 s49, s49, 0x100
	s_addc_u32 s63, s63, 0
	s_cmp_gt_u32 s70, 13
	s_barrier
;     __device__ __forceinline__ void operator()(AccRef acc, const Unit& u, int wr, int wc, int fr, int fq) const {
;     ...
;         for (int ai = 0; ai < 2; ++ai)
; #pragma unroll
;             for (int mh = 0; mh < 2; ++mh) {
;                 f32x4 bs[2][2][2];
; #pragma unroll
;                 for (int m = 0; m < 2; ++m)
; #pragma unroll
;                     for (int bj = 0; bj < 2; ++bj)
; #pragma unroll
;                         for (int n = 0; n < 2; ++n) bs[m][bj][n] = *(const f32x4*)(base + (size_t)(row0 + ai * 128 + (2 * mh + m) * 16) * D + col0 + bj * 128 + n * 16);
; #pragma unroll
;                 for (int m = 0; m < 2; ++m)
; #pragma unroll
;                     for (int bj = 0; bj < 2; ++bj)
; #pragma unroll
;                         for (int n = 0; n < 2; ++n) *(f32x4*)(out + (size_t)(row0 + ai * 128 + (2 * mh + m) * 16) * D + col0 + bj * 128 + n * 16) = bs[m][bj][n] + sv[bj][n] * (acc[ai][bj][2 * mh + m][n] + bv[bj][n]);
;                 asm volatile("" ::: "memory"); }
	s_cbranch_scc0 .LBB0_1820
	v_lshl_or_b32 v144, s46, 8, v148
	v_lshl_add_u32 v145, s30, 8, v146
	v_lshlrev_b32_e32 v144, 2, v144
	v_lshl_add_u32 v145, v145, 12, v144
	v_add_u32_e32 v216, 0x10000, v145
	v_add_u32_e32 v217, 0x20000, v145
	v_add_u32_e32 v218, 0x30000, v145
	v_add_u32_e32 v232, 0x80000, v145
	v_add_u32_e32 v233, 0x90000, v145
	v_add_u32_e32 v235, 0xa0000, v145
	v_add_u32_e32 v253, 0xb0000, v145
	s_and_b64 vcc, exec, s[10:11]
	s_mov_b32 s46, s22
	s_mov_b32 s30, s24
	s_mov_b64 s[36:37], s[28:29]
	s_mov_b64 s[34:35], s[26:27]
	global_load_dwordx4 v[140:143], v145, s[52:53]
	global_load_dwordx4 v[152:155], v145, s[52:53] offset:64
	global_load_dwordx4 v[156:159], v145, s[52:53] offset:512
	global_load_dwordx4 v[160:163], v145, s[52:53] offset:576
	global_load_dwordx4 v[164:167], v216, s[52:53]
	global_load_dwordx4 v[168:171], v216, s[52:53] offset:64
	global_load_dwordx4 v[172:175], v216, s[52:53] offset:512
	global_load_dwordx4 v[176:179], v216, s[52:53] offset:576
	global_load_dwordx4 v[180:183], v217, s[52:53]
	global_load_dwordx4 v[184:187], v217, s[52:53] offset:64
	global_load_dwordx4 v[188:191], v217, s[52:53] offset:512
	global_load_dwordx4 v[192:195], v217, s[52:53] offset:576
	global_load_dwordx4 v[196:199], v218, s[52:53]
	global_load_dwordx4 v[200:203], v218, s[52:53] offset:64
	global_load_dwordx4 v[204:207], v218, s[52:53] offset:512
	global_load_dwordx4 v[208:211], v218, s[52:53] offset:576
	global_load_dwordx4 v[212:215], v232, s[52:53]
	global_load_dwordx4 v[220:223], v232, s[52:53] offset:64
	global_load_dwordx4 v[224:227], v232, s[52:53] offset:512
	global_load_dwordx4 v[228:231], v232, s[52:53] offset:576
	global_load_dwordx4 v[236:239], v233, s[52:53]
	global_load_dwordx4 v[240:243], v233, s[52:53] offset:64
	global_load_dwordx4 v[244:247], v233, s[52:53] offset:512
	global_load_dwordx4 v[248:251], v233, s[52:53] offset:576
	v_pk_add_f32 v[124:125], v[124:125], 0 op_sel_hi:[1,0]
	v_pk_add_f32 v[126:127], v[126:127], 0 op_sel_hi:[1,0]
	v_pk_add_f32 v[120:121], v[120:121], 0 op_sel_hi:[1,0]
	v_pk_add_f32 v[122:123], v[122:123], 0 op_sel_hi:[1,0]
	v_pk_add_f32 v[116:117], v[116:117], 0 op_sel_hi:[1,0]
	v_pk_add_f32 v[118:119], v[118:119], 0 op_sel_hi:[1,0]
	v_pk_add_f32 v[108:109], v[108:109], 0 op_sel_hi:[1,0]
	v_pk_add_f32 v[110:111], v[110:111], 0 op_sel_hi:[1,0]
	v_pk_add_f32 v[112:113], v[112:113], 0 op_sel_hi:[1,0]
	v_pk_add_f32 v[114:115], v[114:115], 0 op_sel_hi:[1,0]
	v_pk_add_f32 v[104:105], v[104:105], 0 op_sel_hi:[1,0]
	v_pk_add_f32 v[106:107], v[106:107], 0 op_sel_hi:[1,0]
	v_pk_add_f32 v[100:101], v[100:101], 0 op_sel_hi:[1,0]
	v_pk_add_f32 v[102:103], v[102:103], 0 op_sel_hi:[1,0]
	v_pk_add_f32 v[96:97], v[96:97], 0 op_sel_hi:[1,0]
	v_pk_add_f32 v[98:99], v[98:99], 0 op_sel_hi:[1,0]
	v_pk_add_f32 v[92:93], v[92:93], 0 op_sel_hi:[1,0]
	v_pk_add_f32 v[94:95], v[94:95], 0 op_sel_hi:[1,0]
	v_pk_add_f32 v[88:89], v[88:89], 0 op_sel_hi:[1,0]
	v_pk_add_f32 v[90:91], v[90:91], 0 op_sel_hi:[1,0]
	v_pk_add_f32 v[84:85], v[84:85], 0 op_sel_hi:[1,0]
	v_pk_add_f32 v[86:87], v[86:87], 0 op_sel_hi:[1,0]
	v_pk_add_f32 v[76:77], v[76:77], 0 op_sel_hi:[1,0]
	v_pk_add_f32 v[78:79], v[78:79], 0 op_sel_hi:[1,0]
	v_pk_add_f32 v[80:81], v[80:81], 0 op_sel_hi:[1,0]
	v_pk_add_f32 v[82:83], v[82:83], 0 op_sel_hi:[1,0]
	v_pk_add_f32 v[72:73], v[72:73], 0 op_sel_hi:[1,0]
	v_pk_add_f32 v[74:75], v[74:75], 0 op_sel_hi:[1,0]
	v_pk_add_f32 v[68:69], v[68:69], 0 op_sel_hi:[1,0]
	v_pk_add_f32 v[70:71], v[70:71], 0 op_sel_hi:[1,0]
	v_pk_add_f32 v[64:65], v[64:65], 0 op_sel_hi:[1,0]
	v_pk_add_f32 v[66:67], v[66:67], 0 op_sel_hi:[1,0]
	v_pk_add_f32 v[60:61], v[60:61], 0 op_sel_hi:[1,0]
	v_pk_add_f32 v[62:63], v[62:63], 0 op_sel_hi:[1,0]
	v_pk_add_f32 v[56:57], v[56:57], 0 op_sel_hi:[1,0]
	v_pk_add_f32 v[58:59], v[58:59], 0 op_sel_hi:[1,0]
	v_pk_add_f32 v[52:53], v[52:53], 0 op_sel_hi:[1,0]
	v_pk_add_f32 v[54:55], v[54:55], 0 op_sel_hi:[1,0]
	v_pk_add_f32 v[44:45], v[44:45], 0 op_sel_hi:[1,0]
	v_pk_add_f32 v[46:47], v[46:47], 0 op_sel_hi:[1,0]
	v_pk_add_f32 v[48:49], v[48:49], 0 op_sel_hi:[1,0]
	v_pk_add_f32 v[50:51], v[50:51], 0 op_sel_hi:[1,0]
	v_pk_add_f32 v[40:41], v[40:41], 0 op_sel_hi:[1,0]
	v_pk_add_f32 v[42:43], v[42:43], 0 op_sel_hi:[1,0]
	v_pk_add_f32 v[36:37], v[36:37], 0 op_sel_hi:[1,0]
	v_pk_add_f32 v[38:39], v[38:39], 0 op_sel_hi:[1,0]
	v_pk_add_f32 v[32:33], v[32:33], 0 op_sel_hi:[1,0]
	v_pk_add_f32 v[34:35], v[34:35], 0 op_sel_hi:[1,0]
	v_pk_add_f32 v[28:29], v[28:29], 0 op_sel_hi:[1,0]
	v_pk_add_f32 v[30:31], v[30:31], 0 op_sel_hi:[1,0]
	v_pk_add_f32 v[24:25], v[24:25], 0 op_sel_hi:[1,0]
	v_pk_add_f32 v[26:27], v[26:27], 0 op_sel_hi:[1,0]
	v_pk_add_f32 v[20:21], v[20:21], 0 op_sel_hi:[1,0]
	v_pk_add_f32 v[22:23], v[22:23], 0 op_sel_hi:[1,0]
	v_pk_add_f32 v[12:13], v[12:13], 0 op_sel_hi:[1,0]
	v_pk_add_f32 v[14:15], v[14:15], 0 op_sel_hi:[1,0]
	v_pk_add_f32 v[16:17], v[16:17], 0 op_sel_hi:[1,0]
	v_pk_add_f32 v[18:19], v[18:19], 0 op_sel_hi:[1,0]
	v_pk_add_f32 v[8:9], v[8:9], 0 op_sel_hi:[1,0]
	v_pk_add_f32 v[10:11], v[10:11], 0 op_sel_hi:[1,0]
	v_pk_add_f32 v[4:5], v[4:5], 0 op_sel_hi:[1,0]
	v_pk_add_f32 v[6:7], v[6:7], 0 op_sel_hi:[1,0]
	v_pk_add_f32 v[0:1], v[0:1], 0 op_sel_hi:[1,0]
	v_pk_add_f32 v[2:3], v[2:3], 0 op_sel_hi:[1,0]
	s_waitcnt vmcnt(16)
; #define PG8_WAIT_V(n) asm volatile("s_waitcnt vmcnt(" #n ")" ::: "memory")
; template <class Epi>
; __device__ __forceinline__ void gemm_phase(LAS unsigned char* lds, const Gemm g, const StaticOrder& S, const Epi& E) {
;     ...
;         if (!has_next) break;
;         {
; #pragma unroll
;         for (int a = 0; a < 2; ++a)
; #pragma unroll
;             for (int b = 0; b < 2; ++b)
; #pragma unroll
;                 for (int m = 0; m < 4; ++m)
; #pragma unroll
;                     for (int n = 0; n < 2; ++n) acc[a][b][m][n] = (f32x4){0.f, 0.f, 0.f, 0.f};
;         }
;         cur = nxt; cA = nA; cB = nB; ++ui;
;     }
;     PG8_WAIT_V(0);
;     __device__ __forceinline__ void operator()(AccRef acc, const Unit& u, int wr, int wc, int fr, int fq) const {
;     ...
;                         for (int n = 0; n < 2; ++n) bs[m][bj][n] = *(const f32x4*)(base + (size_t)(row0 + ai * 128 + (2 * mh + m) * 16) * D + col0 + bj * 128 + n * 16);
; #pragma unroll
;                 for (int m = 0; m < 2; ++m)
; #pragma unroll
;                     for (int bj = 0; bj < 2; ++bj)
; #pragma unroll
;                         for (int n = 0; n < 2; ++n) *(f32x4*)(out + (size_t)(row0 + ai * 128 + (2 * mh + m) * 16) * D + col0 + bj * 128 + n * 16) = bs[m][bj][n] + sv[bj][n] * (acc[ai][bj][2 * mh + m][n] + bv[bj][n]);
;                 asm volatile("" ::: "memory"); }
	v_pk_add_f32 v[124:125], v[124:125], v[140:141]
	v_pk_add_f32 v[126:127], v[126:127], v[142:143]
	v_pk_add_f32 v[120:121], v[120:121], v[152:153]
	v_pk_add_f32 v[122:123], v[122:123], v[154:155]
	v_pk_add_f32 v[116:117], v[116:117], v[156:157]
	v_pk_add_f32 v[118:119], v[118:119], v[158:159]
	v_pk_add_f32 v[108:109], v[108:109], v[160:161]
	v_pk_add_f32 v[110:111], v[110:111], v[162:163]
	v_pk_add_f32 v[112:113], v[112:113], v[164:165]
	v_pk_add_f32 v[114:115], v[114:115], v[166:167]
	v_pk_add_f32 v[104:105], v[104:105], v[168:169]
	v_pk_add_f32 v[106:107], v[106:107], v[170:171]
	v_pk_add_f32 v[100:101], v[100:101], v[172:173]
	v_pk_add_f32 v[102:103], v[102:103], v[174:175]
	v_pk_add_f32 v[96:97], v[96:97], v[176:177]
	v_pk_add_f32 v[98:99], v[98:99], v[178:179]
	global_store_dwordx4 v145, v[124:127], s[52:53]
	global_store_dwordx4 v145, v[120:123], s[52:53] offset:64
	global_store_dwordx4 v145, v[116:119], s[52:53] offset:512
	global_store_dwordx4 v145, v[108:111], s[52:53] offset:576
	global_store_dwordx4 v216, v[112:115], s[52:53]
	global_store_dwordx4 v216, v[104:107], s[52:53] offset:64
	global_store_dwordx4 v216, v[100:103], s[52:53] offset:512
	global_store_dwordx4 v216, v[96:99], s[52:53] offset:576
	global_load_dwordx4 v[140:143], v235, s[52:53]
	global_load_dwordx4 v[152:155], v235, s[52:53] offset:64
	global_load_dwordx4 v[156:159], v235, s[52:53] offset:512
	global_load_dwordx4 v[160:163], v235, s[52:53] offset:576
	global_load_dwordx4 v[164:167], v253, s[52:53]
	global_load_dwordx4 v[168:171], v253, s[52:53] offset:64
	global_load_dwordx4 v[172:175], v253, s[52:53] offset:512
	global_load_dwordx4 v[176:179], v253, s[52:53] offset:576
	s_waitcnt vmcnt(24)
	v_pk_add_f32 v[92:93], v[92:93], v[180:181]
	v_pk_add_f32 v[94:95], v[94:95], v[182:183]
	v_pk_add_f32 v[88:89], v[88:89], v[184:185]
	v_pk_add_f32 v[90:91], v[90:91], v[186:187]
	v_pk_add_f32 v[84:85], v[84:85], v[188:189]
	v_pk_add_f32 v[86:87], v[86:87], v[190:191]
	v_pk_add_f32 v[76:77], v[76:77], v[192:193]
	v_pk_add_f32 v[78:79], v[78:79], v[194:195]
	v_pk_add_f32 v[80:81], v[80:81], v[196:197]
	v_pk_add_f32 v[82:83], v[82:83], v[198:199]
	v_pk_add_f32 v[72:73], v[72:73], v[200:201]
	v_pk_add_f32 v[74:75], v[74:75], v[202:203]
	v_pk_add_f32 v[68:69], v[68:69], v[204:205]
	v_pk_add_f32 v[70:71], v[70:71], v[206:207]
	v_pk_add_f32 v[64:65], v[64:65], v[208:209]
	v_pk_add_f32 v[66:67], v[66:67], v[210:211]
	global_store_dwordx4 v217, v[92:95], s[52:53]
	global_store_dwordx4 v217, v[88:91], s[52:53] offset:64
	global_store_dwordx4 v217, v[84:87], s[52:53] offset:512
	global_store_dwordx4 v217, v[76:79], s[52:53] offset:576
	global_store_dwordx4 v218, v[80:83], s[52:53]
	global_store_dwordx4 v218, v[72:75], s[52:53] offset:64
	global_store_dwordx4 v218, v[68:71], s[52:53] offset:512
	global_store_dwordx4 v218, v[64:67], s[52:53] offset:576
	s_waitcnt vmcnt(24)
	v_pk_add_f32 v[60:61], v[60:61], v[212:213]
	v_pk_add_f32 v[62:63], v[62:63], v[214:215]
	v_pk_add_f32 v[56:57], v[56:57], v[220:221]
	v_pk_add_f32 v[58:59], v[58:59], v[222:223]
	v_pk_add_f32 v[52:53], v[52:53], v[224:225]
	v_pk_add_f32 v[54:55], v[54:55], v[226:227]
	v_pk_add_f32 v[44:45], v[44:45], v[228:229]
	v_pk_add_f32 v[46:47], v[46:47], v[230:231]
	v_pk_add_f32 v[48:49], v[48:49], v[236:237]
	v_pk_add_f32 v[50:51], v[50:51], v[238:239]
	v_pk_add_f32 v[40:41], v[40:41], v[240:241]
	v_pk_add_f32 v[42:43], v[42:43], v[242:243]
	v_pk_add_f32 v[36:37], v[36:37], v[244:245]
	v_pk_add_f32 v[38:39], v[38:39], v[246:247]
	v_pk_add_f32 v[32:33], v[32:33], v[248:249]
	v_pk_add_f32 v[34:35], v[34:35], v[250:251]
	global_store_dwordx4 v232, v[60:63], s[52:53]
	global_store_dwordx4 v232, v[56:59], s[52:53] offset:64
	global_store_dwordx4 v232, v[52:55], s[52:53] offset:512
	global_store_dwordx4 v232, v[44:47], s[52:53] offset:576
	global_store_dwordx4 v233, v[48:51], s[52:53]
	global_store_dwordx4 v233, v[40:43], s[52:53] offset:64
	global_store_dwordx4 v233, v[36:39], s[52:53] offset:512
	global_store_dwordx4 v233, v[32:35], s[52:53] offset:576
	s_waitcnt vmcnt(16)
	v_pk_add_f32 v[28:29], v[28:29], v[140:141]
	v_pk_add_f32 v[30:31], v[30:31], v[142:143]
	v_pk_add_f32 v[24:25], v[24:25], v[152:153]
	v_pk_add_f32 v[26:27], v[26:27], v[154:155]
	v_pk_add_f32 v[20:21], v[20:21], v[156:157]
	v_pk_add_f32 v[22:23], v[22:23], v[158:159]
	v_pk_add_f32 v[12:13], v[12:13], v[160:161]
	v_pk_add_f32 v[14:15], v[14:15], v[162:163]
	v_pk_add_f32 v[16:17], v[16:17], v[164:165]
	v_pk_add_f32 v[18:19], v[18:19], v[166:167]
	v_pk_add_f32 v[8:9], v[8:9], v[168:169]
	v_pk_add_f32 v[10:11], v[10:11], v[170:171]
	v_pk_add_f32 v[4:5], v[4:5], v[172:173]
	v_pk_add_f32 v[6:7], v[6:7], v[174:175]
	v_pk_add_f32 v[0:1], v[0:1], v[176:177]
	v_pk_add_f32 v[2:3], v[2:3], v[178:179]
	global_store_dwordx4 v235, v[28:31], s[52:53]
	global_store_dwordx4 v235, v[24:27], s[52:53] offset:64
	global_store_dwordx4 v235, v[20:23], s[52:53] offset:512
	global_store_dwordx4 v235, v[12:15], s[52:53] offset:576
	global_store_dwordx4 v253, v[16:19], s[52:53]
	global_store_dwordx4 v253, v[8:11], s[52:53] offset:64
	global_store_dwordx4 v253, v[4:7], s[52:53] offset:512
	global_store_dwordx4 v253, v[0:3], s[52:53] offset:576
	s_cbranch_vccz .LBB0_1813
	s_waitcnt vmcnt(0)
	s_cmpk_gt_u32 s4, 0xff
	s_cbranch_scc1 .LBB0_1824
	s_barrier

; #define PG8_STAGE(bufoff, gbase, voff) do { _Pragma("unroll") for (int _i = 0; _i < 2; ++_i) \
;         __builtin_amdgcn_global_load_lds((const unsigned*)((const char*)(gbase) + (voff)[_i]), (LAS unsigned*)(lds + (bufoff) + ldsw + _i * 8192), 16, 0, 0); } while (0)
; #define PG8_LDA(dst, b, h) do { _Pragma("unroll") for (int m = 0; m < 4; ++m) _Pragma("unroll") for (int k = 0; k < 2; ++k) dst[m][k] = *(const LAS bf16x8*)(lds + PG8_SA(b, h) + aoff + m * 2048 + k * 1024); } while (0)
; #define PG8_LDB(dst, b, h) do { _Pragma("unroll") for (int n = 0; n < 2; ++n) _Pragma("unroll") for (int k = 0; k < 2; ++k) dst[n][k] = *(const LAS bf16x8*)(lds + PG8_SB(b, h) + boff + n * 2048 + k * 1024); } while (0)
; #define PG8_MMA(ai, bj, At, Bt) do { __builtin_amdgcn_s_setprio(1); _Pragma("unroll") for (int m = 0; m < 4; ++m) _Pragma("unroll") for (int n = 0; n < 2; ++n) _Pragma("unroll") for (int k = 0; k < 2; ++k) \
;         acc[ai][bj][m][n] = __builtin_amdgcn_mfma_f32_16x16x32_bf16(Bt[n][k], At[m][k], acc[ai][bj][m][n], 0, 0, 0); __builtin_amdgcn_s_setprio(0); } while (0)
; #define PG8_WAIT_V(n) asm volatile("s_waitcnt vmcnt(" #n ")" ::: "memory")
; #define PG8_WAIT_L(n) asm volatile("s_waitcnt lgkmcnt(" #n ")" ::: "memory")
; template <class Epi>
; __device__ __forceinline__ void gemm_phase(LAS unsigned char* lds, const Gemm g, const StaticOrder& S, const Epi& E) {
;     ...
;         for (int t = 0; t < nt; t += 2) {
;             const bool last = (t == nt - 2);
;             const char* a1 = cA + (size_t)(t + 1) * kstep;
;             const char* a2 = last ? nA : cA + (size_t)(t + 2) * kstep; const char* b2 = last ? nB : cB + (size_t)(t + 2) * kstep;
;             const char* a3 = a2 + kstep; const char* b3 = b2 + kstep;
;             PG8_LDB(B0, 0, 0); PG8_SCHED; PG8_LDA(At, 0, 0); PG8_STAGE(PG8_SA(1, 1), a1 + hstepA, voffA);
;             PG8_WAIT_L(8); PG8_BAR; PG8_WAIT_L(0); PG8_MMA(0, 0, At, B0); PG8_BAR; PG8_SCHED;
;             PG8_LDB(B1, 0, 1); PG8_STAGE(PG8_SB(0, 0), b2, voffB);
;             PG8_BAR; PG8_WAIT_L(0); PG8_MMA(0, 1, At, B1); PG8_BAR;
;             PG8_LDA(At, 0, 1); PG8_STAGE(PG8_SA(0, 0), a2, voffA);
;             PG8_BAR; PG8_WAIT_L(0); PG8_MMA(1, 0, At, B0); PG8_BAR; PG8_SCHED;
;             PG8_STAGE(PG8_SB(0, 1), b2 + hstepB, voffB);
;             PG8_WAIT_V(6); PG8_BAR; PG8_MMA(1, 1, At, B1); PG8_BAR;
.LBB0_1939:
	s_ashr_i32 s27, s26, 31
	v_cmp_lt_i64_e32 vcc, s[28:29], v[228:229]
	s_lshl_b64 s[28:29], s[26:27], 19
	s_add_u32 s28, s66, s28
	s_addc_u32 s29, s67, s29
	s_and_b64 s[30:31], vcc, exec
	s_cselect_b32 s27, s29, s37
	s_cselect_b32 s68, s28, s36
	s_ashr_i32 s25, s24, 31
	s_lshl_b64 s[30:31], s[24:25], 19
	s_add_u32 s30, s5, s30
	s_addc_u32 s31, s6, s31
	s_and_b64 s[40:41], vcc, exec
	s_cselect_b32 s25, s31, s39
	s_cselect_b32 s69, s30, s38
	s_add_u32 s70, s38, 0x100
	s_addc_u32 s71, s39, 0
	s_mov_b32 s72, -2
	ds_read_b128 v[96:99], v242
	ds_read_b128 v[100:103], v242 offset:1024
	ds_read_b128 v[104:107], v242 offset:2048
	ds_read_b128 v[108:111], v242 offset:3072
	s_add_u32 s38, s36, 0x100
	s_addc_u32 s39, s37, 0
	s_cmp_eq_u32 s72, 12
	s_cselect_b32 s43, s27, s39
	s_cselect_b32 s42, s68, s38
	s_cselect_b32 s41, s25, s71
	s_cselect_b32 s40, s69, s70
	s_add_i32 m0, s45, 0xc000
	ds_read_b128 v[112:115], v243
	ds_read_b128 v[116:119], v243 offset:1024
	ds_read_b128 v[120:123], v243 offset:2048
	ds_read_b128 v[124:127], v243 offset:3072
	ds_read_b128 v[160:163], v243 offset:4096
	ds_read_b128 v[164:167], v243 offset:5120
	ds_read_b128 v[168:171], v243 offset:6144
	ds_read_b128 v[172:175], v243 offset:7168
	global_load_lds_dwordx4 v224, s[36:37]
	s_add_i32 m0, s45, 0xe000
	s_nop 0
	global_load_lds_dwordx4 v226, s[36:37]
	ds_read_b128 v[176:179], v244
	ds_read_b128 v[180:183], v244 offset:1024
	ds_read_b128 v[184:187], v244 offset:2048
	ds_read_b128 v[188:191], v244 offset:3072
	s_waitcnt lgkmcnt(0)
	s_barrier
	s_setprio 1
	v_mfma_f32_16x16x32_bf16 v[156:159], v[96:99], v[112:115], 0
	v_mfma_f32_16x16x32_bf16 v[60:63], v[104:107], v[112:115], 0
	v_mfma_f32_16x16x32_bf16 v[144:147], v[96:99], v[120:123], 0
	v_mfma_f32_16x16x32_bf16 v[48:51], v[104:107], v[120:123], 0
	v_mfma_f32_16x16x32_bf16 v[136:139], v[96:99], v[160:163], 0
	v_mfma_f32_16x16x32_bf16 v[40:43], v[104:107], v[160:163], 0
	v_mfma_f32_16x16x32_bf16 v[148:151], v[96:99], v[168:171], 0
	v_mfma_f32_16x16x32_bf16 v[52:55], v[104:107], v[168:171], 0
	v_mfma_f32_16x16x32_bf16 v[156:159], v[100:103], v[116:119], v[156:159]
	v_mfma_f32_16x16x32_bf16 v[60:63], v[108:111], v[116:119], v[60:63]
	v_mfma_f32_16x16x32_bf16 v[144:147], v[100:103], v[124:127], v[144:147]
	v_mfma_f32_16x16x32_bf16 v[48:51], v[108:111], v[124:127], v[48:51]
	v_mfma_f32_16x16x32_bf16 v[136:139], v[100:103], v[164:167], v[136:139]
	v_mfma_f32_16x16x32_bf16 v[40:43], v[108:111], v[164:167], v[40:43]
	v_mfma_f32_16x16x32_bf16 v[148:151], v[100:103], v[172:175], v[148:151]
	v_mfma_f32_16x16x32_bf16 v[52:55], v[108:111], v[172:175], v[52:55]
	v_mfma_f32_16x16x32_bf16 v[152:155], v[176:179], v[112:115], 0
	v_mfma_f32_16x16x32_bf16 v[56:59], v[184:187], v[112:115], 0
	v_mfma_f32_16x16x32_bf16 v[36:39], v[184:187], v[120:123], 0
	v_mfma_f32_16x16x32_bf16 v[32:35], v[184:187], v[160:163], 0
	v_mfma_f32_16x16x32_bf16 v[44:47], v[184:187], v[168:171], 0
	v_mfma_f32_16x16x32_bf16 v[152:155], v[180:183], v[116:119], v[152:155]
	v_mfma_f32_16x16x32_bf16 v[56:59], v[188:191], v[116:119], v[56:59]
	v_mfma_f32_16x16x32_bf16 v[112:115], v[176:179], v[120:123], 0
	v_mfma_f32_16x16x32_bf16 v[36:39], v[188:191], v[124:127], v[36:39]
	v_mfma_f32_16x16x32_bf16 v[116:119], v[176:179], v[160:163], 0
	v_mfma_f32_16x16x32_bf16 v[32:35], v[188:191], v[164:167], v[32:35]
	v_mfma_f32_16x16x32_bf16 v[120:123], v[176:179], v[168:171], 0
	v_mfma_f32_16x16x32_bf16 v[44:47], v[188:191], v[172:175], v[44:47]
	v_mfma_f32_16x16x32_bf16 v[112:115], v[180:183], v[124:127], v[112:115]
	v_mfma_f32_16x16x32_bf16 v[116:119], v[180:183], v[164:167], v[116:119]
	v_mfma_f32_16x16x32_bf16 v[120:123], v[180:183], v[172:175], v[120:123]
	s_setprio 0
	s_barrier
	s_nop 1
	ds_read_b128 v[124:127], v243 offset:16384
	ds_read_b128 v[128:131], v243 offset:17408
	ds_read_b128 v[132:135], v243 offset:18432
	ds_read_b128 v[140:143], v243 offset:19456
	ds_read_b128 v[160:163], v243 offset:20480
	ds_read_b128 v[164:167], v243 offset:21504
	ds_read_b128 v[168:171], v243 offset:22528
	ds_read_b128 v[172:175], v243 offset:23552
	s_add_i32 s36, s59, s7
	v_lshl_add_u64 v[196:197], s[40:41], 0, v[214:215]
	s_mov_b32 m0, s36
	s_nop 0
	global_load_lds_dwordx4 v214, s[40:41]
	v_lshl_add_u64 v[198:199], s[40:41], 0, v[210:211]
	s_add_i32 m0, s36, 0x2000
	s_nop 0
	global_load_lds_dwordx4 v210, s[40:41]
	s_mov_b32 m0, s45
	v_lshl_add_u64 v[200:201], s[42:43], 0, v[216:217]
	global_load_lds_dwordx4 v216, s[42:43]
	v_lshl_add_u64 v[202:203], s[42:43], 0, v[212:213]
	s_mov_b32 m0, s46
	s_nop 0
	global_load_lds_dwordx4 v212, s[42:43]
	s_add_u32 s36, s40, 0x40000
	s_addc_u32 s37, s41, 0
	s_add_i32 s73, s62, s7
	s_mov_b32 m0, s73
	s_nop 0
	global_load_lds_dwordx4 v214, s[36:37]
	s_add_i32 m0, s73, 0x2000
	s_nop 0
	global_load_lds_dwordx4 v210, s[36:37]
	s_waitcnt vmcnt(6)
	s_waitcnt lgkmcnt(0)
	s_barrier
; #define PG8_STAGE(bufoff, gbase, voff) do { _Pragma("unroll") for (int _i = 0; _i < 2; ++_i) \
;         __builtin_amdgcn_global_load_lds((const unsigned*)((const char*)(gbase) + (voff)[_i]), (LAS unsigned*)(lds + (bufoff) + ldsw + _i * 8192), 16, 0, 0); } while (0)
; #define PG8_LDA(dst, b, h) do { _Pragma("unroll") for (int m = 0; m < 4; ++m) _Pragma("unroll") for (int k = 0; k < 2; ++k) dst[m][k] = *(const LAS bf16x8*)(lds + PG8_SA(b, h) + aoff + m * 2048 + k * 1024); } while (0)
; #define PG8_LDB(dst, b, h) do { _Pragma("unroll") for (int n = 0; n < 2; ++n) _Pragma("unroll") for (int k = 0; k < 2; ++k) dst[n][k] = *(const LAS bf16x8*)(lds + PG8_SB(b, h) + boff + n * 2048 + k * 1024); } while (0)
; #define PG8_MMA(ai, bj, At, Bt) do { __builtin_amdgcn_s_setprio(1); _Pragma("unroll") for (int m = 0; m < 4; ++m) _Pragma("unroll") for (int n = 0; n < 2; ++n) _Pragma("unroll") for (int k = 0; k < 2; ++k) \
;         acc[ai][bj][m][n] = __builtin_amdgcn_mfma_f32_16x16x32_bf16(Bt[n][k], At[m][k], acc[ai][bj][m][n], 0, 0, 0); __builtin_amdgcn_s_setprio(0); } while (0)
; #define PG8_WAIT_V(n) asm volatile("s_waitcnt vmcnt(" #n ")" ::: "memory")
; #define PG8_WAIT_L(n) asm volatile("s_waitcnt lgkmcnt(" #n ")" ::: "memory")
; #define PG8_BAR __builtin_amdgcn_s_barrier()
; template <class Epi>
; __device__ __forceinline__ void gemm_phase(LAS unsigned char* lds, const Gemm g, const StaticOrder& S, const Epi& E) {
;     ...
;             PG8_LDB(B0, 0, 0); PG8_SCHED; PG8_LDA(At, 0, 0); PG8_STAGE(PG8_SA(1, 1), a1 + hstepA, voffA);
;             PG8_WAIT_L(8); PG8_BAR; PG8_WAIT_L(0); PG8_MMA(0, 0, At, B0); PG8_BAR; PG8_SCHED;
;             PG8_LDB(B1, 0, 1); PG8_STAGE(PG8_SB(0, 0), b2, voffB);
;             PG8_BAR; PG8_WAIT_L(0); PG8_MMA(0, 1, At, B1); PG8_BAR;
;             PG8_LDA(At, 0, 1); PG8_STAGE(PG8_SA(0, 0), a2, voffA);
;             PG8_BAR; PG8_WAIT_L(0); PG8_MMA(1, 0, At, B0); PG8_BAR; PG8_SCHED;
;             PG8_STAGE(PG8_SB(0, 1), b2 + hstepB, voffB);
;             PG8_WAIT_V(6); PG8_BAR; PG8_MMA(1, 1, At, B1); PG8_BAR;
;             PG8_LDB(B0, 1, 0); PG8_SCHED; PG8_LDA(At, 1, 0); PG8_STAGE(PG8_SA(0, 1), a2 + hstepA, voffA);
;             PG8_WAIT_L(8); PG8_BAR; PG8_WAIT_L(0); PG8_MMA(0, 0, At, B0); PG8_BAR; PG8_SCHED;
;             PG8_LDB(B1, 1, 1); PG8_STAGE(PG8_SB(1, 0), b3, voffB);
;             PG8_BAR; PG8_WAIT_L(0); PG8_MMA(0, 1, At, B1); PG8_BAR;
	s_setprio 1
	v_mfma_f32_16x16x32_bf16 v[92:95], v[96:99], v[124:127], 0
	v_mfma_f32_16x16x32_bf16 v[28:31], v[104:107], v[124:127], 0
	v_mfma_f32_16x16x32_bf16 v[80:83], v[96:99], v[132:135], 0
	v_mfma_f32_16x16x32_bf16 v[16:19], v[104:107], v[132:135], 0
	v_mfma_f32_16x16x32_bf16 v[76:79], v[96:99], v[160:163], 0
	v_mfma_f32_16x16x32_bf16 v[12:15], v[104:107], v[160:163], 0
	v_mfma_f32_16x16x32_bf16 v[84:87], v[96:99], v[168:171], 0
	v_mfma_f32_16x16x32_bf16 v[20:23], v[104:107], v[168:171], 0
	v_mfma_f32_16x16x32_bf16 v[92:95], v[100:103], v[128:131], v[92:95]
	v_mfma_f32_16x16x32_bf16 v[28:31], v[108:111], v[128:131], v[28:31]
	v_mfma_f32_16x16x32_bf16 v[80:83], v[100:103], v[140:143], v[80:83]
	v_mfma_f32_16x16x32_bf16 v[16:19], v[108:111], v[140:143], v[16:19]
	v_mfma_f32_16x16x32_bf16 v[76:79], v[100:103], v[164:167], v[76:79]
	v_mfma_f32_16x16x32_bf16 v[12:15], v[108:111], v[164:167], v[12:15]
	v_mfma_f32_16x16x32_bf16 v[84:87], v[100:103], v[172:175], v[84:87]
	v_mfma_f32_16x16x32_bf16 v[20:23], v[108:111], v[172:175], v[20:23]
	v_mfma_f32_16x16x32_bf16 v[88:91], v[176:179], v[124:127], 0
	v_mfma_f32_16x16x32_bf16 v[24:27], v[184:187], v[124:127], 0
	v_mfma_f32_16x16x32_bf16 v[68:71], v[176:179], v[132:135], 0
	v_mfma_f32_16x16x32_bf16 v[4:7], v[184:187], v[132:135], 0
	v_mfma_f32_16x16x32_bf16 v[64:67], v[176:179], v[160:163], 0
	v_mfma_f32_16x16x32_bf16 v[0:3], v[184:187], v[160:163], 0
	v_mfma_f32_16x16x32_bf16 v[72:75], v[176:179], v[168:171], 0
	v_mfma_f32_16x16x32_bf16 v[8:11], v[184:187], v[168:171], 0
	v_mfma_f32_16x16x32_bf16 v[88:91], v[180:183], v[128:131], v[88:91]
	v_mfma_f32_16x16x32_bf16 v[24:27], v[188:191], v[128:131], v[24:27]
	v_mfma_f32_16x16x32_bf16 v[68:71], v[180:183], v[140:143], v[68:71]
	v_mfma_f32_16x16x32_bf16 v[4:7], v[188:191], v[140:143], v[4:7]
	v_mfma_f32_16x16x32_bf16 v[64:67], v[180:183], v[164:167], v[64:67]
	v_mfma_f32_16x16x32_bf16 v[0:3], v[188:191], v[164:167], v[0:3]
	v_mfma_f32_16x16x32_bf16 v[72:75], v[180:183], v[172:175], v[72:75]
	v_mfma_f32_16x16x32_bf16 v[8:11], v[188:191], v[172:175], v[8:11]
	s_setprio 0
	s_add_i32 s73, 0, 0x18000
	v_add_u32_e32 v108, s73, v234
	s_barrier
	ds_read_b128 v[96:99], v108
	ds_read_b128 v[100:103], v108 offset:1024
	ds_read_b128 v[104:107], v108 offset:2048
	ds_read_b128 v[108:111], v108 offset:3072
	s_add_u32 s36, s42, 0x40000
	s_addc_u32 s37, s43, 0
	s_mov_b32 m0, s47
	ds_read_b128 v[124:127], v243 offset:32768
	ds_read_b128 v[128:131], v243 offset:33792
	ds_read_b128 v[140:143], v243 offset:34816
	ds_read_b128 v[160:163], v243 offset:35840
	ds_read_b128 v[164:167], v243 offset:36864
	ds_read_b128 v[168:171], v243 offset:37888
	ds_read_b128 v[172:175], v243 offset:38912
	ds_read_b128 v[176:179], v243 offset:39936
	global_load_lds_dwordx4 v216, s[36:37]
	v_lshl_add_u64 v[132:133], s[36:37], 0, v[212:213]
	s_mov_b32 m0, s48
	s_nop 0
	global_load_lds_dwordx4 v212, s[36:37]
	s_add_i32 s42, 0, 0x1c000
	v_add_u32_e32 v132, s42, v234
	ds_read_b128 v[180:183], v132
	ds_read_b128 v[184:187], v132 offset:1024
	ds_read_b128 v[188:191], v132 offset:2048
	ds_read_b128 v[192:195], v132 offset:3072
	s_waitcnt lgkmcnt(0)
	s_barrier
	s_setprio 1
	v_mfma_f32_16x16x32_bf16 v[132:135], v[96:99], v[124:127], v[156:159]
	v_mfma_f32_16x16x32_bf16 v[156:159], v[100:103], v[128:131], v[132:135]
	v_mfma_f32_16x16x32_bf16 v[132:135], v[96:99], v[140:143], v[144:147]
	v_mfma_f32_16x16x32_bf16 v[144:147], v[100:103], v[160:163], v[132:135]
	v_mfma_f32_16x16x32_bf16 v[132:135], v[96:99], v[164:167], v[136:139]
	v_mfma_f32_16x16x32_bf16 v[60:63], v[104:107], v[124:127], v[60:63]
	v_mfma_f32_16x16x32_bf16 v[48:51], v[104:107], v[140:143], v[48:51]
	v_mfma_f32_16x16x32_bf16 v[136:139], v[100:103], v[168:171], v[132:135]
	v_mfma_f32_16x16x32_bf16 v[40:43], v[104:107], v[164:167], v[40:43]
	v_mfma_f32_16x16x32_bf16 v[132:135], v[96:99], v[172:175], v[148:151]
	v_mfma_f32_16x16x32_bf16 v[52:55], v[104:107], v[172:175], v[52:55]
	v_mfma_f32_16x16x32_bf16 v[60:63], v[108:111], v[128:131], v[60:63]
	v_mfma_f32_16x16x32_bf16 v[48:51], v[108:111], v[160:163], v[48:51]
	v_mfma_f32_16x16x32_bf16 v[40:43], v[108:111], v[168:171], v[40:43]
	v_mfma_f32_16x16x32_bf16 v[148:151], v[100:103], v[176:179], v[132:135]
	v_mfma_f32_16x16x32_bf16 v[52:55], v[108:111], v[176:179], v[52:55]
	v_mfma_f32_16x16x32_bf16 v[132:135], v[180:183], v[124:127], v[152:155]
	v_mfma_f32_16x16x32_bf16 v[112:115], v[180:183], v[140:143], v[112:115]
	v_mfma_f32_16x16x32_bf16 v[152:155], v[184:187], v[128:131], v[132:135]
	v_mfma_f32_16x16x32_bf16 v[56:59], v[188:191], v[124:127], v[56:59]
	v_mfma_f32_16x16x32_bf16 v[132:135], v[184:187], v[160:163], v[112:115]
	v_mfma_f32_16x16x32_bf16 v[112:115], v[180:183], v[164:167], v[116:119]
	v_mfma_f32_16x16x32_bf16 v[56:59], v[192:195], v[128:131], v[56:59]
	v_mfma_f32_16x16x32_bf16 v[36:39], v[188:191], v[140:143], v[36:39]
	v_mfma_f32_16x16x32_bf16 v[128:131], v[184:187], v[168:171], v[112:115]
	v_mfma_f32_16x16x32_bf16 v[32:35], v[188:191], v[164:167], v[32:35]
	v_mfma_f32_16x16x32_bf16 v[112:115], v[180:183], v[172:175], v[120:123]
	v_mfma_f32_16x16x32_bf16 v[44:47], v[188:191], v[172:175], v[44:47]
	v_mfma_f32_16x16x32_bf16 v[36:39], v[192:195], v[160:163], v[36:39]
	v_mfma_f32_16x16x32_bf16 v[32:35], v[192:195], v[168:171], v[32:35]
	v_mfma_f32_16x16x32_bf16 v[140:143], v[184:187], v[176:179], v[112:115]
	v_mfma_f32_16x16x32_bf16 v[44:47], v[192:195], v[176:179], v[44:47]
	s_setprio 0
	s_barrier
; #define PG8_STAGE(bufoff, gbase, voff) do { _Pragma("unroll") for (int _i = 0; _i < 2; ++_i) \
;         __builtin_amdgcn_global_load_lds((const unsigned*)((const char*)(gbase) + (voff)[_i]), (LAS unsigned*)(lds + (bufoff) + ldsw + _i * 8192), 16, 0, 0); } while (0)
; #define PG8_LDA(dst, b, h) do { _Pragma("unroll") for (int m = 0; m < 4; ++m) _Pragma("unroll") for (int k = 0; k < 2; ++k) dst[m][k] = *(const LAS bf16x8*)(lds + PG8_SA(b, h) + aoff + m * 2048 + k * 1024); } while (0)
; #define PG8_LDB(dst, b, h) do { _Pragma("unroll") for (int n = 0; n < 2; ++n) _Pragma("unroll") for (int k = 0; k < 2; ++k) dst[n][k] = *(const LAS bf16x8*)(lds + PG8_SB(b, h) + boff + n * 2048 + k * 1024); } while (0)
; #define PG8_WAIT_V(n) asm volatile("s_waitcnt vmcnt(" #n ")" ::: "memory")
; #define PG8_BAR __builtin_amdgcn_s_barrier()
; template <class Epi>
; __device__ __forceinline__ void gemm_phase(LAS unsigned char* lds, const Gemm g, const StaticOrder& S, const Epi& E) {
;     ...
;         for (int t = 0; t < nt; t += 2) {
;             const bool last = (t == nt - 2);
;             const char* a1 = cA + (size_t)(t + 1) * kstep;
;             const char* a2 = last ? nA : cA + (size_t)(t + 2) * kstep; const char* b2 = last ? nB : cB + (size_t)(t + 2) * kstep;
;             const char* a3 = a2 + kstep; const char* b3 = b2 + kstep;
;             PG8_LDB(B0, 0, 0); PG8_SCHED; PG8_LDA(At, 0, 0); PG8_STAGE(PG8_SA(1, 1), a1 + hstepA, voffA);
;             PG8_WAIT_L(8); PG8_BAR; PG8_WAIT_L(0); PG8_MMA(0, 0, At, B0); PG8_BAR; PG8_SCHED;
;     ...
;             PG8_BAR; PG8_WAIT_L(0); PG8_MMA(1, 0, At, B0); PG8_BAR; PG8_SCHED;
;             PG8_STAGE(PG8_SB(0, 1), b2 + hstepB, voffB);
;             PG8_WAIT_V(6); PG8_BAR; PG8_MMA(1, 1, At, B1); PG8_BAR;
;             PG8_LDB(B0, 1, 0); PG8_SCHED; PG8_LDA(At, 1, 0); PG8_STAGE(PG8_SA(0, 1), a2 + hstepA, voffA);
;             PG8_WAIT_L(8); PG8_BAR; PG8_WAIT_L(0); PG8_MMA(0, 0, At, B0); PG8_BAR; PG8_SCHED;
;             PG8_LDB(B1, 1, 1); PG8_STAGE(PG8_SB(1, 0), b3, voffB);
;             PG8_BAR; PG8_WAIT_L(0); PG8_MMA(0, 1, At, B1); PG8_BAR;
;             PG8_LDA(At, 1, 1); PG8_STAGE(PG8_SA(1, 0), a3, voffA);
;             PG8_BAR; PG8_WAIT_L(0); PG8_MMA(1, 0, At, B0); PG8_BAR; PG8_SCHED;
;             PG8_STAGE(PG8_SB(1, 1), b3 + hstepB, voffB);
;             PG8_WAIT_V(6); PG8_BAR; PG8_MMA(1, 1, At, B1); PG8_BAR;
	s_nop 1
	ds_read_b128 v[112:115], v243 offset:49152
	ds_read_b128 v[116:119], v243 offset:50176
	ds_read_b128 v[120:123], v243 offset:51200
	ds_read_b128 v[124:127], v243 offset:52224
	ds_read_b128 v[160:163], v243 offset:53248
	ds_read_b128 v[164:167], v243 offset:54272
	ds_read_b128 v[168:171], v243 offset:55296
	ds_read_b128 v[172:175], v243 offset:56320
	s_add_i32 s36, s73, s7
	s_mov_b32 m0, s36
	s_nop 0
	s_add_u32 s100, s40, s16
	s_addc_u32 s101, s41, s17
	global_load_lds_dwordx4 v214, s[100:101]
	s_add_i32 m0, s36, 0x2000
	s_nop 0
	s_add_u32 s100, s40, s16
	s_addc_u32 s101, s41, s17
	global_load_lds_dwordx4 v210, s[100:101]
	s_mov_b32 m0, s57
	v_lshl_add_u64 v[254:255], v[200:201], 0, s[16:17]
	global_load_lds_dwordx4 v[254:255], off
	v_lshl_add_u64 v[254:255], v[202:203], 0, s[16:17]
	s_mov_b32 m0, s58
	s_nop 0
	global_load_lds_dwordx4 v[254:255], off
	s_add_u32 s36, s40, 0x40080
	s_addc_u32 s37, s41, 0
	s_add_i32 s40, s42, s7
	s_mov_b32 m0, s40
	s_nop 0
	global_load_lds_dwordx4 v214, s[36:37]
	s_add_i32 m0, s40, 0x2000
	s_nop 0
	global_load_lds_dwordx4 v210, s[36:37]
	s_waitcnt vmcnt(6)
	s_waitcnt lgkmcnt(0)
	s_barrier
	s_setprio 1
	v_mfma_f32_16x16x32_bf16 v[92:95], v[96:99], v[112:115], v[92:95]
	v_mfma_f32_16x16x32_bf16 v[28:31], v[104:107], v[112:115], v[28:31]
	v_mfma_f32_16x16x32_bf16 v[80:83], v[96:99], v[120:123], v[80:83]
	v_mfma_f32_16x16x32_bf16 v[16:19], v[104:107], v[120:123], v[16:19]
	v_mfma_f32_16x16x32_bf16 v[76:79], v[96:99], v[160:163], v[76:79]
	v_mfma_f32_16x16x32_bf16 v[12:15], v[104:107], v[160:163], v[12:15]
	v_mfma_f32_16x16x32_bf16 v[84:87], v[96:99], v[168:171], v[84:87]
	v_mfma_f32_16x16x32_bf16 v[20:23], v[104:107], v[168:171], v[20:23]
	v_mfma_f32_16x16x32_bf16 v[92:95], v[100:103], v[116:119], v[92:95]
	v_mfma_f32_16x16x32_bf16 v[28:31], v[108:111], v[116:119], v[28:31]
	v_mfma_f32_16x16x32_bf16 v[80:83], v[100:103], v[124:127], v[80:83]
	v_mfma_f32_16x16x32_bf16 v[16:19], v[108:111], v[124:127], v[16:19]
	v_mfma_f32_16x16x32_bf16 v[76:79], v[100:103], v[164:167], v[76:79]
	v_mfma_f32_16x16x32_bf16 v[12:15], v[108:111], v[164:167], v[12:15]
	v_mfma_f32_16x16x32_bf16 v[84:87], v[100:103], v[172:175], v[84:87]
	v_mfma_f32_16x16x32_bf16 v[20:23], v[108:111], v[172:175], v[20:23]
	v_mfma_f32_16x16x32_bf16 v[88:91], v[180:183], v[112:115], v[88:91]
	v_mfma_f32_16x16x32_bf16 v[24:27], v[188:191], v[112:115], v[24:27]
	v_mfma_f32_16x16x32_bf16 v[68:71], v[180:183], v[120:123], v[68:71]
	v_mfma_f32_16x16x32_bf16 v[4:7], v[188:191], v[120:123], v[4:7]
	v_mfma_f32_16x16x32_bf16 v[64:67], v[180:183], v[160:163], v[64:67]
	v_mfma_f32_16x16x32_bf16 v[0:3], v[188:191], v[160:163], v[0:3]
	v_mfma_f32_16x16x32_bf16 v[72:75], v[180:183], v[168:171], v[72:75]
	v_mfma_f32_16x16x32_bf16 v[8:11], v[188:191], v[168:171], v[8:11]
	v_mfma_f32_16x16x32_bf16 v[88:91], v[184:187], v[116:119], v[88:91]
	v_mfma_f32_16x16x32_bf16 v[24:27], v[192:195], v[116:119], v[24:27]
	v_mfma_f32_16x16x32_bf16 v[68:71], v[184:187], v[124:127], v[68:71]
	v_mfma_f32_16x16x32_bf16 v[4:7], v[192:195], v[124:127], v[4:7]
	v_mfma_f32_16x16x32_bf16 v[64:67], v[184:187], v[164:167], v[64:67]
	v_mfma_f32_16x16x32_bf16 v[0:3], v[192:195], v[164:167], v[0:3]
	v_mfma_f32_16x16x32_bf16 v[72:75], v[184:187], v[172:175], v[72:75]
	v_mfma_f32_16x16x32_bf16 v[8:11], v[192:195], v[172:175], v[8:11]
	s_setprio 0
	s_add_i32 s72, s72, 2
	s_add_u32 s70, s70, 0x100
	s_addc_u32 s71, s71, 0
	s_cmp_gt_u32 s72, 13
	s_mov_b64 s[36:37], s[38:39]
	s_barrier
.LBB0_1940:
	ds_read_b128 v[96:99], v242
	ds_read_b128 v[100:103], v242 offset:1024
	ds_read_b128 v[104:107], v242 offset:2048
	ds_read_b128 v[108:111], v242 offset:3072
	s_add_u32 s38, s36, 0x100
	s_addc_u32 s39, s37, 0
	s_cmp_eq_u32 s72, 12
	s_cselect_b32 s43, s27, s39
	s_cselect_b32 s42, s68, s38
	s_cselect_b32 s41, s25, s71
	s_cselect_b32 s40, s69, s70
	s_add_i32 m0, s45, 0xc000
	ds_read_b128 v[112:115], v243
	ds_read_b128 v[116:119], v243 offset:1024
	ds_read_b128 v[120:123], v243 offset:2048
	ds_read_b128 v[124:127], v243 offset:3072
	ds_read_b128 v[160:163], v243 offset:4096
	ds_read_b128 v[164:167], v243 offset:5120
	ds_read_b128 v[168:171], v243 offset:6144
	ds_read_b128 v[172:175], v243 offset:7168
	global_load_lds_dwordx4 v224, s[36:37]
	s_add_i32 m0, s45, 0xe000
	s_nop 0
	global_load_lds_dwordx4 v226, s[36:37]
	ds_read_b128 v[176:179], v244
	ds_read_b128 v[180:183], v244 offset:1024
	ds_read_b128 v[184:187], v244 offset:2048
	ds_read_b128 v[188:191], v244 offset:3072
	s_waitcnt lgkmcnt(0)
	s_barrier
; #define PG8_STAGE(bufoff, gbase, voff) do { _Pragma("unroll") for (int _i = 0; _i < 2; ++_i) \
;         __builtin_amdgcn_global_load_lds((const unsigned*)((const char*)(gbase) + (voff)[_i]), (LAS unsigned*)(lds + (bufoff) + ldsw + _i * 8192), 16, 0, 0); } while (0)
; #define PG8_LDA(dst, b, h) do { _Pragma("unroll") for (int m = 0; m < 4; ++m) _Pragma("unroll") for (int k = 0; k < 2; ++k) dst[m][k] = *(const LAS bf16x8*)(lds + PG8_SA(b, h) + aoff + m * 2048 + k * 1024); } while (0)
; #define PG8_WAIT_V(n) asm volatile("s_waitcnt vmcnt(" #n ")" ::: "memory")
; #define PG8_WAIT_L(n) asm volatile("s_waitcnt lgkmcnt(" #n ")" ::: "memory")
; template <class Epi>
; __device__ __forceinline__ void gemm_phase(LAS unsigned char* lds, const Gemm g, const StaticOrder& S, const Epi& E) {
;     ...
;         for (int t = 0; t < nt; t += 2) {
;             const bool last = (t == nt - 2);
;             const char* a1 = cA + (size_t)(t + 1) * kstep;
;             const char* a2 = last ? nA : cA + (size_t)(t + 2) * kstep; const char* b2 = last ? nB : cB + (size_t)(t + 2) * kstep;
;             const char* a3 = a2 + kstep; const char* b3 = b2 + kstep;
;             PG8_LDB(B0, 0, 0); PG8_SCHED; PG8_LDA(At, 0, 0); PG8_STAGE(PG8_SA(1, 1), a1 + hstepA, voffA);
;             PG8_WAIT_L(8); PG8_BAR; PG8_WAIT_L(0); PG8_MMA(0, 0, At, B0); PG8_BAR; PG8_SCHED;
;             PG8_LDB(B1, 0, 1); PG8_STAGE(PG8_SB(0, 0), b2, voffB);
;             PG8_BAR; PG8_WAIT_L(0); PG8_MMA(0, 1, At, B1); PG8_BAR;
;             PG8_LDA(At, 0, 1); PG8_STAGE(PG8_SA(0, 0), a2, voffA);
;             PG8_BAR; PG8_WAIT_L(0); PG8_MMA(1, 0, At, B0); PG8_BAR; PG8_SCHED;
;             PG8_STAGE(PG8_SB(0, 1), b2 + hstepB, voffB);
;             PG8_WAIT_V(6); PG8_BAR; PG8_MMA(1, 1, At, B1); PG8_BAR;
;             PG8_LDB(B0, 1, 0); PG8_SCHED; PG8_LDA(At, 1, 0); PG8_STAGE(PG8_SA(0, 1), a2 + hstepA, voffA);
;             PG8_WAIT_L(8); PG8_BAR; PG8_WAIT_L(0); PG8_MMA(0, 0, At, B0); PG8_BAR; PG8_SCHED;
;             PG8_LDB(B1, 1, 1); PG8_STAGE(PG8_SB(1, 0), b3, voffB);
;             PG8_BAR; PG8_WAIT_L(0); PG8_MMA(0, 1, At, B1); PG8_BAR;
;             PG8_LDA(At, 1, 1); PG8_STAGE(PG8_SA(1, 0), a3, voffA);
;             PG8_BAR; PG8_WAIT_L(0); PG8_MMA(1, 0, At, B0); PG8_BAR; PG8_SCHED;
;             PG8_STAGE(PG8_SB(1, 1), b3 + hstepB, voffB);
;             PG8_WAIT_V(6); PG8_BAR; PG8_MMA(1, 1, At, B1); PG8_BAR;
	s_setprio 1
	v_mfma_f32_16x16x32_bf16 v[156:159], v[96:99], v[112:115], v[156:159]
	v_mfma_f32_16x16x32_bf16 v[60:63], v[104:107], v[112:115], v[60:63]
	v_mfma_f32_16x16x32_bf16 v[144:147], v[96:99], v[120:123], v[144:147]
	v_mfma_f32_16x16x32_bf16 v[48:51], v[104:107], v[120:123], v[48:51]
	v_mfma_f32_16x16x32_bf16 v[136:139], v[96:99], v[160:163], v[136:139]
	v_mfma_f32_16x16x32_bf16 v[40:43], v[104:107], v[160:163], v[40:43]
	v_mfma_f32_16x16x32_bf16 v[148:151], v[96:99], v[168:171], v[148:151]
	v_mfma_f32_16x16x32_bf16 v[52:55], v[104:107], v[168:171], v[52:55]
	v_mfma_f32_16x16x32_bf16 v[156:159], v[100:103], v[116:119], v[156:159]
	v_mfma_f32_16x16x32_bf16 v[60:63], v[108:111], v[116:119], v[60:63]
	v_mfma_f32_16x16x32_bf16 v[144:147], v[100:103], v[124:127], v[144:147]
	v_mfma_f32_16x16x32_bf16 v[48:51], v[108:111], v[124:127], v[48:51]
	v_mfma_f32_16x16x32_bf16 v[136:139], v[100:103], v[164:167], v[136:139]
	v_mfma_f32_16x16x32_bf16 v[40:43], v[108:111], v[164:167], v[40:43]
	v_mfma_f32_16x16x32_bf16 v[148:151], v[100:103], v[172:175], v[148:151]
	v_mfma_f32_16x16x32_bf16 v[52:55], v[108:111], v[172:175], v[52:55]
	v_mfma_f32_16x16x32_bf16 v[152:155], v[176:179], v[112:115], v[152:155]
	v_mfma_f32_16x16x32_bf16 v[56:59], v[184:187], v[112:115], v[56:59]
	v_mfma_f32_16x16x32_bf16 v[36:39], v[184:187], v[120:123], v[36:39]
	v_mfma_f32_16x16x32_bf16 v[32:35], v[184:187], v[160:163], v[32:35]
	v_mfma_f32_16x16x32_bf16 v[44:47], v[184:187], v[168:171], v[44:47]
	v_mfma_f32_16x16x32_bf16 v[152:155], v[180:183], v[116:119], v[152:155]
	v_mfma_f32_16x16x32_bf16 v[56:59], v[188:191], v[116:119], v[56:59]
	v_mfma_f32_16x16x32_bf16 v[112:115], v[176:179], v[120:123], v[132:135]
	v_mfma_f32_16x16x32_bf16 v[36:39], v[188:191], v[124:127], v[36:39]
	v_mfma_f32_16x16x32_bf16 v[116:119], v[176:179], v[160:163], v[128:131]
	v_mfma_f32_16x16x32_bf16 v[32:35], v[188:191], v[164:167], v[32:35]
	v_mfma_f32_16x16x32_bf16 v[120:123], v[176:179], v[168:171], v[140:143]
	v_mfma_f32_16x16x32_bf16 v[44:47], v[188:191], v[172:175], v[44:47]
	v_mfma_f32_16x16x32_bf16 v[112:115], v[180:183], v[124:127], v[112:115]
	v_mfma_f32_16x16x32_bf16 v[116:119], v[180:183], v[164:167], v[116:119]
	v_mfma_f32_16x16x32_bf16 v[120:123], v[180:183], v[172:175], v[120:123]
	s_setprio 0
	s_barrier
	s_nop 1
	ds_read_b128 v[124:127], v243 offset:16384
	ds_read_b128 v[128:131], v243 offset:17408
	ds_read_b128 v[132:135], v243 offset:18432
	ds_read_b128 v[140:143], v243 offset:19456
	ds_read_b128 v[160:163], v243 offset:20480
	ds_read_b128 v[164:167], v243 offset:21504
	ds_read_b128 v[168:171], v243 offset:22528
	ds_read_b128 v[172:175], v243 offset:23552
	s_add_i32 s36, s59, s7
	v_lshl_add_u64 v[196:197], s[40:41], 0, v[214:215]
	s_mov_b32 m0, s36
	s_nop 0
	global_load_lds_dwordx4 v214, s[40:41]
	v_lshl_add_u64 v[198:199], s[40:41], 0, v[210:211]
	s_add_i32 m0, s36, 0x2000
	s_nop 0
	global_load_lds_dwordx4 v210, s[40:41]
	s_mov_b32 m0, s45
	v_lshl_add_u64 v[200:201], s[42:43], 0, v[216:217]
	global_load_lds_dwordx4 v216, s[42:43]
	v_lshl_add_u64 v[202:203], s[42:43], 0, v[212:213]
	s_mov_b32 m0, s46
	s_nop 0
	global_load_lds_dwordx4 v212, s[42:43]
	s_add_u32 s36, s40, 0x40000
	s_addc_u32 s37, s41, 0
	s_add_i32 s73, s62, s7
	s_mov_b32 m0, s73
	s_nop 0
	global_load_lds_dwordx4 v214, s[36:37]
	s_add_i32 m0, s73, 0x2000
	s_nop 0
	global_load_lds_dwordx4 v210, s[36:37]
	s_waitcnt vmcnt(6)
	s_waitcnt lgkmcnt(0)
	s_barrier
	s_setprio 1
	v_mfma_f32_16x16x32_bf16 v[92:95], v[96:99], v[124:127], v[92:95]
	v_mfma_f32_16x16x32_bf16 v[28:31], v[104:107], v[124:127], v[28:31]
	v_mfma_f32_16x16x32_bf16 v[80:83], v[96:99], v[132:135], v[80:83]
	v_mfma_f32_16x16x32_bf16 v[16:19], v[104:107], v[132:135], v[16:19]
	v_mfma_f32_16x16x32_bf16 v[76:79], v[96:99], v[160:163], v[76:79]
	v_mfma_f32_16x16x32_bf16 v[12:15], v[104:107], v[160:163], v[12:15]
	v_mfma_f32_16x16x32_bf16 v[84:87], v[96:99], v[168:171], v[84:87]
	v_mfma_f32_16x16x32_bf16 v[20:23], v[104:107], v[168:171], v[20:23]
	v_mfma_f32_16x16x32_bf16 v[92:95], v[100:103], v[128:131], v[92:95]
	v_mfma_f32_16x16x32_bf16 v[28:31], v[108:111], v[128:131], v[28:31]
	v_mfma_f32_16x16x32_bf16 v[80:83], v[100:103], v[140:143], v[80:83]
	v_mfma_f32_16x16x32_bf16 v[16:19], v[108:111], v[140:143], v[16:19]
	v_mfma_f32_16x16x32_bf16 v[76:79], v[100:103], v[164:167], v[76:79]
	v_mfma_f32_16x16x32_bf16 v[12:15], v[108:111], v[164:167], v[12:15]
	v_mfma_f32_16x16x32_bf16 v[84:87], v[100:103], v[172:175], v[84:87]
	v_mfma_f32_16x16x32_bf16 v[20:23], v[108:111], v[172:175], v[20:23]
	v_mfma_f32_16x16x32_bf16 v[88:91], v[176:179], v[124:127], v[88:91]
	v_mfma_f32_16x16x32_bf16 v[24:27], v[184:187], v[124:127], v[24:27]
	v_mfma_f32_16x16x32_bf16 v[68:71], v[176:179], v[132:135], v[68:71]
	v_mfma_f32_16x16x32_bf16 v[4:7], v[184:187], v[132:135], v[4:7]
	v_mfma_f32_16x16x32_bf16 v[64:67], v[176:179], v[160:163], v[64:67]
	v_mfma_f32_16x16x32_bf16 v[0:3], v[184:187], v[160:163], v[0:3]
	v_mfma_f32_16x16x32_bf16 v[72:75], v[176:179], v[168:171], v[72:75]
	v_mfma_f32_16x16x32_bf16 v[8:11], v[184:187], v[168:171], v[8:11]
	v_mfma_f32_16x16x32_bf16 v[88:91], v[180:183], v[128:131], v[88:91]
	v_mfma_f32_16x16x32_bf16 v[24:27], v[188:191], v[128:131], v[24:27]
	v_mfma_f32_16x16x32_bf16 v[68:71], v[180:183], v[140:143], v[68:71]
	v_mfma_f32_16x16x32_bf16 v[4:7], v[188:191], v[140:143], v[4:7]
	v_mfma_f32_16x16x32_bf16 v[64:67], v[180:183], v[164:167], v[64:67]
	v_mfma_f32_16x16x32_bf16 v[0:3], v[188:191], v[164:167], v[0:3]
	v_mfma_f32_16x16x32_bf16 v[72:75], v[180:183], v[172:175], v[72:75]
	v_mfma_f32_16x16x32_bf16 v[8:11], v[188:191], v[172:175], v[8:11]
	s_setprio 0
	s_add_i32 s73, 0, 0x18000
	v_add_u32_e32 v108, s73, v234
	s_barrier
; #define PG8_STAGE(bufoff, gbase, voff) do { _Pragma("unroll") for (int _i = 0; _i < 2; ++_i) \
;         __builtin_amdgcn_global_load_lds((const unsigned*)((const char*)(gbase) + (voff)[_i]), (LAS unsigned*)(lds + (bufoff) + ldsw + _i * 8192), 16, 0, 0); } while (0)
; #define PG8_LDA(dst, b, h) do { _Pragma("unroll") for (int m = 0; m < 4; ++m) _Pragma("unroll") for (int k = 0; k < 2; ++k) dst[m][k] = *(const LAS bf16x8*)(lds + PG8_SA(b, h) + aoff + m * 2048 + k * 1024); } while (0)
; #define PG8_LDB(dst, b, h) do { _Pragma("unroll") for (int n = 0; n < 2; ++n) _Pragma("unroll") for (int k = 0; k < 2; ++k) dst[n][k] = *(const LAS bf16x8*)(lds + PG8_SB(b, h) + boff + n * 2048 + k * 1024); } while (0)
; #define PG8_WAIT_V(n) asm volatile("s_waitcnt vmcnt(" #n ")" ::: "memory")
; #define PG8_WAIT_L(n) asm volatile("s_waitcnt lgkmcnt(" #n ")" ::: "memory")
; #define PG8_BAR __builtin_amdgcn_s_barrier()
; #define PG8_SCHED __builtin_amdgcn_sched_barrier(0)
; template <class Epi>
; __device__ __forceinline__ void gemm_phase(LAS unsigned char* lds, const Gemm g, const StaticOrder& S, const Epi& E) {
;     ...
;             PG8_LDB(B0, 0, 0); PG8_SCHED; PG8_LDA(At, 0, 0); PG8_STAGE(PG8_SA(1, 1), a1 + hstepA, voffA);
;             PG8_WAIT_L(8); PG8_BAR; PG8_WAIT_L(0); PG8_MMA(0, 0, At, B0); PG8_BAR; PG8_SCHED;
;             PG8_LDB(B1, 0, 1); PG8_STAGE(PG8_SB(0, 0), b2, voffB);
;             PG8_BAR; PG8_WAIT_L(0); PG8_MMA(0, 1, At, B1); PG8_BAR;
;             PG8_LDA(At, 0, 1); PG8_STAGE(PG8_SA(0, 0), a2, voffA);
;             PG8_BAR; PG8_WAIT_L(0); PG8_MMA(1, 0, At, B0); PG8_BAR; PG8_SCHED;
;             PG8_STAGE(PG8_SB(0, 1), b2 + hstepB, voffB);
;             PG8_WAIT_V(6); PG8_BAR; PG8_MMA(1, 1, At, B1); PG8_BAR;
;             PG8_LDB(B0, 1, 0); PG8_SCHED; PG8_LDA(At, 1, 0); PG8_STAGE(PG8_SA(0, 1), a2 + hstepA, voffA);
;             PG8_WAIT_L(8); PG8_BAR; PG8_WAIT_L(0); PG8_MMA(0, 0, At, B0); PG8_BAR; PG8_SCHED;
;             PG8_LDB(B1, 1, 1); PG8_STAGE(PG8_SB(1, 0), b3, voffB);
;             PG8_BAR; PG8_WAIT_L(0); PG8_MMA(0, 1, At, B1); PG8_BAR;
;             PG8_LDA(At, 1, 1); PG8_STAGE(PG8_SA(1, 0), a3, voffA);
;             PG8_BAR; PG8_WAIT_L(0); PG8_MMA(1, 0, At, B0); PG8_BAR; PG8_SCHED;
;             PG8_STAGE(PG8_SB(1, 1), b3 + hstepB, voffB);
;             PG8_WAIT_V(6); PG8_BAR; PG8_MMA(1, 1, At, B1); PG8_BAR;
	ds_read_b128 v[96:99], v108
	ds_read_b128 v[100:103], v108 offset:1024
	ds_read_b128 v[104:107], v108 offset:2048
	ds_read_b128 v[108:111], v108 offset:3072
	s_add_u32 s36, s42, 0x40000
	s_addc_u32 s37, s43, 0
	s_mov_b32 m0, s47
	ds_read_b128 v[124:127], v243 offset:32768
	ds_read_b128 v[128:131], v243 offset:33792
	ds_read_b128 v[140:143], v243 offset:34816
	ds_read_b128 v[160:163], v243 offset:35840
	ds_read_b128 v[164:167], v243 offset:36864
	ds_read_b128 v[168:171], v243 offset:37888
	ds_read_b128 v[172:175], v243 offset:38912
	ds_read_b128 v[176:179], v243 offset:39936
	global_load_lds_dwordx4 v216, s[36:37]
	v_lshl_add_u64 v[132:133], s[36:37], 0, v[212:213]
	s_mov_b32 m0, s48
	s_nop 0
	global_load_lds_dwordx4 v212, s[36:37]
	s_add_i32 s42, 0, 0x1c000
	v_add_u32_e32 v132, s42, v234
	ds_read_b128 v[180:183], v132
	ds_read_b128 v[184:187], v132 offset:1024
	ds_read_b128 v[188:191], v132 offset:2048
	ds_read_b128 v[192:195], v132 offset:3072
	s_waitcnt lgkmcnt(0)
	s_barrier
	s_setprio 1
	v_mfma_f32_16x16x32_bf16 v[132:135], v[96:99], v[124:127], v[156:159]
	v_mfma_f32_16x16x32_bf16 v[156:159], v[100:103], v[128:131], v[132:135]
	v_mfma_f32_16x16x32_bf16 v[132:135], v[96:99], v[140:143], v[144:147]
	v_mfma_f32_16x16x32_bf16 v[144:147], v[100:103], v[160:163], v[132:135]
	v_mfma_f32_16x16x32_bf16 v[132:135], v[96:99], v[164:167], v[136:139]
	v_mfma_f32_16x16x32_bf16 v[60:63], v[104:107], v[124:127], v[60:63]
	v_mfma_f32_16x16x32_bf16 v[48:51], v[104:107], v[140:143], v[48:51]
	v_mfma_f32_16x16x32_bf16 v[136:139], v[100:103], v[168:171], v[132:135]
	v_mfma_f32_16x16x32_bf16 v[40:43], v[104:107], v[164:167], v[40:43]
	v_mfma_f32_16x16x32_bf16 v[132:135], v[96:99], v[172:175], v[148:151]
	v_mfma_f32_16x16x32_bf16 v[52:55], v[104:107], v[172:175], v[52:55]
	v_mfma_f32_16x16x32_bf16 v[60:63], v[108:111], v[128:131], v[60:63]
	v_mfma_f32_16x16x32_bf16 v[48:51], v[108:111], v[160:163], v[48:51]
	v_mfma_f32_16x16x32_bf16 v[40:43], v[108:111], v[168:171], v[40:43]
	v_mfma_f32_16x16x32_bf16 v[148:151], v[100:103], v[176:179], v[132:135]
	v_mfma_f32_16x16x32_bf16 v[52:55], v[108:111], v[176:179], v[52:55]
	v_mfma_f32_16x16x32_bf16 v[132:135], v[180:183], v[124:127], v[152:155]
	v_mfma_f32_16x16x32_bf16 v[112:115], v[180:183], v[140:143], v[112:115]
	v_mfma_f32_16x16x32_bf16 v[152:155], v[184:187], v[128:131], v[132:135]
	v_mfma_f32_16x16x32_bf16 v[56:59], v[188:191], v[124:127], v[56:59]
	v_mfma_f32_16x16x32_bf16 v[132:135], v[184:187], v[160:163], v[112:115]
	v_mfma_f32_16x16x32_bf16 v[112:115], v[180:183], v[164:167], v[116:119]
	v_mfma_f32_16x16x32_bf16 v[56:59], v[192:195], v[128:131], v[56:59]
	v_mfma_f32_16x16x32_bf16 v[36:39], v[188:191], v[140:143], v[36:39]
	v_mfma_f32_16x16x32_bf16 v[128:131], v[184:187], v[168:171], v[112:115]
	v_mfma_f32_16x16x32_bf16 v[32:35], v[188:191], v[164:167], v[32:35]
	v_mfma_f32_16x16x32_bf16 v[112:115], v[180:183], v[172:175], v[120:123]
	v_mfma_f32_16x16x32_bf16 v[44:47], v[188:191], v[172:175], v[44:47]
	v_mfma_f32_16x16x32_bf16 v[36:39], v[192:195], v[160:163], v[36:39]
	v_mfma_f32_16x16x32_bf16 v[32:35], v[192:195], v[168:171], v[32:35]
	v_mfma_f32_16x16x32_bf16 v[140:143], v[184:187], v[176:179], v[112:115]
	v_mfma_f32_16x16x32_bf16 v[44:47], v[192:195], v[176:179], v[44:47]
	s_setprio 0
	s_barrier
	s_nop 1
	ds_read_b128 v[112:115], v243 offset:49152
	ds_read_b128 v[116:119], v243 offset:50176
	ds_read_b128 v[120:123], v243 offset:51200
	ds_read_b128 v[124:127], v243 offset:52224
	ds_read_b128 v[160:163], v243 offset:53248
	ds_read_b128 v[164:167], v243 offset:54272
	ds_read_b128 v[168:171], v243 offset:55296
	ds_read_b128 v[172:175], v243 offset:56320
	s_add_i32 s36, s73, s7
	s_mov_b32 m0, s36
	s_nop 0
	s_add_u32 s100, s40, s16
	s_addc_u32 s101, s41, s17
	global_load_lds_dwordx4 v214, s[100:101]
	s_add_i32 m0, s36, 0x2000
	s_nop 0
	s_add_u32 s100, s40, s16
	s_addc_u32 s101, s41, s17
	global_load_lds_dwordx4 v210, s[100:101]
	s_mov_b32 m0, s57
	v_lshl_add_u64 v[254:255], v[200:201], 0, s[16:17]
	global_load_lds_dwordx4 v[254:255], off
	v_lshl_add_u64 v[254:255], v[202:203], 0, s[16:17]
	s_mov_b32 m0, s58
	s_nop 0
	global_load_lds_dwordx4 v[254:255], off
	s_add_u32 s36, s40, 0x40080
	s_addc_u32 s37, s41, 0
	s_add_i32 s40, s42, s7
	s_mov_b32 m0, s40
	s_nop 0
	global_load_lds_dwordx4 v214, s[36:37]
	s_add_i32 m0, s40, 0x2000
	s_nop 0
	global_load_lds_dwordx4 v210, s[36:37]
	s_waitcnt vmcnt(6)
	s_waitcnt lgkmcnt(0)
	s_barrier
; #define LAS __attribute__((address_space(3)))
; #define PG8_STAGE(bufoff, gbase, voff) do { _Pragma("unroll") for (int _i = 0; _i < 2; ++_i) \
;         __builtin_amdgcn_global_load_lds((const unsigned*)((const char*)(gbase) + (voff)[_i]), (LAS unsigned*)(lds + (bufoff) + ldsw + _i * 8192), 16, 0, 0); } while (0)
; #define PG8_WAIT_V(n) asm volatile("s_waitcnt vmcnt(" #n ")" ::: "memory")
; #define PG8_BAR __builtin_amdgcn_s_barrier()
; template <class Epi>
; __device__ __forceinline__ void gemm_phase(LAS unsigned char* lds, const Gemm g, const StaticOrder& S, const Epi& E) {
;     ...
;             PG8_WAIT_V(6); PG8_BAR; PG8_MMA(1, 1, At, B1); PG8_BAR;
;             PG8_LDB(B0, 1, 0); PG8_SCHED; PG8_LDA(At, 1, 0); PG8_STAGE(PG8_SA(0, 1), a2 + hstepA, voffA);
;             PG8_WAIT_L(8); PG8_BAR; PG8_WAIT_L(0); PG8_MMA(0, 0, At, B0); PG8_BAR; PG8_SCHED;
;             PG8_LDB(B1, 1, 1); PG8_STAGE(PG8_SB(1, 0), b3, voffB);
;             PG8_BAR; PG8_WAIT_L(0); PG8_MMA(0, 1, At, B1); PG8_BAR;
;             PG8_LDA(At, 1, 1); PG8_STAGE(PG8_SA(1, 0), a3, voffA);
;             PG8_BAR; PG8_WAIT_L(0); PG8_MMA(1, 0, At, B0); PG8_BAR; PG8_SCHED;
;             PG8_STAGE(PG8_SB(1, 1), b3 + hstepB, voffB);
;             PG8_WAIT_V(6); PG8_BAR; PG8_MMA(1, 1, At, B1); PG8_BAR;
;         }
;         E(acc, cur, wr, wc, fr, fq);
;     __device__ __forceinline__ void operator()(AccRef acc, const Unit& u, int wr, int wc, int fr, int fq) const {
;         const int clb = 32 * wc + 8 * fq;
;         f32x4 cwv[2][8];
;         { const float* cv = cw + 128 * u.pn + clb; const float* cg = cv + FH; const float* bp = cb + 128 * u.pn + clb;
;           cwv[0][0] = *(const f32x4*)(cv); cwv[0][1] = *(const f32x4*)(cv + F2); cwv[0][2] = *(const f32x4*)(cv + 2 * F2); cwv[0][3] = *(const f32x4*)(bp);
;           cwv[0][4] = *(const f32x4*)(cg); cwv[0][5] = *(const f32x4*)(cg + F2); cwv[0][6] = *(const f32x4*)(cg + 2 * F2); cwv[0][7] = *(const f32x4*)(bp + FH); }
;         if (fr == 15) {
; #pragma unroll
;             for (int ai = 0; ai < 2; ++ai)
; #pragma unroll
;                 for (int bj = 0; bj < 2; ++bj)
; #pragma unroll
;                     for (int n = 0; n < 2; ++n) { *(LAS f32x4*)(xch + ((ai * 2 + wr) * 2 + 0) * 256 + bj * 128 + clb + 4 * n) = acc[ai][bj][2][n]; *(LAS f32x4*)(xch + ((ai * 2 + wr) * 2 + 1) * 256 + bj * 128 + clb + 4 * n) = acc[ai][bj][3][n]; }
	s_setprio 1
	v_mfma_f32_16x16x32_bf16 v[92:95], v[96:99], v[112:115], v[92:95]
	v_mfma_f32_16x16x32_bf16 v[28:31], v[104:107], v[112:115], v[28:31]
	v_mfma_f32_16x16x32_bf16 v[80:83], v[96:99], v[120:123], v[80:83]
	v_mfma_f32_16x16x32_bf16 v[16:19], v[104:107], v[120:123], v[16:19]
	v_mfma_f32_16x16x32_bf16 v[76:79], v[96:99], v[160:163], v[76:79]
	v_mfma_f32_16x16x32_bf16 v[12:15], v[104:107], v[160:163], v[12:15]
	v_mfma_f32_16x16x32_bf16 v[84:87], v[96:99], v[168:171], v[84:87]
	v_mfma_f32_16x16x32_bf16 v[20:23], v[104:107], v[168:171], v[20:23]
	v_mfma_f32_16x16x32_bf16 v[92:95], v[100:103], v[116:119], v[92:95]
	v_mfma_f32_16x16x32_bf16 v[28:31], v[108:111], v[116:119], v[28:31]
	v_mfma_f32_16x16x32_bf16 v[80:83], v[100:103], v[124:127], v[80:83]
	v_mfma_f32_16x16x32_bf16 v[16:19], v[108:111], v[124:127], v[16:19]
	v_mfma_f32_16x16x32_bf16 v[76:79], v[100:103], v[164:167], v[76:79]
	v_mfma_f32_16x16x32_bf16 v[12:15], v[108:111], v[164:167], v[12:15]
	v_mfma_f32_16x16x32_bf16 v[84:87], v[100:103], v[172:175], v[84:87]
	v_mfma_f32_16x16x32_bf16 v[20:23], v[108:111], v[172:175], v[20:23]
	v_mfma_f32_16x16x32_bf16 v[88:91], v[180:183], v[112:115], v[88:91]
	v_mfma_f32_16x16x32_bf16 v[24:27], v[188:191], v[112:115], v[24:27]
	v_mfma_f32_16x16x32_bf16 v[68:71], v[180:183], v[120:123], v[68:71]
	v_mfma_f32_16x16x32_bf16 v[4:7], v[188:191], v[120:123], v[4:7]
	v_mfma_f32_16x16x32_bf16 v[64:67], v[180:183], v[160:163], v[64:67]
	v_mfma_f32_16x16x32_bf16 v[0:3], v[188:191], v[160:163], v[0:3]
	v_mfma_f32_16x16x32_bf16 v[72:75], v[180:183], v[168:171], v[72:75]
	v_mfma_f32_16x16x32_bf16 v[8:11], v[188:191], v[168:171], v[8:11]
	v_mfma_f32_16x16x32_bf16 v[88:91], v[184:187], v[116:119], v[88:91]
	v_mfma_f32_16x16x32_bf16 v[24:27], v[192:195], v[116:119], v[24:27]
	v_mfma_f32_16x16x32_bf16 v[68:71], v[184:187], v[124:127], v[68:71]
	v_mfma_f32_16x16x32_bf16 v[4:7], v[192:195], v[124:127], v[4:7]
	v_mfma_f32_16x16x32_bf16 v[64:67], v[184:187], v[164:167], v[64:67]
	v_mfma_f32_16x16x32_bf16 v[0:3], v[192:195], v[164:167], v[0:3]
	v_mfma_f32_16x16x32_bf16 v[72:75], v[184:187], v[172:175], v[72:75]
	v_mfma_f32_16x16x32_bf16 v[8:11], v[192:195], v[172:175], v[8:11]
	s_setprio 0
	s_add_i32 s72, s72, 2
	s_add_u32 s70, s70, 0x100
	s_addc_u32 s71, s71, 0
	s_cmp_gt_u32 s72, 13
	s_mov_b64 s[36:37], s[38:39]
	s_barrier
	s_cbranch_scc0 .LBB0_1940
	s_lshl_b32 s36, s35, 7
	s_ashr_i32 s37, s36, 31
	s_lshl_b64 s[38:39], s[36:37], 2
	v_lshl_add_u64 v[96:97], v[220:221], 0, s[38:39]
	v_add_co_u32_e32 v100, vcc, 0x5000, v96
	v_lshl_add_u64 v[98:99], v[222:223], 0, s[38:39]
	s_nop 0
	v_addc_co_u32_e32 v101, vcc, 0, v97, vcc
	v_add_co_u32_e32 v102, vcc, 0xb000, v96
	global_load_dwordx4 v[160:163], v[96:97], off
	s_nop 0
	v_addc_co_u32_e32 v103, vcc, 0, v97, vcc
	global_load_dwordx4 v[164:167], v[100:101], off offset:2048
	global_load_dwordx4 v[168:171], v[102:103], off
	global_load_dwordx4 v[172:175], v[98:99], off
	v_add_co_u32_e32 v100, vcc, s49, v96
	s_nop 1
	v_addc_co_u32_e32 v101, vcc, 0, v97, vcc
	v_add_co_u32_e32 v102, vcc, 0x8000, v96
	s_nop 1
	v_addc_co_u32_e32 v103, vcc, 0, v97, vcc
	v_add_co_u32_e32 v96, vcc, 0xd000, v96
	global_load_dwordx4 v[176:179], v[100:101], off offset:3072
	global_load_dwordx4 v[180:183], v[102:103], off offset:1024
	v_addc_co_u32_e32 v97, vcc, 0, v97, vcc
	global_load_dwordx4 v[184:187], v[96:97], off offset:3072
	v_add_co_u32_e32 v96, vcc, 0x2000, v98
	s_nop 1
	v_addc_co_u32_e32 v97, vcc, 0, v99, vcc
	global_load_dwordx4 v[188:191], v[96:97], off offset:3072
	s_and_saveexec_b64 s[38:39], s[0:1]
	s_cbranch_execz .LBB0_1943
	ds_write_b128 v236, v[136:139]
	ds_write_b128 v236, v[148:151] offset:1024
	ds_write_b128 v236, v[40:43] offset:16
	ds_write_b128 v236, v[52:55] offset:1040
	ds_write_b128 v236, v[128:131] offset:512
	ds_write_b128 v236, v[140:143] offset:1536
	ds_write_b128 v236, v[32:35] offset:528
	ds_write_b128 v236, v[44:47] offset:1552
	ds_write_b128 v236, v[76:79] offset:4096
	ds_write_b128 v236, v[84:87] offset:5120
	ds_write_b128 v236, v[12:15] offset:4112
	ds_write_b128 v236, v[20:23] offset:5136
	ds_write_b128 v236, v[64:67] offset:4608
	ds_write_b128 v236, v[72:75] offset:5632
	ds_write_b128 v236, v[0:3] offset:4624
	ds_write_b128 v236, v[8:11] offset:5648

; #define PG8_STAGE(bufoff, gbase, voff) do { _Pragma("unroll") for (int _i = 0; _i < 2; ++_i) \
;         __builtin_amdgcn_global_load_lds((const unsigned*)((const char*)(gbase) + (voff)[_i]), (LAS unsigned*)(lds + (bufoff) + ldsw + _i * 8192), 16, 0, 0); } while (0)
; #define PG8_LDA(dst, b, h) do { _Pragma("unroll") for (int m = 0; m < 4; ++m) _Pragma("unroll") for (int k = 0; k < 2; ++k) dst[m][k] = *(const LAS bf16x8*)(lds + PG8_SA(b, h) + aoff + m * 2048 + k * 1024); } while (0)
; #define PG8_LDB(dst, b, h) do { _Pragma("unroll") for (int n = 0; n < 2; ++n) _Pragma("unroll") for (int k = 0; k < 2; ++k) dst[n][k] = *(const LAS bf16x8*)(lds + PG8_SB(b, h) + boff + n * 2048 + k * 1024); } while (0)
; #define PG8_WAIT_V(n) asm volatile("s_waitcnt vmcnt(" #n ")" ::: "memory")
; #define PG8_WAIT_L(n) asm volatile("s_waitcnt lgkmcnt(" #n ")" ::: "memory")
; #define PG8_BAR __builtin_amdgcn_s_barrier()
; #define PG8_SCHED __builtin_amdgcn_sched_barrier(0)
; template <class Epi>
; __device__ __forceinline__ void gemm_phase(LAS unsigned char* lds, const Gemm g, const StaticOrder& S, const Epi& E) {
;     ...
;     for (;;) {
;         const bool has_next = S.next(ui + 1, nxt);
;         const char* nA = has_next ? (const char*)g.A + (size_t)nxt.pm * tstepA + (size_t)(nxt.pn >> g.a_shift) * g.a_step : cA; const char* nB = has_next ? (const char*)g.Bt + (size_t)nxt.pn * tstepB : cB;
;         for (int t = 0; t < nt; t += 2) {
;             const bool last = (t == nt - 2);
;             const char* a1 = cA + (size_t)(t + 1) * kstep;
;             const char* a2 = last ? nA : cA + (size_t)(t + 2) * kstep; const char* b2 = last ? nB : cB + (size_t)(t + 2) * kstep;
;             const char* a3 = a2 + kstep; const char* b3 = b2 + kstep;
;             PG8_LDB(B0, 0, 0); PG8_SCHED; PG8_LDA(At, 0, 0); PG8_STAGE(PG8_SA(1, 1), a1 + hstepA, voffA);
;             PG8_WAIT_L(8); PG8_BAR; PG8_WAIT_L(0); PG8_MMA(0, 0, At, B0); PG8_BAR; PG8_SCHED;
;             PG8_LDB(B1, 0, 1); PG8_STAGE(PG8_SB(0, 0), b2, voffB);
;             PG8_BAR; PG8_WAIT_L(0); PG8_MMA(0, 1, At, B1); PG8_BAR;
;             PG8_LDA(At, 0, 1); PG8_STAGE(PG8_SA(0, 0), a2, voffA);
;             PG8_BAR; PG8_WAIT_L(0); PG8_MMA(1, 0, At, B0); PG8_BAR; PG8_SCHED;
;             PG8_STAGE(PG8_SB(0, 1), b2 + hstepB, voffB);
;             PG8_WAIT_V(6); PG8_BAR; PG8_MMA(1, 1, At, B1); PG8_BAR;
.LBB0_2041:
	s_add_u32 s44, s20, 0x100
	s_addc_u32 s45, s21, 0
	s_mov_b32 s46, -2
	ds_read_b128 v[140:143], v149
	ds_read_b128 v[152:155], v149 offset:1024
	ds_read_b128 v[156:159], v149 offset:2048
	ds_read_b128 v[160:163], v149 offset:3072
	s_add_u32 s20, s18, 0x100
	s_addc_u32 s21, s19, 0
	s_cmp_eq_u32 s46, 40
	s_cselect_b32 s25, s5, s21
	s_cselect_b32 s24, s4, s20
	s_cselect_b32 s23, s7, s45
	s_cselect_b32 s22, s6, s44
	s_add_i32 m0, s30, 0xc000
	ds_read_b128 v[164:167], v150
	ds_read_b128 v[168:171], v150 offset:1024
	ds_read_b128 v[172:175], v150 offset:2048
	ds_read_b128 v[176:179], v150 offset:3072
	ds_read_b128 v[180:183], v150 offset:4096
	ds_read_b128 v[184:187], v150 offset:5120
	ds_read_b128 v[188:191], v150 offset:6144
	ds_read_b128 v[192:195], v150 offset:7168
	global_load_lds_dwordx4 v132, s[18:19]
	s_add_i32 m0, s30, 0xe000
	s_nop 0
	global_load_lds_dwordx4 v134, s[18:19]
	ds_read_b128 v[196:199], v151
	ds_read_b128 v[200:203], v151 offset:1024
	ds_read_b128 v[204:207], v151 offset:2048
	ds_read_b128 v[208:211], v151 offset:3072
	s_waitcnt lgkmcnt(0)
	s_barrier
	s_setprio 1
	v_mfma_f32_16x16x32_bf16 v[124:127], v[140:143], v[164:167], 0
	v_mfma_f32_16x16x32_bf16 v[120:123], v[156:159], v[164:167], 0
	v_mfma_f32_16x16x32_bf16 v[112:115], v[140:143], v[172:175], 0
	v_mfma_f32_16x16x32_bf16 v[104:107], v[156:159], v[172:175], 0
	v_mfma_f32_16x16x32_bf16 v[92:95], v[140:143], v[180:183], 0
	v_mfma_f32_16x16x32_bf16 v[88:91], v[156:159], v[180:183], 0
	v_mfma_f32_16x16x32_bf16 v[80:83], v[140:143], v[188:191], 0
	v_mfma_f32_16x16x32_bf16 v[72:75], v[156:159], v[188:191], 0
	v_mfma_f32_16x16x32_bf16 v[124:127], v[152:155], v[168:171], v[124:127]
	v_mfma_f32_16x16x32_bf16 v[120:123], v[160:163], v[168:171], v[120:123]
	v_mfma_f32_16x16x32_bf16 v[112:115], v[152:155], v[176:179], v[112:115]
	v_mfma_f32_16x16x32_bf16 v[104:107], v[160:163], v[176:179], v[104:107]
	v_mfma_f32_16x16x32_bf16 v[92:95], v[152:155], v[184:187], v[92:95]
	v_mfma_f32_16x16x32_bf16 v[88:91], v[160:163], v[184:187], v[88:91]
	v_mfma_f32_16x16x32_bf16 v[80:83], v[152:155], v[192:195], v[80:83]
	v_mfma_f32_16x16x32_bf16 v[72:75], v[160:163], v[192:195], v[72:75]
	v_mfma_f32_16x16x32_bf16 v[116:119], v[196:199], v[164:167], 0
	v_mfma_f32_16x16x32_bf16 v[108:111], v[204:207], v[164:167], 0
	v_mfma_f32_16x16x32_bf16 v[100:103], v[196:199], v[172:175], 0
	v_mfma_f32_16x16x32_bf16 v[96:99], v[204:207], v[172:175], 0
	v_mfma_f32_16x16x32_bf16 v[84:87], v[196:199], v[180:183], 0
	v_mfma_f32_16x16x32_bf16 v[76:79], v[204:207], v[180:183], 0
	v_mfma_f32_16x16x32_bf16 v[68:71], v[196:199], v[188:191], 0
	v_mfma_f32_16x16x32_bf16 v[64:67], v[204:207], v[188:191], 0
	v_mfma_f32_16x16x32_bf16 v[116:119], v[200:203], v[168:171], v[116:119]
	v_mfma_f32_16x16x32_bf16 v[108:111], v[208:211], v[168:171], v[108:111]
	v_mfma_f32_16x16x32_bf16 v[100:103], v[200:203], v[176:179], v[100:103]
	v_mfma_f32_16x16x32_bf16 v[96:99], v[208:211], v[176:179], v[96:99]
	v_mfma_f32_16x16x32_bf16 v[84:87], v[200:203], v[184:187], v[84:87]
	v_mfma_f32_16x16x32_bf16 v[76:79], v[208:211], v[184:187], v[76:79]
	v_mfma_f32_16x16x32_bf16 v[68:71], v[200:203], v[192:195], v[68:71]
	v_mfma_f32_16x16x32_bf16 v[64:67], v[208:211], v[192:195], v[64:67]
	s_setprio 0
	s_barrier
	s_nop 1
	ds_read_b128 v[164:167], v150 offset:16384
	ds_read_b128 v[168:171], v150 offset:17408
	ds_read_b128 v[172:175], v150 offset:18432
	ds_read_b128 v[176:179], v150 offset:19456
	ds_read_b128 v[180:183], v150 offset:20480
	ds_read_b128 v[184:187], v150 offset:21504
	ds_read_b128 v[188:191], v150 offset:22528
	ds_read_b128 v[192:195], v150 offset:23552
	s_add_i32 s18, s38, s29
	v_lshl_add_u64 v[144:145], s[22:23], 0, v[128:129]
	s_mov_b32 m0, s18
	s_nop 0
	global_load_lds_dwordx4 v128, s[22:23]
	v_lshl_add_u64 v[212:213], s[22:23], 0, v[130:131]
	s_add_i32 m0, s18, 0x2000
	s_nop 0
	global_load_lds_dwordx4 v130, s[22:23]
	s_mov_b32 m0, s30
	v_lshl_add_u64 v[214:215], s[24:25], 0, v[128:129]
	global_load_lds_dwordx4 v128, s[24:25]
	v_lshl_add_u64 v[216:217], s[24:25], 0, v[130:131]
	s_mov_b32 m0, s31
	s_nop 0
	global_load_lds_dwordx4 v130, s[24:25]
	s_add_u32 s18, s22, 0xb0000
	s_addc_u32 s19, s23, 0
	s_add_i32 s47, s39, s29
	s_mov_b32 m0, s47
	s_nop 0
	global_load_lds_dwordx4 v128, s[18:19]
	s_add_i32 m0, s47, 0x2000
	s_nop 0
	global_load_lds_dwordx4 v130, s[18:19]
	s_waitcnt vmcnt(6)
	s_waitcnt lgkmcnt(0)
	s_barrier
	s_setprio 1
	v_mfma_f32_16x16x32_bf16 v[60:63], v[140:143], v[164:167], 0
	v_mfma_f32_16x16x32_bf16 v[56:59], v[156:159], v[164:167], 0
	v_mfma_f32_16x16x32_bf16 v[48:51], v[140:143], v[172:175], 0
	v_mfma_f32_16x16x32_bf16 v[40:43], v[156:159], v[172:175], 0
	v_mfma_f32_16x16x32_bf16 v[28:31], v[140:143], v[180:183], 0
	v_mfma_f32_16x16x32_bf16 v[24:27], v[156:159], v[180:183], 0
	v_mfma_f32_16x16x32_bf16 v[16:19], v[140:143], v[188:191], 0
	v_mfma_f32_16x16x32_bf16 v[8:11], v[156:159], v[188:191], 0
	v_mfma_f32_16x16x32_bf16 v[60:63], v[152:155], v[168:171], v[60:63]
	v_mfma_f32_16x16x32_bf16 v[56:59], v[160:163], v[168:171], v[56:59]
	v_mfma_f32_16x16x32_bf16 v[48:51], v[152:155], v[176:179], v[48:51]
	v_mfma_f32_16x16x32_bf16 v[40:43], v[160:163], v[176:179], v[40:43]
	v_mfma_f32_16x16x32_bf16 v[28:31], v[152:155], v[184:187], v[28:31]
	v_mfma_f32_16x16x32_bf16 v[24:27], v[160:163], v[184:187], v[24:27]
	v_mfma_f32_16x16x32_bf16 v[16:19], v[152:155], v[192:195], v[16:19]
	v_mfma_f32_16x16x32_bf16 v[8:11], v[160:163], v[192:195], v[8:11]
	v_mfma_f32_16x16x32_bf16 v[52:55], v[196:199], v[164:167], 0
	v_mfma_f32_16x16x32_bf16 v[44:47], v[204:207], v[164:167], 0
	v_mfma_f32_16x16x32_bf16 v[36:39], v[196:199], v[172:175], 0
	v_mfma_f32_16x16x32_bf16 v[32:35], v[204:207], v[172:175], 0
	v_mfma_f32_16x16x32_bf16 v[20:23], v[196:199], v[180:183], 0
	v_mfma_f32_16x16x32_bf16 v[12:15], v[204:207], v[180:183], 0
	v_mfma_f32_16x16x32_bf16 v[4:7], v[196:199], v[188:191], 0
	v_mfma_f32_16x16x32_bf16 v[0:3], v[204:207], v[188:191], 0
	v_mfma_f32_16x16x32_bf16 v[52:55], v[200:203], v[168:171], v[52:55]
	v_mfma_f32_16x16x32_bf16 v[44:47], v[208:211], v[168:171], v[44:47]
	v_mfma_f32_16x16x32_bf16 v[36:39], v[200:203], v[176:179], v[36:39]
	v_mfma_f32_16x16x32_bf16 v[32:35], v[208:211], v[176:179], v[32:35]
	v_mfma_f32_16x16x32_bf16 v[20:23], v[200:203], v[184:187], v[20:23]
	v_mfma_f32_16x16x32_bf16 v[12:15], v[208:211], v[184:187], v[12:15]
	v_mfma_f32_16x16x32_bf16 v[4:7], v[200:203], v[192:195], v[4:7]
	v_mfma_f32_16x16x32_bf16 v[0:3], v[208:211], v[192:195], v[0:3]
	s_setprio 0
	s_add_i32 s47, 0, 0x18000
	v_add_u32_e32 v160, s47, v147
	s_barrier
; #define PG8_STAGE(bufoff, gbase, voff) do { _Pragma("unroll") for (int _i = 0; _i < 2; ++_i) \
;         __builtin_amdgcn_global_load_lds((const unsigned*)((const char*)(gbase) + (voff)[_i]), (LAS unsigned*)(lds + (bufoff) + ldsw + _i * 8192), 16, 0, 0); } while (0)
; #define PG8_LDA(dst, b, h) do { _Pragma("unroll") for (int m = 0; m < 4; ++m) _Pragma("unroll") for (int k = 0; k < 2; ++k) dst[m][k] = *(const LAS bf16x8*)(lds + PG8_SA(b, h) + aoff + m * 2048 + k * 1024); } while (0)
; #define PG8_LDB(dst, b, h) do { _Pragma("unroll") for (int n = 0; n < 2; ++n) _Pragma("unroll") for (int k = 0; k < 2; ++k) dst[n][k] = *(const LAS bf16x8*)(lds + PG8_SB(b, h) + boff + n * 2048 + k * 1024); } while (0)
; #define PG8_MMA(ai, bj, At, Bt) do { __builtin_amdgcn_s_setprio(1); _Pragma("unroll") for (int m = 0; m < 4; ++m) _Pragma("unroll") for (int n = 0; n < 2; ++n) _Pragma("unroll") for (int k = 0; k < 2; ++k) \
;         acc[ai][bj][m][n] = __builtin_amdgcn_mfma_f32_16x16x32_bf16(Bt[n][k], At[m][k], acc[ai][bj][m][n], 0, 0, 0); __builtin_amdgcn_s_setprio(0); } while (0)
; #define PG8_WAIT_V(n) asm volatile("s_waitcnt vmcnt(" #n ")" ::: "memory")
; #define PG8_WAIT_L(n) asm volatile("s_waitcnt lgkmcnt(" #n ")" ::: "memory")
; template <class Epi>
; __device__ __forceinline__ void gemm_phase(LAS unsigned char* lds, const Gemm g, const StaticOrder& S, const Epi& E) {
;     ...
;             PG8_BAR; PG8_WAIT_L(0); PG8_MMA(0, 1, At, B1); PG8_BAR;
;             PG8_LDA(At, 0, 1); PG8_STAGE(PG8_SA(0, 0), a2, voffA);
;             PG8_BAR; PG8_WAIT_L(0); PG8_MMA(1, 0, At, B0); PG8_BAR; PG8_SCHED;
;             PG8_STAGE(PG8_SB(0, 1), b2 + hstepB, voffB);
;             PG8_WAIT_V(6); PG8_BAR; PG8_MMA(1, 1, At, B1); PG8_BAR;
;             PG8_LDB(B0, 1, 0); PG8_SCHED; PG8_LDA(At, 1, 0); PG8_STAGE(PG8_SA(0, 1), a2 + hstepA, voffA);
;             PG8_WAIT_L(8); PG8_BAR; PG8_WAIT_L(0); PG8_MMA(0, 0, At, B0); PG8_BAR; PG8_SCHED;
;             PG8_LDB(B1, 1, 1); PG8_STAGE(PG8_SB(1, 0), b3, voffB);
;             PG8_BAR; PG8_WAIT_L(0); PG8_MMA(0, 1, At, B1); PG8_BAR;
;             PG8_LDA(At, 1, 1); PG8_STAGE(PG8_SA(1, 0), a3, voffA);
;             PG8_BAR; PG8_WAIT_L(0); PG8_MMA(1, 0, At, B0); PG8_BAR; PG8_SCHED;
;             PG8_STAGE(PG8_SB(1, 1), b3 + hstepB, voffB);
;             PG8_WAIT_V(6); PG8_BAR; PG8_MMA(1, 1, At, B1); PG8_BAR;
	ds_read_b128 v[140:143], v160
	ds_read_b128 v[152:155], v160 offset:1024
	ds_read_b128 v[156:159], v160 offset:2048
	ds_read_b128 v[160:163], v160 offset:3072
	s_add_u32 s18, s24, 0xb0000
	s_addc_u32 s19, s25, 0
	s_mov_b32 m0, s33
	ds_read_b128 v[164:167], v150 offset:32768
	ds_read_b128 v[168:171], v150 offset:33792
	ds_read_b128 v[172:175], v150 offset:34816
	ds_read_b128 v[176:179], v150 offset:35840
	ds_read_b128 v[180:183], v150 offset:36864
	ds_read_b128 v[184:187], v150 offset:37888
	ds_read_b128 v[188:191], v150 offset:38912
	ds_read_b128 v[192:195], v150 offset:39936
	global_load_lds_dwordx4 v128, s[18:19]
	s_mov_b32 m0, s34
	s_nop 0
	global_load_lds_dwordx4 v130, s[18:19]
	s_add_i32 s24, 0, 0x1c000
	v_add_u32_e32 v208, s24, v147
	ds_read_b128 v[196:199], v208
	ds_read_b128 v[200:203], v208 offset:1024
	ds_read_b128 v[204:207], v208 offset:2048
	ds_read_b128 v[208:211], v208 offset:3072
	s_waitcnt lgkmcnt(0)
	s_barrier
	s_setprio 1
	v_mfma_f32_16x16x32_bf16 v[124:127], v[140:143], v[164:167], v[124:127]
	v_mfma_f32_16x16x32_bf16 v[120:123], v[156:159], v[164:167], v[120:123]
	v_mfma_f32_16x16x32_bf16 v[112:115], v[140:143], v[172:175], v[112:115]
	v_mfma_f32_16x16x32_bf16 v[104:107], v[156:159], v[172:175], v[104:107]
	v_mfma_f32_16x16x32_bf16 v[92:95], v[140:143], v[180:183], v[92:95]
	v_mfma_f32_16x16x32_bf16 v[88:91], v[156:159], v[180:183], v[88:91]
	v_mfma_f32_16x16x32_bf16 v[80:83], v[140:143], v[188:191], v[80:83]
	v_mfma_f32_16x16x32_bf16 v[72:75], v[156:159], v[188:191], v[72:75]
	v_mfma_f32_16x16x32_bf16 v[124:127], v[152:155], v[168:171], v[124:127]
	v_mfma_f32_16x16x32_bf16 v[120:123], v[160:163], v[168:171], v[120:123]
	v_mfma_f32_16x16x32_bf16 v[112:115], v[152:155], v[176:179], v[112:115]
	v_mfma_f32_16x16x32_bf16 v[104:107], v[160:163], v[176:179], v[104:107]
	v_mfma_f32_16x16x32_bf16 v[92:95], v[152:155], v[184:187], v[92:95]
	v_mfma_f32_16x16x32_bf16 v[88:91], v[160:163], v[184:187], v[88:91]
	v_mfma_f32_16x16x32_bf16 v[80:83], v[152:155], v[192:195], v[80:83]
	v_mfma_f32_16x16x32_bf16 v[72:75], v[160:163], v[192:195], v[72:75]
	v_mfma_f32_16x16x32_bf16 v[116:119], v[196:199], v[164:167], v[116:119]
	v_mfma_f32_16x16x32_bf16 v[108:111], v[204:207], v[164:167], v[108:111]
	v_mfma_f32_16x16x32_bf16 v[100:103], v[196:199], v[172:175], v[100:103]
	v_mfma_f32_16x16x32_bf16 v[96:99], v[204:207], v[172:175], v[96:99]
	v_mfma_f32_16x16x32_bf16 v[84:87], v[196:199], v[180:183], v[84:87]
	v_mfma_f32_16x16x32_bf16 v[76:79], v[204:207], v[180:183], v[76:79]
	v_mfma_f32_16x16x32_bf16 v[68:71], v[196:199], v[188:191], v[68:71]
	v_mfma_f32_16x16x32_bf16 v[64:67], v[204:207], v[188:191], v[64:67]
	v_mfma_f32_16x16x32_bf16 v[116:119], v[200:203], v[168:171], v[116:119]
	v_mfma_f32_16x16x32_bf16 v[108:111], v[208:211], v[168:171], v[108:111]
	v_mfma_f32_16x16x32_bf16 v[100:103], v[200:203], v[176:179], v[100:103]
	v_mfma_f32_16x16x32_bf16 v[96:99], v[208:211], v[176:179], v[96:99]
	v_mfma_f32_16x16x32_bf16 v[84:87], v[200:203], v[184:187], v[84:87]
	v_mfma_f32_16x16x32_bf16 v[76:79], v[208:211], v[184:187], v[76:79]
	v_mfma_f32_16x16x32_bf16 v[68:71], v[200:203], v[192:195], v[68:71]
	v_mfma_f32_16x16x32_bf16 v[64:67], v[208:211], v[192:195], v[64:67]
	s_setprio 0
	s_barrier
	s_nop 1
	ds_read_b128 v[164:167], v150 offset:49152
	ds_read_b128 v[168:171], v150 offset:50176
	ds_read_b128 v[172:175], v150 offset:51200
	ds_read_b128 v[176:179], v150 offset:52224
	ds_read_b128 v[180:183], v150 offset:53248
	ds_read_b128 v[184:187], v150 offset:54272
	ds_read_b128 v[188:191], v150 offset:55296
	ds_read_b128 v[192:195], v150 offset:56320
	s_add_i32 s18, s47, s29
	s_mov_b32 m0, s18
	s_nop 0
	s_add_u32 s100, s22, s10
	s_addc_u32 s101, s23, s11
	global_load_lds_dwordx4 v128, s[100:101]
	s_add_i32 m0, s18, 0x2000
	s_nop 0
	s_add_u32 s100, s22, s10
	s_addc_u32 s101, s23, s11
	global_load_lds_dwordx4 v130, s[100:101]
	s_mov_b32 m0, s36
	v_lshl_add_u64 v[254:255], v[214:215], 0, s[10:11]
	global_load_lds_dwordx4 v[254:255], off
	v_lshl_add_u64 v[144:145], v[216:217], 0, s[10:11]
	s_mov_b32 m0, s37
	s_nop 0
	global_load_lds_dwordx4 v[144:145], off
	s_add_u32 s18, s22, 0xb0080
	s_addc_u32 s19, s23, 0
	s_add_i32 s22, s24, s29
	s_mov_b32 m0, s22
	s_nop 0
	global_load_lds_dwordx4 v128, s[18:19]
	s_add_i32 m0, s22, 0x2000
	s_nop 0
	global_load_lds_dwordx4 v130, s[18:19]
	s_waitcnt vmcnt(6)
	s_waitcnt lgkmcnt(0)
	s_barrier
	s_setprio 1
	v_mfma_f32_16x16x32_bf16 v[60:63], v[140:143], v[164:167], v[60:63]
	v_mfma_f32_16x16x32_bf16 v[56:59], v[156:159], v[164:167], v[56:59]
	v_mfma_f32_16x16x32_bf16 v[48:51], v[140:143], v[172:175], v[48:51]
	v_mfma_f32_16x16x32_bf16 v[40:43], v[156:159], v[172:175], v[40:43]
	v_mfma_f32_16x16x32_bf16 v[28:31], v[140:143], v[180:183], v[28:31]
	v_mfma_f32_16x16x32_bf16 v[24:27], v[156:159], v[180:183], v[24:27]
	v_mfma_f32_16x16x32_bf16 v[16:19], v[140:143], v[188:191], v[16:19]
	v_mfma_f32_16x16x32_bf16 v[8:11], v[156:159], v[188:191], v[8:11]
	v_mfma_f32_16x16x32_bf16 v[60:63], v[152:155], v[168:171], v[60:63]
	v_mfma_f32_16x16x32_bf16 v[56:59], v[160:163], v[168:171], v[56:59]
	v_mfma_f32_16x16x32_bf16 v[48:51], v[152:155], v[176:179], v[48:51]
	v_mfma_f32_16x16x32_bf16 v[40:43], v[160:163], v[176:179], v[40:43]
	v_mfma_f32_16x16x32_bf16 v[28:31], v[152:155], v[184:187], v[28:31]
	v_mfma_f32_16x16x32_bf16 v[24:27], v[160:163], v[184:187], v[24:27]
	v_mfma_f32_16x16x32_bf16 v[16:19], v[152:155], v[192:195], v[16:19]
	v_mfma_f32_16x16x32_bf16 v[8:11], v[160:163], v[192:195], v[8:11]
	v_mfma_f32_16x16x32_bf16 v[52:55], v[196:199], v[164:167], v[52:55]
	v_mfma_f32_16x16x32_bf16 v[44:47], v[204:207], v[164:167], v[44:47]
	v_mfma_f32_16x16x32_bf16 v[36:39], v[196:199], v[172:175], v[36:39]
	v_mfma_f32_16x16x32_bf16 v[32:35], v[204:207], v[172:175], v[32:35]
	v_mfma_f32_16x16x32_bf16 v[20:23], v[196:199], v[180:183], v[20:23]
	v_mfma_f32_16x16x32_bf16 v[12:15], v[204:207], v[180:183], v[12:15]
	v_mfma_f32_16x16x32_bf16 v[4:7], v[196:199], v[188:191], v[4:7]
	v_mfma_f32_16x16x32_bf16 v[0:3], v[204:207], v[188:191], v[0:3]
	v_mfma_f32_16x16x32_bf16 v[52:55], v[200:203], v[168:171], v[52:55]
	v_mfma_f32_16x16x32_bf16 v[44:47], v[208:211], v[168:171], v[44:47]
	v_mfma_f32_16x16x32_bf16 v[36:39], v[200:203], v[176:179], v[36:39]
	v_mfma_f32_16x16x32_bf16 v[32:35], v[208:211], v[176:179], v[32:35]
	v_mfma_f32_16x16x32_bf16 v[20:23], v[200:203], v[184:187], v[20:23]
	v_mfma_f32_16x16x32_bf16 v[12:15], v[208:211], v[184:187], v[12:15]
	v_mfma_f32_16x16x32_bf16 v[4:7], v[200:203], v[192:195], v[4:7]
	v_mfma_f32_16x16x32_bf16 v[0:3], v[208:211], v[192:195], v[0:3]
	s_setprio 0
	s_add_i32 s46, s46, 2
	s_add_u32 s44, s44, 0x100
	s_addc_u32 s45, s45, 0
	s_cmp_gt_u32 s46, 41
	s_mov_b64 s[18:19], s[20:21]
	s_barrier
; #define PG8_STAGE(bufoff, gbase, voff) do { _Pragma("unroll") for (int _i = 0; _i < 2; ++_i) \
;         __builtin_amdgcn_global_load_lds((const unsigned*)((const char*)(gbase) + (voff)[_i]), (LAS unsigned*)(lds + (bufoff) + ldsw + _i * 8192), 16, 0, 0); } while (0)
; #define PG8_LDA(dst, b, h) do { _Pragma("unroll") for (int m = 0; m < 4; ++m) _Pragma("unroll") for (int k = 0; k < 2; ++k) dst[m][k] = *(const LAS bf16x8*)(lds + PG8_SA(b, h) + aoff + m * 2048 + k * 1024); } while (0)
; #define PG8_LDB(dst, b, h) do { _Pragma("unroll") for (int n = 0; n < 2; ++n) _Pragma("unroll") for (int k = 0; k < 2; ++k) dst[n][k] = *(const LAS bf16x8*)(lds + PG8_SB(b, h) + boff + n * 2048 + k * 1024); } while (0)
; #define PG8_MMA(ai, bj, At, Bt) do { __builtin_amdgcn_s_setprio(1); _Pragma("unroll") for (int m = 0; m < 4; ++m) _Pragma("unroll") for (int n = 0; n < 2; ++n) _Pragma("unroll") for (int k = 0; k < 2; ++k) \
;         acc[ai][bj][m][n] = __builtin_amdgcn_mfma_f32_16x16x32_bf16(Bt[n][k], At[m][k], acc[ai][bj][m][n], 0, 0, 0); __builtin_amdgcn_s_setprio(0); } while (0)
; #define PG8_WAIT_V(n) asm volatile("s_waitcnt vmcnt(" #n ")" ::: "memory")
; #define PG8_WAIT_L(n) asm volatile("s_waitcnt lgkmcnt(" #n ")" ::: "memory")
; template <class Epi>
; __device__ __forceinline__ void gemm_phase(LAS unsigned char* lds, const Gemm g, const StaticOrder& S, const Epi& E) {
;     ...
;         for (int t = 0; t < nt; t += 2) {
;             const bool last = (t == nt - 2);
;             const char* a1 = cA + (size_t)(t + 1) * kstep;
;             const char* a2 = last ? nA : cA + (size_t)(t + 2) * kstep; const char* b2 = last ? nB : cB + (size_t)(t + 2) * kstep;
;             const char* a3 = a2 + kstep; const char* b3 = b2 + kstep;
;             PG8_LDB(B0, 0, 0); PG8_SCHED; PG8_LDA(At, 0, 0); PG8_STAGE(PG8_SA(1, 1), a1 + hstepA, voffA);
;             PG8_WAIT_L(8); PG8_BAR; PG8_WAIT_L(0); PG8_MMA(0, 0, At, B0); PG8_BAR; PG8_SCHED;
;             PG8_LDB(B1, 0, 1); PG8_STAGE(PG8_SB(0, 0), b2, voffB);
;             PG8_BAR; PG8_WAIT_L(0); PG8_MMA(0, 1, At, B1); PG8_BAR;
;             PG8_LDA(At, 0, 1); PG8_STAGE(PG8_SA(0, 0), a2, voffA);
;             PG8_BAR; PG8_WAIT_L(0); PG8_MMA(1, 0, At, B0); PG8_BAR; PG8_SCHED;
;             PG8_STAGE(PG8_SB(0, 1), b2 + hstepB, voffB);
;             PG8_WAIT_V(6); PG8_BAR; PG8_MMA(1, 1, At, B1); PG8_BAR;
.LBB0_2042:
	ds_read_b128 v[140:143], v149
	ds_read_b128 v[152:155], v149 offset:1024
	ds_read_b128 v[156:159], v149 offset:2048
	ds_read_b128 v[160:163], v149 offset:3072
	s_add_u32 s20, s18, 0x100
	s_addc_u32 s21, s19, 0
	s_cmp_eq_u32 s46, 40
	s_cselect_b32 s25, s5, s21
	s_cselect_b32 s24, s4, s20
	s_cselect_b32 s23, s7, s45
	s_cselect_b32 s22, s6, s44
	s_add_i32 m0, s30, 0xc000
	ds_read_b128 v[164:167], v150
	ds_read_b128 v[168:171], v150 offset:1024
	ds_read_b128 v[172:175], v150 offset:2048
	ds_read_b128 v[176:179], v150 offset:3072
	ds_read_b128 v[180:183], v150 offset:4096
	ds_read_b128 v[184:187], v150 offset:5120
	ds_read_b128 v[188:191], v150 offset:6144
	ds_read_b128 v[192:195], v150 offset:7168
	global_load_lds_dwordx4 v132, s[18:19]
	s_add_i32 m0, s30, 0xe000
	s_nop 0
	global_load_lds_dwordx4 v134, s[18:19]
	ds_read_b128 v[196:199], v151
	ds_read_b128 v[200:203], v151 offset:1024
	ds_read_b128 v[204:207], v151 offset:2048
	ds_read_b128 v[208:211], v151 offset:3072
	s_waitcnt lgkmcnt(0)
	s_barrier
	s_setprio 1
	v_mfma_f32_16x16x32_bf16 v[124:127], v[140:143], v[164:167], v[124:127]
	v_mfma_f32_16x16x32_bf16 v[120:123], v[156:159], v[164:167], v[120:123]
	v_mfma_f32_16x16x32_bf16 v[112:115], v[140:143], v[172:175], v[112:115]
	v_mfma_f32_16x16x32_bf16 v[104:107], v[156:159], v[172:175], v[104:107]
	v_mfma_f32_16x16x32_bf16 v[92:95], v[140:143], v[180:183], v[92:95]
	v_mfma_f32_16x16x32_bf16 v[88:91], v[156:159], v[180:183], v[88:91]
	v_mfma_f32_16x16x32_bf16 v[80:83], v[140:143], v[188:191], v[80:83]
	v_mfma_f32_16x16x32_bf16 v[72:75], v[156:159], v[188:191], v[72:75]
	v_mfma_f32_16x16x32_bf16 v[124:127], v[152:155], v[168:171], v[124:127]
	v_mfma_f32_16x16x32_bf16 v[120:123], v[160:163], v[168:171], v[120:123]
	v_mfma_f32_16x16x32_bf16 v[112:115], v[152:155], v[176:179], v[112:115]
	v_mfma_f32_16x16x32_bf16 v[104:107], v[160:163], v[176:179], v[104:107]
	v_mfma_f32_16x16x32_bf16 v[92:95], v[152:155], v[184:187], v[92:95]
	v_mfma_f32_16x16x32_bf16 v[88:91], v[160:163], v[184:187], v[88:91]
	v_mfma_f32_16x16x32_bf16 v[80:83], v[152:155], v[192:195], v[80:83]
	v_mfma_f32_16x16x32_bf16 v[72:75], v[160:163], v[192:195], v[72:75]
	v_mfma_f32_16x16x32_bf16 v[116:119], v[196:199], v[164:167], v[116:119]
	v_mfma_f32_16x16x32_bf16 v[108:111], v[204:207], v[164:167], v[108:111]
	v_mfma_f32_16x16x32_bf16 v[100:103], v[196:199], v[172:175], v[100:103]
	v_mfma_f32_16x16x32_bf16 v[96:99], v[204:207], v[172:175], v[96:99]
	v_mfma_f32_16x16x32_bf16 v[84:87], v[196:199], v[180:183], v[84:87]
	v_mfma_f32_16x16x32_bf16 v[76:79], v[204:207], v[180:183], v[76:79]
	v_mfma_f32_16x16x32_bf16 v[68:71], v[196:199], v[188:191], v[68:71]
	v_mfma_f32_16x16x32_bf16 v[64:67], v[204:207], v[188:191], v[64:67]
	v_mfma_f32_16x16x32_bf16 v[116:119], v[200:203], v[168:171], v[116:119]
	v_mfma_f32_16x16x32_bf16 v[108:111], v[208:211], v[168:171], v[108:111]
	v_mfma_f32_16x16x32_bf16 v[100:103], v[200:203], v[176:179], v[100:103]
	v_mfma_f32_16x16x32_bf16 v[96:99], v[208:211], v[176:179], v[96:99]
	v_mfma_f32_16x16x32_bf16 v[84:87], v[200:203], v[184:187], v[84:87]
	v_mfma_f32_16x16x32_bf16 v[76:79], v[208:211], v[184:187], v[76:79]
	v_mfma_f32_16x16x32_bf16 v[68:71], v[200:203], v[192:195], v[68:71]
	v_mfma_f32_16x16x32_bf16 v[64:67], v[208:211], v[192:195], v[64:67]
	s_setprio 0
	s_barrier
	s_nop 1
	ds_read_b128 v[164:167], v150 offset:16384
	ds_read_b128 v[168:171], v150 offset:17408
	ds_read_b128 v[172:175], v150 offset:18432
	ds_read_b128 v[176:179], v150 offset:19456
	ds_read_b128 v[180:183], v150 offset:20480
	ds_read_b128 v[184:187], v150 offset:21504
	ds_read_b128 v[188:191], v150 offset:22528
	ds_read_b128 v[192:195], v150 offset:23552
	s_add_i32 s18, s38, s29
	v_lshl_add_u64 v[144:145], s[22:23], 0, v[128:129]
	s_mov_b32 m0, s18
	s_nop 0
	global_load_lds_dwordx4 v128, s[22:23]
	v_lshl_add_u64 v[212:213], s[22:23], 0, v[130:131]
	s_add_i32 m0, s18, 0x2000
	s_nop 0
	global_load_lds_dwordx4 v130, s[22:23]
	s_mov_b32 m0, s30
	v_lshl_add_u64 v[214:215], s[24:25], 0, v[128:129]
	global_load_lds_dwordx4 v128, s[24:25]
	v_lshl_add_u64 v[216:217], s[24:25], 0, v[130:131]
	s_mov_b32 m0, s31
	s_nop 0
	global_load_lds_dwordx4 v130, s[24:25]
	s_add_u32 s18, s22, 0xb0000
	s_addc_u32 s19, s23, 0
	s_add_i32 s47, s39, s29
	s_mov_b32 m0, s47
	s_nop 0
	global_load_lds_dwordx4 v128, s[18:19]
	s_add_i32 m0, s47, 0x2000
	s_nop 0
	global_load_lds_dwordx4 v130, s[18:19]
	s_waitcnt vmcnt(6)
	s_waitcnt lgkmcnt(0)
	s_barrier
	s_setprio 1
	v_mfma_f32_16x16x32_bf16 v[60:63], v[140:143], v[164:167], v[60:63]
	v_mfma_f32_16x16x32_bf16 v[56:59], v[156:159], v[164:167], v[56:59]
	v_mfma_f32_16x16x32_bf16 v[48:51], v[140:143], v[172:175], v[48:51]
	v_mfma_f32_16x16x32_bf16 v[40:43], v[156:159], v[172:175], v[40:43]
	v_mfma_f32_16x16x32_bf16 v[28:31], v[140:143], v[180:183], v[28:31]
	v_mfma_f32_16x16x32_bf16 v[24:27], v[156:159], v[180:183], v[24:27]
	v_mfma_f32_16x16x32_bf16 v[16:19], v[140:143], v[188:191], v[16:19]
	v_mfma_f32_16x16x32_bf16 v[8:11], v[156:159], v[188:191], v[8:11]
	v_mfma_f32_16x16x32_bf16 v[60:63], v[152:155], v[168:171], v[60:63]
	v_mfma_f32_16x16x32_bf16 v[56:59], v[160:163], v[168:171], v[56:59]
	v_mfma_f32_16x16x32_bf16 v[48:51], v[152:155], v[176:179], v[48:51]
	v_mfma_f32_16x16x32_bf16 v[40:43], v[160:163], v[176:179], v[40:43]
	v_mfma_f32_16x16x32_bf16 v[28:31], v[152:155], v[184:187], v[28:31]
	v_mfma_f32_16x16x32_bf16 v[24:27], v[160:163], v[184:187], v[24:27]
	v_mfma_f32_16x16x32_bf16 v[16:19], v[152:155], v[192:195], v[16:19]
	v_mfma_f32_16x16x32_bf16 v[8:11], v[160:163], v[192:195], v[8:11]
	v_mfma_f32_16x16x32_bf16 v[52:55], v[196:199], v[164:167], v[52:55]
	v_mfma_f32_16x16x32_bf16 v[44:47], v[204:207], v[164:167], v[44:47]
	v_mfma_f32_16x16x32_bf16 v[36:39], v[196:199], v[172:175], v[36:39]
	v_mfma_f32_16x16x32_bf16 v[32:35], v[204:207], v[172:175], v[32:35]
	v_mfma_f32_16x16x32_bf16 v[20:23], v[196:199], v[180:183], v[20:23]
	v_mfma_f32_16x16x32_bf16 v[12:15], v[204:207], v[180:183], v[12:15]
	v_mfma_f32_16x16x32_bf16 v[4:7], v[196:199], v[188:191], v[4:7]
	v_mfma_f32_16x16x32_bf16 v[0:3], v[204:207], v[188:191], v[0:3]
	v_mfma_f32_16x16x32_bf16 v[52:55], v[200:203], v[168:171], v[52:55]
	v_mfma_f32_16x16x32_bf16 v[44:47], v[208:211], v[168:171], v[44:47]
	v_mfma_f32_16x16x32_bf16 v[36:39], v[200:203], v[176:179], v[36:39]
	v_mfma_f32_16x16x32_bf16 v[32:35], v[208:211], v[176:179], v[32:35]
	v_mfma_f32_16x16x32_bf16 v[20:23], v[200:203], v[184:187], v[20:23]
	v_mfma_f32_16x16x32_bf16 v[12:15], v[208:211], v[184:187], v[12:15]
	v_mfma_f32_16x16x32_bf16 v[4:7], v[200:203], v[192:195], v[4:7]
	v_mfma_f32_16x16x32_bf16 v[0:3], v[208:211], v[192:195], v[0:3]
	s_setprio 0
	s_add_i32 s47, 0, 0x18000
	v_add_u32_e32 v160, s47, v147
	s_barrier
; #define PG8_STAGE(bufoff, gbase, voff) do { _Pragma("unroll") for (int _i = 0; _i < 2; ++_i) \
;         __builtin_amdgcn_global_load_lds((const unsigned*)((const char*)(gbase) + (voff)[_i]), (LAS unsigned*)(lds + (bufoff) + ldsw + _i * 8192), 16, 0, 0); } while (0)
; #define PG8_LDA(dst, b, h) do { _Pragma("unroll") for (int m = 0; m < 4; ++m) _Pragma("unroll") for (int k = 0; k < 2; ++k) dst[m][k] = *(const LAS bf16x8*)(lds + PG8_SA(b, h) + aoff + m * 2048 + k * 1024); } while (0)
; #define PG8_LDB(dst, b, h) do { _Pragma("unroll") for (int n = 0; n < 2; ++n) _Pragma("unroll") for (int k = 0; k < 2; ++k) dst[n][k] = *(const LAS bf16x8*)(lds + PG8_SB(b, h) + boff + n * 2048 + k * 1024); } while (0)
; #define PG8_MMA(ai, bj, At, Bt) do { __builtin_amdgcn_s_setprio(1); _Pragma("unroll") for (int m = 0; m < 4; ++m) _Pragma("unroll") for (int n = 0; n < 2; ++n) _Pragma("unroll") for (int k = 0; k < 2; ++k) \
;         acc[ai][bj][m][n] = __builtin_amdgcn_mfma_f32_16x16x32_bf16(Bt[n][k], At[m][k], acc[ai][bj][m][n], 0, 0, 0); __builtin_amdgcn_s_setprio(0); } while (0)
; #define PG8_WAIT_V(n) asm volatile("s_waitcnt vmcnt(" #n ")" ::: "memory")
; #define PG8_WAIT_L(n) asm volatile("s_waitcnt lgkmcnt(" #n ")" ::: "memory")
; template <class Epi>
; __device__ __forceinline__ void gemm_phase(LAS unsigned char* lds, const Gemm g, const StaticOrder& S, const Epi& E) {
;     ...
;             PG8_BAR; PG8_WAIT_L(0); PG8_MMA(0, 1, At, B1); PG8_BAR;
;             PG8_LDA(At, 0, 1); PG8_STAGE(PG8_SA(0, 0), a2, voffA);
;             PG8_BAR; PG8_WAIT_L(0); PG8_MMA(1, 0, At, B0); PG8_BAR; PG8_SCHED;
;             PG8_STAGE(PG8_SB(0, 1), b2 + hstepB, voffB);
;             PG8_WAIT_V(6); PG8_BAR; PG8_MMA(1, 1, At, B1); PG8_BAR;
;             PG8_LDB(B0, 1, 0); PG8_SCHED; PG8_LDA(At, 1, 0); PG8_STAGE(PG8_SA(0, 1), a2 + hstepA, voffA);
;             PG8_WAIT_L(8); PG8_BAR; PG8_WAIT_L(0); PG8_MMA(0, 0, At, B0); PG8_BAR; PG8_SCHED;
;             PG8_LDB(B1, 1, 1); PG8_STAGE(PG8_SB(1, 0), b3, voffB);
;             PG8_BAR; PG8_WAIT_L(0); PG8_MMA(0, 1, At, B1); PG8_BAR;
;             PG8_LDA(At, 1, 1); PG8_STAGE(PG8_SA(1, 0), a3, voffA);
;             PG8_BAR; PG8_WAIT_L(0); PG8_MMA(1, 0, At, B0); PG8_BAR; PG8_SCHED;
;             PG8_STAGE(PG8_SB(1, 1), b3 + hstepB, voffB);
;             PG8_WAIT_V(6); PG8_BAR; PG8_MMA(1, 1, At, B1); PG8_BAR;
	ds_read_b128 v[140:143], v160
	ds_read_b128 v[152:155], v160 offset:1024
	ds_read_b128 v[156:159], v160 offset:2048
	ds_read_b128 v[160:163], v160 offset:3072
	s_add_u32 s18, s24, 0xb0000
	s_addc_u32 s19, s25, 0
	s_mov_b32 m0, s33
	ds_read_b128 v[164:167], v150 offset:32768
	ds_read_b128 v[168:171], v150 offset:33792
	ds_read_b128 v[172:175], v150 offset:34816
	ds_read_b128 v[176:179], v150 offset:35840
	ds_read_b128 v[180:183], v150 offset:36864
	ds_read_b128 v[184:187], v150 offset:37888
	ds_read_b128 v[188:191], v150 offset:38912
	ds_read_b128 v[192:195], v150 offset:39936
	global_load_lds_dwordx4 v128, s[18:19]
	s_mov_b32 m0, s34
	s_nop 0
	global_load_lds_dwordx4 v130, s[18:19]
	s_add_i32 s24, 0, 0x1c000
	v_add_u32_e32 v208, s24, v147
	ds_read_b128 v[196:199], v208
	ds_read_b128 v[200:203], v208 offset:1024
	ds_read_b128 v[204:207], v208 offset:2048
	ds_read_b128 v[208:211], v208 offset:3072
	s_waitcnt lgkmcnt(0)
	s_barrier
	s_setprio 1
	v_mfma_f32_16x16x32_bf16 v[124:127], v[140:143], v[164:167], v[124:127]
	v_mfma_f32_16x16x32_bf16 v[120:123], v[156:159], v[164:167], v[120:123]
	v_mfma_f32_16x16x32_bf16 v[112:115], v[140:143], v[172:175], v[112:115]
	v_mfma_f32_16x16x32_bf16 v[104:107], v[156:159], v[172:175], v[104:107]
	v_mfma_f32_16x16x32_bf16 v[92:95], v[140:143], v[180:183], v[92:95]
	v_mfma_f32_16x16x32_bf16 v[88:91], v[156:159], v[180:183], v[88:91]
	v_mfma_f32_16x16x32_bf16 v[80:83], v[140:143], v[188:191], v[80:83]
	v_mfma_f32_16x16x32_bf16 v[72:75], v[156:159], v[188:191], v[72:75]
	v_mfma_f32_16x16x32_bf16 v[124:127], v[152:155], v[168:171], v[124:127]
	v_mfma_f32_16x16x32_bf16 v[120:123], v[160:163], v[168:171], v[120:123]
	v_mfma_f32_16x16x32_bf16 v[112:115], v[152:155], v[176:179], v[112:115]
	v_mfma_f32_16x16x32_bf16 v[104:107], v[160:163], v[176:179], v[104:107]
	v_mfma_f32_16x16x32_bf16 v[92:95], v[152:155], v[184:187], v[92:95]
	v_mfma_f32_16x16x32_bf16 v[88:91], v[160:163], v[184:187], v[88:91]
	v_mfma_f32_16x16x32_bf16 v[80:83], v[152:155], v[192:195], v[80:83]
	v_mfma_f32_16x16x32_bf16 v[72:75], v[160:163], v[192:195], v[72:75]
	v_mfma_f32_16x16x32_bf16 v[116:119], v[196:199], v[164:167], v[116:119]
	v_mfma_f32_16x16x32_bf16 v[108:111], v[204:207], v[164:167], v[108:111]
	v_mfma_f32_16x16x32_bf16 v[100:103], v[196:199], v[172:175], v[100:103]
	v_mfma_f32_16x16x32_bf16 v[96:99], v[204:207], v[172:175], v[96:99]
	v_mfma_f32_16x16x32_bf16 v[84:87], v[196:199], v[180:183], v[84:87]
	v_mfma_f32_16x16x32_bf16 v[76:79], v[204:207], v[180:183], v[76:79]
	v_mfma_f32_16x16x32_bf16 v[68:71], v[196:199], v[188:191], v[68:71]
	v_mfma_f32_16x16x32_bf16 v[64:67], v[204:207], v[188:191], v[64:67]
	v_mfma_f32_16x16x32_bf16 v[116:119], v[200:203], v[168:171], v[116:119]
	v_mfma_f32_16x16x32_bf16 v[108:111], v[208:211], v[168:171], v[108:111]
	v_mfma_f32_16x16x32_bf16 v[100:103], v[200:203], v[176:179], v[100:103]
	v_mfma_f32_16x16x32_bf16 v[96:99], v[208:211], v[176:179], v[96:99]
	v_mfma_f32_16x16x32_bf16 v[84:87], v[200:203], v[184:187], v[84:87]
	v_mfma_f32_16x16x32_bf16 v[76:79], v[208:211], v[184:187], v[76:79]
	v_mfma_f32_16x16x32_bf16 v[68:71], v[200:203], v[192:195], v[68:71]
	v_mfma_f32_16x16x32_bf16 v[64:67], v[208:211], v[192:195], v[64:67]
	s_setprio 0
	s_barrier
	s_nop 1
	ds_read_b128 v[164:167], v150 offset:49152
	ds_read_b128 v[168:171], v150 offset:50176
	ds_read_b128 v[172:175], v150 offset:51200
	ds_read_b128 v[176:179], v150 offset:52224
	ds_read_b128 v[180:183], v150 offset:53248
	ds_read_b128 v[184:187], v150 offset:54272
	ds_read_b128 v[188:191], v150 offset:55296
	ds_read_b128 v[192:195], v150 offset:56320
	s_add_i32 s18, s47, s29
	s_mov_b32 m0, s18
	s_nop 0
	s_add_u32 s100, s22, s10
	s_addc_u32 s101, s23, s11
	global_load_lds_dwordx4 v128, s[100:101]
	s_add_i32 m0, s18, 0x2000
	s_nop 0
	s_add_u32 s100, s22, s10
	s_addc_u32 s101, s23, s11
	global_load_lds_dwordx4 v130, s[100:101]
	s_mov_b32 m0, s36
	v_lshl_add_u64 v[254:255], v[214:215], 0, s[10:11]
	global_load_lds_dwordx4 v[254:255], off
	v_lshl_add_u64 v[144:145], v[216:217], 0, s[10:11]
	s_mov_b32 m0, s37
	s_nop 0
	global_load_lds_dwordx4 v[144:145], off
	s_add_u32 s18, s22, 0xb0080
	s_addc_u32 s19, s23, 0
	s_add_i32 s22, s24, s29
	s_mov_b32 m0, s22
	s_nop 0
	global_load_lds_dwordx4 v128, s[18:19]
	s_add_i32 m0, s22, 0x2000
	s_nop 0
	global_load_lds_dwordx4 v130, s[18:19]
	s_waitcnt vmcnt(6)
	s_waitcnt lgkmcnt(0)
	s_barrier
	s_setprio 1
	v_mfma_f32_16x16x32_bf16 v[60:63], v[140:143], v[164:167], v[60:63]
	v_mfma_f32_16x16x32_bf16 v[56:59], v[156:159], v[164:167], v[56:59]
	v_mfma_f32_16x16x32_bf16 v[48:51], v[140:143], v[172:175], v[48:51]
	v_mfma_f32_16x16x32_bf16 v[40:43], v[156:159], v[172:175], v[40:43]
	v_mfma_f32_16x16x32_bf16 v[28:31], v[140:143], v[180:183], v[28:31]
	v_mfma_f32_16x16x32_bf16 v[24:27], v[156:159], v[180:183], v[24:27]
	v_mfma_f32_16x16x32_bf16 v[16:19], v[140:143], v[188:191], v[16:19]
	v_mfma_f32_16x16x32_bf16 v[8:11], v[156:159], v[188:191], v[8:11]
	v_mfma_f32_16x16x32_bf16 v[60:63], v[152:155], v[168:171], v[60:63]
	v_mfma_f32_16x16x32_bf16 v[56:59], v[160:163], v[168:171], v[56:59]
	v_mfma_f32_16x16x32_bf16 v[48:51], v[152:155], v[176:179], v[48:51]
	v_mfma_f32_16x16x32_bf16 v[40:43], v[160:163], v[176:179], v[40:43]
	v_mfma_f32_16x16x32_bf16 v[28:31], v[152:155], v[184:187], v[28:31]
	v_mfma_f32_16x16x32_bf16 v[24:27], v[160:163], v[184:187], v[24:27]
	v_mfma_f32_16x16x32_bf16 v[16:19], v[152:155], v[192:195], v[16:19]
	v_mfma_f32_16x16x32_bf16 v[8:11], v[160:163], v[192:195], v[8:11]
	v_mfma_f32_16x16x32_bf16 v[52:55], v[196:199], v[164:167], v[52:55]
	v_mfma_f32_16x16x32_bf16 v[44:47], v[204:207], v[164:167], v[44:47]
	v_mfma_f32_16x16x32_bf16 v[36:39], v[196:199], v[172:175], v[36:39]
	v_mfma_f32_16x16x32_bf16 v[32:35], v[204:207], v[172:175], v[32:35]
	v_mfma_f32_16x16x32_bf16 v[20:23], v[196:199], v[180:183], v[20:23]
	v_mfma_f32_16x16x32_bf16 v[12:15], v[204:207], v[180:183], v[12:15]
	v_mfma_f32_16x16x32_bf16 v[4:7], v[196:199], v[188:191], v[4:7]
	v_mfma_f32_16x16x32_bf16 v[0:3], v[204:207], v[188:191], v[0:3]
	v_mfma_f32_16x16x32_bf16 v[52:55], v[200:203], v[168:171], v[52:55]
	v_mfma_f32_16x16x32_bf16 v[44:47], v[208:211], v[168:171], v[44:47]
	v_mfma_f32_16x16x32_bf16 v[36:39], v[200:203], v[176:179], v[36:39]
	v_mfma_f32_16x16x32_bf16 v[32:35], v[208:211], v[176:179], v[32:35]
	v_mfma_f32_16x16x32_bf16 v[20:23], v[200:203], v[184:187], v[20:23]
	v_mfma_f32_16x16x32_bf16 v[12:15], v[208:211], v[184:187], v[12:15]
	v_mfma_f32_16x16x32_bf16 v[4:7], v[200:203], v[192:195], v[4:7]
	v_mfma_f32_16x16x32_bf16 v[0:3], v[208:211], v[192:195], v[0:3]
	s_setprio 0
	s_add_i32 s46, s46, 2
	s_add_u32 s44, s44, 0x100
	s_addc_u32 s45, s45, 0
	s_cmp_gt_u32 s46, 41
	s_mov_b64 s[18:19], s[20:21]
	s_barrier
;     __device__ __forceinline__ void operator()(AccRef acc, const Unit& u, int wr, int wc, int fr, int fq) const {
;     ...
;         for (int ai = 0; ai < 2; ++ai)
; #pragma unroll
;             for (int mh = 0; mh < 2; ++mh) {
;                 f32x4 bs[2][2][2];
; #pragma unroll
;                 for (int m = 0; m < 2; ++m)
; #pragma unroll
;                     for (int bj = 0; bj < 2; ++bj)
; #pragma unroll
;                         for (int n = 0; n < 2; ++n) bs[m][bj][n] = *(const f32x4*)(base + (size_t)(row0 + ai * 128 + (2 * mh + m) * 16) * D + col0 + bj * 128 + n * 16);
; #pragma unroll
;                 for (int m = 0; m < 2; ++m)
; #pragma unroll
;                     for (int bj = 0; bj < 2; ++bj)
; #pragma unroll
;                         for (int n = 0; n < 2; ++n) *(f32x4*)(out + (size_t)(row0 + ai * 128 + (2 * mh + m) * 16) * D + col0 + bj * 128 + n * 16) = bs[m][bj][n] + sv[bj][n] * (acc[ai][bj][2 * mh + m][n] + bv[bj][n]);
;                 asm volatile("" ::: "memory"); }
	s_cbranch_scc0 .LBB0_2042
	v_lshl_or_b32 v144, s42, 8, v148
	v_lshl_add_u32 v145, s43, 8, v146
	v_lshlrev_b32_e32 v144, 2, v144
	v_lshl_add_u32 v145, v145, 12, v144
	v_add_u32_e32 v216, 0x10000, v145
	v_add_u32_e32 v217, 0x20000, v145
	v_add_u32_e32 v218, 0x30000, v145
	v_add_u32_e32 v232, 0x80000, v145
	v_add_u32_e32 v233, 0x90000, v145
	v_add_u32_e32 v235, 0xa0000, v145
	v_add_u32_e32 v253, 0xb0000, v145
	s_and_b64 vcc, exec, s[0:1]
	s_mov_b32 s42, s40
	s_mov_b32 s43, s41
	s_mov_b64 s[20:21], s[6:7]
	s_mov_b64 s[18:19], s[4:5]
	global_load_dwordx4 v[140:143], v145, s[52:53]
	global_load_dwordx4 v[152:155], v145, s[52:53] offset:64
	global_load_dwordx4 v[156:159], v145, s[52:53] offset:512
	global_load_dwordx4 v[160:163], v145, s[52:53] offset:576
	global_load_dwordx4 v[164:167], v216, s[52:53]
	global_load_dwordx4 v[168:171], v216, s[52:53] offset:64
	global_load_dwordx4 v[172:175], v216, s[52:53] offset:512
	global_load_dwordx4 v[176:179], v216, s[52:53] offset:576
	global_load_dwordx4 v[180:183], v217, s[52:53]
	global_load_dwordx4 v[184:187], v217, s[52:53] offset:64
	global_load_dwordx4 v[188:191], v217, s[52:53] offset:512
	global_load_dwordx4 v[192:195], v217, s[52:53] offset:576
	global_load_dwordx4 v[196:199], v218, s[52:53]
	global_load_dwordx4 v[200:203], v218, s[52:53] offset:64
	global_load_dwordx4 v[204:207], v218, s[52:53] offset:512
	global_load_dwordx4 v[208:211], v218, s[52:53] offset:576
	global_load_dwordx4 v[212:215], v232, s[52:53]
	global_load_dwordx4 v[220:223], v232, s[52:53] offset:64
	global_load_dwordx4 v[224:227], v232, s[52:53] offset:512
	global_load_dwordx4 v[228:231], v232, s[52:53] offset:576
	global_load_dwordx4 v[236:239], v233, s[52:53]
	global_load_dwordx4 v[240:243], v233, s[52:53] offset:64
	global_load_dwordx4 v[244:247], v233, s[52:53] offset:512
	global_load_dwordx4 v[248:251], v233, s[52:53] offset:576
	v_pk_add_f32 v[124:125], v[124:125], 0 op_sel_hi:[1,0]
	v_pk_add_f32 v[126:127], v[126:127], 0 op_sel_hi:[1,0]
	v_pk_add_f32 v[120:121], v[120:121], 0 op_sel_hi:[1,0]
	v_pk_add_f32 v[122:123], v[122:123], 0 op_sel_hi:[1,0]
	v_pk_add_f32 v[116:117], v[116:117], 0 op_sel_hi:[1,0]
	v_pk_add_f32 v[118:119], v[118:119], 0 op_sel_hi:[1,0]
	v_pk_add_f32 v[108:109], v[108:109], 0 op_sel_hi:[1,0]
	v_pk_add_f32 v[110:111], v[110:111], 0 op_sel_hi:[1,0]
	v_pk_add_f32 v[112:113], v[112:113], 0 op_sel_hi:[1,0]
	v_pk_add_f32 v[114:115], v[114:115], 0 op_sel_hi:[1,0]
	v_pk_add_f32 v[104:105], v[104:105], 0 op_sel_hi:[1,0]
	v_pk_add_f32 v[106:107], v[106:107], 0 op_sel_hi:[1,0]
	v_pk_add_f32 v[100:101], v[100:101], 0 op_sel_hi:[1,0]
	v_pk_add_f32 v[102:103], v[102:103], 0 op_sel_hi:[1,0]
	v_pk_add_f32 v[96:97], v[96:97], 0 op_sel_hi:[1,0]
	v_pk_add_f32 v[98:99], v[98:99], 0 op_sel_hi:[1,0]
	v_pk_add_f32 v[92:93], v[92:93], 0 op_sel_hi:[1,0]
	v_pk_add_f32 v[94:95], v[94:95], 0 op_sel_hi:[1,0]
	v_pk_add_f32 v[88:89], v[88:89], 0 op_sel_hi:[1,0]
	v_pk_add_f32 v[90:91], v[90:91], 0 op_sel_hi:[1,0]
	v_pk_add_f32 v[84:85], v[84:85], 0 op_sel_hi:[1,0]
	v_pk_add_f32 v[86:87], v[86:87], 0 op_sel_hi:[1,0]
	v_pk_add_f32 v[76:77], v[76:77], 0 op_sel_hi:[1,0]
	v_pk_add_f32 v[78:79], v[78:79], 0 op_sel_hi:[1,0]
	v_pk_add_f32 v[80:81], v[80:81], 0 op_sel_hi:[1,0]
	v_pk_add_f32 v[82:83], v[82:83], 0 op_sel_hi:[1,0]
	v_pk_add_f32 v[72:73], v[72:73], 0 op_sel_hi:[1,0]
	v_pk_add_f32 v[74:75], v[74:75], 0 op_sel_hi:[1,0]
	v_pk_add_f32 v[68:69], v[68:69], 0 op_sel_hi:[1,0]
	v_pk_add_f32 v[70:71], v[70:71], 0 op_sel_hi:[1,0]
	v_pk_add_f32 v[64:65], v[64:65], 0 op_sel_hi:[1,0]
	v_pk_add_f32 v[66:67], v[66:67], 0 op_sel_hi:[1,0]
	v_pk_add_f32 v[60:61], v[60:61], 0 op_sel_hi:[1,0]
	v_pk_add_f32 v[62:63], v[62:63], 0 op_sel_hi:[1,0]
	v_pk_add_f32 v[56:57], v[56:57], 0 op_sel_hi:[1,0]
	v_pk_add_f32 v[58:59], v[58:59], 0 op_sel_hi:[1,0]
	v_pk_add_f32 v[52:53], v[52:53], 0 op_sel_hi:[1,0]
	v_pk_add_f32 v[54:55], v[54:55], 0 op_sel_hi:[1,0]
	v_pk_add_f32 v[44:45], v[44:45], 0 op_sel_hi:[1,0]
	v_pk_add_f32 v[46:47], v[46:47], 0 op_sel_hi:[1,0]
	v_pk_add_f32 v[48:49], v[48:49], 0 op_sel_hi:[1,0]
	v_pk_add_f32 v[50:51], v[50:51], 0 op_sel_hi:[1,0]
	v_pk_add_f32 v[40:41], v[40:41], 0 op_sel_hi:[1,0]
	v_pk_add_f32 v[42:43], v[42:43], 0 op_sel_hi:[1,0]
	v_pk_add_f32 v[36:37], v[36:37], 0 op_sel_hi:[1,0]
	v_pk_add_f32 v[38:39], v[38:39], 0 op_sel_hi:[1,0]
	v_pk_add_f32 v[32:33], v[32:33], 0 op_sel_hi:[1,0]
	v_pk_add_f32 v[34:35], v[34:35], 0 op_sel_hi:[1,0]
	v_pk_add_f32 v[28:29], v[28:29], 0 op_sel_hi:[1,0]
	v_pk_add_f32 v[30:31], v[30:31], 0 op_sel_hi:[1,0]
	v_pk_add_f32 v[24:25], v[24:25], 0 op_sel_hi:[1,0]
	v_pk_add_f32 v[26:27], v[26:27], 0 op_sel_hi:[1,0]
	v_pk_add_f32 v[20:21], v[20:21], 0 op_sel_hi:[1,0]
	v_pk_add_f32 v[22:23], v[22:23], 0 op_sel_hi:[1,0]
	v_pk_add_f32 v[12:13], v[12:13], 0 op_sel_hi:[1,0]
	v_pk_add_f32 v[14:15], v[14:15], 0 op_sel_hi:[1,0]
	v_pk_add_f32 v[16:17], v[16:17], 0 op_sel_hi:[1,0]
	v_pk_add_f32 v[18:19], v[18:19], 0 op_sel_hi:[1,0]
	v_pk_add_f32 v[8:9], v[8:9], 0 op_sel_hi:[1,0]
	v_pk_add_f32 v[10:11], v[10:11], 0 op_sel_hi:[1,0]
	v_pk_add_f32 v[4:5], v[4:5], 0 op_sel_hi:[1,0]
	v_pk_add_f32 v[6:7], v[6:7], 0 op_sel_hi:[1,0]
	v_pk_add_f32 v[0:1], v[0:1], 0 op_sel_hi:[1,0]
	v_pk_add_f32 v[2:3], v[2:3], 0 op_sel_hi:[1,0]
	s_waitcnt vmcnt(16)
; #define PG8_WAIT_V(n) asm volatile("s_waitcnt vmcnt(" #n ")" ::: "memory")
; template <class Epi>
; __device__ __forceinline__ void gemm_phase(LAS unsigned char* lds, const Gemm g, const StaticOrder& S, const Epi& E) {
;     ...
;         if (!has_next) break;
;         {
; #pragma unroll
;         for (int a = 0; a < 2; ++a)
; #pragma unroll
;             for (int b = 0; b < 2; ++b)
; #pragma unroll
;                 for (int m = 0; m < 4; ++m)
; #pragma unroll
;                     for (int n = 0; n < 2; ++n) acc[a][b][m][n] = (f32x4){0.f, 0.f, 0.f, 0.f};
;         }
;         cur = nxt; cA = nA; cB = nB; ++ui;
;     }
;     PG8_WAIT_V(0);
;     __device__ __forceinline__ void operator()(AccRef acc, const Unit& u, int wr, int wc, int fr, int fq) const {
;     ...
;                         for (int n = 0; n < 2; ++n) bs[m][bj][n] = *(const f32x4*)(base + (size_t)(row0 + ai * 128 + (2 * mh + m) * 16) * D + col0 + bj * 128 + n * 16);
; #pragma unroll
;                 for (int m = 0; m < 2; ++m)
; #pragma unroll
;                     for (int bj = 0; bj < 2; ++bj)
; #pragma unroll
;                         for (int n = 0; n < 2; ++n) *(f32x4*)(out + (size_t)(row0 + ai * 128 + (2 * mh + m) * 16) * D + col0 + bj * 128 + n * 16) = bs[m][bj][n] + sv[bj][n] * (acc[ai][bj][2 * mh + m][n] + bv[bj][n]);
;                 asm volatile("" ::: "memory"); }
	v_pk_add_f32 v[124:125], v[124:125], v[140:141]
	v_pk_add_f32 v[126:127], v[126:127], v[142:143]
	v_pk_add_f32 v[120:121], v[120:121], v[152:153]
	v_pk_add_f32 v[122:123], v[122:123], v[154:155]
	v_pk_add_f32 v[116:117], v[116:117], v[156:157]
	v_pk_add_f32 v[118:119], v[118:119], v[158:159]
	v_pk_add_f32 v[108:109], v[108:109], v[160:161]
	v_pk_add_f32 v[110:111], v[110:111], v[162:163]
	v_pk_add_f32 v[112:113], v[112:113], v[164:165]
	v_pk_add_f32 v[114:115], v[114:115], v[166:167]
	v_pk_add_f32 v[104:105], v[104:105], v[168:169]
	v_pk_add_f32 v[106:107], v[106:107], v[170:171]
	v_pk_add_f32 v[100:101], v[100:101], v[172:173]
	v_pk_add_f32 v[102:103], v[102:103], v[174:175]
	v_pk_add_f32 v[96:97], v[96:97], v[176:177]
	v_pk_add_f32 v[98:99], v[98:99], v[178:179]
	global_store_dwordx4 v145, v[124:127], s[52:53]
	global_store_dwordx4 v145, v[120:123], s[52:53] offset:64
	global_store_dwordx4 v145, v[116:119], s[52:53] offset:512
	global_store_dwordx4 v145, v[108:111], s[52:53] offset:576
	global_store_dwordx4 v216, v[112:115], s[52:53]
	global_store_dwordx4 v216, v[104:107], s[52:53] offset:64
	global_store_dwordx4 v216, v[100:103], s[52:53] offset:512
	global_store_dwordx4 v216, v[96:99], s[52:53] offset:576
	global_load_dwordx4 v[140:143], v235, s[52:53]
	global_load_dwordx4 v[152:155], v235, s[52:53] offset:64
	global_load_dwordx4 v[156:159], v235, s[52:53] offset:512
	global_load_dwordx4 v[160:163], v235, s[52:53] offset:576
	global_load_dwordx4 v[164:167], v253, s[52:53]
	global_load_dwordx4 v[168:171], v253, s[52:53] offset:64
	global_load_dwordx4 v[172:175], v253, s[52:53] offset:512
	global_load_dwordx4 v[176:179], v253, s[52:53] offset:576
	s_waitcnt vmcnt(24)
	v_pk_add_f32 v[92:93], v[92:93], v[180:181]
	v_pk_add_f32 v[94:95], v[94:95], v[182:183]
	v_pk_add_f32 v[88:89], v[88:89], v[184:185]
	v_pk_add_f32 v[90:91], v[90:91], v[186:187]
	v_pk_add_f32 v[84:85], v[84:85], v[188:189]
	v_pk_add_f32 v[86:87], v[86:87], v[190:191]
	v_pk_add_f32 v[76:77], v[76:77], v[192:193]
	v_pk_add_f32 v[78:79], v[78:79], v[194:195]
	v_pk_add_f32 v[80:81], v[80:81], v[196:197]
	v_pk_add_f32 v[82:83], v[82:83], v[198:199]
	v_pk_add_f32 v[72:73], v[72:73], v[200:201]
	v_pk_add_f32 v[74:75], v[74:75], v[202:203]
	v_pk_add_f32 v[68:69], v[68:69], v[204:205]
	v_pk_add_f32 v[70:71], v[70:71], v[206:207]
	v_pk_add_f32 v[64:65], v[64:65], v[208:209]
	v_pk_add_f32 v[66:67], v[66:67], v[210:211]
	global_store_dwordx4 v217, v[92:95], s[52:53]
	global_store_dwordx4 v217, v[88:91], s[52:53] offset:64
	global_store_dwordx4 v217, v[84:87], s[52:53] offset:512
	global_store_dwordx4 v217, v[76:79], s[52:53] offset:576
	global_store_dwordx4 v218, v[80:83], s[52:53]
	global_store_dwordx4 v218, v[72:75], s[52:53] offset:64
	global_store_dwordx4 v218, v[68:71], s[52:53] offset:512
	global_store_dwordx4 v218, v[64:67], s[52:53] offset:576
	s_waitcnt vmcnt(24)
	v_pk_add_f32 v[60:61], v[60:61], v[212:213]
	v_pk_add_f32 v[62:63], v[62:63], v[214:215]
	v_pk_add_f32 v[56:57], v[56:57], v[220:221]
	v_pk_add_f32 v[58:59], v[58:59], v[222:223]
	v_pk_add_f32 v[52:53], v[52:53], v[224:225]
	v_pk_add_f32 v[54:55], v[54:55], v[226:227]
	v_pk_add_f32 v[44:45], v[44:45], v[228:229]
	v_pk_add_f32 v[46:47], v[46:47], v[230:231]
	v_pk_add_f32 v[48:49], v[48:49], v[236:237]
	v_pk_add_f32 v[50:51], v[50:51], v[238:239]
	v_pk_add_f32 v[40:41], v[40:41], v[240:241]
	v_pk_add_f32 v[42:43], v[42:43], v[242:243]
	v_pk_add_f32 v[36:37], v[36:37], v[244:245]
	v_pk_add_f32 v[38:39], v[38:39], v[246:247]
	v_pk_add_f32 v[32:33], v[32:33], v[248:249]
	v_pk_add_f32 v[34:35], v[34:35], v[250:251]
	global_store_dwordx4 v232, v[60:63], s[52:53]
	global_store_dwordx4 v232, v[56:59], s[52:53] offset:64
	global_store_dwordx4 v232, v[52:55], s[52:53] offset:512
	global_store_dwordx4 v232, v[44:47], s[52:53] offset:576
	global_store_dwordx4 v233, v[48:51], s[52:53]
	global_store_dwordx4 v233, v[40:43], s[52:53] offset:64
	global_store_dwordx4 v233, v[36:39], s[52:53] offset:512
	global_store_dwordx4 v233, v[32:35], s[52:53] offset:576
	s_waitcnt vmcnt(16)
	v_pk_add_f32 v[28:29], v[28:29], v[140:141]
	v_pk_add_f32 v[30:31], v[30:31], v[142:143]
	v_pk_add_f32 v[24:25], v[24:25], v[152:153]
	v_pk_add_f32 v[26:27], v[26:27], v[154:155]
	v_pk_add_f32 v[20:21], v[20:21], v[156:157]
	v_pk_add_f32 v[22:23], v[22:23], v[158:159]
	v_pk_add_f32 v[12:13], v[12:13], v[160:161]
	v_pk_add_f32 v[14:15], v[14:15], v[162:163]
	v_pk_add_f32 v[16:17], v[16:17], v[164:165]
	v_pk_add_f32 v[18:19], v[18:19], v[166:167]
	v_pk_add_f32 v[8:9], v[8:9], v[168:169]
	v_pk_add_f32 v[10:11], v[10:11], v[170:171]
	v_pk_add_f32 v[4:5], v[4:5], v[172:173]
	v_pk_add_f32 v[6:7], v[6:7], v[174:175]
	v_pk_add_f32 v[0:1], v[0:1], v[176:177]
	v_pk_add_f32 v[2:3], v[2:3], v[178:179]
	global_store_dwordx4 v235, v[28:31], s[52:53]
	global_store_dwordx4 v235, v[24:27], s[52:53] offset:64
	global_store_dwordx4 v235, v[20:23], s[52:53] offset:512
	global_store_dwordx4 v235, v[12:15], s[52:53] offset:576
	global_store_dwordx4 v253, v[16:19], s[52:53]
	global_store_dwordx4 v253, v[8:11], s[52:53] offset:64
	global_store_dwordx4 v253, v[4:7], s[52:53] offset:512
	global_store_dwordx4 v253, v[0:3], s[52:53] offset:576
	s_cbranch_vccz .LBB0_2031
	s_waitcnt vmcnt(0)
	s_cmpk_gt_u32 s26, 0xff
	s_cbranch_scc1 .LBB0_2046
	s_barrier
